# f32->bf16 pair conversions: 794 bit-trick sequences (bfe/add3/lshr/and_or, 6 VALU) replaced by v_cvt_pk_bf16_f32 (same RNE rounding); plus skinny GEMM load batching in P4/P5/P7 and MODE1 unit-end stor
# speedup vs baseline: 1.0226x; 1.0011x over previous
; #define LAS __attribute__((address_space(3)))
; __device__ __forceinline__ void p0_transpose_item(const float* W, int Nsrc, bf16_t* WT, int Kdst, int k0, int src_col0, int dst_row0, LAS float* scr, int lane) {
; #pragma unroll
;     for (int i = 0; i < 32; ++i) { const int kk = 2 * i + (lane >> 5); scr[kk * 33 + (lane & 31)] = (src_col0 >= 0) ? W[(size_t)(k0 + kk) * Nsrc + src_col0 + (lane & 31)] : 0.f; }
; __device__ __forceinline__ void phase_prologue(const Prm& P, Ctx& C) {
;     ...
;         { const int blk = r >> 4, kb = r & 15; p0_transpose_item(P.w_out_odd, 1024, (bf16_t*)(ws + WS_W5T), 1024, 64 * kb, 32 * blk, 32 * blk, scr, C.lane); }
.LBB0_11:
	s_cmpk_lt_i32 s36, 0xf80
	s_mov_b64 s[8:9], -1
	s_cbranch_scc0 .LBB0_81
	s_cmpk_gt_i32 s36, 0x6ff
	s_cbranch_scc0 .LBB0_26
	s_cmpk_gt_u32 s36, 0x8ff
	s_cbranch_scc0 .LBB0_23
	s_cmpk_gt_u32 s36, 0xcff
	s_cbranch_scc0 .LBB0_20
	s_cmpk_gt_u32 s36, 0xd7f
	s_cbranch_scc0 .LBB0_17
	s_and_b32 s8, s12, 0x3c0
	s_and_b32 s0, s24, 0x7fffffe0
	v_add_u32_e32 v76, s8, v25
	v_add_u32_e32 v78, s8, v28
	v_add_u32_e32 v80, s8, v29
	v_add_u32_e32 v82, s8, v30
	v_add_u32_e32 v84, s8, v31
	v_add_u32_e32 v86, s8, v32
	v_add_u32_e32 v88, s8, v33
	v_add_u32_e32 v90, s8, v35
	s_addk_i32 s0, 0xe500
	v_ashrrev_i32_e32 v77, 31, v76
	v_ashrrev_i32_e32 v79, 31, v78
	v_ashrrev_i32_e32 v81, 31, v80
	v_ashrrev_i32_e32 v83, 31, v82
	v_ashrrev_i32_e32 v85, 31, v84
	v_ashrrev_i32_e32 v87, 31, v86
	v_ashrrev_i32_e32 v89, 31, v88
	v_ashrrev_i32_e32 v91, 31, v90
	v_lshl_add_u64 v[22:23], s[0:1], 2, v[2:3]
	v_lshlrev_b64 v[76:77], 12, v[76:77]
	v_lshlrev_b64 v[78:79], 12, v[78:79]
	v_lshlrev_b64 v[80:81], 12, v[80:81]
	v_lshlrev_b64 v[82:83], 12, v[82:83]
	v_lshlrev_b64 v[84:85], 12, v[84:85]
	v_lshlrev_b64 v[86:87], 12, v[86:87]
	v_lshlrev_b64 v[88:89], 12, v[88:89]
	v_lshlrev_b64 v[90:91], 12, v[90:91]
	v_lshl_add_u64 v[76:77], v[22:23], 0, v[76:77]
	v_lshl_add_u64 v[78:79], v[22:23], 0, v[78:79]
	v_lshl_add_u64 v[80:81], v[22:23], 0, v[80:81]
	v_lshl_add_u64 v[82:83], v[22:23], 0, v[82:83]
	v_lshl_add_u64 v[84:85], v[22:23], 0, v[84:85]
	v_lshl_add_u64 v[86:87], v[22:23], 0, v[86:87]
	v_lshl_add_u64 v[88:89], v[22:23], 0, v[88:89]
	v_lshl_add_u64 v[90:91], v[22:23], 0, v[90:91]
	global_load_dword v21, v[76:77], off
	global_load_dword v92, v[78:79], off
	global_load_dword v93, v[80:81], off
	global_load_dword v94, v[82:83], off
	global_load_dword v95, v[84:85], off
	global_load_dword v96, v[86:87], off
	global_load_dword v97, v[88:89], off
	global_load_dword v98, v[90:91], off
	v_add_u32_e32 v76, s8, v36
	v_add_u32_e32 v78, s8, v37
	v_add_u32_e32 v80, s8, v38
	v_add_u32_e32 v82, s8, v39
	v_add_u32_e32 v84, s8, v40
	v_add_u32_e32 v86, s8, v42
	v_add_u32_e32 v88, s8, v43
	v_add_u32_e32 v90, s8, v44
	v_ashrrev_i32_e32 v77, 31, v76
	v_ashrrev_i32_e32 v79, 31, v78
	v_ashrrev_i32_e32 v81, 31, v80
	v_ashrrev_i32_e32 v83, 31, v82
	v_ashrrev_i32_e32 v85, 31, v84
	v_ashrrev_i32_e32 v87, 31, v86
	v_ashrrev_i32_e32 v89, 31, v88
	v_ashrrev_i32_e32 v91, 31, v90
	v_lshlrev_b64 v[76:77], 12, v[76:77]
	v_lshlrev_b64 v[78:79], 12, v[78:79]
	v_lshlrev_b64 v[80:81], 12, v[80:81]
	v_lshlrev_b64 v[82:83], 12, v[82:83]
	v_lshlrev_b64 v[84:85], 12, v[84:85]
	v_lshlrev_b64 v[86:87], 12, v[86:87]
	v_lshlrev_b64 v[88:89], 12, v[88:89]
	v_lshlrev_b64 v[90:91], 12, v[90:91]
	v_lshl_add_u64 v[76:77], v[22:23], 0, v[76:77]
	v_lshl_add_u64 v[78:79], v[22:23], 0, v[78:79]
	v_lshl_add_u64 v[80:81], v[22:23], 0, v[80:81]
	v_lshl_add_u64 v[82:83], v[22:23], 0, v[82:83]
	v_lshl_add_u64 v[84:85], v[22:23], 0, v[84:85]
	v_lshl_add_u64 v[86:87], v[22:23], 0, v[86:87]
	v_lshl_add_u64 v[88:89], v[22:23], 0, v[88:89]
	v_lshl_add_u64 v[90:91], v[22:23], 0, v[90:91]
	global_load_dword v99, v[76:77], off
	global_load_dword v100, v[78:79], off
	global_load_dword v101, v[80:81], off
	global_load_dword v102, v[82:83], off
	global_load_dword v103, v[84:85], off
	global_load_dword v104, v[86:87], off
	global_load_dword v105, v[88:89], off
	global_load_dword v106, v[90:91], off
	v_add_u32_e32 v76, s8, v45
	v_add_u32_e32 v78, s8, v46
	v_add_u32_e32 v80, s8, v47
	v_add_u32_e32 v82, s8, v49
	v_add_u32_e32 v84, s8, v50
	v_add_u32_e32 v86, s8, v51
	v_add_u32_e32 v88, s8, v62
	v_add_u32_e32 v90, s8, v63
	v_ashrrev_i32_e32 v77, 31, v76
	v_ashrrev_i32_e32 v79, 31, v78
	v_ashrrev_i32_e32 v81, 31, v80
	v_ashrrev_i32_e32 v83, 31, v82
	v_ashrrev_i32_e32 v85, 31, v84
	v_ashrrev_i32_e32 v87, 31, v86
	v_ashrrev_i32_e32 v89, 31, v88
	v_ashrrev_i32_e32 v91, 31, v90
	v_lshlrev_b64 v[76:77], 12, v[76:77]
	v_lshlrev_b64 v[78:79], 12, v[78:79]
	v_lshlrev_b64 v[80:81], 12, v[80:81]
	v_lshlrev_b64 v[82:83], 12, v[82:83]
	v_lshlrev_b64 v[84:85], 12, v[84:85]
	v_lshlrev_b64 v[86:87], 12, v[86:87]
	v_lshlrev_b64 v[88:89], 12, v[88:89]
	v_lshlrev_b64 v[90:91], 12, v[90:91]
	v_lshl_add_u64 v[76:77], v[22:23], 0, v[76:77]
	v_lshl_add_u64 v[78:79], v[22:23], 0, v[78:79]
	v_lshl_add_u64 v[80:81], v[22:23], 0, v[80:81]
	v_lshl_add_u64 v[82:83], v[22:23], 0, v[82:83]
	v_lshl_add_u64 v[84:85], v[22:23], 0, v[84:85]
	v_lshl_add_u64 v[86:87], v[22:23], 0, v[86:87]
	v_lshl_add_u64 v[88:89], v[22:23], 0, v[88:89]
	v_lshl_add_u64 v[90:91], v[22:23], 0, v[90:91]
	global_load_dword v107, v[76:77], off
	global_load_dword v108, v[78:79], off
	global_load_dword v109, v[80:81], off
	global_load_dword v110, v[82:83], off
	global_load_dword v111, v[84:85], off
	global_load_dword v112, v[86:87], off
	global_load_dword v113, v[88:89], off
	global_load_dword v114, v[90:91], off
	v_add_u32_e32 v76, s8, v64
	v_add_u32_e32 v78, s8, v66
	v_add_u32_e32 v80, s8, v67
	v_add_u32_e32 v82, s8, v68
	v_add_u32_e32 v84, s8, v69
	v_add_u32_e32 v86, s8, v70
	v_add_u32_e32 v88, s8, v71
	v_add_u32_e32 v90, s8, v72
	v_ashrrev_i32_e32 v77, 31, v76
	v_ashrrev_i32_e32 v79, 31, v78
	v_ashrrev_i32_e32 v81, 31, v80
	v_ashrrev_i32_e32 v83, 31, v82
	v_ashrrev_i32_e32 v85, 31, v84
	v_ashrrev_i32_e32 v87, 31, v86
	v_ashrrev_i32_e32 v89, 31, v88
	v_ashrrev_i32_e32 v91, 31, v90
	v_lshlrev_b64 v[76:77], 12, v[76:77]
	v_lshlrev_b64 v[78:79], 12, v[78:79]
	v_lshlrev_b64 v[80:81], 12, v[80:81]
	v_lshlrev_b64 v[82:83], 12, v[82:83]
	v_lshlrev_b64 v[84:85], 12, v[84:85]
	v_lshlrev_b64 v[86:87], 12, v[86:87]
	v_lshlrev_b64 v[88:89], 12, v[88:89]
	v_lshlrev_b64 v[90:91], 12, v[90:91]
	v_lshl_add_u64 v[76:77], v[22:23], 0, v[76:77]
	v_lshl_add_u64 v[78:79], v[22:23], 0, v[78:79]
	v_lshl_add_u64 v[80:81], v[22:23], 0, v[80:81]
	v_lshl_add_u64 v[82:83], v[22:23], 0, v[82:83]
	v_lshl_add_u64 v[84:85], v[22:23], 0, v[84:85]
	v_lshl_add_u64 v[86:87], v[22:23], 0, v[86:87]
	v_lshl_add_u64 v[88:89], v[22:23], 0, v[88:89]
	v_lshl_add_u64 v[22:23], v[22:23], 0, v[90:91]
	global_load_dword v76, v[76:77], off
	s_nop 0
	global_load_dword v77, v[78:79], off
	s_nop 0
	global_load_dword v78, v[80:81], off
	global_load_dword v79, v[82:83], off
	s_nop 0
	global_load_dword v80, v[84:85], off
	global_load_dword v81, v[86:87], off
	global_load_dword v82, v[88:89], off
	s_nop 0
	global_load_dword v22, v[22:23], off
	v_add_u32_e32 v23, v26, v27
	s_waitcnt vmcnt(30)
; #define LAS __attribute__((address_space(3)))
; __device__ __forceinline__ unsigned pk2(float lo, float hi) { return f2bf(lo) | (f2bf(hi) << 16); }
; #define LDS_WAIT() asm volatile("s_waitcnt lgkmcnt(0)" ::: "memory")
; __device__ __forceinline__ void p0_transpose_item(const float* W, int Nsrc, bf16_t* WT, int Kdst, int k0, int src_col0, int dst_row0, LAS float* scr, int lane) {
;     ...
;     LDS_WAIT();
;     const int c = lane & 7;
; #pragma unroll
;     for (int j = 0; j < 4; ++j) { const int n = (lane >> 3) + 8 * j; const LAS float* s = scr + (8 * c) * 33 + n;
;         u32x4 o; o.x = pk2(s[0 * 33], s[1 * 33]); o.y = pk2(s[2 * 33], s[3 * 33]); o.z = pk2(s[4 * 33], s[5 * 33]); o.w = pk2(s[6 * 33], s[7 * 33]);
;         *(u32x4*)(WT + (size_t)(dst_row0 + n) * Kdst + k0 + 8 * c) = o; }
; __device__ __forceinline__ void phase_prologue(const Prm& P, Ctx& C) {
;     ...
;         if (r < 128) { const int g = r >> 5, rr = r & 31, blk = rr >> 2, kb = rr & 3; p0_transpose_item(P.w_grp + g * 65536, 256, (bf16_t*)(ws + WS_W4T) + g * 65536, 256, 64 * kb, 32 * blk, 32 * blk, scr, C.lane); continue; } r -= 128;
	ds_write2_b32 v23, v21, v92 offset1:66
	s_waitcnt vmcnt(28)
	ds_write2_b32 v23, v93, v94 offset0:132 offset1:198
	v_add_u32_e32 v21, 0x400, v23
	s_waitcnt vmcnt(26)
	ds_write2_b32 v21, v95, v96 offset0:8 offset1:74
	v_add_u32_e32 v21, v26, v34
	s_waitcnt vmcnt(24)
	ds_write2_b32 v21, v97, v98 offset1:66
	s_waitcnt vmcnt(22)
	ds_write2_b32 v21, v99, v100 offset0:132 offset1:198
	v_add_u32_e32 v21, 0x400, v21
	s_waitcnt vmcnt(20)
	ds_write2_b32 v21, v101, v102 offset0:8 offset1:74
	v_add_u32_e32 v21, v26, v41
	s_waitcnt vmcnt(18)
	ds_write2_b32 v21, v103, v104 offset1:66
	s_waitcnt vmcnt(16)
	ds_write2_b32 v21, v105, v106 offset0:132 offset1:198
	v_add_u32_e32 v21, 0x400, v21
	v_add_u32_e32 v96, s0, v52
	s_lshl_b32 s8, s8, 1
	s_mov_b32 s9, s1
	v_ashrrev_i32_e32 v97, 31, v96
	v_lshlrev_b64 v[96:97], 11, v[96:97]
	s_waitcnt vmcnt(14)
	ds_write2_b32 v21, v107, v108 offset0:8 offset1:74
	v_add_u32_e32 v21, v26, v48
	s_waitcnt vmcnt(12)
	ds_write2_b32 v21, v109, v110 offset1:66
	s_waitcnt vmcnt(10)
	ds_write2_b32 v21, v111, v112 offset0:132 offset1:198
	v_add_u32_e32 v21, 0x400, v21
	s_waitcnt vmcnt(8)
	ds_write2_b32 v21, v113, v114 offset0:8 offset1:74
	v_add_u32_e32 v21, v26, v65
	s_waitcnt vmcnt(6)
	ds_write2_b32 v21, v76, v77 offset1:66
	s_waitcnt vmcnt(4)
	ds_write2_b32 v21, v78, v79 offset0:132 offset1:198
	v_add_u32_e32 v21, 0x400, v21
	s_waitcnt vmcnt(2)
	ds_write2_b32 v21, v80, v81 offset0:8 offset1:74
	s_waitcnt vmcnt(0)
	ds_write2_b32 v21, v82, v22 offset0:140 offset1:206
	s_waitcnt lgkmcnt(0)
	ds_read2_b32 v[22:23], v53 offset1:8
	ds_read2_b32 v[82:83], v53 offset0:33 offset1:41
	ds_read2_b32 v[84:85], v53 offset0:66 offset1:74
	ds_read2_b32 v[86:87], v53 offset0:99 offset1:107
	ds_read2_b32 v[88:89], v53 offset0:132 offset1:140
	s_waitcnt lgkmcnt(4)
	s_waitcnt lgkmcnt(3)
	ds_read2_b32 v[90:91], v53 offset0:165 offset1:173
	v_cvt_pk_bf16_f32 v76, v22, v82
	s_waitcnt lgkmcnt(3)
	s_waitcnt lgkmcnt(2)
	ds_read2_b32 v[92:93], v53 offset0:198 offset1:206
	ds_read2_b32 v[94:95], v53 offset0:231 offset1:239
	v_cvt_pk_bf16_f32 v77, v84, v86
	s_waitcnt lgkmcnt(3)
	s_waitcnt lgkmcnt(2)
	v_cvt_pk_bf16_f32 v78, v88, v90
	s_waitcnt lgkmcnt(1)
	s_waitcnt lgkmcnt(0)
	v_cvt_pk_bf16_f32 v79, v92, v94
	v_bfe_u32 v21, v23, 16, 1
	v_lshl_add_u64 v[80:81], v[4:5], 0, s[8:9]
	v_add3_u32 v21, v23, v21, s33
	v_bfe_u32 v22, v83, 16, 1
	v_lshl_add_u64 v[96:97], v[80:81], 0, v[96:97]
	v_lshrrev_b32_e32 v21, 16, v21
	v_add3_u32 v22, v83, v22, s33
	global_store_dwordx4 v[96:97], v[76:79], off
	ds_read2_b32 v[82:83], v53 offset0:16 offset1:24
	v_add_u32_e32 v96, s0, v74
	v_and_or_b32 v76, v22, s34, v21
	v_cvt_pk_bf16_f32 v77, v85, v87
	v_cvt_pk_bf16_f32 v78, v89, v91
	v_cvt_pk_bf16_f32 v79, v93, v95
	v_add_u32_e32 v22, s0, v73
	v_ashrrev_i32_e32 v23, 31, v22
	v_lshlrev_b64 v[22:23], 11, v[22:23]
	v_lshl_add_u64 v[22:23], v[80:81], 0, v[22:23]
	global_store_dwordx4 v[22:23], v[76:79], off
	ds_read2_b32 v[22:23], v53 offset0:49 offset1:57
	ds_read2_b32 v[84:85], v53 offset0:82 offset1:90
	ds_read2_b32 v[86:87], v53 offset0:115 offset1:123
	s_waitcnt lgkmcnt(3)
	s_waitcnt lgkmcnt(2)
	ds_read2_b32 v[88:89], v53 offset0:148 offset1:156
	ds_read2_b32 v[90:91], v53 offset0:181 offset1:189
	v_cvt_pk_bf16_f32 v76, v82, v22
	s_waitcnt lgkmcnt(3)
	s_waitcnt lgkmcnt(2)
	ds_read2_b32 v[92:93], v53 offset0:214 offset1:222
	ds_read2_b32 v[94:95], v53 offset0:247 offset1:255
	v_cvt_pk_bf16_f32 v77, v84, v86
	s_waitcnt lgkmcnt(3)
	s_waitcnt lgkmcnt(2)
	v_cvt_pk_bf16_f32 v78, v88, v90
	s_waitcnt lgkmcnt(1)
	s_waitcnt lgkmcnt(0)
	v_cvt_pk_bf16_f32 v79, v92, v94
	v_ashrrev_i32_e32 v97, 31, v96
	v_lshlrev_b64 v[96:97], 11, v[96:97]
	v_lshl_add_u64 v[96:97], v[80:81], 0, v[96:97]
	global_store_dwordx4 v[96:97], v[76:79], off
	s_mov_b64 s[8:9], 0
	s_nop 0
	v_cvt_pk_bf16_f32 v76, v83, v23
	v_cvt_pk_bf16_f32 v77, v85, v87
	v_cvt_pk_bf16_f32 v78, v89, v91
	v_cvt_pk_bf16_f32 v79, v93, v95
	v_add_u32_e32 v22, s0, v75
	v_ashrrev_i32_e32 v23, 31, v22
	v_lshlrev_b64 v[22:23], 11, v[22:23]
	v_lshl_add_u64 v[22:23], v[80:81], 0, v[22:23]
	global_store_dwordx4 v[22:23], v[76:79], off
	s_waitcnt lgkmcnt(0)
.LBB0_17:
	s_andn2_b64 vcc, exec, s[8:9]
	s_cbranch_vccnz .LBB0_19
	s_and_b32 s0, s28, 0x7f0000
	s_add_i32 s0, s0, 0xff980000
	s_lshl_b64 s[8:9], s[0:1], 2
	v_readlane_b32 s16, v250, 0
	v_readlane_b32 s17, v250, 1
	s_add_u32 s37, s16, s8
	s_addc_u32 s39, s17, s9
	s_lshl_b64 s[10:11], s[0:1], 1
	s_add_u32 s9, s5, s10
	s_addc_u32 s8, s7, s11
	s_and_b32 s0, s30, 0xe0
	s_and_b32 s10, s12, 0xc0
	s_lshl_b32 s11, s0, 2
	s_add_u32 s38, s37, s11
	v_add_u32_e32 v76, s10, v25
	v_add_u32_e32 v78, s10, v28
	v_add_u32_e32 v80, s10, v29
	v_add_u32_e32 v82, s10, v30
	v_add_u32_e32 v84, s10, v31
	v_add_u32_e32 v86, s10, v32
	v_add_u32_e32 v88, s10, v33
	v_add_u32_e32 v90, s10, v35
	s_addc_u32 s39, s39, 0
	v_ashrrev_i32_e32 v77, 31, v76
	v_ashrrev_i32_e32 v79, 31, v78
	v_ashrrev_i32_e32 v81, 31, v80
	v_ashrrev_i32_e32 v83, 31, v82
	v_ashrrev_i32_e32 v85, 31, v84
	v_ashrrev_i32_e32 v87, 31, v86
	v_ashrrev_i32_e32 v89, 31, v88
	v_ashrrev_i32_e32 v91, 31, v90
	v_lshl_add_u64 v[22:23], s[38:39], 0, v[0:1]
	v_lshlrev_b64 v[76:77], 10, v[76:77]
	v_lshlrev_b64 v[78:79], 10, v[78:79]
	v_lshlrev_b64 v[80:81], 10, v[80:81]
	v_lshlrev_b64 v[82:83], 10, v[82:83]
	v_lshlrev_b64 v[84:85], 10, v[84:85]
	v_lshlrev_b64 v[86:87], 10, v[86:87]
	v_lshlrev_b64 v[88:89], 10, v[88:89]
	v_lshlrev_b64 v[90:91], 10, v[90:91]
	v_lshl_add_u64 v[76:77], v[22:23], 0, v[76:77]
	v_lshl_add_u64 v[78:79], v[22:23], 0, v[78:79]
	v_lshl_add_u64 v[80:81], v[22:23], 0, v[80:81]
	v_lshl_add_u64 v[82:83], v[22:23], 0, v[82:83]
; __device__ __forceinline__ void p0_transpose_item(const float* W, int Nsrc, bf16_t* WT, int Kdst, int k0, int src_col0, int dst_row0, LAS float* scr, int lane) {
;     ...
;     for (int i = 0; i < 32; ++i) { const int kk = 2 * i + (lane >> 5); scr[kk * 33 + (lane & 31)] = (src_col0 >= 0) ? W[(size_t)(k0 + kk) * Nsrc + src_col0 + (lane & 31)] : 0.f; }
; __device__ __forceinline__ void phase_prologue(const Prm& P, Ctx& C) {
;     ...
;         if (r < 128) { const int g = r >> 5, rr = r & 31, blk = rr >> 2, kb = rr & 3; p0_transpose_item(P.w_grp + g * 65536, 256, (bf16_t*)(ws + WS_W4T) + g * 65536, 256, 64 * kb, 32 * blk, 32 * blk, scr, C.lane); continue; } r -= 128;
	v_lshl_add_u64 v[84:85], v[22:23], 0, v[84:85]
	v_lshl_add_u64 v[86:87], v[22:23], 0, v[86:87]
	v_lshl_add_u64 v[88:89], v[22:23], 0, v[88:89]
	v_lshl_add_u64 v[90:91], v[22:23], 0, v[90:91]
	global_load_dword v21, v[76:77], off
	global_load_dword v92, v[78:79], off
	global_load_dword v93, v[80:81], off
	global_load_dword v94, v[82:83], off
	global_load_dword v95, v[84:85], off
	global_load_dword v96, v[86:87], off
	global_load_dword v97, v[88:89], off
	global_load_dword v98, v[90:91], off
	v_add_u32_e32 v76, s10, v36
	v_add_u32_e32 v78, s10, v37
	v_add_u32_e32 v80, s10, v38
	v_add_u32_e32 v82, s10, v39
	v_add_u32_e32 v84, s10, v40
	v_add_u32_e32 v86, s10, v42
	v_add_u32_e32 v88, s10, v43
	v_add_u32_e32 v90, s10, v44
	v_ashrrev_i32_e32 v77, 31, v76
	v_ashrrev_i32_e32 v79, 31, v78
	v_ashrrev_i32_e32 v81, 31, v80
	v_ashrrev_i32_e32 v83, 31, v82
	v_ashrrev_i32_e32 v85, 31, v84
	v_ashrrev_i32_e32 v87, 31, v86
	v_ashrrev_i32_e32 v89, 31, v88
	v_ashrrev_i32_e32 v91, 31, v90
	v_lshlrev_b64 v[76:77], 10, v[76:77]
	v_lshlrev_b64 v[78:79], 10, v[78:79]
	v_lshlrev_b64 v[80:81], 10, v[80:81]
	v_lshlrev_b64 v[82:83], 10, v[82:83]
	v_lshlrev_b64 v[84:85], 10, v[84:85]
	v_lshlrev_b64 v[86:87], 10, v[86:87]
	v_lshlrev_b64 v[88:89], 10, v[88:89]
	v_lshlrev_b64 v[90:91], 10, v[90:91]
	v_lshl_add_u64 v[76:77], v[22:23], 0, v[76:77]
	v_lshl_add_u64 v[78:79], v[22:23], 0, v[78:79]
	v_lshl_add_u64 v[80:81], v[22:23], 0, v[80:81]
	v_lshl_add_u64 v[82:83], v[22:23], 0, v[82:83]
	v_lshl_add_u64 v[84:85], v[22:23], 0, v[84:85]
	v_lshl_add_u64 v[86:87], v[22:23], 0, v[86:87]
	v_lshl_add_u64 v[88:89], v[22:23], 0, v[88:89]
	v_lshl_add_u64 v[90:91], v[22:23], 0, v[90:91]
	global_load_dword v99, v[76:77], off
	global_load_dword v100, v[78:79], off
	global_load_dword v101, v[80:81], off
	global_load_dword v102, v[82:83], off
	global_load_dword v103, v[84:85], off
	global_load_dword v104, v[86:87], off
	global_load_dword v105, v[88:89], off
	global_load_dword v106, v[90:91], off
	v_add_u32_e32 v76, s10, v45
	v_add_u32_e32 v78, s10, v46
	v_add_u32_e32 v80, s10, v47
	v_add_u32_e32 v82, s10, v49
	v_add_u32_e32 v84, s10, v50
	v_add_u32_e32 v86, s10, v51
	v_add_u32_e32 v88, s10, v62
	v_add_u32_e32 v90, s10, v63
	v_ashrrev_i32_e32 v77, 31, v76
	v_ashrrev_i32_e32 v79, 31, v78
	v_ashrrev_i32_e32 v81, 31, v80
	v_ashrrev_i32_e32 v83, 31, v82
	v_ashrrev_i32_e32 v85, 31, v84
	v_ashrrev_i32_e32 v87, 31, v86
	v_ashrrev_i32_e32 v89, 31, v88
	v_ashrrev_i32_e32 v91, 31, v90
	v_lshlrev_b64 v[76:77], 10, v[76:77]
	v_lshlrev_b64 v[78:79], 10, v[78:79]
	v_lshlrev_b64 v[80:81], 10, v[80:81]
	v_lshlrev_b64 v[82:83], 10, v[82:83]
	v_lshlrev_b64 v[84:85], 10, v[84:85]
	v_lshlrev_b64 v[86:87], 10, v[86:87]
	v_lshlrev_b64 v[88:89], 10, v[88:89]
	v_lshlrev_b64 v[90:91], 10, v[90:91]
	v_lshl_add_u64 v[76:77], v[22:23], 0, v[76:77]
	v_lshl_add_u64 v[78:79], v[22:23], 0, v[78:79]
	v_lshl_add_u64 v[80:81], v[22:23], 0, v[80:81]
	v_lshl_add_u64 v[82:83], v[22:23], 0, v[82:83]
	v_lshl_add_u64 v[84:85], v[22:23], 0, v[84:85]
	v_lshl_add_u64 v[86:87], v[22:23], 0, v[86:87]
	v_lshl_add_u64 v[88:89], v[22:23], 0, v[88:89]
	v_lshl_add_u64 v[90:91], v[22:23], 0, v[90:91]
	global_load_dword v107, v[76:77], off
	global_load_dword v108, v[78:79], off
	global_load_dword v109, v[80:81], off
	global_load_dword v110, v[82:83], off
	global_load_dword v111, v[84:85], off
	global_load_dword v112, v[86:87], off
	global_load_dword v113, v[88:89], off
	global_load_dword v114, v[90:91], off
	v_add_u32_e32 v76, s10, v64
	v_add_u32_e32 v78, s10, v66
	v_add_u32_e32 v80, s10, v67
	v_add_u32_e32 v82, s10, v68
	v_add_u32_e32 v84, s10, v69
	v_add_u32_e32 v86, s10, v70
	v_add_u32_e32 v88, s10, v71
	v_add_u32_e32 v90, s10, v72
	v_ashrrev_i32_e32 v77, 31, v76
	v_ashrrev_i32_e32 v79, 31, v78
	v_ashrrev_i32_e32 v81, 31, v80
	v_ashrrev_i32_e32 v83, 31, v82
	v_ashrrev_i32_e32 v85, 31, v84
	v_ashrrev_i32_e32 v87, 31, v86
	v_ashrrev_i32_e32 v89, 31, v88
	v_ashrrev_i32_e32 v91, 31, v90
	v_lshlrev_b64 v[76:77], 10, v[76:77]
	v_lshlrev_b64 v[78:79], 10, v[78:79]
	v_lshlrev_b64 v[80:81], 10, v[80:81]
	v_lshlrev_b64 v[82:83], 10, v[82:83]
	v_lshlrev_b64 v[84:85], 10, v[84:85]
	v_lshlrev_b64 v[86:87], 10, v[86:87]
	v_lshlrev_b64 v[88:89], 10, v[88:89]
	v_lshlrev_b64 v[90:91], 10, v[90:91]
	v_lshl_add_u64 v[76:77], v[22:23], 0, v[76:77]
	v_lshl_add_u64 v[78:79], v[22:23], 0, v[78:79]
	v_lshl_add_u64 v[80:81], v[22:23], 0, v[80:81]
	v_lshl_add_u64 v[82:83], v[22:23], 0, v[82:83]
	v_lshl_add_u64 v[84:85], v[22:23], 0, v[84:85]
	v_lshl_add_u64 v[86:87], v[22:23], 0, v[86:87]
	v_lshl_add_u64 v[88:89], v[22:23], 0, v[88:89]
	v_lshl_add_u64 v[22:23], v[22:23], 0, v[90:91]
	global_load_dword v76, v[76:77], off
	s_nop 0
	global_load_dword v77, v[78:79], off
	s_nop 0
	global_load_dword v78, v[80:81], off
	global_load_dword v79, v[82:83], off
	s_nop 0
	global_load_dword v80, v[84:85], off
	global_load_dword v81, v[86:87], off
	global_load_dword v82, v[88:89], off
	s_nop 0
	global_load_dword v22, v[22:23], off
	v_add_u32_e32 v23, v26, v27
	s_waitcnt vmcnt(30)
; #define LAS __attribute__((address_space(3)))
; __device__ __forceinline__ unsigned pk2(float lo, float hi) { return f2bf(lo) | (f2bf(hi) << 16); }
; #define LDS_WAIT() asm volatile("s_waitcnt lgkmcnt(0)" ::: "memory")
; __device__ __forceinline__ void p0_transpose_item(const float* W, int Nsrc, bf16_t* WT, int Kdst, int k0, int src_col0, int dst_row0, LAS float* scr, int lane) {
;     ...
;     LDS_WAIT();
;     const int c = lane & 7;
; #pragma unroll
;     for (int j = 0; j < 4; ++j) { const int n = (lane >> 3) + 8 * j; const LAS float* s = scr + (8 * c) * 33 + n;
;         u32x4 o; o.x = pk2(s[0 * 33], s[1 * 33]); o.y = pk2(s[2 * 33], s[3 * 33]); o.z = pk2(s[4 * 33], s[5 * 33]); o.w = pk2(s[6 * 33], s[7 * 33]);
;         *(u32x4*)(WT + (size_t)(dst_row0 + n) * Kdst + k0 + 8 * c) = o; }
; __device__ __forceinline__ void phase_prologue(const Prm& P, Ctx& C) {
;     ...
;         if (r < 128) { const int g = r >> 5, rr = r & 31, blk = rr >> 2, kb = rr & 3; p0_transpose_item(P.w_grp + g * 65536, 256, (bf16_t*)(ws + WS_W4T) + g * 65536, 256, 64 * kb, 32 * blk, 32 * blk, scr, C.lane); continue; } r -= 128;
	ds_write2_b32 v23, v21, v92 offset1:66
	s_waitcnt vmcnt(28)
	ds_write2_b32 v23, v93, v94 offset0:132 offset1:198
	v_add_u32_e32 v21, 0x400, v23
	s_waitcnt vmcnt(26)
	ds_write2_b32 v21, v95, v96 offset0:8 offset1:74
	v_add_u32_e32 v21, v26, v34
	s_waitcnt vmcnt(24)
	ds_write2_b32 v21, v97, v98 offset1:66
	s_waitcnt vmcnt(22)
	ds_write2_b32 v21, v99, v100 offset0:132 offset1:198
	v_add_u32_e32 v21, 0x400, v21
	s_waitcnt vmcnt(20)
	ds_write2_b32 v21, v101, v102 offset0:8 offset1:74
	v_add_u32_e32 v21, v26, v41
	s_waitcnt vmcnt(18)
	ds_write2_b32 v21, v103, v104 offset1:66
	s_waitcnt vmcnt(16)
	ds_write2_b32 v21, v105, v106 offset0:132 offset1:198
	v_add_u32_e32 v21, 0x400, v21
	s_lshl_b32 s10, s10, 1
	s_add_u32 s10, s9, s10
	s_addc_u32 s11, s8, 0
	v_add_u32_e32 v96, s0, v52
	v_ashrrev_i32_e32 v97, 31, v96
	v_lshlrev_b64 v[96:97], 9, v[96:97]
	v_readlane_b32 s18, v250, 2
	v_readlane_b32 s19, v250, 3
	v_readlane_b32 s20, v250, 4
	v_readlane_b32 s21, v250, 5
	v_readlane_b32 s22, v250, 6
	v_readlane_b32 s23, v250, 7
	s_waitcnt vmcnt(14)
	ds_write2_b32 v21, v107, v108 offset0:8 offset1:74
	v_add_u32_e32 v21, v26, v48
	s_waitcnt vmcnt(12)
	ds_write2_b32 v21, v109, v110 offset1:66
	s_waitcnt vmcnt(10)
	ds_write2_b32 v21, v111, v112 offset0:132 offset1:198
	v_add_u32_e32 v21, 0x400, v21
	s_waitcnt vmcnt(8)
	ds_write2_b32 v21, v113, v114 offset0:8 offset1:74
	v_add_u32_e32 v21, v26, v65
	s_waitcnt vmcnt(6)
	ds_write2_b32 v21, v76, v77 offset1:66
	s_waitcnt vmcnt(4)
	ds_write2_b32 v21, v78, v79 offset0:132 offset1:198
	v_add_u32_e32 v21, 0x400, v21
	s_waitcnt vmcnt(2)
	ds_write2_b32 v21, v80, v81 offset0:8 offset1:74
	s_waitcnt vmcnt(0)
	ds_write2_b32 v21, v82, v22 offset0:140 offset1:206
	s_waitcnt lgkmcnt(0)
	ds_read2_b32 v[22:23], v53 offset1:8
	ds_read2_b32 v[82:83], v53 offset0:33 offset1:41
	ds_read2_b32 v[84:85], v53 offset0:66 offset1:74
	v_mov_b32_e32 v21, v1
	ds_read2_b32 v[86:87], v53 offset0:99 offset1:107
	v_lshl_add_u64 v[80:81], s[10:11], 0, v[20:21]
	s_waitcnt lgkmcnt(3)
	s_waitcnt lgkmcnt(2)
	ds_read2_b32 v[88:89], v53 offset0:132 offset1:140
	ds_read2_b32 v[90:91], v53 offset0:165 offset1:173
	v_cvt_pk_bf16_f32 v76, v22, v82
	s_waitcnt lgkmcnt(3)
	s_waitcnt lgkmcnt(2)
	ds_read2_b32 v[92:93], v53 offset0:198 offset1:206
	ds_read2_b32 v[94:95], v53 offset0:231 offset1:239
	v_cvt_pk_bf16_f32 v77, v84, v86
	s_waitcnt lgkmcnt(3)
	s_waitcnt lgkmcnt(2)
	v_cvt_pk_bf16_f32 v78, v88, v90
	s_waitcnt lgkmcnt(1)
	s_waitcnt lgkmcnt(0)
	v_cvt_pk_bf16_f32 v79, v92, v94
	v_bfe_u32 v21, v23, 16, 1
	v_add3_u32 v21, v23, v21, s33
	v_bfe_u32 v22, v83, 16, 1
	v_lshl_add_u64 v[96:97], v[80:81], 0, v[96:97]
	v_lshrrev_b32_e32 v21, 16, v21
	v_add3_u32 v22, v83, v22, s33
	global_store_dwordx4 v[96:97], v[76:79], off
	ds_read2_b32 v[82:83], v53 offset0:16 offset1:24
	v_add_u32_e32 v96, s0, v74
	v_and_or_b32 v76, v22, s34, v21
	v_cvt_pk_bf16_f32 v77, v85, v87
	v_cvt_pk_bf16_f32 v78, v89, v91
	v_cvt_pk_bf16_f32 v79, v93, v95
	v_add_u32_e32 v22, s0, v73
	v_ashrrev_i32_e32 v23, 31, v22
	v_lshlrev_b64 v[22:23], 9, v[22:23]
	v_lshl_add_u64 v[22:23], v[80:81], 0, v[22:23]
	global_store_dwordx4 v[22:23], v[76:79], off
	ds_read2_b32 v[22:23], v53 offset0:49 offset1:57
	ds_read2_b32 v[84:85], v53 offset0:82 offset1:90
	ds_read2_b32 v[86:87], v53 offset0:115 offset1:123
	s_waitcnt lgkmcnt(3)
	s_waitcnt lgkmcnt(2)
	ds_read2_b32 v[88:89], v53 offset0:148 offset1:156
	ds_read2_b32 v[90:91], v53 offset0:181 offset1:189
	v_cvt_pk_bf16_f32 v76, v82, v22
	s_waitcnt lgkmcnt(3)
	s_waitcnt lgkmcnt(2)
	ds_read2_b32 v[92:93], v53 offset0:214 offset1:222
	ds_read2_b32 v[94:95], v53 offset0:247 offset1:255
	v_cvt_pk_bf16_f32 v77, v84, v86
	s_waitcnt lgkmcnt(3)
	s_waitcnt lgkmcnt(2)
	v_cvt_pk_bf16_f32 v78, v88, v90
	s_waitcnt lgkmcnt(1)
	s_waitcnt lgkmcnt(0)
	v_cvt_pk_bf16_f32 v79, v92, v94
	v_ashrrev_i32_e32 v97, 31, v96
	v_lshlrev_b64 v[96:97], 9, v[96:97]
	v_lshl_add_u64 v[96:97], v[80:81], 0, v[96:97]
	global_store_dwordx4 v[96:97], v[76:79], off
	s_nop 1
	v_cvt_pk_bf16_f32 v76, v83, v23
	v_cvt_pk_bf16_f32 v77, v85, v87
	v_cvt_pk_bf16_f32 v78, v89, v91
	v_cvt_pk_bf16_f32 v79, v93, v95
	v_add_u32_e32 v22, s0, v75
	v_ashrrev_i32_e32 v23, 31, v22
	v_lshlrev_b64 v[22:23], 9, v[22:23]
	v_lshl_add_u64 v[22:23], v[80:81], 0, v[22:23]
	global_store_dwordx4 v[22:23], v[76:79], off
	s_waitcnt lgkmcnt(0)

; #define LAS __attribute__((address_space(3)))
; __device__ __forceinline__ void p0_transpose_item(const float* W, int Nsrc, bf16_t* WT, int Kdst, int k0, int src_col0, int dst_row0, LAS float* scr, int lane) {
; #pragma unroll
;     for (int i = 0; i < 32; ++i) { const int kk = 2 * i + (lane >> 5); scr[kk * 33 + (lane & 31)] = (src_col0 >= 0) ? W[(size_t)(k0 + kk) * Nsrc + src_col0 + (lane & 31)] : 0.f; }
; __device__ __forceinline__ void phase_prologue(const Prm& P, Ctx& C) {
;     ...
;         if (r < 1024) { const int blk = r >> 4, kb = r & 15; p0_transpose_item(P.w_in_odd, 2048, (bf16_t*)(ws + WS_W3T), 1024, 64 * kb, 32 * blk, 32 * blk, scr, C.lane); continue; } r -= 1024;
.LBB0_20:
	s_andn2_b64 vcc, exec, s[8:9]
	s_cbranch_vccnz .LBB0_22
	s_and_b32 s8, s12, 0x3c0
	s_and_b32 s0, s24, 0x1fe0
	v_add_u32_e32 v76, s8, v25
	v_add_u32_e32 v78, s8, v28
	v_add_u32_e32 v80, s8, v29
	v_add_u32_e32 v82, s8, v30
	v_add_u32_e32 v84, s8, v31
	v_add_u32_e32 v86, s8, v32
	v_add_u32_e32 v88, s8, v33
	v_add_u32_e32 v90, s8, v35
	s_addk_i32 s0, 0xee00
	v_ashrrev_i32_e32 v77, 31, v76
	v_ashrrev_i32_e32 v79, 31, v78
	v_ashrrev_i32_e32 v81, 31, v80
	v_ashrrev_i32_e32 v83, 31, v82
	v_ashrrev_i32_e32 v85, 31, v84
	v_ashrrev_i32_e32 v87, 31, v86
	v_ashrrev_i32_e32 v89, 31, v88
	v_ashrrev_i32_e32 v91, 31, v90
	v_lshl_add_u64 v[22:23], s[0:1], 2, v[6:7]
	v_lshlrev_b64 v[76:77], 13, v[76:77]
	v_lshlrev_b64 v[78:79], 13, v[78:79]
	v_lshlrev_b64 v[80:81], 13, v[80:81]
	v_lshlrev_b64 v[82:83], 13, v[82:83]
	v_lshlrev_b64 v[84:85], 13, v[84:85]
	v_lshlrev_b64 v[86:87], 13, v[86:87]
	v_lshlrev_b64 v[88:89], 13, v[88:89]
	v_lshlrev_b64 v[90:91], 13, v[90:91]
	v_lshl_add_u64 v[76:77], v[22:23], 0, v[76:77]
	v_lshl_add_u64 v[78:79], v[22:23], 0, v[78:79]
	v_lshl_add_u64 v[80:81], v[22:23], 0, v[80:81]
	v_lshl_add_u64 v[82:83], v[22:23], 0, v[82:83]
	v_lshl_add_u64 v[84:85], v[22:23], 0, v[84:85]
	v_lshl_add_u64 v[86:87], v[22:23], 0, v[86:87]
	v_lshl_add_u64 v[88:89], v[22:23], 0, v[88:89]
	v_lshl_add_u64 v[90:91], v[22:23], 0, v[90:91]
	global_load_dword v21, v[76:77], off
	global_load_dword v92, v[78:79], off
	global_load_dword v93, v[80:81], off
	global_load_dword v94, v[82:83], off
	global_load_dword v95, v[84:85], off
	global_load_dword v96, v[86:87], off
	global_load_dword v97, v[88:89], off
	global_load_dword v98, v[90:91], off
	v_add_u32_e32 v76, s8, v36
	v_add_u32_e32 v78, s8, v37
	v_add_u32_e32 v80, s8, v38
	v_add_u32_e32 v82, s8, v39
	v_add_u32_e32 v84, s8, v40
	v_add_u32_e32 v86, s8, v42
	v_add_u32_e32 v88, s8, v43
	v_add_u32_e32 v90, s8, v44
	v_ashrrev_i32_e32 v77, 31, v76
	v_ashrrev_i32_e32 v79, 31, v78
	v_ashrrev_i32_e32 v81, 31, v80
	v_ashrrev_i32_e32 v83, 31, v82
	v_ashrrev_i32_e32 v85, 31, v84
	v_ashrrev_i32_e32 v87, 31, v86
	v_ashrrev_i32_e32 v89, 31, v88
	v_ashrrev_i32_e32 v91, 31, v90
	v_lshlrev_b64 v[76:77], 13, v[76:77]
	v_lshlrev_b64 v[78:79], 13, v[78:79]
	v_lshlrev_b64 v[80:81], 13, v[80:81]
	v_lshlrev_b64 v[82:83], 13, v[82:83]
	v_lshlrev_b64 v[84:85], 13, v[84:85]
	v_lshlrev_b64 v[86:87], 13, v[86:87]
	v_lshlrev_b64 v[88:89], 13, v[88:89]
	v_lshlrev_b64 v[90:91], 13, v[90:91]
	v_lshl_add_u64 v[76:77], v[22:23], 0, v[76:77]
	v_lshl_add_u64 v[78:79], v[22:23], 0, v[78:79]
	v_lshl_add_u64 v[80:81], v[22:23], 0, v[80:81]
	v_lshl_add_u64 v[82:83], v[22:23], 0, v[82:83]
	v_lshl_add_u64 v[84:85], v[22:23], 0, v[84:85]
	v_lshl_add_u64 v[86:87], v[22:23], 0, v[86:87]
	v_lshl_add_u64 v[88:89], v[22:23], 0, v[88:89]
	v_lshl_add_u64 v[90:91], v[22:23], 0, v[90:91]
	global_load_dword v99, v[76:77], off
	global_load_dword v100, v[78:79], off
	global_load_dword v101, v[80:81], off
	global_load_dword v102, v[82:83], off
	global_load_dword v103, v[84:85], off
	global_load_dword v104, v[86:87], off
	global_load_dword v105, v[88:89], off
	global_load_dword v106, v[90:91], off
	v_add_u32_e32 v76, s8, v45
	v_add_u32_e32 v78, s8, v46
	v_add_u32_e32 v80, s8, v47
	v_add_u32_e32 v82, s8, v49
	v_add_u32_e32 v84, s8, v50
	v_add_u32_e32 v86, s8, v51
	v_add_u32_e32 v88, s8, v62
	v_add_u32_e32 v90, s8, v63
	v_ashrrev_i32_e32 v77, 31, v76
	v_ashrrev_i32_e32 v79, 31, v78
	v_ashrrev_i32_e32 v81, 31, v80
	v_ashrrev_i32_e32 v83, 31, v82
	v_ashrrev_i32_e32 v85, 31, v84
	v_ashrrev_i32_e32 v87, 31, v86
	v_ashrrev_i32_e32 v89, 31, v88
	v_ashrrev_i32_e32 v91, 31, v90
	v_lshlrev_b64 v[76:77], 13, v[76:77]
	v_lshlrev_b64 v[78:79], 13, v[78:79]
	v_lshlrev_b64 v[80:81], 13, v[80:81]
	v_lshlrev_b64 v[82:83], 13, v[82:83]
	v_lshlrev_b64 v[84:85], 13, v[84:85]
	v_lshlrev_b64 v[86:87], 13, v[86:87]
	v_lshlrev_b64 v[88:89], 13, v[88:89]
	v_lshlrev_b64 v[90:91], 13, v[90:91]
	v_lshl_add_u64 v[76:77], v[22:23], 0, v[76:77]
	v_lshl_add_u64 v[78:79], v[22:23], 0, v[78:79]
	v_lshl_add_u64 v[80:81], v[22:23], 0, v[80:81]
	v_lshl_add_u64 v[82:83], v[22:23], 0, v[82:83]
	v_lshl_add_u64 v[84:85], v[22:23], 0, v[84:85]
	v_lshl_add_u64 v[86:87], v[22:23], 0, v[86:87]
	v_lshl_add_u64 v[88:89], v[22:23], 0, v[88:89]
	v_lshl_add_u64 v[90:91], v[22:23], 0, v[90:91]
	global_load_dword v107, v[76:77], off
	global_load_dword v108, v[78:79], off
	global_load_dword v109, v[80:81], off
	global_load_dword v110, v[82:83], off
	global_load_dword v111, v[84:85], off
	global_load_dword v112, v[86:87], off
	global_load_dword v113, v[88:89], off
	global_load_dword v114, v[90:91], off
	v_add_u32_e32 v76, s8, v64
	v_add_u32_e32 v78, s8, v66
	v_add_u32_e32 v80, s8, v67
	v_add_u32_e32 v82, s8, v68
	v_add_u32_e32 v84, s8, v69
	v_add_u32_e32 v86, s8, v70
	v_add_u32_e32 v88, s8, v71
	v_add_u32_e32 v90, s8, v72
	v_ashrrev_i32_e32 v77, 31, v76
	v_ashrrev_i32_e32 v79, 31, v78
	v_ashrrev_i32_e32 v81, 31, v80
	v_ashrrev_i32_e32 v83, 31, v82
	v_ashrrev_i32_e32 v85, 31, v84
	v_ashrrev_i32_e32 v87, 31, v86
	v_ashrrev_i32_e32 v89, 31, v88
	v_ashrrev_i32_e32 v91, 31, v90
	v_lshlrev_b64 v[76:77], 13, v[76:77]
	v_lshlrev_b64 v[78:79], 13, v[78:79]
	v_lshlrev_b64 v[80:81], 13, v[80:81]
	v_lshlrev_b64 v[82:83], 13, v[82:83]
	v_lshlrev_b64 v[84:85], 13, v[84:85]
	v_lshlrev_b64 v[86:87], 13, v[86:87]
	v_lshlrev_b64 v[88:89], 13, v[88:89]
	v_lshlrev_b64 v[90:91], 13, v[90:91]
	v_lshl_add_u64 v[76:77], v[22:23], 0, v[76:77]
	v_lshl_add_u64 v[78:79], v[22:23], 0, v[78:79]
	v_lshl_add_u64 v[80:81], v[22:23], 0, v[80:81]
	v_lshl_add_u64 v[82:83], v[22:23], 0, v[82:83]
	v_lshl_add_u64 v[84:85], v[22:23], 0, v[84:85]
	v_lshl_add_u64 v[86:87], v[22:23], 0, v[86:87]
	v_lshl_add_u64 v[88:89], v[22:23], 0, v[88:89]
	v_lshl_add_u64 v[22:23], v[22:23], 0, v[90:91]
	global_load_dword v76, v[76:77], off
	s_nop 0
	global_load_dword v77, v[78:79], off
	s_nop 0
	global_load_dword v78, v[80:81], off
	global_load_dword v79, v[82:83], off
	s_nop 0
	global_load_dword v80, v[84:85], off
	global_load_dword v81, v[86:87], off
	global_load_dword v82, v[88:89], off
	s_nop 0
	global_load_dword v22, v[22:23], off
	v_add_u32_e32 v23, v26, v27
	s_waitcnt vmcnt(30)
; #define LAS __attribute__((address_space(3)))
; __device__ __forceinline__ unsigned pk2(float lo, float hi) { return f2bf(lo) | (f2bf(hi) << 16); }
; #define LDS_WAIT() asm volatile("s_waitcnt lgkmcnt(0)" ::: "memory")
; __device__ __forceinline__ void p0_transpose_item(const float* W, int Nsrc, bf16_t* WT, int Kdst, int k0, int src_col0, int dst_row0, LAS float* scr, int lane) {
;     ...
;     LDS_WAIT();
;     const int c = lane & 7;
; #pragma unroll
;     for (int j = 0; j < 4; ++j) { const int n = (lane >> 3) + 8 * j; const LAS float* s = scr + (8 * c) * 33 + n;
;         u32x4 o; o.x = pk2(s[0 * 33], s[1 * 33]); o.y = pk2(s[2 * 33], s[3 * 33]); o.z = pk2(s[4 * 33], s[5 * 33]); o.w = pk2(s[6 * 33], s[7 * 33]);
;         *(u32x4*)(WT + (size_t)(dst_row0 + n) * Kdst + k0 + 8 * c) = o; }
; __device__ __forceinline__ void phase_prologue(const Prm& P, Ctx& C) {
;     ...
;         if (r < 1024) { const int blk = r >> 4, kb = r & 15; p0_transpose_item(P.w_in_odd, 2048, (bf16_t*)(ws + WS_W3T), 1024, 64 * kb, 32 * blk, 32 * blk, scr, C.lane); continue; } r -= 1024;
	ds_write2_b32 v23, v21, v92 offset1:66
	s_waitcnt vmcnt(28)
	ds_write2_b32 v23, v93, v94 offset0:132 offset1:198
	v_add_u32_e32 v21, 0x400, v23
	s_waitcnt vmcnt(26)
	ds_write2_b32 v21, v95, v96 offset0:8 offset1:74
	v_add_u32_e32 v21, v26, v34
	s_waitcnt vmcnt(24)
	ds_write2_b32 v21, v97, v98 offset1:66
	s_waitcnt vmcnt(22)
	ds_write2_b32 v21, v99, v100 offset0:132 offset1:198
	v_add_u32_e32 v21, 0x400, v21
	s_waitcnt vmcnt(20)
	ds_write2_b32 v21, v101, v102 offset0:8 offset1:74
	v_add_u32_e32 v21, v26, v41
	s_waitcnt vmcnt(18)
	ds_write2_b32 v21, v103, v104 offset1:66
	s_waitcnt vmcnt(16)
	ds_write2_b32 v21, v105, v106 offset0:132 offset1:198
	v_add_u32_e32 v21, 0x400, v21
	v_add_u32_e32 v96, s0, v52
	s_lshl_b32 s8, s8, 1
	s_mov_b32 s9, s1
	v_ashrrev_i32_e32 v97, 31, v96
	v_lshlrev_b64 v[96:97], 11, v[96:97]
	s_waitcnt vmcnt(14)
	ds_write2_b32 v21, v107, v108 offset0:8 offset1:74
	v_add_u32_e32 v21, v26, v48
	s_waitcnt vmcnt(12)
	ds_write2_b32 v21, v109, v110 offset1:66
	s_waitcnt vmcnt(10)
	ds_write2_b32 v21, v111, v112 offset0:132 offset1:198
	v_add_u32_e32 v21, 0x400, v21
	s_waitcnt vmcnt(8)
	ds_write2_b32 v21, v113, v114 offset0:8 offset1:74
	v_add_u32_e32 v21, v26, v65
	s_waitcnt vmcnt(6)
	ds_write2_b32 v21, v76, v77 offset1:66
	s_waitcnt vmcnt(4)
	ds_write2_b32 v21, v78, v79 offset0:132 offset1:198
	v_add_u32_e32 v21, 0x400, v21
	s_waitcnt vmcnt(2)
	ds_write2_b32 v21, v80, v81 offset0:8 offset1:74
	s_waitcnt vmcnt(0)
	ds_write2_b32 v21, v82, v22 offset0:140 offset1:206
	s_waitcnt lgkmcnt(0)
	ds_read2_b32 v[22:23], v53 offset1:8
	ds_read2_b32 v[82:83], v53 offset0:33 offset1:41
	ds_read2_b32 v[84:85], v53 offset0:66 offset1:74
	ds_read2_b32 v[86:87], v53 offset0:99 offset1:107
	ds_read2_b32 v[88:89], v53 offset0:132 offset1:140
	s_waitcnt lgkmcnt(4)
	s_waitcnt lgkmcnt(3)
	ds_read2_b32 v[90:91], v53 offset0:165 offset1:173
	v_cvt_pk_bf16_f32 v76, v22, v82
	s_waitcnt lgkmcnt(3)
	s_waitcnt lgkmcnt(2)
	ds_read2_b32 v[92:93], v53 offset0:198 offset1:206
	ds_read2_b32 v[94:95], v53 offset0:231 offset1:239
	v_cvt_pk_bf16_f32 v77, v84, v86
	s_waitcnt lgkmcnt(3)
	s_waitcnt lgkmcnt(2)
	v_cvt_pk_bf16_f32 v78, v88, v90
	s_waitcnt lgkmcnt(1)
	s_waitcnt lgkmcnt(0)
	v_cvt_pk_bf16_f32 v79, v92, v94
	v_bfe_u32 v21, v23, 16, 1
	v_lshl_add_u64 v[80:81], v[8:9], 0, s[8:9]
	v_add3_u32 v21, v23, v21, s33
	v_bfe_u32 v22, v83, 16, 1
	v_lshl_add_u64 v[96:97], v[80:81], 0, v[96:97]
	v_lshrrev_b32_e32 v21, 16, v21
	v_add3_u32 v22, v83, v22, s33
	global_store_dwordx4 v[96:97], v[76:79], off
	ds_read2_b32 v[82:83], v53 offset0:16 offset1:24
	v_add_u32_e32 v96, s0, v74
	v_and_or_b32 v76, v22, s34, v21
	v_cvt_pk_bf16_f32 v77, v85, v87
	v_cvt_pk_bf16_f32 v78, v89, v91
	v_cvt_pk_bf16_f32 v79, v93, v95
	v_add_u32_e32 v22, s0, v73
	v_ashrrev_i32_e32 v23, 31, v22
	v_lshlrev_b64 v[22:23], 11, v[22:23]
	v_lshl_add_u64 v[22:23], v[80:81], 0, v[22:23]
	global_store_dwordx4 v[22:23], v[76:79], off
	ds_read2_b32 v[22:23], v53 offset0:49 offset1:57
	ds_read2_b32 v[84:85], v53 offset0:82 offset1:90
	ds_read2_b32 v[86:87], v53 offset0:115 offset1:123
	s_waitcnt lgkmcnt(3)
	s_waitcnt lgkmcnt(2)
	ds_read2_b32 v[88:89], v53 offset0:148 offset1:156
	ds_read2_b32 v[90:91], v53 offset0:181 offset1:189
	v_cvt_pk_bf16_f32 v76, v82, v22
	s_waitcnt lgkmcnt(3)
	s_waitcnt lgkmcnt(2)
	ds_read2_b32 v[92:93], v53 offset0:214 offset1:222
	ds_read2_b32 v[94:95], v53 offset0:247 offset1:255
	v_cvt_pk_bf16_f32 v77, v84, v86
	s_waitcnt lgkmcnt(3)
	s_waitcnt lgkmcnt(2)
	v_cvt_pk_bf16_f32 v78, v88, v90
	s_waitcnt lgkmcnt(1)
	s_waitcnt lgkmcnt(0)
	v_cvt_pk_bf16_f32 v79, v92, v94
	v_ashrrev_i32_e32 v97, 31, v96
	v_lshlrev_b64 v[96:97], 11, v[96:97]
	v_lshl_add_u64 v[96:97], v[80:81], 0, v[96:97]
	global_store_dwordx4 v[96:97], v[76:79], off
	s_nop 1
	v_cvt_pk_bf16_f32 v76, v83, v23
	v_cvt_pk_bf16_f32 v77, v85, v87
	v_cvt_pk_bf16_f32 v78, v89, v91
	v_cvt_pk_bf16_f32 v79, v93, v95
	v_add_u32_e32 v22, s0, v75
	v_ashrrev_i32_e32 v23, 31, v22
	v_lshlrev_b64 v[22:23], 11, v[22:23]
	v_lshl_add_u64 v[22:23], v[80:81], 0, v[22:23]
	global_store_dwordx4 v[22:23], v[76:79], off
	s_waitcnt lgkmcnt(0)

; #define LAS __attribute__((address_space(3)))
; __device__ __forceinline__ void p0_transpose_item(const float* W, int Nsrc, bf16_t* WT, int Kdst, int k0, int src_col0, int dst_row0, LAS float* scr, int lane) {
; #pragma unroll
;     for (int i = 0; i < 32; ++i) { const int kk = 2 * i + (lane >> 5); scr[kk * 33 + (lane & 31)] = (src_col0 >= 0) ? W[(size_t)(k0 + kk) * Nsrc + src_col0 + (lane & 31)] : 0.f; }
; __device__ __forceinline__ void phase_prologue(const Prm& P, Ctx& C) {
;     ...
;         if (r < 512) { const int blk = r >> 4, kb = r & 15; p0_transpose_item(P.w_out_even, 1024, (bf16_t*)(ws + WS_W2T), 1024, 64 * kb, 32 * blk, 32 * blk, scr, C.lane); continue; } r -= 512;
.LBB0_23:
	s_andn2_b64 vcc, exec, s[8:9]
	s_cbranch_vccnz .LBB0_25
	s_and_b32 s8, s12, 0x3c0
	s_and_b32 s0, s24, 0x1fe0
	v_add_u32_e32 v76, s8, v25
	v_add_u32_e32 v78, s8, v28
	v_add_u32_e32 v80, s8, v29
	v_add_u32_e32 v82, s8, v30
	v_add_u32_e32 v84, s8, v31
	v_add_u32_e32 v86, s8, v32
	v_add_u32_e32 v88, s8, v33
	v_add_u32_e32 v90, s8, v35
	s_addk_i32 s0, 0xf200
	v_ashrrev_i32_e32 v77, 31, v76
	v_ashrrev_i32_e32 v79, 31, v78
	v_ashrrev_i32_e32 v81, 31, v80
	v_ashrrev_i32_e32 v83, 31, v82
	v_ashrrev_i32_e32 v85, 31, v84
	v_ashrrev_i32_e32 v87, 31, v86
	v_ashrrev_i32_e32 v89, 31, v88
	v_ashrrev_i32_e32 v91, 31, v90
	v_lshl_add_u64 v[22:23], s[0:1], 2, v[10:11]
	v_lshlrev_b64 v[76:77], 12, v[76:77]
	v_lshlrev_b64 v[78:79], 12, v[78:79]
	v_lshlrev_b64 v[80:81], 12, v[80:81]
	v_lshlrev_b64 v[82:83], 12, v[82:83]
	v_lshlrev_b64 v[84:85], 12, v[84:85]
	v_lshlrev_b64 v[86:87], 12, v[86:87]
	v_lshlrev_b64 v[88:89], 12, v[88:89]
	v_lshlrev_b64 v[90:91], 12, v[90:91]
	v_lshl_add_u64 v[76:77], v[22:23], 0, v[76:77]
	v_lshl_add_u64 v[78:79], v[22:23], 0, v[78:79]
	v_lshl_add_u64 v[80:81], v[22:23], 0, v[80:81]
	v_lshl_add_u64 v[82:83], v[22:23], 0, v[82:83]
	v_lshl_add_u64 v[84:85], v[22:23], 0, v[84:85]
	v_lshl_add_u64 v[86:87], v[22:23], 0, v[86:87]
	v_lshl_add_u64 v[88:89], v[22:23], 0, v[88:89]
	v_lshl_add_u64 v[90:91], v[22:23], 0, v[90:91]
	global_load_dword v21, v[76:77], off
	global_load_dword v92, v[78:79], off
	global_load_dword v93, v[80:81], off
	global_load_dword v94, v[82:83], off
	global_load_dword v95, v[84:85], off
	global_load_dword v96, v[86:87], off
	global_load_dword v97, v[88:89], off
	global_load_dword v98, v[90:91], off
	v_add_u32_e32 v76, s8, v36
	v_add_u32_e32 v78, s8, v37
	v_add_u32_e32 v80, s8, v38
	v_add_u32_e32 v82, s8, v39
	v_add_u32_e32 v84, s8, v40
	v_add_u32_e32 v86, s8, v42
	v_add_u32_e32 v88, s8, v43
	v_add_u32_e32 v90, s8, v44
	v_ashrrev_i32_e32 v77, 31, v76
	v_ashrrev_i32_e32 v79, 31, v78
	v_ashrrev_i32_e32 v81, 31, v80
	v_ashrrev_i32_e32 v83, 31, v82
	v_ashrrev_i32_e32 v85, 31, v84
	v_ashrrev_i32_e32 v87, 31, v86
	v_ashrrev_i32_e32 v89, 31, v88
	v_ashrrev_i32_e32 v91, 31, v90
	v_lshlrev_b64 v[76:77], 12, v[76:77]
	v_lshlrev_b64 v[78:79], 12, v[78:79]
	v_lshlrev_b64 v[80:81], 12, v[80:81]
	v_lshlrev_b64 v[82:83], 12, v[82:83]
	v_lshlrev_b64 v[84:85], 12, v[84:85]
	v_lshlrev_b64 v[86:87], 12, v[86:87]
	v_lshlrev_b64 v[88:89], 12, v[88:89]
	v_lshlrev_b64 v[90:91], 12, v[90:91]
	v_lshl_add_u64 v[76:77], v[22:23], 0, v[76:77]
	v_lshl_add_u64 v[78:79], v[22:23], 0, v[78:79]
	v_lshl_add_u64 v[80:81], v[22:23], 0, v[80:81]
	v_lshl_add_u64 v[82:83], v[22:23], 0, v[82:83]
	v_lshl_add_u64 v[84:85], v[22:23], 0, v[84:85]
	v_lshl_add_u64 v[86:87], v[22:23], 0, v[86:87]
	v_lshl_add_u64 v[88:89], v[22:23], 0, v[88:89]
	v_lshl_add_u64 v[90:91], v[22:23], 0, v[90:91]
	global_load_dword v99, v[76:77], off
	global_load_dword v100, v[78:79], off
	global_load_dword v101, v[80:81], off
	global_load_dword v102, v[82:83], off
	global_load_dword v103, v[84:85], off
	global_load_dword v104, v[86:87], off
	global_load_dword v105, v[88:89], off
	global_load_dword v106, v[90:91], off
	v_add_u32_e32 v76, s8, v45
	v_add_u32_e32 v78, s8, v46
	v_add_u32_e32 v80, s8, v47
	v_add_u32_e32 v82, s8, v49
	v_add_u32_e32 v84, s8, v50
	v_add_u32_e32 v86, s8, v51
	v_add_u32_e32 v88, s8, v62
	v_add_u32_e32 v90, s8, v63
	v_ashrrev_i32_e32 v77, 31, v76
	v_ashrrev_i32_e32 v79, 31, v78
	v_ashrrev_i32_e32 v81, 31, v80
	v_ashrrev_i32_e32 v83, 31, v82
	v_ashrrev_i32_e32 v85, 31, v84
	v_ashrrev_i32_e32 v87, 31, v86
	v_ashrrev_i32_e32 v89, 31, v88
	v_ashrrev_i32_e32 v91, 31, v90
	v_lshlrev_b64 v[76:77], 12, v[76:77]
	v_lshlrev_b64 v[78:79], 12, v[78:79]
	v_lshlrev_b64 v[80:81], 12, v[80:81]
	v_lshlrev_b64 v[82:83], 12, v[82:83]
	v_lshlrev_b64 v[84:85], 12, v[84:85]
	v_lshlrev_b64 v[86:87], 12, v[86:87]
	v_lshlrev_b64 v[88:89], 12, v[88:89]
	v_lshlrev_b64 v[90:91], 12, v[90:91]
	v_lshl_add_u64 v[76:77], v[22:23], 0, v[76:77]
	v_lshl_add_u64 v[78:79], v[22:23], 0, v[78:79]
	v_lshl_add_u64 v[80:81], v[22:23], 0, v[80:81]
	v_lshl_add_u64 v[82:83], v[22:23], 0, v[82:83]
	v_lshl_add_u64 v[84:85], v[22:23], 0, v[84:85]
	v_lshl_add_u64 v[86:87], v[22:23], 0, v[86:87]
	v_lshl_add_u64 v[88:89], v[22:23], 0, v[88:89]
	v_lshl_add_u64 v[90:91], v[22:23], 0, v[90:91]
	global_load_dword v107, v[76:77], off
	global_load_dword v108, v[78:79], off
	global_load_dword v109, v[80:81], off
	global_load_dword v110, v[82:83], off
	global_load_dword v111, v[84:85], off
	global_load_dword v112, v[86:87], off
	global_load_dword v113, v[88:89], off
	global_load_dword v114, v[90:91], off
	v_add_u32_e32 v76, s8, v64
	v_add_u32_e32 v78, s8, v66
	v_add_u32_e32 v80, s8, v67
	v_add_u32_e32 v82, s8, v68
	v_add_u32_e32 v84, s8, v69
	v_add_u32_e32 v86, s8, v70
	v_add_u32_e32 v88, s8, v71
	v_add_u32_e32 v90, s8, v72
	v_ashrrev_i32_e32 v77, 31, v76
	v_ashrrev_i32_e32 v79, 31, v78
	v_ashrrev_i32_e32 v81, 31, v80
	v_ashrrev_i32_e32 v83, 31, v82
	v_ashrrev_i32_e32 v85, 31, v84
	v_ashrrev_i32_e32 v87, 31, v86
	v_ashrrev_i32_e32 v89, 31, v88
	v_ashrrev_i32_e32 v91, 31, v90
	v_lshlrev_b64 v[76:77], 12, v[76:77]
	v_lshlrev_b64 v[78:79], 12, v[78:79]
	v_lshlrev_b64 v[80:81], 12, v[80:81]
	v_lshlrev_b64 v[82:83], 12, v[82:83]
	v_lshlrev_b64 v[84:85], 12, v[84:85]
	v_lshlrev_b64 v[86:87], 12, v[86:87]
	v_lshlrev_b64 v[88:89], 12, v[88:89]
	v_lshlrev_b64 v[90:91], 12, v[90:91]
	v_lshl_add_u64 v[76:77], v[22:23], 0, v[76:77]
	v_lshl_add_u64 v[78:79], v[22:23], 0, v[78:79]
	v_lshl_add_u64 v[80:81], v[22:23], 0, v[80:81]
	v_lshl_add_u64 v[82:83], v[22:23], 0, v[82:83]
	v_lshl_add_u64 v[84:85], v[22:23], 0, v[84:85]
	v_lshl_add_u64 v[86:87], v[22:23], 0, v[86:87]
	v_lshl_add_u64 v[88:89], v[22:23], 0, v[88:89]
	v_lshl_add_u64 v[22:23], v[22:23], 0, v[90:91]
	global_load_dword v76, v[76:77], off
	s_nop 0
	global_load_dword v77, v[78:79], off
	s_nop 0
	global_load_dword v78, v[80:81], off
	global_load_dword v79, v[82:83], off
	s_nop 0
	global_load_dword v80, v[84:85], off
	global_load_dword v81, v[86:87], off
	global_load_dword v82, v[88:89], off
	s_nop 0
	global_load_dword v22, v[22:23], off
	v_add_u32_e32 v23, v26, v27
	s_waitcnt vmcnt(30)
; #define LAS __attribute__((address_space(3)))
; __device__ __forceinline__ unsigned pk2(float lo, float hi) { return f2bf(lo) | (f2bf(hi) << 16); }
; #define LDS_WAIT() asm volatile("s_waitcnt lgkmcnt(0)" ::: "memory")
; __device__ __forceinline__ void p0_transpose_item(const float* W, int Nsrc, bf16_t* WT, int Kdst, int k0, int src_col0, int dst_row0, LAS float* scr, int lane) {
;     ...
;     LDS_WAIT();
;     const int c = lane & 7;
; #pragma unroll
;     for (int j = 0; j < 4; ++j) { const int n = (lane >> 3) + 8 * j; const LAS float* s = scr + (8 * c) * 33 + n;
;         u32x4 o; o.x = pk2(s[0 * 33], s[1 * 33]); o.y = pk2(s[2 * 33], s[3 * 33]); o.z = pk2(s[4 * 33], s[5 * 33]); o.w = pk2(s[6 * 33], s[7 * 33]);
;         *(u32x4*)(WT + (size_t)(dst_row0 + n) * Kdst + k0 + 8 * c) = o; }
; __device__ __forceinline__ void phase_prologue(const Prm& P, Ctx& C) {
;     ...
;         if (r < 512) { const int blk = r >> 4, kb = r & 15; p0_transpose_item(P.w_out_even, 1024, (bf16_t*)(ws + WS_W2T), 1024, 64 * kb, 32 * blk, 32 * blk, scr, C.lane); continue; } r -= 512;
	ds_write2_b32 v23, v21, v92 offset1:66
	s_waitcnt vmcnt(28)
	ds_write2_b32 v23, v93, v94 offset0:132 offset1:198
	v_add_u32_e32 v21, 0x400, v23
	s_waitcnt vmcnt(26)
	ds_write2_b32 v21, v95, v96 offset0:8 offset1:74
	v_add_u32_e32 v21, v26, v34
	s_waitcnt vmcnt(24)
	ds_write2_b32 v21, v97, v98 offset1:66
	s_waitcnt vmcnt(22)
	ds_write2_b32 v21, v99, v100 offset0:132 offset1:198
	v_add_u32_e32 v21, 0x400, v21
	s_waitcnt vmcnt(20)
	ds_write2_b32 v21, v101, v102 offset0:8 offset1:74
	v_add_u32_e32 v21, v26, v41
	s_waitcnt vmcnt(18)
	ds_write2_b32 v21, v103, v104 offset1:66
	s_waitcnt vmcnt(16)
	ds_write2_b32 v21, v105, v106 offset0:132 offset1:198
	v_add_u32_e32 v21, 0x400, v21
	v_add_u32_e32 v96, s0, v52
	s_lshl_b32 s8, s8, 1
	s_mov_b32 s9, s1
	v_ashrrev_i32_e32 v97, 31, v96
	v_lshlrev_b64 v[96:97], 11, v[96:97]
	s_waitcnt vmcnt(14)
	ds_write2_b32 v21, v107, v108 offset0:8 offset1:74
	v_add_u32_e32 v21, v26, v48
	s_waitcnt vmcnt(12)
	ds_write2_b32 v21, v109, v110 offset1:66
	s_waitcnt vmcnt(10)
	ds_write2_b32 v21, v111, v112 offset0:132 offset1:198
	v_add_u32_e32 v21, 0x400, v21
	s_waitcnt vmcnt(8)
	ds_write2_b32 v21, v113, v114 offset0:8 offset1:74
	v_add_u32_e32 v21, v26, v65
	s_waitcnt vmcnt(6)
	ds_write2_b32 v21, v76, v77 offset1:66
	s_waitcnt vmcnt(4)
	ds_write2_b32 v21, v78, v79 offset0:132 offset1:198
	v_add_u32_e32 v21, 0x400, v21
	s_waitcnt vmcnt(2)
	ds_write2_b32 v21, v80, v81 offset0:8 offset1:74
	s_waitcnt vmcnt(0)
	ds_write2_b32 v21, v82, v22 offset0:140 offset1:206
	s_waitcnt lgkmcnt(0)
	ds_read2_b32 v[22:23], v53 offset1:8
	ds_read2_b32 v[82:83], v53 offset0:33 offset1:41
	ds_read2_b32 v[84:85], v53 offset0:66 offset1:74
	ds_read2_b32 v[86:87], v53 offset0:99 offset1:107
	ds_read2_b32 v[88:89], v53 offset0:132 offset1:140
	s_waitcnt lgkmcnt(4)
	s_waitcnt lgkmcnt(3)
	ds_read2_b32 v[90:91], v53 offset0:165 offset1:173
	v_cvt_pk_bf16_f32 v76, v22, v82
	s_waitcnt lgkmcnt(3)
	s_waitcnt lgkmcnt(2)
	ds_read2_b32 v[92:93], v53 offset0:198 offset1:206
	ds_read2_b32 v[94:95], v53 offset0:231 offset1:239
	v_cvt_pk_bf16_f32 v77, v84, v86
	s_waitcnt lgkmcnt(3)
	s_waitcnt lgkmcnt(2)
	v_cvt_pk_bf16_f32 v78, v88, v90
	s_waitcnt lgkmcnt(1)
	s_waitcnt lgkmcnt(0)
	v_cvt_pk_bf16_f32 v79, v92, v94
	v_bfe_u32 v21, v23, 16, 1
	v_lshl_add_u64 v[80:81], v[12:13], 0, s[8:9]
	v_add3_u32 v21, v23, v21, s33
	v_bfe_u32 v22, v83, 16, 1
	v_lshl_add_u64 v[96:97], v[80:81], 0, v[96:97]
	v_lshrrev_b32_e32 v21, 16, v21
	v_add3_u32 v22, v83, v22, s33
	global_store_dwordx4 v[96:97], v[76:79], off
	ds_read2_b32 v[82:83], v53 offset0:16 offset1:24
	v_add_u32_e32 v96, s0, v74
	v_and_or_b32 v76, v22, s34, v21
	v_cvt_pk_bf16_f32 v77, v85, v87
	v_cvt_pk_bf16_f32 v78, v89, v91
	v_cvt_pk_bf16_f32 v79, v93, v95
	v_add_u32_e32 v22, s0, v73
	v_ashrrev_i32_e32 v23, 31, v22
	v_lshlrev_b64 v[22:23], 11, v[22:23]
	v_lshl_add_u64 v[22:23], v[80:81], 0, v[22:23]
	global_store_dwordx4 v[22:23], v[76:79], off
	ds_read2_b32 v[22:23], v53 offset0:49 offset1:57
	ds_read2_b32 v[84:85], v53 offset0:82 offset1:90
	ds_read2_b32 v[86:87], v53 offset0:115 offset1:123
	s_waitcnt lgkmcnt(3)
	s_waitcnt lgkmcnt(2)
	ds_read2_b32 v[88:89], v53 offset0:148 offset1:156
	ds_read2_b32 v[90:91], v53 offset0:181 offset1:189
	v_cvt_pk_bf16_f32 v76, v82, v22
	s_waitcnt lgkmcnt(3)
	s_waitcnt lgkmcnt(2)
	ds_read2_b32 v[92:93], v53 offset0:214 offset1:222
	ds_read2_b32 v[94:95], v53 offset0:247 offset1:255
	v_cvt_pk_bf16_f32 v77, v84, v86
	s_waitcnt lgkmcnt(3)
	s_waitcnt lgkmcnt(2)
	v_cvt_pk_bf16_f32 v78, v88, v90
	s_waitcnt lgkmcnt(1)
	s_waitcnt lgkmcnt(0)
	v_cvt_pk_bf16_f32 v79, v92, v94
	v_ashrrev_i32_e32 v97, 31, v96
	v_lshlrev_b64 v[96:97], 11, v[96:97]
	v_lshl_add_u64 v[96:97], v[80:81], 0, v[96:97]
	global_store_dwordx4 v[96:97], v[76:79], off
	s_nop 1
	v_cvt_pk_bf16_f32 v76, v83, v23
	v_cvt_pk_bf16_f32 v77, v85, v87
	v_cvt_pk_bf16_f32 v78, v89, v91
	v_cvt_pk_bf16_f32 v79, v93, v95
	v_add_u32_e32 v22, s0, v75
	v_ashrrev_i32_e32 v23, 31, v22
	v_lshlrev_b64 v[22:23], 11, v[22:23]
	v_lshl_add_u64 v[22:23], v[80:81], 0, v[22:23]
	global_store_dwordx4 v[22:23], v[76:79], off
	s_waitcnt lgkmcnt(0)

; #define LAS __attribute__((address_space(3)))
; __device__ __forceinline__ unsigned pk2(float lo, float hi) { return f2bf(lo) | (f2bf(hi) << 16); }
; #define LDS_WAIT() asm volatile("s_waitcnt lgkmcnt(0)" ::: "memory")
; __device__ __forceinline__ void p0_transpose_item(const float* W, int Nsrc, bf16_t* WT, int Kdst, int k0, int src_col0, int dst_row0, LAS float* scr, int lane) {
;     ...
;     LDS_WAIT();
;     const int c = lane & 7;
; #pragma unroll
;     for (int j = 0; j < 4; ++j) { const int n = (lane >> 3) + 8 * j; const LAS float* s = scr + (8 * c) * 33 + n;
;         u32x4 o; o.x = pk2(s[0 * 33], s[1 * 33]); o.y = pk2(s[2 * 33], s[3 * 33]); o.z = pk2(s[4 * 33], s[5 * 33]); o.w = pk2(s[6 * 33], s[7 * 33]);
;         *(u32x4*)(WT + (size_t)(dst_row0 + n) * Kdst + k0 + 8 * c) = o; }
; __device__ __forceinline__ void phase_prologue(const Prm& P, Ctx& C) {
;     ...
;         if (r < 1792) { const int blk = r >> 4, kb = r & 15; p0_transpose_item(P.w_in_even, E_IN, (bf16_t*)(ws + WS_W1T), 1024, 64 * kb, w1_src_col(blk), 32 * blk, scr, C.lane); continue; } r -= 1792;
.LBB0_79:
	s_waitcnt vmcnt(0)
	ds_write2_b32 v21, v76, v77 offset0:140 offset1:206
	s_waitcnt lgkmcnt(0)
	ds_read2_b32 v[22:23], v53 offset1:8
	ds_read2_b32 v[82:83], v53 offset0:33 offset1:41
	ds_read2_b32 v[84:85], v53 offset0:66 offset1:74
	ds_read2_b32 v[86:87], v53 offset0:99 offset1:107
	ds_read2_b32 v[88:89], v53 offset0:132 offset1:140
	ds_read2_b32 v[90:91], v53 offset0:165 offset1:173
	s_waitcnt lgkmcnt(5)
	s_waitcnt lgkmcnt(4)
	v_cvt_pk_bf16_f32 v76, v22, v82
	s_waitcnt lgkmcnt(3)
	s_waitcnt lgkmcnt(2)
	ds_read2_b32 v[92:93], v53 offset0:198 offset1:206
	ds_read2_b32 v[94:95], v53 offset0:231 offset1:239
	v_cvt_pk_bf16_f32 v77, v84, v86
	s_waitcnt lgkmcnt(3)
	s_waitcnt lgkmcnt(2)
	v_cvt_pk_bf16_f32 v78, v88, v90
	s_waitcnt lgkmcnt(1)
	s_waitcnt lgkmcnt(0)
	v_add_u32_e32 v96, s37, v52
	s_lshl_b32 s0, s38, 1
	v_cvt_pk_bf16_f32 v79, v92, v94
	v_ashrrev_i32_e32 v97, 31, v96
	v_bfe_u32 v21, v23, 16, 1
	v_lshl_add_u64 v[80:81], v[16:17], 0, s[0:1]
	v_lshlrev_b64 v[96:97], 11, v[96:97]
	v_add3_u32 v21, v23, v21, s33
	v_bfe_u32 v22, v83, 16, 1
	v_lshl_add_u64 v[96:97], v[80:81], 0, v[96:97]
	v_lshrrev_b32_e32 v21, 16, v21
	v_add3_u32 v22, v83, v22, s33
	global_store_dwordx4 v[96:97], v[76:79], off
	ds_read2_b32 v[82:83], v53 offset0:16 offset1:24
	v_add_u32_e32 v96, s37, v74
	v_and_or_b32 v76, v22, s34, v21
	v_cvt_pk_bf16_f32 v77, v85, v87
	v_cvt_pk_bf16_f32 v78, v89, v91
	v_cvt_pk_bf16_f32 v79, v93, v95
	v_add_u32_e32 v22, s37, v73
	v_ashrrev_i32_e32 v23, 31, v22
	v_lshlrev_b64 v[22:23], 11, v[22:23]
	v_lshl_add_u64 v[22:23], v[80:81], 0, v[22:23]
	global_store_dwordx4 v[22:23], v[76:79], off
	ds_read2_b32 v[22:23], v53 offset0:49 offset1:57
	ds_read2_b32 v[84:85], v53 offset0:82 offset1:90
	ds_read2_b32 v[86:87], v53 offset0:115 offset1:123
	s_waitcnt lgkmcnt(3)
	s_waitcnt lgkmcnt(2)
	ds_read2_b32 v[88:89], v53 offset0:148 offset1:156
	ds_read2_b32 v[90:91], v53 offset0:181 offset1:189
	v_cvt_pk_bf16_f32 v76, v82, v22
	s_waitcnt lgkmcnt(3)
	s_waitcnt lgkmcnt(2)
	ds_read2_b32 v[92:93], v53 offset0:214 offset1:222
	ds_read2_b32 v[94:95], v53 offset0:247 offset1:255
	v_cvt_pk_bf16_f32 v77, v84, v86
	s_waitcnt lgkmcnt(3)
	s_waitcnt lgkmcnt(2)
	v_cvt_pk_bf16_f32 v78, v88, v90
	s_waitcnt lgkmcnt(1)
	s_waitcnt lgkmcnt(0)
	v_cvt_pk_bf16_f32 v79, v92, v94
	v_ashrrev_i32_e32 v97, 31, v96
	v_lshlrev_b64 v[96:97], 11, v[96:97]
	v_lshl_add_u64 v[96:97], v[80:81], 0, v[96:97]
	global_store_dwordx4 v[96:97], v[76:79], off
	s_nop 1
	v_cvt_pk_bf16_f32 v76, v83, v23
	v_cvt_pk_bf16_f32 v77, v85, v87
	v_cvt_pk_bf16_f32 v78, v89, v91
	v_cvt_pk_bf16_f32 v79, v93, v95
	v_add_u32_e32 v22, s37, v75
	v_ashrrev_i32_e32 v23, 31, v22
	v_lshlrev_b64 v[22:23], 11, v[22:23]
	v_lshl_add_u64 v[22:23], v[80:81], 0, v[22:23]
	global_store_dwordx4 v[22:23], v[76:79], off
	s_waitcnt lgkmcnt(0)

; #define LAS __attribute__((address_space(3)))
; __device__ __forceinline__ void p0_transpose_item(const float* W, int Nsrc, bf16_t* WT, int Kdst, int k0, int src_col0, int dst_row0, LAS float* scr, int lane) {
; #pragma unroll
;     for (int i = 0; i < 32; ++i) { const int kk = 2 * i + (lane >> 5); scr[kk * 33 + (lane & 31)] = (src_col0 >= 0) ? W[(size_t)(k0 + kk) * Nsrc + src_col0 + (lane & 31)] : 0.f; }
; __device__ __forceinline__ void phase_prologue(const Prm& P, Ctx& C) {
;     ...
;             p0_transpose_item(P.w_in_odd, 2048, (bf16_t*)(ws + WS_W3P), 1024, 64 * kb, 32 * blk, 32 * blk, scr, C.lane); continue; }
.LBB0_81:
	s_andn2_b64 vcc, exec, s[8:9]
	s_cbranch_vccnz .LBB0_10
	s_and_b32 s8, s12, 0x3c0
	s_and_b32 s0, s24, 0x7fffffe0
	v_add_u32_e32 v76, s8, v25
	v_add_u32_e32 v78, s8, v28
	v_add_u32_e32 v80, s8, v29
	v_add_u32_e32 v82, s8, v30
	v_add_u32_e32 v84, s8, v31
	v_add_u32_e32 v86, s8, v32
	v_add_u32_e32 v88, s8, v33
	v_add_u32_e32 v90, s8, v35
	s_addk_i32 s0, 0xe500
	v_ashrrev_i32_e32 v77, 31, v76
	v_ashrrev_i32_e32 v79, 31, v78
	v_ashrrev_i32_e32 v81, 31, v80
	v_ashrrev_i32_e32 v83, 31, v82
	v_ashrrev_i32_e32 v85, 31, v84
	v_ashrrev_i32_e32 v87, 31, v86
	v_ashrrev_i32_e32 v89, 31, v88
	v_ashrrev_i32_e32 v91, 31, v90
	v_lshl_add_u64 v[22:23], s[0:1], 2, v[6:7]
	v_lshlrev_b64 v[76:77], 13, v[76:77]
	v_lshlrev_b64 v[78:79], 13, v[78:79]
	v_lshlrev_b64 v[80:81], 13, v[80:81]
	v_lshlrev_b64 v[82:83], 13, v[82:83]
	v_lshlrev_b64 v[84:85], 13, v[84:85]
	v_lshlrev_b64 v[86:87], 13, v[86:87]
	v_lshlrev_b64 v[88:89], 13, v[88:89]
	v_lshlrev_b64 v[90:91], 13, v[90:91]
	v_lshl_add_u64 v[76:77], v[22:23], 0, v[76:77]
	v_lshl_add_u64 v[78:79], v[22:23], 0, v[78:79]
	v_lshl_add_u64 v[80:81], v[22:23], 0, v[80:81]
	v_lshl_add_u64 v[82:83], v[22:23], 0, v[82:83]
	v_lshl_add_u64 v[84:85], v[22:23], 0, v[84:85]
	v_lshl_add_u64 v[86:87], v[22:23], 0, v[86:87]
	v_lshl_add_u64 v[88:89], v[22:23], 0, v[88:89]
	v_lshl_add_u64 v[90:91], v[22:23], 0, v[90:91]
	global_load_dword v21, v[76:77], off
	global_load_dword v92, v[78:79], off
	global_load_dword v93, v[80:81], off
	global_load_dword v94, v[82:83], off
	global_load_dword v95, v[84:85], off
	global_load_dword v96, v[86:87], off
	global_load_dword v97, v[88:89], off
	global_load_dword v98, v[90:91], off
	v_add_u32_e32 v76, s8, v36
	v_add_u32_e32 v78, s8, v37
	v_add_u32_e32 v80, s8, v38
	v_add_u32_e32 v82, s8, v39
	v_add_u32_e32 v84, s8, v40
	v_add_u32_e32 v86, s8, v42
	v_add_u32_e32 v88, s8, v43
	v_add_u32_e32 v90, s8, v44
	v_ashrrev_i32_e32 v77, 31, v76
	v_ashrrev_i32_e32 v79, 31, v78
	v_ashrrev_i32_e32 v81, 31, v80
	v_ashrrev_i32_e32 v83, 31, v82
	v_ashrrev_i32_e32 v85, 31, v84
	v_ashrrev_i32_e32 v87, 31, v86
	v_ashrrev_i32_e32 v89, 31, v88
	v_ashrrev_i32_e32 v91, 31, v90
	v_lshlrev_b64 v[76:77], 13, v[76:77]
	v_lshlrev_b64 v[78:79], 13, v[78:79]
	v_lshlrev_b64 v[80:81], 13, v[80:81]
	v_lshlrev_b64 v[82:83], 13, v[82:83]
	v_lshlrev_b64 v[84:85], 13, v[84:85]
	v_lshlrev_b64 v[86:87], 13, v[86:87]
	v_lshlrev_b64 v[88:89], 13, v[88:89]
	v_lshlrev_b64 v[90:91], 13, v[90:91]
	v_lshl_add_u64 v[76:77], v[22:23], 0, v[76:77]
	v_lshl_add_u64 v[78:79], v[22:23], 0, v[78:79]
	v_lshl_add_u64 v[80:81], v[22:23], 0, v[80:81]
	v_lshl_add_u64 v[82:83], v[22:23], 0, v[82:83]
	v_lshl_add_u64 v[84:85], v[22:23], 0, v[84:85]
	v_lshl_add_u64 v[86:87], v[22:23], 0, v[86:87]
	v_lshl_add_u64 v[88:89], v[22:23], 0, v[88:89]
	v_lshl_add_u64 v[90:91], v[22:23], 0, v[90:91]
	global_load_dword v99, v[76:77], off
	global_load_dword v100, v[78:79], off
	global_load_dword v101, v[80:81], off
	global_load_dword v102, v[82:83], off
	global_load_dword v103, v[84:85], off
	global_load_dword v104, v[86:87], off
	global_load_dword v105, v[88:89], off
	global_load_dword v106, v[90:91], off
	v_add_u32_e32 v76, s8, v45
	v_add_u32_e32 v78, s8, v46
	v_add_u32_e32 v80, s8, v47
	v_add_u32_e32 v82, s8, v49
	v_add_u32_e32 v84, s8, v50
	v_add_u32_e32 v86, s8, v51
	v_add_u32_e32 v88, s8, v62
	v_add_u32_e32 v90, s8, v63
	v_ashrrev_i32_e32 v77, 31, v76
	v_ashrrev_i32_e32 v79, 31, v78
	v_ashrrev_i32_e32 v81, 31, v80
	v_ashrrev_i32_e32 v83, 31, v82
	v_ashrrev_i32_e32 v85, 31, v84
	v_ashrrev_i32_e32 v87, 31, v86
	v_ashrrev_i32_e32 v89, 31, v88
	v_ashrrev_i32_e32 v91, 31, v90
	v_lshlrev_b64 v[76:77], 13, v[76:77]
	v_lshlrev_b64 v[78:79], 13, v[78:79]
	v_lshlrev_b64 v[80:81], 13, v[80:81]
	v_lshlrev_b64 v[82:83], 13, v[82:83]
	v_lshlrev_b64 v[84:85], 13, v[84:85]
	v_lshlrev_b64 v[86:87], 13, v[86:87]
	v_lshlrev_b64 v[88:89], 13, v[88:89]
	v_lshlrev_b64 v[90:91], 13, v[90:91]
	v_lshl_add_u64 v[76:77], v[22:23], 0, v[76:77]
	v_lshl_add_u64 v[78:79], v[22:23], 0, v[78:79]
	v_lshl_add_u64 v[80:81], v[22:23], 0, v[80:81]
	v_lshl_add_u64 v[82:83], v[22:23], 0, v[82:83]
	v_lshl_add_u64 v[84:85], v[22:23], 0, v[84:85]
	v_lshl_add_u64 v[86:87], v[22:23], 0, v[86:87]
	v_lshl_add_u64 v[88:89], v[22:23], 0, v[88:89]
	v_lshl_add_u64 v[90:91], v[22:23], 0, v[90:91]
	global_load_dword v107, v[76:77], off
	global_load_dword v108, v[78:79], off
	global_load_dword v109, v[80:81], off
	global_load_dword v110, v[82:83], off
	global_load_dword v111, v[84:85], off
	global_load_dword v112, v[86:87], off
	global_load_dword v113, v[88:89], off
	global_load_dword v114, v[90:91], off
	v_add_u32_e32 v76, s8, v64
	v_add_u32_e32 v78, s8, v66
	v_add_u32_e32 v80, s8, v67
	v_add_u32_e32 v82, s8, v68
	v_add_u32_e32 v84, s8, v69
	v_add_u32_e32 v86, s8, v70
	v_add_u32_e32 v88, s8, v71
	v_add_u32_e32 v90, s8, v72
	v_ashrrev_i32_e32 v77, 31, v76
	v_ashrrev_i32_e32 v79, 31, v78
	v_ashrrev_i32_e32 v81, 31, v80
	v_ashrrev_i32_e32 v83, 31, v82
	v_ashrrev_i32_e32 v85, 31, v84
	v_ashrrev_i32_e32 v87, 31, v86
	v_ashrrev_i32_e32 v89, 31, v88
	v_ashrrev_i32_e32 v91, 31, v90
	v_lshlrev_b64 v[76:77], 13, v[76:77]
	v_lshlrev_b64 v[78:79], 13, v[78:79]
	v_lshlrev_b64 v[80:81], 13, v[80:81]
	v_lshlrev_b64 v[82:83], 13, v[82:83]
	v_lshlrev_b64 v[84:85], 13, v[84:85]
	v_lshlrev_b64 v[86:87], 13, v[86:87]
	v_lshlrev_b64 v[88:89], 13, v[88:89]
	v_lshlrev_b64 v[90:91], 13, v[90:91]
	v_lshl_add_u64 v[76:77], v[22:23], 0, v[76:77]
	v_lshl_add_u64 v[78:79], v[22:23], 0, v[78:79]
	v_lshl_add_u64 v[80:81], v[22:23], 0, v[80:81]
	v_lshl_add_u64 v[82:83], v[22:23], 0, v[82:83]
	v_lshl_add_u64 v[84:85], v[22:23], 0, v[84:85]
	v_lshl_add_u64 v[86:87], v[22:23], 0, v[86:87]
	v_lshl_add_u64 v[88:89], v[22:23], 0, v[88:89]
	v_lshl_add_u64 v[22:23], v[22:23], 0, v[90:91]
	global_load_dword v76, v[76:77], off
	s_nop 0
	global_load_dword v77, v[78:79], off
	s_nop 0
	global_load_dword v78, v[80:81], off
	global_load_dword v79, v[82:83], off
	s_nop 0
	global_load_dword v80, v[84:85], off
	global_load_dword v81, v[86:87], off
	global_load_dword v82, v[88:89], off
	s_nop 0
	global_load_dword v22, v[22:23], off
	v_add_u32_e32 v23, v26, v27
	s_waitcnt vmcnt(30)
; #define LAS __attribute__((address_space(3)))
; __device__ __forceinline__ unsigned pk2(float lo, float hi) { return f2bf(lo) | (f2bf(hi) << 16); }
; #define LDS_WAIT() asm volatile("s_waitcnt lgkmcnt(0)" ::: "memory")
; __device__ __forceinline__ void p0_transpose_item(const float* W, int Nsrc, bf16_t* WT, int Kdst, int k0, int src_col0, int dst_row0, LAS float* scr, int lane) {
;     ...
;     LDS_WAIT();
;     const int c = lane & 7;
; #pragma unroll
;     for (int j = 0; j < 4; ++j) { const int n = (lane >> 3) + 8 * j; const LAS float* s = scr + (8 * c) * 33 + n;
;         u32x4 o; o.x = pk2(s[0 * 33], s[1 * 33]); o.y = pk2(s[2 * 33], s[3 * 33]); o.z = pk2(s[4 * 33], s[5 * 33]); o.w = pk2(s[6 * 33], s[7 * 33]);
;         *(u32x4*)(WT + (size_t)(dst_row0 + n) * Kdst + k0 + 8 * c) = o; }
; __device__ __forceinline__ void phase_prologue(const Prm& P, Ctx& C) {
;     ...
;             p0_transpose_item(P.w_in_odd, 2048, (bf16_t*)(ws + WS_W3P), 1024, 64 * kb, 32 * blk, 32 * blk, scr, C.lane); continue; }
	ds_write2_b32 v23, v21, v92 offset1:66
	s_waitcnt vmcnt(28)
	ds_write2_b32 v23, v93, v94 offset0:132 offset1:198
	v_add_u32_e32 v21, 0x400, v23
	s_waitcnt vmcnt(26)
	ds_write2_b32 v21, v95, v96 offset0:8 offset1:74
	v_add_u32_e32 v21, v26, v34
	s_waitcnt vmcnt(24)
	ds_write2_b32 v21, v97, v98 offset1:66
	s_waitcnt vmcnt(22)
	ds_write2_b32 v21, v99, v100 offset0:132 offset1:198
	v_add_u32_e32 v21, 0x400, v21
	s_waitcnt vmcnt(20)
	ds_write2_b32 v21, v101, v102 offset0:8 offset1:74
	v_add_u32_e32 v21, v26, v41
	s_waitcnt vmcnt(18)
	ds_write2_b32 v21, v103, v104 offset1:66
	s_waitcnt vmcnt(16)
	ds_write2_b32 v21, v105, v106 offset0:132 offset1:198
	v_add_u32_e32 v21, 0x400, v21
	v_add_u32_e32 v96, s0, v52
	s_lshl_b32 s8, s8, 1
	s_mov_b32 s9, s1
	v_ashrrev_i32_e32 v97, 31, v96
	v_lshlrev_b64 v[96:97], 11, v[96:97]
	s_waitcnt vmcnt(14)
	ds_write2_b32 v21, v107, v108 offset0:8 offset1:74
	v_add_u32_e32 v21, v26, v48
	s_waitcnt vmcnt(12)
	ds_write2_b32 v21, v109, v110 offset1:66
	s_waitcnt vmcnt(10)
	ds_write2_b32 v21, v111, v112 offset0:132 offset1:198
	v_add_u32_e32 v21, 0x400, v21
	s_waitcnt vmcnt(8)
	ds_write2_b32 v21, v113, v114 offset0:8 offset1:74
	v_add_u32_e32 v21, v26, v65
	s_waitcnt vmcnt(6)
	ds_write2_b32 v21, v76, v77 offset1:66
	s_waitcnt vmcnt(4)
	ds_write2_b32 v21, v78, v79 offset0:132 offset1:198
	v_add_u32_e32 v21, 0x400, v21
	s_waitcnt vmcnt(2)
	ds_write2_b32 v21, v80, v81 offset0:8 offset1:74
	s_waitcnt vmcnt(0)
	ds_write2_b32 v21, v82, v22 offset0:140 offset1:206
	s_waitcnt lgkmcnt(0)
	ds_read2_b32 v[22:23], v53 offset1:8
	ds_read2_b32 v[82:83], v53 offset0:33 offset1:41
	ds_read2_b32 v[84:85], v53 offset0:66 offset1:74
	ds_read2_b32 v[86:87], v53 offset0:99 offset1:107
	ds_read2_b32 v[88:89], v53 offset0:132 offset1:140
	s_waitcnt lgkmcnt(4)
	s_waitcnt lgkmcnt(3)
	ds_read2_b32 v[90:91], v53 offset0:165 offset1:173
	v_cvt_pk_bf16_f32 v76, v22, v82
	s_waitcnt lgkmcnt(3)
	s_waitcnt lgkmcnt(2)
	ds_read2_b32 v[92:93], v53 offset0:198 offset1:206
	ds_read2_b32 v[94:95], v53 offset0:231 offset1:239
	v_cvt_pk_bf16_f32 v77, v84, v86
	s_waitcnt lgkmcnt(3)
	s_waitcnt lgkmcnt(2)
	v_cvt_pk_bf16_f32 v78, v88, v90
	s_waitcnt lgkmcnt(1)
	s_waitcnt lgkmcnt(0)
	v_cvt_pk_bf16_f32 v79, v92, v94
	v_bfe_u32 v21, v23, 16, 1
	v_lshl_add_u64 v[80:81], v[18:19], 0, s[8:9]
	v_add3_u32 v21, v23, v21, s33
	v_bfe_u32 v22, v83, 16, 1
	v_lshl_add_u64 v[96:97], v[80:81], 0, v[96:97]
	v_lshrrev_b32_e32 v21, 16, v21
	v_add3_u32 v22, v83, v22, s33
	global_store_dwordx4 v[96:97], v[76:79], off
	ds_read2_b32 v[82:83], v53 offset0:16 offset1:24
	v_add_u32_e32 v96, s0, v74
	v_and_or_b32 v76, v22, s34, v21
	v_cvt_pk_bf16_f32 v77, v85, v87
	v_cvt_pk_bf16_f32 v78, v89, v91
	v_cvt_pk_bf16_f32 v79, v93, v95
	v_add_u32_e32 v22, s0, v73
	v_ashrrev_i32_e32 v23, 31, v22
	v_lshlrev_b64 v[22:23], 11, v[22:23]
	v_lshl_add_u64 v[22:23], v[80:81], 0, v[22:23]
	global_store_dwordx4 v[22:23], v[76:79], off
	ds_read2_b32 v[22:23], v53 offset0:49 offset1:57
	ds_read2_b32 v[84:85], v53 offset0:82 offset1:90
	ds_read2_b32 v[86:87], v53 offset0:115 offset1:123
	s_waitcnt lgkmcnt(3)
	s_waitcnt lgkmcnt(2)
	ds_read2_b32 v[88:89], v53 offset0:148 offset1:156
	ds_read2_b32 v[90:91], v53 offset0:181 offset1:189
	v_cvt_pk_bf16_f32 v76, v82, v22
	s_waitcnt lgkmcnt(3)
	s_waitcnt lgkmcnt(2)
	ds_read2_b32 v[92:93], v53 offset0:214 offset1:222
	ds_read2_b32 v[94:95], v53 offset0:247 offset1:255
	v_cvt_pk_bf16_f32 v77, v84, v86
	s_waitcnt lgkmcnt(3)
	s_waitcnt lgkmcnt(2)
	v_cvt_pk_bf16_f32 v78, v88, v90
	s_waitcnt lgkmcnt(1)
	s_waitcnt lgkmcnt(0)
	v_cvt_pk_bf16_f32 v79, v92, v94
	v_ashrrev_i32_e32 v97, 31, v96
	v_lshlrev_b64 v[96:97], 11, v[96:97]
	v_lshl_add_u64 v[96:97], v[80:81], 0, v[96:97]
	global_store_dwordx4 v[96:97], v[76:79], off
	s_nop 1
	v_cvt_pk_bf16_f32 v76, v83, v23
	v_cvt_pk_bf16_f32 v77, v85, v87
	v_cvt_pk_bf16_f32 v78, v89, v91
	v_cvt_pk_bf16_f32 v79, v93, v95
	v_add_u32_e32 v22, s0, v75
	v_ashrrev_i32_e32 v23, 31, v22
	v_lshlrev_b64 v[22:23], 11, v[22:23]
	v_lshl_add_u64 v[22:23], v[80:81], 0, v[22:23]
	global_store_dwordx4 v[22:23], v[76:79], off
	s_waitcnt lgkmcnt(0)
	s_branch .LBB0_10

; __device__ __forceinline__ unsigned pk2(float lo, float hi) { return f2bf(lo) | (f2bf(hi) << 16); }
; __device__ __forceinline__ void phase_prologue(const Prm& P, Ctx& C) {
;     ...
;     for (int m = gw; m < 1024; m += NGW) {
; #pragma unroll
;         for (int j = 0; j < 4; ++j) { const f32x4 v = *(const f32x4*)(P.w_in_odd + (size_t)m * 2048 + 4 * C.lane + 256 * j);
;             u32x2 o; o.x = pk2(v[0], v[1]); o.y = pk2(v[2], v[3]); *(u32x2*)((bf16_t*)(ws + WS_WN) + (size_t)m * 1024 + 4 * C.lane + 256 * j) = o; }
;     }
.LBB0_85:
	global_load_dwordx4 v[4:7], v[2:3], off offset:-3072
	s_add_i32 s10, s10, s6
	s_cmpk_lt_i32 s10, 0x400
	s_waitcnt vmcnt(0)
	v_cvt_pk_bf16_f32 v4, v4, v5
	v_cvt_pk_bf16_f32 v5, v6, v7
	global_store_dwordx2 v[0:1], v[4:5], off
	global_load_dwordx4 v[4:7], v[2:3], off offset:-2048
	s_waitcnt vmcnt(0)
	v_cvt_pk_bf16_f32 v4, v4, v5
	v_cvt_pk_bf16_f32 v5, v6, v7
	global_store_dwordx2 v[0:1], v[4:5], off offset:512
	global_load_dwordx4 v[4:7], v[2:3], off offset:-1024
	s_waitcnt vmcnt(0)
	v_cvt_pk_bf16_f32 v4, v4, v5
	v_cvt_pk_bf16_f32 v5, v6, v7
	global_store_dwordx2 v[0:1], v[4:5], off offset:1024
	global_load_dwordx4 v[4:7], v[2:3], off
	v_lshl_add_u64 v[2:3], v[2:3], 0, s[8:9]
	s_waitcnt vmcnt(0)
	v_cvt_pk_bf16_f32 v4, v4, v5
	v_cvt_pk_bf16_f32 v5, v6, v7
	global_store_dwordx2 v[0:1], v[4:5], off offset:1536
	v_lshl_add_u64 v[0:1], v[0:1], 0, s[0:1]
	s_cbranch_scc1 .LBB0_85

; __device__ __forceinline__ unsigned pk2(float lo, float hi) { return f2bf(lo) | (f2bf(hi) << 16); }
; __device__ __forceinline__ void phase_prologue(const Prm& P, Ctx& C) {
;     ...
;     bf16_t* XA = (bf16_t*)(ws + WS_XA);
; #pragma unroll 1
;     for (int m0 = gw; m0 < MA; m0 += 4 * NGW) {
;         f32x4 v[4][4];
; #pragma unroll
;         for (int u = 0; u < 4; ++u) { const int m = m0 + u * NGW;
;             const float* src = m < MP ? P.x_prompt + (size_t)m * DM : (m < MR ? P.x_sample + (size_t)(m - MP) * DM : nullptr);
; #pragma unroll
;             for (int j = 0; j < 4; ++j) v[u][j] = src ? __builtin_nontemporal_load((const f32x4*)(src + 4 * C.lane + 256 * j)) : (f32x4){0.f, 0.f, 0.f, 0.f}; }
; #pragma unroll
;         for (int u = 0; u < 4; ++u) { const int m = m0 + u * NGW;
;             if (m < MA) {
; #pragma unroll
;                 for (int j = 0; j < 4; ++j) { u32x2 o; o.x = pk2(v[u][j][0], v[u][j][1]); o.y = pk2(v[u][j][2], v[u][j][3]); *(u32x2*)(XA + (size_t)m * DM + 4 * C.lane + 256 * j) = o; } } }
;     }
.LBB0_135:
	s_waitcnt vmcnt(0)
	v_bfe_u32 v70, v4, 16, 1
	v_add3_u32 v4, v4, v70, s9
	v_bfe_u32 v70, v5, 16, 1
	v_lshrrev_b32_e32 v4, 16, v4
	v_add3_u32 v5, v5, v70, s9
	v_and_or_b32 v4, v5, s33, v4
	v_cvt_pk_bf16_f32 v5, v6, v7
	global_store_dwordx2 v[68:69], v[4:5], off
	v_cvt_pk_bf16_f32 v0, v0, v1
	v_cvt_pk_bf16_f32 v1, v2, v3
	global_store_dwordx2 v[68:69], v[0:1], off offset:512
	v_cvt_pk_bf16_f32 v0, v12, v13
	v_cvt_pk_bf16_f32 v1, v14, v15
	global_store_dwordx2 v[68:69], v[0:1], off offset:1024
	v_cvt_pk_bf16_f32 v0, v8, v9
	v_cvt_pk_bf16_f32 v1, v10, v11
	s_cmp_gt_i32 s28, 0x80ff
	global_store_dwordx2 v[68:69], v[0:1], off offset:1536
	s_cbranch_scc1 .LBB0_138
	v_cvt_pk_bf16_f32 v0, v24, v25
	s_ashr_i32 s29, s28, 31
	s_lshl_b64 s[0:1], s[28:29], 11
	v_cvt_pk_bf16_f32 v1, v26, v27
	v_lshl_add_u64 v[2:3], v[66:67], 0, s[0:1]
	global_store_dwordx2 v[2:3], v[0:1], off
	v_cvt_pk_bf16_f32 v0, v16, v17
	v_cvt_pk_bf16_f32 v1, v18, v19
	global_store_dwordx2 v[2:3], v[0:1], off offset:512
	v_cvt_pk_bf16_f32 v0, v28, v29
	v_cvt_pk_bf16_f32 v1, v30, v31
	global_store_dwordx2 v[2:3], v[0:1], off offset:1024
	v_cvt_pk_bf16_f32 v0, v20, v21
	v_cvt_pk_bf16_f32 v1, v22, v23
	global_store_dwordx2 v[2:3], v[0:1], off offset:1536
	s_cmp_gt_i32 s30, 0x80ff
	s_cbranch_scc0 .LBB0_139

; __device__ __forceinline__ unsigned pk2(float lo, float hi) { return f2bf(lo) | (f2bf(hi) << 16); }
; __device__ __forceinline__ void phase_prologue(const Prm& P, Ctx& C) {
;     ...
; #pragma unroll
;         for (int u = 0; u < 4; ++u) { const int m = m0 + u * NGW;
;             if (m < MA) {
; #pragma unroll
;                 for (int j = 0; j < 4; ++j) { u32x2 o; o.x = pk2(v[u][j][0], v[u][j][1]); o.y = pk2(v[u][j][2], v[u][j][3]); *(u32x2*)(XA + (size_t)m * DM + 4 * C.lane + 256 * j) = o; } } }
;     }
.LBB0_139:
	v_cvt_pk_bf16_f32 v0, v40, v41
	s_ashr_i32 s31, s30, 31
	s_lshl_b64 s[0:1], s[30:31], 11
	v_cvt_pk_bf16_f32 v1, v42, v43
	v_lshl_add_u64 v[2:3], v[66:67], 0, s[0:1]
	global_store_dwordx2 v[2:3], v[0:1], off
	v_cvt_pk_bf16_f32 v0, v32, v33
	v_cvt_pk_bf16_f32 v1, v34, v35
	global_store_dwordx2 v[2:3], v[0:1], off offset:512
	v_cvt_pk_bf16_f32 v0, v44, v45
	v_cvt_pk_bf16_f32 v1, v46, v47
	global_store_dwordx2 v[2:3], v[0:1], off offset:1024
	v_cvt_pk_bf16_f32 v0, v36, v37
	v_cvt_pk_bf16_f32 v1, v38, v39
	global_store_dwordx2 v[2:3], v[0:1], off offset:1536
	s_cmp_gt_i32 s34, 0x80ff
	s_cbranch_scc1 .LBB0_88
.LBB0_140:
	v_cvt_pk_bf16_f32 v0, v56, v57
	s_ashr_i32 s35, s34, 31
	s_lshl_b64 s[0:1], s[34:35], 11
	v_cvt_pk_bf16_f32 v1, v58, v59
	v_lshl_add_u64 v[2:3], v[66:67], 0, s[0:1]
	global_store_dwordx2 v[2:3], v[0:1], off
	v_cvt_pk_bf16_f32 v0, v48, v49
	v_cvt_pk_bf16_f32 v1, v50, v51
	global_store_dwordx2 v[2:3], v[0:1], off offset:512
	v_cvt_pk_bf16_f32 v0, v60, v61
	v_cvt_pk_bf16_f32 v1, v62, v63
	global_store_dwordx2 v[2:3], v[0:1], off offset:1024
	v_cvt_pk_bf16_f32 v0, v52, v53
	v_cvt_pk_bf16_f32 v1, v54, v55
	global_store_dwordx2 v[2:3], v[0:1], off offset:1536
	s_branch .LBB0_88

; __device__ __forceinline__ void st8bf(bf16_t* p, f32x4 a, f32x4 b) { u32x4 w; w.x = pk2(a[0], a[1]); w.y = pk2(a[2], a[3]); w.z = pk2(b[0], b[1]); w.w = pk2(b[2], b[3]); st16(p, w); }
; __device__ __forceinline__ f32x4 sig4(f32x4 v) { f32x4 r; r[0] = sigmoidf_(v[0]); r[1] = sigmoidf_(v[1]); r[2] = sigmoidf_(v[2]); r[3] = sigmoidf_(v[3]); return r; }
;     __device__ __forceinline__ void st_glu(int pn, int row, int c, f32x4 a0, f32x4 a1, f32x4 g0, f32x4 g1) const {
;         const bool smp = row >= MP; const int b = smp ? (row - MP) >> 2 : row >> 13, t = smp ? (row - MP) & 3 : row & (SEQ - 1);
;         const f32x4 v0 = a0 * sig4(g0), v1 = a1 * sig4(g1);
;         const int col = pn * 128 + c;
;         st8bf(U + (size_t)row * 512 + col, v0, v1);
;     ...
;         if (kh == 0 && act) {
; #pragma unroll
;             for (int q = 0; q < KS - 1; ++q)
; #pragma unroll
;                 for (int j = 0; j < NACC; ++j) acc[j] += red[((pw * (KS - 1) + q) * NACC + j) * 64 + lane];
;             const int row = row_base + mt * mt_stride + r, c = 32 * sub + 8 * fq;
;             if (glu) epi.st_glu(pn, row, c, acc[0], acc[1], acc[2], acc[3]); else epi.st(pn, row, c, acc[0], acc[1]);
.LBB0_207:
	s_andn2_b64 vcc, exec, s[54:55]
	s_waitcnt lgkmcnt(0)
	s_barrier
	s_cbranch_vccnz .LBB0_195
	ds_read_b128 v[16:19], v40
	ds_read_b128 v[26:29], v40 offset:1024
	s_lshl_b32 s0, s62, 3
	s_sub_i32 s0, s61, s0
	s_lshl_b32 s54, s0, 4
	s_add_i32 s54, s54, 0x8000
	s_waitcnt lgkmcnt(1)
	v_pk_add_f32 v[6:7], v[6:7], v[18:19]
	v_pk_add_f32 v[4:5], v[4:5], v[16:17]
	s_waitcnt lgkmcnt(0)
	v_pk_add_f32 v[2:3], v[2:3], v[28:29]
	v_pk_add_f32 v[0:1], v[0:1], v[26:27]
	v_or_b32_e32 v22, s54, v207
	v_lshl_add_u32 v16, s42, 5, v20
	s_andn2_b64 vcc, exec, s[52:53]
	s_mov_b64 s[0:1], -1
	s_cbranch_vccnz .LBB0_216
	ds_read_b128 v[26:29], v40 offset:3072
	ds_read_b128 v[30:33], v40 offset:2048
	v_lshl_add_u32 v18, s60, 7, v16
	v_ashrrev_i32_e32 v19, 31, v18
	v_cmp_gt_i32_e32 vcc, s56, v22
	s_waitcnt lgkmcnt(1)
	v_pk_add_f32 v[12:13], v[12:13], v[26:27]
	s_waitcnt lgkmcnt(0)
	v_pk_add_f32 v[8:9], v[8:9], v[30:31]
	v_pk_add_f32 v[10:11], v[10:11], v[32:33]
	v_mul_f32_e32 v8, 0xbfb8aa3b, v8
	v_mul_f32_e32 v9, 0xbfb8aa3b, v9
	v_exp_f32_e32 v8, v8
	v_exp_f32_e32 v9, v9
	v_mul_f32_e32 v10, 0xbfb8aa3b, v10
	v_mul_f32_e32 v11, 0xbfb8aa3b, v11
	v_exp_f32_e32 v10, v10
	v_exp_f32_e32 v11, v11
	v_add_f32_e32 v8, 1.0, v8
	v_add_f32_e32 v9, 1.0, v9
	v_rcp_f32_e32 v8, v8
	v_rcp_f32_e32 v9, v9
	v_mul_f32_e32 v12, 0xbfb8aa3b, v12
	v_mul_f32_e32 v13, 0xbfb8aa3b, v13
	v_exp_f32_e32 v12, v12
	v_exp_f32_e32 v13, v13
	v_pk_add_f32 v[14:15], v[14:15], v[28:29]
	v_add_f32_e32 v10, 1.0, v10
	v_add_f32_e32 v11, 1.0, v11
	v_rcp_f32_e32 v10, v10
	v_rcp_f32_e32 v11, v11
	v_mul_f32_e32 v14, 0xbfb8aa3b, v14
	v_mul_f32_e32 v15, 0xbfb8aa3b, v15
	v_exp_f32_e32 v14, v14
	v_exp_f32_e32 v15, v15
	v_pk_mul_f32 v[8:9], v[4:5], v[8:9]
	v_lshlrev_b64 v[26:27], 10, v[22:23]
	v_add_f32_e32 v12, 1.0, v12
	v_add_f32_e32 v13, 1.0, v13
	v_lshl_add_u64 v[26:27], s[26:27], 0, v[26:27]
	v_rcp_f32_e32 v12, v12
	v_rcp_f32_e32 v13, v13
	v_lshl_add_u64 v[30:31], v[18:19], 1, v[26:27]
	v_pk_mul_f32 v[10:11], v[6:7], v[10:11]
	v_add_f32_e32 v14, 1.0, v14
	v_add_f32_e32 v15, 1.0, v15
	v_cvt_pk_bf16_f32 v26, v8, v9
	v_rcp_f32_e32 v14, v14
	v_rcp_f32_e32 v15, v15
	v_pk_mul_f32 v[12:13], v[0:1], v[12:13]
	v_cvt_pk_bf16_f32 v27, v10, v11
	v_pk_mul_f32 v[14:15], v[2:3], v[14:15]
	v_cvt_pk_bf16_f32 v28, v12, v13
	v_cvt_pk_bf16_f32 v29, v14, v15
	global_store_dwordx4 v[30:31], v[26:29], off
	s_and_saveexec_b64 s[0:1], vcc
	s_xor_b64 s[0:1], exec, s[0:1]
	s_cbranch_execz .LBB0_219
	v_and_b32_e32 v28, 0x1fff, v22
	s_movk_i32 s2, 0x1fe1
	v_cmp_lt_u32_e32 vcc, s2, v28
	v_mov_b64_e32 v[26:27], 0
	s_and_saveexec_b64 s[2:3], vcc
	s_lshr_b32 s4, s54, 13
	v_mad_u64_u32 v[26:27], s[4:5], s4, 30, v[28:29]
	v_add_u32_e32 v26, 0xffffe01e, v26
	v_mov_b32_e32 v27, v23
	v_lshlrev_b64 v[26:27], 11, v[26:27]
	v_lshl_add_u64 v[26:27], s[30:31], 0, v[26:27]
	v_lshl_add_u64 v[26:27], v[18:19], 2, v[26:27]
	s_or_b64 exec, exec, s[2:3]
	s_andn2_saveexec_b64 s[0:1], s[0:1]
	s_cbranch_execnz .LBB0_220

; __device__ __forceinline__ void st16f(float* p, f32x4 v) { st16(p, __builtin_bit_cast(u32x4, v)); }
; __device__ __forceinline__ void st8bf(bf16_t* p, f32x4 a, f32x4 b) { u32x4 w; w.x = pk2(a[0], a[1]); w.y = pk2(a[2], a[3]); w.z = pk2(b[0], b[1]); w.w = pk2(b[2], b[3]); st16(p, w); }
;     __device__ __forceinline__ void st(int pn, int row, int c, f32x4 v0, f32x4 v1) const {
;     ...
;         else if (pn == 10) { float* o = nullptr;
;             if (!smp) { if (t >= SEQ - 512) o = out + O_WIN + ((size_t)b * 512 + (t - (SEQ - 512))) * 256 + c; } else o = out + O_WINS + ((size_t)b * 512 + 508 + t) * 256 + c;
;             st8bf(KW + (size_t)row * 256 + c, v0, v1); if (o) { st16f(o, v0); st16f(o + 4, v1); } }
.LBB0_240:
	s_or_b64 exec, exec, s[2:3]
	v_lshlrev_b64 v[12:13], 9, v[22:23]
	v_lshl_add_u64 v[12:13], s[8:9], 0, v[12:13]
	v_lshl_add_u64 v[18:19], v[16:17], 1, v[12:13]
	v_cvt_pk_bf16_f32 v12, v4, v5
	v_cvt_pk_bf16_f32 v13, v6, v7
	v_cvt_pk_bf16_f32 v14, v0, v1
	v_cvt_pk_bf16_f32 v15, v2, v3
	v_cmp_ne_u64_e32 vcc, 0, v[10:11]
	global_store_dwordx4 v[18:19], v[12:15], off
	s_and_saveexec_b64 s[2:3], vcc
	s_cbranch_execz .LBB0_242
	global_store_dwordx4 v[10:11], v[4:7], off
	global_store_dwordx4 v[10:11], v[0:3], off offset:16

; __device__ __forceinline__ void st16f(float* p, f32x4 v) { st16(p, __builtin_bit_cast(u32x4, v)); }
; __device__ __forceinline__ void st8bf(bf16_t* p, f32x4 a, f32x4 b) { u32x4 w; w.x = pk2(a[0], a[1]); w.y = pk2(a[2], a[3]); w.z = pk2(b[0], b[1]); w.w = pk2(b[2], b[3]); st16(p, w); }
;     __device__ __forceinline__ void st(int pn, int row, int c, f32x4 v0, f32x4 v1) const {
;     ...
;         else if (pn == 8) { float* o = (smp ? out + O_KCS + (size_t)(row - MP) * 256 : out + O_KC + (size_t)row * 256) + c; st16f(o, v0); st16f(o + 4, v1); }
;         else if (pn == 9) { float* o = (smp ? out + O_KSS + (size_t)(row - MP) * 256 : out + O_KSEL + (size_t)row * 256) + c; st16f(o, v0); st16f(o + 4, v1); st8bf(KS + (size_t)row * 256 + c, v0, v1); }
.LBB0_244:
	s_andn2_b64 vcc, exec, s[4:5]
	s_cbranch_vccnz .LBB0_246
	v_mov_b32_e32 v9, v23
	v_lshlrev_b64 v[10:11], 10, v[22:23]
	v_lshlrev_b64 v[12:13], 10, v[8:9]
	v_lshl_add_u64 v[10:11], s[36:37], 0, v[10:11]
	v_lshl_add_u64 v[12:13], s[38:39], 0, v[12:13]
	v_cndmask_b32_e64 v11, v11, v13, s[0:1]
	v_cndmask_b32_e64 v10, v10, v12, s[0:1]
	v_ashrrev_i32_e32 v17, 31, v16
	v_lshl_add_u64 v[10:11], v[16:17], 2, v[10:11]
	global_store_dwordx4 v[10:11], v[4:7], off
	global_store_dwordx4 v[10:11], v[0:3], off offset:16
	v_lshlrev_b64 v[10:11], 9, v[22:23]
	v_lshl_add_u64 v[10:11], s[6:7], 0, v[10:11]
	v_lshl_add_u64 v[14:15], v[16:17], 1, v[10:11]
	v_cvt_pk_bf16_f32 v10, v4, v5
	v_cvt_pk_bf16_f32 v11, v6, v7
	v_cvt_pk_bf16_f32 v12, v0, v1
	v_cvt_pk_bf16_f32 v13, v2, v3
	global_store_dwordx4 v[14:15], v[10:13], off

; __device__ __forceinline__ void st8bf(bf16_t* p, f32x4 a, f32x4 b) { u32x4 w; w.x = pk2(a[0], a[1]); w.y = pk2(a[2], a[3]); w.z = pk2(b[0], b[1]); w.w = pk2(b[2], b[3]); st16(p, w); }
; __device__ __forceinline__ f32x4 sig4(f32x4 v) { f32x4 r; r[0] = sigmoidf_(v[0]); r[1] = sigmoidf_(v[1]); r[2] = sigmoidf_(v[2]); r[3] = sigmoidf_(v[3]); return r; }
; __device__ __forceinline__ unsigned f2bf(float f) { unsigned u = __builtin_bit_cast(unsigned, f); return (u + 0x7fffu + ((u >> 16) & 1u)) >> 16; }
; __device__ __forceinline__ unsigned pk2(float lo, float hi) { return f2bf(lo) | (f2bf(hi) << 16); }
;     __device__ __forceinline__ void st(int pn, int row, int c, f32x4 v0, f32x4 v1) const {
;         const bool smp = row >= MP; const int b = smp ? (row - MP) >> 2 : row >> 13, t = smp ? (row - MP) & 3 : row & (SEQ - 1);
;         if (pn < 6 || pn == 11 || pn == 12) st8bf((pn < 6 ? AG : BG) + (size_t)row * 512 + (pn < 6 ? pn - 4 : pn - 11) * 256 + c, v0 * sig4(v0), v1 * sig4(v1));
;         else if (pn < 8) st8bf(Q + (size_t)row * 512 + (pn - 6) * 256 + c, v0 * C2, v1 * C2);
.LBB0_250:
	s_and_b64 vcc, exec, s[0:1]
	s_cbranch_vccz .LBB0_252
	v_lshlrev_b64 v[8:9], 10, v[22:23]
	v_lshl_add_u64 v[8:9], s[28:29], 0, v[8:9]
	s_lshl_b32 s42, s60, 9
	v_lshl_add_u64 v[8:9], v[8:9], 0, s[42:43]
	v_ashrrev_i32_e32 v17, 31, v16
	v_lshl_add_u64 v[12:13], v[16:17], 1, v[8:9]
	v_pk_mul_f32 v[8:9], v[4:5], s[50:51] op_sel_hi:[1,0]
	v_pk_mul_f32 v[10:11], v[6:7], s[50:51] op_sel_hi:[1,0]
	v_cvt_pk_bf16_f32 v8, v8, v9
	v_pk_mul_f32 v[18:19], v[0:1], s[50:51] op_sel_hi:[1,0]
	v_cvt_pk_bf16_f32 v9, v10, v11
	v_pk_mul_f32 v[14:15], v[2:3], s[50:51] op_sel_hi:[1,0]
	v_cvt_pk_bf16_f32 v10, v18, v19
	v_cvt_pk_bf16_f32 v11, v14, v15
	global_store_dwordx4 v[12:13], v[8:11], off offset:-3072

; __device__ __forceinline__ void st8bf(bf16_t* p, f32x4 a, f32x4 b) { u32x4 w; w.x = pk2(a[0], a[1]); w.y = pk2(a[2], a[3]); w.z = pk2(b[0], b[1]); w.w = pk2(b[2], b[3]); st16(p, w); }
; __device__ __forceinline__ f32x4 sig4(f32x4 v) { f32x4 r; r[0] = sigmoidf_(v[0]); r[1] = sigmoidf_(v[1]); r[2] = sigmoidf_(v[2]); r[3] = sigmoidf_(v[3]); return r; }
; __device__ __forceinline__ float sigmoidf_(float x) { return __builtin_amdgcn_rcpf(1.0f + __expf(-x)); }
; __device__ __forceinline__ float siluf_(float x) { return x * sigmoidf_(x); }
;     __device__ __forceinline__ void st(int pn, int row, int c, f32x4 v0, f32x4 v1) const {
;         const bool smp = row >= MP; const int b = smp ? (row - MP) >> 2 : row >> 13, t = smp ? (row - MP) & 3 : row & (SEQ - 1);
;         if (pn < 6 || pn == 11 || pn == 12) st8bf((pn < 6 ? AG : BG) + (size_t)row * 512 + (pn < 6 ? pn - 4 : pn - 11) * 256 + c, v0 * sig4(v0), v1 * sig4(v1));
.LBB0_254:
	s_cmp_lt_u32 s60, 6
	s_cselect_b64 s[0:1], -1, 0
	s_and_b64 s[0:1], s[0:1], exec
	s_cselect_b32 s2, -4, -11
	s_cselect_b32 s1, s51, s79
	s_cselect_b32 s0, s33, s78
	v_lshlrev_b64 v[8:9], 10, v[22:23]
	s_add_i32 s2, s2, s60
	v_lshl_add_u64 v[8:9], s[0:1], 0, v[8:9]
	s_lshl_b32 s0, s2, 8
	s_ashr_i32 s1, s0, 31
	v_mul_f32_e32 v10, 0xbfb8aa3b, v4
	v_lshl_add_u64 v[8:9], s[0:1], 1, v[8:9]
	v_ashrrev_i32_e32 v17, 31, v16
	v_mul_f32_e32 v11, 0xbfb8aa3b, v5
	v_exp_f32_e32 v10, v10
	v_lshl_add_u64 v[8:9], v[16:17], 1, v[8:9]
	v_exp_f32_e32 v11, v11
	v_mul_f32_e32 v14, 0xbfb8aa3b, v0
	v_mul_f32_e32 v15, 0xbfb8aa3b, v1
	v_mul_f32_e32 v16, 0xbfb8aa3b, v2
	v_mul_f32_e32 v17, 0xbfb8aa3b, v3
	v_exp_f32_e32 v14, v14
	v_exp_f32_e32 v15, v15
	v_exp_f32_e32 v16, v16
	v_exp_f32_e32 v17, v17
	v_mul_f32_e32 v12, 0xbfb8aa3b, v6
	v_mul_f32_e32 v13, 0xbfb8aa3b, v7
	v_exp_f32_e32 v12, v12
	v_exp_f32_e32 v13, v13
	v_add_f32_e32 v10, 1.0, v10
	v_add_f32_e32 v11, 1.0, v11
	v_rcp_f32_e32 v10, v10
	v_rcp_f32_e32 v11, v11
	v_add_f32_e32 v14, 1.0, v14
	v_add_f32_e32 v15, 1.0, v15
	v_add_f32_e32 v16, 1.0, v16
	v_add_f32_e32 v17, 1.0, v17
	v_rcp_f32_e32 v14, v14
	v_rcp_f32_e32 v16, v16
	v_rcp_f32_e32 v17, v17
	v_rcp_f32_e32 v15, v15
	v_add_f32_e32 v12, 1.0, v12
	v_add_f32_e32 v13, 1.0, v13
	v_rcp_f32_e32 v12, v12
	v_rcp_f32_e32 v13, v13
	v_pk_mul_f32 v[4:5], v[4:5], v[10:11]
	v_pk_mul_f32 v[10:11], v[2:3], v[16:17]
	v_pk_mul_f32 v[2:3], v[0:1], v[14:15]
	v_pk_mul_f32 v[6:7], v[6:7], v[12:13]
	v_cvt_pk_bf16_f32 v0, v4, v5
	v_cvt_pk_bf16_f32 v1, v6, v7
	v_cvt_pk_bf16_f32 v2, v2, v3
	v_cvt_pk_bf16_f32 v3, v10, v11
	global_store_dwordx4 v[8:9], v[0:3], off
	s_branch .LBB0_195

; __device__ __forceinline__ void st16f(float* p, f32x4 v) { st16(p, __builtin_bit_cast(u32x4, v)); }
; __device__ __forceinline__ void st8bf(bf16_t* p, f32x4 a, f32x4 b) { u32x4 w; w.x = pk2(a[0], a[1]); w.y = pk2(a[2], a[3]); w.z = pk2(b[0], b[1]); w.w = pk2(b[2], b[3]); st16(p, w); }
; __device__ __forceinline__ unsigned f2bf(float f) { unsigned u = __builtin_bit_cast(unsigned, f); return (u + 0x7fffu + ((u >> 16) & 1u)) >> 16; }
; __device__ __forceinline__ unsigned pk2(float lo, float hi) { return f2bf(lo) | (f2bf(hi) << 16); }
;     __device__ __forceinline__ void st(int pn, int row, int c, f32x4 v0, f32x4 v1) const {
;     ...
;         else if (pn == 10) { float* o = nullptr;
;             if (!smp) { if (t >= SEQ - 512) o = out + O_WIN + ((size_t)b * 512 + (t - (SEQ - 512))) * 256 + c; } else o = out + O_WINS + ((size_t)b * 512 + 508 + t) * 256 + c;
;             st8bf(KW + (size_t)row * 256 + c, v0, v1); if (o) { st16f(o, v0); st16f(o + 4, v1); } }
.LBB0_297:
	s_andn2_saveexec_b64 s[10:11], s[10:11]
	v_lshl_add_u64 v[144:145], v[214:215], 0, v[140:141]
	s_or_b64 exec, exec, s[10:11]
	v_cvt_pk_bf16_f32 v146, v120, v121
	v_cvt_pk_bf16_f32 v147, v122, v123
	v_cvt_pk_bf16_f32 v148, v116, v117
	v_bfe_u32 v149, v118, 16, 1
	v_add3_u32 v149, v118, v149, s81
	v_bfe_u32 v152, v119, 16, 1
	v_lshrrev_b32_e32 v149, 16, v149
	v_add3_u32 v152, v119, v152, s81
	v_lshl_add_u64 v[150:151], v[208:209], 0, v[138:139]
	v_and_or_b32 v149, v152, s25, v149
	v_cmp_ne_u64_e32 vcc, 0, v[144:145]
	global_store_dwordx4 v[150:151], v[146:149], off
	s_and_saveexec_b64 s[10:11], vcc
	s_cbranch_execz .LBB0_301
	global_store_dwordx4 v[144:145], v[120:123], off
	global_store_dwordx4 v[144:145], v[116:119], off offset:16

; __device__ __forceinline__ void st16f(float* p, f32x4 v) { st16(p, __builtin_bit_cast(u32x4, v)); }
; __device__ __forceinline__ void st8bf(bf16_t* p, f32x4 a, f32x4 b) { u32x4 w; w.x = pk2(a[0], a[1]); w.y = pk2(a[2], a[3]); w.z = pk2(b[0], b[1]); w.w = pk2(b[2], b[3]); st16(p, w); }
; __device__ __forceinline__ unsigned f2bf(float f) { unsigned u = __builtin_bit_cast(unsigned, f); return (u + 0x7fffu + ((u >> 16) & 1u)) >> 16; }
; __device__ __forceinline__ unsigned pk2(float lo, float hi) { return f2bf(lo) | (f2bf(hi) << 16); }
;     __device__ __forceinline__ void st(int pn, int row, int c, f32x4 v0, f32x4 v1) const {
;     ...
;         else if (pn == 8) { float* o = (smp ? out + O_KCS + (size_t)(row - MP) * 256 : out + O_KC + (size_t)row * 256) + c; st16f(o, v0); st16f(o + 4, v1); }
;         else if (pn == 9) { float* o = (smp ? out + O_KSS + (size_t)(row - MP) * 256 : out + O_KSEL + (size_t)row * 256) + c; st16f(o, v0); st16f(o + 4, v1); st8bf(KS + (size_t)row * 256 + c, v0, v1); }
.LBB0_303:
	s_andn2_b64 vcc, exec, s[10:11]
	s_cbranch_vccnz .LBB0_305
	v_lshl_add_u64 v[144:145], s[36:37], 0, v[2:3]
	v_lshl_add_u64 v[146:147], s[38:39], 0, v[136:137]
	v_cndmask_b32_e64 v145, v145, v147, s[4:5]
	v_cndmask_b32_e64 v144, v144, v146, s[4:5]
	v_lshlrev_b32_e32 v146, 2, v206
	v_mov_b32_e32 v147, v1
	v_cndmask_b32_e64 v149, v133, 0, s[4:5]
	v_cndmask_b32_e64 v148, v132, v132, s[4:5]
	v_lshl_add_u64 v[144:145], v[144:145], 0, v[146:147]
	global_store_dwordx4 v[144:145], v[120:123], off
	global_store_dwordx4 v[144:145], v[116:119], off offset:16
	v_lshlrev_b64 v[144:145], 9, v[148:149]
	v_lshl_add_u64 v[148:149], v[210:211], 0, v[144:145]
	v_cvt_pk_bf16_f32 v144, v120, v121
	v_cvt_pk_bf16_f32 v145, v122, v123
	v_cvt_pk_bf16_f32 v146, v116, v117
	v_bfe_u32 v147, v118, 16, 1
	v_add3_u32 v147, v118, v147, s81
	v_bfe_u32 v150, v119, 16, 1
	v_lshrrev_b32_e32 v147, 16, v147
	v_add3_u32 v150, v119, v150, s81
	v_and_or_b32 v147, v150, s25, v147
	global_store_dwordx4 v[148:149], v[144:147], off

; __device__ __forceinline__ void st8bf(bf16_t* p, f32x4 a, f32x4 b) { u32x4 w; w.x = pk2(a[0], a[1]); w.y = pk2(a[2], a[3]); w.z = pk2(b[0], b[1]); w.w = pk2(b[2], b[3]); st16(p, w); }
; __device__ __forceinline__ unsigned f2bf(float f) { unsigned u = __builtin_bit_cast(unsigned, f); return (u + 0x7fffu + ((u >> 16) & 1u)) >> 16; }
; __device__ __forceinline__ unsigned pk2(float lo, float hi) { return f2bf(lo) | (f2bf(hi) << 16); }
;     __device__ __forceinline__ void st(int pn, int row, int c, f32x4 v0, f32x4 v1) const {
;     ...
;         else if (pn < 8) st8bf(Q + (size_t)row * 512 + (pn - 6) * 256 + c, v0 * C2, v1 * C2);
.LBB0_309:
	s_and_b64 vcc, exec, s[10:11]
	s_cbranch_vccz .LBB0_311
	v_lshl_add_u64 v[144:145], s[28:29], 0, v[2:3]
	s_lshl_b32 s40, s43, 1
	v_lshl_add_u64 v[144:145], v[144:145], 0, s[40:41]
	v_lshlrev_b32_e32 v146, 1, v206
	v_mov_b32_e32 v147, v1
	v_lshl_add_u64 v[148:149], v[144:145], 0, v[146:147]
	v_pk_mul_f32 v[144:145], v[120:121], s[50:51] op_sel_hi:[1,0]
	v_pk_mul_f32 v[146:147], v[122:123], s[50:51] op_sel_hi:[1,0]
	v_cvt_pk_bf16_f32 v144, v144, v145
	v_pk_mul_f32 v[152:153], v[116:117], s[50:51] op_sel_hi:[1,0]
	v_cvt_pk_bf16_f32 v145, v146, v147
	v_pk_mul_f32 v[150:151], v[118:119], s[50:51] op_sel_hi:[1,0]
	v_cvt_pk_bf16_f32 v146, v152, v153
	v_cvt_pk_bf16_f32 v147, v150, v151
	global_store_dwordx4 v[148:149], v[144:147], off offset:-3072

; __device__ __forceinline__ void st16f(float* p, f32x4 v) { st16(p, __builtin_bit_cast(u32x4, v)); }
; __device__ __forceinline__ void st8bf(bf16_t* p, f32x4 a, f32x4 b) { u32x4 w; w.x = pk2(a[0], a[1]); w.y = pk2(a[2], a[3]); w.z = pk2(b[0], b[1]); w.w = pk2(b[2], b[3]); st16(p, w); }
; __device__ __forceinline__ unsigned f2bf(float f) { unsigned u = __builtin_bit_cast(unsigned, f); return (u + 0x7fffu + ((u >> 16) & 1u)) >> 16; }
; __device__ __forceinline__ unsigned pk2(float lo, float hi) { return f2bf(lo) | (f2bf(hi) << 16); }
;     __device__ __forceinline__ void st(int pn, int row, int c, f32x4 v0, f32x4 v1) const {
;     ...
;         else if (pn == 10) { float* o = nullptr;
;             if (!smp) { if (t >= SEQ - 512) o = out + O_WIN + ((size_t)b * 512 + (t - (SEQ - 512))) * 256 + c; } else o = out + O_WINS + ((size_t)b * 512 + 508 + t) * 256 + c;
;             st8bf(KW + (size_t)row * 256 + c, v0, v1); if (o) { st16f(o, v0); st16f(o + 4, v1); } }
.LBB0_319:
	s_andn2_saveexec_b64 s[6:7], s[8:9]
	v_lshl_add_u64 v[140:141], v[214:215], 0, v[140:141]
	s_mov_b64 s[8:9], 0x200
	v_lshl_add_u64 v[144:145], v[140:141], 0, s[8:9]
	s_or_b64 exec, exec, s[6:7]
	v_lshl_add_u64 v[142:143], v[216:217], 0, v[138:139]
	v_cvt_pk_bf16_f32 v138, v128, v129
	v_cvt_pk_bf16_f32 v139, v130, v131
	v_cvt_pk_bf16_f32 v140, v124, v125
	v_cvt_pk_bf16_f32 v141, v126, v127
	v_cmp_ne_u64_e32 vcc, 0, v[144:145]
	global_store_dwordx4 v[142:143], v[138:141], off
	s_and_saveexec_b64 s[6:7], vcc
	s_cbranch_execz .LBB0_323
	global_store_dwordx4 v[144:145], v[128:131], off
	global_store_dwordx4 v[144:145], v[124:127], off offset:16

; __device__ __forceinline__ void st16f(float* p, f32x4 v) { st16(p, __builtin_bit_cast(u32x4, v)); }
; __device__ __forceinline__ void st8bf(bf16_t* p, f32x4 a, f32x4 b) { u32x4 w; w.x = pk2(a[0], a[1]); w.y = pk2(a[2], a[3]); w.z = pk2(b[0], b[1]); w.w = pk2(b[2], b[3]); st16(p, w); }
; __device__ __forceinline__ unsigned f2bf(float f) { unsigned u = __builtin_bit_cast(unsigned, f); return (u + 0x7fffu + ((u >> 16) & 1u)) >> 16; }
; __device__ __forceinline__ unsigned pk2(float lo, float hi) { return f2bf(lo) | (f2bf(hi) << 16); }
;     __device__ __forceinline__ void st(int pn, int row, int c, f32x4 v0, f32x4 v1) const {
;     ...
;         else if (pn == 8) { float* o = (smp ? out + O_KCS + (size_t)(row - MP) * 256 : out + O_KC + (size_t)row * 256) + c; st16f(o, v0); st16f(o + 4, v1); }
;         else if (pn == 9) { float* o = (smp ? out + O_KSS + (size_t)(row - MP) * 256 : out + O_KSEL + (size_t)row * 256) + c; st16f(o, v0); st16f(o + 4, v1); st8bf(KS + (size_t)row * 256 + c, v0, v1); }
.LBB0_325:
	s_andn2_b64 vcc, exec, s[10:11]
	s_cbranch_vccnz .LBB0_327
	v_lshl_add_u64 v[138:139], s[36:37], 0, v[2:3]
	v_lshl_add_u64 v[136:137], s[38:39], 0, v[136:137]
	v_cndmask_b32_e64 v137, v139, v137, s[4:5]
	v_cndmask_b32_e64 v136, v138, v136, s[4:5]
	v_lshlrev_b32_e32 v138, 2, v206
	v_mov_b32_e32 v139, v1
	v_cndmask_b32_e64 v141, v133, 0, s[4:5]
	v_cndmask_b32_e64 v140, v132, v132, s[4:5]
	v_lshl_add_u64 v[136:137], v[136:137], 0, v[138:139]
	global_store_dwordx4 v[136:137], v[128:131], off offset:512
	global_store_dwordx4 v[136:137], v[124:127], off offset:528
	v_lshlrev_b64 v[136:137], 9, v[140:141]
	v_lshl_add_u64 v[140:141], v[218:219], 0, v[136:137]
	v_cvt_pk_bf16_f32 v136, v128, v129
	v_cvt_pk_bf16_f32 v137, v130, v131
	v_cvt_pk_bf16_f32 v138, v124, v125
	v_cvt_pk_bf16_f32 v139, v126, v127
	global_store_dwordx4 v[140:141], v[136:139], off

; __device__ __forceinline__ void st8bf(bf16_t* p, f32x4 a, f32x4 b) { u32x4 w; w.x = pk2(a[0], a[1]); w.y = pk2(a[2], a[3]); w.z = pk2(b[0], b[1]); w.w = pk2(b[2], b[3]); st16(p, w); }
; __device__ __forceinline__ unsigned f2bf(float f) { unsigned u = __builtin_bit_cast(unsigned, f); return (u + 0x7fffu + ((u >> 16) & 1u)) >> 16; }
; __device__ __forceinline__ unsigned pk2(float lo, float hi) { return f2bf(lo) | (f2bf(hi) << 16); }
;     __device__ __forceinline__ void st(int pn, int row, int c, f32x4 v0, f32x4 v1) const {
;     ...
;         else if (pn < 8) st8bf(Q + (size_t)row * 512 + (pn - 6) * 256 + c, v0 * C2, v1 * C2);
.LBB0_331:
	s_and_b64 vcc, exec, s[10:11]
	s_cbranch_vccz .LBB0_333
	v_lshl_add_u64 v[134:135], s[28:29], 0, v[2:3]
	s_lshl_b32 s40, s43, 1
	v_lshl_add_u64 v[134:135], v[134:135], 0, s[40:41]
	v_lshlrev_b32_e32 v0, 1, v206
	v_lshl_add_u64 v[138:139], v[134:135], 0, v[0:1]
	v_pk_mul_f32 v[134:135], v[128:129], s[50:51] op_sel_hi:[1,0]
	v_pk_mul_f32 v[136:137], v[130:131], s[50:51] op_sel_hi:[1,0]
	v_cvt_pk_bf16_f32 v134, v134, v135
	v_pk_mul_f32 v[142:143], v[124:125], s[50:51] op_sel_hi:[1,0]
	v_cvt_pk_bf16_f32 v135, v136, v137
	v_pk_mul_f32 v[140:141], v[126:127], s[50:51] op_sel_hi:[1,0]
	v_cvt_pk_bf16_f32 v136, v142, v143
	v_cvt_pk_bf16_f32 v137, v140, v141
	global_store_dwordx4 v[138:139], v[134:137], off offset:-2816

; __device__ __forceinline__ void st8bf(bf16_t* p, f32x4 a, f32x4 b) { u32x4 w; w.x = pk2(a[0], a[1]); w.y = pk2(a[2], a[3]); w.z = pk2(b[0], b[1]); w.w = pk2(b[2], b[3]); st16(p, w); }
; __device__ __forceinline__ f32x4 sig4(f32x4 v) { f32x4 r; r[0] = sigmoidf_(v[0]); r[1] = sigmoidf_(v[1]); r[2] = sigmoidf_(v[2]); r[3] = sigmoidf_(v[3]); return r; }
; __device__ __forceinline__ float sigmoidf_(float x) { return __builtin_amdgcn_rcpf(1.0f + __expf(-x)); }
; __device__ __forceinline__ float siluf_(float x) { return x * sigmoidf_(x); }
;     __device__ __forceinline__ void st(int pn, int row, int c, f32x4 v0, f32x4 v1) const {
;         const bool smp = row >= MP; const int b = smp ? (row - MP) >> 2 : row >> 13, t = smp ? (row - MP) & 3 : row & (SEQ - 1);
;         if (pn < 6 || pn == 11 || pn == 12) st8bf((pn < 6 ? AG : BG) + (size_t)row * 512 + (pn < 6 ? pn - 4 : pn - 11) * 256 + c, v0 * sig4(v0), v1 * sig4(v1));
.LBB0_335:
	s_and_b64 s[10:11], s[66:67], exec
	s_cselect_b32 s11, s51, s79
	s_cselect_b32 s10, s33, s78
	v_lshl_add_u64 v[144:145], s[10:11], 0, v[2:3]
	v_mul_f32_e32 v146, 0xbfb8aa3b, v120
	v_lshl_add_u64 v[144:145], s[64:65], 1, v[144:145]
	v_exp_f32_e32 v150, v146
	v_lshlrev_b32_e32 v146, 1, v206
	v_mov_b32_e32 v147, v1
	v_lshl_add_u64 v[148:149], v[144:145], 0, v[146:147]
	v_mul_f32_e32 v145, 0xbfb8aa3b, v121
	v_exp_f32_e32 v145, v145
	v_mul_f32_e32 v146, 0xbfb8aa3b, v122
	v_mul_f32_e32 v147, 0xbfb8aa3b, v123
	v_exp_f32_e32 v146, v146
	v_exp_f32_e32 v147, v147
	v_add_f32_e32 v144, 1.0, v150
	v_add_f32_e32 v145, 1.0, v145
	v_rcp_f32_e32 v144, v144
	v_rcp_f32_e32 v145, v145
	v_mul_f32_e32 v150, 0xbfb8aa3b, v116
	v_mul_f32_e32 v151, 0xbfb8aa3b, v117
	v_exp_f32_e32 v150, v150
	v_exp_f32_e32 v151, v151
	v_add_f32_e32 v146, 1.0, v146
	v_add_f32_e32 v147, 1.0, v147
	v_rcp_f32_e32 v146, v146
	v_rcp_f32_e32 v147, v147
	v_mul_f32_e32 v152, 0xbfb8aa3b, v118
	v_mul_f32_e32 v153, 0xbfb8aa3b, v119
	v_exp_f32_e32 v152, v152
	v_exp_f32_e32 v153, v153
	v_pk_mul_f32 v[144:145], v[120:121], v[144:145]
	v_add_f32_e32 v150, 1.0, v150
	v_add_f32_e32 v151, 1.0, v151
	v_bfe_u32 v154, v144, 16, 1
	v_rcp_f32_e32 v150, v150
	v_rcp_f32_e32 v151, v151
	v_add3_u32 v144, v144, v154, s81
	v_bfe_u32 v154, v145, 16, 1
	v_pk_mul_f32 v[146:147], v[122:123], v[146:147]
	v_lshrrev_b32_e32 v144, 16, v144
	v_add3_u32 v145, v145, v154, s81
	v_add_f32_e32 v152, 1.0, v152
	v_add_f32_e32 v153, 1.0, v153
	v_and_or_b32 v144, v145, s25, v144
	v_rcp_f32_e32 v152, v152
	v_rcp_f32_e32 v153, v153
	v_pk_mul_f32 v[150:151], v[116:117], v[150:151]
	v_cvt_pk_bf16_f32 v145, v146, v147
	v_pk_mul_f32 v[152:153], v[118:119], v[152:153]
	v_cvt_pk_bf16_f32 v146, v150, v151
	v_bfe_u32 v147, v152, 16, 1
	v_add3_u32 v147, v152, v147, s81
	v_bfe_u32 v150, v153, 16, 1
	v_lshrrev_b32_e32 v147, 16, v147
	v_add3_u32 v150, v153, v150, s81
	v_and_or_b32 v147, v150, s25, v147
	global_store_dwordx4 v[148:149], v[144:147], off
	s_andn2_b64 vcc, exec, s[68:69]
	s_mov_b64 s[10:11], -1
	s_cbranch_vccz .LBB0_313

; __device__ __forceinline__ void st8bf(bf16_t* p, f32x4 a, f32x4 b) { u32x4 w; w.x = pk2(a[0], a[1]); w.y = pk2(a[2], a[3]); w.z = pk2(b[0], b[1]); w.w = pk2(b[2], b[3]); st16(p, w); }
; __device__ __forceinline__ f32x4 sig4(f32x4 v) { f32x4 r; r[0] = sigmoidf_(v[0]); r[1] = sigmoidf_(v[1]); r[2] = sigmoidf_(v[2]); r[3] = sigmoidf_(v[3]); return r; }
; __device__ __forceinline__ float sigmoidf_(float x) { return __builtin_amdgcn_rcpf(1.0f + __expf(-x)); }
; __device__ __forceinline__ float siluf_(float x) { return x * sigmoidf_(x); }
;     __device__ __forceinline__ void st(int pn, int row, int c, f32x4 v0, f32x4 v1) const {
;         const bool smp = row >= MP; const int b = smp ? (row - MP) >> 2 : row >> 13, t = smp ? (row - MP) & 3 : row & (SEQ - 1);
;         if (pn < 6 || pn == 11 || pn == 12) st8bf((pn < 6 ? AG : BG) + (size_t)row * 512 + (pn < 6 ? pn - 4 : pn - 11) * 256 + c, v0 * sig4(v0), v1 * sig4(v1));
.LBB0_337:
	v_mul_f32_e32 v0, 0xbfb8aa3b, v128
	s_and_b64 s[6:7], s[66:67], exec
	v_exp_f32_e32 v133, v0
	s_cselect_b32 s7, s51, s79
	s_cselect_b32 s6, s33, s78
	v_lshl_add_u64 v[2:3], s[6:7], 0, v[2:3]
	v_lshl_add_u64 v[2:3], s[64:65], 1, v[2:3]
	v_lshlrev_b32_e32 v0, 1, v206
	v_lshl_add_u64 v[2:3], v[2:3], 0, v[0:1]
	v_add_f32_e32 v0, 1.0, v133
	v_mul_f32_e32 v133, 0xbfb8aa3b, v129
	v_exp_f32_e32 v133, v133
	v_mul_f32_e32 v134, 0xbfb8aa3b, v130
	v_exp_f32_e32 v136, v134
	v_rcp_f32_e32 v134, v0
	v_add_f32_e32 v0, 1.0, v133
	v_mul_f32_e32 v133, 0xbfb8aa3b, v131
	v_rcp_f32_e32 v135, v0
	v_add_f32_e32 v0, 1.0, v136
	v_exp_f32_e32 v133, v133
	v_mul_f32_e32 v136, 0xbfb8aa3b, v124
	v_exp_f32_e32 v138, v136
	v_rcp_f32_e32 v136, v0
	v_add_f32_e32 v0, 1.0, v133
	v_rcp_f32_e32 v137, v0
	v_add_f32_e32 v0, 1.0, v138
	v_rcp_f32_e32 v138, v0
	v_mul_f32_e32 v0, 0xbfb8aa3b, v125
	v_mul_f32_e32 v133, 0xbfb8aa3b, v126
	v_exp_f32_e32 v0, v0
	v_exp_f32_e32 v133, v133
	v_mul_f32_e32 v139, 0xbfb8aa3b, v127
	v_exp_f32_e32 v139, v139
	v_add_f32_e32 v0, 1.0, v0
	v_add_f32_e32 v133, 1.0, v133
	v_pk_mul_f32 v[134:135], v[128:129], v[134:135]
	v_rcp_f32_e32 v140, v133
	v_add_f32_e32 v133, 1.0, v139
	v_rcp_f32_e32 v139, v0
	v_rcp_f32_e32 v141, v133
	v_pk_mul_f32 v[136:137], v[130:131], v[136:137]
	v_cvt_pk_bf16_f32 v134, v134, v135
	v_pk_mul_f32 v[138:139], v[124:125], v[138:139]
	v_cvt_pk_bf16_f32 v135, v136, v137
	v_pk_mul_f32 v[140:141], v[126:127], v[140:141]
	v_cvt_pk_bf16_f32 v136, v138, v139
	v_cvt_pk_bf16_f32 v137, v140, v141
	global_store_dwordx4 v[2:3], v[134:137], off offset:256

; __device__ __forceinline__ void st16f(float* p, f32x4 v) { st16(p, __builtin_bit_cast(u32x4, v)); }
; __device__ __forceinline__ void st8bf(bf16_t* p, f32x4 a, f32x4 b) { u32x4 w; w.x = pk2(a[0], a[1]); w.y = pk2(a[2], a[3]); w.z = pk2(b[0], b[1]); w.w = pk2(b[2], b[3]); st16(p, w); }
; __device__ __forceinline__ f32x4 sig4(f32x4 v) { f32x4 r; r[0] = sigmoidf_(v[0]); r[1] = sigmoidf_(v[1]); r[2] = sigmoidf_(v[2]); r[3] = sigmoidf_(v[3]); return r; }
;     __device__ __forceinline__ void st_glu(int pn, int row, int c, f32x4 a0, f32x4 a1, f32x4 g0, f32x4 g1) const {
;         const bool smp = row >= MP; const int b = smp ? (row - MP) >> 2 : row >> 13, t = smp ? (row - MP) & 3 : row & (SEQ - 1);
;         const f32x4 v0 = a0 * sig4(g0), v1 = a1 * sig4(g1);
;         const int col = pn * 128 + c;
;         st8bf(U + (size_t)row * 512 + col, v0, v1);
;         float* o = nullptr;
;         if (!smp) { if (t >= SEQ - 30) o = out + O_CONV + ((size_t)b * 30 + (t - (SEQ - 30))) * 512 + col; }
;         else o = out + O_CONVS + ((size_t)b * 30 + 26 + t) * 512 + col;
;         if (o) { st16f(o, v0); st16f(o + 4, v1); }
.LBB0_339:
	v_lshl_or_b32 v2, s62, 7, v206
	v_ashrrev_i32_e32 v3, 31, v2
	s_and_b64 vcc, exec, s[6:7]
	s_cbranch_vccz .LBB0_345
	v_mul_f32_e32 v0, 0xbfb8aa3b, v128
	v_exp_f32_e32 v0, v0
	v_mul_f32_e32 v128, 0xbfb8aa3b, v129
	v_mul_f32_e32 v129, 0xbfb8aa3b, v130
	v_exp_f32_e32 v130, v128
	v_add_f32_e32 v0, 1.0, v0
	v_exp_f32_e32 v133, v129
	v_rcp_f32_e32 v128, v0
	v_add_f32_e32 v0, 1.0, v130
	v_mul_f32_e32 v130, 0xbfb8aa3b, v131
	v_exp_f32_e32 v131, v130
	v_mul_f32_e32 v124, 0xbfb8aa3b, v124
	v_exp_f32_e32 v124, v124
	v_rcp_f32_e32 v129, v0
	v_add_f32_e32 v0, 1.0, v133
	v_rcp_f32_e32 v130, v0
	v_add_f32_e32 v0, 1.0, v131
	v_rcp_f32_e32 v131, v0
	v_add_f32_e32 v0, 1.0, v124
	v_rcp_f32_e32 v124, v0
	v_mul_f32_e32 v0, 0xbfb8aa3b, v125
	v_mul_f32_e32 v125, 0xbfb8aa3b, v126
	v_exp_f32_e32 v125, v125
	v_mul_f32_e32 v126, 0xbfb8aa3b, v127
	v_exp_f32_e32 v0, v0
	v_exp_f32_e32 v127, v126
	v_add_f32_e32 v125, 1.0, v125
	v_rcp_f32_e32 v126, v125
	v_add_f32_e32 v0, 1.0, v0
	v_add_f32_e32 v125, 1.0, v127
	v_rcp_f32_e32 v127, v125
	v_rcp_f32_e32 v125, v0
	v_ashrrev_i32_e32 v133, 31, v132
	v_pk_mul_f32 v[120:121], v[120:121], v[128:129]
	v_pk_mul_f32 v[122:123], v[122:123], v[130:131]
	v_pk_mul_f32 v[116:117], v[116:117], v[124:125]
	v_lshlrev_b64 v[124:125], 10, v[132:133]
	v_lshl_add_u64 v[124:125], s[26:27], 0, v[124:125]
	v_lshl_add_u64 v[128:129], v[2:3], 1, v[124:125]
	v_cvt_pk_bf16_f32 v124, v120, v121
	v_cvt_pk_bf16_f32 v125, v122, v123
	v_pk_mul_f32 v[118:119], v[118:119], v[126:127]
	v_cvt_pk_bf16_f32 v126, v116, v117
	v_cvt_pk_bf16_f32 v127, v118, v119
	global_store_dwordx4 v[128:129], v[124:127], off
	s_nop 1
	v_mov_b64_e32 v[124:125], 0
	s_and_saveexec_b64 s[6:7], s[4:5]
	v_add_u32_e32 v0, 0xffff8000, v132
	v_lshrrev_b32_e32 v0, 2, v0
	v_mad_u64_u32 v[124:125], s[4:5], v0, 30, v[196:197]
	v_lshlrev_b64 v[124:125], 11, v[124:125]
	v_lshl_add_u64 v[124:125], s[34:35], 0, v[124:125]
	v_lshl_add_u64 v[124:125], v[2:3], 2, v[124:125]
	s_or_b64 exec, exec, s[6:7]
	v_cmp_ne_u64_e32 vcc, 0, v[124:125]
	s_and_saveexec_b64 s[4:5], vcc
	s_cbranch_execz .LBB0_344
	global_store_dwordx4 v[124:125], v[120:123], off
	global_store_dwordx4 v[124:125], v[116:119], off offset:16

; __device__ __forceinline__ void st16f(float* p, f32x4 v) { st16(p, __builtin_bit_cast(u32x4, v)); }
; __device__ __forceinline__ void st8bf(bf16_t* p, f32x4 a, f32x4 b) { u32x4 w; w.x = pk2(a[0], a[1]); w.y = pk2(a[2], a[3]); w.z = pk2(b[0], b[1]); w.w = pk2(b[2], b[3]); st16(p, w); }
; __device__ __forceinline__ unsigned f2bf(float f) { unsigned u = __builtin_bit_cast(unsigned, f); return (u + 0x7fffu + ((u >> 16) & 1u)) >> 16; }
; __device__ __forceinline__ unsigned pk2(float lo, float hi) { return f2bf(lo) | (f2bf(hi) << 16); }
;     __device__ __forceinline__ void st(int pn, int row, int c, f32x4 v0, f32x4 v1) const {
;     ...
;         else if (pn == 10) { float* o = nullptr;
;             if (!smp) { if (t >= SEQ - 512) o = out + O_WIN + ((size_t)b * 512 + (t - (SEQ - 512))) * 256 + c; } else o = out + O_WINS + ((size_t)b * 512 + 508 + t) * 256 + c;
;             st8bf(KW + (size_t)row * 256 + c, v0, v1); if (o) { st16f(o, v0); st16f(o + 4, v1); } }
.LBB0_357:
	s_andn2_saveexec_b64 s[76:77], s[76:77]
	v_lshl_add_u64 v[130:131], v[214:215], 0, v[126:127]
	s_or_b64 exec, exec, s[76:77]
	v_cvt_pk_bf16_f32 v134, v104, v105
	v_cvt_pk_bf16_f32 v135, v106, v107
	v_cvt_pk_bf16_f32 v136, v100, v101
	v_lshl_add_u64 v[138:139], v[208:209], 0, v[124:125]
	v_cvt_pk_bf16_f32 v137, v102, v103
	v_cmp_ne_u64_e32 vcc, 0, v[130:131]
	global_store_dwordx4 v[138:139], v[134:137], off
	s_and_saveexec_b64 s[76:77], vcc
	s_cbranch_execz .LBB0_361
	global_store_dwordx4 v[130:131], v[104:107], off
	global_store_dwordx4 v[130:131], v[100:103], off offset:16

; __device__ __forceinline__ void st16f(float* p, f32x4 v) { st16(p, __builtin_bit_cast(u32x4, v)); }
; __device__ __forceinline__ void st8bf(bf16_t* p, f32x4 a, f32x4 b) { u32x4 w; w.x = pk2(a[0], a[1]); w.y = pk2(a[2], a[3]); w.z = pk2(b[0], b[1]); w.w = pk2(b[2], b[3]); st16(p, w); }
; __device__ __forceinline__ unsigned f2bf(float f) { unsigned u = __builtin_bit_cast(unsigned, f); return (u + 0x7fffu + ((u >> 16) & 1u)) >> 16; }
; __device__ __forceinline__ unsigned pk2(float lo, float hi) { return f2bf(lo) | (f2bf(hi) << 16); }
;     __device__ __forceinline__ void st(int pn, int row, int c, f32x4 v0, f32x4 v1) const {
;     ...
;         else if (pn == 8) { float* o = (smp ? out + O_KCS + (size_t)(row - MP) * 256 : out + O_KC + (size_t)row * 256) + c; st16f(o, v0); st16f(o + 4, v1); }
;         else if (pn == 9) { float* o = (smp ? out + O_KSS + (size_t)(row - MP) * 256 : out + O_KSEL + (size_t)row * 256) + c; st16f(o, v0); st16f(o + 4, v1); st8bf(KS + (size_t)row * 256 + c, v0, v1); }
.LBB0_363:
	s_andn2_b64 vcc, exec, s[76:77]
	s_cbranch_vccnz .LBB0_365
	v_lshl_add_u64 v[130:131], s[36:37], 0, v[118:119]
	v_lshl_add_u64 v[134:135], s[38:39], 0, v[122:123]
	v_cndmask_b32_e64 v131, v131, v135, s[6:7]
	v_cndmask_b32_e64 v130, v130, v134, s[6:7]
	v_lshlrev_b32_e32 v134, 2, v206
	v_mov_b32_e32 v135, v1
	v_lshl_add_u64 v[130:131], v[130:131], 0, v[134:135]
	v_cvt_pk_bf16_f32 v134, v104, v105
	v_cndmask_b32_e64 v137, v117, 0, s[6:7]
	v_cndmask_b32_e64 v136, v116, v116, s[6:7]
	v_cvt_pk_bf16_f32 v135, v106, v107
	global_store_dwordx4 v[130:131], v[104:107], off
	global_store_dwordx4 v[130:131], v[100:103], off offset:16
	v_lshlrev_b64 v[130:131], 9, v[136:137]
	v_cvt_pk_bf16_f32 v136, v100, v101
	v_lshl_add_u64 v[130:131], v[210:211], 0, v[130:131]
	v_cvt_pk_bf16_f32 v137, v102, v103
	global_store_dwordx4 v[130:131], v[134:137], off

; __device__ __forceinline__ void st8bf(bf16_t* p, f32x4 a, f32x4 b) { u32x4 w; w.x = pk2(a[0], a[1]); w.y = pk2(a[2], a[3]); w.z = pk2(b[0], b[1]); w.w = pk2(b[2], b[3]); st16(p, w); }
; __device__ __forceinline__ unsigned f2bf(float f) { unsigned u = __builtin_bit_cast(unsigned, f); return (u + 0x7fffu + ((u >> 16) & 1u)) >> 16; }
; __device__ __forceinline__ unsigned pk2(float lo, float hi) { return f2bf(lo) | (f2bf(hi) << 16); }
;     __device__ __forceinline__ void st(int pn, int row, int c, f32x4 v0, f32x4 v1) const {
;     ...
;         else if (pn < 8) st8bf(Q + (size_t)row * 512 + (pn - 6) * 256 + c, v0 * C2, v1 * C2);
.LBB0_369:
	s_and_b64 vcc, exec, s[76:77]
	s_cbranch_vccz .LBB0_371
	v_lshl_add_u64 v[130:131], s[28:29], 0, v[118:119]
	s_lshl_b32 s40, s43, 1
	v_lshl_add_u64 v[130:131], v[130:131], 0, s[40:41]
	v_lshlrev_b32_e32 v134, 1, v206
	v_mov_b32_e32 v135, v1
	v_lshl_add_u64 v[130:131], v[130:131], 0, v[134:135]
	v_pk_mul_f32 v[134:135], v[104:105], s[50:51] op_sel_hi:[1,0]
	v_pk_mul_f32 v[136:137], v[106:107], s[50:51] op_sel_hi:[1,0]
	v_cvt_pk_bf16_f32 v134, v134, v135
	v_pk_mul_f32 v[140:141], v[100:101], s[50:51] op_sel_hi:[1,0]
	v_cvt_pk_bf16_f32 v135, v136, v137
	v_pk_mul_f32 v[138:139], v[102:103], s[50:51] op_sel_hi:[1,0]
	v_cvt_pk_bf16_f32 v136, v140, v141
	v_cvt_pk_bf16_f32 v137, v138, v139
	global_store_dwordx4 v[130:131], v[134:137], off offset:-3072

; __device__ __forceinline__ void st16f(float* p, f32x4 v) { st16(p, __builtin_bit_cast(u32x4, v)); }
; __device__ __forceinline__ void st8bf(bf16_t* p, f32x4 a, f32x4 b) { u32x4 w; w.x = pk2(a[0], a[1]); w.y = pk2(a[2], a[3]); w.z = pk2(b[0], b[1]); w.w = pk2(b[2], b[3]); st16(p, w); }
; __device__ __forceinline__ unsigned f2bf(float f) { unsigned u = __builtin_bit_cast(unsigned, f); return (u + 0x7fffu + ((u >> 16) & 1u)) >> 16; }
; __device__ __forceinline__ unsigned pk2(float lo, float hi) { return f2bf(lo) | (f2bf(hi) << 16); }
;     __device__ __forceinline__ void st(int pn, int row, int c, f32x4 v0, f32x4 v1) const {
;     ...
;         else if (pn == 10) { float* o = nullptr;
;             if (!smp) { if (t >= SEQ - 512) o = out + O_WIN + ((size_t)b * 512 + (t - (SEQ - 512))) * 256 + c; } else o = out + O_WINS + ((size_t)b * 512 + 508 + t) * 256 + c;
;             st8bf(KW + (size_t)row * 256 + c, v0, v1); if (o) { st16f(o, v0); st16f(o + 4, v1); } }
.LBB0_379:
	s_andn2_saveexec_b64 s[8:9], s[10:11]
	v_lshl_add_u64 v[126:127], v[214:215], 0, v[126:127]
	s_mov_b64 s[10:11], 0x200
	v_lshl_add_u64 v[130:131], v[126:127], 0, s[10:11]
	s_or_b64 exec, exec, s[8:9]
	v_lshl_add_u64 v[128:129], v[216:217], 0, v[124:125]
	v_cvt_pk_bf16_f32 v124, v112, v113
	v_cvt_pk_bf16_f32 v125, v114, v115
	v_cvt_pk_bf16_f32 v126, v108, v109
	v_cvt_pk_bf16_f32 v127, v110, v111
	v_cmp_ne_u64_e32 vcc, 0, v[130:131]
	global_store_dwordx4 v[128:129], v[124:127], off
	s_and_saveexec_b64 s[8:9], vcc
	s_cbranch_execz .LBB0_383
	global_store_dwordx4 v[130:131], v[112:115], off
	global_store_dwordx4 v[130:131], v[108:111], off offset:16

; __device__ __forceinline__ void st16f(float* p, f32x4 v) { st16(p, __builtin_bit_cast(u32x4, v)); }
; __device__ __forceinline__ void st8bf(bf16_t* p, f32x4 a, f32x4 b) { u32x4 w; w.x = pk2(a[0], a[1]); w.y = pk2(a[2], a[3]); w.z = pk2(b[0], b[1]); w.w = pk2(b[2], b[3]); st16(p, w); }
; __device__ __forceinline__ unsigned f2bf(float f) { unsigned u = __builtin_bit_cast(unsigned, f); return (u + 0x7fffu + ((u >> 16) & 1u)) >> 16; }
; __device__ __forceinline__ unsigned pk2(float lo, float hi) { return f2bf(lo) | (f2bf(hi) << 16); }
;     __device__ __forceinline__ void st(int pn, int row, int c, f32x4 v0, f32x4 v1) const {
;     ...
;         else if (pn == 8) { float* o = (smp ? out + O_KCS + (size_t)(row - MP) * 256 : out + O_KC + (size_t)row * 256) + c; st16f(o, v0); st16f(o + 4, v1); }
;         else if (pn == 9) { float* o = (smp ? out + O_KSS + (size_t)(row - MP) * 256 : out + O_KSEL + (size_t)row * 256) + c; st16f(o, v0); st16f(o + 4, v1); st8bf(KS + (size_t)row * 256 + c, v0, v1); }
.LBB0_385:
	s_andn2_b64 vcc, exec, s[12:13]
	s_cbranch_vccnz .LBB0_387
	v_lshl_add_u64 v[124:125], s[36:37], 0, v[118:119]
	v_lshl_add_u64 v[122:123], s[38:39], 0, v[122:123]
	v_cndmask_b32_e64 v123, v125, v123, s[6:7]
	v_cndmask_b32_e64 v122, v124, v122, s[6:7]
	v_lshlrev_b32_e32 v124, 2, v206
	v_mov_b32_e32 v125, v1
	v_cndmask_b32_e64 v127, v117, 0, s[6:7]
	v_cndmask_b32_e64 v126, v116, v116, s[6:7]
	v_lshl_add_u64 v[122:123], v[122:123], 0, v[124:125]
	global_store_dwordx4 v[122:123], v[112:115], off offset:512
	global_store_dwordx4 v[122:123], v[108:111], off offset:528
	v_lshlrev_b64 v[122:123], 9, v[126:127]
	v_lshl_add_u64 v[126:127], v[218:219], 0, v[122:123]
	v_cvt_pk_bf16_f32 v122, v112, v113
	v_cvt_pk_bf16_f32 v123, v114, v115
	v_cvt_pk_bf16_f32 v124, v108, v109
	v_cvt_pk_bf16_f32 v125, v110, v111
	global_store_dwordx4 v[126:127], v[122:125], off

; __device__ __forceinline__ void st8bf(bf16_t* p, f32x4 a, f32x4 b) { u32x4 w; w.x = pk2(a[0], a[1]); w.y = pk2(a[2], a[3]); w.z = pk2(b[0], b[1]); w.w = pk2(b[2], b[3]); st16(p, w); }
; __device__ __forceinline__ unsigned f2bf(float f) { unsigned u = __builtin_bit_cast(unsigned, f); return (u + 0x7fffu + ((u >> 16) & 1u)) >> 16; }
; __device__ __forceinline__ unsigned pk2(float lo, float hi) { return f2bf(lo) | (f2bf(hi) << 16); }
;     __device__ __forceinline__ void st(int pn, int row, int c, f32x4 v0, f32x4 v1) const {
;     ...
;         else if (pn < 8) st8bf(Q + (size_t)row * 512 + (pn - 6) * 256 + c, v0 * C2, v1 * C2);
.LBB0_391:
	s_and_b64 vcc, exec, s[12:13]
	s_cbranch_vccz .LBB0_393
	v_lshl_add_u64 v[120:121], s[28:29], 0, v[118:119]
	s_lshl_b32 s40, s43, 1
	v_lshl_add_u64 v[120:121], v[120:121], 0, s[40:41]
	v_lshlrev_b32_e32 v0, 1, v206
	v_lshl_add_u64 v[124:125], v[120:121], 0, v[0:1]
	v_pk_mul_f32 v[120:121], v[112:113], s[50:51] op_sel_hi:[1,0]
	v_pk_mul_f32 v[122:123], v[114:115], s[50:51] op_sel_hi:[1,0]
	v_cvt_pk_bf16_f32 v120, v120, v121
	v_pk_mul_f32 v[128:129], v[108:109], s[50:51] op_sel_hi:[1,0]
	v_cvt_pk_bf16_f32 v121, v122, v123
	v_pk_mul_f32 v[126:127], v[110:111], s[50:51] op_sel_hi:[1,0]
	v_cvt_pk_bf16_f32 v122, v128, v129
	v_cvt_pk_bf16_f32 v123, v126, v127
	global_store_dwordx4 v[124:125], v[120:123], off offset:-2816

; __device__ __forceinline__ void st8bf(bf16_t* p, f32x4 a, f32x4 b) { u32x4 w; w.x = pk2(a[0], a[1]); w.y = pk2(a[2], a[3]); w.z = pk2(b[0], b[1]); w.w = pk2(b[2], b[3]); st16(p, w); }
; __device__ __forceinline__ f32x4 sig4(f32x4 v) { f32x4 r; r[0] = sigmoidf_(v[0]); r[1] = sigmoidf_(v[1]); r[2] = sigmoidf_(v[2]); r[3] = sigmoidf_(v[3]); return r; }
; __device__ __forceinline__ float sigmoidf_(float x) { return __builtin_amdgcn_rcpf(1.0f + __expf(-x)); }
; __device__ __forceinline__ float siluf_(float x) { return x * sigmoidf_(x); }
;     __device__ __forceinline__ void st(int pn, int row, int c, f32x4 v0, f32x4 v1) const {
;         const bool smp = row >= MP; const int b = smp ? (row - MP) >> 2 : row >> 13, t = smp ? (row - MP) & 3 : row & (SEQ - 1);
;         if (pn < 6 || pn == 11 || pn == 12) st8bf((pn < 6 ? AG : BG) + (size_t)row * 512 + (pn < 6 ? pn - 4 : pn - 11) * 256 + c, v0 * sig4(v0), v1 * sig4(v1));
.LBB0_395:
	s_and_b64 s[76:77], s[66:67], exec
	s_cselect_b32 s77, s51, s79
	s_cselect_b32 s76, s33, s78
	v_lshl_add_u64 v[130:131], s[76:77], 0, v[118:119]
	v_lshl_add_u64 v[130:131], s[64:65], 1, v[130:131]
	v_mul_f32_e32 v133, 0xbfb8aa3b, v104
	v_lshlrev_b32_e32 v134, 1, v206
	v_mov_b32_e32 v135, v1
	v_exp_f32_e32 v133, v133
	v_lshl_add_u64 v[130:131], v[130:131], 0, v[134:135]
	v_mul_f32_e32 v134, 0xbfb8aa3b, v105
	v_exp_f32_e32 v135, v134
	v_mul_f32_e32 v134, 0xbfb8aa3b, v106
	v_exp_f32_e32 v136, v134
	v_add_f32_e32 v133, 1.0, v133
	v_rcp_f32_e32 v134, v133
	v_add_f32_e32 v133, 1.0, v135
	v_rcp_f32_e32 v135, v133
	v_add_f32_e32 v133, 1.0, v136
	v_mul_f32_e32 v136, 0xbfb8aa3b, v107
	v_exp_f32_e32 v137, v136
	v_mul_f32_e32 v136, 0xbfb8aa3b, v100
	v_exp_f32_e32 v138, v136
	v_rcp_f32_e32 v136, v133
	v_add_f32_e32 v133, 1.0, v137
	v_rcp_f32_e32 v137, v133
	v_add_f32_e32 v133, 1.0, v138
	v_mul_f32_e32 v139, 0xbfb8aa3b, v102
	v_rcp_f32_e32 v138, v133
	v_mul_f32_e32 v133, 0xbfb8aa3b, v101
	v_exp_f32_e32 v139, v139
	v_mul_f32_e32 v140, 0xbfb8aa3b, v103
	v_exp_f32_e32 v133, v133
	v_exp_f32_e32 v141, v140
	v_add_f32_e32 v139, 1.0, v139
	v_rcp_f32_e32 v140, v139
	v_add_f32_e32 v133, 1.0, v133
	v_add_f32_e32 v139, 1.0, v141
	v_pk_mul_f32 v[134:135], v[104:105], v[134:135]
	v_rcp_f32_e32 v141, v139
	v_rcp_f32_e32 v139, v133
	v_pk_mul_f32 v[136:137], v[106:107], v[136:137]
	v_cvt_pk_bf16_f32 v134, v134, v135
	v_pk_mul_f32 v[138:139], v[100:101], v[138:139]
	v_cvt_pk_bf16_f32 v135, v136, v137
	v_pk_mul_f32 v[140:141], v[102:103], v[140:141]
	v_cvt_pk_bf16_f32 v136, v138, v139
	v_bfe_u32 v133, v140, 16, 1
	v_add3_u32 v133, v140, v133, s81
	v_bfe_u32 v137, v141, 16, 1
	v_lshrrev_b32_e32 v133, 16, v133
	v_add3_u32 v137, v141, v137, s81
	v_and_or_b32 v137, v137, s25, v133
	global_store_dwordx4 v[130:131], v[134:137], off
	s_and_b64 vcc, exec, s[12:13]
	s_mov_b64 s[12:13], -1
	s_cbranch_vccz .LBB0_373

; __device__ __forceinline__ void st8bf(bf16_t* p, f32x4 a, f32x4 b) { u32x4 w; w.x = pk2(a[0], a[1]); w.y = pk2(a[2], a[3]); w.z = pk2(b[0], b[1]); w.w = pk2(b[2], b[3]); st16(p, w); }
; __device__ __forceinline__ f32x4 sig4(f32x4 v) { f32x4 r; r[0] = sigmoidf_(v[0]); r[1] = sigmoidf_(v[1]); r[2] = sigmoidf_(v[2]); r[3] = sigmoidf_(v[3]); return r; }
; __device__ __forceinline__ float sigmoidf_(float x) { return __builtin_amdgcn_rcpf(1.0f + __expf(-x)); }
; __device__ __forceinline__ float siluf_(float x) { return x * sigmoidf_(x); }
;     __device__ __forceinline__ void st(int pn, int row, int c, f32x4 v0, f32x4 v1) const {
;         const bool smp = row >= MP; const int b = smp ? (row - MP) >> 2 : row >> 13, t = smp ? (row - MP) & 3 : row & (SEQ - 1);
;         if (pn < 6 || pn == 11 || pn == 12) st8bf((pn < 6 ? AG : BG) + (size_t)row * 512 + (pn < 6 ? pn - 4 : pn - 11) * 256 + c, v0 * sig4(v0), v1 * sig4(v1));
.LBB0_397:
	v_mul_f32_e32 v0, 0xbfb8aa3b, v112
	s_and_b64 s[8:9], s[66:67], exec
	v_exp_f32_e32 v117, v0
	s_cselect_b32 s9, s51, s79
	s_cselect_b32 s8, s33, s78
	v_lshl_add_u64 v[118:119], s[8:9], 0, v[118:119]
	v_lshl_add_u64 v[118:119], s[64:65], 1, v[118:119]
	v_lshlrev_b32_e32 v0, 1, v206
	v_lshl_add_u64 v[122:123], v[118:119], 0, v[0:1]
	v_add_f32_e32 v0, 1.0, v117
	v_mul_f32_e32 v117, 0xbfb8aa3b, v113
	v_exp_f32_e32 v117, v117
	v_mul_f32_e32 v118, 0xbfb8aa3b, v114
	v_exp_f32_e32 v120, v118
	v_rcp_f32_e32 v118, v0
	v_add_f32_e32 v0, 1.0, v117
	v_mul_f32_e32 v117, 0xbfb8aa3b, v115
	v_rcp_f32_e32 v119, v0
	v_add_f32_e32 v0, 1.0, v120
	v_exp_f32_e32 v117, v117
	v_mul_f32_e32 v120, 0xbfb8aa3b, v108
	v_exp_f32_e32 v124, v120
	v_rcp_f32_e32 v120, v0
	v_add_f32_e32 v0, 1.0, v117
	v_rcp_f32_e32 v121, v0
	v_add_f32_e32 v0, 1.0, v124
	v_rcp_f32_e32 v124, v0
	v_mul_f32_e32 v0, 0xbfb8aa3b, v109
	v_mul_f32_e32 v117, 0xbfb8aa3b, v110
	v_exp_f32_e32 v0, v0
	v_exp_f32_e32 v117, v117
	v_mul_f32_e32 v125, 0xbfb8aa3b, v111
	v_exp_f32_e32 v125, v125
	v_add_f32_e32 v0, 1.0, v0
	v_add_f32_e32 v117, 1.0, v117
	v_pk_mul_f32 v[118:119], v[112:113], v[118:119]
	v_rcp_f32_e32 v126, v117
	v_add_f32_e32 v117, 1.0, v125
	v_rcp_f32_e32 v125, v0
	v_rcp_f32_e32 v127, v117
	v_pk_mul_f32 v[120:121], v[114:115], v[120:121]
	v_cvt_pk_bf16_f32 v118, v118, v119
	v_pk_mul_f32 v[124:125], v[108:109], v[124:125]
	v_cvt_pk_bf16_f32 v119, v120, v121
	v_pk_mul_f32 v[126:127], v[110:111], v[126:127]
	v_cvt_pk_bf16_f32 v120, v124, v125
	v_cvt_pk_bf16_f32 v121, v126, v127
	global_store_dwordx4 v[122:123], v[118:121], off offset:256

; __device__ __forceinline__ void st16f(float* p, f32x4 v) { st16(p, __builtin_bit_cast(u32x4, v)); }
; __device__ __forceinline__ void st8bf(bf16_t* p, f32x4 a, f32x4 b) { u32x4 w; w.x = pk2(a[0], a[1]); w.y = pk2(a[2], a[3]); w.z = pk2(b[0], b[1]); w.w = pk2(b[2], b[3]); st16(p, w); }
; __device__ __forceinline__ f32x4 sig4(f32x4 v) { f32x4 r; r[0] = sigmoidf_(v[0]); r[1] = sigmoidf_(v[1]); r[2] = sigmoidf_(v[2]); r[3] = sigmoidf_(v[3]); return r; }
;     __device__ __forceinline__ void st_glu(int pn, int row, int c, f32x4 a0, f32x4 a1, f32x4 g0, f32x4 g1) const {
;         const bool smp = row >= MP; const int b = smp ? (row - MP) >> 2 : row >> 13, t = smp ? (row - MP) & 3 : row & (SEQ - 1);
;         const f32x4 v0 = a0 * sig4(g0), v1 = a1 * sig4(g1);
;         const int col = pn * 128 + c;
;         st8bf(U + (size_t)row * 512 + col, v0, v1);
;         float* o = nullptr;
;         if (!smp) { if (t >= SEQ - 30) o = out + O_CONV + ((size_t)b * 30 + (t - (SEQ - 30))) * 512 + col; }
;         else o = out + O_CONVS + ((size_t)b * 30 + 26 + t) * 512 + col;
;         if (o) { st16f(o, v0); st16f(o + 4, v1); }
.LBB0_399:
	s_and_b64 vcc, exec, s[8:9]
	s_cbranch_vccz .LBB0_405
	v_mul_f32_e32 v0, 0xbfb8aa3b, v112
	v_exp_f32_e32 v0, v0
	v_mul_f32_e32 v112, 0xbfb8aa3b, v113
	v_mul_f32_e32 v113, 0xbfb8aa3b, v114
	v_exp_f32_e32 v114, v112
	v_add_f32_e32 v0, 1.0, v0
	v_exp_f32_e32 v117, v113
	v_rcp_f32_e32 v112, v0
	v_add_f32_e32 v0, 1.0, v114
	v_mul_f32_e32 v114, 0xbfb8aa3b, v115
	v_exp_f32_e32 v115, v114
	v_mul_f32_e32 v108, 0xbfb8aa3b, v108
	v_exp_f32_e32 v108, v108
	v_rcp_f32_e32 v113, v0
	v_add_f32_e32 v0, 1.0, v117
	v_rcp_f32_e32 v114, v0
	v_add_f32_e32 v0, 1.0, v115
	v_rcp_f32_e32 v115, v0
	v_add_f32_e32 v0, 1.0, v108
	v_rcp_f32_e32 v108, v0
	v_mul_f32_e32 v0, 0xbfb8aa3b, v109
	v_mul_f32_e32 v109, 0xbfb8aa3b, v110
	v_exp_f32_e32 v109, v109
	v_mul_f32_e32 v110, 0xbfb8aa3b, v111
	v_exp_f32_e32 v0, v0
	v_exp_f32_e32 v111, v110
	v_add_f32_e32 v109, 1.0, v109
	v_rcp_f32_e32 v110, v109
	v_add_f32_e32 v0, 1.0, v0
	v_add_f32_e32 v109, 1.0, v111
	v_rcp_f32_e32 v111, v109
	v_rcp_f32_e32 v109, v0
	v_ashrrev_i32_e32 v117, 31, v116
	v_pk_mul_f32 v[104:105], v[104:105], v[112:113]
	v_pk_mul_f32 v[106:107], v[106:107], v[114:115]
	v_pk_mul_f32 v[100:101], v[100:101], v[108:109]
	v_lshlrev_b64 v[108:109], 10, v[116:117]
	v_lshl_add_u64 v[108:109], s[26:27], 0, v[108:109]
	v_lshl_add_u64 v[112:113], v[2:3], 1, v[108:109]
	v_cvt_pk_bf16_f32 v108, v104, v105
	v_cvt_pk_bf16_f32 v109, v106, v107
	v_pk_mul_f32 v[102:103], v[102:103], v[110:111]
	v_cvt_pk_bf16_f32 v110, v100, v101
	v_cvt_pk_bf16_f32 v111, v102, v103
	global_store_dwordx4 v[112:113], v[108:111], off
	s_nop 1
	v_mov_b64_e32 v[108:109], 0
	s_and_saveexec_b64 s[8:9], s[6:7]
	v_add_u32_e32 v0, 0xffff8010, v132
	v_lshrrev_b32_e32 v0, 2, v0
	v_mad_u64_u32 v[108:109], s[6:7], v0, 30, v[196:197]
	v_lshlrev_b64 v[108:109], 11, v[108:109]
	v_lshl_add_u64 v[108:109], s[34:35], 0, v[108:109]
	v_lshl_add_u64 v[108:109], v[2:3], 2, v[108:109]
	s_or_b64 exec, exec, s[8:9]
	v_cmp_ne_u64_e32 vcc, 0, v[108:109]
	s_and_saveexec_b64 s[6:7], vcc
	s_cbranch_execz .LBB0_404
	global_store_dwordx4 v[108:109], v[104:107], off
	global_store_dwordx4 v[108:109], v[100:103], off offset:16

; __device__ __forceinline__ void st16f(float* p, f32x4 v) { st16(p, __builtin_bit_cast(u32x4, v)); }
; __device__ __forceinline__ void st8bf(bf16_t* p, f32x4 a, f32x4 b) { u32x4 w; w.x = pk2(a[0], a[1]); w.y = pk2(a[2], a[3]); w.z = pk2(b[0], b[1]); w.w = pk2(b[2], b[3]); st16(p, w); }
; __device__ __forceinline__ unsigned f2bf(float f) { unsigned u = __builtin_bit_cast(unsigned, f); return (u + 0x7fffu + ((u >> 16) & 1u)) >> 16; }
; __device__ __forceinline__ unsigned pk2(float lo, float hi) { return f2bf(lo) | (f2bf(hi) << 16); }
;     __device__ __forceinline__ void st(int pn, int row, int c, f32x4 v0, f32x4 v1) const {
;     ...
;         else if (pn == 10) { float* o = nullptr;
;             if (!smp) { if (t >= SEQ - 512) o = out + O_WIN + ((size_t)b * 512 + (t - (SEQ - 512))) * 256 + c; } else o = out + O_WINS + ((size_t)b * 512 + 508 + t) * 256 + c;
;             st8bf(KW + (size_t)row * 256 + c, v0, v1); if (o) { st16f(o, v0); st16f(o + 4, v1); } }
.LBB0_417:
	s_andn2_saveexec_b64 s[76:77], s[76:77]
	v_lshl_add_u64 v[114:115], v[214:215], 0, v[110:111]
	s_or_b64 exec, exec, s[76:77]
	v_cvt_pk_bf16_f32 v116, v88, v89
	v_cvt_pk_bf16_f32 v117, v90, v91
	v_cvt_pk_bf16_f32 v118, v84, v85
	v_bfe_u32 v119, v86, 16, 1
	v_add3_u32 v119, v86, v119, s81
	v_bfe_u32 v122, v87, 16, 1
	v_lshrrev_b32_e32 v119, 16, v119
	v_add3_u32 v122, v87, v122, s81
	v_lshl_add_u64 v[120:121], v[208:209], 0, v[108:109]
	v_and_or_b32 v119, v122, s25, v119
	v_cmp_ne_u64_e32 vcc, 0, v[114:115]
	global_store_dwordx4 v[120:121], v[116:119], off
	s_and_saveexec_b64 s[76:77], vcc
	s_cbranch_execz .LBB0_421
	global_store_dwordx4 v[114:115], v[88:91], off
	global_store_dwordx4 v[114:115], v[84:87], off offset:16

; __device__ __forceinline__ void st16f(float* p, f32x4 v) { st16(p, __builtin_bit_cast(u32x4, v)); }
; __device__ __forceinline__ void st8bf(bf16_t* p, f32x4 a, f32x4 b) { u32x4 w; w.x = pk2(a[0], a[1]); w.y = pk2(a[2], a[3]); w.z = pk2(b[0], b[1]); w.w = pk2(b[2], b[3]); st16(p, w); }
; __device__ __forceinline__ unsigned f2bf(float f) { unsigned u = __builtin_bit_cast(unsigned, f); return (u + 0x7fffu + ((u >> 16) & 1u)) >> 16; }
; __device__ __forceinline__ unsigned pk2(float lo, float hi) { return f2bf(lo) | (f2bf(hi) << 16); }
;     __device__ __forceinline__ void st(int pn, int row, int c, f32x4 v0, f32x4 v1) const {
;     ...
;         else if (pn == 8) { float* o = (smp ? out + O_KCS + (size_t)(row - MP) * 256 : out + O_KC + (size_t)row * 256) + c; st16f(o, v0); st16f(o + 4, v1); }
;         else if (pn == 9) { float* o = (smp ? out + O_KSS + (size_t)(row - MP) * 256 : out + O_KSEL + (size_t)row * 256) + c; st16f(o, v0); st16f(o + 4, v1); st8bf(KS + (size_t)row * 256 + c, v0, v1); }
.LBB0_423:
	s_andn2_b64 vcc, exec, s[76:77]
	s_cbranch_vccnz .LBB0_425
	v_lshl_add_u64 v[114:115], s[36:37], 0, v[102:103]
	v_lshl_add_u64 v[116:117], s[38:39], 0, v[106:107]
	v_cndmask_b32_e64 v115, v115, v117, s[8:9]
	v_cndmask_b32_e64 v114, v114, v116, s[8:9]
	v_lshlrev_b32_e32 v116, 2, v206
	v_mov_b32_e32 v117, v1
	v_cndmask_b32_e64 v119, v101, 0, s[8:9]
	v_cndmask_b32_e64 v118, v100, v100, s[8:9]
	v_lshl_add_u64 v[114:115], v[114:115], 0, v[116:117]
	global_store_dwordx4 v[114:115], v[88:91], off
	global_store_dwordx4 v[114:115], v[84:87], off offset:16
	v_lshlrev_b64 v[114:115], 9, v[118:119]
	v_lshl_add_u64 v[118:119], v[210:211], 0, v[114:115]
	v_cvt_pk_bf16_f32 v114, v88, v89
	v_cvt_pk_bf16_f32 v115, v90, v91
	v_cvt_pk_bf16_f32 v116, v84, v85
	v_bfe_u32 v117, v86, 16, 1
	v_add3_u32 v117, v86, v117, s81
	v_bfe_u32 v120, v87, 16, 1
	v_lshrrev_b32_e32 v117, 16, v117
	v_add3_u32 v120, v87, v120, s81
	v_and_or_b32 v117, v120, s25, v117
	global_store_dwordx4 v[118:119], v[114:117], off

; __device__ __forceinline__ void st8bf(bf16_t* p, f32x4 a, f32x4 b) { u32x4 w; w.x = pk2(a[0], a[1]); w.y = pk2(a[2], a[3]); w.z = pk2(b[0], b[1]); w.w = pk2(b[2], b[3]); st16(p, w); }
; __device__ __forceinline__ unsigned f2bf(float f) { unsigned u = __builtin_bit_cast(unsigned, f); return (u + 0x7fffu + ((u >> 16) & 1u)) >> 16; }
; __device__ __forceinline__ unsigned pk2(float lo, float hi) { return f2bf(lo) | (f2bf(hi) << 16); }
;     __device__ __forceinline__ void st(int pn, int row, int c, f32x4 v0, f32x4 v1) const {
;     ...
;         else if (pn < 8) st8bf(Q + (size_t)row * 512 + (pn - 6) * 256 + c, v0 * C2, v1 * C2);
.LBB0_429:
	s_and_b64 vcc, exec, s[76:77]
	s_cbranch_vccz .LBB0_431
	v_lshl_add_u64 v[114:115], s[28:29], 0, v[102:103]
	s_lshl_b32 s40, s43, 1
	v_lshl_add_u64 v[114:115], v[114:115], 0, s[40:41]
	v_lshlrev_b32_e32 v116, 1, v206
	v_mov_b32_e32 v117, v1
	v_lshl_add_u64 v[118:119], v[114:115], 0, v[116:117]
	v_pk_mul_f32 v[114:115], v[88:89], s[50:51] op_sel_hi:[1,0]
	v_pk_mul_f32 v[116:117], v[90:91], s[50:51] op_sel_hi:[1,0]
	v_cvt_pk_bf16_f32 v114, v114, v115
	v_pk_mul_f32 v[122:123], v[84:85], s[50:51] op_sel_hi:[1,0]
	v_cvt_pk_bf16_f32 v115, v116, v117
	v_pk_mul_f32 v[120:121], v[86:87], s[50:51] op_sel_hi:[1,0]
	v_cvt_pk_bf16_f32 v116, v122, v123
	v_cvt_pk_bf16_f32 v117, v120, v121
	global_store_dwordx4 v[118:119], v[114:117], off offset:-3072

; __device__ __forceinline__ void st16f(float* p, f32x4 v) { st16(p, __builtin_bit_cast(u32x4, v)); }
; __device__ __forceinline__ void st8bf(bf16_t* p, f32x4 a, f32x4 b) { u32x4 w; w.x = pk2(a[0], a[1]); w.y = pk2(a[2], a[3]); w.z = pk2(b[0], b[1]); w.w = pk2(b[2], b[3]); st16(p, w); }
; __device__ __forceinline__ unsigned f2bf(float f) { unsigned u = __builtin_bit_cast(unsigned, f); return (u + 0x7fffu + ((u >> 16) & 1u)) >> 16; }
; __device__ __forceinline__ unsigned pk2(float lo, float hi) { return f2bf(lo) | (f2bf(hi) << 16); }
;     __device__ __forceinline__ void st(int pn, int row, int c, f32x4 v0, f32x4 v1) const {
;     ...
;         else if (pn == 10) { float* o = nullptr;
;             if (!smp) { if (t >= SEQ - 512) o = out + O_WIN + ((size_t)b * 512 + (t - (SEQ - 512))) * 256 + c; } else o = out + O_WINS + ((size_t)b * 512 + 508 + t) * 256 + c;
;             st8bf(KW + (size_t)row * 256 + c, v0, v1); if (o) { st16f(o, v0); st16f(o + 4, v1); } }
.LBB0_439:
	s_andn2_saveexec_b64 s[10:11], s[12:13]
	v_lshl_add_u64 v[110:111], v[214:215], 0, v[110:111]
	s_mov_b64 s[12:13], 0x200
	v_lshl_add_u64 v[114:115], v[110:111], 0, s[12:13]
	s_or_b64 exec, exec, s[10:11]
	v_lshl_add_u64 v[112:113], v[216:217], 0, v[108:109]
	v_cvt_pk_bf16_f32 v108, v96, v97
	v_cvt_pk_bf16_f32 v109, v98, v99
	v_cvt_pk_bf16_f32 v110, v92, v93
	v_cvt_pk_bf16_f32 v111, v94, v95
	v_cmp_ne_u64_e32 vcc, 0, v[114:115]
	global_store_dwordx4 v[112:113], v[108:111], off
	s_and_saveexec_b64 s[10:11], vcc
	s_cbranch_execz .LBB0_443
	global_store_dwordx4 v[114:115], v[96:99], off
	global_store_dwordx4 v[114:115], v[92:95], off offset:16

; __device__ __forceinline__ void st16f(float* p, f32x4 v) { st16(p, __builtin_bit_cast(u32x4, v)); }
; __device__ __forceinline__ void st8bf(bf16_t* p, f32x4 a, f32x4 b) { u32x4 w; w.x = pk2(a[0], a[1]); w.y = pk2(a[2], a[3]); w.z = pk2(b[0], b[1]); w.w = pk2(b[2], b[3]); st16(p, w); }
; __device__ __forceinline__ unsigned f2bf(float f) { unsigned u = __builtin_bit_cast(unsigned, f); return (u + 0x7fffu + ((u >> 16) & 1u)) >> 16; }
; __device__ __forceinline__ unsigned pk2(float lo, float hi) { return f2bf(lo) | (f2bf(hi) << 16); }
;     __device__ __forceinline__ void st(int pn, int row, int c, f32x4 v0, f32x4 v1) const {
;     ...
;         else if (pn == 8) { float* o = (smp ? out + O_KCS + (size_t)(row - MP) * 256 : out + O_KC + (size_t)row * 256) + c; st16f(o, v0); st16f(o + 4, v1); }
;         else if (pn == 9) { float* o = (smp ? out + O_KSS + (size_t)(row - MP) * 256 : out + O_KSEL + (size_t)row * 256) + c; st16f(o, v0); st16f(o + 4, v1); st8bf(KS + (size_t)row * 256 + c, v0, v1); }
.LBB0_445:
	s_andn2_b64 vcc, exec, s[12:13]
	s_cbranch_vccnz .LBB0_447
	v_lshl_add_u64 v[108:109], s[36:37], 0, v[102:103]
	v_lshl_add_u64 v[106:107], s[38:39], 0, v[106:107]
	v_cndmask_b32_e64 v107, v109, v107, s[8:9]
	v_cndmask_b32_e64 v106, v108, v106, s[8:9]
	v_lshlrev_b32_e32 v108, 2, v206
	v_mov_b32_e32 v109, v1
	v_cndmask_b32_e64 v111, v101, 0, s[8:9]
	v_cndmask_b32_e64 v110, v100, v100, s[8:9]
	v_lshl_add_u64 v[106:107], v[106:107], 0, v[108:109]
	global_store_dwordx4 v[106:107], v[96:99], off offset:512
	global_store_dwordx4 v[106:107], v[92:95], off offset:528
	v_lshlrev_b64 v[106:107], 9, v[110:111]
	v_lshl_add_u64 v[110:111], v[218:219], 0, v[106:107]
	v_cvt_pk_bf16_f32 v106, v96, v97
	v_cvt_pk_bf16_f32 v107, v98, v99
	v_cvt_pk_bf16_f32 v108, v92, v93
	v_cvt_pk_bf16_f32 v109, v94, v95
	global_store_dwordx4 v[110:111], v[106:109], off

; __device__ __forceinline__ void st8bf(bf16_t* p, f32x4 a, f32x4 b) { u32x4 w; w.x = pk2(a[0], a[1]); w.y = pk2(a[2], a[3]); w.z = pk2(b[0], b[1]); w.w = pk2(b[2], b[3]); st16(p, w); }
; __device__ __forceinline__ unsigned f2bf(float f) { unsigned u = __builtin_bit_cast(unsigned, f); return (u + 0x7fffu + ((u >> 16) & 1u)) >> 16; }
; __device__ __forceinline__ unsigned pk2(float lo, float hi) { return f2bf(lo) | (f2bf(hi) << 16); }
;     __device__ __forceinline__ void st(int pn, int row, int c, f32x4 v0, f32x4 v1) const {
;     ...
;         else if (pn < 8) st8bf(Q + (size_t)row * 512 + (pn - 6) * 256 + c, v0 * C2, v1 * C2);
.LBB0_451:
	s_and_b64 vcc, exec, s[12:13]
	s_cbranch_vccz .LBB0_453
	v_lshl_add_u64 v[104:105], s[28:29], 0, v[102:103]
	s_lshl_b32 s40, s43, 1
	v_lshl_add_u64 v[104:105], v[104:105], 0, s[40:41]
	v_lshlrev_b32_e32 v0, 1, v206
	v_lshl_add_u64 v[108:109], v[104:105], 0, v[0:1]
	v_pk_mul_f32 v[104:105], v[96:97], s[50:51] op_sel_hi:[1,0]
	v_pk_mul_f32 v[106:107], v[98:99], s[50:51] op_sel_hi:[1,0]
	v_cvt_pk_bf16_f32 v104, v104, v105
	v_pk_mul_f32 v[112:113], v[92:93], s[50:51] op_sel_hi:[1,0]
	v_cvt_pk_bf16_f32 v105, v106, v107
	v_pk_mul_f32 v[110:111], v[94:95], s[50:51] op_sel_hi:[1,0]
	v_cvt_pk_bf16_f32 v106, v112, v113
	v_cvt_pk_bf16_f32 v107, v110, v111
	global_store_dwordx4 v[108:109], v[104:107], off offset:-2816

; __device__ __forceinline__ void st8bf(bf16_t* p, f32x4 a, f32x4 b) { u32x4 w; w.x = pk2(a[0], a[1]); w.y = pk2(a[2], a[3]); w.z = pk2(b[0], b[1]); w.w = pk2(b[2], b[3]); st16(p, w); }
; __device__ __forceinline__ f32x4 sig4(f32x4 v) { f32x4 r; r[0] = sigmoidf_(v[0]); r[1] = sigmoidf_(v[1]); r[2] = sigmoidf_(v[2]); r[3] = sigmoidf_(v[3]); return r; }
; __device__ __forceinline__ float sigmoidf_(float x) { return __builtin_amdgcn_rcpf(1.0f + __expf(-x)); }
; __device__ __forceinline__ float siluf_(float x) { return x * sigmoidf_(x); }
;     __device__ __forceinline__ void st(int pn, int row, int c, f32x4 v0, f32x4 v1) const {
;         const bool smp = row >= MP; const int b = smp ? (row - MP) >> 2 : row >> 13, t = smp ? (row - MP) & 3 : row & (SEQ - 1);
;         if (pn < 6 || pn == 11 || pn == 12) st8bf((pn < 6 ? AG : BG) + (size_t)row * 512 + (pn < 6 ? pn - 4 : pn - 11) * 256 + c, v0 * sig4(v0), v1 * sig4(v1));
.LBB0_455:
	s_and_b64 s[76:77], s[66:67], exec
	s_cselect_b32 s77, s51, s79
	s_cselect_b32 s76, s33, s78
	v_lshl_add_u64 v[114:115], s[76:77], 0, v[102:103]
	v_mul_f32_e32 v116, 0xbfb8aa3b, v88
	v_lshl_add_u64 v[114:115], s[64:65], 1, v[114:115]
	v_exp_f32_e32 v120, v116
	v_lshlrev_b32_e32 v116, 1, v206
	v_mov_b32_e32 v117, v1
	v_lshl_add_u64 v[118:119], v[114:115], 0, v[116:117]
	v_mul_f32_e32 v115, 0xbfb8aa3b, v89
	v_exp_f32_e32 v115, v115
	v_mul_f32_e32 v116, 0xbfb8aa3b, v90
	v_mul_f32_e32 v117, 0xbfb8aa3b, v91
	v_exp_f32_e32 v116, v116
	v_exp_f32_e32 v117, v117
	v_add_f32_e32 v114, 1.0, v120
	v_add_f32_e32 v115, 1.0, v115
	v_rcp_f32_e32 v114, v114
	v_rcp_f32_e32 v115, v115
	v_mul_f32_e32 v120, 0xbfb8aa3b, v84
	v_mul_f32_e32 v121, 0xbfb8aa3b, v85
	v_exp_f32_e32 v120, v120
	v_exp_f32_e32 v121, v121
	v_add_f32_e32 v116, 1.0, v116
	v_add_f32_e32 v117, 1.0, v117
	v_rcp_f32_e32 v116, v116
	v_rcp_f32_e32 v117, v117
	v_mul_f32_e32 v122, 0xbfb8aa3b, v86
	v_mul_f32_e32 v123, 0xbfb8aa3b, v87
	v_exp_f32_e32 v122, v122
	v_exp_f32_e32 v123, v123
	v_pk_mul_f32 v[114:115], v[88:89], v[114:115]
	v_add_f32_e32 v120, 1.0, v120
	v_add_f32_e32 v121, 1.0, v121
	v_bfe_u32 v124, v114, 16, 1
	v_rcp_f32_e32 v120, v120
	v_rcp_f32_e32 v121, v121
	v_add3_u32 v114, v114, v124, s81
	v_bfe_u32 v124, v115, 16, 1
	v_pk_mul_f32 v[116:117], v[90:91], v[116:117]
	v_lshrrev_b32_e32 v114, 16, v114
	v_add3_u32 v115, v115, v124, s81
	v_add_f32_e32 v122, 1.0, v122
	v_add_f32_e32 v123, 1.0, v123
	v_and_or_b32 v114, v115, s25, v114
	v_rcp_f32_e32 v122, v122
	v_rcp_f32_e32 v123, v123
	v_pk_mul_f32 v[120:121], v[84:85], v[120:121]
	v_cvt_pk_bf16_f32 v115, v116, v117
	v_pk_mul_f32 v[122:123], v[86:87], v[122:123]
	v_cvt_pk_bf16_f32 v116, v120, v121
	v_bfe_u32 v117, v122, 16, 1
	v_add3_u32 v117, v122, v117, s81
	v_bfe_u32 v120, v123, 16, 1
	v_lshrrev_b32_e32 v117, 16, v117
	v_add3_u32 v120, v123, v120, s81
	v_and_or_b32 v117, v120, s25, v117
	global_store_dwordx4 v[118:119], v[114:117], off
	s_and_b64 vcc, exec, s[12:13]
	s_mov_b64 s[12:13], -1
	s_cbranch_vccz .LBB0_433

; __device__ __forceinline__ void st8bf(bf16_t* p, f32x4 a, f32x4 b) { u32x4 w; w.x = pk2(a[0], a[1]); w.y = pk2(a[2], a[3]); w.z = pk2(b[0], b[1]); w.w = pk2(b[2], b[3]); st16(p, w); }
; __device__ __forceinline__ f32x4 sig4(f32x4 v) { f32x4 r; r[0] = sigmoidf_(v[0]); r[1] = sigmoidf_(v[1]); r[2] = sigmoidf_(v[2]); r[3] = sigmoidf_(v[3]); return r; }
; __device__ __forceinline__ float sigmoidf_(float x) { return __builtin_amdgcn_rcpf(1.0f + __expf(-x)); }
; __device__ __forceinline__ float siluf_(float x) { return x * sigmoidf_(x); }
;     __device__ __forceinline__ void st(int pn, int row, int c, f32x4 v0, f32x4 v1) const {
;         const bool smp = row >= MP; const int b = smp ? (row - MP) >> 2 : row >> 13, t = smp ? (row - MP) & 3 : row & (SEQ - 1);
;         if (pn < 6 || pn == 11 || pn == 12) st8bf((pn < 6 ? AG : BG) + (size_t)row * 512 + (pn < 6 ? pn - 4 : pn - 11) * 256 + c, v0 * sig4(v0), v1 * sig4(v1));
.LBB0_457:
	v_mul_f32_e32 v0, 0xbfb8aa3b, v96
	s_and_b64 s[8:9], s[66:67], exec
	v_exp_f32_e32 v101, v0
	s_cselect_b32 s9, s51, s79
	s_cselect_b32 s8, s33, s78
	v_lshl_add_u64 v[102:103], s[8:9], 0, v[102:103]
	v_lshl_add_u64 v[102:103], s[64:65], 1, v[102:103]
	v_lshlrev_b32_e32 v0, 1, v206
	v_lshl_add_u64 v[106:107], v[102:103], 0, v[0:1]
	v_add_f32_e32 v0, 1.0, v101
	v_mul_f32_e32 v101, 0xbfb8aa3b, v97
	v_exp_f32_e32 v101, v101
	v_mul_f32_e32 v102, 0xbfb8aa3b, v98
	v_exp_f32_e32 v104, v102
	v_rcp_f32_e32 v102, v0
	v_add_f32_e32 v0, 1.0, v101
	v_mul_f32_e32 v101, 0xbfb8aa3b, v99
	v_rcp_f32_e32 v103, v0
	v_add_f32_e32 v0, 1.0, v104
	v_exp_f32_e32 v101, v101
	v_mul_f32_e32 v104, 0xbfb8aa3b, v92
	v_exp_f32_e32 v108, v104
	v_rcp_f32_e32 v104, v0
	v_add_f32_e32 v0, 1.0, v101
	v_rcp_f32_e32 v105, v0
	v_add_f32_e32 v0, 1.0, v108
	v_rcp_f32_e32 v108, v0
	v_mul_f32_e32 v0, 0xbfb8aa3b, v93
	v_mul_f32_e32 v101, 0xbfb8aa3b, v94
	v_exp_f32_e32 v0, v0
	v_exp_f32_e32 v101, v101
	v_mul_f32_e32 v109, 0xbfb8aa3b, v95
	v_exp_f32_e32 v109, v109
	v_add_f32_e32 v0, 1.0, v0
	v_add_f32_e32 v101, 1.0, v101
	v_pk_mul_f32 v[102:103], v[96:97], v[102:103]
	v_rcp_f32_e32 v110, v101
	v_add_f32_e32 v101, 1.0, v109
	v_rcp_f32_e32 v109, v0
	v_rcp_f32_e32 v111, v101
	v_pk_mul_f32 v[104:105], v[98:99], v[104:105]
	v_cvt_pk_bf16_f32 v102, v102, v103
	v_pk_mul_f32 v[108:109], v[92:93], v[108:109]
	v_cvt_pk_bf16_f32 v103, v104, v105
	v_pk_mul_f32 v[110:111], v[94:95], v[110:111]
	v_cvt_pk_bf16_f32 v104, v108, v109
	v_cvt_pk_bf16_f32 v105, v110, v111
	global_store_dwordx4 v[106:107], v[102:105], off offset:256

; __device__ __forceinline__ void st16f(float* p, f32x4 v) { st16(p, __builtin_bit_cast(u32x4, v)); }
; __device__ __forceinline__ void st8bf(bf16_t* p, f32x4 a, f32x4 b) { u32x4 w; w.x = pk2(a[0], a[1]); w.y = pk2(a[2], a[3]); w.z = pk2(b[0], b[1]); w.w = pk2(b[2], b[3]); st16(p, w); }
; __device__ __forceinline__ f32x4 sig4(f32x4 v) { f32x4 r; r[0] = sigmoidf_(v[0]); r[1] = sigmoidf_(v[1]); r[2] = sigmoidf_(v[2]); r[3] = sigmoidf_(v[3]); return r; }
;     __device__ __forceinline__ void st_glu(int pn, int row, int c, f32x4 a0, f32x4 a1, f32x4 g0, f32x4 g1) const {
;         const bool smp = row >= MP; const int b = smp ? (row - MP) >> 2 : row >> 13, t = smp ? (row - MP) & 3 : row & (SEQ - 1);
;         const f32x4 v0 = a0 * sig4(g0), v1 = a1 * sig4(g1);
;         const int col = pn * 128 + c;
;         st8bf(U + (size_t)row * 512 + col, v0, v1);
;         float* o = nullptr;
;         if (!smp) { if (t >= SEQ - 30) o = out + O_CONV + ((size_t)b * 30 + (t - (SEQ - 30))) * 512 + col; }
;         else o = out + O_CONVS + ((size_t)b * 30 + 26 + t) * 512 + col;
;         if (o) { st16f(o, v0); st16f(o + 4, v1); }
.LBB0_459:
	s_mul_i32 s74, s74, 30
	s_ashr_i32 s75, s74, 31
	s_and_b64 vcc, exec, s[10:11]
	s_cbranch_vccz .LBB0_465
	v_mul_f32_e32 v0, 0xbfb8aa3b, v96
	v_exp_f32_e32 v0, v0
	v_mul_f32_e32 v96, 0xbfb8aa3b, v97
	v_mul_f32_e32 v97, 0xbfb8aa3b, v98
	v_exp_f32_e32 v98, v96
	v_add_f32_e32 v0, 1.0, v0
	v_exp_f32_e32 v101, v97
	v_rcp_f32_e32 v96, v0
	v_add_f32_e32 v0, 1.0, v98
	v_mul_f32_e32 v98, 0xbfb8aa3b, v99
	v_exp_f32_e32 v99, v98
	v_mul_f32_e32 v92, 0xbfb8aa3b, v92
	v_exp_f32_e32 v92, v92
	v_rcp_f32_e32 v97, v0
	v_add_f32_e32 v0, 1.0, v101
	v_rcp_f32_e32 v98, v0
	v_add_f32_e32 v0, 1.0, v99
	v_rcp_f32_e32 v99, v0
	v_add_f32_e32 v0, 1.0, v92
	v_rcp_f32_e32 v92, v0
	v_mul_f32_e32 v0, 0xbfb8aa3b, v93
	v_mul_f32_e32 v93, 0xbfb8aa3b, v94
	v_exp_f32_e32 v93, v93
	v_mul_f32_e32 v94, 0xbfb8aa3b, v95
	v_exp_f32_e32 v0, v0
	v_exp_f32_e32 v95, v94
	v_add_f32_e32 v93, 1.0, v93
	v_rcp_f32_e32 v94, v93
	v_add_f32_e32 v0, 1.0, v0
	v_add_f32_e32 v93, 1.0, v95
	v_rcp_f32_e32 v95, v93
	v_rcp_f32_e32 v93, v0
	v_ashrrev_i32_e32 v101, 31, v100
	v_pk_mul_f32 v[88:89], v[88:89], v[96:97]
	v_pk_mul_f32 v[90:91], v[90:91], v[98:99]
	v_pk_mul_f32 v[84:85], v[84:85], v[92:93]
	v_lshlrev_b64 v[92:93], 10, v[100:101]
	v_lshl_add_u64 v[92:93], s[26:27], 0, v[92:93]
	v_lshl_add_u64 v[96:97], v[2:3], 1, v[92:93]
	v_cvt_pk_bf16_f32 v92, v88, v89
	v_cvt_pk_bf16_f32 v93, v90, v91
	v_pk_mul_f32 v[86:87], v[86:87], v[94:95]
	v_cvt_pk_bf16_f32 v94, v84, v85
	v_cvt_pk_bf16_f32 v95, v86, v87
	global_store_dwordx4 v[96:97], v[92:95], off
	s_and_saveexec_b64 s[8:9], s[6:7]
	s_xor_b64 s[6:7], exec, s[8:9]
	s_cbranch_execz .LBB0_514
	v_and_b32_e32 v0, 0x1fef, v100
	s_movk_i32 s8, 0x1fe1
	v_cmp_lt_u32_e32 vcc, s8, v0
	v_add_u32_e32 v0, 0xffffe01e, v0
	v_lshl_add_u64 v[92:93], v[0:1], 0, s[74:75]
	v_lshlrev_b64 v[92:93], 11, v[92:93]
	v_lshl_add_u64 v[92:93], s[30:31], 0, v[92:93]
	v_lshl_add_u64 v[92:93], v[2:3], 2, v[92:93]
	v_cndmask_b32_e32 v93, 0, v93, vcc
	v_cndmask_b32_e32 v92, 0, v92, vcc
	s_andn2_saveexec_b64 s[6:7], s[6:7]
	s_cbranch_execnz .LBB0_515

; __device__ __forceinline__ void st16f(float* p, f32x4 v) { st16(p, __builtin_bit_cast(u32x4, v)); }
; __device__ __forceinline__ void st8bf(bf16_t* p, f32x4 a, f32x4 b) { u32x4 w; w.x = pk2(a[0], a[1]); w.y = pk2(a[2], a[3]); w.z = pk2(b[0], b[1]); w.w = pk2(b[2], b[3]); st16(p, w); }
; __device__ __forceinline__ unsigned f2bf(float f) { unsigned u = __builtin_bit_cast(unsigned, f); return (u + 0x7fffu + ((u >> 16) & 1u)) >> 16; }
; __device__ __forceinline__ unsigned pk2(float lo, float hi) { return f2bf(lo) | (f2bf(hi) << 16); }
;     __device__ __forceinline__ void st(int pn, int row, int c, f32x4 v0, f32x4 v1) const {
;     ...
;         else if (pn == 10) { float* o = nullptr;
;             if (!smp) { if (t >= SEQ - 512) o = out + O_WIN + ((size_t)b * 512 + (t - (SEQ - 512))) * 256 + c; } else o = out + O_WINS + ((size_t)b * 512 + 508 + t) * 256 + c;
;             st8bf(KW + (size_t)row * 256 + c, v0, v1); if (o) { st16f(o, v0); st16f(o + 4, v1); } }
.LBB0_477:
	s_andn2_saveexec_b64 s[76:77], s[76:77]
	v_lshl_add_u64 v[98:99], v[214:215], 0, v[94:95]
	s_or_b64 exec, exec, s[76:77]
	v_cvt_pk_bf16_f32 v100, v72, v73
	v_cvt_pk_bf16_f32 v101, v74, v75
	v_cvt_pk_bf16_f32 v102, v68, v69
	v_bfe_u32 v103, v70, 16, 1
	v_add3_u32 v103, v70, v103, s81
	v_bfe_u32 v106, v71, 16, 1
	v_lshrrev_b32_e32 v103, 16, v103
	v_add3_u32 v106, v71, v106, s81
	v_lshl_add_u64 v[104:105], v[208:209], 0, v[92:93]
	v_and_or_b32 v103, v106, s25, v103
	v_cmp_ne_u64_e32 vcc, 0, v[98:99]
	global_store_dwordx4 v[104:105], v[100:103], off
	s_and_saveexec_b64 s[76:77], vcc
	s_cbranch_execz .LBB0_481
	global_store_dwordx4 v[98:99], v[72:75], off
	global_store_dwordx4 v[98:99], v[68:71], off offset:16

; __device__ __forceinline__ void st16f(float* p, f32x4 v) { st16(p, __builtin_bit_cast(u32x4, v)); }
; __device__ __forceinline__ void st8bf(bf16_t* p, f32x4 a, f32x4 b) { u32x4 w; w.x = pk2(a[0], a[1]); w.y = pk2(a[2], a[3]); w.z = pk2(b[0], b[1]); w.w = pk2(b[2], b[3]); st16(p, w); }
; __device__ __forceinline__ unsigned f2bf(float f) { unsigned u = __builtin_bit_cast(unsigned, f); return (u + 0x7fffu + ((u >> 16) & 1u)) >> 16; }
; __device__ __forceinline__ unsigned pk2(float lo, float hi) { return f2bf(lo) | (f2bf(hi) << 16); }
;     __device__ __forceinline__ void st(int pn, int row, int c, f32x4 v0, f32x4 v1) const {
;     ...
;         else if (pn == 8) { float* o = (smp ? out + O_KCS + (size_t)(row - MP) * 256 : out + O_KC + (size_t)row * 256) + c; st16f(o, v0); st16f(o + 4, v1); }
;         else if (pn == 9) { float* o = (smp ? out + O_KSS + (size_t)(row - MP) * 256 : out + O_KSEL + (size_t)row * 256) + c; st16f(o, v0); st16f(o + 4, v1); st8bf(KS + (size_t)row * 256 + c, v0, v1); }
.LBB0_483:
	s_andn2_b64 vcc, exec, s[76:77]
	s_cbranch_vccnz .LBB0_485
	v_lshl_add_u64 v[98:99], s[36:37], 0, v[86:87]
	v_lshl_add_u64 v[100:101], s[38:39], 0, v[90:91]
	v_cndmask_b32_e64 v99, v99, v101, s[8:9]
	v_cndmask_b32_e64 v98, v98, v100, s[8:9]
	v_lshlrev_b32_e32 v100, 2, v206
	v_mov_b32_e32 v101, v1
	v_cndmask_b32_e64 v103, v85, 0, s[8:9]
	v_cndmask_b32_e64 v102, v84, v84, s[8:9]
	v_lshl_add_u64 v[98:99], v[98:99], 0, v[100:101]
	global_store_dwordx4 v[98:99], v[72:75], off
	global_store_dwordx4 v[98:99], v[68:71], off offset:16
	v_lshlrev_b64 v[98:99], 9, v[102:103]
	v_lshl_add_u64 v[102:103], v[210:211], 0, v[98:99]
	v_cvt_pk_bf16_f32 v98, v72, v73
	v_cvt_pk_bf16_f32 v99, v74, v75
	v_cvt_pk_bf16_f32 v100, v68, v69
	v_bfe_u32 v101, v70, 16, 1
	v_add3_u32 v101, v70, v101, s81
	v_bfe_u32 v104, v71, 16, 1
	v_lshrrev_b32_e32 v101, 16, v101
	v_add3_u32 v104, v71, v104, s81
	v_and_or_b32 v101, v104, s25, v101
	global_store_dwordx4 v[102:103], v[98:101], off

; __device__ __forceinline__ void st8bf(bf16_t* p, f32x4 a, f32x4 b) { u32x4 w; w.x = pk2(a[0], a[1]); w.y = pk2(a[2], a[3]); w.z = pk2(b[0], b[1]); w.w = pk2(b[2], b[3]); st16(p, w); }
; __device__ __forceinline__ unsigned f2bf(float f) { unsigned u = __builtin_bit_cast(unsigned, f); return (u + 0x7fffu + ((u >> 16) & 1u)) >> 16; }
; __device__ __forceinline__ unsigned pk2(float lo, float hi) { return f2bf(lo) | (f2bf(hi) << 16); }
;     __device__ __forceinline__ void st(int pn, int row, int c, f32x4 v0, f32x4 v1) const {
;     ...
;         else if (pn < 8) st8bf(Q + (size_t)row * 512 + (pn - 6) * 256 + c, v0 * C2, v1 * C2);
.LBB0_489:
	s_and_b64 vcc, exec, s[76:77]
	s_cbranch_vccz .LBB0_491
	v_lshl_add_u64 v[98:99], s[28:29], 0, v[86:87]
	s_lshl_b32 s40, s43, 1
	v_lshl_add_u64 v[98:99], v[98:99], 0, s[40:41]
	v_lshlrev_b32_e32 v100, 1, v206
	v_mov_b32_e32 v101, v1
	v_lshl_add_u64 v[102:103], v[98:99], 0, v[100:101]
	v_pk_mul_f32 v[98:99], v[72:73], s[50:51] op_sel_hi:[1,0]
	v_pk_mul_f32 v[100:101], v[74:75], s[50:51] op_sel_hi:[1,0]
	v_cvt_pk_bf16_f32 v98, v98, v99
	v_pk_mul_f32 v[106:107], v[68:69], s[50:51] op_sel_hi:[1,0]
	v_cvt_pk_bf16_f32 v99, v100, v101
	v_pk_mul_f32 v[104:105], v[70:71], s[50:51] op_sel_hi:[1,0]
	v_cvt_pk_bf16_f32 v100, v106, v107
	v_cvt_pk_bf16_f32 v101, v104, v105
	global_store_dwordx4 v[102:103], v[98:101], off offset:-3072

; __device__ __forceinline__ void st16f(float* p, f32x4 v) { st16(p, __builtin_bit_cast(u32x4, v)); }
; __device__ __forceinline__ void st8bf(bf16_t* p, f32x4 a, f32x4 b) { u32x4 w; w.x = pk2(a[0], a[1]); w.y = pk2(a[2], a[3]); w.z = pk2(b[0], b[1]); w.w = pk2(b[2], b[3]); st16(p, w); }
; __device__ __forceinline__ unsigned f2bf(float f) { unsigned u = __builtin_bit_cast(unsigned, f); return (u + 0x7fffu + ((u >> 16) & 1u)) >> 16; }
; __device__ __forceinline__ unsigned pk2(float lo, float hi) { return f2bf(lo) | (f2bf(hi) << 16); }
;     __device__ __forceinline__ void st(int pn, int row, int c, f32x4 v0, f32x4 v1) const {
;     ...
;         else if (pn == 10) { float* o = nullptr;
;             if (!smp) { if (t >= SEQ - 512) o = out + O_WIN + ((size_t)b * 512 + (t - (SEQ - 512))) * 256 + c; } else o = out + O_WINS + ((size_t)b * 512 + 508 + t) * 256 + c;
;             st8bf(KW + (size_t)row * 256 + c, v0, v1); if (o) { st16f(o, v0); st16f(o + 4, v1); } }
.LBB0_499:
	s_andn2_saveexec_b64 s[10:11], s[12:13]
	v_lshl_add_u64 v[94:95], v[214:215], 0, v[94:95]
	s_mov_b64 s[12:13], 0x200
	v_lshl_add_u64 v[98:99], v[94:95], 0, s[12:13]
	s_or_b64 exec, exec, s[10:11]
	v_lshl_add_u64 v[96:97], v[216:217], 0, v[92:93]
	v_cvt_pk_bf16_f32 v92, v80, v81
	v_cvt_pk_bf16_f32 v93, v82, v83
	v_cvt_pk_bf16_f32 v94, v76, v77
	v_cvt_pk_bf16_f32 v95, v78, v79
	v_cmp_ne_u64_e32 vcc, 0, v[98:99]
	global_store_dwordx4 v[96:97], v[92:95], off
	s_and_saveexec_b64 s[10:11], vcc
	s_cbranch_execz .LBB0_503
	global_store_dwordx4 v[98:99], v[80:83], off
	global_store_dwordx4 v[98:99], v[76:79], off offset:16

; __device__ __forceinline__ void st16f(float* p, f32x4 v) { st16(p, __builtin_bit_cast(u32x4, v)); }
; __device__ __forceinline__ void st8bf(bf16_t* p, f32x4 a, f32x4 b) { u32x4 w; w.x = pk2(a[0], a[1]); w.y = pk2(a[2], a[3]); w.z = pk2(b[0], b[1]); w.w = pk2(b[2], b[3]); st16(p, w); }
; __device__ __forceinline__ unsigned f2bf(float f) { unsigned u = __builtin_bit_cast(unsigned, f); return (u + 0x7fffu + ((u >> 16) & 1u)) >> 16; }
; __device__ __forceinline__ unsigned pk2(float lo, float hi) { return f2bf(lo) | (f2bf(hi) << 16); }
;     __device__ __forceinline__ void st(int pn, int row, int c, f32x4 v0, f32x4 v1) const {
;     ...
;         else if (pn == 8) { float* o = (smp ? out + O_KCS + (size_t)(row - MP) * 256 : out + O_KC + (size_t)row * 256) + c; st16f(o, v0); st16f(o + 4, v1); }
;         else if (pn == 9) { float* o = (smp ? out + O_KSS + (size_t)(row - MP) * 256 : out + O_KSEL + (size_t)row * 256) + c; st16f(o, v0); st16f(o + 4, v1); st8bf(KS + (size_t)row * 256 + c, v0, v1); }
.LBB0_505:
	s_andn2_b64 vcc, exec, s[12:13]
	s_cbranch_vccnz .LBB0_507
	v_lshl_add_u64 v[92:93], s[36:37], 0, v[86:87]
	v_lshl_add_u64 v[90:91], s[38:39], 0, v[90:91]
	v_cndmask_b32_e64 v91, v93, v91, s[8:9]
	v_cndmask_b32_e64 v90, v92, v90, s[8:9]
	v_lshlrev_b32_e32 v92, 2, v206
	v_mov_b32_e32 v93, v1
	v_cndmask_b32_e64 v95, v85, 0, s[8:9]
	v_cndmask_b32_e64 v94, v84, v84, s[8:9]
	v_lshl_add_u64 v[90:91], v[90:91], 0, v[92:93]
	global_store_dwordx4 v[90:91], v[80:83], off offset:512
	global_store_dwordx4 v[90:91], v[76:79], off offset:528
	v_lshlrev_b64 v[90:91], 9, v[94:95]
	v_lshl_add_u64 v[94:95], v[218:219], 0, v[90:91]
	v_cvt_pk_bf16_f32 v90, v80, v81
	v_cvt_pk_bf16_f32 v91, v82, v83
	v_cvt_pk_bf16_f32 v92, v76, v77
	v_cvt_pk_bf16_f32 v93, v78, v79
	global_store_dwordx4 v[94:95], v[90:93], off

; __device__ __forceinline__ void st8bf(bf16_t* p, f32x4 a, f32x4 b) { u32x4 w; w.x = pk2(a[0], a[1]); w.y = pk2(a[2], a[3]); w.z = pk2(b[0], b[1]); w.w = pk2(b[2], b[3]); st16(p, w); }
; __device__ __forceinline__ unsigned f2bf(float f) { unsigned u = __builtin_bit_cast(unsigned, f); return (u + 0x7fffu + ((u >> 16) & 1u)) >> 16; }
; __device__ __forceinline__ unsigned pk2(float lo, float hi) { return f2bf(lo) | (f2bf(hi) << 16); }
;     __device__ __forceinline__ void st(int pn, int row, int c, f32x4 v0, f32x4 v1) const {
;     ...
;         else if (pn < 8) st8bf(Q + (size_t)row * 512 + (pn - 6) * 256 + c, v0 * C2, v1 * C2);
.LBB0_511:
	s_and_b64 vcc, exec, s[12:13]
	s_cbranch_vccz .LBB0_513
	v_lshl_add_u64 v[88:89], s[28:29], 0, v[86:87]
	s_lshl_b32 s40, s43, 1
	v_lshl_add_u64 v[88:89], v[88:89], 0, s[40:41]
	v_lshlrev_b32_e32 v0, 1, v206
	v_lshl_add_u64 v[92:93], v[88:89], 0, v[0:1]
	v_pk_mul_f32 v[88:89], v[80:81], s[50:51] op_sel_hi:[1,0]
	v_pk_mul_f32 v[90:91], v[82:83], s[50:51] op_sel_hi:[1,0]
	v_cvt_pk_bf16_f32 v88, v88, v89
	v_pk_mul_f32 v[96:97], v[76:77], s[50:51] op_sel_hi:[1,0]
	v_cvt_pk_bf16_f32 v89, v90, v91
	v_pk_mul_f32 v[94:95], v[78:79], s[50:51] op_sel_hi:[1,0]
	v_cvt_pk_bf16_f32 v90, v96, v97
	v_cvt_pk_bf16_f32 v91, v94, v95
	global_store_dwordx4 v[92:93], v[88:91], off offset:-2816

; __device__ __forceinline__ void st8bf(bf16_t* p, f32x4 a, f32x4 b) { u32x4 w; w.x = pk2(a[0], a[1]); w.y = pk2(a[2], a[3]); w.z = pk2(b[0], b[1]); w.w = pk2(b[2], b[3]); st16(p, w); }
; __device__ __forceinline__ f32x4 sig4(f32x4 v) { f32x4 r; r[0] = sigmoidf_(v[0]); r[1] = sigmoidf_(v[1]); r[2] = sigmoidf_(v[2]); r[3] = sigmoidf_(v[3]); return r; }
; __device__ __forceinline__ float sigmoidf_(float x) { return __builtin_amdgcn_rcpf(1.0f + __expf(-x)); }
; __device__ __forceinline__ float siluf_(float x) { return x * sigmoidf_(x); }
;     __device__ __forceinline__ void st(int pn, int row, int c, f32x4 v0, f32x4 v1) const {
;         const bool smp = row >= MP; const int b = smp ? (row - MP) >> 2 : row >> 13, t = smp ? (row - MP) & 3 : row & (SEQ - 1);
;         if (pn < 6 || pn == 11 || pn == 12) st8bf((pn < 6 ? AG : BG) + (size_t)row * 512 + (pn < 6 ? pn - 4 : pn - 11) * 256 + c, v0 * sig4(v0), v1 * sig4(v1));
.LBB0_517:
	s_and_b64 s[76:77], s[66:67], exec
	s_cselect_b32 s77, s51, s79
	s_cselect_b32 s76, s33, s78
	v_lshl_add_u64 v[98:99], s[76:77], 0, v[86:87]
	v_mul_f32_e32 v100, 0xbfb8aa3b, v72
	v_lshl_add_u64 v[98:99], s[64:65], 1, v[98:99]
	v_exp_f32_e32 v104, v100
	v_lshlrev_b32_e32 v100, 1, v206
	v_mov_b32_e32 v101, v1
	v_lshl_add_u64 v[102:103], v[98:99], 0, v[100:101]
	v_mul_f32_e32 v99, 0xbfb8aa3b, v73
	v_exp_f32_e32 v99, v99
	v_mul_f32_e32 v100, 0xbfb8aa3b, v74
	v_mul_f32_e32 v101, 0xbfb8aa3b, v75
	v_exp_f32_e32 v100, v100
	v_exp_f32_e32 v101, v101
	v_add_f32_e32 v98, 1.0, v104
	v_add_f32_e32 v99, 1.0, v99
	v_rcp_f32_e32 v98, v98
	v_rcp_f32_e32 v99, v99
	v_mul_f32_e32 v104, 0xbfb8aa3b, v68
	v_mul_f32_e32 v105, 0xbfb8aa3b, v69
	v_exp_f32_e32 v104, v104
	v_exp_f32_e32 v105, v105
	v_add_f32_e32 v100, 1.0, v100
	v_add_f32_e32 v101, 1.0, v101
	v_rcp_f32_e32 v100, v100
	v_rcp_f32_e32 v101, v101
	v_mul_f32_e32 v106, 0xbfb8aa3b, v70
	v_mul_f32_e32 v107, 0xbfb8aa3b, v71
	v_exp_f32_e32 v106, v106
	v_exp_f32_e32 v107, v107
	v_pk_mul_f32 v[98:99], v[72:73], v[98:99]
	v_add_f32_e32 v104, 1.0, v104
	v_add_f32_e32 v105, 1.0, v105
	v_bfe_u32 v108, v98, 16, 1
	v_rcp_f32_e32 v104, v104
	v_rcp_f32_e32 v105, v105
	v_add3_u32 v98, v98, v108, s81
	v_bfe_u32 v108, v99, 16, 1
	v_pk_mul_f32 v[100:101], v[74:75], v[100:101]
	v_lshrrev_b32_e32 v98, 16, v98
	v_add3_u32 v99, v99, v108, s81
	v_add_f32_e32 v106, 1.0, v106
	v_add_f32_e32 v107, 1.0, v107
	v_and_or_b32 v98, v99, s25, v98
	v_rcp_f32_e32 v106, v106
	v_rcp_f32_e32 v107, v107
	v_pk_mul_f32 v[104:105], v[68:69], v[104:105]
	v_cvt_pk_bf16_f32 v99, v100, v101
	v_pk_mul_f32 v[106:107], v[70:71], v[106:107]
	v_cvt_pk_bf16_f32 v100, v104, v105
	v_bfe_u32 v101, v106, 16, 1
	v_add3_u32 v101, v106, v101, s81
	v_bfe_u32 v104, v107, 16, 1
	v_lshrrev_b32_e32 v101, 16, v101
	v_add3_u32 v104, v107, v104, s81
	v_and_or_b32 v101, v104, s25, v101
	global_store_dwordx4 v[102:103], v[98:101], off
	s_and_b64 vcc, exec, s[12:13]
	s_mov_b64 s[12:13], -1
	s_cbranch_vccz .LBB0_493

; __device__ __forceinline__ void st8bf(bf16_t* p, f32x4 a, f32x4 b) { u32x4 w; w.x = pk2(a[0], a[1]); w.y = pk2(a[2], a[3]); w.z = pk2(b[0], b[1]); w.w = pk2(b[2], b[3]); st16(p, w); }
; __device__ __forceinline__ f32x4 sig4(f32x4 v) { f32x4 r; r[0] = sigmoidf_(v[0]); r[1] = sigmoidf_(v[1]); r[2] = sigmoidf_(v[2]); r[3] = sigmoidf_(v[3]); return r; }
; __device__ __forceinline__ float sigmoidf_(float x) { return __builtin_amdgcn_rcpf(1.0f + __expf(-x)); }
; __device__ __forceinline__ float siluf_(float x) { return x * sigmoidf_(x); }
;     __device__ __forceinline__ void st(int pn, int row, int c, f32x4 v0, f32x4 v1) const {
;         const bool smp = row >= MP; const int b = smp ? (row - MP) >> 2 : row >> 13, t = smp ? (row - MP) & 3 : row & (SEQ - 1);
;         if (pn < 6 || pn == 11 || pn == 12) st8bf((pn < 6 ? AG : BG) + (size_t)row * 512 + (pn < 6 ? pn - 4 : pn - 11) * 256 + c, v0 * sig4(v0), v1 * sig4(v1));
.LBB0_519:
	v_mul_f32_e32 v0, 0xbfb8aa3b, v80
	s_and_b64 s[8:9], s[66:67], exec
	v_exp_f32_e32 v85, v0
	s_cselect_b32 s9, s51, s79
	s_cselect_b32 s8, s33, s78
	v_lshl_add_u64 v[86:87], s[8:9], 0, v[86:87]
	v_lshl_add_u64 v[86:87], s[64:65], 1, v[86:87]
	v_lshlrev_b32_e32 v0, 1, v206
	v_lshl_add_u64 v[90:91], v[86:87], 0, v[0:1]
	v_add_f32_e32 v0, 1.0, v85
	v_mul_f32_e32 v85, 0xbfb8aa3b, v81
	v_exp_f32_e32 v85, v85
	v_mul_f32_e32 v86, 0xbfb8aa3b, v82
	v_exp_f32_e32 v88, v86
	v_rcp_f32_e32 v86, v0
	v_add_f32_e32 v0, 1.0, v85
	v_mul_f32_e32 v85, 0xbfb8aa3b, v83
	v_rcp_f32_e32 v87, v0
	v_add_f32_e32 v0, 1.0, v88
	v_exp_f32_e32 v85, v85
	v_mul_f32_e32 v88, 0xbfb8aa3b, v76
	v_exp_f32_e32 v92, v88
	v_rcp_f32_e32 v88, v0
	v_add_f32_e32 v0, 1.0, v85
	v_rcp_f32_e32 v89, v0
	v_add_f32_e32 v0, 1.0, v92
	v_rcp_f32_e32 v92, v0
	v_mul_f32_e32 v0, 0xbfb8aa3b, v77
	v_mul_f32_e32 v85, 0xbfb8aa3b, v78
	v_exp_f32_e32 v0, v0
	v_exp_f32_e32 v85, v85
	v_mul_f32_e32 v93, 0xbfb8aa3b, v79
	v_exp_f32_e32 v93, v93
	v_add_f32_e32 v0, 1.0, v0
	v_add_f32_e32 v85, 1.0, v85
	v_pk_mul_f32 v[86:87], v[80:81], v[86:87]
	v_rcp_f32_e32 v94, v85
	v_add_f32_e32 v85, 1.0, v93
	v_rcp_f32_e32 v93, v0
	v_rcp_f32_e32 v95, v85
	v_pk_mul_f32 v[88:89], v[82:83], v[88:89]
	v_cvt_pk_bf16_f32 v86, v86, v87
	v_pk_mul_f32 v[92:93], v[76:77], v[92:93]
	v_cvt_pk_bf16_f32 v87, v88, v89
	v_pk_mul_f32 v[94:95], v[78:79], v[94:95]
	v_cvt_pk_bf16_f32 v88, v92, v93
	v_cvt_pk_bf16_f32 v89, v94, v95
	global_store_dwordx4 v[90:91], v[86:89], off offset:256

; __device__ __forceinline__ void st16f(float* p, f32x4 v) { st16(p, __builtin_bit_cast(u32x4, v)); }
; __device__ __forceinline__ void st8bf(bf16_t* p, f32x4 a, f32x4 b) { u32x4 w; w.x = pk2(a[0], a[1]); w.y = pk2(a[2], a[3]); w.z = pk2(b[0], b[1]); w.w = pk2(b[2], b[3]); st16(p, w); }
; __device__ __forceinline__ f32x4 sig4(f32x4 v) { f32x4 r; r[0] = sigmoidf_(v[0]); r[1] = sigmoidf_(v[1]); r[2] = sigmoidf_(v[2]); r[3] = sigmoidf_(v[3]); return r; }
;     __device__ __forceinline__ void st_glu(int pn, int row, int c, f32x4 a0, f32x4 a1, f32x4 g0, f32x4 g1) const {
;         const bool smp = row >= MP; const int b = smp ? (row - MP) >> 2 : row >> 13, t = smp ? (row - MP) & 3 : row & (SEQ - 1);
;         const f32x4 v0 = a0 * sig4(g0), v1 = a1 * sig4(g1);
;         const int col = pn * 128 + c;
;         st8bf(U + (size_t)row * 512 + col, v0, v1);
;         float* o = nullptr;
;         if (!smp) { if (t >= SEQ - 30) o = out + O_CONV + ((size_t)b * 30 + (t - (SEQ - 30))) * 512 + col; }
;         else o = out + O_CONVS + ((size_t)b * 30 + 26 + t) * 512 + col;
;         if (o) { st16f(o, v0); st16f(o + 4, v1); }
.LBB0_521:
	s_and_b64 vcc, exec, s[10:11]
	s_cbranch_vccz .LBB0_527
	v_mul_f32_e32 v0, 0xbfb8aa3b, v80
	v_exp_f32_e32 v0, v0
	v_mul_f32_e32 v80, 0xbfb8aa3b, v81
	v_mul_f32_e32 v81, 0xbfb8aa3b, v82
	v_exp_f32_e32 v82, v80
	v_add_f32_e32 v0, 1.0, v0
	v_exp_f32_e32 v85, v81
	v_rcp_f32_e32 v80, v0
	v_add_f32_e32 v0, 1.0, v82
	v_mul_f32_e32 v82, 0xbfb8aa3b, v83
	v_exp_f32_e32 v83, v82
	v_mul_f32_e32 v76, 0xbfb8aa3b, v76
	v_exp_f32_e32 v76, v76
	v_rcp_f32_e32 v81, v0
	v_add_f32_e32 v0, 1.0, v85
	v_rcp_f32_e32 v82, v0
	v_add_f32_e32 v0, 1.0, v83
	v_rcp_f32_e32 v83, v0
	v_add_f32_e32 v0, 1.0, v76
	v_rcp_f32_e32 v76, v0
	v_mul_f32_e32 v0, 0xbfb8aa3b, v77
	v_mul_f32_e32 v77, 0xbfb8aa3b, v78
	v_exp_f32_e32 v77, v77
	v_mul_f32_e32 v78, 0xbfb8aa3b, v79
	v_exp_f32_e32 v0, v0
	v_exp_f32_e32 v79, v78
	v_add_f32_e32 v77, 1.0, v77
	v_rcp_f32_e32 v78, v77
	v_add_f32_e32 v0, 1.0, v0
	v_add_f32_e32 v77, 1.0, v79
	v_rcp_f32_e32 v79, v77
	v_rcp_f32_e32 v77, v0
	v_ashrrev_i32_e32 v85, 31, v84
	v_pk_mul_f32 v[72:73], v[72:73], v[80:81]
	v_pk_mul_f32 v[74:75], v[74:75], v[82:83]
	v_pk_mul_f32 v[68:69], v[68:69], v[76:77]
	v_lshlrev_b64 v[76:77], 10, v[84:85]
	v_lshl_add_u64 v[76:77], s[26:27], 0, v[76:77]
	v_lshl_add_u64 v[80:81], v[2:3], 1, v[76:77]
	v_cvt_pk_bf16_f32 v76, v72, v73
	v_cvt_pk_bf16_f32 v77, v74, v75
	v_pk_mul_f32 v[70:71], v[70:71], v[78:79]
	v_cvt_pk_bf16_f32 v78, v68, v69
	v_cvt_pk_bf16_f32 v79, v70, v71
	global_store_dwordx4 v[80:81], v[76:79], off
	s_and_saveexec_b64 s[8:9], s[6:7]
	s_xor_b64 s[6:7], exec, s[8:9]
	s_cbranch_execz .LBB0_576
	v_and_b32_e32 v78, 0x1fff, v84
	v_add_u32_e32 v0, 0xffffe01e, v78
	v_lshl_add_u64 v[76:77], v[0:1], 0, s[74:75]
	v_lshlrev_b64 v[76:77], 11, v[76:77]
	v_lshl_add_u64 v[76:77], s[30:31], 0, v[76:77]
	s_movk_i32 s8, 0x1fe1
	v_lshl_add_u64 v[76:77], v[2:3], 2, v[76:77]
	v_cmp_lt_u32_e32 vcc, s8, v78
	s_nop 1
	v_cndmask_b32_e32 v77, 0, v77, vcc
	v_cndmask_b32_e32 v76, 0, v76, vcc
	s_andn2_saveexec_b64 s[6:7], s[6:7]
	s_cbranch_execnz .LBB0_577

; __device__ __forceinline__ void st16f(float* p, f32x4 v) { st16(p, __builtin_bit_cast(u32x4, v)); }
; __device__ __forceinline__ void st8bf(bf16_t* p, f32x4 a, f32x4 b) { u32x4 w; w.x = pk2(a[0], a[1]); w.y = pk2(a[2], a[3]); w.z = pk2(b[0], b[1]); w.w = pk2(b[2], b[3]); st16(p, w); }
; __device__ __forceinline__ unsigned f2bf(float f) { unsigned u = __builtin_bit_cast(unsigned, f); return (u + 0x7fffu + ((u >> 16) & 1u)) >> 16; }
; __device__ __forceinline__ unsigned pk2(float lo, float hi) { return f2bf(lo) | (f2bf(hi) << 16); }
;     __device__ __forceinline__ void st(int pn, int row, int c, f32x4 v0, f32x4 v1) const {
;     ...
;         else if (pn == 10) { float* o = nullptr;
;             if (!smp) { if (t >= SEQ - 512) o = out + O_WIN + ((size_t)b * 512 + (t - (SEQ - 512))) * 256 + c; } else o = out + O_WINS + ((size_t)b * 512 + 508 + t) * 256 + c;
;             st8bf(KW + (size_t)row * 256 + c, v0, v1); if (o) { st16f(o, v0); st16f(o + 4, v1); } }
.LBB0_539:
	s_andn2_saveexec_b64 s[76:77], s[76:77]
	v_lshl_add_u64 v[82:83], v[214:215], 0, v[78:79]
	s_or_b64 exec, exec, s[76:77]
	v_cvt_pk_bf16_f32 v84, v56, v57
	v_cvt_pk_bf16_f32 v85, v58, v59
	v_cvt_pk_bf16_f32 v86, v52, v53
	v_bfe_u32 v87, v54, 16, 1
	v_add3_u32 v87, v54, v87, s81
	v_bfe_u32 v90, v55, 16, 1
	v_lshrrev_b32_e32 v87, 16, v87
	v_add3_u32 v90, v55, v90, s81
	v_lshl_add_u64 v[88:89], v[208:209], 0, v[76:77]
	v_and_or_b32 v87, v90, s25, v87
	v_cmp_ne_u64_e32 vcc, 0, v[82:83]
	global_store_dwordx4 v[88:89], v[84:87], off
	s_and_saveexec_b64 s[76:77], vcc
	s_cbranch_execz .LBB0_543
	global_store_dwordx4 v[82:83], v[56:59], off
	global_store_dwordx4 v[82:83], v[52:55], off offset:16

; __device__ __forceinline__ void st16f(float* p, f32x4 v) { st16(p, __builtin_bit_cast(u32x4, v)); }
; __device__ __forceinline__ void st8bf(bf16_t* p, f32x4 a, f32x4 b) { u32x4 w; w.x = pk2(a[0], a[1]); w.y = pk2(a[2], a[3]); w.z = pk2(b[0], b[1]); w.w = pk2(b[2], b[3]); st16(p, w); }
; __device__ __forceinline__ unsigned f2bf(float f) { unsigned u = __builtin_bit_cast(unsigned, f); return (u + 0x7fffu + ((u >> 16) & 1u)) >> 16; }
; __device__ __forceinline__ unsigned pk2(float lo, float hi) { return f2bf(lo) | (f2bf(hi) << 16); }
;     __device__ __forceinline__ void st(int pn, int row, int c, f32x4 v0, f32x4 v1) const {
;     ...
;         else if (pn == 8) { float* o = (smp ? out + O_KCS + (size_t)(row - MP) * 256 : out + O_KC + (size_t)row * 256) + c; st16f(o, v0); st16f(o + 4, v1); }
;         else if (pn == 9) { float* o = (smp ? out + O_KSS + (size_t)(row - MP) * 256 : out + O_KSEL + (size_t)row * 256) + c; st16f(o, v0); st16f(o + 4, v1); st8bf(KS + (size_t)row * 256 + c, v0, v1); }
.LBB0_545:
	s_andn2_b64 vcc, exec, s[76:77]
	s_cbranch_vccnz .LBB0_547
	v_lshl_add_u64 v[82:83], s[36:37], 0, v[70:71]
	v_lshl_add_u64 v[84:85], s[38:39], 0, v[74:75]
	v_cndmask_b32_e64 v83, v83, v85, s[6:7]
	v_cndmask_b32_e64 v82, v82, v84, s[6:7]
	v_lshlrev_b32_e32 v84, 2, v206
	v_mov_b32_e32 v85, v1
	v_cndmask_b32_e64 v87, v69, 0, s[6:7]
	v_cndmask_b32_e64 v86, v68, v68, s[6:7]
	v_lshl_add_u64 v[82:83], v[82:83], 0, v[84:85]
	global_store_dwordx4 v[82:83], v[56:59], off
	global_store_dwordx4 v[82:83], v[52:55], off offset:16
	v_lshlrev_b64 v[82:83], 9, v[86:87]
	v_lshl_add_u64 v[86:87], v[210:211], 0, v[82:83]
	v_cvt_pk_bf16_f32 v82, v56, v57
	v_cvt_pk_bf16_f32 v83, v58, v59
	v_cvt_pk_bf16_f32 v84, v52, v53
	v_bfe_u32 v85, v54, 16, 1
	v_add3_u32 v85, v54, v85, s81
	v_bfe_u32 v88, v55, 16, 1
	v_lshrrev_b32_e32 v85, 16, v85
	v_add3_u32 v88, v55, v88, s81
	v_and_or_b32 v85, v88, s25, v85
	global_store_dwordx4 v[86:87], v[82:85], off

; __device__ __forceinline__ void st8bf(bf16_t* p, f32x4 a, f32x4 b) { u32x4 w; w.x = pk2(a[0], a[1]); w.y = pk2(a[2], a[3]); w.z = pk2(b[0], b[1]); w.w = pk2(b[2], b[3]); st16(p, w); }
; __device__ __forceinline__ unsigned f2bf(float f) { unsigned u = __builtin_bit_cast(unsigned, f); return (u + 0x7fffu + ((u >> 16) & 1u)) >> 16; }
; __device__ __forceinline__ unsigned pk2(float lo, float hi) { return f2bf(lo) | (f2bf(hi) << 16); }
;     __device__ __forceinline__ void st(int pn, int row, int c, f32x4 v0, f32x4 v1) const {
;     ...
;         else if (pn < 8) st8bf(Q + (size_t)row * 512 + (pn - 6) * 256 + c, v0 * C2, v1 * C2);
.LBB0_551:
	s_and_b64 vcc, exec, s[76:77]
	s_cbranch_vccz .LBB0_553
	v_lshl_add_u64 v[82:83], s[28:29], 0, v[70:71]
	s_lshl_b32 s40, s43, 1
	v_lshl_add_u64 v[82:83], v[82:83], 0, s[40:41]
	v_lshlrev_b32_e32 v84, 1, v206
	v_mov_b32_e32 v85, v1
	v_lshl_add_u64 v[86:87], v[82:83], 0, v[84:85]
	v_pk_mul_f32 v[82:83], v[56:57], s[50:51] op_sel_hi:[1,0]
	v_pk_mul_f32 v[84:85], v[58:59], s[50:51] op_sel_hi:[1,0]
	v_cvt_pk_bf16_f32 v82, v82, v83
	v_pk_mul_f32 v[90:91], v[52:53], s[50:51] op_sel_hi:[1,0]
	v_cvt_pk_bf16_f32 v83, v84, v85
	v_pk_mul_f32 v[88:89], v[54:55], s[50:51] op_sel_hi:[1,0]
	v_cvt_pk_bf16_f32 v84, v90, v91
	v_cvt_pk_bf16_f32 v85, v88, v89
	global_store_dwordx4 v[86:87], v[82:85], off offset:-3072

; __device__ __forceinline__ void st16f(float* p, f32x4 v) { st16(p, __builtin_bit_cast(u32x4, v)); }
; __device__ __forceinline__ void st8bf(bf16_t* p, f32x4 a, f32x4 b) { u32x4 w; w.x = pk2(a[0], a[1]); w.y = pk2(a[2], a[3]); w.z = pk2(b[0], b[1]); w.w = pk2(b[2], b[3]); st16(p, w); }
; __device__ __forceinline__ unsigned f2bf(float f) { unsigned u = __builtin_bit_cast(unsigned, f); return (u + 0x7fffu + ((u >> 16) & 1u)) >> 16; }
; __device__ __forceinline__ unsigned pk2(float lo, float hi) { return f2bf(lo) | (f2bf(hi) << 16); }
;     __device__ __forceinline__ void st(int pn, int row, int c, f32x4 v0, f32x4 v1) const {
;     ...
;         else if (pn == 10) { float* o = nullptr;
;             if (!smp) { if (t >= SEQ - 512) o = out + O_WIN + ((size_t)b * 512 + (t - (SEQ - 512))) * 256 + c; } else o = out + O_WINS + ((size_t)b * 512 + 508 + t) * 256 + c;
;             st8bf(KW + (size_t)row * 256 + c, v0, v1); if (o) { st16f(o, v0); st16f(o + 4, v1); } }
.LBB0_561:
	s_andn2_saveexec_b64 s[8:9], s[10:11]
	v_lshl_add_u64 v[78:79], v[214:215], 0, v[78:79]
	s_mov_b64 s[10:11], 0x200
	v_lshl_add_u64 v[82:83], v[78:79], 0, s[10:11]
	s_or_b64 exec, exec, s[8:9]
	v_lshl_add_u64 v[80:81], v[216:217], 0, v[76:77]
	v_cvt_pk_bf16_f32 v76, v64, v65
	v_cvt_pk_bf16_f32 v77, v66, v67
	v_cvt_pk_bf16_f32 v78, v60, v61
	v_cvt_pk_bf16_f32 v79, v62, v63
	v_cmp_ne_u64_e32 vcc, 0, v[82:83]
	global_store_dwordx4 v[80:81], v[76:79], off
	s_and_saveexec_b64 s[8:9], vcc
	s_cbranch_execz .LBB0_565
	global_store_dwordx4 v[82:83], v[64:67], off
	global_store_dwordx4 v[82:83], v[60:63], off offset:16

; __device__ __forceinline__ void st16f(float* p, f32x4 v) { st16(p, __builtin_bit_cast(u32x4, v)); }
; __device__ __forceinline__ void st8bf(bf16_t* p, f32x4 a, f32x4 b) { u32x4 w; w.x = pk2(a[0], a[1]); w.y = pk2(a[2], a[3]); w.z = pk2(b[0], b[1]); w.w = pk2(b[2], b[3]); st16(p, w); }
; __device__ __forceinline__ unsigned f2bf(float f) { unsigned u = __builtin_bit_cast(unsigned, f); return (u + 0x7fffu + ((u >> 16) & 1u)) >> 16; }
; __device__ __forceinline__ unsigned pk2(float lo, float hi) { return f2bf(lo) | (f2bf(hi) << 16); }
;     __device__ __forceinline__ void st(int pn, int row, int c, f32x4 v0, f32x4 v1) const {
;     ...
;         else if (pn == 8) { float* o = (smp ? out + O_KCS + (size_t)(row - MP) * 256 : out + O_KC + (size_t)row * 256) + c; st16f(o, v0); st16f(o + 4, v1); }
;         else if (pn == 9) { float* o = (smp ? out + O_KSS + (size_t)(row - MP) * 256 : out + O_KSEL + (size_t)row * 256) + c; st16f(o, v0); st16f(o + 4, v1); st8bf(KS + (size_t)row * 256 + c, v0, v1); }
.LBB0_567:
	s_andn2_b64 vcc, exec, s[12:13]
	s_cbranch_vccnz .LBB0_569
	v_lshl_add_u64 v[76:77], s[36:37], 0, v[70:71]
	v_lshl_add_u64 v[74:75], s[38:39], 0, v[74:75]
	v_cndmask_b32_e64 v75, v77, v75, s[6:7]
	v_cndmask_b32_e64 v74, v76, v74, s[6:7]
	v_lshlrev_b32_e32 v76, 2, v206
	v_mov_b32_e32 v77, v1
	v_cndmask_b32_e64 v79, v69, 0, s[6:7]
	v_cndmask_b32_e64 v78, v68, v68, s[6:7]
	v_lshl_add_u64 v[74:75], v[74:75], 0, v[76:77]
	global_store_dwordx4 v[74:75], v[64:67], off offset:512
	global_store_dwordx4 v[74:75], v[60:63], off offset:528
	v_lshlrev_b64 v[74:75], 9, v[78:79]
	v_lshl_add_u64 v[78:79], v[218:219], 0, v[74:75]
	v_cvt_pk_bf16_f32 v74, v64, v65
	v_cvt_pk_bf16_f32 v75, v66, v67
	v_cvt_pk_bf16_f32 v76, v60, v61
	v_cvt_pk_bf16_f32 v77, v62, v63
	global_store_dwordx4 v[78:79], v[74:77], off

; __device__ __forceinline__ void st8bf(bf16_t* p, f32x4 a, f32x4 b) { u32x4 w; w.x = pk2(a[0], a[1]); w.y = pk2(a[2], a[3]); w.z = pk2(b[0], b[1]); w.w = pk2(b[2], b[3]); st16(p, w); }
; __device__ __forceinline__ unsigned f2bf(float f) { unsigned u = __builtin_bit_cast(unsigned, f); return (u + 0x7fffu + ((u >> 16) & 1u)) >> 16; }
; __device__ __forceinline__ unsigned pk2(float lo, float hi) { return f2bf(lo) | (f2bf(hi) << 16); }
;     __device__ __forceinline__ void st(int pn, int row, int c, f32x4 v0, f32x4 v1) const {
;     ...
;         else if (pn < 8) st8bf(Q + (size_t)row * 512 + (pn - 6) * 256 + c, v0 * C2, v1 * C2);
.LBB0_573:
	s_and_b64 vcc, exec, s[12:13]
	s_cbranch_vccz .LBB0_575
	v_lshl_add_u64 v[72:73], s[28:29], 0, v[70:71]
	s_lshl_b32 s40, s43, 1
	v_lshl_add_u64 v[72:73], v[72:73], 0, s[40:41]
	v_lshlrev_b32_e32 v0, 1, v206
	v_lshl_add_u64 v[76:77], v[72:73], 0, v[0:1]
	v_pk_mul_f32 v[72:73], v[64:65], s[50:51] op_sel_hi:[1,0]
	v_pk_mul_f32 v[74:75], v[66:67], s[50:51] op_sel_hi:[1,0]
	v_cvt_pk_bf16_f32 v72, v72, v73
	v_pk_mul_f32 v[80:81], v[60:61], s[50:51] op_sel_hi:[1,0]
	v_cvt_pk_bf16_f32 v73, v74, v75
	v_pk_mul_f32 v[78:79], v[62:63], s[50:51] op_sel_hi:[1,0]
	v_cvt_pk_bf16_f32 v74, v80, v81
	v_cvt_pk_bf16_f32 v75, v78, v79
	global_store_dwordx4 v[76:77], v[72:75], off offset:-2816

; __device__ __forceinline__ void st8bf(bf16_t* p, f32x4 a, f32x4 b) { u32x4 w; w.x = pk2(a[0], a[1]); w.y = pk2(a[2], a[3]); w.z = pk2(b[0], b[1]); w.w = pk2(b[2], b[3]); st16(p, w); }
; __device__ __forceinline__ f32x4 sig4(f32x4 v) { f32x4 r; r[0] = sigmoidf_(v[0]); r[1] = sigmoidf_(v[1]); r[2] = sigmoidf_(v[2]); r[3] = sigmoidf_(v[3]); return r; }
; __device__ __forceinline__ float sigmoidf_(float x) { return __builtin_amdgcn_rcpf(1.0f + __expf(-x)); }
; __device__ __forceinline__ float siluf_(float x) { return x * sigmoidf_(x); }
;     __device__ __forceinline__ void st(int pn, int row, int c, f32x4 v0, f32x4 v1) const {
;         const bool smp = row >= MP; const int b = smp ? (row - MP) >> 2 : row >> 13, t = smp ? (row - MP) & 3 : row & (SEQ - 1);
;         if (pn < 6 || pn == 11 || pn == 12) st8bf((pn < 6 ? AG : BG) + (size_t)row * 512 + (pn < 6 ? pn - 4 : pn - 11) * 256 + c, v0 * sig4(v0), v1 * sig4(v1));
.LBB0_579:
	s_and_b64 s[76:77], s[66:67], exec
	s_cselect_b32 s77, s51, s79
	s_cselect_b32 s76, s33, s78
	v_lshl_add_u64 v[82:83], s[76:77], 0, v[70:71]
	v_mul_f32_e32 v84, 0xbfb8aa3b, v56
	v_lshl_add_u64 v[82:83], s[64:65], 1, v[82:83]
	v_exp_f32_e32 v88, v84
	v_lshlrev_b32_e32 v84, 1, v206
	v_mov_b32_e32 v85, v1
	v_lshl_add_u64 v[86:87], v[82:83], 0, v[84:85]
	v_mul_f32_e32 v83, 0xbfb8aa3b, v57
	v_exp_f32_e32 v83, v83
	v_mul_f32_e32 v84, 0xbfb8aa3b, v58
	v_mul_f32_e32 v85, 0xbfb8aa3b, v59
	v_exp_f32_e32 v84, v84
	v_exp_f32_e32 v85, v85
	v_add_f32_e32 v82, 1.0, v88
	v_add_f32_e32 v83, 1.0, v83
	v_rcp_f32_e32 v82, v82
	v_rcp_f32_e32 v83, v83
	v_mul_f32_e32 v88, 0xbfb8aa3b, v52
	v_mul_f32_e32 v89, 0xbfb8aa3b, v53
	v_exp_f32_e32 v88, v88
	v_exp_f32_e32 v89, v89
	v_add_f32_e32 v84, 1.0, v84
	v_add_f32_e32 v85, 1.0, v85
	v_rcp_f32_e32 v84, v84
	v_rcp_f32_e32 v85, v85
	v_mul_f32_e32 v90, 0xbfb8aa3b, v54
	v_mul_f32_e32 v91, 0xbfb8aa3b, v55
	v_exp_f32_e32 v90, v90
	v_exp_f32_e32 v91, v91
	v_pk_mul_f32 v[82:83], v[56:57], v[82:83]
	v_add_f32_e32 v88, 1.0, v88
	v_add_f32_e32 v89, 1.0, v89
	v_bfe_u32 v92, v82, 16, 1
	v_rcp_f32_e32 v88, v88
	v_rcp_f32_e32 v89, v89
	v_add3_u32 v82, v82, v92, s81
	v_bfe_u32 v92, v83, 16, 1
	v_pk_mul_f32 v[84:85], v[58:59], v[84:85]
	v_lshrrev_b32_e32 v82, 16, v82
	v_add3_u32 v83, v83, v92, s81
	v_add_f32_e32 v90, 1.0, v90
	v_add_f32_e32 v91, 1.0, v91
	v_and_or_b32 v82, v83, s25, v82
	v_rcp_f32_e32 v90, v90
	v_rcp_f32_e32 v91, v91
	v_pk_mul_f32 v[88:89], v[52:53], v[88:89]
	v_cvt_pk_bf16_f32 v83, v84, v85
	v_pk_mul_f32 v[90:91], v[54:55], v[90:91]
	v_cvt_pk_bf16_f32 v84, v88, v89
	v_bfe_u32 v85, v90, 16, 1
	v_add3_u32 v85, v90, v85, s81
	v_bfe_u32 v88, v91, 16, 1
	v_lshrrev_b32_e32 v85, 16, v85
	v_add3_u32 v88, v91, v88, s81
	v_and_or_b32 v85, v88, s25, v85
	global_store_dwordx4 v[86:87], v[82:85], off
	s_and_b64 vcc, exec, s[12:13]
	s_mov_b64 s[12:13], -1
	s_cbranch_vccz .LBB0_555

; __device__ __forceinline__ void st8bf(bf16_t* p, f32x4 a, f32x4 b) { u32x4 w; w.x = pk2(a[0], a[1]); w.y = pk2(a[2], a[3]); w.z = pk2(b[0], b[1]); w.w = pk2(b[2], b[3]); st16(p, w); }
; __device__ __forceinline__ f32x4 sig4(f32x4 v) { f32x4 r; r[0] = sigmoidf_(v[0]); r[1] = sigmoidf_(v[1]); r[2] = sigmoidf_(v[2]); r[3] = sigmoidf_(v[3]); return r; }
; __device__ __forceinline__ float sigmoidf_(float x) { return __builtin_amdgcn_rcpf(1.0f + __expf(-x)); }
; __device__ __forceinline__ float siluf_(float x) { return x * sigmoidf_(x); }
;     __device__ __forceinline__ void st(int pn, int row, int c, f32x4 v0, f32x4 v1) const {
;         const bool smp = row >= MP; const int b = smp ? (row - MP) >> 2 : row >> 13, t = smp ? (row - MP) & 3 : row & (SEQ - 1);
;         if (pn < 6 || pn == 11 || pn == 12) st8bf((pn < 6 ? AG : BG) + (size_t)row * 512 + (pn < 6 ? pn - 4 : pn - 11) * 256 + c, v0 * sig4(v0), v1 * sig4(v1));
.LBB0_581:
	v_mul_f32_e32 v0, 0xbfb8aa3b, v64
	s_and_b64 s[8:9], s[66:67], exec
	v_exp_f32_e32 v69, v0
	s_cselect_b32 s9, s51, s79
	s_cselect_b32 s8, s33, s78
	v_lshl_add_u64 v[70:71], s[8:9], 0, v[70:71]
	v_lshl_add_u64 v[70:71], s[64:65], 1, v[70:71]
	v_lshlrev_b32_e32 v0, 1, v206
	v_lshl_add_u64 v[74:75], v[70:71], 0, v[0:1]
	v_add_f32_e32 v0, 1.0, v69
	v_mul_f32_e32 v69, 0xbfb8aa3b, v65
	v_exp_f32_e32 v69, v69
	v_mul_f32_e32 v70, 0xbfb8aa3b, v66
	v_exp_f32_e32 v72, v70
	v_rcp_f32_e32 v70, v0
	v_add_f32_e32 v0, 1.0, v69
	v_mul_f32_e32 v69, 0xbfb8aa3b, v67
	v_rcp_f32_e32 v71, v0
	v_add_f32_e32 v0, 1.0, v72
	v_exp_f32_e32 v69, v69
	v_mul_f32_e32 v72, 0xbfb8aa3b, v60
	v_exp_f32_e32 v76, v72
	v_rcp_f32_e32 v72, v0
	v_add_f32_e32 v0, 1.0, v69
	v_rcp_f32_e32 v73, v0
	v_add_f32_e32 v0, 1.0, v76
	v_rcp_f32_e32 v76, v0
	v_mul_f32_e32 v0, 0xbfb8aa3b, v61
	v_mul_f32_e32 v69, 0xbfb8aa3b, v62
	v_exp_f32_e32 v0, v0
	v_exp_f32_e32 v69, v69
	v_mul_f32_e32 v77, 0xbfb8aa3b, v63
	v_exp_f32_e32 v77, v77
	v_add_f32_e32 v0, 1.0, v0
	v_add_f32_e32 v69, 1.0, v69
	v_pk_mul_f32 v[70:71], v[64:65], v[70:71]
	v_rcp_f32_e32 v78, v69
	v_add_f32_e32 v69, 1.0, v77
	v_rcp_f32_e32 v77, v0
	v_rcp_f32_e32 v79, v69
	v_pk_mul_f32 v[72:73], v[66:67], v[72:73]
	v_cvt_pk_bf16_f32 v70, v70, v71
	v_pk_mul_f32 v[76:77], v[60:61], v[76:77]
	v_cvt_pk_bf16_f32 v71, v72, v73
	v_pk_mul_f32 v[78:79], v[62:63], v[78:79]
	v_cvt_pk_bf16_f32 v72, v76, v77
	v_cvt_pk_bf16_f32 v73, v78, v79
	global_store_dwordx4 v[74:75], v[70:73], off offset:256

; __device__ __forceinline__ void st16f(float* p, f32x4 v) { st16(p, __builtin_bit_cast(u32x4, v)); }
; __device__ __forceinline__ void st8bf(bf16_t* p, f32x4 a, f32x4 b) { u32x4 w; w.x = pk2(a[0], a[1]); w.y = pk2(a[2], a[3]); w.z = pk2(b[0], b[1]); w.w = pk2(b[2], b[3]); st16(p, w); }
; __device__ __forceinline__ f32x4 sig4(f32x4 v) { f32x4 r; r[0] = sigmoidf_(v[0]); r[1] = sigmoidf_(v[1]); r[2] = sigmoidf_(v[2]); r[3] = sigmoidf_(v[3]); return r; }
;     __device__ __forceinline__ void st_glu(int pn, int row, int c, f32x4 a0, f32x4 a1, f32x4 g0, f32x4 g1) const {
;         const bool smp = row >= MP; const int b = smp ? (row - MP) >> 2 : row >> 13, t = smp ? (row - MP) & 3 : row & (SEQ - 1);
;         const f32x4 v0 = a0 * sig4(g0), v1 = a1 * sig4(g1);
;         const int col = pn * 128 + c;
;         st8bf(U + (size_t)row * 512 + col, v0, v1);
;         float* o = nullptr;
;         if (!smp) { if (t >= SEQ - 30) o = out + O_CONV + ((size_t)b * 30 + (t - (SEQ - 30))) * 512 + col; }
;         else o = out + O_CONVS + ((size_t)b * 30 + 26 + t) * 512 + col;
;         if (o) { st16f(o, v0); st16f(o + 4, v1); }
.LBB0_583:
	s_and_b64 vcc, exec, s[8:9]
	s_cbranch_vccz .LBB0_589
	v_mul_f32_e32 v0, 0xbfb8aa3b, v64
	v_exp_f32_e32 v0, v0
	v_mul_f32_e32 v64, 0xbfb8aa3b, v65
	v_mul_f32_e32 v65, 0xbfb8aa3b, v66
	v_exp_f32_e32 v66, v64
	v_add_f32_e32 v0, 1.0, v0
	v_exp_f32_e32 v69, v65
	v_rcp_f32_e32 v64, v0
	v_add_f32_e32 v0, 1.0, v66
	v_mul_f32_e32 v66, 0xbfb8aa3b, v67
	v_exp_f32_e32 v67, v66
	v_mul_f32_e32 v60, 0xbfb8aa3b, v60
	v_exp_f32_e32 v60, v60
	v_rcp_f32_e32 v65, v0
	v_add_f32_e32 v0, 1.0, v69
	v_rcp_f32_e32 v66, v0
	v_add_f32_e32 v0, 1.0, v67
	v_rcp_f32_e32 v67, v0
	v_add_f32_e32 v0, 1.0, v60
	v_rcp_f32_e32 v60, v0
	v_mul_f32_e32 v0, 0xbfb8aa3b, v61
	v_mul_f32_e32 v61, 0xbfb8aa3b, v62
	v_exp_f32_e32 v61, v61
	v_mul_f32_e32 v62, 0xbfb8aa3b, v63
	v_exp_f32_e32 v0, v0
	v_exp_f32_e32 v63, v62
	v_add_f32_e32 v61, 1.0, v61
	v_rcp_f32_e32 v62, v61
	v_add_f32_e32 v0, 1.0, v0
	v_add_f32_e32 v61, 1.0, v63
	v_rcp_f32_e32 v63, v61
	v_rcp_f32_e32 v61, v0
	v_ashrrev_i32_e32 v69, 31, v68
	v_pk_mul_f32 v[56:57], v[56:57], v[64:65]
	v_pk_mul_f32 v[58:59], v[58:59], v[66:67]
	v_pk_mul_f32 v[52:53], v[52:53], v[60:61]
	v_lshlrev_b64 v[60:61], 10, v[68:69]
	v_lshl_add_u64 v[60:61], s[26:27], 0, v[60:61]
	v_lshl_add_u64 v[64:65], v[2:3], 1, v[60:61]
	v_cvt_pk_bf16_f32 v60, v56, v57
	v_cvt_pk_bf16_f32 v61, v58, v59
	v_pk_mul_f32 v[54:55], v[54:55], v[62:63]
	v_cvt_pk_bf16_f32 v62, v52, v53
	v_cvt_pk_bf16_f32 v63, v54, v55
	global_store_dwordx4 v[64:65], v[60:63], off
	s_nop 1
	v_mov_b64_e32 v[60:61], 0
	s_and_saveexec_b64 s[8:9], s[6:7]
	v_add_u32_e32 v0, 0xffff8000, v68
	v_lshrrev_b32_e32 v0, 2, v0
	v_mad_u64_u32 v[60:61], s[6:7], v0, 30, v[196:197]
	v_lshlrev_b64 v[60:61], 11, v[60:61]
	v_lshl_add_u64 v[60:61], s[34:35], 0, v[60:61]
	v_lshl_add_u64 v[60:61], v[2:3], 2, v[60:61]
	s_or_b64 exec, exec, s[8:9]
	v_cmp_ne_u64_e32 vcc, 0, v[60:61]
	s_and_saveexec_b64 s[6:7], vcc
	s_cbranch_execz .LBB0_588
	global_store_dwordx4 v[60:61], v[56:59], off
	global_store_dwordx4 v[60:61], v[52:55], off offset:16

; __device__ __forceinline__ void st16f(float* p, f32x4 v) { st16(p, __builtin_bit_cast(u32x4, v)); }
; __device__ __forceinline__ void st8bf(bf16_t* p, f32x4 a, f32x4 b) { u32x4 w; w.x = pk2(a[0], a[1]); w.y = pk2(a[2], a[3]); w.z = pk2(b[0], b[1]); w.w = pk2(b[2], b[3]); st16(p, w); }
; __device__ __forceinline__ unsigned f2bf(float f) { unsigned u = __builtin_bit_cast(unsigned, f); return (u + 0x7fffu + ((u >> 16) & 1u)) >> 16; }
; __device__ __forceinline__ unsigned pk2(float lo, float hi) { return f2bf(lo) | (f2bf(hi) << 16); }
;     __device__ __forceinline__ void st(int pn, int row, int c, f32x4 v0, f32x4 v1) const {
;     ...
;         else if (pn == 10) { float* o = nullptr;
;             if (!smp) { if (t >= SEQ - 512) o = out + O_WIN + ((size_t)b * 512 + (t - (SEQ - 512))) * 256 + c; } else o = out + O_WINS + ((size_t)b * 512 + 508 + t) * 256 + c;
;             st8bf(KW + (size_t)row * 256 + c, v0, v1); if (o) { st16f(o, v0); st16f(o + 4, v1); } }
.LBB0_601:
	s_andn2_saveexec_b64 s[76:77], s[76:77]
	v_lshl_add_u64 v[66:67], v[214:215], 0, v[62:63]
	s_or_b64 exec, exec, s[76:77]
	v_cvt_pk_bf16_f32 v70, v40, v41
	v_cvt_pk_bf16_f32 v71, v42, v43
	v_cvt_pk_bf16_f32 v72, v36, v37
	v_lshl_add_u64 v[74:75], v[208:209], 0, v[60:61]
	v_cvt_pk_bf16_f32 v73, v38, v39
	v_cmp_ne_u64_e32 vcc, 0, v[66:67]
	global_store_dwordx4 v[74:75], v[70:73], off
	s_and_saveexec_b64 s[76:77], vcc
	s_cbranch_execz .LBB0_605
	global_store_dwordx4 v[66:67], v[40:43], off
	global_store_dwordx4 v[66:67], v[36:39], off offset:16

; __device__ __forceinline__ void st16f(float* p, f32x4 v) { st16(p, __builtin_bit_cast(u32x4, v)); }
; __device__ __forceinline__ void st8bf(bf16_t* p, f32x4 a, f32x4 b) { u32x4 w; w.x = pk2(a[0], a[1]); w.y = pk2(a[2], a[3]); w.z = pk2(b[0], b[1]); w.w = pk2(b[2], b[3]); st16(p, w); }
; __device__ __forceinline__ unsigned f2bf(float f) { unsigned u = __builtin_bit_cast(unsigned, f); return (u + 0x7fffu + ((u >> 16) & 1u)) >> 16; }
; __device__ __forceinline__ unsigned pk2(float lo, float hi) { return f2bf(lo) | (f2bf(hi) << 16); }
;     __device__ __forceinline__ void st(int pn, int row, int c, f32x4 v0, f32x4 v1) const {
;     ...
;         else if (pn == 8) { float* o = (smp ? out + O_KCS + (size_t)(row - MP) * 256 : out + O_KC + (size_t)row * 256) + c; st16f(o, v0); st16f(o + 4, v1); }
;         else if (pn == 9) { float* o = (smp ? out + O_KSS + (size_t)(row - MP) * 256 : out + O_KSEL + (size_t)row * 256) + c; st16f(o, v0); st16f(o + 4, v1); st8bf(KS + (size_t)row * 256 + c, v0, v1); }
.LBB0_607:
	s_andn2_b64 vcc, exec, s[76:77]
	s_cbranch_vccnz .LBB0_609
	v_lshl_add_u64 v[66:67], s[36:37], 0, v[54:55]
	v_lshl_add_u64 v[70:71], s[38:39], 0, v[58:59]
	v_cndmask_b32_e64 v67, v67, v71, s[6:7]
	v_cndmask_b32_e64 v66, v66, v70, s[6:7]
	v_lshlrev_b32_e32 v70, 2, v206
	v_mov_b32_e32 v71, v1
	v_lshl_add_u64 v[66:67], v[66:67], 0, v[70:71]
	v_cvt_pk_bf16_f32 v70, v40, v41
	v_cndmask_b32_e64 v73, v53, 0, s[6:7]
	v_cndmask_b32_e64 v72, v52, v52, s[6:7]
	v_cvt_pk_bf16_f32 v71, v42, v43
	global_store_dwordx4 v[66:67], v[40:43], off
	global_store_dwordx4 v[66:67], v[36:39], off offset:16
	v_lshlrev_b64 v[66:67], 9, v[72:73]
	v_cvt_pk_bf16_f32 v72, v36, v37
	v_lshl_add_u64 v[66:67], v[210:211], 0, v[66:67]
	v_cvt_pk_bf16_f32 v73, v38, v39
	global_store_dwordx4 v[66:67], v[70:73], off

; __device__ __forceinline__ void st8bf(bf16_t* p, f32x4 a, f32x4 b) { u32x4 w; w.x = pk2(a[0], a[1]); w.y = pk2(a[2], a[3]); w.z = pk2(b[0], b[1]); w.w = pk2(b[2], b[3]); st16(p, w); }
; __device__ __forceinline__ unsigned f2bf(float f) { unsigned u = __builtin_bit_cast(unsigned, f); return (u + 0x7fffu + ((u >> 16) & 1u)) >> 16; }
; __device__ __forceinline__ unsigned pk2(float lo, float hi) { return f2bf(lo) | (f2bf(hi) << 16); }
;     __device__ __forceinline__ void st(int pn, int row, int c, f32x4 v0, f32x4 v1) const {
;     ...
;         else if (pn < 8) st8bf(Q + (size_t)row * 512 + (pn - 6) * 256 + c, v0 * C2, v1 * C2);
.LBB0_613:
	s_and_b64 vcc, exec, s[76:77]
	s_cbranch_vccz .LBB0_615
	v_lshl_add_u64 v[66:67], s[28:29], 0, v[54:55]
	s_lshl_b32 s40, s43, 1
	v_lshl_add_u64 v[66:67], v[66:67], 0, s[40:41]
	v_lshlrev_b32_e32 v70, 1, v206
	v_mov_b32_e32 v71, v1
	v_lshl_add_u64 v[66:67], v[66:67], 0, v[70:71]
	v_pk_mul_f32 v[70:71], v[40:41], s[50:51] op_sel_hi:[1,0]
	v_pk_mul_f32 v[72:73], v[42:43], s[50:51] op_sel_hi:[1,0]
	v_cvt_pk_bf16_f32 v70, v70, v71
	v_pk_mul_f32 v[76:77], v[36:37], s[50:51] op_sel_hi:[1,0]
	v_cvt_pk_bf16_f32 v71, v72, v73
	v_pk_mul_f32 v[74:75], v[38:39], s[50:51] op_sel_hi:[1,0]
	v_cvt_pk_bf16_f32 v72, v76, v77
	v_cvt_pk_bf16_f32 v73, v74, v75
	global_store_dwordx4 v[66:67], v[70:73], off offset:-3072

; __device__ __forceinline__ void st16f(float* p, f32x4 v) { st16(p, __builtin_bit_cast(u32x4, v)); }
; __device__ __forceinline__ void st8bf(bf16_t* p, f32x4 a, f32x4 b) { u32x4 w; w.x = pk2(a[0], a[1]); w.y = pk2(a[2], a[3]); w.z = pk2(b[0], b[1]); w.w = pk2(b[2], b[3]); st16(p, w); }
; __device__ __forceinline__ unsigned f2bf(float f) { unsigned u = __builtin_bit_cast(unsigned, f); return (u + 0x7fffu + ((u >> 16) & 1u)) >> 16; }
; __device__ __forceinline__ unsigned pk2(float lo, float hi) { return f2bf(lo) | (f2bf(hi) << 16); }
;     __device__ __forceinline__ void st(int pn, int row, int c, f32x4 v0, f32x4 v1) const {
;     ...
;         else if (pn == 10) { float* o = nullptr;
;             if (!smp) { if (t >= SEQ - 512) o = out + O_WIN + ((size_t)b * 512 + (t - (SEQ - 512))) * 256 + c; } else o = out + O_WINS + ((size_t)b * 512 + 508 + t) * 256 + c;
;             st8bf(KW + (size_t)row * 256 + c, v0, v1); if (o) { st16f(o, v0); st16f(o + 4, v1); } }
.LBB0_623:
	s_andn2_saveexec_b64 s[8:9], s[10:11]
	v_lshl_add_u64 v[62:63], v[214:215], 0, v[62:63]
	s_mov_b64 s[10:11], 0x200
	v_lshl_add_u64 v[66:67], v[62:63], 0, s[10:11]
	s_or_b64 exec, exec, s[8:9]
	v_lshl_add_u64 v[64:65], v[216:217], 0, v[60:61]
	v_cvt_pk_bf16_f32 v60, v48, v49
	v_cvt_pk_bf16_f32 v61, v50, v51
	v_cvt_pk_bf16_f32 v62, v44, v45
	v_cvt_pk_bf16_f32 v63, v46, v47
	v_cmp_ne_u64_e32 vcc, 0, v[66:67]
	global_store_dwordx4 v[64:65], v[60:63], off
	s_and_saveexec_b64 s[8:9], vcc
	s_cbranch_execz .LBB0_627
	global_store_dwordx4 v[66:67], v[48:51], off
	global_store_dwordx4 v[66:67], v[44:47], off offset:16

; __device__ __forceinline__ void st16f(float* p, f32x4 v) { st16(p, __builtin_bit_cast(u32x4, v)); }
; __device__ __forceinline__ void st8bf(bf16_t* p, f32x4 a, f32x4 b) { u32x4 w; w.x = pk2(a[0], a[1]); w.y = pk2(a[2], a[3]); w.z = pk2(b[0], b[1]); w.w = pk2(b[2], b[3]); st16(p, w); }
; __device__ __forceinline__ unsigned f2bf(float f) { unsigned u = __builtin_bit_cast(unsigned, f); return (u + 0x7fffu + ((u >> 16) & 1u)) >> 16; }
; __device__ __forceinline__ unsigned pk2(float lo, float hi) { return f2bf(lo) | (f2bf(hi) << 16); }
;     __device__ __forceinline__ void st(int pn, int row, int c, f32x4 v0, f32x4 v1) const {
;     ...
;         else if (pn == 8) { float* o = (smp ? out + O_KCS + (size_t)(row - MP) * 256 : out + O_KC + (size_t)row * 256) + c; st16f(o, v0); st16f(o + 4, v1); }
;         else if (pn == 9) { float* o = (smp ? out + O_KSS + (size_t)(row - MP) * 256 : out + O_KSEL + (size_t)row * 256) + c; st16f(o, v0); st16f(o + 4, v1); st8bf(KS + (size_t)row * 256 + c, v0, v1); }
.LBB0_629:
	s_andn2_b64 vcc, exec, s[12:13]
	s_cbranch_vccnz .LBB0_631
	v_lshl_add_u64 v[60:61], s[36:37], 0, v[54:55]
	v_lshl_add_u64 v[58:59], s[38:39], 0, v[58:59]
	v_cndmask_b32_e64 v59, v61, v59, s[6:7]
	v_cndmask_b32_e64 v58, v60, v58, s[6:7]
	v_lshlrev_b32_e32 v60, 2, v206
	v_mov_b32_e32 v61, v1
	v_cndmask_b32_e64 v63, v53, 0, s[6:7]
	v_cndmask_b32_e64 v62, v52, v52, s[6:7]
	v_lshl_add_u64 v[58:59], v[58:59], 0, v[60:61]
	global_store_dwordx4 v[58:59], v[48:51], off offset:512
	global_store_dwordx4 v[58:59], v[44:47], off offset:528
	v_lshlrev_b64 v[58:59], 9, v[62:63]
	v_lshl_add_u64 v[62:63], v[218:219], 0, v[58:59]
	v_cvt_pk_bf16_f32 v58, v48, v49
	v_cvt_pk_bf16_f32 v59, v50, v51
	v_cvt_pk_bf16_f32 v60, v44, v45
	v_cvt_pk_bf16_f32 v61, v46, v47
	global_store_dwordx4 v[62:63], v[58:61], off

; __device__ __forceinline__ void st8bf(bf16_t* p, f32x4 a, f32x4 b) { u32x4 w; w.x = pk2(a[0], a[1]); w.y = pk2(a[2], a[3]); w.z = pk2(b[0], b[1]); w.w = pk2(b[2], b[3]); st16(p, w); }
; __device__ __forceinline__ unsigned f2bf(float f) { unsigned u = __builtin_bit_cast(unsigned, f); return (u + 0x7fffu + ((u >> 16) & 1u)) >> 16; }
; __device__ __forceinline__ unsigned pk2(float lo, float hi) { return f2bf(lo) | (f2bf(hi) << 16); }
;     __device__ __forceinline__ void st(int pn, int row, int c, f32x4 v0, f32x4 v1) const {
;     ...
;         else if (pn < 8) st8bf(Q + (size_t)row * 512 + (pn - 6) * 256 + c, v0 * C2, v1 * C2);
.LBB0_635:
	s_and_b64 vcc, exec, s[12:13]
	s_cbranch_vccz .LBB0_637
	v_lshl_add_u64 v[56:57], s[28:29], 0, v[54:55]
	s_lshl_b32 s40, s43, 1
	v_lshl_add_u64 v[56:57], v[56:57], 0, s[40:41]
	v_lshlrev_b32_e32 v0, 1, v206
	v_lshl_add_u64 v[60:61], v[56:57], 0, v[0:1]
	v_pk_mul_f32 v[56:57], v[48:49], s[50:51] op_sel_hi:[1,0]
	v_pk_mul_f32 v[58:59], v[50:51], s[50:51] op_sel_hi:[1,0]
	v_cvt_pk_bf16_f32 v56, v56, v57
	v_pk_mul_f32 v[64:65], v[44:45], s[50:51] op_sel_hi:[1,0]
	v_cvt_pk_bf16_f32 v57, v58, v59
	v_pk_mul_f32 v[62:63], v[46:47], s[50:51] op_sel_hi:[1,0]
	v_cvt_pk_bf16_f32 v58, v64, v65
	v_cvt_pk_bf16_f32 v59, v62, v63
	global_store_dwordx4 v[60:61], v[56:59], off offset:-2816

; __device__ __forceinline__ void st8bf(bf16_t* p, f32x4 a, f32x4 b) { u32x4 w; w.x = pk2(a[0], a[1]); w.y = pk2(a[2], a[3]); w.z = pk2(b[0], b[1]); w.w = pk2(b[2], b[3]); st16(p, w); }
; __device__ __forceinline__ f32x4 sig4(f32x4 v) { f32x4 r; r[0] = sigmoidf_(v[0]); r[1] = sigmoidf_(v[1]); r[2] = sigmoidf_(v[2]); r[3] = sigmoidf_(v[3]); return r; }
; __device__ __forceinline__ float sigmoidf_(float x) { return __builtin_amdgcn_rcpf(1.0f + __expf(-x)); }
; __device__ __forceinline__ float siluf_(float x) { return x * sigmoidf_(x); }
;     __device__ __forceinline__ void st(int pn, int row, int c, f32x4 v0, f32x4 v1) const {
;         const bool smp = row >= MP; const int b = smp ? (row - MP) >> 2 : row >> 13, t = smp ? (row - MP) & 3 : row & (SEQ - 1);
;         if (pn < 6 || pn == 11 || pn == 12) st8bf((pn < 6 ? AG : BG) + (size_t)row * 512 + (pn < 6 ? pn - 4 : pn - 11) * 256 + c, v0 * sig4(v0), v1 * sig4(v1));
.LBB0_639:
	s_and_b64 s[76:77], s[66:67], exec
	s_cselect_b32 s77, s51, s79
	s_cselect_b32 s76, s33, s78
	v_lshl_add_u64 v[66:67], s[76:77], 0, v[54:55]
	v_lshl_add_u64 v[66:67], s[64:65], 1, v[66:67]
	v_mul_f32_e32 v69, 0xbfb8aa3b, v40
	v_lshlrev_b32_e32 v70, 1, v206
	v_mov_b32_e32 v71, v1
	v_exp_f32_e32 v69, v69
	v_lshl_add_u64 v[66:67], v[66:67], 0, v[70:71]
	v_mul_f32_e32 v70, 0xbfb8aa3b, v41
	v_exp_f32_e32 v71, v70
	v_mul_f32_e32 v70, 0xbfb8aa3b, v42
	v_exp_f32_e32 v72, v70
	v_add_f32_e32 v69, 1.0, v69
	v_rcp_f32_e32 v70, v69
	v_add_f32_e32 v69, 1.0, v71
	v_rcp_f32_e32 v71, v69
	v_add_f32_e32 v69, 1.0, v72
	v_mul_f32_e32 v72, 0xbfb8aa3b, v43
	v_exp_f32_e32 v73, v72
	v_mul_f32_e32 v72, 0xbfb8aa3b, v36
	v_exp_f32_e32 v74, v72
	v_rcp_f32_e32 v72, v69
	v_add_f32_e32 v69, 1.0, v73
	v_rcp_f32_e32 v73, v69
	v_add_f32_e32 v69, 1.0, v74
	v_mul_f32_e32 v75, 0xbfb8aa3b, v38
	v_rcp_f32_e32 v74, v69
	v_mul_f32_e32 v69, 0xbfb8aa3b, v37
	v_exp_f32_e32 v75, v75
	v_mul_f32_e32 v76, 0xbfb8aa3b, v39
	v_exp_f32_e32 v69, v69
	v_exp_f32_e32 v77, v76
	v_add_f32_e32 v75, 1.0, v75
	v_rcp_f32_e32 v76, v75
	v_add_f32_e32 v69, 1.0, v69
	v_add_f32_e32 v75, 1.0, v77
	v_pk_mul_f32 v[70:71], v[40:41], v[70:71]
	v_rcp_f32_e32 v77, v75
	v_rcp_f32_e32 v75, v69
	v_pk_mul_f32 v[72:73], v[42:43], v[72:73]
	v_cvt_pk_bf16_f32 v70, v70, v71
	v_pk_mul_f32 v[74:75], v[36:37], v[74:75]
	v_cvt_pk_bf16_f32 v71, v72, v73
	v_pk_mul_f32 v[76:77], v[38:39], v[76:77]
	v_cvt_pk_bf16_f32 v72, v74, v75
	v_bfe_u32 v69, v76, 16, 1
	v_add3_u32 v69, v76, v69, s81
	v_bfe_u32 v73, v77, 16, 1
	v_lshrrev_b32_e32 v69, 16, v69
	v_add3_u32 v73, v77, v73, s81
	v_and_or_b32 v73, v73, s25, v69
	global_store_dwordx4 v[66:67], v[70:73], off
	s_and_b64 vcc, exec, s[12:13]
	s_mov_b64 s[12:13], -1
	s_cbranch_vccz .LBB0_617

; __device__ __forceinline__ void st8bf(bf16_t* p, f32x4 a, f32x4 b) { u32x4 w; w.x = pk2(a[0], a[1]); w.y = pk2(a[2], a[3]); w.z = pk2(b[0], b[1]); w.w = pk2(b[2], b[3]); st16(p, w); }
; __device__ __forceinline__ f32x4 sig4(f32x4 v) { f32x4 r; r[0] = sigmoidf_(v[0]); r[1] = sigmoidf_(v[1]); r[2] = sigmoidf_(v[2]); r[3] = sigmoidf_(v[3]); return r; }
; __device__ __forceinline__ float sigmoidf_(float x) { return __builtin_amdgcn_rcpf(1.0f + __expf(-x)); }
; __device__ __forceinline__ float siluf_(float x) { return x * sigmoidf_(x); }
;     __device__ __forceinline__ void st(int pn, int row, int c, f32x4 v0, f32x4 v1) const {
;         const bool smp = row >= MP; const int b = smp ? (row - MP) >> 2 : row >> 13, t = smp ? (row - MP) & 3 : row & (SEQ - 1);
;         if (pn < 6 || pn == 11 || pn == 12) st8bf((pn < 6 ? AG : BG) + (size_t)row * 512 + (pn < 6 ? pn - 4 : pn - 11) * 256 + c, v0 * sig4(v0), v1 * sig4(v1));
.LBB0_641:
	v_mul_f32_e32 v0, 0xbfb8aa3b, v48
	s_and_b64 s[8:9], s[66:67], exec
	v_exp_f32_e32 v53, v0
	s_cselect_b32 s9, s51, s79
	s_cselect_b32 s8, s33, s78
	v_lshl_add_u64 v[54:55], s[8:9], 0, v[54:55]
	v_lshl_add_u64 v[54:55], s[64:65], 1, v[54:55]
	v_lshlrev_b32_e32 v0, 1, v206
	v_lshl_add_u64 v[58:59], v[54:55], 0, v[0:1]
	v_add_f32_e32 v0, 1.0, v53
	v_mul_f32_e32 v53, 0xbfb8aa3b, v49
	v_exp_f32_e32 v53, v53
	v_mul_f32_e32 v54, 0xbfb8aa3b, v50
	v_exp_f32_e32 v56, v54
	v_rcp_f32_e32 v54, v0
	v_add_f32_e32 v0, 1.0, v53
	v_mul_f32_e32 v53, 0xbfb8aa3b, v51
	v_rcp_f32_e32 v55, v0
	v_add_f32_e32 v0, 1.0, v56
	v_exp_f32_e32 v53, v53
	v_mul_f32_e32 v56, 0xbfb8aa3b, v44
	v_exp_f32_e32 v60, v56
	v_rcp_f32_e32 v56, v0
	v_add_f32_e32 v0, 1.0, v53
	v_rcp_f32_e32 v57, v0
	v_add_f32_e32 v0, 1.0, v60
	v_rcp_f32_e32 v60, v0
	v_mul_f32_e32 v0, 0xbfb8aa3b, v45
	v_mul_f32_e32 v53, 0xbfb8aa3b, v46
	v_exp_f32_e32 v0, v0
	v_exp_f32_e32 v53, v53
	v_mul_f32_e32 v61, 0xbfb8aa3b, v47
	v_exp_f32_e32 v61, v61
	v_add_f32_e32 v0, 1.0, v0
	v_add_f32_e32 v53, 1.0, v53
	v_pk_mul_f32 v[54:55], v[48:49], v[54:55]
	v_rcp_f32_e32 v62, v53
	v_add_f32_e32 v53, 1.0, v61
	v_rcp_f32_e32 v61, v0
	v_rcp_f32_e32 v63, v53
	v_pk_mul_f32 v[56:57], v[50:51], v[56:57]
	v_cvt_pk_bf16_f32 v54, v54, v55
	v_pk_mul_f32 v[60:61], v[44:45], v[60:61]
	v_cvt_pk_bf16_f32 v55, v56, v57
	v_pk_mul_f32 v[62:63], v[46:47], v[62:63]
	v_cvt_pk_bf16_f32 v56, v60, v61
	v_cvt_pk_bf16_f32 v57, v62, v63
	global_store_dwordx4 v[58:59], v[54:57], off offset:256

; __device__ __forceinline__ void st16f(float* p, f32x4 v) { st16(p, __builtin_bit_cast(u32x4, v)); }
; __device__ __forceinline__ void st8bf(bf16_t* p, f32x4 a, f32x4 b) { u32x4 w; w.x = pk2(a[0], a[1]); w.y = pk2(a[2], a[3]); w.z = pk2(b[0], b[1]); w.w = pk2(b[2], b[3]); st16(p, w); }
; __device__ __forceinline__ f32x4 sig4(f32x4 v) { f32x4 r; r[0] = sigmoidf_(v[0]); r[1] = sigmoidf_(v[1]); r[2] = sigmoidf_(v[2]); r[3] = sigmoidf_(v[3]); return r; }
;     __device__ __forceinline__ void st_glu(int pn, int row, int c, f32x4 a0, f32x4 a1, f32x4 g0, f32x4 g1) const {
;         const bool smp = row >= MP; const int b = smp ? (row - MP) >> 2 : row >> 13, t = smp ? (row - MP) & 3 : row & (SEQ - 1);
;         const f32x4 v0 = a0 * sig4(g0), v1 = a1 * sig4(g1);
;         const int col = pn * 128 + c;
;         st8bf(U + (size_t)row * 512 + col, v0, v1);
;         float* o = nullptr;
;         if (!smp) { if (t >= SEQ - 30) o = out + O_CONV + ((size_t)b * 30 + (t - (SEQ - 30))) * 512 + col; }
;         else o = out + O_CONVS + ((size_t)b * 30 + 26 + t) * 512 + col;
;         if (o) { st16f(o, v0); st16f(o + 4, v1); }
.LBB0_643:
	s_and_b64 vcc, exec, s[8:9]
	s_cbranch_vccz .LBB0_649
	v_mul_f32_e32 v0, 0xbfb8aa3b, v48
	v_exp_f32_e32 v0, v0
	v_mul_f32_e32 v48, 0xbfb8aa3b, v49
	v_mul_f32_e32 v49, 0xbfb8aa3b, v50
	v_exp_f32_e32 v50, v48
	v_add_f32_e32 v0, 1.0, v0
	v_exp_f32_e32 v53, v49
	v_rcp_f32_e32 v48, v0
	v_add_f32_e32 v0, 1.0, v50
	v_mul_f32_e32 v50, 0xbfb8aa3b, v51
	v_exp_f32_e32 v51, v50
	v_mul_f32_e32 v44, 0xbfb8aa3b, v44
	v_exp_f32_e32 v44, v44
	v_rcp_f32_e32 v49, v0
	v_add_f32_e32 v0, 1.0, v53
	v_rcp_f32_e32 v50, v0
	v_add_f32_e32 v0, 1.0, v51
	v_rcp_f32_e32 v51, v0
	v_add_f32_e32 v0, 1.0, v44
	v_rcp_f32_e32 v44, v0
	v_mul_f32_e32 v0, 0xbfb8aa3b, v45
	v_mul_f32_e32 v45, 0xbfb8aa3b, v46
	v_exp_f32_e32 v45, v45
	v_mul_f32_e32 v46, 0xbfb8aa3b, v47
	v_exp_f32_e32 v0, v0
	v_exp_f32_e32 v47, v46
	v_add_f32_e32 v45, 1.0, v45
	v_rcp_f32_e32 v46, v45
	v_add_f32_e32 v0, 1.0, v0
	v_add_f32_e32 v45, 1.0, v47
	v_rcp_f32_e32 v47, v45
	v_rcp_f32_e32 v45, v0
	v_ashrrev_i32_e32 v53, 31, v52
	v_pk_mul_f32 v[40:41], v[40:41], v[48:49]
	v_pk_mul_f32 v[42:43], v[42:43], v[50:51]
	v_pk_mul_f32 v[36:37], v[36:37], v[44:45]
	v_lshlrev_b64 v[44:45], 10, v[52:53]
	v_lshl_add_u64 v[44:45], s[26:27], 0, v[44:45]
	v_lshl_add_u64 v[48:49], v[2:3], 1, v[44:45]
	v_cvt_pk_bf16_f32 v44, v40, v41
	v_cvt_pk_bf16_f32 v45, v42, v43
	v_pk_mul_f32 v[38:39], v[38:39], v[46:47]
	v_cvt_pk_bf16_f32 v46, v36, v37
	v_cvt_pk_bf16_f32 v47, v38, v39
	global_store_dwordx4 v[48:49], v[44:47], off
	s_nop 1
	v_mov_b64_e32 v[44:45], 0
	s_and_saveexec_b64 s[8:9], s[6:7]
	v_add_u32_e32 v0, 0xffff8010, v68
	v_lshrrev_b32_e32 v0, 2, v0
	v_mad_u64_u32 v[44:45], s[6:7], v0, 30, v[196:197]
	v_lshlrev_b64 v[44:45], 11, v[44:45]
	v_lshl_add_u64 v[44:45], s[34:35], 0, v[44:45]
	v_lshl_add_u64 v[44:45], v[2:3], 2, v[44:45]
	s_or_b64 exec, exec, s[8:9]
	v_cmp_ne_u64_e32 vcc, 0, v[44:45]
	s_and_saveexec_b64 s[6:7], vcc
	s_cbranch_execz .LBB0_648
	global_store_dwordx4 v[44:45], v[40:43], off
	global_store_dwordx4 v[44:45], v[36:39], off offset:16

; __device__ __forceinline__ void st16f(float* p, f32x4 v) { st16(p, __builtin_bit_cast(u32x4, v)); }
; __device__ __forceinline__ void st8bf(bf16_t* p, f32x4 a, f32x4 b) { u32x4 w; w.x = pk2(a[0], a[1]); w.y = pk2(a[2], a[3]); w.z = pk2(b[0], b[1]); w.w = pk2(b[2], b[3]); st16(p, w); }
; __device__ __forceinline__ unsigned f2bf(float f) { unsigned u = __builtin_bit_cast(unsigned, f); return (u + 0x7fffu + ((u >> 16) & 1u)) >> 16; }
; __device__ __forceinline__ unsigned pk2(float lo, float hi) { return f2bf(lo) | (f2bf(hi) << 16); }
;     __device__ __forceinline__ void st(int pn, int row, int c, f32x4 v0, f32x4 v1) const {
;     ...
;         else if (pn == 10) { float* o = nullptr;
;             if (!smp) { if (t >= SEQ - 512) o = out + O_WIN + ((size_t)b * 512 + (t - (SEQ - 512))) * 256 + c; } else o = out + O_WINS + ((size_t)b * 512 + 508 + t) * 256 + c;
;             st8bf(KW + (size_t)row * 256 + c, v0, v1); if (o) { st16f(o, v0); st16f(o + 4, v1); } }
.LBB0_661:
	s_andn2_saveexec_b64 s[76:77], s[76:77]
	v_lshl_add_u64 v[50:51], v[214:215], 0, v[46:47]
	s_or_b64 exec, exec, s[76:77]
	v_cvt_pk_bf16_f32 v52, v24, v25
	v_cvt_pk_bf16_f32 v53, v26, v27
	v_cvt_pk_bf16_f32 v54, v20, v21
	v_bfe_u32 v55, v22, 16, 1
	v_add3_u32 v55, v22, v55, s81
	v_bfe_u32 v58, v23, 16, 1
	v_lshrrev_b32_e32 v55, 16, v55
	v_add3_u32 v58, v23, v58, s81
	v_lshl_add_u64 v[56:57], v[208:209], 0, v[44:45]
	v_and_or_b32 v55, v58, s25, v55
	v_cmp_ne_u64_e32 vcc, 0, v[50:51]
	global_store_dwordx4 v[56:57], v[52:55], off
	s_and_saveexec_b64 s[76:77], vcc
	s_cbranch_execz .LBB0_665
	global_store_dwordx4 v[50:51], v[24:27], off
	global_store_dwordx4 v[50:51], v[20:23], off offset:16

; __device__ __forceinline__ void st16f(float* p, f32x4 v) { st16(p, __builtin_bit_cast(u32x4, v)); }
; __device__ __forceinline__ void st8bf(bf16_t* p, f32x4 a, f32x4 b) { u32x4 w; w.x = pk2(a[0], a[1]); w.y = pk2(a[2], a[3]); w.z = pk2(b[0], b[1]); w.w = pk2(b[2], b[3]); st16(p, w); }
; __device__ __forceinline__ unsigned f2bf(float f) { unsigned u = __builtin_bit_cast(unsigned, f); return (u + 0x7fffu + ((u >> 16) & 1u)) >> 16; }
; __device__ __forceinline__ unsigned pk2(float lo, float hi) { return f2bf(lo) | (f2bf(hi) << 16); }
;     __device__ __forceinline__ void st(int pn, int row, int c, f32x4 v0, f32x4 v1) const {
;     ...
;         else if (pn == 8) { float* o = (smp ? out + O_KCS + (size_t)(row - MP) * 256 : out + O_KC + (size_t)row * 256) + c; st16f(o, v0); st16f(o + 4, v1); }
;         else if (pn == 9) { float* o = (smp ? out + O_KSS + (size_t)(row - MP) * 256 : out + O_KSEL + (size_t)row * 256) + c; st16f(o, v0); st16f(o + 4, v1); st8bf(KS + (size_t)row * 256 + c, v0, v1); }
.LBB0_667:
	s_andn2_b64 vcc, exec, s[76:77]
	s_cbranch_vccnz .LBB0_669
	v_lshl_add_u64 v[50:51], s[36:37], 0, v[38:39]
	v_lshl_add_u64 v[52:53], s[38:39], 0, v[42:43]
	v_cndmask_b32_e64 v51, v51, v53, s[8:9]
	v_cndmask_b32_e64 v50, v50, v52, s[8:9]
	v_lshlrev_b32_e32 v52, 2, v206
	v_mov_b32_e32 v53, v1
	v_cndmask_b32_e64 v55, v37, 0, s[8:9]
	v_cndmask_b32_e64 v54, v36, v36, s[8:9]
	v_lshl_add_u64 v[50:51], v[50:51], 0, v[52:53]
	global_store_dwordx4 v[50:51], v[24:27], off
	global_store_dwordx4 v[50:51], v[20:23], off offset:16
	v_lshlrev_b64 v[50:51], 9, v[54:55]
	v_lshl_add_u64 v[54:55], v[210:211], 0, v[50:51]
	v_cvt_pk_bf16_f32 v50, v24, v25
	v_cvt_pk_bf16_f32 v51, v26, v27
	v_cvt_pk_bf16_f32 v52, v20, v21
	v_bfe_u32 v53, v22, 16, 1
	v_add3_u32 v53, v22, v53, s81
	v_bfe_u32 v56, v23, 16, 1
	v_lshrrev_b32_e32 v53, 16, v53
	v_add3_u32 v56, v23, v56, s81
	v_and_or_b32 v53, v56, s25, v53
	global_store_dwordx4 v[54:55], v[50:53], off

; __device__ __forceinline__ void st8bf(bf16_t* p, f32x4 a, f32x4 b) { u32x4 w; w.x = pk2(a[0], a[1]); w.y = pk2(a[2], a[3]); w.z = pk2(b[0], b[1]); w.w = pk2(b[2], b[3]); st16(p, w); }
; __device__ __forceinline__ unsigned f2bf(float f) { unsigned u = __builtin_bit_cast(unsigned, f); return (u + 0x7fffu + ((u >> 16) & 1u)) >> 16; }
; __device__ __forceinline__ unsigned pk2(float lo, float hi) { return f2bf(lo) | (f2bf(hi) << 16); }
;     __device__ __forceinline__ void st(int pn, int row, int c, f32x4 v0, f32x4 v1) const {
;     ...
;         else if (pn < 8) st8bf(Q + (size_t)row * 512 + (pn - 6) * 256 + c, v0 * C2, v1 * C2);
.LBB0_673:
	s_and_b64 vcc, exec, s[76:77]
	s_cbranch_vccz .LBB0_675
	v_lshl_add_u64 v[50:51], s[28:29], 0, v[38:39]
	s_lshl_b32 s40, s43, 1
	v_lshl_add_u64 v[50:51], v[50:51], 0, s[40:41]
	v_lshlrev_b32_e32 v52, 1, v206
	v_mov_b32_e32 v53, v1
	v_lshl_add_u64 v[54:55], v[50:51], 0, v[52:53]
	v_pk_mul_f32 v[50:51], v[24:25], s[50:51] op_sel_hi:[1,0]
	v_pk_mul_f32 v[52:53], v[26:27], s[50:51] op_sel_hi:[1,0]
	v_cvt_pk_bf16_f32 v50, v50, v51
	v_pk_mul_f32 v[58:59], v[20:21], s[50:51] op_sel_hi:[1,0]
	v_cvt_pk_bf16_f32 v51, v52, v53
	v_pk_mul_f32 v[56:57], v[22:23], s[50:51] op_sel_hi:[1,0]
	v_cvt_pk_bf16_f32 v52, v58, v59
	v_cvt_pk_bf16_f32 v53, v56, v57
	global_store_dwordx4 v[54:55], v[50:53], off offset:-3072

; __device__ __forceinline__ void st16f(float* p, f32x4 v) { st16(p, __builtin_bit_cast(u32x4, v)); }
; __device__ __forceinline__ void st8bf(bf16_t* p, f32x4 a, f32x4 b) { u32x4 w; w.x = pk2(a[0], a[1]); w.y = pk2(a[2], a[3]); w.z = pk2(b[0], b[1]); w.w = pk2(b[2], b[3]); st16(p, w); }
; __device__ __forceinline__ unsigned f2bf(float f) { unsigned u = __builtin_bit_cast(unsigned, f); return (u + 0x7fffu + ((u >> 16) & 1u)) >> 16; }
; __device__ __forceinline__ unsigned pk2(float lo, float hi) { return f2bf(lo) | (f2bf(hi) << 16); }
;     __device__ __forceinline__ void st(int pn, int row, int c, f32x4 v0, f32x4 v1) const {
;     ...
;         else if (pn == 10) { float* o = nullptr;
;             if (!smp) { if (t >= SEQ - 512) o = out + O_WIN + ((size_t)b * 512 + (t - (SEQ - 512))) * 256 + c; } else o = out + O_WINS + ((size_t)b * 512 + 508 + t) * 256 + c;
;             st8bf(KW + (size_t)row * 256 + c, v0, v1); if (o) { st16f(o, v0); st16f(o + 4, v1); } }
.LBB0_683:
	s_andn2_saveexec_b64 s[10:11], s[12:13]
	v_lshl_add_u64 v[46:47], v[214:215], 0, v[46:47]
	s_mov_b64 s[12:13], 0x200
	v_lshl_add_u64 v[50:51], v[46:47], 0, s[12:13]
	s_or_b64 exec, exec, s[10:11]
	v_lshl_add_u64 v[48:49], v[216:217], 0, v[44:45]
	v_cvt_pk_bf16_f32 v44, v32, v33
	v_cvt_pk_bf16_f32 v45, v34, v35
	v_cvt_pk_bf16_f32 v46, v28, v29
	v_cvt_pk_bf16_f32 v47, v30, v31
	v_cmp_ne_u64_e32 vcc, 0, v[50:51]
	global_store_dwordx4 v[48:49], v[44:47], off
	s_and_saveexec_b64 s[10:11], vcc
	s_cbranch_execz .LBB0_687
	global_store_dwordx4 v[50:51], v[32:35], off
	global_store_dwordx4 v[50:51], v[28:31], off offset:16

; __device__ __forceinline__ void st16f(float* p, f32x4 v) { st16(p, __builtin_bit_cast(u32x4, v)); }
; __device__ __forceinline__ void st8bf(bf16_t* p, f32x4 a, f32x4 b) { u32x4 w; w.x = pk2(a[0], a[1]); w.y = pk2(a[2], a[3]); w.z = pk2(b[0], b[1]); w.w = pk2(b[2], b[3]); st16(p, w); }
; __device__ __forceinline__ f32x4 sig4(f32x4 v) { f32x4 r; r[0] = sigmoidf_(v[0]); r[1] = sigmoidf_(v[1]); r[2] = sigmoidf_(v[2]); r[3] = sigmoidf_(v[3]); return r; }
;     __device__ __forceinline__ void st(int pn, int row, int c, f32x4 v0, f32x4 v1) const {
;         const bool smp = row >= MP; const int b = smp ? (row - MP) >> 2 : row >> 13, t = smp ? (row - MP) & 3 : row & (SEQ - 1);
;         if (pn < 6 || pn == 11 || pn == 12) st8bf((pn < 6 ? AG : BG) + (size_t)row * 512 + (pn < 6 ? pn - 4 : pn - 11) * 256 + c, v0 * sig4(v0), v1 * sig4(v1));
;         else if (pn < 8) st8bf(Q + (size_t)row * 512 + (pn - 6) * 256 + c, v0 * C2, v1 * C2);
;         else if (pn == 8) { float* o = (smp ? out + O_KCS + (size_t)(row - MP) * 256 : out + O_KC + (size_t)row * 256) + c; st16f(o, v0); st16f(o + 4, v1); }
;         else if (pn == 9) { float* o = (smp ? out + O_KSS + (size_t)(row - MP) * 256 : out + O_KSEL + (size_t)row * 256) + c; st16f(o, v0); st16f(o + 4, v1); st8bf(KS + (size_t)row * 256 + c, v0, v1); }
.LBB0_689:
	s_andn2_b64 vcc, exec, s[12:13]
	s_cbranch_vccnz .LBB0_691
	v_lshl_add_u64 v[44:45], s[36:37], 0, v[38:39]
	v_lshl_add_u64 v[42:43], s[38:39], 0, v[42:43]
	v_cndmask_b32_e64 v43, v45, v43, s[8:9]
	v_cndmask_b32_e64 v42, v44, v42, s[8:9]
	v_lshlrev_b32_e32 v44, 2, v206
	v_mov_b32_e32 v45, v1
	v_cndmask_b32_e64 v47, v37, 0, s[8:9]
	v_cndmask_b32_e64 v46, v36, v36, s[8:9]
	v_lshl_add_u64 v[42:43], v[42:43], 0, v[44:45]
	global_store_dwordx4 v[42:43], v[32:35], off offset:512
	global_store_dwordx4 v[42:43], v[28:31], off offset:528
	v_lshlrev_b64 v[42:43], 9, v[46:47]
	v_lshl_add_u64 v[46:47], v[218:219], 0, v[42:43]
	v_cvt_pk_bf16_f32 v42, v32, v33
	v_cvt_pk_bf16_f32 v43, v34, v35
	v_cvt_pk_bf16_f32 v44, v28, v29
	v_cvt_pk_bf16_f32 v45, v30, v31
	global_store_dwordx4 v[46:47], v[42:45], off

; __device__ __forceinline__ void st8bf(bf16_t* p, f32x4 a, f32x4 b) { u32x4 w; w.x = pk2(a[0], a[1]); w.y = pk2(a[2], a[3]); w.z = pk2(b[0], b[1]); w.w = pk2(b[2], b[3]); st16(p, w); }
;     __device__ __forceinline__ void st(int pn, int row, int c, f32x4 v0, f32x4 v1) const {
;     ...
;         else if (pn < 8) st8bf(Q + (size_t)row * 512 + (pn - 6) * 256 + c, v0 * C2, v1 * C2);
.LBB0_695:
	s_and_b64 vcc, exec, s[12:13]
	s_cbranch_vccz .LBB0_697
	v_lshl_add_u64 v[40:41], s[28:29], 0, v[38:39]
	s_lshl_b32 s40, s43, 1
	v_lshl_add_u64 v[40:41], v[40:41], 0, s[40:41]
	v_lshlrev_b32_e32 v0, 1, v206
	v_lshl_add_u64 v[44:45], v[40:41], 0, v[0:1]
	v_pk_mul_f32 v[40:41], v[32:33], s[50:51] op_sel_hi:[1,0]
	v_pk_mul_f32 v[42:43], v[34:35], s[50:51] op_sel_hi:[1,0]
	v_cvt_pk_bf16_f32 v40, v40, v41
	v_pk_mul_f32 v[48:49], v[28:29], s[50:51] op_sel_hi:[1,0]
	v_cvt_pk_bf16_f32 v41, v42, v43
	v_pk_mul_f32 v[46:47], v[30:31], s[50:51] op_sel_hi:[1,0]
	v_cvt_pk_bf16_f32 v42, v48, v49
	v_cvt_pk_bf16_f32 v43, v46, v47
	global_store_dwordx4 v[44:45], v[40:43], off offset:-2816

; __device__ __forceinline__ void st8bf(bf16_t* p, f32x4 a, f32x4 b) { u32x4 w; w.x = pk2(a[0], a[1]); w.y = pk2(a[2], a[3]); w.z = pk2(b[0], b[1]); w.w = pk2(b[2], b[3]); st16(p, w); }
; __device__ __forceinline__ f32x4 sig4(f32x4 v) { f32x4 r; r[0] = sigmoidf_(v[0]); r[1] = sigmoidf_(v[1]); r[2] = sigmoidf_(v[2]); r[3] = sigmoidf_(v[3]); return r; }
;     __device__ __forceinline__ void st(int pn, int row, int c, f32x4 v0, f32x4 v1) const {
;     ...
;         if (pn < 6 || pn == 11 || pn == 12) st8bf((pn < 6 ? AG : BG) + (size_t)row * 512 + (pn < 6 ? pn - 4 : pn - 11) * 256 + c, v0 * sig4(v0), v1 * sig4(v1));
.LBB0_699:
	s_and_b64 s[76:77], s[66:67], exec
	s_cselect_b32 s77, s51, s79
	s_cselect_b32 s76, s33, s78
	v_lshl_add_u64 v[50:51], s[76:77], 0, v[38:39]
	v_mul_f32_e32 v52, 0xbfb8aa3b, v24
	v_lshl_add_u64 v[50:51], s[64:65], 1, v[50:51]
	v_exp_f32_e32 v56, v52
	v_lshlrev_b32_e32 v52, 1, v206
	v_mov_b32_e32 v53, v1
	v_lshl_add_u64 v[54:55], v[50:51], 0, v[52:53]
	v_mul_f32_e32 v51, 0xbfb8aa3b, v25
	v_exp_f32_e32 v51, v51
	v_mul_f32_e32 v52, 0xbfb8aa3b, v26
	v_mul_f32_e32 v53, 0xbfb8aa3b, v27
	v_exp_f32_e32 v52, v52
	v_exp_f32_e32 v53, v53
	v_add_f32_e32 v50, 1.0, v56
	v_add_f32_e32 v51, 1.0, v51
	v_rcp_f32_e32 v50, v50
	v_rcp_f32_e32 v51, v51
	v_mul_f32_e32 v56, 0xbfb8aa3b, v20
	v_mul_f32_e32 v57, 0xbfb8aa3b, v21
	v_exp_f32_e32 v56, v56
	v_exp_f32_e32 v57, v57
	v_add_f32_e32 v52, 1.0, v52
	v_add_f32_e32 v53, 1.0, v53
	v_rcp_f32_e32 v52, v52
	v_rcp_f32_e32 v53, v53
	v_mul_f32_e32 v58, 0xbfb8aa3b, v22
	v_mul_f32_e32 v59, 0xbfb8aa3b, v23
	v_exp_f32_e32 v58, v58
	v_exp_f32_e32 v59, v59
	v_pk_mul_f32 v[50:51], v[24:25], v[50:51]
	v_add_f32_e32 v56, 1.0, v56
	v_add_f32_e32 v57, 1.0, v57
	v_bfe_u32 v60, v50, 16, 1
	v_rcp_f32_e32 v56, v56
	v_rcp_f32_e32 v57, v57
	v_add3_u32 v50, v50, v60, s81
	v_bfe_u32 v60, v51, 16, 1
	v_pk_mul_f32 v[52:53], v[26:27], v[52:53]
	v_lshrrev_b32_e32 v50, 16, v50
	v_add3_u32 v51, v51, v60, s81
	v_add_f32_e32 v58, 1.0, v58
	v_add_f32_e32 v59, 1.0, v59
	v_and_or_b32 v50, v51, s25, v50
	v_rcp_f32_e32 v58, v58
	v_rcp_f32_e32 v59, v59
	v_pk_mul_f32 v[56:57], v[20:21], v[56:57]
	v_cvt_pk_bf16_f32 v51, v52, v53
	v_pk_mul_f32 v[58:59], v[22:23], v[58:59]
	v_cvt_pk_bf16_f32 v52, v56, v57
	v_bfe_u32 v53, v58, 16, 1
	v_add3_u32 v53, v58, v53, s81
	v_bfe_u32 v56, v59, 16, 1
	v_lshrrev_b32_e32 v53, 16, v53
	v_add3_u32 v56, v59, v56, s81
	v_and_or_b32 v53, v56, s25, v53
	global_store_dwordx4 v[54:55], v[50:53], off
	s_and_b64 vcc, exec, s[12:13]
	s_mov_b64 s[12:13], -1
	s_cbranch_vccz .LBB0_677

; __device__ __forceinline__ void st8bf(bf16_t* p, f32x4 a, f32x4 b) { u32x4 w; w.x = pk2(a[0], a[1]); w.y = pk2(a[2], a[3]); w.z = pk2(b[0], b[1]); w.w = pk2(b[2], b[3]); st16(p, w); }
; __device__ __forceinline__ f32x4 sig4(f32x4 v) { f32x4 r; r[0] = sigmoidf_(v[0]); r[1] = sigmoidf_(v[1]); r[2] = sigmoidf_(v[2]); r[3] = sigmoidf_(v[3]); return r; }
;     __device__ __forceinline__ void st(int pn, int row, int c, f32x4 v0, f32x4 v1) const {
;     ...
;         if (pn < 6 || pn == 11 || pn == 12) st8bf((pn < 6 ? AG : BG) + (size_t)row * 512 + (pn < 6 ? pn - 4 : pn - 11) * 256 + c, v0 * sig4(v0), v1 * sig4(v1));
.LBB0_701:
	v_mul_f32_e32 v0, 0xbfb8aa3b, v32
	s_and_b64 s[8:9], s[66:67], exec
	v_exp_f32_e32 v37, v0
	s_cselect_b32 s9, s51, s79
	s_cselect_b32 s8, s33, s78
	v_lshl_add_u64 v[38:39], s[8:9], 0, v[38:39]
	v_lshl_add_u64 v[38:39], s[64:65], 1, v[38:39]
	v_lshlrev_b32_e32 v0, 1, v206
	v_lshl_add_u64 v[42:43], v[38:39], 0, v[0:1]
	v_add_f32_e32 v0, 1.0, v37
	v_mul_f32_e32 v37, 0xbfb8aa3b, v33
	v_exp_f32_e32 v37, v37
	v_mul_f32_e32 v38, 0xbfb8aa3b, v34
	v_exp_f32_e32 v40, v38
	v_rcp_f32_e32 v38, v0
	v_add_f32_e32 v0, 1.0, v37
	v_mul_f32_e32 v37, 0xbfb8aa3b, v35
	v_rcp_f32_e32 v39, v0
	v_add_f32_e32 v0, 1.0, v40
	v_exp_f32_e32 v37, v37
	v_mul_f32_e32 v40, 0xbfb8aa3b, v28
	v_exp_f32_e32 v44, v40
	v_rcp_f32_e32 v40, v0
	v_add_f32_e32 v0, 1.0, v37
	v_rcp_f32_e32 v41, v0
	v_add_f32_e32 v0, 1.0, v44
	v_rcp_f32_e32 v44, v0
	v_mul_f32_e32 v0, 0xbfb8aa3b, v29
	v_mul_f32_e32 v37, 0xbfb8aa3b, v30
	v_exp_f32_e32 v0, v0
	v_exp_f32_e32 v37, v37
	v_mul_f32_e32 v45, 0xbfb8aa3b, v31
	v_exp_f32_e32 v45, v45
	v_add_f32_e32 v0, 1.0, v0
	v_add_f32_e32 v37, 1.0, v37
	v_pk_mul_f32 v[38:39], v[32:33], v[38:39]
	v_rcp_f32_e32 v46, v37
	v_add_f32_e32 v37, 1.0, v45
	v_rcp_f32_e32 v45, v0
	v_rcp_f32_e32 v47, v37
	v_pk_mul_f32 v[40:41], v[34:35], v[40:41]
	v_cvt_pk_bf16_f32 v38, v38, v39
	v_pk_mul_f32 v[44:45], v[28:29], v[44:45]
	v_cvt_pk_bf16_f32 v39, v40, v41
	v_pk_mul_f32 v[46:47], v[30:31], v[46:47]
	v_cvt_pk_bf16_f32 v40, v44, v45
	v_cvt_pk_bf16_f32 v41, v46, v47
	global_store_dwordx4 v[42:43], v[38:41], off offset:256

; __device__ __forceinline__ void st16f(float* p, f32x4 v) { st16(p, __builtin_bit_cast(u32x4, v)); }
; __device__ __forceinline__ void st8bf(bf16_t* p, f32x4 a, f32x4 b) { u32x4 w; w.x = pk2(a[0], a[1]); w.y = pk2(a[2], a[3]); w.z = pk2(b[0], b[1]); w.w = pk2(b[2], b[3]); st16(p, w); }
; __device__ __forceinline__ f32x4 sig4(f32x4 v) { f32x4 r; r[0] = sigmoidf_(v[0]); r[1] = sigmoidf_(v[1]); r[2] = sigmoidf_(v[2]); r[3] = sigmoidf_(v[3]); return r; }
;     __device__ __forceinline__ void st_glu(int pn, int row, int c, f32x4 a0, f32x4 a1, f32x4 g0, f32x4 g1) const {
;         const bool smp = row >= MP; const int b = smp ? (row - MP) >> 2 : row >> 13, t = smp ? (row - MP) & 3 : row & (SEQ - 1);
;         const f32x4 v0 = a0 * sig4(g0), v1 = a1 * sig4(g1);
;         const int col = pn * 128 + c;
;         st8bf(U + (size_t)row * 512 + col, v0, v1);
;         float* o = nullptr;
;         if (!smp) { if (t >= SEQ - 30) o = out + O_CONV + ((size_t)b * 30 + (t - (SEQ - 30))) * 512 + col; }
;         else o = out + O_CONVS + ((size_t)b * 30 + 26 + t) * 512 + col;
;         if (o) { st16f(o, v0); st16f(o + 4, v1); }
.LBB0_703:
	s_mul_i32 s74, s74, 30
	s_ashr_i32 s75, s74, 31
	s_and_b64 vcc, exec, s[10:11]
	s_cbranch_vccz .LBB0_709
	v_mul_f32_e32 v0, 0xbfb8aa3b, v32
	v_exp_f32_e32 v0, v0
	v_mul_f32_e32 v32, 0xbfb8aa3b, v33
	v_mul_f32_e32 v33, 0xbfb8aa3b, v34
	v_exp_f32_e32 v34, v32
	v_add_f32_e32 v0, 1.0, v0
	v_exp_f32_e32 v37, v33
	v_rcp_f32_e32 v32, v0
	v_add_f32_e32 v0, 1.0, v34
	v_mul_f32_e32 v34, 0xbfb8aa3b, v35
	v_exp_f32_e32 v35, v34
	v_mul_f32_e32 v28, 0xbfb8aa3b, v28
	v_exp_f32_e32 v28, v28
	v_rcp_f32_e32 v33, v0
	v_add_f32_e32 v0, 1.0, v37
	v_rcp_f32_e32 v34, v0
	v_add_f32_e32 v0, 1.0, v35
	v_rcp_f32_e32 v35, v0
	v_add_f32_e32 v0, 1.0, v28
	v_rcp_f32_e32 v28, v0
	v_mul_f32_e32 v0, 0xbfb8aa3b, v29
	v_mul_f32_e32 v29, 0xbfb8aa3b, v30
	v_exp_f32_e32 v29, v29
	v_mul_f32_e32 v30, 0xbfb8aa3b, v31
	v_exp_f32_e32 v0, v0
	v_exp_f32_e32 v31, v30
	v_add_f32_e32 v29, 1.0, v29
	v_rcp_f32_e32 v30, v29
	v_add_f32_e32 v0, 1.0, v0
	v_add_f32_e32 v29, 1.0, v31
	v_rcp_f32_e32 v31, v29
	v_rcp_f32_e32 v29, v0
	v_ashrrev_i32_e32 v37, 31, v36
	v_pk_mul_f32 v[24:25], v[24:25], v[32:33]
	v_pk_mul_f32 v[26:27], v[26:27], v[34:35]
	v_pk_mul_f32 v[20:21], v[20:21], v[28:29]
	v_lshlrev_b64 v[28:29], 10, v[36:37]
	v_lshl_add_u64 v[28:29], s[26:27], 0, v[28:29]
	v_lshl_add_u64 v[32:33], v[2:3], 1, v[28:29]
	v_cvt_pk_bf16_f32 v28, v24, v25
	v_cvt_pk_bf16_f32 v29, v26, v27
	v_pk_mul_f32 v[22:23], v[22:23], v[30:31]
	v_cvt_pk_bf16_f32 v30, v20, v21
	v_cvt_pk_bf16_f32 v31, v22, v23
	global_store_dwordx4 v[32:33], v[28:31], off
	s_and_saveexec_b64 s[8:9], s[6:7]
	s_xor_b64 s[6:7], exec, s[8:9]
	s_cbranch_execz .LBB0_764
	v_and_b32_e32 v0, 0x1fef, v36
	s_movk_i32 s8, 0x1fe1
	v_cmp_lt_u32_e32 vcc, s8, v0
	v_add_u32_e32 v0, 0xffffe01e, v0
	v_lshl_add_u64 v[28:29], v[0:1], 0, s[74:75]
	v_lshlrev_b64 v[28:29], 11, v[28:29]
	v_lshl_add_u64 v[28:29], s[30:31], 0, v[28:29]
	v_lshl_add_u64 v[28:29], v[2:3], 2, v[28:29]
	v_cndmask_b32_e32 v29, 0, v29, vcc
	v_cndmask_b32_e32 v28, 0, v28, vcc
	s_andn2_saveexec_b64 s[6:7], s[6:7]
	s_cbranch_execnz .LBB0_765

; __device__ __forceinline__ void st16f(float* p, f32x4 v) { st16(p, __builtin_bit_cast(u32x4, v)); }
; __device__ __forceinline__ void st8bf(bf16_t* p, f32x4 a, f32x4 b) { u32x4 w; w.x = pk2(a[0], a[1]); w.y = pk2(a[2], a[3]); w.z = pk2(b[0], b[1]); w.w = pk2(b[2], b[3]); st16(p, w); }
;     __device__ __forceinline__ void st(int pn, int row, int c, f32x4 v0, f32x4 v1) const {
;     ...
;         else if (pn == 10) { float* o = nullptr;
;             if (!smp) { if (t >= SEQ - 512) o = out + O_WIN + ((size_t)b * 512 + (t - (SEQ - 512))) * 256 + c; } else o = out + O_WINS + ((size_t)b * 512 + 508 + t) * 256 + c;
;             st8bf(KW + (size_t)row * 256 + c, v0, v1); if (o) { st16f(o, v0); st16f(o + 4, v1); } }
.LBB0_721:
	s_andn2_saveexec_b64 s[68:69], s[68:69]
	v_lshl_add_u64 v[34:35], v[214:215], 0, v[30:31]
	s_or_b64 exec, exec, s[68:69]
	v_cvt_pk_bf16_f32 v36, v8, v9
	v_cvt_pk_bf16_f32 v37, v10, v11
	v_cvt_pk_bf16_f32 v38, v4, v5
	v_bfe_u32 v39, v6, 16, 1
	v_add3_u32 v39, v6, v39, s81
	v_bfe_u32 v42, v7, 16, 1
	v_lshrrev_b32_e32 v39, 16, v39
	v_add3_u32 v42, v7, v42, s81
	v_lshl_add_u64 v[40:41], v[208:209], 0, v[28:29]
	v_and_or_b32 v39, v42, s25, v39
	v_cmp_ne_u64_e32 vcc, 0, v[34:35]
	global_store_dwordx4 v[40:41], v[36:39], off
	s_and_saveexec_b64 s[68:69], vcc
	s_cbranch_execz .LBB0_725
	global_store_dwordx4 v[34:35], v[8:11], off
	global_store_dwordx4 v[34:35], v[4:7], off offset:16

; __device__ __forceinline__ void st16f(float* p, f32x4 v) { st16(p, __builtin_bit_cast(u32x4, v)); }
; __device__ __forceinline__ void st8bf(bf16_t* p, f32x4 a, f32x4 b) { u32x4 w; w.x = pk2(a[0], a[1]); w.y = pk2(a[2], a[3]); w.z = pk2(b[0], b[1]); w.w = pk2(b[2], b[3]); st16(p, w); }
;     __device__ __forceinline__ void st(int pn, int row, int c, f32x4 v0, f32x4 v1) const {
;     ...
;         else if (pn == 8) { float* o = (smp ? out + O_KCS + (size_t)(row - MP) * 256 : out + O_KC + (size_t)row * 256) + c; st16f(o, v0); st16f(o + 4, v1); }
;         else if (pn == 9) { float* o = (smp ? out + O_KSS + (size_t)(row - MP) * 256 : out + O_KSEL + (size_t)row * 256) + c; st16f(o, v0); st16f(o + 4, v1); st8bf(KS + (size_t)row * 256 + c, v0, v1); }
.LBB0_727:
	s_andn2_b64 vcc, exec, s[68:69]
	s_cbranch_vccnz .LBB0_729
	v_lshl_add_u64 v[34:35], s[36:37], 0, v[22:23]
	v_lshl_add_u64 v[36:37], s[38:39], 0, v[26:27]
	v_cndmask_b32_e64 v35, v35, v37, s[8:9]
	v_cndmask_b32_e64 v34, v34, v36, s[8:9]
	v_lshlrev_b32_e32 v36, 2, v206
	v_mov_b32_e32 v37, v1
	v_cndmask_b32_e64 v39, v21, 0, s[8:9]
	v_cndmask_b32_e64 v38, v20, v20, s[8:9]
	v_lshl_add_u64 v[34:35], v[34:35], 0, v[36:37]
	global_store_dwordx4 v[34:35], v[8:11], off
	global_store_dwordx4 v[34:35], v[4:7], off offset:16
	v_lshlrev_b64 v[34:35], 9, v[38:39]
	v_lshl_add_u64 v[38:39], v[210:211], 0, v[34:35]
	v_cvt_pk_bf16_f32 v34, v8, v9
	v_cvt_pk_bf16_f32 v35, v10, v11
	v_cvt_pk_bf16_f32 v36, v4, v5
	v_bfe_u32 v37, v6, 16, 1
	v_add3_u32 v37, v6, v37, s81
	v_bfe_u32 v40, v7, 16, 1
	v_lshrrev_b32_e32 v37, 16, v37
	v_add3_u32 v40, v7, v40, s81
	v_and_or_b32 v37, v40, s25, v37
	global_store_dwordx4 v[38:39], v[34:37], off

; __device__ __forceinline__ void st8bf(bf16_t* p, f32x4 a, f32x4 b) { u32x4 w; w.x = pk2(a[0], a[1]); w.y = pk2(a[2], a[3]); w.z = pk2(b[0], b[1]); w.w = pk2(b[2], b[3]); st16(p, w); }
;     __device__ __forceinline__ void st(int pn, int row, int c, f32x4 v0, f32x4 v1) const {
;     ...
;         else if (pn < 8) st8bf(Q + (size_t)row * 512 + (pn - 6) * 256 + c, v0 * C2, v1 * C2);
.LBB0_733:
	s_and_b64 vcc, exec, s[68:69]
	s_cbranch_vccz .LBB0_735
	v_lshl_add_u64 v[34:35], s[28:29], 0, v[22:23]
	s_lshl_b32 s40, s43, 1
	v_lshl_add_u64 v[34:35], v[34:35], 0, s[40:41]
	v_lshlrev_b32_e32 v36, 1, v206
	v_mov_b32_e32 v37, v1
	v_lshl_add_u64 v[38:39], v[34:35], 0, v[36:37]
	v_pk_mul_f32 v[34:35], v[8:9], s[50:51] op_sel_hi:[1,0]
	v_pk_mul_f32 v[36:37], v[10:11], s[50:51] op_sel_hi:[1,0]
	v_cvt_pk_bf16_f32 v34, v34, v35
	v_pk_mul_f32 v[42:43], v[4:5], s[50:51] op_sel_hi:[1,0]
	v_cvt_pk_bf16_f32 v35, v36, v37
	v_pk_mul_f32 v[40:41], v[6:7], s[50:51] op_sel_hi:[1,0]
	v_cvt_pk_bf16_f32 v36, v42, v43
	v_cvt_pk_bf16_f32 v37, v40, v41
	global_store_dwordx4 v[38:39], v[34:37], off offset:-3072

; __device__ __forceinline__ void st16f(float* p, f32x4 v) { st16(p, __builtin_bit_cast(u32x4, v)); }
; __device__ __forceinline__ void st8bf(bf16_t* p, f32x4 a, f32x4 b) { u32x4 w; w.x = pk2(a[0], a[1]); w.y = pk2(a[2], a[3]); w.z = pk2(b[0], b[1]); w.w = pk2(b[2], b[3]); st16(p, w); }
;     __device__ __forceinline__ void st(int pn, int row, int c, f32x4 v0, f32x4 v1) const {
;     ...
;         else if (pn == 10) { float* o = nullptr;
;             if (!smp) { if (t >= SEQ - 512) o = out + O_WIN + ((size_t)b * 512 + (t - (SEQ - 512))) * 256 + c; } else o = out + O_WINS + ((size_t)b * 512 + 508 + t) * 256 + c;
;             st8bf(KW + (size_t)row * 256 + c, v0, v1); if (o) { st16f(o, v0); st16f(o + 4, v1); } }
.LBB0_743:
	s_andn2_saveexec_b64 s[4:5], s[10:11]
	v_lshl_add_u64 v[30:31], v[214:215], 0, v[30:31]
	s_mov_b64 s[10:11], 0x200
	v_lshl_add_u64 v[36:37], v[30:31], 0, s[10:11]
	s_or_b64 exec, exec, s[4:5]
	v_lshl_add_u64 v[32:33], v[216:217], 0, v[28:29]
	v_cvt_pk_bf16_f32 v28, v16, v17
	v_cvt_pk_bf16_f32 v29, v18, v19
	v_cvt_pk_bf16_f32 v30, v12, v13
	v_cvt_pk_bf16_f32 v31, v14, v15
	v_cmp_ne_u64_e32 vcc, 0, v[36:37]
	global_store_dwordx4 v[32:33], v[28:31], off
	s_and_saveexec_b64 s[4:5], vcc
	s_cbranch_execz .LBB0_747
	global_store_dwordx4 v[36:37], v[16:19], off
	global_store_dwordx4 v[36:37], v[12:15], off offset:16

; __device__ __forceinline__ void st16f(float* p, f32x4 v) { st16(p, __builtin_bit_cast(u32x4, v)); }
; __device__ __forceinline__ void st8bf(bf16_t* p, f32x4 a, f32x4 b) { u32x4 w; w.x = pk2(a[0], a[1]); w.y = pk2(a[2], a[3]); w.z = pk2(b[0], b[1]); w.w = pk2(b[2], b[3]); st16(p, w); }
;     __device__ __forceinline__ void st(int pn, int row, int c, f32x4 v0, f32x4 v1) const {
;     ...
;         else if (pn == 8) { float* o = (smp ? out + O_KCS + (size_t)(row - MP) * 256 : out + O_KC + (size_t)row * 256) + c; st16f(o, v0); st16f(o + 4, v1); }
;         else if (pn == 9) { float* o = (smp ? out + O_KSS + (size_t)(row - MP) * 256 : out + O_KSEL + (size_t)row * 256) + c; st16f(o, v0); st16f(o + 4, v1); st8bf(KS + (size_t)row * 256 + c, v0, v1); }
.LBB0_749:
	s_andn2_b64 vcc, exec, s[10:11]
	s_cbranch_vccnz .LBB0_751
	v_lshl_add_u64 v[28:29], s[36:37], 0, v[22:23]
	v_lshl_add_u64 v[26:27], s[38:39], 0, v[26:27]
	v_cndmask_b32_e64 v27, v29, v27, s[8:9]
	v_cndmask_b32_e64 v26, v28, v26, s[8:9]
	v_lshlrev_b32_e32 v28, 2, v206
	v_mov_b32_e32 v29, v1
	v_cndmask_b32_e64 v31, v21, 0, s[8:9]
	v_cndmask_b32_e64 v30, v20, v20, s[8:9]
	v_lshl_add_u64 v[26:27], v[26:27], 0, v[28:29]
	global_store_dwordx4 v[26:27], v[16:19], off offset:512
	global_store_dwordx4 v[26:27], v[12:15], off offset:528
	v_lshlrev_b64 v[26:27], 9, v[30:31]
	v_lshl_add_u64 v[30:31], v[218:219], 0, v[26:27]
	v_cvt_pk_bf16_f32 v26, v16, v17
	v_cvt_pk_bf16_f32 v27, v18, v19
	v_cvt_pk_bf16_f32 v28, v12, v13
	v_cvt_pk_bf16_f32 v29, v14, v15
	global_store_dwordx4 v[30:31], v[26:29], off

; __device__ __forceinline__ void st8bf(bf16_t* p, f32x4 a, f32x4 b) { u32x4 w; w.x = pk2(a[0], a[1]); w.y = pk2(a[2], a[3]); w.z = pk2(b[0], b[1]); w.w = pk2(b[2], b[3]); st16(p, w); }
;     __device__ __forceinline__ void st(int pn, int row, int c, f32x4 v0, f32x4 v1) const {
;     ...
;         else if (pn < 8) st8bf(Q + (size_t)row * 512 + (pn - 6) * 256 + c, v0 * C2, v1 * C2);
.LBB0_755:
	s_and_b64 vcc, exec, s[10:11]
	s_cbranch_vccz .LBB0_757
	v_lshl_add_u64 v[24:25], s[28:29], 0, v[22:23]
	s_lshl_b32 s40, s43, 1
	v_lshl_add_u64 v[24:25], v[24:25], 0, s[40:41]
	v_mov_b32_e32 v35, v1
	v_lshl_add_u64 v[28:29], v[24:25], 0, v[34:35]
	v_pk_mul_f32 v[24:25], v[16:17], s[50:51] op_sel_hi:[1,0]
	v_pk_mul_f32 v[26:27], v[18:19], s[50:51] op_sel_hi:[1,0]
	v_cvt_pk_bf16_f32 v24, v24, v25
	v_pk_mul_f32 v[32:33], v[12:13], s[50:51] op_sel_hi:[1,0]
	v_cvt_pk_bf16_f32 v25, v26, v27
	v_pk_mul_f32 v[30:31], v[14:15], s[50:51] op_sel_hi:[1,0]
	v_cvt_pk_bf16_f32 v26, v32, v33
	v_cvt_pk_bf16_f32 v27, v30, v31
	global_store_dwordx4 v[28:29], v[24:27], off offset:-2816

; __device__ __forceinline__ void st16f(float* p, f32x4 v) { st16(p, __builtin_bit_cast(u32x4, v)); }
; __device__ __forceinline__ void st8bf(bf16_t* p, f32x4 a, f32x4 b) { u32x4 w; w.x = pk2(a[0], a[1]); w.y = pk2(a[2], a[3]); w.z = pk2(b[0], b[1]); w.w = pk2(b[2], b[3]); st16(p, w); }
; __device__ __forceinline__ f32x4 sig4(f32x4 v) { f32x4 r; r[0] = sigmoidf_(v[0]); r[1] = sigmoidf_(v[1]); r[2] = sigmoidf_(v[2]); r[3] = sigmoidf_(v[3]); return r; }
;     __device__ __forceinline__ void st_glu(int pn, int row, int c, f32x4 a0, f32x4 a1, f32x4 g0, f32x4 g1) const {
;         const bool smp = row >= MP; const int b = smp ? (row - MP) >> 2 : row >> 13, t = smp ? (row - MP) & 3 : row & (SEQ - 1);
;         const f32x4 v0 = a0 * sig4(g0), v1 = a1 * sig4(g1);
;         const int col = pn * 128 + c;
;         st8bf(U + (size_t)row * 512 + col, v0, v1);
;         float* o = nullptr;
;         if (!smp) { if (t >= SEQ - 30) o = out + O_CONV + ((size_t)b * 30 + (t - (SEQ - 30))) * 512 + col; }
;         else o = out + O_CONVS + ((size_t)b * 30 + 26 + t) * 512 + col;
;         if (o) { st16f(o, v0); st16f(o + 4, v1); }
.LBB0_758:
	s_and_b64 vcc, exec, s[4:5]
	s_cbranch_vccz .LBB0_771
	v_mul_f32_e32 v0, 0xbfb8aa3b, v16
	v_exp_f32_e32 v0, v0
	v_mul_f32_e32 v16, 0xbfb8aa3b, v17
	v_mul_f32_e32 v17, 0xbfb8aa3b, v18
	v_exp_f32_e32 v18, v16
	v_add_f32_e32 v0, 1.0, v0
	v_exp_f32_e32 v21, v17
	v_rcp_f32_e32 v16, v0
	v_add_f32_e32 v0, 1.0, v18
	v_mul_f32_e32 v18, 0xbfb8aa3b, v19
	v_exp_f32_e32 v19, v18
	v_mul_f32_e32 v12, 0xbfb8aa3b, v12
	v_exp_f32_e32 v12, v12
	v_rcp_f32_e32 v17, v0
	v_add_f32_e32 v0, 1.0, v21
	v_rcp_f32_e32 v18, v0
	v_add_f32_e32 v0, 1.0, v19
	v_rcp_f32_e32 v19, v0
	v_add_f32_e32 v0, 1.0, v12
	v_rcp_f32_e32 v12, v0
	v_mul_f32_e32 v0, 0xbfb8aa3b, v13
	v_mul_f32_e32 v13, 0xbfb8aa3b, v14
	v_exp_f32_e32 v13, v13
	v_mul_f32_e32 v14, 0xbfb8aa3b, v15
	v_exp_f32_e32 v0, v0
	v_exp_f32_e32 v15, v14
	v_add_f32_e32 v13, 1.0, v13
	v_rcp_f32_e32 v14, v13
	v_add_f32_e32 v0, 1.0, v0
	v_add_f32_e32 v13, 1.0, v15
	v_rcp_f32_e32 v15, v13
	v_rcp_f32_e32 v13, v0
	v_ashrrev_i32_e32 v21, 31, v20
	v_pk_mul_f32 v[8:9], v[8:9], v[16:17]
	v_pk_mul_f32 v[10:11], v[10:11], v[18:19]
	v_pk_mul_f32 v[4:5], v[4:5], v[12:13]
	v_lshlrev_b64 v[12:13], 10, v[20:21]
	v_lshl_add_u64 v[12:13], s[26:27], 0, v[12:13]
	v_lshl_add_u64 v[16:17], v[2:3], 1, v[12:13]
	v_cvt_pk_bf16_f32 v12, v8, v9
	v_cvt_pk_bf16_f32 v13, v10, v11
	v_pk_mul_f32 v[6:7], v[6:7], v[14:15]
	v_cvt_pk_bf16_f32 v14, v4, v5
	v_cvt_pk_bf16_f32 v15, v6, v7
	global_store_dwordx4 v[16:17], v[12:15], off
	s_and_saveexec_b64 s[4:5], s[6:7]
	s_xor_b64 s[4:5], exec, s[4:5]
	s_cbranch_execz .LBB0_774
	v_and_b32_e32 v14, 0x1fff, v20
	v_add_u32_e32 v0, 0xffffe01e, v14
	v_lshl_add_u64 v[12:13], v[0:1], 0, s[74:75]
	v_lshlrev_b64 v[12:13], 11, v[12:13]
	v_lshl_add_u64 v[12:13], s[30:31], 0, v[12:13]
	s_movk_i32 s6, 0x1fe1
	v_lshl_add_u64 v[2:3], v[2:3], 2, v[12:13]
	v_cmp_lt_u32_e32 vcc, s6, v14
	s_nop 1
	v_cndmask_b32_e32 v13, 0, v3, vcc
	v_cndmask_b32_e32 v12, 0, v2, vcc
	s_andn2_saveexec_b64 s[4:5], s[4:5]
	s_cbranch_execnz .LBB0_775

; __device__ __forceinline__ void st8bf(bf16_t* p, f32x4 a, f32x4 b) { u32x4 w; w.x = pk2(a[0], a[1]); w.y = pk2(a[2], a[3]); w.z = pk2(b[0], b[1]); w.w = pk2(b[2], b[3]); st16(p, w); }
; __device__ __forceinline__ f32x4 sig4(f32x4 v) { f32x4 r; r[0] = sigmoidf_(v[0]); r[1] = sigmoidf_(v[1]); r[2] = sigmoidf_(v[2]); r[3] = sigmoidf_(v[3]); return r; }
;     __device__ __forceinline__ void st(int pn, int row, int c, f32x4 v0, f32x4 v1) const {
;     ...
;         if (pn < 6 || pn == 11 || pn == 12) st8bf((pn < 6 ? AG : BG) + (size_t)row * 512 + (pn < 6 ? pn - 4 : pn - 11) * 256 + c, v0 * sig4(v0), v1 * sig4(v1));
.LBB0_767:
	s_and_b64 s[68:69], s[66:67], exec
	s_cselect_b32 s69, s51, s79
	s_cselect_b32 s68, s33, s78
	v_mul_f32_e32 v35, 0xbfb8aa3b, v8
	v_lshl_add_u64 v[36:37], s[68:69], 0, v[22:23]
	v_exp_f32_e32 v38, v35
	v_lshl_add_u64 v[36:37], s[64:65], 1, v[36:37]
	v_mov_b32_e32 v35, v1
	v_lshl_add_u64 v[40:41], v[36:37], 0, v[34:35]
	v_mul_f32_e32 v36, 0xbfb8aa3b, v9
	v_exp_f32_e32 v37, v36
	v_mul_f32_e32 v36, 0xbfb8aa3b, v10
	v_add_f32_e32 v35, 1.0, v38
	v_exp_f32_e32 v38, v36
	v_rcp_f32_e32 v36, v35
	v_add_f32_e32 v35, 1.0, v37
	v_rcp_f32_e32 v37, v35
	v_add_f32_e32 v35, 1.0, v38
	v_mul_f32_e32 v38, 0xbfb8aa3b, v11
	v_exp_f32_e32 v39, v38
	v_mul_f32_e32 v38, 0xbfb8aa3b, v4
	v_exp_f32_e32 v42, v38
	v_rcp_f32_e32 v38, v35
	v_add_f32_e32 v35, 1.0, v39
	v_rcp_f32_e32 v39, v35
	v_add_f32_e32 v35, 1.0, v42
	v_mul_f32_e32 v43, 0xbfb8aa3b, v6
	v_rcp_f32_e32 v42, v35
	v_mul_f32_e32 v35, 0xbfb8aa3b, v5
	v_exp_f32_e32 v43, v43
	v_mul_f32_e32 v44, 0xbfb8aa3b, v7
	v_exp_f32_e32 v35, v35
	v_exp_f32_e32 v45, v44
	v_add_f32_e32 v43, 1.0, v43
	v_rcp_f32_e32 v44, v43
	v_add_f32_e32 v35, 1.0, v35
	v_add_f32_e32 v43, 1.0, v45
	v_pk_mul_f32 v[36:37], v[8:9], v[36:37]
	v_rcp_f32_e32 v45, v43
	v_rcp_f32_e32 v43, v35
	v_pk_mul_f32 v[38:39], v[10:11], v[38:39]
	v_cvt_pk_bf16_f32 v36, v36, v37
	v_pk_mul_f32 v[42:43], v[4:5], v[42:43]
	v_cvt_pk_bf16_f32 v37, v38, v39
	v_pk_mul_f32 v[44:45], v[6:7], v[44:45]
	v_cvt_pk_bf16_f32 v38, v42, v43
	v_cvt_pk_bf16_f32 v39, v44, v45
	global_store_dwordx4 v[40:41], v[36:39], off
	s_and_b64 vcc, exec, s[12:13]
	s_mov_b64 s[12:13], -1
	s_cbranch_vccz .LBB0_737

; __device__ __forceinline__ void st8bf(bf16_t* p, f32x4 a, f32x4 b) { u32x4 w; w.x = pk2(a[0], a[1]); w.y = pk2(a[2], a[3]); w.z = pk2(b[0], b[1]); w.w = pk2(b[2], b[3]); st16(p, w); }
; __device__ __forceinline__ f32x4 sig4(f32x4 v) { f32x4 r; r[0] = sigmoidf_(v[0]); r[1] = sigmoidf_(v[1]); r[2] = sigmoidf_(v[2]); r[3] = sigmoidf_(v[3]); return r; }
;     __device__ __forceinline__ void st(int pn, int row, int c, f32x4 v0, f32x4 v1) const {
;     ...
;         if (pn < 6 || pn == 11 || pn == 12) st8bf((pn < 6 ? AG : BG) + (size_t)row * 512 + (pn < 6 ? pn - 4 : pn - 11) * 256 + c, v0 * sig4(v0), v1 * sig4(v1));
.LBB0_769:
	s_and_b64 s[4:5], s[66:67], exec
	s_cselect_b32 s5, s51, s79
	s_cselect_b32 s4, s33, s78
	v_lshl_add_u64 v[22:23], s[4:5], 0, v[22:23]
	v_mul_f32_e32 v0, 0xbfb8aa3b, v16
	v_exp_f32_e32 v0, v0
	v_lshl_add_u64 v[22:23], s[64:65], 1, v[22:23]
	v_mov_b32_e32 v35, v1
	v_mul_f32_e32 v21, 0xbfb8aa3b, v17
	v_lshl_add_u64 v[26:27], v[22:23], 0, v[34:35]
	v_exp_f32_e32 v21, v21
	v_mul_f32_e32 v22, 0xbfb8aa3b, v18
	v_exp_f32_e32 v24, v22
	v_add_f32_e32 v0, 1.0, v0
	v_rcp_f32_e32 v22, v0
	v_add_f32_e32 v0, 1.0, v21
	v_mul_f32_e32 v21, 0xbfb8aa3b, v19
	v_rcp_f32_e32 v23, v0
	v_add_f32_e32 v0, 1.0, v24
	v_exp_f32_e32 v21, v21
	v_mul_f32_e32 v24, 0xbfb8aa3b, v12
	v_exp_f32_e32 v28, v24
	v_rcp_f32_e32 v24, v0
	v_add_f32_e32 v0, 1.0, v21
	v_rcp_f32_e32 v25, v0
	v_add_f32_e32 v0, 1.0, v28
	v_rcp_f32_e32 v28, v0
	v_mul_f32_e32 v0, 0xbfb8aa3b, v13
	v_mul_f32_e32 v21, 0xbfb8aa3b, v14
	v_exp_f32_e32 v0, v0
	v_exp_f32_e32 v21, v21
	v_mul_f32_e32 v29, 0xbfb8aa3b, v15
	v_exp_f32_e32 v29, v29
	v_add_f32_e32 v0, 1.0, v0
	v_add_f32_e32 v21, 1.0, v21
	v_pk_mul_f32 v[22:23], v[16:17], v[22:23]
	v_rcp_f32_e32 v30, v21
	v_add_f32_e32 v21, 1.0, v29
	v_rcp_f32_e32 v29, v0
	v_rcp_f32_e32 v31, v21
	v_pk_mul_f32 v[24:25], v[18:19], v[24:25]
	v_cvt_pk_bf16_f32 v22, v22, v23
	v_pk_mul_f32 v[28:29], v[12:13], v[28:29]
	v_cvt_pk_bf16_f32 v23, v24, v25
	v_pk_mul_f32 v[30:31], v[14:15], v[30:31]
	v_cvt_pk_bf16_f32 v24, v28, v29
	v_bfe_u32 v0, v30, 16, 1
	v_add3_u32 v0, v30, v0, s81
	v_bfe_u32 v21, v31, 16, 1
	v_lshrrev_b32_e32 v0, 16, v0
	v_add3_u32 v21, v31, v21, s81
	v_and_or_b32 v25, v21, s25, v0
	global_store_dwordx4 v[26:27], v[22:25], off offset:256

; #define LAS __attribute__((address_space(3)))
; __device__ __forceinline__ void kc_slice(const Prm& P, Ctx& C, const LAS float* wl, int b, int p) {
;     const int n = 8 * p + C.wave, lane = C.lane;
;     unsigned long long* dst = (unsigned long long*)((bf16_t*)(P.ws + WS_KC) + ((size_t)b * 512 + n) * 256) + lane;
;     unsigned long long o = 0ull;
;     if (n < 511) {
;         const f32x4* src = (const f32x4*)(P.out + O_KC + ((size_t)b * SEQ + 16 * n) * 256) + lane;
;         f32x4 v[32];
; #pragma unroll
;         for (int j = 0; j < 32; ++j) v[j] = src[64 * j];
;         f32x4 s = (f32x4){0.f, 0.f, 0.f, 0.f};
; #pragma unroll
;         for (int j = 0; j < 32; ++j) s += v[j] * *(const LAS f32x4*)(wl + j * 256 + 4 * lane);
.LBB0_831:
	s_or_b64 exec, exec, s[0:1]
	v_readlane_b32 s14, v250, 8
	s_cmpk_lg_i32 s14, 0x100
	v_readlane_b32 s0, v250, 49
	s_cselect_b64 s[10:11], -1, 0
	s_bfe_u32 s90, s77, 0x20001
	v_readlane_b32 s4, v250, 53
	v_readlane_b32 s5, v250, 54
	s_add_u32 s0, s4, 0x1200000
	v_readlane_b32 s2, v250, 51
	v_writelane_b32 v251, s0, 0
	s_addc_u32 s0, s5, 0
	v_readlane_b32 s3, v250, 52
	s_add_u32 s8, s2, 0x8080000
	s_addc_u32 s9, s3, 0
	s_add_u32 s88, s4, 0xc000
	v_readlane_b32 s1, v250, 50
	s_addc_u32 s89, s5, 0
	v_readlane_b32 s6, v250, 55
	v_readlane_b32 s7, v250, 56
	v_writelane_b32 v250, s0, 58
	s_cmpk_eq_i32 s14, 0x100
	s_mov_b64 s[0:1], -1
	s_waitcnt vmcnt(0) lgkmcnt(0)
	s_barrier
	s_cbranch_scc0 .LBB0_838
	s_lshl_b32 s0, s77, 8
	s_and_b32 s0, s0, 0x100
	s_add_i32 s0, s0, s77
	s_and_b32 s0, s0, -8
	s_add_i32 s0, s96, s0
	s_cmpk_gt_i32 s0, 0x1fe
	v_ashrrev_i32_e32 v7, 31, v6
	v_mov_b64_e32 v[0:1], 0
	s_cbranch_scc1 .LBB0_834
	s_lshl_b32 s2, s0, 4
	s_ashr_i32 s3, s2, 31
	s_lshl_b32 s1, s90, 23
	s_add_u32 s1, s8, s1
	s_addc_u32 s4, s9, 0
	s_lshl_b64 s[2:3], s[2:3], 10
	s_add_u32 s2, s1, s2
	s_addc_u32 s3, s4, s3
	v_lshl_add_u64 v[0:1], v[6:7], 4, s[2:3]
	global_load_dwordx4 v[8:11], v[0:1], off
	global_load_dwordx4 v[12:15], v[0:1], off offset:1024
	global_load_dwordx4 v[16:19], v[0:1], off offset:2048
	global_load_dwordx4 v[20:23], v[0:1], off offset:3072
	v_add_co_u32_e32 v2, vcc, 0x1000, v0
	v_lshl_add_u32 v60, v6, 4, 0
	s_nop 0
	v_addc_co_u32_e32 v3, vcc, 0, v1, vcc
	global_load_dwordx4 v[24:27], v[2:3], off
	global_load_dwordx4 v[28:31], v[2:3], off offset:1024
	global_load_dwordx4 v[32:35], v[2:3], off offset:2048
	global_load_dwordx4 v[36:39], v[2:3], off offset:3072
	v_add_co_u32_e32 v52, vcc, 0x2000, v0
	v_add_u32_e32 v156, 0x12000, v60
	s_nop 0
	v_addc_co_u32_e32 v53, vcc, 0, v1, vcc
	global_load_dwordx4 v[40:43], v[52:53], off
	global_load_dwordx4 v[44:47], v[52:53], off offset:1024
	global_load_dwordx4 v[48:51], v[52:53], off offset:2048
	v_add_co_u32_e32 v2, vcc, 0x3000, v0
	global_load_dwordx4 v[52:55], v[52:53], off offset:3072
	s_nop 0
	v_addc_co_u32_e32 v3, vcc, 0, v1, vcc
	global_load_dwordx4 v[56:59], v[2:3], off
	global_load_dwordx4 v[60:63], v[2:3], off offset:1024
	global_load_dwordx4 v[64:67], v[2:3], off offset:2048
	global_load_dwordx4 v[68:71], v[2:3], off offset:3072
	v_add_co_u32_e32 v100, vcc, 0x4000, v0
	s_movk_i32 s1, 0x7fff
	s_nop 0
	v_addc_co_u32_e32 v101, vcc, 0, v1, vcc
	global_load_dwordx4 v[72:75], v[100:101], off
	ds_read_b128 v[76:79], v156
	ds_read_b128 v[80:83], v156 offset:1024
	global_load_dwordx4 v[84:87], v[100:101], off offset:1024
	ds_read_b128 v[88:91], v156 offset:2048
	ds_read_b128 v[92:95], v156 offset:3072
	global_load_dwordx4 v[96:99], v[100:101], off offset:2048
	v_add_co_u32_e32 v2, vcc, 0x5000, v0
	s_mov_b32 s2, 0xffff0000
	s_nop 0
	v_addc_co_u32_e32 v3, vcc, 0, v1, vcc
	global_load_dwordx4 v[104:107], v[2:3], off
	v_add_co_u32_e32 v140, vcc, 0x6000, v0
	global_load_dwordx4 v[100:103], v[100:101], off offset:3072
	ds_read_b128 v[108:111], v156 offset:4096
	ds_read_b128 v[112:115], v156 offset:5120
	global_load_dwordx4 v[116:119], v[2:3], off offset:1024
	global_load_dwordx4 v[120:123], v[2:3], off offset:2048
	global_load_dwordx4 v[124:127], v[2:3], off offset:3072
	v_addc_co_u32_e32 v141, vcc, 0, v1, vcc
	global_load_dwordx4 v[128:131], v[140:141], off
	global_load_dwordx4 v[132:135], v[140:141], off offset:1024
	global_load_dwordx4 v[136:139], v[140:141], off offset:2048
	s_nop 0
	global_load_dwordx4 v[140:143], v[140:141], off offset:3072
	v_add_co_u32_e32 v0, vcc, 0x7000, v0
	s_waitcnt vmcnt(27) lgkmcnt(5)
	v_pk_fma_f32 v[10:11], v[10:11], v[78:79], 0 op_sel_hi:[1,1,0]
	v_addc_co_u32_e32 v1, vcc, 0, v1, vcc
	global_load_dwordx4 v[144:147], v[0:1], off
	global_load_dwordx4 v[148:151], v[0:1], off offset:1024
	global_load_dwordx4 v[152:155], v[0:1], off offset:2048
	s_nop 0
	global_load_dwordx4 v[0:3], v[0:1], off offset:3072
	v_pk_fma_f32 v[8:9], v[8:9], v[76:77], 0 op_sel_hi:[1,1,0]
	s_waitcnt vmcnt(30) lgkmcnt(4)
	v_pk_fma_f32 v[10:11], v[14:15], v[82:83], v[10:11]
	v_pk_fma_f32 v[8:9], v[12:13], v[80:81], v[8:9]
	s_waitcnt vmcnt(29) lgkmcnt(3)
	v_pk_fma_f32 v[10:11], v[18:19], v[90:91], v[10:11]
	v_pk_fma_f32 v[8:9], v[16:17], v[88:89], v[8:9]
	s_waitcnt vmcnt(28) lgkmcnt(2)
	v_pk_fma_f32 v[10:11], v[22:23], v[94:95], v[10:11]
	v_pk_fma_f32 v[12:13], v[20:21], v[92:93], v[8:9]
	s_waitcnt vmcnt(27) lgkmcnt(1)
	v_pk_fma_f32 v[14:15], v[26:27], v[110:111], v[10:11]
	ds_read_b128 v[8:11], v156 offset:6144
	v_pk_fma_f32 v[16:17], v[24:25], v[108:109], v[12:13]
	s_waitcnt vmcnt(26) lgkmcnt(1)
; #define LAS __attribute__((address_space(3)))
; __device__ __forceinline__ unsigned pk2(float lo, float hi) { return f2bf(lo) | (f2bf(hi) << 16); }
; __device__ __forceinline__ void kc_slice(const Prm& P, Ctx& C, const LAS float* wl, int b, int p) {
;     ...
;         for (int j = 0; j < 32; ++j) v[j] = src[64 * j];
;         f32x4 s = (f32x4){0.f, 0.f, 0.f, 0.f};
; #pragma unroll
;         for (int j = 0; j < 32; ++j) s += v[j] * *(const LAS f32x4*)(wl + j * 256 + 4 * lane);
;         o = ((unsigned long long)pk2(s[2], s[3]) << 32) | pk2(s[0], s[1]);
	v_pk_fma_f32 v[18:19], v[30:31], v[114:115], v[14:15]
	ds_read_b128 v[12:15], v156 offset:7168
	v_pk_fma_f32 v[20:21], v[28:29], v[112:113], v[16:17]
	s_waitcnt vmcnt(25) lgkmcnt(1)
	v_pk_fma_f32 v[10:11], v[34:35], v[10:11], v[18:19]
	ds_read_b128 v[16:19], v156 offset:8192
	v_pk_fma_f32 v[20:21], v[32:33], v[8:9], v[20:21]
	s_waitcnt vmcnt(24) lgkmcnt(1)
	v_pk_fma_f32 v[14:15], v[38:39], v[14:15], v[10:11]
	ds_read_b128 v[8:11], v156 offset:9216
	v_pk_fma_f32 v[20:21], v[36:37], v[12:13], v[20:21]
	s_waitcnt vmcnt(23) lgkmcnt(1)
	v_pk_fma_f32 v[18:19], v[42:43], v[18:19], v[14:15]
	ds_read_b128 v[12:15], v156 offset:10240
	v_pk_fma_f32 v[20:21], v[40:41], v[16:17], v[20:21]
	s_waitcnt vmcnt(22) lgkmcnt(1)
	v_pk_fma_f32 v[10:11], v[46:47], v[10:11], v[18:19]
	ds_read_b128 v[16:19], v156 offset:11264
	v_pk_fma_f32 v[20:21], v[44:45], v[8:9], v[20:21]
	s_waitcnt vmcnt(21) lgkmcnt(1)
	v_pk_fma_f32 v[14:15], v[50:51], v[14:15], v[10:11]
	ds_read_b128 v[8:11], v156 offset:12288
	v_pk_fma_f32 v[20:21], v[48:49], v[12:13], v[20:21]
	s_waitcnt vmcnt(20) lgkmcnt(1)
	v_pk_fma_f32 v[18:19], v[54:55], v[18:19], v[14:15]
	ds_read_b128 v[12:15], v156 offset:13312
	v_pk_fma_f32 v[20:21], v[52:53], v[16:17], v[20:21]
	s_waitcnt vmcnt(19) lgkmcnt(1)
	v_pk_fma_f32 v[10:11], v[58:59], v[10:11], v[18:19]
	ds_read_b128 v[16:19], v156 offset:14336
	v_pk_fma_f32 v[20:21], v[56:57], v[8:9], v[20:21]
	s_waitcnt vmcnt(18) lgkmcnt(1)
	v_pk_fma_f32 v[14:15], v[62:63], v[14:15], v[10:11]
	ds_read_b128 v[8:11], v156 offset:15360
	v_pk_fma_f32 v[20:21], v[60:61], v[12:13], v[20:21]
	s_waitcnt vmcnt(17) lgkmcnt(1)
	v_pk_fma_f32 v[18:19], v[66:67], v[18:19], v[14:15]
	ds_read_b128 v[12:15], v156 offset:16384
	v_pk_fma_f32 v[20:21], v[64:65], v[16:17], v[20:21]
	s_waitcnt vmcnt(16) lgkmcnt(1)
	v_pk_fma_f32 v[10:11], v[70:71], v[10:11], v[18:19]
	ds_read_b128 v[16:19], v156 offset:17408
	v_pk_fma_f32 v[20:21], v[68:69], v[8:9], v[20:21]
	s_waitcnt vmcnt(15) lgkmcnt(1)
	v_pk_fma_f32 v[14:15], v[74:75], v[14:15], v[10:11]
	ds_read_b128 v[8:11], v156 offset:18432
	v_pk_fma_f32 v[20:21], v[72:73], v[12:13], v[20:21]
	s_waitcnt vmcnt(14) lgkmcnt(1)
	v_pk_fma_f32 v[18:19], v[86:87], v[18:19], v[14:15]
	ds_read_b128 v[12:15], v156 offset:19456
	v_pk_fma_f32 v[20:21], v[84:85], v[16:17], v[20:21]
	s_waitcnt vmcnt(13) lgkmcnt(1)
	v_pk_fma_f32 v[10:11], v[98:99], v[10:11], v[18:19]
	ds_read_b128 v[16:19], v156 offset:20480
	v_pk_fma_f32 v[20:21], v[96:97], v[8:9], v[20:21]
	s_waitcnt vmcnt(11) lgkmcnt(1)
	v_pk_fma_f32 v[14:15], v[102:103], v[14:15], v[10:11]
	ds_read_b128 v[8:11], v156 offset:21504
	v_pk_fma_f32 v[20:21], v[100:101], v[12:13], v[20:21]
	s_waitcnt lgkmcnt(1)
	v_pk_fma_f32 v[18:19], v[106:107], v[18:19], v[14:15]
	ds_read_b128 v[12:15], v156 offset:22528
	v_pk_fma_f32 v[20:21], v[104:105], v[16:17], v[20:21]
	s_waitcnt vmcnt(10) lgkmcnt(1)
	v_pk_fma_f32 v[10:11], v[118:119], v[10:11], v[18:19]
	ds_read_b128 v[16:19], v156 offset:23552
	v_pk_fma_f32 v[20:21], v[116:117], v[8:9], v[20:21]
	s_waitcnt vmcnt(9) lgkmcnt(1)
	v_pk_fma_f32 v[14:15], v[122:123], v[14:15], v[10:11]
	ds_read_b128 v[8:11], v156 offset:24576
	v_pk_fma_f32 v[20:21], v[120:121], v[12:13], v[20:21]
	s_waitcnt vmcnt(8) lgkmcnt(1)
	v_pk_fma_f32 v[18:19], v[126:127], v[18:19], v[14:15]
	ds_read_b128 v[12:15], v156 offset:25600
	v_pk_fma_f32 v[20:21], v[124:125], v[16:17], v[20:21]
	s_waitcnt vmcnt(7) lgkmcnt(1)
	v_pk_fma_f32 v[10:11], v[130:131], v[10:11], v[18:19]
	ds_read_b128 v[16:19], v156 offset:26624
	v_pk_fma_f32 v[20:21], v[128:129], v[8:9], v[20:21]
	s_waitcnt vmcnt(6) lgkmcnt(1)
	v_pk_fma_f32 v[14:15], v[134:135], v[14:15], v[10:11]
	ds_read_b128 v[8:11], v156 offset:27648
	v_pk_fma_f32 v[20:21], v[132:133], v[12:13], v[20:21]
	s_waitcnt vmcnt(5) lgkmcnt(1)
	v_pk_fma_f32 v[18:19], v[138:139], v[18:19], v[14:15]
	ds_read_b128 v[12:15], v156 offset:28672
	v_pk_fma_f32 v[16:17], v[136:137], v[16:17], v[20:21]
	s_waitcnt vmcnt(4) lgkmcnt(1)
	v_pk_fma_f32 v[18:19], v[142:143], v[10:11], v[18:19]
	v_pk_fma_f32 v[20:21], v[140:141], v[8:9], v[16:17]
	ds_read_b128 v[8:11], v156 offset:29696
	s_waitcnt vmcnt(3) lgkmcnt(1)
	v_pk_fma_f32 v[22:23], v[146:147], v[14:15], v[18:19]
	ds_read_b128 v[14:17], v156 offset:30720
	v_pk_fma_f32 v[12:13], v[144:145], v[12:13], v[20:21]
	ds_read_b128 v[18:21], v156 offset:31744
	s_waitcnt vmcnt(2) lgkmcnt(2)
	v_pk_fma_f32 v[10:11], v[150:151], v[10:11], v[22:23]
	v_pk_fma_f32 v[8:9], v[148:149], v[8:9], v[12:13]
	s_waitcnt vmcnt(1) lgkmcnt(1)
	v_pk_fma_f32 v[10:11], v[154:155], v[16:17], v[10:11]
	v_pk_fma_f32 v[8:9], v[152:153], v[14:15], v[8:9]
	s_waitcnt vmcnt(0) lgkmcnt(0)
	v_pk_fma_f32 v[2:3], v[2:3], v[20:21], v[10:11]
	v_pk_fma_f32 v[8:9], v[0:1], v[18:19], v[8:9]
	v_cvt_pk_bf16_f32 v1, v2, v3
	v_cvt_pk_bf16_f32 v0, v8, v9

; #define LAS __attribute__((address_space(3)))
; __device__ __forceinline__ void kc_slice(const Prm& P, Ctx& C, const LAS float* wl, int b, int p) {
;     const int n = 8 * p + C.wave, lane = C.lane;
;     unsigned long long* dst = (unsigned long long*)((bf16_t*)(P.ws + WS_KC) + ((size_t)b * 512 + n) * 256) + lane;
;     unsigned long long o = 0ull;
;     if (n < 511) {
;         const f32x4* src = (const f32x4*)(P.out + O_KC + ((size_t)b * SEQ + 16 * n) * 256) + lane;
;         f32x4 v[32];
; #pragma unroll
;         for (int j = 0; j < 32; ++j) v[j] = src[64 * j];
;         f32x4 s = (f32x4){0.f, 0.f, 0.f, 0.f};
; #pragma unroll
;         for (int j = 0; j < 32; ++j) s += v[j] * *(const LAS f32x4*)(wl + j * 256 + 4 * lane);
; __device__ __forceinline__ void phase_conv_cmp(const Prm& P, Ctx& C) {
;     ...
;     else for (int t = C.bid; t < NBATCH * 64; t += C.G) kc_slice(P, C, wl, t >> 6, t & 63);
.LBB0_842:
	s_ashr_i32 s6, s36, 6
	s_and_b32 s2, s35, 0x1f8
	s_add_i32 s4, s2, s96
	s_ashr_i32 s7, s6, 31
	s_cmpk_gt_u32 s4, 0x1fe
	v_mov_b64_e32 v[0:1], 0
	s_cbranch_scc1 .LBB0_844
	s_lshl_b32 s37, s4, 14
	s_lshl_b64 s[2:3], s[6:7], 23
	s_add_u32 s2, s8, s2
	s_addc_u32 s3, s9, s3
	s_add_u32 s2, s2, s37
	s_addc_u32 s3, s3, 0
	v_lshl_add_u64 v[0:1], v[6:7], 4, s[2:3]
	v_add_co_u32_e32 v36, vcc, s24, v0
	s_mov_b64 s[2:3], vcc
	v_add_co_u32_e32 v52, vcc, s25, v0
	global_load_dwordx4 v[8:11], v[0:1], off
	global_load_dwordx4 v[12:15], v[0:1], off offset:1024
	global_load_dwordx4 v[16:19], v[0:1], off offset:2048
	global_load_dwordx4 v[20:23], v[0:1], off offset:3072
	v_addc_co_u32_e32 v53, vcc, 0, v1, vcc
	global_load_dwordx4 v[24:27], v[52:53], off offset:-4096
	v_addc_co_u32_e64 v37, vcc, 0, v1, s[2:3]
	global_load_dwordx4 v[28:31], v[36:37], off offset:1024
	global_load_dwordx4 v[32:35], v[36:37], off offset:2048
	s_nop 0
	global_load_dwordx4 v[36:39], v[36:37], off offset:3072
	s_nop 0
	global_load_dwordx4 v[40:43], v[52:53], off
	v_add_co_u32_e32 v68, vcc, s26, v0
	global_load_dwordx4 v[44:47], v[52:53], off offset:1024
	global_load_dwordx4 v[48:51], v[52:53], off offset:2048
	s_nop 0
	global_load_dwordx4 v[52:55], v[52:53], off offset:3072
	s_mov_b64 s[2:3], vcc
	v_add_co_u32_e32 v84, vcc, s27, v0
	s_nop 1
	v_addc_co_u32_e32 v85, vcc, 0, v1, vcc
	global_load_dwordx4 v[56:59], v[84:85], off offset:-4096
	v_addc_co_u32_e64 v69, vcc, 0, v1, s[2:3]
	global_load_dwordx4 v[60:63], v[68:69], off offset:1024
	global_load_dwordx4 v[64:67], v[68:69], off offset:2048
	s_nop 0
	global_load_dwordx4 v[68:71], v[68:69], off offset:3072
	s_nop 0
	global_load_dwordx4 v[72:75], v[84:85], off
	v_add_co_u32_e32 v116, vcc, s28, v0
	global_load_dwordx4 v[76:79], v[84:85], off offset:1024
	global_load_dwordx4 v[80:83], v[84:85], off offset:2048
	s_nop 0
	global_load_dwordx4 v[84:87], v[84:85], off offset:3072
	s_mov_b64 s[2:3], vcc
	v_add_co_u32_e32 v144, vcc, s29, v0
	s_nop 1
	v_addc_co_u32_e32 v145, vcc, 0, v1, vcc
	global_load_dwordx4 v[88:91], v[144:145], off offset:-4096
	v_addc_co_u32_e64 v117, vcc, 0, v1, s[2:3]
	global_load_dwordx4 v[92:95], v[116:117], off offset:1024
	ds_read_b128 v[96:99], v2
	ds_read_b128 v[100:103], v2 offset:1024
	global_load_dwordx4 v[104:107], v[116:117], off offset:2048
	ds_read_b128 v[108:111], v2 offset:2048
	ds_read_b128 v[112:115], v2 offset:3072
	global_load_dwordx4 v[116:119], v[116:117], off offset:3072
	ds_read_b128 v[120:123], v2 offset:4096
	ds_read_b128 v[124:127], v2 offset:5120
	ds_read_b128 v[128:131], v2 offset:6144
	global_load_dwordx4 v[132:135], v[144:145], off
	global_load_dwordx4 v[136:139], v[144:145], off offset:1024
	global_load_dwordx4 v[140:143], v[144:145], off offset:2048
	s_nop 0
	global_load_dwordx4 v[144:147], v[144:145], off offset:3072
	v_add_co_u32_e32 v0, vcc, s30, v0
	s_waitcnt vmcnt(27) lgkmcnt(6)
	v_pk_fma_f32 v[8:9], v[8:9], v[96:97], 0 op_sel_hi:[1,1,0]
	v_addc_co_u32_e32 v1, vcc, 0, v1, vcc
	global_load_dwordx4 v[148:151], v[0:1], off
	global_load_dwordx4 v[152:155], v[0:1], off offset:1024
	global_load_dwordx4 v[156:159], v[0:1], off offset:2048
	global_load_dwordx4 v[160:163], v[0:1], off offset:3072
	s_waitcnt vmcnt(30) lgkmcnt(5)
	v_pk_fma_f32 v[8:9], v[12:13], v[100:101], v[8:9]
	v_pk_fma_f32 v[0:1], v[10:11], v[98:99], 0 op_sel_hi:[1,1,0]
	s_waitcnt vmcnt(29) lgkmcnt(4)
	v_pk_fma_f32 v[8:9], v[16:17], v[108:109], v[8:9]
	v_pk_fma_f32 v[0:1], v[14:15], v[102:103], v[0:1]
	s_waitcnt vmcnt(28) lgkmcnt(3)
	v_pk_fma_f32 v[8:9], v[20:21], v[112:113], v[8:9]
	v_pk_fma_f32 v[0:1], v[18:19], v[110:111], v[0:1]
	s_waitcnt vmcnt(27) lgkmcnt(2)
	v_pk_fma_f32 v[12:13], v[24:25], v[120:121], v[8:9]
	ds_read_b128 v[8:11], v2 offset:7168
	v_pk_fma_f32 v[0:1], v[22:23], v[114:115], v[0:1]
	s_waitcnt vmcnt(26) lgkmcnt(2)
	v_pk_fma_f32 v[16:17], v[28:29], v[124:125], v[12:13]
	v_pk_fma_f32 v[0:1], v[26:27], v[122:123], v[0:1]
	ds_read_b128 v[12:15], v2 offset:8192
	v_pk_fma_f32 v[0:1], v[30:31], v[126:127], v[0:1]
	s_waitcnt vmcnt(25) lgkmcnt(2)
	v_pk_fma_f32 v[20:21], v[32:33], v[128:129], v[16:17]
	ds_read_b128 v[16:19], v2 offset:9216
	v_pk_fma_f32 v[0:1], v[34:35], v[130:131], v[0:1]
	s_waitcnt vmcnt(24) lgkmcnt(2)
; #define LAS __attribute__((address_space(3)))
; __device__ __forceinline__ unsigned pk2(float lo, float hi) { return f2bf(lo) | (f2bf(hi) << 16); }
; __device__ __forceinline__ void kc_slice(const Prm& P, Ctx& C, const LAS float* wl, int b, int p) {
;     ...
;         f32x4 s = (f32x4){0.f, 0.f, 0.f, 0.f};
; #pragma unroll
;         for (int j = 0; j < 32; ++j) s += v[j] * *(const LAS f32x4*)(wl + j * 256 + 4 * lane);
;         o = ((unsigned long long)pk2(s[2], s[3]) << 32) | pk2(s[0], s[1]);
	v_pk_fma_f32 v[20:21], v[36:37], v[8:9], v[20:21]
	v_pk_fma_f32 v[0:1], v[38:39], v[10:11], v[0:1]
	ds_read_b128 v[8:11], v2 offset:10240
	s_waitcnt vmcnt(23) lgkmcnt(2)
	v_pk_fma_f32 v[0:1], v[42:43], v[14:15], v[0:1]
	v_pk_fma_f32 v[20:21], v[40:41], v[12:13], v[20:21]
	ds_read_b128 v[12:15], v2 offset:11264
	s_waitcnt vmcnt(22) lgkmcnt(2)
	v_pk_fma_f32 v[0:1], v[46:47], v[18:19], v[0:1]
	v_pk_fma_f32 v[20:21], v[44:45], v[16:17], v[20:21]
	ds_read_b128 v[16:19], v2 offset:12288
	s_waitcnt vmcnt(21) lgkmcnt(2)
	v_pk_fma_f32 v[0:1], v[50:51], v[10:11], v[0:1]
	v_pk_fma_f32 v[20:21], v[48:49], v[8:9], v[20:21]
	ds_read_b128 v[8:11], v2 offset:13312
	s_waitcnt vmcnt(20) lgkmcnt(2)
	v_pk_fma_f32 v[0:1], v[54:55], v[14:15], v[0:1]
	v_pk_fma_f32 v[20:21], v[52:53], v[12:13], v[20:21]
	ds_read_b128 v[12:15], v2 offset:14336
	s_waitcnt vmcnt(19) lgkmcnt(2)
	v_pk_fma_f32 v[0:1], v[58:59], v[18:19], v[0:1]
	v_pk_fma_f32 v[20:21], v[56:57], v[16:17], v[20:21]
	ds_read_b128 v[16:19], v2 offset:15360
	s_waitcnt vmcnt(18) lgkmcnt(2)
	v_pk_fma_f32 v[0:1], v[62:63], v[10:11], v[0:1]
	v_pk_fma_f32 v[20:21], v[60:61], v[8:9], v[20:21]
	ds_read_b128 v[8:11], v2 offset:16384
	s_waitcnt vmcnt(17) lgkmcnt(2)
	v_pk_fma_f32 v[0:1], v[66:67], v[14:15], v[0:1]
	v_pk_fma_f32 v[20:21], v[64:65], v[12:13], v[20:21]
	ds_read_b128 v[12:15], v2 offset:17408
	s_waitcnt vmcnt(16) lgkmcnt(2)
	v_pk_fma_f32 v[0:1], v[70:71], v[18:19], v[0:1]
	v_pk_fma_f32 v[20:21], v[68:69], v[16:17], v[20:21]
	ds_read_b128 v[16:19], v2 offset:18432
	s_waitcnt vmcnt(15) lgkmcnt(2)
	v_pk_fma_f32 v[0:1], v[74:75], v[10:11], v[0:1]
	v_pk_fma_f32 v[20:21], v[72:73], v[8:9], v[20:21]
	ds_read_b128 v[8:11], v2 offset:19456
	s_waitcnt vmcnt(14) lgkmcnt(2)
	v_pk_fma_f32 v[0:1], v[78:79], v[14:15], v[0:1]
	v_pk_fma_f32 v[20:21], v[76:77], v[12:13], v[20:21]
	ds_read_b128 v[12:15], v2 offset:20480
	s_waitcnt vmcnt(13) lgkmcnt(2)
	v_pk_fma_f32 v[0:1], v[82:83], v[18:19], v[0:1]
	v_pk_fma_f32 v[20:21], v[80:81], v[16:17], v[20:21]
	ds_read_b128 v[16:19], v2 offset:21504
	s_waitcnt vmcnt(12) lgkmcnt(2)
	v_pk_fma_f32 v[0:1], v[86:87], v[10:11], v[0:1]
	v_pk_fma_f32 v[20:21], v[84:85], v[8:9], v[20:21]
	ds_read_b128 v[8:11], v2 offset:22528
	s_waitcnt vmcnt(11) lgkmcnt(2)
	v_pk_fma_f32 v[0:1], v[90:91], v[14:15], v[0:1]
	v_pk_fma_f32 v[20:21], v[88:89], v[12:13], v[20:21]
	ds_read_b128 v[12:15], v2 offset:23552
	s_waitcnt vmcnt(10) lgkmcnt(2)
	v_pk_fma_f32 v[0:1], v[94:95], v[18:19], v[0:1]
	v_pk_fma_f32 v[20:21], v[92:93], v[16:17], v[20:21]
	ds_read_b128 v[16:19], v2 offset:24576
	s_waitcnt vmcnt(9) lgkmcnt(2)
	v_pk_fma_f32 v[0:1], v[106:107], v[10:11], v[0:1]
	v_pk_fma_f32 v[20:21], v[104:105], v[8:9], v[20:21]
	ds_read_b128 v[8:11], v2 offset:25600
	s_waitcnt vmcnt(8) lgkmcnt(2)
	v_pk_fma_f32 v[0:1], v[118:119], v[14:15], v[0:1]
	v_pk_fma_f32 v[20:21], v[116:117], v[12:13], v[20:21]
	ds_read_b128 v[12:15], v2 offset:26624
	s_waitcnt vmcnt(7) lgkmcnt(2)
	v_pk_fma_f32 v[0:1], v[134:135], v[18:19], v[0:1]
	v_pk_fma_f32 v[20:21], v[132:133], v[16:17], v[20:21]
	ds_read_b128 v[16:19], v2 offset:27648
	s_waitcnt vmcnt(6) lgkmcnt(2)
	v_pk_fma_f32 v[0:1], v[138:139], v[10:11], v[0:1]
	v_pk_fma_f32 v[20:21], v[136:137], v[8:9], v[20:21]
	ds_read_b128 v[8:11], v2 offset:28672
	s_waitcnt vmcnt(5) lgkmcnt(2)
	v_pk_fma_f32 v[12:13], v[140:141], v[12:13], v[20:21]
	v_pk_fma_f32 v[0:1], v[142:143], v[14:15], v[0:1]
	s_waitcnt vmcnt(4) lgkmcnt(1)
	v_pk_fma_f32 v[20:21], v[144:145], v[16:17], v[12:13]
	ds_read_b128 v[12:15], v2 offset:29696
	v_pk_fma_f32 v[0:1], v[146:147], v[18:19], v[0:1]
	ds_read_b128 v[16:19], v2 offset:30720
	s_waitcnt vmcnt(3) lgkmcnt(2)
	v_pk_fma_f32 v[0:1], v[150:151], v[10:11], v[0:1]
	v_pk_fma_f32 v[20:21], v[148:149], v[8:9], v[20:21]
	ds_read_b128 v[8:11], v2 offset:31744
	s_waitcnt vmcnt(2) lgkmcnt(2)
	v_pk_fma_f32 v[0:1], v[154:155], v[14:15], v[0:1]
	v_pk_fma_f32 v[12:13], v[152:153], v[12:13], v[20:21]
	s_waitcnt vmcnt(1) lgkmcnt(1)
	v_pk_fma_f32 v[0:1], v[158:159], v[18:19], v[0:1]
	v_pk_fma_f32 v[12:13], v[156:157], v[16:17], v[12:13]
	s_waitcnt vmcnt(0) lgkmcnt(0)
	v_pk_fma_f32 v[0:1], v[162:163], v[10:11], v[0:1]
	v_pk_fma_f32 v[8:9], v[160:161], v[8:9], v[12:13]
	v_cvt_pk_bf16_f32 v1, v0, v1
	v_cvt_pk_bf16_f32 v0, v8, v9

; __device__ __forceinline__ void conv_load32(const Prm& P, int c, int b, int t0, unsigned (&ur)[62]) {
;     const unsigned short* U = (const unsigned short*)(P.ws + WS_U);
;     const int row0 = b * SEQ + t0;
; #pragma unroll
;     for (int i = 0; i < 62; ++i) { const int ti = t0 - 30 + i; ur[i] = ti >= 0 ? (unsigned)U[(size_t)(row0 + i - 30) * 512 + c] : 0u; }
; }
; __device__ __forceinline__ void conv_unit_piped(const Prm& P, Ctx& C, int b, int t0, unsigned (&ur)[62], const float (&w)[31], const float bias, bool has_next, int nb, int nt0) {
;     ...
;     conv_load32(P, c, has_next ? nb : b, has_next ? nt0 : t0, ur);
;     __syncthreads();
.LBB0_984:
	s_ashr_i32 s49, s48, 31
	s_lshl_b64 s[8:9], s[48:49], 10
	v_lshl_add_u64 v[100:101], v[96:97], 0, s[8:9]
	s_add_i32 s8, s46, 31
	s_ashr_i32 s9, s8, 31
	s_lshl_b64 s[8:9], s[8:9], 10
	v_lshl_add_u64 v[132:133], v[96:97], 0, s[8:9]
	s_add_i32 s8, s46, 32
	s_ashr_i32 s9, s8, 31
	s_lshl_b64 s[8:9], s[8:9], 10
	global_load_ushort v100, v[100:101], off
	s_and_b64 vcc, exec, s[6:7]
	global_load_ushort v101, v[132:133], off
	v_lshl_add_u64 v[132:133], v[96:97], 0, s[8:9]
	s_add_i32 s8, s46, 33
	s_ashr_i32 s9, s8, 31
	s_lshl_b64 s[8:9], s[8:9], 10
	v_lshl_add_u64 v[134:135], v[96:97], 0, s[8:9]
	s_add_i32 s8, s46, 34
	s_ashr_i32 s9, s8, 31
	s_lshl_b64 s[8:9], s[8:9], 10
	global_load_ushort v132, v[132:133], off
	s_nop 0
	global_load_ushort v133, v[134:135], off
	v_lshl_add_u64 v[134:135], v[96:97], 0, s[8:9]
	s_add_i32 s8, s46, 35
	s_ashr_i32 s9, s8, 31
	s_lshl_b64 s[8:9], s[8:9], 10
	v_lshl_add_u64 v[136:137], v[96:97], 0, s[8:9]
	s_add_i32 s8, s46, 36
	s_ashr_i32 s9, s8, 31
	s_lshl_b64 s[8:9], s[8:9], 10
	global_load_ushort v134, v[134:135], off
	s_nop 0
	global_load_ushort v135, v[136:137], off
	v_lshl_add_u64 v[136:137], v[96:97], 0, s[8:9]
	s_add_i32 s8, s46, 37
	s_ashr_i32 s9, s8, 31
	s_lshl_b64 s[8:9], s[8:9], 10
	v_lshl_add_u64 v[138:139], v[96:97], 0, s[8:9]
	s_add_i32 s8, s46, 38
	s_ashr_i32 s9, s8, 31
	s_lshl_b64 s[8:9], s[8:9], 10
	global_load_ushort v136, v[136:137], off
	s_nop 0
	global_load_ushort v137, v[138:139], off
	v_lshl_add_u64 v[138:139], v[96:97], 0, s[8:9]
	s_add_i32 s8, s46, 39
	s_ashr_i32 s9, s8, 31
	s_lshl_b64 s[8:9], s[8:9], 10
	v_lshl_add_u64 v[140:141], v[96:97], 0, s[8:9]
	s_add_i32 s8, s46, 40
	s_ashr_i32 s9, s8, 31
	s_lshl_b64 s[8:9], s[8:9], 10
	global_load_ushort v138, v[138:139], off
	s_nop 0
	global_load_ushort v139, v[140:141], off
	v_lshl_add_u64 v[140:141], v[96:97], 0, s[8:9]
	s_add_i32 s8, s46, 41
	s_ashr_i32 s9, s8, 31
	s_lshl_b64 s[8:9], s[8:9], 10
	v_lshl_add_u64 v[142:143], v[96:97], 0, s[8:9]
	s_add_i32 s8, s46, 42
	s_ashr_i32 s9, s8, 31
	s_lshl_b64 s[8:9], s[8:9], 10
	global_load_ushort v140, v[140:141], off
	s_nop 0
	global_load_ushort v141, v[142:143], off
	v_lshl_add_u64 v[142:143], v[96:97], 0, s[8:9]
	s_add_i32 s8, s46, 43
	s_ashr_i32 s9, s8, 31
	s_lshl_b64 s[8:9], s[8:9], 10
	v_lshl_add_u64 v[144:145], v[96:97], 0, s[8:9]
	s_add_i32 s8, s46, 44
	s_ashr_i32 s9, s8, 31
	s_lshl_b64 s[8:9], s[8:9], 10
	global_load_ushort v142, v[142:143], off
	s_nop 0
	global_load_ushort v143, v[144:145], off
	v_lshl_add_u64 v[144:145], v[96:97], 0, s[8:9]
	s_add_i32 s8, s46, 45
	s_ashr_i32 s9, s8, 31
	s_lshl_b64 s[8:9], s[8:9], 10
	v_lshl_add_u64 v[146:147], v[96:97], 0, s[8:9]
	s_add_i32 s8, s46, 46
	s_ashr_i32 s9, s8, 31
	s_lshl_b64 s[8:9], s[8:9], 10
	global_load_ushort v144, v[144:145], off
	s_nop 0
	global_load_ushort v145, v[146:147], off
	v_lshl_add_u64 v[146:147], v[96:97], 0, s[8:9]
	s_add_i32 s8, s46, 47
	s_ashr_i32 s9, s8, 31
	s_lshl_b64 s[8:9], s[8:9], 10
	v_lshl_add_u64 v[148:149], v[96:97], 0, s[8:9]
	s_add_i32 s8, s46, 48
	s_ashr_i32 s9, s8, 31
	s_lshl_b64 s[8:9], s[8:9], 10
	global_load_ushort v146, v[146:147], off
	s_nop 0
	global_load_ushort v147, v[148:149], off
	v_lshl_add_u64 v[148:149], v[96:97], 0, s[8:9]
	s_add_i32 s8, s46, 49
	s_ashr_i32 s9, s8, 31
	s_lshl_b64 s[8:9], s[8:9], 10
	v_lshl_add_u64 v[150:151], v[96:97], 0, s[8:9]
	s_add_i32 s8, s46, 50
	s_ashr_i32 s9, s8, 31
	s_lshl_b64 s[8:9], s[8:9], 10
	global_load_ushort v148, v[148:149], off
	s_nop 0
	global_load_ushort v149, v[150:151], off
	v_lshl_add_u64 v[150:151], v[96:97], 0, s[8:9]
	s_add_i32 s8, s46, 51
	s_ashr_i32 s9, s8, 31
	s_lshl_b64 s[8:9], s[8:9], 10
	v_lshl_add_u64 v[152:153], v[96:97], 0, s[8:9]
	s_add_i32 s8, s46, 52
	s_ashr_i32 s9, s8, 31
	s_lshl_b64 s[8:9], s[8:9], 10
	global_load_ushort v150, v[150:151], off
	s_nop 0
	global_load_ushort v151, v[152:153], off
	v_lshl_add_u64 v[152:153], v[96:97], 0, s[8:9]
	s_add_i32 s8, s46, 53
	s_ashr_i32 s9, s8, 31
	s_lshl_b64 s[8:9], s[8:9], 10
	v_lshl_add_u64 v[154:155], v[96:97], 0, s[8:9]
	s_add_i32 s8, s46, 54
	s_ashr_i32 s9, s8, 31
	s_lshl_b64 s[8:9], s[8:9], 10
	global_load_ushort v152, v[152:153], off
	s_nop 0
	global_load_ushort v153, v[154:155], off
	v_lshl_add_u64 v[154:155], v[96:97], 0, s[8:9]
	s_add_i32 s8, s46, 55
	s_ashr_i32 s9, s8, 31
	s_lshl_b64 s[8:9], s[8:9], 10
	v_lshl_add_u64 v[156:157], v[96:97], 0, s[8:9]
	s_add_i32 s8, s46, 56
	s_ashr_i32 s9, s8, 31
	s_lshl_b64 s[8:9], s[8:9], 10
	global_load_ushort v154, v[154:155], off
	s_nop 0
	global_load_ushort v155, v[156:157], off
	v_lshl_add_u64 v[156:157], v[96:97], 0, s[8:9]
	s_add_i32 s8, s46, 57
	s_ashr_i32 s9, s8, 31
	s_lshl_b64 s[8:9], s[8:9], 10
	v_lshl_add_u64 v[158:159], v[96:97], 0, s[8:9]
	s_add_i32 s8, s46, 58
	s_ashr_i32 s9, s8, 31
	s_lshl_b64 s[8:9], s[8:9], 10
	global_load_ushort v156, v[156:157], off
	s_nop 0
	global_load_ushort v157, v[158:159], off
	v_lshl_add_u64 v[158:159], v[96:97], 0, s[8:9]
	s_add_i32 s8, s46, 59
	s_ashr_i32 s9, s8, 31
	s_lshl_b64 s[8:9], s[8:9], 10
	v_lshl_add_u64 v[160:161], v[96:97], 0, s[8:9]
	s_add_i32 s8, s46, 60
	s_ashr_i32 s9, s8, 31
	s_lshl_b64 s[8:9], s[8:9], 10
	global_load_ushort v158, v[158:159], off
	s_nop 0
	global_load_ushort v159, v[160:161], off
	v_lshl_add_u64 v[160:161], v[96:97], 0, s[8:9]
	s_add_i32 s8, s46, 61
	s_ashr_i32 s9, s8, 31
	s_lshl_b64 s[8:9], s[8:9], 10
	v_lshl_add_u64 v[162:163], v[96:97], 0, s[8:9]
	global_load_ushort v160, v[160:161], off
	s_nop 0
	global_load_ushort v161, v[162:163], off
	v_lshl_add_u32 v162, v98, 2, 0
	v_lshl_add_u64 v[98:99], v[98:99], 1, s[30:31]
	s_waitcnt lgkmcnt(0)
	s_barrier
	s_cbranch_vccnz .LBB0_988
; #define LAS __attribute__((address_space(3)))
; __device__ __forceinline__ unsigned pk2(float lo, float hi) { return f2bf(lo) | (f2bf(hi) << 16); }
; __device__ __forceinline__ float siluf_(float x) { return x * sigmoidf_(x); }
; __device__ __forceinline__ void conv_unit_piped(const Prm& P, Ctx& C, int b, int t0, unsigned (&ur)[62], const float (&w)[31], const float bias, bool has_next, int nb, int nt0) {
;     ...
;     for (int rq = 0; rq < NRW; ++rq) {
;         const int i = C.wave + rq * NWAVES;
;         if (i < NT) {
;             const size_t row = (size_t)(row0 + i);
;             f32x4 v0 = *(const LAS f32x4*)(y + i * 512 + c8), v1 = *(const LAS f32x4*)(y + i * 512 + c8 + 4);
;             const float s = ((v0[0] + v0[1]) + (v0[2] + v0[3])) + ((v1[0] + v1[1]) + (v1[2] + v1[3]));
;             const float mean = wave_sum(s) * (1.f / 512.f);
;             v0 = v0 - mean; v1 = v1 - mean;
;             const float q2 = ((v0[0] * v0[0] + v0[1] * v0[1]) + (v0[2] * v0[2] + v0[3] * v0[3])) + ((v1[0] * v1[0] + v1[1] * v1[1]) + (v1[2] * v1[2] + v1[3] * v1[3]));
;             const float rstd = 1.f / sqrtf(wave_sum(q2) * (1.f / 512.f) + LN_EPS);
;             const u32x4 ag = agv[rq];
;             f32x4 z0 = v0 * rstd * g0 + b0, z1 = v1 * rstd * g1 + b1;
;             z0[0] = siluf_(z0[0]) * bflo(ag.x); z0[1] = siluf_(z0[1]) * bfhi(ag.x); z0[2] = siluf_(z0[2]) * bflo(ag.y); z0[3] = siluf_(z0[3]) * bfhi(ag.y);
;             z1[0] = siluf_(z1[0]) * bflo(ag.z); z1[1] = siluf_(z1[1]) * bfhi(ag.z); z1[2] = siluf_(z1[2]) * bflo(ag.w); z1[3] = siluf_(z1[3]) * bfhi(ag.w);
;             u32x4 o; o.x = pk2(z0[0], z0[1]); o.y = pk2(z0[2], z0[3]); o.z = pk2(z1[0], z1[1]); o.w = pk2(z1[2], z1[3]);
;             *(u32x4*)(H2 + row * 1024 + c8) = o;
	v_add_u32_e32 v163, s53, v162
	ds_read_b128 v[164:167], v163
	ds_read_b128 v[168:171], v163 offset:16
	s_waitcnt lgkmcnt(1)
	v_mov_b32_e32 v172, v164
	s_waitcnt lgkmcnt(0)
	v_mov_b32_e32 v173, v168
	v_mov_b32_e32 v174, v165
	v_mov_b32_e32 v175, v169
	v_pk_add_f32 v[172:173], v[172:173], v[174:175]
	v_mov_b32_e32 v174, v166
	v_mov_b32_e32 v175, v170
	v_mov_b32_e32 v176, v167
	v_mov_b32_e32 v177, v171
	v_pk_add_f32 v[174:175], v[174:175], v[176:177]
	s_nop 0
	v_pk_add_f32 v[172:173], v[172:173], v[174:175]
	s_nop 0
	v_add_f32_e32 v163, v172, v173
	v_mov_b32_e32 v172, 0
	s_nop 0
	v_add_f32_dpp v163, v163, v163 row_shr:1 row_mask:0xf bank_mask:0xf bound_ctrl:1
	s_nop 1
	v_add_f32_dpp v163, v163, v163 row_shr:2 row_mask:0xf bank_mask:0xf bound_ctrl:1
	s_nop 1
	v_add_f32_dpp v163, v163, v163 row_shr:4 row_mask:0xf bank_mask:0xf bound_ctrl:1
	s_nop 1
	v_add_f32_dpp v163, v163, v163 row_shr:8 row_mask:0xf bank_mask:0xf bound_ctrl:1
	s_nop 1
	v_mov_b32_dpp v172, v163 row_bcast:15 row_mask:0xa bank_mask:0xf
	v_add_f32_e32 v163, v163, v172
	v_mov_b32_e32 v172, 0
	s_nop 1
	v_mov_b32_dpp v172, v163 row_bcast:31 row_mask:0xc bank_mask:0xf
	v_add_f32_e32 v163, v163, v172
	s_nop 0
	v_readlane_b32 s6, v163, 63
	s_nop 1
	v_fma_f32 v167, s6, v187, v167
	v_fmac_f32_e32 v165, s6, v187
	v_fma_f32 v166, s6, v187, v166
	v_fma_f32 v164, s6, v187, v164
	v_mul_f32_e32 v163, v165, v165
	v_mul_f32_e32 v172, v167, v167
	v_fma_f32 v171, s6, v187, v171
	v_fmac_f32_e32 v169, s6, v187
	v_fmac_f32_e32 v163, v164, v164
	v_fmac_f32_e32 v172, v166, v166
	v_fma_f32 v170, s6, v187, v170
	v_fma_f32 v168, s6, v187, v168
	v_add_f32_e32 v163, v163, v172
	v_mul_f32_e32 v172, v169, v169
	v_mul_f32_e32 v173, v171, v171
	v_fmac_f32_e32 v172, v168, v168
	v_fmac_f32_e32 v173, v170, v170
	v_add_f32_e32 v172, v172, v173
	v_add_f32_e32 v163, v163, v172
	v_mov_b32_e32 v172, 0
	s_nop 0
	v_add_f32_dpp v163, v163, v163 row_shr:1 row_mask:0xf bank_mask:0xf bound_ctrl:1
	s_nop 1
	v_add_f32_dpp v163, v163, v163 row_shr:2 row_mask:0xf bank_mask:0xf bound_ctrl:1
	s_nop 1
	v_add_f32_dpp v163, v163, v163 row_shr:4 row_mask:0xf bank_mask:0xf bound_ctrl:1
	s_nop 1
	v_add_f32_dpp v163, v163, v163 row_shr:8 row_mask:0xf bank_mask:0xf bound_ctrl:1
	s_nop 1
	v_mov_b32_dpp v172, v163 row_bcast:15 row_mask:0xa bank_mask:0xf
	v_add_f32_e32 v163, v163, v172
	v_mov_b32_e32 v172, 0
	s_nop 1
	v_mov_b32_dpp v172, v163 row_bcast:31 row_mask:0xc bank_mask:0xf
	v_add_f32_e32 v163, v163, v172
	s_nop 0
	v_readlane_b32 s6, v163, 63
	s_nop 1
	v_fma_f32 v163, s6, v188, v185
	v_mul_f32_e32 v172, 0x4f800000, v163
	v_cmp_gt_f32_e32 vcc, s63, v163
	s_nop 1
	v_cndmask_b32_e32 v163, v163, v172, vcc
	v_sqrt_f32_e32 v172, v163
	s_nop 0
	v_add_u32_e32 v173, -1, v172
	v_fma_f32 v174, -v173, v172, v163
	v_cmp_ge_f32_e64 s[6:7], 0, v174
	v_add_u32_e32 v174, 1, v172
	s_nop 0
	v_cndmask_b32_e64 v173, v172, v173, s[6:7]
	v_fma_f32 v172, -v174, v172, v163
	v_cmp_lt_f32_e64 s[6:7], 0, v172
	s_nop 1
	v_cndmask_b32_e64 v172, v173, v174, s[6:7]
	v_mul_f32_e32 v173, 0x37800000, v172
	v_cndmask_b32_e32 v172, v172, v173, vcc
	v_cmp_class_f32_e32 vcc, v163, v186
	s_nop 1
	v_cndmask_b32_e32 v163, v172, v163, vcc
	v_div_scale_f32 v172, s[6:7], v163, v163, 1.0
	v_rcp_f32_e32 v173, v172
	s_or_b32 s6, s66, s96
	s_ashr_i32 s7, s6, 31
	s_lshl_b64 s[6:7], s[6:7], 11
	v_fma_f32 v174, -v172, v173, 1.0
	v_fmac_f32_e32 v173, v174, v173
	v_div_scale_f32 v174, vcc, 1.0, v163, 1.0
	v_mul_f32_e32 v175, v174, v173
	v_fma_f32 v176, -v172, v175, v174
	v_fmac_f32_e32 v175, v176, v173
	v_fma_f32 v172, -v172, v175, v174
	v_div_fmas_f32 v172, v172, v173, v175
	v_div_fixup_f32 v172, v172, v163, 1.0
	v_pk_mul_f32 v[164:165], v[164:165], v[172:173] op_sel_hi:[1,0]
	v_pk_mul_f32 v[166:167], v[166:167], v[172:173] op_sel_hi:[1,0]
	s_waitcnt vmcnt(32)
	v_pk_fma_f32 v[164:165], v[8:9], v[164:165], v[12:13]
	v_pk_mul_f32 v[168:169], v[168:169], v[172:173] op_sel_hi:[1,0]
	v_mul_f32_e32 v163, 0xbfb8aa3b, v164
	v_pk_mul_f32 v[170:171], v[170:171], v[172:173] op_sel_hi:[1,0]
	v_exp_f32_e32 v163, v163
	v_mul_f32_e32 v172, 0xbfb8aa3b, v165
	v_exp_f32_e32 v173, v172
	v_pk_fma_f32 v[166:167], v[10:11], v[166:167], v[14:15]
	v_add_f32_e32 v163, 1.0, v163
	v_rcp_f32_e32 v172, v163
	v_add_f32_e32 v163, 1.0, v173
	v_mul_f32_e32 v173, 0xbfb8aa3b, v166
	v_exp_f32_e32 v173, v173
	v_mul_f32_e32 v174, 0xbfb8aa3b, v167
	v_exp_f32_e32 v175, v174
	v_pk_fma_f32 v[168:169], v[0:1], v[168:169], v[4:5]
	v_rcp_f32_e32 v174, v163
	v_add_f32_e32 v163, 1.0, v173
	v_rcp_f32_e32 v173, v163
	v_add_f32_e32 v163, 1.0, v175
	v_mul_f32_e32 v175, 0xbfb8aa3b, v168
	v_exp_f32_e32 v176, v175
	v_mul_f32_e32 v175, 0xbfb8aa3b, v169
	v_exp_f32_e32 v177, v175
	v_pk_fma_f32 v[170:171], v[2:3], v[170:171], v[6:7]
	v_rcp_f32_e32 v175, v163
	v_add_f32_e32 v163, 1.0, v176
	v_rcp_f32_e32 v176, v163
	v_add_f32_e32 v163, 1.0, v177
	v_mul_f32_e32 v177, 0xbfb8aa3b, v170
	v_exp_f32_e32 v177, v177
	v_mul_f32_e32 v178, 0xbfb8aa3b, v171
	v_exp_f32_e32 v179, v178
	v_rcp_f32_e32 v178, v163
	v_add_f32_e32 v163, 1.0, v177
	v_rcp_f32_e32 v177, v163
	v_add_f32_e32 v163, 1.0, v179
	v_rcp_f32_e32 v179, v163
	v_mov_b32_e32 v180, v164
	v_mov_b32_e32 v181, v166
	v_mov_b32_e32 v166, v165
	v_pk_mul_f32 v[172:173], v[180:181], v[172:173]
	v_lshlrev_b32_e32 v181, 16, v29
	v_lshlrev_b32_e32 v180, 16, v28
	v_pk_mul_f32 v[164:165], v[166:167], v[174:175]
	v_and_b32_e32 v29, 0xffff0000, v29
	v_and_b32_e32 v28, 0xffff0000, v28
	v_pk_mul_f32 v[28:29], v[164:165], v[28:29]
	v_mov_b32_e32 v164, v168
	v_mov_b32_e32 v165, v170
	v_pk_mul_f32 v[164:165], v[164:165], v[176:177]
	v_lshlrev_b32_e32 v167, 16, v31
	v_lshlrev_b32_e32 v166, 16, v30
	v_mov_b32_e32 v170, v169
	v_pk_mul_f32 v[164:165], v[164:165], v[166:167]
	v_pk_mul_f32 v[166:167], v[170:171], v[178:179]
	v_and_b32_e32 v31, 0xffff0000, v31
	v_and_b32_e32 v30, 0xffff0000, v30
	v_pk_mul_f32 v[30:31], v[166:167], v[30:31]
	v_pk_mul_f32 v[172:173], v[172:173], v[180:181]
	v_cvt_pk_bf16_f32 v31, v165, v31
	v_cvt_pk_bf16_f32 v30, v164, v30
	v_cvt_pk_bf16_f32 v29, v173, v29
	v_cvt_pk_bf16_f32 v28, v172, v28
	v_lshl_add_u64 v[164:165], v[98:99], 0, s[6:7]
	global_store_dwordx4 v[164:165], v[28:31], off
	s_and_b64 vcc, exec, s[4:5]
	s_cbranch_vccz .LBB0_989

; #define LAS __attribute__((address_space(3)))
; __device__ __forceinline__ unsigned pk2(float lo, float hi) { return f2bf(lo) | (f2bf(hi) << 16); }
; __device__ __forceinline__ float siluf_(float x) { return x * sigmoidf_(x); }
; __device__ __forceinline__ void conv_unit_piped(const Prm& P, Ctx& C, int b, int t0, unsigned (&ur)[62], const float (&w)[31], const float bias, bool has_next, int nb, int nt0) {
;     ...
;     for (int rq = 0; rq < NRW; ++rq) {
;         const int i = C.wave + rq * NWAVES;
;         if (i < NT) {
;             const size_t row = (size_t)(row0 + i);
;             f32x4 v0 = *(const LAS f32x4*)(y + i * 512 + c8), v1 = *(const LAS f32x4*)(y + i * 512 + c8 + 4);
;             const float s = ((v0[0] + v0[1]) + (v0[2] + v0[3])) + ((v1[0] + v1[1]) + (v1[2] + v1[3]));
;             const float mean = wave_sum(s) * (1.f / 512.f);
;             v0 = v0 - mean; v1 = v1 - mean;
;             const float q2 = ((v0[0] * v0[0] + v0[1] * v0[1]) + (v0[2] * v0[2] + v0[3] * v0[3])) + ((v1[0] * v1[0] + v1[1] * v1[1]) + (v1[2] * v1[2] + v1[3] * v1[3]));
;             const float rstd = 1.f / sqrtf(wave_sum(q2) * (1.f / 512.f) + LN_EPS);
;             const u32x4 ag = agv[rq];
;             f32x4 z0 = v0 * rstd * g0 + b0, z1 = v1 * rstd * g1 + b1;
;             z0[0] = siluf_(z0[0]) * bflo(ag.x); z0[1] = siluf_(z0[1]) * bfhi(ag.x); z0[2] = siluf_(z0[2]) * bflo(ag.y); z0[3] = siluf_(z0[3]) * bfhi(ag.y);
;             z1[0] = siluf_(z1[0]) * bflo(ag.z); z1[1] = siluf_(z1[1]) * bfhi(ag.z); z1[2] = siluf_(z1[2]) * bflo(ag.w); z1[3] = siluf_(z1[3]) * bfhi(ag.w);
;             u32x4 o; o.x = pk2(z0[0], z0[1]); o.y = pk2(z0[2], z0[3]); o.z = pk2(z1[0], z1[1]); o.w = pk2(z1[2], z1[3]);
;             *(u32x4*)(H2 + row * 1024 + c8) = o;
.LBB0_987:
	s_waitcnt vmcnt(32)
	v_add_u32_e32 v28, s59, v162
	ds_read_b128 v[24:27], v28
	ds_read_b128 v[28:31], v28 offset:16
	s_waitcnt lgkmcnt(1)
	v_mov_b32_e32 v164, v24
	s_waitcnt lgkmcnt(0)
	v_mov_b32_e32 v165, v28
	v_mov_b32_e32 v166, v25
	v_mov_b32_e32 v167, v29
	v_pk_add_f32 v[164:165], v[164:165], v[166:167]
	v_mov_b32_e32 v166, v26
	v_mov_b32_e32 v167, v30
	v_mov_b32_e32 v168, v27
	v_mov_b32_e32 v169, v31
	v_pk_add_f32 v[166:167], v[166:167], v[168:169]
	s_nop 0
	v_pk_add_f32 v[164:165], v[164:165], v[166:167]
	s_nop 0
	v_add_f32_e32 v163, v164, v165
	v_mov_b32_e32 v164, 0
	s_nop 0
	v_add_f32_dpp v163, v163, v163 row_shr:1 row_mask:0xf bank_mask:0xf bound_ctrl:1
	s_nop 1
	v_add_f32_dpp v163, v163, v163 row_shr:2 row_mask:0xf bank_mask:0xf bound_ctrl:1
	s_nop 1
	v_add_f32_dpp v163, v163, v163 row_shr:4 row_mask:0xf bank_mask:0xf bound_ctrl:1
	s_nop 1
	v_add_f32_dpp v163, v163, v163 row_shr:8 row_mask:0xf bank_mask:0xf bound_ctrl:1
	s_nop 1
	v_mov_b32_dpp v164, v163 row_bcast:15 row_mask:0xa bank_mask:0xf
	v_add_f32_e32 v163, v163, v164
	v_mov_b32_e32 v164, 0
	s_nop 1
	v_mov_b32_dpp v164, v163 row_bcast:31 row_mask:0xc bank_mask:0xf
	v_add_f32_e32 v163, v163, v164
	s_nop 0
	v_readlane_b32 s2, v163, 63
	s_nop 1
	v_fma_f32 v27, s2, v187, v27
	v_fmac_f32_e32 v25, s2, v187
	v_fma_f32 v26, s2, v187, v26
	v_fma_f32 v24, s2, v187, v24
	v_mul_f32_e32 v163, v25, v25
	v_mul_f32_e32 v164, v27, v27
	v_fma_f32 v31, s2, v187, v31
	v_fmac_f32_e32 v29, s2, v187
	v_fmac_f32_e32 v163, v24, v24
	v_fmac_f32_e32 v164, v26, v26
	v_fma_f32 v30, s2, v187, v30
	v_fma_f32 v28, s2, v187, v28
	v_add_f32_e32 v163, v163, v164
	v_mul_f32_e32 v164, v29, v29
	v_mul_f32_e32 v165, v31, v31
	v_fmac_f32_e32 v164, v28, v28
	v_fmac_f32_e32 v165, v30, v30
	v_add_f32_e32 v164, v164, v165
	v_add_f32_e32 v163, v163, v164
	v_mov_b32_e32 v164, 0
	s_nop 0
	v_add_f32_dpp v163, v163, v163 row_shr:1 row_mask:0xf bank_mask:0xf bound_ctrl:1
	s_nop 1
	v_add_f32_dpp v163, v163, v163 row_shr:2 row_mask:0xf bank_mask:0xf bound_ctrl:1
	s_nop 1
	v_add_f32_dpp v163, v163, v163 row_shr:4 row_mask:0xf bank_mask:0xf bound_ctrl:1
	s_nop 1
	v_add_f32_dpp v163, v163, v163 row_shr:8 row_mask:0xf bank_mask:0xf bound_ctrl:1
	s_nop 1
	v_mov_b32_dpp v164, v163 row_bcast:15 row_mask:0xa bank_mask:0xf
	v_add_f32_e32 v163, v163, v164
	v_mov_b32_e32 v164, 0
	s_nop 1
	v_mov_b32_dpp v164, v163 row_bcast:31 row_mask:0xc bank_mask:0xf
	v_add_f32_e32 v163, v163, v164
	s_nop 0
	v_readlane_b32 s2, v163, 63
	s_nop 1
	v_fma_f32 v163, s2, v188, v185
	v_mul_f32_e32 v164, 0x4f800000, v163
	v_cmp_gt_f32_e32 vcc, s63, v163
	s_nop 1
	v_cndmask_b32_e32 v163, v163, v164, vcc
	v_sqrt_f32_e32 v164, v163
	s_nop 0
	v_add_u32_e32 v165, -1, v164
	v_fma_f32 v166, -v165, v164, v163
	v_cmp_ge_f32_e64 s[2:3], 0, v166
	v_add_u32_e32 v166, 1, v164
	s_nop 0
	v_cndmask_b32_e64 v165, v164, v165, s[2:3]
	v_fma_f32 v164, -v166, v164, v163
	v_cmp_lt_f32_e64 s[2:3], 0, v164
	s_nop 1
	v_cndmask_b32_e64 v164, v165, v166, s[2:3]
	v_mul_f32_e32 v165, 0x37800000, v164
	v_cndmask_b32_e32 v164, v164, v165, vcc
	v_cmp_class_f32_e32 vcc, v163, v186
	s_nop 1
	v_cndmask_b32_e32 v163, v164, v163, vcc
	v_div_scale_f32 v164, s[2:3], v163, v163, 1.0
	v_rcp_f32_e32 v165, v164
	s_or_b32 s2, s66, s58
	s_ashr_i32 s3, s2, 31
	s_lshl_b64 s[2:3], s[2:3], 11
	v_fma_f32 v166, -v164, v165, 1.0
	v_fmac_f32_e32 v165, v166, v165
	v_div_scale_f32 v166, vcc, 1.0, v163, 1.0
	v_mul_f32_e32 v167, v166, v165
	v_fma_f32 v168, -v164, v167, v166
	v_fmac_f32_e32 v167, v168, v165
	v_fma_f32 v164, -v164, v167, v166
	v_div_fmas_f32 v164, v164, v165, v167
	v_div_fixup_f32 v164, v164, v163, 1.0
	v_pk_mul_f32 v[24:25], v[24:25], v[164:165] op_sel_hi:[1,0]
	v_pk_mul_f32 v[26:27], v[26:27], v[164:165] op_sel_hi:[1,0]
	v_pk_fma_f32 v[24:25], v[8:9], v[24:25], v[12:13]
	v_pk_mul_f32 v[28:29], v[28:29], v[164:165] op_sel_hi:[1,0]
	v_mul_f32_e32 v163, 0xbfb8aa3b, v24
	v_pk_mul_f32 v[30:31], v[30:31], v[164:165] op_sel_hi:[1,0]
	v_exp_f32_e32 v163, v163
	v_mul_f32_e32 v164, 0xbfb8aa3b, v25
	v_exp_f32_e32 v165, v164
	v_pk_fma_f32 v[26:27], v[10:11], v[26:27], v[14:15]
	v_add_f32_e32 v163, 1.0, v163
	v_rcp_f32_e32 v164, v163
	v_add_f32_e32 v163, 1.0, v165
	v_mul_f32_e32 v165, 0xbfb8aa3b, v26
	v_exp_f32_e32 v165, v165
	v_mul_f32_e32 v166, 0xbfb8aa3b, v27
	v_exp_f32_e32 v167, v166
	v_pk_fma_f32 v[28:29], v[0:1], v[28:29], v[4:5]
	v_rcp_f32_e32 v166, v163
	v_add_f32_e32 v163, 1.0, v165
	v_rcp_f32_e32 v165, v163
	v_add_f32_e32 v163, 1.0, v167
	v_mul_f32_e32 v167, 0xbfb8aa3b, v28
	v_exp_f32_e32 v168, v167
	v_mul_f32_e32 v167, 0xbfb8aa3b, v29
	v_exp_f32_e32 v169, v167
	v_pk_fma_f32 v[30:31], v[2:3], v[30:31], v[6:7]
	v_rcp_f32_e32 v167, v163
	v_add_f32_e32 v163, 1.0, v168
	v_rcp_f32_e32 v168, v163
	v_add_f32_e32 v163, 1.0, v169
	v_mul_f32_e32 v169, 0xbfb8aa3b, v30
	v_exp_f32_e32 v169, v169
	v_mul_f32_e32 v170, 0xbfb8aa3b, v31
	v_exp_f32_e32 v171, v170
	v_rcp_f32_e32 v170, v163
	v_add_f32_e32 v163, 1.0, v169
	v_rcp_f32_e32 v169, v163
	v_add_f32_e32 v163, 1.0, v171
	v_rcp_f32_e32 v171, v163
	v_mov_b32_e32 v172, v24
	v_mov_b32_e32 v173, v26
	v_mov_b32_e32 v26, v25
	v_pk_mul_f32 v[164:165], v[172:173], v[164:165]
	v_lshlrev_b32_e32 v173, 16, v21
	v_lshlrev_b32_e32 v172, 16, v20
	v_pk_mul_f32 v[24:25], v[26:27], v[166:167]
	v_and_b32_e32 v21, 0xffff0000, v21
	v_and_b32_e32 v20, 0xffff0000, v20
	v_pk_mul_f32 v[20:21], v[24:25], v[20:21]
	v_mov_b32_e32 v24, v28
	v_mov_b32_e32 v25, v30
	v_pk_mul_f32 v[24:25], v[24:25], v[168:169]
	v_lshlrev_b32_e32 v27, 16, v23
	v_lshlrev_b32_e32 v26, 16, v22
	v_mov_b32_e32 v30, v29
	v_pk_mul_f32 v[24:25], v[24:25], v[26:27]
	v_pk_mul_f32 v[26:27], v[30:31], v[170:171]
	v_and_b32_e32 v23, 0xffff0000, v23
	v_and_b32_e32 v22, 0xffff0000, v22
	v_pk_mul_f32 v[22:23], v[26:27], v[22:23]
	v_pk_mul_f32 v[164:165], v[164:165], v[172:173]
	v_bfe_u32 v28, v21, 16, 1
	v_bfe_u32 v29, v20, 16, 1
	v_add3_u32 v20, v20, v29, s65
	v_add3_u32 v21, v21, v28, s65
	v_bfe_u32 v26, v164, 16, 1
	v_bfe_u32 v27, v165, 16, 1
	v_add3_u32 v27, v165, v27, s65
	v_add3_u32 v26, v164, v26, s65
	v_lshrrev_b32_e32 v26, 16, v26
	v_lshrrev_b32_e32 v27, 16, v27
	v_cvt_pk_bf16_f32 v23, v25, v23
	v_cvt_pk_bf16_f32 v22, v24, v22
	v_and_or_b32 v21, v21, s64, v27
	v_and_or_b32 v20, v20, s64, v26
	v_lshl_add_u64 v[24:25], v[98:99], 0, s[2:3]
	global_store_dwordx4 v[24:25], v[20:23], off
	s_and_b64 vcc, exec, s[0:1]
	s_cbranch_vccnz .LBB0_913
	s_branch .LBB0_991

; #define LAS __attribute__((address_space(3)))
; __device__ __forceinline__ unsigned pk2(float lo, float hi) { return f2bf(lo) | (f2bf(hi) << 16); }
; __device__ __forceinline__ float siluf_(float x) { return x * sigmoidf_(x); }
; __device__ __forceinline__ void conv_unit_piped(const Prm& P, Ctx& C, int b, int t0, unsigned (&ur)[62], const float (&w)[31], const float bias, bool has_next, int nb, int nt0) {
;     ...
;     for (int rq = 0; rq < NRW; ++rq) {
;         const int i = C.wave + rq * NWAVES;
;         if (i < NT) {
;             const size_t row = (size_t)(row0 + i);
;             f32x4 v0 = *(const LAS f32x4*)(y + i * 512 + c8), v1 = *(const LAS f32x4*)(y + i * 512 + c8 + 4);
;             const float s = ((v0[0] + v0[1]) + (v0[2] + v0[3])) + ((v1[0] + v1[1]) + (v1[2] + v1[3]));
;             const float mean = wave_sum(s) * (1.f / 512.f);
;             v0 = v0 - mean; v1 = v1 - mean;
;             const float q2 = ((v0[0] * v0[0] + v0[1] * v0[1]) + (v0[2] * v0[2] + v0[3] * v0[3])) + ((v1[0] * v1[0] + v1[1] * v1[1]) + (v1[2] * v1[2] + v1[3] * v1[3]));
;             const float rstd = 1.f / sqrtf(wave_sum(q2) * (1.f / 512.f) + LN_EPS);
;             const u32x4 ag = agv[rq];
;             f32x4 z0 = v0 * rstd * g0 + b0, z1 = v1 * rstd * g1 + b1;
;             z0[0] = siluf_(z0[0]) * bflo(ag.x); z0[1] = siluf_(z0[1]) * bfhi(ag.x); z0[2] = siluf_(z0[2]) * bflo(ag.y); z0[3] = siluf_(z0[3]) * bfhi(ag.y);
;             z1[0] = siluf_(z1[0]) * bflo(ag.z); z1[1] = siluf_(z1[1]) * bfhi(ag.z); z1[2] = siluf_(z1[2]) * bflo(ag.w); z1[3] = siluf_(z1[3]) * bfhi(ag.w);
;             u32x4 o; o.x = pk2(z0[0], z0[1]); o.y = pk2(z0[2], z0[3]); o.z = pk2(z1[0], z1[1]); o.w = pk2(z1[2], z1[3]);
;             *(u32x4*)(H2 + row * 1024 + c8) = o;
.LBB0_989:
	v_add_u32_e32 v163, s57, v162
	s_waitcnt vmcnt(32)
	ds_read_b128 v[28:31], v163
	ds_read_b128 v[164:167], v163 offset:16
	s_waitcnt lgkmcnt(1)
	v_mov_b32_e32 v168, v28
	s_waitcnt lgkmcnt(0)
	v_mov_b32_e32 v169, v164
	v_mov_b32_e32 v170, v29
	v_mov_b32_e32 v171, v165
	v_pk_add_f32 v[168:169], v[168:169], v[170:171]
	v_mov_b32_e32 v170, v30
	v_mov_b32_e32 v171, v166
	v_mov_b32_e32 v172, v31
	v_mov_b32_e32 v173, v167
	v_pk_add_f32 v[170:171], v[170:171], v[172:173]
	s_nop 0
	v_pk_add_f32 v[168:169], v[168:169], v[170:171]
	s_nop 0
	v_add_f32_e32 v163, v168, v169
	v_mov_b32_e32 v168, 0
	s_nop 0
	v_add_f32_dpp v163, v163, v163 row_shr:1 row_mask:0xf bank_mask:0xf bound_ctrl:1
	s_nop 1
	v_add_f32_dpp v163, v163, v163 row_shr:2 row_mask:0xf bank_mask:0xf bound_ctrl:1
	s_nop 1
	v_add_f32_dpp v163, v163, v163 row_shr:4 row_mask:0xf bank_mask:0xf bound_ctrl:1
	s_nop 1
	v_add_f32_dpp v163, v163, v163 row_shr:8 row_mask:0xf bank_mask:0xf bound_ctrl:1
	s_nop 1
	v_mov_b32_dpp v168, v163 row_bcast:15 row_mask:0xa bank_mask:0xf
	v_add_f32_e32 v163, v163, v168
	v_mov_b32_e32 v168, 0
	s_nop 1
	v_mov_b32_dpp v168, v163 row_bcast:31 row_mask:0xc bank_mask:0xf
	v_add_f32_e32 v163, v163, v168
	s_nop 0
	v_readlane_b32 s4, v163, 63
	s_nop 1
	v_fma_f32 v31, s4, v187, v31
	v_fmac_f32_e32 v29, s4, v187
	v_fma_f32 v30, s4, v187, v30
	v_fma_f32 v28, s4, v187, v28
	v_mul_f32_e32 v163, v29, v29
	v_mul_f32_e32 v168, v31, v31
	v_fma_f32 v167, s4, v187, v167
	v_fmac_f32_e32 v165, s4, v187
	v_fmac_f32_e32 v163, v28, v28
	v_fmac_f32_e32 v168, v30, v30
	v_fma_f32 v166, s4, v187, v166
	v_fma_f32 v164, s4, v187, v164
	v_add_f32_e32 v163, v163, v168
	v_mul_f32_e32 v168, v165, v165
	v_mul_f32_e32 v169, v167, v167
	v_fmac_f32_e32 v168, v164, v164
	v_fmac_f32_e32 v169, v166, v166
	v_add_f32_e32 v168, v168, v169
	v_add_f32_e32 v163, v163, v168
	v_mov_b32_e32 v168, 0
	s_nop 0
	v_add_f32_dpp v163, v163, v163 row_shr:1 row_mask:0xf bank_mask:0xf bound_ctrl:1
	s_nop 1
	v_add_f32_dpp v163, v163, v163 row_shr:2 row_mask:0xf bank_mask:0xf bound_ctrl:1
	s_nop 1
	v_add_f32_dpp v163, v163, v163 row_shr:4 row_mask:0xf bank_mask:0xf bound_ctrl:1
	s_nop 1
	v_add_f32_dpp v163, v163, v163 row_shr:8 row_mask:0xf bank_mask:0xf bound_ctrl:1
	s_nop 1
	v_mov_b32_dpp v168, v163 row_bcast:15 row_mask:0xa bank_mask:0xf
	v_add_f32_e32 v163, v163, v168
	v_mov_b32_e32 v168, 0
	s_nop 1
	v_mov_b32_dpp v168, v163 row_bcast:31 row_mask:0xc bank_mask:0xf
	v_add_f32_e32 v163, v163, v168
	s_nop 0
	v_readlane_b32 s4, v163, 63
	s_nop 1
	v_fma_f32 v163, s4, v188, v185
	v_mul_f32_e32 v168, 0x4f800000, v163
	v_cmp_gt_f32_e32 vcc, s63, v163
	s_nop 1
	v_cndmask_b32_e32 v163, v163, v168, vcc
	v_sqrt_f32_e32 v168, v163
	s_nop 0
	v_add_u32_e32 v169, -1, v168
	v_fma_f32 v170, -v169, v168, v163
	v_cmp_ge_f32_e64 s[4:5], 0, v170
	v_add_u32_e32 v170, 1, v168
	s_nop 0
	v_cndmask_b32_e64 v169, v168, v169, s[4:5]
	v_fma_f32 v168, -v170, v168, v163
	v_cmp_lt_f32_e64 s[4:5], 0, v168
	s_nop 1
	v_cndmask_b32_e64 v168, v169, v170, s[4:5]
	v_mul_f32_e32 v169, 0x37800000, v168
	v_cndmask_b32_e32 v168, v168, v169, vcc
	v_cmp_class_f32_e32 vcc, v163, v186
	s_nop 1
	v_cndmask_b32_e32 v163, v168, v163, vcc
	v_div_scale_f32 v168, s[4:5], v163, v163, 1.0
	v_rcp_f32_e32 v169, v168
	s_add_i32 s4, s66, s54
	s_ashr_i32 s5, s4, 31
	s_lshl_b64 s[4:5], s[4:5], 11
	v_fma_f32 v170, -v168, v169, 1.0
	v_fmac_f32_e32 v169, v170, v169
	v_div_scale_f32 v170, vcc, 1.0, v163, 1.0
	v_mul_f32_e32 v171, v170, v169
	v_fma_f32 v172, -v168, v171, v170
	v_fmac_f32_e32 v171, v172, v169
	v_fma_f32 v168, -v168, v171, v170
	v_div_fmas_f32 v168, v168, v169, v171
	v_div_fixup_f32 v168, v168, v163, 1.0
	v_pk_mul_f32 v[28:29], v[28:29], v[168:169] op_sel_hi:[1,0]
	v_pk_mul_f32 v[30:31], v[30:31], v[168:169] op_sel_hi:[1,0]
	v_pk_fma_f32 v[28:29], v[8:9], v[28:29], v[12:13]
	v_pk_mul_f32 v[164:165], v[164:165], v[168:169] op_sel_hi:[1,0]
	v_mul_f32_e32 v163, 0xbfb8aa3b, v28
	v_pk_mul_f32 v[166:167], v[166:167], v[168:169] op_sel_hi:[1,0]
	v_exp_f32_e32 v163, v163
	v_mul_f32_e32 v168, 0xbfb8aa3b, v29
	v_exp_f32_e32 v169, v168
	v_pk_fma_f32 v[30:31], v[10:11], v[30:31], v[14:15]
	v_add_f32_e32 v163, 1.0, v163
	v_rcp_f32_e32 v168, v163
	v_add_f32_e32 v163, 1.0, v169
	v_mul_f32_e32 v169, 0xbfb8aa3b, v30
	v_exp_f32_e32 v169, v169
	v_mul_f32_e32 v170, 0xbfb8aa3b, v31
	v_exp_f32_e32 v171, v170
	v_pk_fma_f32 v[164:165], v[0:1], v[164:165], v[4:5]
	v_rcp_f32_e32 v170, v163
	v_add_f32_e32 v163, 1.0, v169
	v_rcp_f32_e32 v169, v163
	v_add_f32_e32 v163, 1.0, v171
	v_mul_f32_e32 v171, 0xbfb8aa3b, v164
	v_exp_f32_e32 v172, v171
	v_mul_f32_e32 v171, 0xbfb8aa3b, v165
	v_exp_f32_e32 v173, v171
	v_pk_fma_f32 v[166:167], v[2:3], v[166:167], v[6:7]
	v_rcp_f32_e32 v171, v163
	v_add_f32_e32 v163, 1.0, v172
	v_rcp_f32_e32 v172, v163
	v_add_f32_e32 v163, 1.0, v173
	v_mul_f32_e32 v173, 0xbfb8aa3b, v166
	v_exp_f32_e32 v173, v173
	v_mul_f32_e32 v174, 0xbfb8aa3b, v167
	v_exp_f32_e32 v175, v174
	v_rcp_f32_e32 v174, v163
	v_add_f32_e32 v163, 1.0, v173
	v_rcp_f32_e32 v173, v163
	v_add_f32_e32 v163, 1.0, v175
	v_rcp_f32_e32 v175, v163
	v_mov_b32_e32 v176, v28
	v_mov_b32_e32 v177, v30
	v_mov_b32_e32 v30, v29
	v_pk_mul_f32 v[168:169], v[176:177], v[168:169]
	v_lshlrev_b32_e32 v177, 16, v25
	v_lshlrev_b32_e32 v176, 16, v24
	v_pk_mul_f32 v[28:29], v[30:31], v[170:171]
	v_and_b32_e32 v25, 0xffff0000, v25
	v_and_b32_e32 v24, 0xffff0000, v24
	v_pk_mul_f32 v[24:25], v[28:29], v[24:25]
	v_mov_b32_e32 v28, v164
	v_mov_b32_e32 v29, v166
	v_pk_mul_f32 v[28:29], v[28:29], v[172:173]
	v_lshlrev_b32_e32 v31, 16, v27
	v_lshlrev_b32_e32 v30, 16, v26
	v_mov_b32_e32 v166, v165
	v_pk_mul_f32 v[28:29], v[28:29], v[30:31]
	v_pk_mul_f32 v[30:31], v[166:167], v[174:175]
	v_and_b32_e32 v27, 0xffff0000, v27
	v_and_b32_e32 v26, 0xffff0000, v26
	v_pk_mul_f32 v[26:27], v[30:31], v[26:27]
	v_pk_mul_f32 v[168:169], v[168:169], v[176:177]
	v_bfe_u32 v30, v27, 16, 1
	v_add3_u32 v27, v27, v30, s65
	v_bfe_u32 v164, v29, 16, 1
	v_add3_u32 v29, v29, v164, s65
	v_lshrrev_b32_e32 v29, 16, v29
	v_and_or_b32 v27, v27, s64, v29
	v_cvt_pk_bf16_f32 v26, v28, v26
	v_cvt_pk_bf16_f32 v25, v169, v25
	v_cvt_pk_bf16_f32 v24, v168, v24
	v_lshl_add_u64 v[28:29], v[98:99], 0, s[4:5]
	global_store_dwordx4 v[28:29], v[24:27], off
	s_and_b64 vcc, exec, s[2:3]
	s_cbranch_vccz .LBB0_987

; #define LAS __attribute__((address_space(3)))
; __device__ __forceinline__ unsigned pk2(float lo, float hi) { return f2bf(lo) | (f2bf(hi) << 16); }
; __device__ __forceinline__ float siluf_(float x) { return x * sigmoidf_(x); }
; __device__ __forceinline__ void conv_unit_piped(const Prm& P, Ctx& C, int b, int t0, unsigned (&ur)[62], const float (&w)[31], const float bias, bool has_next, int nb, int nt0) {
;     ...
;     for (int rq = 0; rq < NRW; ++rq) {
;         const int i = C.wave + rq * NWAVES;
;         if (i < NT) {
;             const size_t row = (size_t)(row0 + i);
;             f32x4 v0 = *(const LAS f32x4*)(y + i * 512 + c8), v1 = *(const LAS f32x4*)(y + i * 512 + c8 + 4);
;             const float s = ((v0[0] + v0[1]) + (v0[2] + v0[3])) + ((v1[0] + v1[1]) + (v1[2] + v1[3]));
;             const float mean = wave_sum(s) * (1.f / 512.f);
;             v0 = v0 - mean; v1 = v1 - mean;
;             const float q2 = ((v0[0] * v0[0] + v0[1] * v0[1]) + (v0[2] * v0[2] + v0[3] * v0[3])) + ((v1[0] * v1[0] + v1[1] * v1[1]) + (v1[2] * v1[2] + v1[3] * v1[3]));
;             const float rstd = 1.f / sqrtf(wave_sum(q2) * (1.f / 512.f) + LN_EPS);
;             const u32x4 ag = agv[rq];
;             f32x4 z0 = v0 * rstd * g0 + b0, z1 = v1 * rstd * g1 + b1;
;             z0[0] = siluf_(z0[0]) * bflo(ag.x); z0[1] = siluf_(z0[1]) * bfhi(ag.x); z0[2] = siluf_(z0[2]) * bflo(ag.y); z0[3] = siluf_(z0[3]) * bfhi(ag.y);
;             z1[0] = siluf_(z1[0]) * bflo(ag.z); z1[1] = siluf_(z1[1]) * bfhi(ag.z); z1[2] = siluf_(z1[2]) * bflo(ag.w); z1[3] = siluf_(z1[3]) * bfhi(ag.w);
;             u32x4 o; o.x = pk2(z0[0], z0[1]); o.y = pk2(z0[2], z0[3]); o.z = pk2(z1[0], z1[1]); o.w = pk2(z1[2], z1[3]);
;             *(u32x4*)(H2 + row * 1024 + c8) = o;
.LBB0_991:
	s_waitcnt vmcnt(32)
	v_add_u32_e32 v24, s61, v162
	ds_read_b128 v[20:23], v24
	ds_read_b128 v[24:27], v24 offset:16
	s_waitcnt lgkmcnt(1)
	v_mov_b32_e32 v28, v20
	s_waitcnt lgkmcnt(0)
	v_mov_b32_e32 v29, v24
	v_mov_b32_e32 v30, v21
	v_mov_b32_e32 v31, v25
	v_pk_add_f32 v[28:29], v[28:29], v[30:31]
	v_mov_b32_e32 v30, v22
	v_mov_b32_e32 v31, v26
	v_mov_b32_e32 v162, v23
	v_mov_b32_e32 v163, v27
	v_pk_add_f32 v[30:31], v[30:31], v[162:163]
	s_nop 0
	v_pk_add_f32 v[28:29], v[28:29], v[30:31]
	s_nop 0
	v_add_f32_e32 v28, v28, v29
	v_mov_b32_e32 v29, 0
	s_nop 0
	v_add_f32_dpp v28, v28, v28 row_shr:1 row_mask:0xf bank_mask:0xf bound_ctrl:1
	s_nop 1
	v_add_f32_dpp v28, v28, v28 row_shr:2 row_mask:0xf bank_mask:0xf bound_ctrl:1
	s_nop 1
	v_add_f32_dpp v28, v28, v28 row_shr:4 row_mask:0xf bank_mask:0xf bound_ctrl:1
	s_nop 1
	v_add_f32_dpp v28, v28, v28 row_shr:8 row_mask:0xf bank_mask:0xf bound_ctrl:1
	s_nop 1
	v_mov_b32_dpp v29, v28 row_bcast:15 row_mask:0xa bank_mask:0xf
	v_add_f32_e32 v28, v28, v29
	v_mov_b32_e32 v29, 0
	s_nop 1
	v_mov_b32_dpp v29, v28 row_bcast:31 row_mask:0xc bank_mask:0xf
	v_add_f32_e32 v28, v28, v29
	s_nop 0
	v_readlane_b32 s0, v28, 63
	s_nop 1
	v_fma_f32 v23, s0, v187, v23
	v_fmac_f32_e32 v21, s0, v187
	v_fma_f32 v22, s0, v187, v22
	v_fma_f32 v20, s0, v187, v20
	v_mul_f32_e32 v28, v21, v21
	v_mul_f32_e32 v29, v23, v23
	v_fma_f32 v27, s0, v187, v27
	v_fmac_f32_e32 v25, s0, v187
	v_fmac_f32_e32 v28, v20, v20
	v_fmac_f32_e32 v29, v22, v22
	v_fma_f32 v26, s0, v187, v26
	v_fma_f32 v24, s0, v187, v24
	v_add_f32_e32 v28, v28, v29
	v_mul_f32_e32 v29, v25, v25
	v_mul_f32_e32 v30, v27, v27
	v_fmac_f32_e32 v29, v24, v24
	v_fmac_f32_e32 v30, v26, v26
	v_add_f32_e32 v29, v29, v30
	v_add_f32_e32 v28, v28, v29
	v_mov_b32_e32 v29, 0
	s_nop 0
	v_add_f32_dpp v28, v28, v28 row_shr:1 row_mask:0xf bank_mask:0xf bound_ctrl:1
	s_nop 1
	v_add_f32_dpp v28, v28, v28 row_shr:2 row_mask:0xf bank_mask:0xf bound_ctrl:1
	s_nop 1
	v_add_f32_dpp v28, v28, v28 row_shr:4 row_mask:0xf bank_mask:0xf bound_ctrl:1
	s_nop 1
	v_add_f32_dpp v28, v28, v28 row_shr:8 row_mask:0xf bank_mask:0xf bound_ctrl:1
	s_nop 1
	v_mov_b32_dpp v29, v28 row_bcast:15 row_mask:0xa bank_mask:0xf
	v_add_f32_e32 v28, v28, v29
	v_mov_b32_e32 v29, 0
	s_nop 1
	v_mov_b32_dpp v29, v28 row_bcast:31 row_mask:0xc bank_mask:0xf
	v_add_f32_e32 v28, v28, v29
	s_nop 0
	v_readlane_b32 s0, v28, 63
	s_nop 1
	v_fma_f32 v28, s0, v188, v185
	v_mul_f32_e32 v29, 0x4f800000, v28
	v_cmp_gt_f32_e32 vcc, s63, v28
	s_nop 1
	v_cndmask_b32_e32 v28, v28, v29, vcc
	v_sqrt_f32_e32 v29, v28
	s_nop 0
	v_add_u32_e32 v30, -1, v29
	v_fma_f32 v31, -v30, v29, v28
	v_cmp_ge_f32_e64 s[0:1], 0, v31
	v_add_u32_e32 v31, 1, v29
	s_nop 0
	v_cndmask_b32_e64 v30, v29, v30, s[0:1]
	v_fma_f32 v29, -v31, v29, v28
	v_cmp_lt_f32_e64 s[0:1], 0, v29
	s_nop 1
	v_cndmask_b32_e64 v29, v30, v31, s[0:1]
	v_mul_f32_e32 v30, 0x37800000, v29
	v_cndmask_b32_e32 v29, v29, v30, vcc
	v_cmp_class_f32_e32 vcc, v28, v186
	s_nop 1
	v_cndmask_b32_e32 v28, v29, v28, vcc
	v_div_scale_f32 v29, s[0:1], v28, v28, 1.0
	v_rcp_f32_e32 v30, v29
	s_or_b32 s0, s66, s60
	s_ashr_i32 s1, s0, 31
	s_lshl_b64 s[0:1], s[0:1], 11
	v_fma_f32 v31, -v29, v30, 1.0
	v_fmac_f32_e32 v30, v31, v30
	v_div_scale_f32 v31, vcc, 1.0, v28, 1.0
	v_mul_f32_e32 v162, v31, v30
	v_fma_f32 v163, -v29, v162, v31
	v_fmac_f32_e32 v162, v163, v30
	v_fma_f32 v29, -v29, v162, v31
	v_div_fmas_f32 v29, v29, v30, v162
	v_div_fixup_f32 v28, v29, v28, 1.0
	v_pk_mul_f32 v[20:21], v[20:21], v[28:29] op_sel_hi:[1,0]
	v_pk_mul_f32 v[22:23], v[22:23], v[28:29] op_sel_hi:[1,0]
	v_pk_fma_f32 v[8:9], v[8:9], v[20:21], v[12:13]
	v_pk_fma_f32 v[10:11], v[10:11], v[22:23], v[14:15]
	v_pk_mul_f32 v[14:15], v[26:27], v[28:29] op_sel_hi:[1,0]
	v_pk_mul_f32 v[12:13], v[24:25], v[28:29] op_sel_hi:[1,0]
	v_pk_fma_f32 v[2:3], v[2:3], v[14:15], v[6:7]
	v_mul_f32_e32 v6, 0xbfb8aa3b, v8
	v_exp_f32_e32 v6, v6
	v_mul_f32_e32 v7, 0xbfb8aa3b, v9
	v_exp_f32_e32 v7, v7
	v_pk_fma_f32 v[0:1], v[0:1], v[12:13], v[4:5]
	v_add_f32_e32 v4, 1.0, v6
	v_mul_f32_e32 v6, 0xbfb8aa3b, v10
	v_add_f32_e32 v5, 1.0, v7
	v_exp_f32_e32 v7, v6
	v_mul_f32_e32 v6, 0xbfb8aa3b, v11
	v_exp_f32_e32 v12, v6
	v_mul_f32_e32 v13, 0xbfb8aa3b, v1
	v_mul_f32_e32 v14, 0xbfb8aa3b, v2
	v_exp_f32_e32 v13, v13
	v_exp_f32_e32 v15, v14
	v_mul_f32_e32 v14, 0xbfb8aa3b, v3
	v_rcp_f32_e32 v6, v5
	v_add_f32_e32 v5, 1.0, v7
	v_add_f32_e32 v7, 1.0, v12
	v_mul_f32_e32 v12, 0xbfb8aa3b, v0
	v_exp_f32_e32 v20, v14
	v_exp_f32_e32 v12, v12
	v_rcp_f32_e32 v7, v7
	v_add_f32_e32 v13, 1.0, v13
	v_rcp_f32_e32 v14, v13
	v_add_f32_e32 v13, 1.0, v15
	v_add_f32_e32 v15, 1.0, v20
	v_add_f32_e32 v12, 1.0, v12
	v_rcp_f32_e32 v15, v15
	v_rcp_f32_e32 v4, v4
	v_rcp_f32_e32 v5, v5
	v_rcp_f32_e32 v12, v12
	v_rcp_f32_e32 v13, v13
	v_mov_b32_e32 v21, v10
	v_mov_b32_e32 v10, v9
	v_mov_b32_e32 v20, v8
	v_pk_mul_f32 v[6:7], v[10:11], v[6:7]
	v_and_b32_e32 v9, 0xffff0000, v17
	v_and_b32_e32 v8, 0xffff0000, v16
	v_pk_mul_f32 v[6:7], v[6:7], v[8:9]
	v_mov_b32_e32 v9, v2
	v_mov_b32_e32 v2, v1
	v_mov_b32_e32 v8, v0
	v_pk_mul_f32 v[0:1], v[2:3], v[14:15]
	v_and_b32_e32 v3, 0xffff0000, v19
	v_and_b32_e32 v2, 0xffff0000, v18
	v_pk_mul_f32 v[4:5], v[20:21], v[4:5]
	v_lshlrev_b32_e32 v21, 16, v17
	v_lshlrev_b32_e32 v20, 16, v16
	v_pk_mul_f32 v[8:9], v[8:9], v[12:13]
	v_lshlrev_b32_e32 v11, 16, v19
	v_lshlrev_b32_e32 v10, 16, v18
	v_pk_mul_f32 v[0:1], v[0:1], v[2:3]
	v_pk_mul_f32 v[4:5], v[4:5], v[20:21]
	v_pk_mul_f32 v[8:9], v[8:9], v[10:11]
	v_cvt_pk_bf16_f32 v3, v9, v1
	v_cvt_pk_bf16_f32 v2, v8, v0
	v_cvt_pk_bf16_f32 v1, v5, v7
	v_cvt_pk_bf16_f32 v0, v4, v6
	v_lshl_add_u64 v[4:5], v[98:99], 0, s[0:1]
	global_store_dwordx4 v[4:5], v[0:3], off
	s_branch .LBB0_913

; template <int NT, bool SMP>
; __device__ __forceinline__ void conv_body(const Prm& P, Ctx& C, int b, int t0) {
;     const int c = C.tid;
;     const bf16_t* U = (const bf16_t*)(P.ws + WS_U);
;     const int row0 = SMP ? MP + 4 * b : b * SEQ + t0;
;     float uu[30 + NT];
; #pragma unroll
;     for (int i = 0; i < 30 + NT; ++i) {
;         if (SMP) uu[i] = i < 30 ? P.state_conv[((size_t)b * 30 + i) * 512 + c] : bf2f(U[(size_t)(row0 + i - 30) * 512 + c]);
;         else { const int ti = t0 - 30 + i; uu[i] = ti >= 0 ? bf2f(U[(size_t)(row0 + i - 30) * 512 + c]) : 0.f; }
;     }
;     float w[31];
; #pragma unroll
;     for (int k = 0; k < 31; ++k) w[k] = P.conv_w[k * 512 + c];
;     const float bias = P.conv_b[c];
.LBB0_995:
	v_add_co_u32_e32 v66, vcc, 0x1000, v64
	s_ashr_i32 s7, s6, 31
	s_nop 0
	v_addc_co_u32_e32 v67, vcc, 0, v65, vcc
	v_add_co_u32_e32 v72, vcc, 0x2000, v64
	s_lshl_b64 s[0:1], s[6:7], 10
	s_nop 0
	v_addc_co_u32_e32 v73, vcc, 0, v65, vcc
	v_add_co_u32_e32 v74, vcc, 0x3000, v64
	s_waitcnt vmcnt(0)
	v_lshl_add_u64 v[94:95], v[0:1], 0, s[0:1]
	v_addc_co_u32_e32 v75, vcc, 0, v65, vcc
	v_add_co_u32_e32 v76, vcc, 0x4000, v64
	s_add_i32 s0, s6, 1
	s_nop 0
	v_addc_co_u32_e32 v77, vcc, 0, v65, vcc
	s_ashr_i32 s1, s0, 31
	global_load_dword v82, v[64:65], off
	global_load_dword v83, v[64:65], off offset:2048
	global_load_dword v70, v[66:67], off
	global_load_dword v71, v[66:67], off offset:2048
	global_load_dword v68, v[72:73], off
	global_load_dword v69, v[72:73], off offset:2048
	s_nop 0
	global_load_dword v66, v[74:75], off
	global_load_dword v67, v[74:75], off offset:2048
	global_load_dword v72, v[76:77], off
	global_load_dword v73, v[76:77], off offset:2048
	v_add_co_u32_e32 v74, vcc, 0x5000, v64
	s_lshl_b64 s[0:1], s[0:1], 10
	s_nop 0
	v_addc_co_u32_e32 v75, vcc, 0, v65, vcc
	v_lshl_add_u64 v[96:97], v[0:1], 0, s[0:1]
	s_add_i32 s0, s6, 2
	v_add_co_u32_e32 v80, vcc, 0x6000, v64
	s_ashr_i32 s1, s0, 31
	s_nop 0
	v_addc_co_u32_e32 v81, vcc, 0, v65, vcc
	s_lshl_b64 s[0:1], s[0:1], 10
	v_add_co_u32_e32 v90, vcc, s16, v64
	v_lshl_add_u64 v[98:99], v[0:1], 0, s[0:1]
	s_add_i32 s0, s6, 3
	v_addc_co_u32_e32 v91, vcc, 0, v65, vcc
	s_ashr_i32 s1, s0, 31
	v_add_co_u32_e32 v92, vcc, 0x8000, v64
	s_lshl_b64 s[0:1], s[0:1], 10
	s_nop 0
	v_addc_co_u32_e32 v93, vcc, 0, v65, vcc
	global_load_dword v78, v[74:75], off
	global_load_dword v79, v[74:75], off offset:2048
	global_load_dword v76, v[80:81], off
	global_load_dword v77, v[80:81], off offset:2048
	s_nop 0
	global_load_dword v74, v[90:91], off
	global_load_dword v75, v[90:91], off offset:2048
	global_load_dword v80, v[92:93], off
	global_load_dword v81, v[92:93], off offset:2048
	v_lshl_add_u64 v[100:101], v[0:1], 0, s[0:1]
	global_load_ushort v89, v[94:95], off
	global_load_ushort v105, v[96:97], off
	global_load_ushort v107, v[98:99], off
	global_load_ushort v109, v[100:101], off
	v_add_co_u32_e32 v90, vcc, 0x9000, v64
	s_waitcnt vmcnt(19)
	v_mov_b32_e32 v175, v70
	v_addc_co_u32_e32 v91, vcc, 0, v65, vcc
	v_add_co_u32_e32 v92, vcc, 0xa000, v64
	s_waitcnt vmcnt(18)
	v_mov_b32_e32 v176, v71
	v_addc_co_u32_e32 v93, vcc, 0, v65, vcc
	v_add_co_u32_e32 v94, vcc, 0xb000, v64
	v_mov_b32_e32 v174, v83
	s_nop 0
	v_addc_co_u32_e32 v95, vcc, 0, v65, vcc
	v_add_co_u32_e32 v96, vcc, 0xc000, v64
	s_waitcnt vmcnt(17)
	v_mov_b32_e32 v177, v68
	v_addc_co_u32_e32 v97, vcc, 0, v65, vcc
	global_load_dword v98, v[90:91], off
	global_load_dword v99, v[90:91], off offset:2048
	s_nop 0
	global_load_dword v90, v[92:93], off
	global_load_dword v91, v[92:93], off offset:2048
	s_nop 0
	global_load_dword v92, v[94:95], off
	global_load_dword v93, v[94:95], off offset:2048
	s_nop 0
	global_load_dword v94, v[96:97], off
	global_load_dword v95, v[96:97], off offset:2048
	v_add_co_u32_e32 v96, vcc, 0xd000, v64
	s_waitcnt vmcnt(24)
	v_mov_b32_e32 v178, v69
	v_addc_co_u32_e32 v97, vcc, 0, v65, vcc
	v_add_co_u32_e32 v100, vcc, 0xe000, v64
	s_waitcnt vmcnt(23)
	v_mov_b32_e32 v179, v66
	v_addc_co_u32_e32 v101, vcc, 0, v65, vcc
	global_load_dword v102, v[96:97], off
	global_load_dword v103, v[96:97], off offset:2048
	s_nop 0
	global_load_dword v96, v[100:101], off
	global_load_dword v97, v[100:101], off offset:2048
	s_nop 0
	global_load_dword v100, v[62:63], off
	global_load_dword v104, v[2:3], off
	global_load_dword v106, v[2:3], off offset:2048
	global_load_dword v108, v[4:5], off
	global_load_dword v110, v[6:7], off
	global_load_dword v112, v[8:9], off
	global_load_dword v114, v[10:11], off
	global_load_dword v116, v[12:13], off
	global_load_dword v118, v[14:15], off
	global_load_dword v122, v[16:17], off
	global_load_dword v124, v[18:19], off
	global_load_dword v126, v[20:21], off
	global_load_dword v128, v[22:23], off
	global_load_dword v130, v[24:25], off
	global_load_dword v132, v[26:27], off
	global_load_dword v134, v[28:29], off
	global_load_dword v136, v[30:31], off
	global_load_dword v138, v[32:33], off
	global_load_dword v140, v[34:35], off
	global_load_dword v142, v[36:37], off
	global_load_dword v144, v[38:39], off
	global_load_dword v146, v[40:41], off
	global_load_dword v148, v[42:43], off
	global_load_dword v150, v[44:45], off
	global_load_dword v152, v[46:47], off
	global_load_dword v154, v[48:49], off
	global_load_dword v156, v[50:51], off
	global_load_dword v158, v[52:53], off
	global_load_dword v160, v[54:55], off
	global_load_dword v162, v[56:57], off
	global_load_dword v164, v[58:59], off
	global_load_dword v166, v[60:61], off
	s_waitcnt vmcnt(58)
	v_mov_b32_e32 v180, v67
	s_waitcnt vmcnt(57)
	v_mov_b32_e32 v181, v72
	s_waitcnt vmcnt(56)
	v_mov_b32_e32 v182, v73
	s_waitcnt vmcnt(55)
	v_mov_b32_e32 v183, v78
	s_waitcnt vmcnt(54)
	v_mov_b32_e32 v184, v79
	s_waitcnt vmcnt(53)
	v_mov_b32_e32 v185, v76
	s_waitcnt vmcnt(52)
	v_mov_b32_e32 v186, v77
	s_waitcnt vmcnt(51)
	v_mov_b32_e32 v187, v74
	s_waitcnt vmcnt(50)
	v_mov_b32_e32 v188, v75
	s_waitcnt vmcnt(49)
	v_mov_b32_e32 v189, v80
	s_waitcnt vmcnt(48)
	v_mov_b32_e32 v190, v81
	s_waitcnt vmcnt(47)
	v_lshlrev_b32_e32 v168, 16, v89
	s_waitcnt vmcnt(46)
	v_lshlrev_b32_e32 v170, 16, v105
	v_mov_b32_e32 v203, v168
	v_mov_b32_e32 v169, v170
	s_waitcnt vmcnt(45)
	v_lshlrev_b32_e32 v171, 16, v107
	s_waitcnt vmcnt(44)
	v_lshlrev_b32_e32 v173, 16, v109
	v_mov_b32_e32 v172, v171
	s_andn2_b64 vcc, exec, s[2:3]
	s_waitcnt vmcnt(35)
	v_mov_b32_e32 v199, v102
	s_waitcnt vmcnt(34)
; template <int NT, bool SMP>
; __device__ __forceinline__ void conv_body(const Prm& P, Ctx& C, int b, int t0) {
;     ...
;     if constexpr ((NT & 1) == 0 && CONV_PK) {
;         constexpr int HB = NT >= 8 ? 8 : NT;
; #pragma unroll
;         for (int h0 = 0; h0 < NT; h0 += HB) {
;             f32x2 ue[(30 + HB) / 2], uo[(30 + HB) / 2 - 1];
; #pragma unroll
;             for (int j = 0; j < (30 + HB) / 2; ++j) ue[j] = (f32x2){uu[h0 + 2 * j], uu[h0 + 2 * j + 1]};
; #pragma unroll
;             for (int j = 0; j < (30 + HB) / 2 - 1; ++j) uo[j] = (f32x2){uu[h0 + 2 * j + 1], uu[h0 + 2 * j + 2]};
; #pragma unroll
;             for (int i = 0; i < HB; i += 2) { f32x2 a = (f32x2){bias, bias};
; #pragma unroll
;                 for (int k = 0; k < 31; ++k) { const f32x2 wk = (f32x2){w[k], w[k]}; a = __builtin_elementwise_fma(wk, ((i + k) & 1) ? uo[(i + k - 1) / 2] : ue[(i + k) / 2], a); }
;                 y[(h0 + i) * 512 + c] = a[0]; y[(h0 + i + 1) * 512 + c] = a[1]; }
;             asm volatile("" ::: "memory");
;         }
;     } else {
; #pragma unroll
;     for (int i = 0; i < NT; ++i) { float a = bias;
; #pragma unroll
;         for (int k = 0; k < 31; ++k) a += w[k] * uu[i + k];
;         y[i * 512 + c] = a; }
;     }
;     __syncthreads();
	v_mov_b32_e32 v200, v103
	s_waitcnt vmcnt(33)
	v_mov_b32_e32 v201, v96
	s_waitcnt vmcnt(32)
	v_mov_b32_e32 v202, v97
	s_waitcnt vmcnt(30)
	v_pk_fma_f32 v[82:83], v[104:105], v[82:83], v[100:101] op_sel_hi:[0,1,0]
	s_waitcnt vmcnt(29)
	v_pk_fma_f32 v[82:83], v[106:107], v[174:175], v[82:83] op_sel_hi:[0,1,1]
	s_waitcnt vmcnt(28)
	v_pk_fma_f32 v[82:83], v[108:109], v[70:71], v[82:83] op_sel_hi:[0,1,1]
	v_pk_fma_f32 v[70:71], v[104:105], v[70:71], v[100:101] op_sel_hi:[0,1,0]
	s_waitcnt vmcnt(27)
	v_pk_fma_f32 v[82:83], v[110:111], v[176:177], v[82:83] op_sel_hi:[0,1,1]
	v_pk_fma_f32 v[70:71], v[106:107], v[176:177], v[70:71] op_sel_hi:[0,1,1]
	s_waitcnt vmcnt(26)
	v_pk_fma_f32 v[82:83], v[112:113], v[68:69], v[82:83] op_sel_hi:[0,1,1]
	v_pk_fma_f32 v[68:69], v[108:109], v[68:69], v[70:71] op_sel_hi:[0,1,1]
	s_waitcnt vmcnt(25)
	v_pk_fma_f32 v[82:83], v[114:115], v[178:179], v[82:83] op_sel_hi:[0,1,1]
	v_pk_fma_f32 v[68:69], v[110:111], v[178:179], v[68:69] op_sel_hi:[0,1,1]
	s_waitcnt vmcnt(24)
	v_pk_fma_f32 v[82:83], v[116:117], v[66:67], v[82:83] op_sel_hi:[0,1,1]
	v_pk_fma_f32 v[66:67], v[112:113], v[66:67], v[68:69] op_sel_hi:[0,1,1]
	v_pk_fma_f32 v[66:67], v[114:115], v[180:181], v[66:67] op_sel_hi:[0,1,1]
	v_pk_fma_f32 v[66:67], v[116:117], v[72:73], v[66:67] op_sel_hi:[0,1,1]
	s_waitcnt vmcnt(23)
	v_pk_fma_f32 v[82:83], v[118:119], v[180:181], v[82:83] op_sel_hi:[0,1,1]
	v_pk_fma_f32 v[66:67], v[118:119], v[182:183], v[66:67] op_sel_hi:[0,1,1]
	s_waitcnt vmcnt(22)
	v_pk_fma_f32 v[82:83], v[122:123], v[72:73], v[82:83] op_sel_hi:[0,1,1]
	v_pk_fma_f32 v[66:67], v[122:123], v[78:79], v[66:67] op_sel_hi:[0,1,1]
	s_waitcnt vmcnt(21)
	v_pk_fma_f32 v[82:83], v[124:125], v[182:183], v[82:83] op_sel_hi:[0,1,1]
	v_pk_fma_f32 v[66:67], v[124:125], v[184:185], v[66:67] op_sel_hi:[0,1,1]
	s_waitcnt vmcnt(20)
	v_pk_fma_f32 v[82:83], v[126:127], v[78:79], v[82:83] op_sel_hi:[0,1,1]
	v_pk_fma_f32 v[66:67], v[126:127], v[76:77], v[66:67] op_sel_hi:[0,1,1]
	s_waitcnt vmcnt(19)
	v_pk_fma_f32 v[82:83], v[128:129], v[184:185], v[82:83] op_sel_hi:[0,1,1]
	v_pk_fma_f32 v[66:67], v[128:129], v[186:187], v[66:67] op_sel_hi:[0,1,1]
	s_waitcnt vmcnt(18)
	v_pk_fma_f32 v[82:83], v[130:131], v[76:77], v[82:83] op_sel_hi:[0,1,1]
	v_pk_fma_f32 v[66:67], v[130:131], v[74:75], v[66:67] op_sel_hi:[0,1,1]
	s_waitcnt vmcnt(17)
	v_pk_fma_f32 v[82:83], v[132:133], v[186:187], v[82:83] op_sel_hi:[0,1,1]
	v_pk_fma_f32 v[66:67], v[132:133], v[188:189], v[66:67] op_sel_hi:[0,1,1]
	v_mov_b32_e32 v191, v98
	s_waitcnt vmcnt(16)
	v_pk_fma_f32 v[82:83], v[134:135], v[74:75], v[82:83] op_sel_hi:[0,1,1]
	v_pk_fma_f32 v[66:67], v[134:135], v[80:81], v[66:67] op_sel_hi:[0,1,1]
	s_waitcnt vmcnt(15)
	v_pk_fma_f32 v[82:83], v[136:137], v[188:189], v[82:83] op_sel_hi:[0,1,1]
	v_pk_fma_f32 v[66:67], v[136:137], v[190:191], v[66:67] op_sel_hi:[0,1,1]
	v_mov_b32_e32 v192, v99
	v_mov_b32_e32 v193, v90
	s_waitcnt vmcnt(14)
	v_pk_fma_f32 v[82:83], v[138:139], v[80:81], v[82:83] op_sel_hi:[0,1,1]
	v_pk_fma_f32 v[66:67], v[138:139], v[98:99], v[66:67] op_sel_hi:[0,1,1]
	s_waitcnt vmcnt(13)
	v_pk_fma_f32 v[82:83], v[140:141], v[190:191], v[82:83] op_sel_hi:[0,1,1]
	v_pk_fma_f32 v[66:67], v[140:141], v[192:193], v[66:67] op_sel_hi:[0,1,1]
	v_mov_b32_e32 v194, v91
	v_mov_b32_e32 v195, v92
	s_waitcnt vmcnt(12)
	v_pk_fma_f32 v[82:83], v[142:143], v[98:99], v[82:83] op_sel_hi:[0,1,1]
	v_pk_fma_f32 v[66:67], v[142:143], v[90:91], v[66:67] op_sel_hi:[0,1,1]
	s_waitcnt vmcnt(11)
	v_pk_fma_f32 v[82:83], v[144:145], v[192:193], v[82:83] op_sel_hi:[0,1,1]
	v_pk_fma_f32 v[66:67], v[144:145], v[194:195], v[66:67] op_sel_hi:[0,1,1]
	v_mov_b32_e32 v196, v93
	v_mov_b32_e32 v197, v94
	s_waitcnt vmcnt(10)
	v_pk_fma_f32 v[82:83], v[146:147], v[90:91], v[82:83] op_sel_hi:[0,1,1]
	v_pk_fma_f32 v[66:67], v[146:147], v[92:93], v[66:67] op_sel_hi:[0,1,1]
	s_waitcnt vmcnt(9)
	v_pk_fma_f32 v[82:83], v[148:149], v[194:195], v[82:83] op_sel_hi:[0,1,1]
	v_pk_fma_f32 v[66:67], v[148:149], v[196:197], v[66:67] op_sel_hi:[0,1,1]
	v_mov_b32_e32 v198, v95
	s_waitcnt vmcnt(8)
	v_pk_fma_f32 v[82:83], v[150:151], v[92:93], v[82:83] op_sel_hi:[0,1,1]
	v_pk_fma_f32 v[66:67], v[150:151], v[94:95], v[66:67] op_sel_hi:[0,1,1]
	s_waitcnt vmcnt(7)
	v_pk_fma_f32 v[82:83], v[152:153], v[196:197], v[82:83] op_sel_hi:[0,1,1]
	v_pk_fma_f32 v[66:67], v[152:153], v[198:199], v[66:67] op_sel_hi:[0,1,1]
	s_waitcnt vmcnt(6)
	v_pk_fma_f32 v[82:83], v[154:155], v[94:95], v[82:83] op_sel_hi:[0,1,1]
	v_pk_fma_f32 v[66:67], v[154:155], v[102:103], v[66:67] op_sel_hi:[0,1,1]
	s_waitcnt vmcnt(5)
	v_pk_fma_f32 v[82:83], v[156:157], v[198:199], v[82:83] op_sel_hi:[0,1,1]
	v_pk_fma_f32 v[66:67], v[156:157], v[200:201], v[66:67] op_sel_hi:[0,1,1]
	s_waitcnt vmcnt(4)
	v_pk_fma_f32 v[82:83], v[158:159], v[102:103], v[82:83] op_sel_hi:[0,1,1]
	v_pk_fma_f32 v[66:67], v[158:159], v[96:97], v[66:67] op_sel_hi:[0,1,1]
	s_waitcnt vmcnt(3)
	v_pk_fma_f32 v[82:83], v[160:161], v[200:201], v[82:83] op_sel_hi:[0,1,1]
	v_pk_fma_f32 v[66:67], v[160:161], v[202:203], v[66:67] op_sel_hi:[0,1,1]
	s_waitcnt vmcnt(2)
	v_pk_fma_f32 v[82:83], v[162:163], v[96:97], v[82:83] op_sel_hi:[0,1,1]
	v_pk_fma_f32 v[66:67], v[162:163], v[168:169], v[66:67] op_sel_hi:[0,1,1]
	s_waitcnt vmcnt(1)
	v_pk_fma_f32 v[82:83], v[164:165], v[202:203], v[82:83] op_sel_hi:[0,1,1]
	v_pk_fma_f32 v[66:67], v[164:165], v[170:171], v[66:67] op_sel_hi:[0,1,1]
	s_waitcnt vmcnt(0)
	v_pk_fma_f32 v[82:83], v[166:167], v[168:169], v[82:83] op_sel_hi:[0,1,1]
	v_pk_fma_f32 v[66:67], v[166:167], v[172:173], v[66:67] op_sel_hi:[0,1,1]
	ds_write2st64_b32 v84, v82, v83 offset1:8
	ds_write2st64_b32 v84, v66, v67 offset0:16 offset1:24
	s_waitcnt lgkmcnt(0)
	s_barrier
; #define LAS __attribute__((address_space(3)))
; template <int NT, bool SMP>
; __device__ __forceinline__ void conv_body(const Prm& P, Ctx& C, int b, int t0) {
;     ...
;     const bf16_t* AG = (const bf16_t*)(P.ws + WS_AG); bf16_t* H2 = (bf16_t*)(P.ws + WS_H2);
;     int l8_; asm volatile("v_mbcnt_lo_u32_b32 %0, -1, 0\n\tv_mbcnt_hi_u32_b32 %0, -1, %0" : "=v"(l8_));
;     const int c8 = 8 * l8_;
;     const f32x4 g0 = *(const f32x4*)(P.conv_ln_g + c8), g1 = *(const f32x4*)(P.conv_ln_g + c8 + 4), b0 = *(const f32x4*)(P.conv_ln_b + c8), b1 = *(const f32x4*)(P.conv_ln_b + c8 + 4);
;     constexpr int NRW = (NT + NWAVES - 1) / NWAVES;
;     u32x4 agv[NRW];
; #pragma unroll
;     for (int rq = 0; rq < NRW; ++rq) { const int i = C.wave + rq * NWAVES; agv[rq] = i < NT ? *(const u32x4*)(AG + (size_t)(row0 + i) * 512 + c8) : (u32x4){0u, 0u, 0u, 0u}; }
; #pragma unroll
;     for (int rq = 0; rq < NRW; ++rq) {
;         const int i = C.wave + rq * NWAVES;
;         if (i < NT) {
;             const size_t row = (size_t)(row0 + i);
;             f32x4 v0 = *(const LAS f32x4*)(y + i * 512 + c8), v1 = *(const LAS f32x4*)(y + i * 512 + c8 + 4);
;             const float s = ((v0[0] + v0[1]) + (v0[2] + v0[3])) + ((v1[0] + v1[1]) + (v1[2] + v1[3]));
;             const float mean = wave_sum(s) * (1.f / 512.f);
;             v0 = v0 - mean; v1 = v1 - mean;
;             const float q2 = ((v0[0] * v0[0] + v0[1] * v0[1]) + (v0[2] * v0[2] + v0[3] * v0[3])) + ((v1[0] * v1[0] + v1[1] * v1[1]) + (v1[2] * v1[2] + v1[3] * v1[3]));
;             const float rstd = 1.f / sqrtf(wave_sum(q2) * (1.f / 512.f) + LN_EPS);
	v_mbcnt_lo_u32_b32 v66, -1, 0
	v_mbcnt_hi_u32_b32 v66, -1, v66
	s_cbranch_vccnz .LBB0_994
	v_readlane_b32 s36, v250, 32
	v_lshlrev_b32_e32 v90, 3, v66
	v_readlane_b32 s44, v250, 40
	v_readlane_b32 s45, v250, 41
	v_ashrrev_i32_e32 v91, 31, v90
	v_readlane_b32 s46, v250, 42
	v_readlane_b32 s47, v250, 43
	s_mov_b64 s[20:21], s[44:45]
	v_lshlrev_b64 v[76:77], 2, v[90:91]
	s_mov_b64 s[22:23], s[46:47]
	v_lshl_add_u64 v[72:73], s[22:23], 0, v[76:77]
	v_lshl_add_u64 v[80:81], s[20:21], 0, v[76:77]
	global_load_dwordx4 v[68:71], v[72:73], off offset:16
	s_nop 0
	global_load_dwordx4 v[72:75], v[72:73], off
	s_nop 0
	global_load_dwordx4 v[76:79], v[80:81], off offset:16
	s_nop 0
	global_load_dwordx4 v[80:83], v[80:81], off
	s_add_i32 s8, s96, s6
	v_lshlrev_b64 v[102:103], 1, v[90:91]
	s_ashr_i32 s9, s8, 31
	v_lshl_add_u32 v66, v66, 5, s26
	v_lshl_add_u64 v[98:99], s[28:29], 0, v[102:103]
	ds_read_b128 v[90:93], v66
	ds_read_b128 v[94:97], v66 offset:16
	s_lshl_b64 s[0:1], s[8:9], 10
	v_lshl_add_u64 v[66:67], v[98:99], 0, s[0:1]
	global_load_dwordx4 v[98:101], v[66:67], off
	s_waitcnt lgkmcnt(1)
	v_mov_b32_e32 v66, v90
	s_waitcnt lgkmcnt(0)
	v_mov_b32_e32 v67, v94
	v_mov_b32_e32 v104, v91
	v_mov_b32_e32 v105, v95
	v_pk_add_f32 v[66:67], v[66:67], v[104:105]
	v_mov_b32_e32 v104, v92
	v_mov_b32_e32 v105, v96
	v_mov_b32_e32 v106, v93
	v_mov_b32_e32 v107, v97
	v_pk_add_f32 v[104:105], v[104:105], v[106:107]
	v_readlane_b32 s37, v250, 33
	v_pk_add_f32 v[66:67], v[66:67], v[104:105]
	v_readlane_b32 s38, v250, 34
	v_add_f32_e32 v66, v66, v67
	v_mov_b32_e32 v67, 0
	v_readlane_b32 s39, v250, 35
	v_add_f32_dpp v66, v66, v66 row_shr:1 row_mask:0xf bank_mask:0xf bound_ctrl:1
	v_readlane_b32 s40, v250, 36
	v_readlane_b32 s41, v250, 37
	v_add_f32_dpp v66, v66, v66 row_shr:2 row_mask:0xf bank_mask:0xf bound_ctrl:1
	v_readlane_b32 s42, v250, 38
	v_readlane_b32 s43, v250, 39
	v_add_f32_dpp v66, v66, v66 row_shr:4 row_mask:0xf bank_mask:0xf bound_ctrl:1
	v_readlane_b32 s48, v250, 44
	v_readlane_b32 s49, v250, 45
	v_add_f32_dpp v66, v66, v66 row_shr:8 row_mask:0xf bank_mask:0xf bound_ctrl:1
	v_readlane_b32 s50, v250, 46
	v_readlane_b32 s51, v250, 47
	v_mov_b32_dpp v67, v66 row_bcast:15 row_mask:0xa bank_mask:0xf
	v_add_f32_e32 v66, v66, v67
	v_mov_b32_e32 v67, 0
	s_nop 1
	v_mov_b32_dpp v67, v66 row_bcast:31 row_mask:0xc bank_mask:0xf
	v_add_f32_e32 v66, v66, v67
	s_nop 0
	v_readlane_b32 s0, v66, 63
	s_nop 1
	v_fma_f32 v67, s0, v87, v93
	v_fmac_f32_e32 v91, s0, v87
	v_fma_f32 v66, s0, v87, v92
	v_fma_f32 v90, s0, v87, v90
	v_fma_f32 v92, s0, v87, v96
	v_mul_f32_e32 v89, v91, v91
	v_mul_f32_e32 v96, v67, v67
	v_fma_f32 v93, s0, v87, v97
	v_fmac_f32_e32 v95, s0, v87
	v_fmac_f32_e32 v89, v90, v90
	v_fmac_f32_e32 v96, v66, v66
	v_fma_f32 v94, s0, v87, v94
	v_add_f32_e32 v89, v89, v96
	v_mul_f32_e32 v96, v95, v95
	v_mul_f32_e32 v97, v93, v93
	v_fmac_f32_e32 v96, v94, v94
	v_fmac_f32_e32 v97, v92, v92
	v_add_f32_e32 v96, v96, v97
	v_add_f32_e32 v89, v89, v96
	v_mov_b32_e32 v96, 0
	s_nop 0
	v_add_f32_dpp v89, v89, v89 row_shr:1 row_mask:0xf bank_mask:0xf bound_ctrl:1
	s_nop 1
	v_add_f32_dpp v89, v89, v89 row_shr:2 row_mask:0xf bank_mask:0xf bound_ctrl:1
	s_nop 1
	v_add_f32_dpp v89, v89, v89 row_shr:4 row_mask:0xf bank_mask:0xf bound_ctrl:1
	s_nop 1
	v_add_f32_dpp v89, v89, v89 row_shr:8 row_mask:0xf bank_mask:0xf bound_ctrl:1
	s_nop 1
	v_mov_b32_dpp v96, v89 row_bcast:15 row_mask:0xa bank_mask:0xf
	v_add_f32_e32 v89, v89, v96
	v_mov_b32_e32 v96, 0
	s_nop 1
	v_mov_b32_dpp v96, v89 row_bcast:31 row_mask:0xc bank_mask:0xf
	v_add_f32_e32 v89, v89, v96
	s_nop 0
	v_readlane_b32 s0, v89, 63
	s_nop 1
	v_fma_f32 v89, s0, v88, v85
	v_mul_f32_e32 v96, 0x4f800000, v89
	v_cmp_gt_f32_e32 vcc, s18, v89
	s_nop 1
	v_cndmask_b32_e32 v89, v89, v96, vcc
	v_sqrt_f32_e32 v96, v89
	s_nop 0
	v_add_u32_e32 v97, -1, v96
	v_fma_f32 v104, -v97, v96, v89
	v_cmp_ge_f32_e64 s[0:1], 0, v104
	v_add_u32_e32 v104, 1, v96
	s_nop 0
	v_cndmask_b32_e64 v97, v96, v97, s[0:1]
	v_fma_f32 v96, -v104, v96, v89
	v_cmp_lt_f32_e64 s[0:1], 0, v96
	s_nop 1
	v_cndmask_b32_e64 v96, v97, v104, s[0:1]
	v_mul_f32_e32 v97, 0x37800000, v96
	v_cndmask_b32_e32 v96, v96, v97, vcc
	v_cmp_class_f32_e32 vcc, v89, v86
	s_nop 1
	v_cndmask_b32_e32 v89, v96, v89, vcc
	v_div_scale_f32 v104, s[0:1], v89, v89, 1.0
	v_rcp_f32_e32 v105, v104
	v_lshl_add_u64 v[96:97], s[30:31], 0, v[102:103]
	s_lshl_b64 s[0:1], s[8:9], 11
	v_fma_f32 v102, -v104, v105, 1.0
	v_fmac_f32_e32 v105, v102, v105
	v_div_scale_f32 v102, vcc, 1.0, v89, 1.0
	v_mul_f32_e32 v103, v102, v105
	v_fma_f32 v106, -v104, v103, v102
	v_fmac_f32_e32 v103, v106, v105
	v_fma_f32 v102, -v104, v103, v102
	v_div_fmas_f32 v102, v102, v105, v103
	v_div_fixup_f32 v102, v102, v89, 1.0
	v_pk_mul_f32 v[90:91], v[90:91], v[102:103] op_sel_hi:[1,0]
	v_pk_mul_f32 v[66:67], v[66:67], v[102:103] op_sel_hi:[1,0]
	s_waitcnt vmcnt(1)
; __device__ __forceinline__ unsigned pk2(float lo, float hi) { return f2bf(lo) | (f2bf(hi) << 16); }
; __device__ __forceinline__ float siluf_(float x) { return x * sigmoidf_(x); }
; template <int NT, bool SMP>
; __device__ __forceinline__ void conv_body(const Prm& P, Ctx& C, int b, int t0) {
;     ...
;             const float rstd = 1.f / sqrtf(wave_sum(q2) * (1.f / 512.f) + LN_EPS);
;             const u32x4 ag = agv[rq];
;             f32x4 z0 = v0 * rstd * g0 + b0, z1 = v1 * rstd * g1 + b1;
;             z0[0] = siluf_(z0[0]) * bflo(ag.x); z0[1] = siluf_(z0[1]) * bfhi(ag.x); z0[2] = siluf_(z0[2]) * bflo(ag.y); z0[3] = siluf_(z0[3]) * bfhi(ag.y);
;             z1[0] = siluf_(z1[0]) * bflo(ag.z); z1[1] = siluf_(z1[1]) * bfhi(ag.z); z1[2] = siluf_(z1[2]) * bflo(ag.w); z1[3] = siluf_(z1[3]) * bfhi(ag.w);
;             u32x4 o; o.x = pk2(z0[0], z0[1]); o.y = pk2(z0[2], z0[3]); o.z = pk2(z1[0], z1[1]); o.w = pk2(z1[2], z1[3]);
;             *(u32x4*)(H2 + row * 1024 + c8) = o;
	v_pk_fma_f32 v[72:73], v[80:81], v[90:91], v[72:73]
	v_pk_mul_f32 v[80:81], v[92:93], v[102:103] op_sel_hi:[1,0]
	v_pk_fma_f32 v[66:67], v[82:83], v[66:67], v[74:75]
	v_pk_fma_f32 v[70:71], v[78:79], v[80:81], v[70:71]
	v_mul_f32_e32 v78, 0xbfb8aa3b, v72
	v_exp_f32_e32 v78, v78
	v_pk_mul_f32 v[74:75], v[94:95], v[102:103] op_sel_hi:[1,0]
	v_mul_f32_e32 v79, 0xbfb8aa3b, v73
	v_exp_f32_e32 v79, v79
	v_pk_fma_f32 v[68:69], v[76:77], v[74:75], v[68:69]
	v_mul_f32_e32 v76, 0xbfb8aa3b, v66
	v_exp_f32_e32 v77, v76
	v_mul_f32_e32 v76, 0xbfb8aa3b, v67
	v_add_f32_e32 v74, 1.0, v78
	v_exp_f32_e32 v78, v76
	v_add_f32_e32 v75, 1.0, v79
	v_mul_f32_e32 v79, 0xbfb8aa3b, v69
	v_mul_f32_e32 v80, 0xbfb8aa3b, v70
	v_exp_f32_e32 v79, v79
	v_exp_f32_e32 v81, v80
	v_mul_f32_e32 v80, 0xbfb8aa3b, v71
	v_rcp_f32_e32 v76, v75
	v_add_f32_e32 v75, 1.0, v77
	v_add_f32_e32 v77, 1.0, v78
	v_mul_f32_e32 v78, 0xbfb8aa3b, v68
	v_exp_f32_e32 v82, v80
	v_exp_f32_e32 v78, v78
	v_rcp_f32_e32 v77, v77
	v_add_f32_e32 v79, 1.0, v79
	v_rcp_f32_e32 v80, v79
	v_add_f32_e32 v79, 1.0, v81
	v_add_f32_e32 v81, 1.0, v82
	v_add_f32_e32 v78, 1.0, v78
	v_rcp_f32_e32 v81, v81
	v_rcp_f32_e32 v74, v74
	v_rcp_f32_e32 v75, v75
	v_rcp_f32_e32 v78, v78
	v_rcp_f32_e32 v79, v79
	v_mov_b32_e32 v93, v66
	v_mov_b32_e32 v66, v73
	s_waitcnt vmcnt(0)
	v_and_b32_e32 v83, 0xffff0000, v99
	v_and_b32_e32 v82, 0xffff0000, v98
	v_pk_mul_f32 v[66:67], v[66:67], v[76:77]
	v_mov_b32_e32 v92, v72
	v_pk_mul_f32 v[66:67], v[66:67], v[82:83]
	v_mov_b32_e32 v83, v70
	v_mov_b32_e32 v70, v69
	v_and_b32_e32 v73, 0xffff0000, v101
	v_and_b32_e32 v72, 0xffff0000, v100
	v_mov_b32_e32 v82, v68
	v_pk_mul_f32 v[68:69], v[70:71], v[80:81]
	v_lshlrev_b32_e32 v91, 16, v99
	v_lshlrev_b32_e32 v90, 16, v98
	v_pk_mul_f32 v[74:75], v[92:93], v[74:75]
	v_lshlrev_b32_e32 v77, 16, v101
	v_lshlrev_b32_e32 v76, 16, v100
	v_pk_mul_f32 v[78:79], v[82:83], v[78:79]
	v_pk_mul_f32 v[68:69], v[68:69], v[72:73]
	v_pk_mul_f32 v[74:75], v[74:75], v[90:91]
	v_pk_mul_f32 v[76:77], v[78:79], v[76:77]
	v_bfe_u32 v70, v69, 16, 1
	v_bfe_u32 v71, v68, 16, 1
	v_add3_u32 v68, v68, v71, s24
	v_add3_u32 v69, v69, v70, s24
	v_bfe_u32 v72, v76, 16, 1
	v_bfe_u32 v73, v77, 16, 1
	v_add3_u32 v73, v77, v73, s24
	v_add3_u32 v72, v76, v72, s24
	v_lshrrev_b32_e32 v72, 16, v72
	v_lshrrev_b32_e32 v73, 16, v73
	v_and_or_b32 v69, v69, s19, v73
	v_and_or_b32 v68, v68, s19, v72
	v_cvt_pk_bf16_f32 v67, v75, v67
	v_cvt_pk_bf16_f32 v66, v74, v66
	v_lshl_add_u64 v[70:71], v[96:97], 0, s[0:1]
	global_store_dwordx4 v[70:71], v[66:69], off
	s_branch .LBB0_994

; template <class RowPtr>
; __device__ __forceinline__ void compress_task_bw(const RowPtr& rp, int nrows, int p, const LAS bf16_t* wl, bf16_t* dst, int nmax, int lane_in) {
;     ...
;     for (int i = 0; i <= 8; ++i) {
;         const int r0 = 128 * p + 16 * i;
;         if (r0 >= nrows) break;
;         f32x4 v0[16];
;         const f32x4* c0 = (const f32x4*)rp(r0) + lane;
; #pragma unroll
;         for (int j = 0; j < 16; ++j) v0[j] = __builtin_nontemporal_load(c0 + 64 * j);
;         f32x4 A0, B0; chunk_ab(v0, wl, lane, A0, B0);
.LBB0_1053:
	s_cmpk_gt_u32 s19, 0x3fff
	s_mov_b64 s[8:9], -1
	s_cbranch_scc1 .LBB0_1052
	s_lshr_b32 s0, s19, 5
	s_and_b32 s0, s0, 0x7fffffc
	v_mov_b32_e32 v0, s0
	global_load_dword v0, v0, s[4:5]
	v_readlane_b32 s80, v250, 12
	s_and_b32 s0, s20, 0x7000
	v_readlane_b32 s84, v250, 16
	v_readlane_b32 s85, v250, 17
	s_lshl_b32 s2, s0, 2
	v_mov_b32_e32 v109, v108
	s_cmp_eq_u32 s21, 0
	v_readlane_b32 s81, v250, 13
	v_readlane_b32 s82, v250, 14
	v_readlane_b32 s83, v250, 15
	v_readlane_b32 s86, v250, 18
	v_readlane_b32 s87, v250, 19
	v_readlane_b32 s88, v250, 20
	v_readlane_b32 s89, v250, 21
	v_readlane_b32 s90, v250, 22
	v_readlane_b32 s91, v250, 23
	v_readlane_b32 s92, v250, 24
	v_readlane_b32 s93, v250, 25
	v_readlane_b32 s94, v250, 26
	v_readlane_b32 s95, v250, 27
	s_waitcnt vmcnt(0)
	v_ashrrev_i32_e32 v1, 31, v0
	v_lshlrev_b64 v[0:1], 17, v[0:1]
	v_lshl_add_u64 v[0:1], s[84:85], 0, v[0:1]
	v_lshl_add_u64 v[0:1], v[0:1], 0, s[2:3]
	v_lshl_add_u64 v[0:1], v[100:101], 4, v[0:1]
	v_add_co_u32_e32 v2, vcc, s12, v0
	global_load_dwordx4 v[84:87], v[0:1], off nt
	global_load_dwordx4 v[76:79], v[0:1], off offset:1024 nt
	global_load_dwordx4 v[68:71], v[0:1], off offset:2048 nt
	global_load_dwordx4 v[60:63], v[0:1], off offset:3072 nt
	v_addc_co_u32_e32 v3, vcc, 0, v1, vcc
	v_add_co_u32_e32 v16, vcc, s13, v0
	s_nop 1
	v_addc_co_u32_e32 v17, vcc, 0, v1, vcc
	v_add_co_u32_e32 v0, vcc, s14, v0
	s_nop 1
	v_addc_co_u32_e32 v1, vcc, 0, v1, vcc
	global_load_dwordx4 v[56:59], v[2:3], off offset:1024 nt
	global_load_dwordx4 v[52:55], v[2:3], off offset:2048 nt
	global_load_dwordx4 v[36:39], v[16:17], off nt
	global_load_dwordx4 v[32:35], v[16:17], off offset:1024 nt
	global_load_dwordx4 v[24:27], v[16:17], off offset:2048 nt
	global_load_dwordx4 v[20:23], v[16:17], off offset:3072 nt
	global_load_dwordx4 v[44:47], v[2:3], off offset:3072 nt
	global_load_dwordx4 v[12:15], v[0:1], off nt
	global_load_dwordx4 v[8:11], v[0:1], off offset:1024 nt
	global_load_dwordx4 v[4:7], v[0:1], off offset:2048 nt
	global_load_dwordx4 v[72:75], v[16:17], off offset:-4096 nt
	s_nop 0
	global_load_dwordx4 v[0:3], v[0:1], off offset:3072 nt
	ds_read2st64_b64 v[92:95], v109 offset1:1
	ds_read2st64_b64 v[88:91], v109 offset0:2 offset1:3
	ds_read2st64_b64 v[80:83], v109 offset0:4 offset1:5
	ds_read2st64_b64 v[64:67], v109 offset0:6 offset1:7
	ds_read2st64_b64 v[48:51], v109 offset0:8 offset1:9
	ds_read2st64_b64 v[40:43], v109 offset0:10 offset1:11
	ds_read2st64_b64 v[28:31], v109 offset0:12 offset1:13
	ds_read2st64_b64 v[16:19], v109 offset0:14 offset1:15
	s_cbranch_scc1 .LBB0_1051
; #define LAS __attribute__((address_space(3)))
; __device__ __forceinline__ unsigned pk2(float lo, float hi) { return f2bf(lo) | (f2bf(hi) << 16); }
; __device__ __forceinline__ void st8_wt(void* p, unsigned lo, unsigned hi) { __hip_atomic_store((unsigned long long*)p, ((unsigned long long)hi << 32) | lo, __ATOMIC_RELAXED, __HIP_MEMORY_SCOPE_AGENT); }
; __device__ __forceinline__ void chunk_ab(const f32x4 (&v)[16], const LAS bf16_t* wl, int lane, f32x4& A, f32x4& B) {
;     A = (f32x4){0.f, 0.f, 0.f, 0.f}; B = A;
;     const LAS bf16_t* wlane = wl + 4 * lane; asm volatile("" : "+v"(wlane));
; #pragma unroll
;     for (int j = 0; j < 16; ++j) { const u32x2 wa = *(const LAS u32x2*)(wlane + j * 256), wb = *(const LAS u32x2*)(wlane + (16 + j) * 256);
;         A += v[j] * (f32x4){bflo(wa.x), bfhi(wa.x), bflo(wa.y), bfhi(wa.y)}; B += v[j] * (f32x4){bflo(wb.x), bfhi(wb.x), bflo(wb.y), bfhi(wb.y)}; }
; }
; template <class RowPtr>
; __device__ __forceinline__ void compress_task_bw(const RowPtr& rp, int nrows, int p, const LAS bf16_t* wl, bf16_t* dst, int nmax, int lane_in) {
;     ...
;         if (i >= 1) { const int n = 8 * p + i - 1; if (n < nmax) { const f32x4 s = Aprev + B0; st8_wt(dst + (size_t)n * 256 + 4 * lane, pk2(s[0], s[1]), pk2(s[2], s[3])); } }
	ds_read2st64_b64 v[110:113], v109 offset0:16 offset1:17
	ds_read2st64_b64 v[114:117], v109 offset0:18 offset1:19
	s_add_i32 s2, s18, s21
	s_lshl_b64 s[8:9], s[2:3], 9
	s_waitcnt lgkmcnt(1)
	v_lshlrev_b32_e32 v118, 16, v110
	v_and_b32_e32 v119, 0xffff0000, v110
	v_lshlrev_b32_e32 v110, 16, v111
	v_and_b32_e32 v111, 0xffff0000, v111
	s_waitcnt vmcnt(15)
	v_pk_fma_f32 v[110:111], v[86:87], v[110:111], 0 op_sel_hi:[1,1,0]
	v_pk_fma_f32 v[118:119], v[84:85], v[118:119], 0 op_sel_hi:[1,1,0]
	v_lshlrev_b32_e32 v122, 16, v112
	v_and_b32_e32 v123, 0xffff0000, v112
	v_lshlrev_b32_e32 v112, 16, v113
	v_and_b32_e32 v113, 0xffff0000, v113
	s_waitcnt vmcnt(14)
	v_pk_fma_f32 v[118:119], v[76:77], v[122:123], v[118:119]
	v_pk_fma_f32 v[110:111], v[78:79], v[112:113], v[110:111]
	s_waitcnt lgkmcnt(0)
	v_lshlrev_b32_e32 v112, 16, v114
	v_and_b32_e32 v113, 0xffff0000, v114
	v_lshlrev_b32_e32 v114, 16, v115
	v_and_b32_e32 v115, 0xffff0000, v115
	s_waitcnt vmcnt(13)
	v_pk_fma_f32 v[114:115], v[70:71], v[114:115], v[110:111]
	v_pk_fma_f32 v[118:119], v[68:69], v[112:113], v[118:119]
	ds_read2st64_b64 v[110:113], v109 offset0:20 offset1:21
	v_lshlrev_b32_e32 v122, 16, v116
	v_and_b32_e32 v123, 0xffff0000, v116
	v_lshlrev_b32_e32 v116, 16, v117
	v_and_b32_e32 v117, 0xffff0000, v117
	s_waitcnt vmcnt(12)
	v_pk_fma_f32 v[118:119], v[60:61], v[122:123], v[118:119]
	v_pk_fma_f32 v[122:123], v[62:63], v[116:117], v[114:115]
	ds_read2st64_b64 v[114:117], v109 offset0:22 offset1:23
	s_waitcnt lgkmcnt(1)
	v_lshlrev_b32_e32 v124, 16, v110
	v_and_b32_e32 v125, 0xffff0000, v110
	v_lshlrev_b32_e32 v110, 16, v111
	v_and_b32_e32 v111, 0xffff0000, v111
	s_waitcnt vmcnt(1)
	v_pk_fma_f32 v[110:111], v[74:75], v[110:111], v[122:123]
	v_pk_fma_f32 v[118:119], v[72:73], v[124:125], v[118:119]
	v_lshlrev_b32_e32 v122, 16, v112
	v_and_b32_e32 v123, 0xffff0000, v112
	v_lshlrev_b32_e32 v112, 16, v113
	v_and_b32_e32 v113, 0xffff0000, v113
	v_pk_fma_f32 v[118:119], v[56:57], v[122:123], v[118:119]
	v_pk_fma_f32 v[110:111], v[58:59], v[112:113], v[110:111]
	s_waitcnt lgkmcnt(0)
	v_lshlrev_b32_e32 v112, 16, v114
	v_and_b32_e32 v113, 0xffff0000, v114
	v_lshlrev_b32_e32 v114, 16, v115
	v_and_b32_e32 v115, 0xffff0000, v115
	v_pk_fma_f32 v[114:115], v[54:55], v[114:115], v[110:111]
	v_pk_fma_f32 v[118:119], v[52:53], v[112:113], v[118:119]
	ds_read2st64_b64 v[110:113], v109 offset0:24 offset1:25
	v_lshlrev_b32_e32 v122, 16, v116
	v_and_b32_e32 v123, 0xffff0000, v116
	v_lshlrev_b32_e32 v116, 16, v117
	v_and_b32_e32 v117, 0xffff0000, v117
	v_pk_fma_f32 v[118:119], v[44:45], v[122:123], v[118:119]
	v_pk_fma_f32 v[122:123], v[46:47], v[116:117], v[114:115]
	ds_read2st64_b64 v[114:117], v109 offset0:26 offset1:27
	s_waitcnt lgkmcnt(1)
	v_lshlrev_b32_e32 v124, 16, v110
	v_and_b32_e32 v125, 0xffff0000, v110
	v_lshlrev_b32_e32 v110, 16, v111
	v_and_b32_e32 v111, 0xffff0000, v111
	v_pk_fma_f32 v[110:111], v[38:39], v[110:111], v[122:123]
	v_pk_fma_f32 v[118:119], v[36:37], v[124:125], v[118:119]
	v_lshlrev_b32_e32 v122, 16, v112
	v_and_b32_e32 v123, 0xffff0000, v112
	v_lshlrev_b32_e32 v112, 16, v113
	v_and_b32_e32 v113, 0xffff0000, v113
	v_pk_fma_f32 v[118:119], v[32:33], v[122:123], v[118:119]
	v_pk_fma_f32 v[110:111], v[34:35], v[112:113], v[110:111]
	s_waitcnt lgkmcnt(0)
	v_lshlrev_b32_e32 v112, 16, v114
	v_and_b32_e32 v113, 0xffff0000, v114
	v_lshlrev_b32_e32 v114, 16, v115
	v_and_b32_e32 v115, 0xffff0000, v115
	v_pk_fma_f32 v[114:115], v[26:27], v[114:115], v[110:111]
	v_pk_fma_f32 v[118:119], v[24:25], v[112:113], v[118:119]
	ds_read2st64_b64 v[110:113], v109 offset0:28 offset1:29
	v_lshlrev_b32_e32 v122, 16, v116
	v_and_b32_e32 v123, 0xffff0000, v116
	v_lshlrev_b32_e32 v116, 16, v117
	v_and_b32_e32 v117, 0xffff0000, v117
	v_pk_fma_f32 v[118:119], v[20:21], v[122:123], v[118:119]
	v_pk_fma_f32 v[122:123], v[22:23], v[116:117], v[114:115]
	ds_read2st64_b64 v[114:117], v109 offset0:30 offset1:31
	s_waitcnt lgkmcnt(1)
	v_lshlrev_b32_e32 v124, 16, v110
	v_and_b32_e32 v125, 0xffff0000, v110
	v_lshlrev_b32_e32 v110, 16, v111
	v_and_b32_e32 v111, 0xffff0000, v111
	v_pk_fma_f32 v[110:111], v[14:15], v[110:111], v[122:123]
	v_pk_fma_f32 v[118:119], v[12:13], v[124:125], v[118:119]
	v_lshlrev_b32_e32 v122, 16, v112
	v_and_b32_e32 v123, 0xffff0000, v112
	v_lshlrev_b32_e32 v112, 16, v113
	v_and_b32_e32 v113, 0xffff0000, v113
	v_pk_fma_f32 v[118:119], v[8:9], v[122:123], v[118:119]
	v_pk_fma_f32 v[110:111], v[10:11], v[112:113], v[110:111]
	s_waitcnt lgkmcnt(0)
	v_lshlrev_b32_e32 v112, 16, v114
	v_and_b32_e32 v113, 0xffff0000, v114
	v_lshlrev_b32_e32 v114, 16, v115
	v_and_b32_e32 v115, 0xffff0000, v115
	v_pk_fma_f32 v[110:111], v[6:7], v[114:115], v[110:111]
	v_pk_fma_f32 v[112:113], v[4:5], v[112:113], v[118:119]
	v_lshlrev_b32_e32 v114, 16, v116
	v_and_b32_e32 v115, 0xffff0000, v116
	s_waitcnt vmcnt(0)
	v_pk_fma_f32 v[112:113], v[0:1], v[114:115], v[112:113]
	v_lshlrev_b32_e32 v116, 16, v117
	v_pk_add_f32 v[104:105], v[104:105], v[112:113]
	v_and_b32_e32 v117, 0xffff0000, v117
	v_pk_fma_f32 v[110:111], v[2:3], v[116:117], v[110:111]
	v_pk_add_f32 v[106:107], v[106:107], v[110:111]
	v_cvt_pk_bf16_f32 v104, v104, v105
	v_lshl_add_u64 v[110:111], v[102:103], 0, s[8:9]
	v_cvt_pk_bf16_f32 v105, v106, v107
	global_store_dwordx2 v[110:111], v[104:105], off sc1
	s_branch .LBB0_1051

; #define LAS __attribute__((address_space(3)))
; __device__ __forceinline__ float ex2(float x) { return __builtin_amdgcn_exp2f(x); }
; __device__ __forceinline__ int crow(int r, int hi) { return (r & 3) + 8 * (r >> 2) + 4 * hi; }
; #define MFMA32(a, b, c) __builtin_amdgcn_mfma_f32_32x32x16_bf16((a), (b), (c), 0, 0, 0)
; __device__ __forceinline__ float quad_sum(float v) { v += __int_as_float(dpp_x1(__float_as_int(v))); v += __int_as_float(dpp_x2(__float_as_int(v))); return v; }
; #define CMP_LOADK(t) do { _Pragma("unroll") for (int s_ = 0; s_ < 4; ++s_) kf[s_] = *(const LAS bf16x8*)(kb + s_ * 16384 + (t) * 512); } while (0)
; __device__ __forceinline__ void cmp_task_lds(const Prm& P, Ctx& C, int b, int kvh, int tg, CStream& CS, const LAS bf16_t* wlb, const int NGW, bf16x8 (&qnx)[4], int& qnx_tg, const int tg_next) {
;     ...
;         for (int tt = 0; tt < 4; ++tt) {
;             const int tile = 4 * k4 + tt;
;             if (tile < ntile) {
;                 f32x16 S = {};
; #pragma unroll
;                 for (int s = 0; s < 4; ++s) S = MFMA32(kf[s], qf[s], S);
;                 __builtin_amdgcn_sched_barrier(0);
;                 CMP_LOADK(tile + 1);
;                 s16x4 vlo[4], vhh[4];
; #pragma unroll
;                 for (int dk = 0; dk < 4; ++dk) { const LAS unsigned char* vp = vb + (dk >> 1) * 32 * CK_VS + (32 * tile + 16 * (dk & 1)) * 2; vlo[dk] = *(const LAS s16x4*)vp; vhh[dk] = *(const LAS s16x4*)(vp + 16); }
;                 __builtin_amdgcn_sched_barrier(0);
;                 if (tile < nfull) {
; #pragma unroll
;                     for (int r = 0; r < 16; ++r) S[r] = ex2(S[r] - ml);
;                 } else {
; #pragma unroll
;                     for (int r = 0; r < 16; ++r) { const bool valid = (32 * tile + crow(r, hi)) < nvq; S[r] = valid ? ex2(S[r] - ml) : 0.f; }
;                 }
; #pragma unroll
;                 for (int i = 0; i < 4; ++i) { const float v = quad_sum(S[4 * i] + S[4 * i + 1] + S[4 * i + 2]); if (g == tt) cur4[i] = v; }
;                 bf16x8 pf[2]; pf[0] = pack8(S, 0); pf[1] = pack8(S, 8);
; #pragma unroll
;                 for (int dk = 0; dk < 4; ++dk)
;                     o[dk >> 1] = MFMA32(((bf16x8){vlo[dk][0], vlo[dk][1], vlo[dk][2], vlo[dk][3], vhh[dk][0], vhh[dk][1], vhh[dk][2], vhh[dk][3]}), pf[dk & 1], o[dk >> 1]);
.LBB0_1081:
	v_mov_b32_e32 v97, v48
	v_cvt_pk_bf16_f32 v48, v48, v49
	v_mov_b32_e32 v99, v49
	v_mov_b32_e32 v96, v52
	v_mov_b32_e32 v98, v53
	v_cvt_pk_bf16_f32 v49, v50, v51
	v_pk_add_f32 v[96:97], v[96:97], v[98:99]
	v_mov_b32_e32 v99, v50
	v_cvt_pk_bf16_f32 v50, v52, v53
	v_cvt_pk_bf16_f32 v51, v54, v55
	v_cvt_pk_bf16_f32 v52, v56, v57
	s_waitcnt lgkmcnt(6)
	v_mfma_f32_32x32x16_bf16 v[32:47], v[116:119], v[48:51], v[32:47]
	v_cvt_pk_bf16_f32 v53, v58, v59
	v_mov_b32_e32 v98, v54
	v_pk_add_f32 v[96:97], v[98:99], v[96:97]
	s_waitcnt lgkmcnt(2)
	v_mfma_f32_32x32x16_bf16 v[16:31], v[100:103], v[48:51], v[16:31]
	v_mov_b32_dpp v99, v97 quad_perm:[1,0,3,2] row_mask:0xf bank_mask:0xf bound_ctrl:1
	v_mov_b32_dpp v98, v96 quad_perm:[1,0,3,2] row_mask:0xf bank_mask:0xf bound_ctrl:1
	v_cvt_pk_bf16_f32 v54, v60, v61
	v_pk_add_f32 v[96:97], v[96:97], v[98:99]
	s_nop 1
	v_mov_b32_dpp v99, v97 quad_perm:[2,3,0,1] row_mask:0xf bank_mask:0xf bound_ctrl:1
	s_nop 0
	v_mov_b32_dpp v98, v96 quad_perm:[2,3,0,1] row_mask:0xf bank_mask:0xf bound_ctrl:1
	v_pk_add_f32 v[96:97], v[96:97], v[98:99]
	v_cvt_pk_bf16_f32 v55, v62, v63
	v_cndmask_b32_e64 v153, 0, v97, s[4:5]
	v_cndmask_b32_e64 v152, 0, v96, s[4:5]
	v_mov_b32_e32 v96, v60
	v_mov_b32_e32 v97, v56
	v_mfma_f32_32x32x16_bf16 v[32:47], v[104:107], v[52:55], v[32:47]
	v_mov_b32_e32 v56, v61
	v_add_f32_e64 v56, v96, v56
	v_add_f32_e64 v57, v97, v57
	v_mov_b32_e32 v60, v62
	v_mov_b32_e32 v61, v58
	v_pk_add_f32 v[56:57], v[60:61], v[56:57]
	s_waitcnt lgkmcnt(0)
	v_mfma_f32_32x32x16_bf16 v[16:31], v[6:9], v[52:55], v[16:31]
	v_mov_b32_dpp v59, v57 quad_perm:[1,0,3,2] row_mask:0xf bank_mask:0xf bound_ctrl:1
	v_mov_b32_dpp v58, v56 quad_perm:[1,0,3,2] row_mask:0xf bank_mask:0xf bound_ctrl:1
	v_add_f32_e64 v48, v56, v58
	v_add_f32_e64 v49, v57, v59
	s_nop 1
	v_mov_b32_dpp v51, v49 quad_perm:[2,3,0,1] row_mask:0xf bank_mask:0xf bound_ctrl:1
	v_mov_b32_dpp v50, v48 quad_perm:[2,3,0,1] row_mask:0xf bank_mask:0xf bound_ctrl:1
	v_pk_add_f32 v[48:49], v[48:49], v[50:51]
	s_nop 0
	v_cndmask_b32_e64 v155, 0, v49, s[4:5]
	v_cndmask_b32_e64 v154, 0, v48, s[4:5]
	s_add_i32 s18, s16, 1
	s_cmp_ge_i32 s18, s14
	s_cbranch_scc0 .LBB0_1086

; #define LAS __attribute__((address_space(3)))
; __device__ __forceinline__ float ex2(float x) { return __builtin_amdgcn_exp2f(x); }
; __device__ __forceinline__ int crow(int r, int hi) { return (r & 3) + 8 * (r >> 2) + 4 * hi; }
; #define MFMA32(a, b, c) __builtin_amdgcn_mfma_f32_32x32x16_bf16((a), (b), (c), 0, 0, 0)
; __device__ __forceinline__ float quad_sum(float v) { v += __int_as_float(dpp_x1(__float_as_int(v))); v += __int_as_float(dpp_x2(__float_as_int(v))); return v; }
; #define CMP_LOADK(t) do { _Pragma("unroll") for (int s_ = 0; s_ < 4; ++s_) kf[s_] = *(const LAS bf16x8*)(kb + s_ * 16384 + (t) * 512); } while (0)
; __device__ __forceinline__ void cmp_task_lds(const Prm& P, Ctx& C, int b, int kvh, int tg, CStream& CS, const LAS bf16_t* wlb, const int NGW, bf16x8 (&qnx)[4], int& qnx_tg, const int tg_next) {
;     ...
;         for (int tt = 0; tt < 4; ++tt) {
;             const int tile = 4 * k4 + tt;
;             if (tile < ntile) {
;                 f32x16 S = {};
; #pragma unroll
;                 for (int s = 0; s < 4; ++s) S = MFMA32(kf[s], qf[s], S);
;                 __builtin_amdgcn_sched_barrier(0);
;                 CMP_LOADK(tile + 1);
;                 s16x4 vlo[4], vhh[4];
; #pragma unroll
;                 for (int dk = 0; dk < 4; ++dk) { const LAS unsigned char* vp = vb + (dk >> 1) * 32 * CK_VS + (32 * tile + 16 * (dk & 1)) * 2; vlo[dk] = *(const LAS s16x4*)vp; vhh[dk] = *(const LAS s16x4*)(vp + 16); }
;                 __builtin_amdgcn_sched_barrier(0);
;                 if (tile < nfull) {
; #pragma unroll
;                     for (int r = 0; r < 16; ++r) S[r] = ex2(S[r] - ml);
;                 } else {
; #pragma unroll
;                     for (int r = 0; r < 16; ++r) { const bool valid = (32 * tile + crow(r, hi)) < nvq; S[r] = valid ? ex2(S[r] - ml) : 0.f; }
;                 }
; #pragma unroll
;                 for (int i = 0; i < 4; ++i) { const float v = quad_sum(S[4 * i] + S[4 * i + 1] + S[4 * i + 2]); if (g == tt) cur4[i] = v; }
;                 bf16x8 pf[2]; pf[0] = pack8(S, 0); pf[1] = pack8(S, 8);
; #pragma unroll
;                 for (int dk = 0; dk < 4; ++dk)
;                     o[dk >> 1] = MFMA32(((bf16x8){vlo[dk][0], vlo[dk][1], vlo[dk][2], vlo[dk][3], vhh[dk][0], vhh[dk][1], vhh[dk][2], vhh[dk][3]}), pf[dk & 1], o[dk >> 1]);
.LBB0_1090:
	v_mov_b32_e32 v2, v52
	v_mov_b32_e32 v3, v48
	v_mov_b32_e32 v4, v53
	v_mov_b32_e32 v5, v49
	v_pk_add_f32 v[2:3], v[2:3], v[4:5]
	v_mov_b32_e32 v4, v54
	v_mov_b32_e32 v5, v50
	v_pk_add_f32 v[2:3], v[4:5], v[2:3]
	v_bfe_u32 v1, v48, 16, 1
	v_add3_u32 v1, v48, v1, s71
	v_mov_b32_dpp v5, v3 quad_perm:[1,0,3,2] row_mask:0xf bank_mask:0xf bound_ctrl:1
	v_mov_b32_dpp v4, v2 quad_perm:[1,0,3,2] row_mask:0xf bank_mask:0xf bound_ctrl:1
	v_pk_add_f32 v[2:3], v[2:3], v[4:5]
	v_lshrrev_b32_e32 v1, 16, v1
	s_nop 0
	v_mov_b32_dpp v5, v3 quad_perm:[2,3,0,1] row_mask:0xf bank_mask:0xf bound_ctrl:1
	v_mov_b32_dpp v4, v2 quad_perm:[2,3,0,1] row_mask:0xf bank_mask:0xf bound_ctrl:1
	v_pk_add_f32 v[2:3], v[2:3], v[4:5]
	v_cndmask_b32_e64 v152, v152, v2, s[6:7]
	v_bfe_u32 v2, v49, 16, 1
	v_add3_u32 v2, v49, v2, s71
	v_and_or_b32 v2, v2, s72, v1
	v_cndmask_b32_e64 v153, v153, v3, s[6:7]
	v_cvt_pk_bf16_f32 v3, v50, v51
	v_cvt_pk_bf16_f32 v4, v52, v53
	v_cvt_pk_bf16_f32 v5, v54, v55
	v_cvt_pk_bf16_f32 v48, v56, v57
	s_waitcnt lgkmcnt(6)
	v_mfma_f32_32x32x16_bf16 v[32:47], v[116:119], v[2:5], v[32:47]
	v_cvt_pk_bf16_f32 v49, v58, v59
	v_cvt_pk_bf16_f32 v50, v60, v61
	s_waitcnt lgkmcnt(2)
	v_mfma_f32_32x32x16_bf16 v[16:31], v[104:107], v[2:5], v[16:31]
	v_cvt_pk_bf16_f32 v51, v62, v63
	v_mov_b32_e32 v214, v60
	v_mov_b32_e32 v215, v56
	v_mfma_f32_32x32x16_bf16 v[32:47], v[112:115], v[48:51], v[32:47]
	v_mov_b32_e32 v52, v61
	v_mov_b32_e32 v53, v57
	v_add_f32_e64 v52, v214, v52
	v_add_f32_e64 v53, v215, v53
	v_mov_b32_e32 v54, v62
	v_mov_b32_e32 v55, v58
	v_pk_add_f32 v[52:53], v[54:55], v[52:53]
	s_waitcnt lgkmcnt(0)
	v_mfma_f32_32x32x16_bf16 v[16:31], v[10:13], v[48:51], v[16:31]
	v_mov_b32_dpp v55, v53 quad_perm:[1,0,3,2] row_mask:0xf bank_mask:0xf bound_ctrl:1
	v_mov_b32_dpp v54, v52 quad_perm:[1,0,3,2] row_mask:0xf bank_mask:0xf bound_ctrl:1
	v_add_f32_e64 v2, v52, v54
	v_add_f32_e64 v3, v53, v55
	s_nop 1
	v_mov_b32_dpp v5, v3 quad_perm:[2,3,0,1] row_mask:0xf bank_mask:0xf bound_ctrl:1
	v_mov_b32_dpp v4, v2 quad_perm:[2,3,0,1] row_mask:0xf bank_mask:0xf bound_ctrl:1
	v_pk_add_f32 v[2:3], v[2:3], v[4:5]
	s_nop 0
	v_cndmask_b32_e64 v155, v155, v3, s[6:7]
	v_cndmask_b32_e64 v154, v154, v2, s[6:7]
	s_add_i32 s18, s16, 2
	s_cmp_ge_i32 s18, s14
	s_cbranch_scc1 .LBB0_1083

; #define LAS __attribute__((address_space(3)))
; __device__ __forceinline__ float ex2(float x) { return __builtin_amdgcn_exp2f(x); }
; __device__ __forceinline__ int crow(int r, int hi) { return (r & 3) + 8 * (r >> 2) + 4 * hi; }
; #define MFMA32(a, b, c) __builtin_amdgcn_mfma_f32_32x32x16_bf16((a), (b), (c), 0, 0, 0)
; __device__ __forceinline__ float quad_sum(float v) { v += __int_as_float(dpp_x1(__float_as_int(v))); v += __int_as_float(dpp_x2(__float_as_int(v))); return v; }
; #define CMP_LOADK(t) do { _Pragma("unroll") for (int s_ = 0; s_ < 4; ++s_) kf[s_] = *(const LAS bf16x8*)(kb + s_ * 16384 + (t) * 512); } while (0)
; __device__ __forceinline__ void cmp_task_lds(const Prm& P, Ctx& C, int b, int kvh, int tg, CStream& CS, const LAS bf16_t* wlb, const int NGW, bf16x8 (&qnx)[4], int& qnx_tg, const int tg_next) {
;     ...
;         for (int tt = 0; tt < 4; ++tt) {
;             const int tile = 4 * k4 + tt;
;             if (tile < ntile) {
;                 f32x16 S = {};
; #pragma unroll
;                 for (int s = 0; s < 4; ++s) S = MFMA32(kf[s], qf[s], S);
;                 __builtin_amdgcn_sched_barrier(0);
;                 CMP_LOADK(tile + 1);
;                 s16x4 vlo[4], vhh[4];
; #pragma unroll
;                 for (int dk = 0; dk < 4; ++dk) { const LAS unsigned char* vp = vb + (dk >> 1) * 32 * CK_VS + (32 * tile + 16 * (dk & 1)) * 2; vlo[dk] = *(const LAS s16x4*)vp; vhh[dk] = *(const LAS s16x4*)(vp + 16); }
;                 __builtin_amdgcn_sched_barrier(0);
;                 if (tile < nfull) {
; #pragma unroll
;                     for (int r = 0; r < 16; ++r) S[r] = ex2(S[r] - ml);
;                 } else {
; #pragma unroll
;                     for (int r = 0; r < 16; ++r) { const bool valid = (32 * tile + crow(r, hi)) < nvq; S[r] = valid ? ex2(S[r] - ml) : 0.f; }
;                 }
; #pragma unroll
;                 for (int i = 0; i < 4; ++i) { const float v = quad_sum(S[4 * i] + S[4 * i + 1] + S[4 * i + 2]); if (g == tt) cur4[i] = v; }
;                 bf16x8 pf[2]; pf[0] = pack8(S, 0); pf[1] = pack8(S, 8);
; #pragma unroll
;                 for (int dk = 0; dk < 4; ++dk)
;                     o[dk >> 1] = MFMA32(((bf16x8){vlo[dk][0], vlo[dk][1], vlo[dk][2], vlo[dk][3], vhh[dk][0], vhh[dk][1], vhh[dk][2], vhh[dk][3]}), pf[dk & 1], o[dk >> 1]);
.LBB0_1095:
	v_mov_b32_e32 v6, v52
	v_mov_b32_e32 v7, v48
	v_mov_b32_e32 v8, v53
	v_mov_b32_e32 v9, v49
	v_pk_add_f32 v[6:7], v[6:7], v[8:9]
	v_mov_b32_e32 v8, v54
	v_mov_b32_e32 v9, v50
	v_pk_add_f32 v[6:7], v[8:9], v[6:7]
	v_bfe_u32 v1, v48, 16, 1
	v_add3_u32 v1, v48, v1, s71
	v_mov_b32_dpp v9, v7 quad_perm:[1,0,3,2] row_mask:0xf bank_mask:0xf bound_ctrl:1
	v_mov_b32_dpp v8, v6 quad_perm:[1,0,3,2] row_mask:0xf bank_mask:0xf bound_ctrl:1
	v_pk_add_f32 v[6:7], v[6:7], v[8:9]
	v_lshrrev_b32_e32 v1, 16, v1
	s_nop 0
	v_mov_b32_dpp v9, v7 quad_perm:[2,3,0,1] row_mask:0xf bank_mask:0xf bound_ctrl:1
	v_mov_b32_dpp v8, v6 quad_perm:[2,3,0,1] row_mask:0xf bank_mask:0xf bound_ctrl:1
	v_pk_add_f32 v[6:7], v[6:7], v[8:9]
	v_cndmask_b32_e64 v152, v152, v6, s[8:9]
	v_bfe_u32 v6, v49, 16, 1
	v_add3_u32 v6, v49, v6, s71
	v_and_or_b32 v6, v6, s72, v1
	v_cndmask_b32_e64 v153, v153, v7, s[8:9]
	v_cvt_pk_bf16_f32 v7, v50, v51
	v_cvt_pk_bf16_f32 v8, v52, v53
	v_cvt_pk_bf16_f32 v9, v54, v55
	v_cvt_pk_bf16_f32 v48, v56, v57
	s_waitcnt lgkmcnt(6)
	v_mfma_f32_32x32x16_bf16 v[32:47], v[116:119], v[6:9], v[32:47]
	v_cvt_pk_bf16_f32 v49, v58, v59
	v_cvt_pk_bf16_f32 v50, v60, v61
	s_waitcnt lgkmcnt(2)
	v_mfma_f32_32x32x16_bf16 v[16:31], v[100:103], v[6:9], v[16:31]
	v_cvt_pk_bf16_f32 v51, v62, v63
	v_mov_b32_e32 v214, v60
	v_mov_b32_e32 v215, v56
	v_mfma_f32_32x32x16_bf16 v[32:47], v[104:107], v[48:51], v[32:47]
	v_mov_b32_e32 v52, v61
	v_mov_b32_e32 v53, v57
	v_add_f32_e64 v52, v214, v52
	v_add_f32_e64 v53, v215, v53
	v_mov_b32_e32 v54, v62
	v_mov_b32_e32 v55, v58
	v_pk_add_f32 v[52:53], v[54:55], v[52:53]
	s_waitcnt lgkmcnt(0)
	v_mfma_f32_32x32x16_bf16 v[16:31], v[96:99], v[48:51], v[16:31]
	v_mov_b32_dpp v55, v53 quad_perm:[1,0,3,2] row_mask:0xf bank_mask:0xf bound_ctrl:1
	v_mov_b32_dpp v54, v52 quad_perm:[1,0,3,2] row_mask:0xf bank_mask:0xf bound_ctrl:1
	v_add_f32_e64 v6, v52, v54
	v_add_f32_e64 v7, v53, v55
	s_nop 1
	v_mov_b32_dpp v9, v7 quad_perm:[2,3,0,1] row_mask:0xf bank_mask:0xf bound_ctrl:1
	v_mov_b32_dpp v8, v6 quad_perm:[2,3,0,1] row_mask:0xf bank_mask:0xf bound_ctrl:1
	v_pk_add_f32 v[6:7], v[6:7], v[8:9]
	s_nop 0
	v_cndmask_b32_e64 v155, v155, v7, s[8:9]
	v_cndmask_b32_e64 v154, v154, v6, s[8:9]
	s_add_i32 s18, s16, 3
	s_cmp_ge_i32 s18, s14
	s_cbranch_scc1 .LBB0_1084

; #define LAS __attribute__((address_space(3)))
; __device__ __forceinline__ float ex2(float x) { return __builtin_amdgcn_exp2f(x); }
; __device__ __forceinline__ int crow(int r, int hi) { return (r & 3) + 8 * (r >> 2) + 4 * hi; }
; #define MFMA32(a, b, c) __builtin_amdgcn_mfma_f32_32x32x16_bf16((a), (b), (c), 0, 0, 0)
; __device__ __forceinline__ float quad_sum(float v) { v += __int_as_float(dpp_x1(__float_as_int(v))); v += __int_as_float(dpp_x2(__float_as_int(v))); return v; }
; #define CMP_LOADK(t) do { _Pragma("unroll") for (int s_ = 0; s_ < 4; ++s_) kf[s_] = *(const LAS bf16x8*)(kb + s_ * 16384 + (t) * 512); } while (0)
; __device__ __forceinline__ void cmp_task_lds(const Prm& P, Ctx& C, int b, int kvh, int tg, CStream& CS, const LAS bf16_t* wlb, const int NGW, bf16x8 (&qnx)[4], int& qnx_tg, const int tg_next) {
;     ...
;         for (int tt = 0; tt < 4; ++tt) {
;             const int tile = 4 * k4 + tt;
;             if (tile < ntile) {
;                 f32x16 S = {};
; #pragma unroll
;                 for (int s = 0; s < 4; ++s) S = MFMA32(kf[s], qf[s], S);
;                 __builtin_amdgcn_sched_barrier(0);
;                 CMP_LOADK(tile + 1);
;                 s16x4 vlo[4], vhh[4];
; #pragma unroll
;                 for (int dk = 0; dk < 4; ++dk) { const LAS unsigned char* vp = vb + (dk >> 1) * 32 * CK_VS + (32 * tile + 16 * (dk & 1)) * 2; vlo[dk] = *(const LAS s16x4*)vp; vhh[dk] = *(const LAS s16x4*)(vp + 16); }
;                 __builtin_amdgcn_sched_barrier(0);
;                 if (tile < nfull) {
; #pragma unroll
;                     for (int r = 0; r < 16; ++r) S[r] = ex2(S[r] - ml);
;                 } else {
; #pragma unroll
;                     for (int r = 0; r < 16; ++r) { const bool valid = (32 * tile + crow(r, hi)) < nvq; S[r] = valid ? ex2(S[r] - ml) : 0.f; }
;                 }
; #pragma unroll
;                 for (int i = 0; i < 4; ++i) { const float v = quad_sum(S[4 * i] + S[4 * i + 1] + S[4 * i + 2]); if (g == tt) cur4[i] = v; }
;                 bf16x8 pf[2]; pf[0] = pack8(S, 0); pf[1] = pack8(S, 8);
; #pragma unroll
;                 for (int dk = 0; dk < 4; ++dk)
;                     o[dk >> 1] = MFMA32(((bf16x8){vlo[dk][0], vlo[dk][1], vlo[dk][2], vlo[dk][3], vhh[dk][0], vhh[dk][1], vhh[dk][2], vhh[dk][3]}), pf[dk & 1], o[dk >> 1]);
.LBB0_1100:
	v_mov_b32_e32 v2, v52
	v_mov_b32_e32 v3, v48
	v_mov_b32_e32 v4, v53
	v_mov_b32_e32 v5, v49
	v_pk_add_f32 v[2:3], v[2:3], v[4:5]
	v_mov_b32_e32 v4, v54
	v_mov_b32_e32 v5, v50
	v_pk_add_f32 v[2:3], v[4:5], v[2:3]
	v_bfe_u32 v1, v48, 16, 1
	v_add3_u32 v1, v48, v1, s71
	v_mov_b32_dpp v5, v3 quad_perm:[1,0,3,2] row_mask:0xf bank_mask:0xf bound_ctrl:1
	v_mov_b32_dpp v4, v2 quad_perm:[1,0,3,2] row_mask:0xf bank_mask:0xf bound_ctrl:1
	v_pk_add_f32 v[2:3], v[2:3], v[4:5]
	v_lshrrev_b32_e32 v1, 16, v1
	s_nop 0
	v_mov_b32_dpp v5, v3 quad_perm:[2,3,0,1] row_mask:0xf bank_mask:0xf bound_ctrl:1
	v_mov_b32_dpp v4, v2 quad_perm:[2,3,0,1] row_mask:0xf bank_mask:0xf bound_ctrl:1
	v_pk_add_f32 v[2:3], v[2:3], v[4:5]
	v_cndmask_b32_e64 v152, v152, v2, s[10:11]
	v_bfe_u32 v2, v49, 16, 1
	v_add3_u32 v2, v49, v2, s71
	v_and_or_b32 v2, v2, s72, v1
	v_cndmask_b32_e64 v153, v153, v3, s[10:11]
	v_cvt_pk_bf16_f32 v3, v50, v51
	v_cvt_pk_bf16_f32 v4, v52, v53
	v_cvt_pk_bf16_f32 v5, v54, v55
	v_cvt_pk_bf16_f32 v48, v56, v57
	s_waitcnt lgkmcnt(6)
	v_mfma_f32_32x32x16_bf16 v[32:47], v[116:119], v[2:5], v[32:47]
	v_cvt_pk_bf16_f32 v49, v58, v59
	v_cvt_pk_bf16_f32 v50, v60, v61
	s_waitcnt lgkmcnt(2)
	v_mfma_f32_32x32x16_bf16 v[16:31], v[10:13], v[2:5], v[16:31]
	v_bfe_u32 v1, v62, 16, 1
	v_add3_u32 v1, v62, v1, s71
	v_bfe_u32 v51, v63, 16, 1
	v_lshrrev_b32_e32 v1, 16, v1
	v_add3_u32 v51, v63, v51, s71
	v_and_or_b32 v51, v51, s72, v1
	v_mov_b32_e32 v212, v60
	v_mov_b32_e32 v213, v56
	v_mfma_f32_32x32x16_bf16 v[32:47], v[112:115], v[48:51], v[32:47]
	v_mov_b32_e32 v52, v61
	v_mov_b32_e32 v53, v57
	v_add_f32_e64 v52, v212, v52
	v_add_f32_e64 v53, v213, v53
	v_mov_b32_e32 v54, v62
	v_mov_b32_e32 v55, v58
	v_pk_add_f32 v[52:53], v[54:55], v[52:53]
	s_waitcnt lgkmcnt(0)
	v_mfma_f32_32x32x16_bf16 v[16:31], v[6:9], v[48:51], v[16:31]
	v_mov_b32_dpp v55, v53 quad_perm:[1,0,3,2] row_mask:0xf bank_mask:0xf bound_ctrl:1
	v_mov_b32_dpp v54, v52 quad_perm:[1,0,3,2] row_mask:0xf bank_mask:0xf bound_ctrl:1
	v_add_f32_e64 v2, v52, v54
	v_add_f32_e64 v3, v53, v55
	s_nop 1
	v_mov_b32_dpp v5, v3 quad_perm:[2,3,0,1] row_mask:0xf bank_mask:0xf bound_ctrl:1
	v_mov_b32_dpp v4, v2 quad_perm:[2,3,0,1] row_mask:0xf bank_mask:0xf bound_ctrl:1
	v_pk_add_f32 v[2:3], v[2:3], v[4:5]
	s_nop 0
	v_cndmask_b32_e64 v155, v155, v3, s[10:11]
	v_cndmask_b32_e64 v154, v154, v2, s[10:11]

; #define LAS __attribute__((address_space(3)))
; __device__ __forceinline__ unsigned pk2(float lo, float hi) { return f2bf(lo) | (f2bf(hi) << 16); }
; __device__ __forceinline__ void chunk_ab(const f32x4 (&v)[16], const LAS bf16_t* wl, int lane, f32x4& A, f32x4& B) {
;     A = (f32x4){0.f, 0.f, 0.f, 0.f}; B = A;
;     const LAS bf16_t* wlane = wl + 4 * lane; asm volatile("" : "+v"(wlane));
; #pragma unroll
;     for (int j = 0; j < 16; ++j) { const u32x2 wa = *(const LAS u32x2*)(wlane + j * 256), wb = *(const LAS u32x2*)(wlane + (16 + j) * 256);
;         A += v[j] * (f32x4){bflo(wa.x), bfhi(wa.x), bflo(wa.y), bfhi(wa.y)}; B += v[j] * (f32x4){bflo(wb.x), bfhi(wb.x), bflo(wb.y), bfhi(wb.y)}; }
; }
; __device__ __forceinline__ void cs_consume(const Prm& P, CStream& S, const LAS bf16_t* wlb, int NGW) {
;     if (S.pend) {
;         int lane; asm volatile("v_mbcnt_lo_u32_b32 %0, -1, 0\n\tv_mbcnt_hi_u32_b32 %0, -1, %0" : "=v"(lane));
;         const int b = S.tk >> 7, p = S.tk & 127;
;         bf16_t* dst = (bf16_t*)(P.ws + WS_KCS) + (size_t)b * 1024 * 256;
;         if (S.pend == 1) {
;             f32x4 A0, B0; chunk_ab(S.v, wlb, lane, A0, B0);
;             if (S.i >= 1) { const int n = 8 * p + S.i - 1; if (n < 1023) { const f32x4 s = S.Aprev + B0; st8_pl(dst + (size_t)n * 256 + 4 * lane, pk2(s[0], s[1]), pk2(s[2], s[3])); } }
;             S.Aprev = A0;
;         }
.LBB0_1215:
	s_cmp_eq_u32 s38, 0
	s_waitcnt vmcnt(0)
	s_cbranch_scc1 .LBB0_1227
	s_ashr_i32 s2, s62, 7
	s_ashr_i32 s3, s2, 31
	s_and_b32 s4, s62, 0x7f
	s_lshl_b64 s[2:3], s[2:3], 19
	s_add_u32 s2, s63, s2
	s_addc_u32 s3, s64, s3
	s_cmp_lg_u32 s38, 1
	v_mbcnt_lo_u32_b32 v1, -1, 0
	v_mbcnt_hi_u32_b32 v1, -1, v1
	s_cbranch_scc1 .LBB0_1224
	v_lshl_add_u32 v7, v1, 3, s68
	ds_read2st64_b64 v[2:5], v7 offset1:1
	ds_read2st64_b64 v[10:13], v7 offset0:2 offset1:3
	s_cmp_lt_i32 s60, 1
	s_waitcnt lgkmcnt(1)
	v_lshlrev_b32_e32 v14, 16, v2
	v_and_b32_e32 v15, 0xffff0000, v2
	v_lshlrev_b32_e32 v2, 16, v3
	v_and_b32_e32 v3, 0xffff0000, v3
	v_pk_fma_f32 v[14:15], v[64:65], v[14:15], 0 op_sel_hi:[1,1,0]
	v_pk_fma_f32 v[2:3], v[66:67], v[2:3], 0 op_sel_hi:[1,1,0]
	v_lshlrev_b32_e32 v16, 16, v4
	v_and_b32_e32 v17, 0xffff0000, v4
	v_lshlrev_b32_e32 v4, 16, v5
	v_and_b32_e32 v5, 0xffff0000, v5
	v_pk_fma_f32 v[2:3], v[70:71], v[4:5], v[2:3]
	v_pk_fma_f32 v[4:5], v[68:69], v[16:17], v[14:15]
	s_waitcnt lgkmcnt(0)
	v_lshlrev_b32_e32 v14, 16, v10
	v_and_b32_e32 v15, 0xffff0000, v10
	v_lshlrev_b32_e32 v10, 16, v11
	v_and_b32_e32 v11, 0xffff0000, v11
	v_pk_fma_f32 v[14:15], v[72:73], v[14:15], v[4:5]
	v_pk_fma_f32 v[10:11], v[74:75], v[10:11], v[2:3]
	ds_read2st64_b64 v[2:5], v7 offset0:4 offset1:5
	v_lshlrev_b32_e32 v16, 16, v12
	v_and_b32_e32 v17, 0xffff0000, v12
	v_lshlrev_b32_e32 v12, 16, v13
	v_and_b32_e32 v13, 0xffff0000, v13
	v_pk_fma_f32 v[20:21], v[78:79], v[12:13], v[10:11]
	ds_read2st64_b64 v[10:13], v7 offset0:6 offset1:7
	v_pk_fma_f32 v[14:15], v[76:77], v[16:17], v[14:15]
	s_waitcnt lgkmcnt(1)
	v_lshlrev_b32_e32 v16, 16, v2
	v_and_b32_e32 v17, 0xffff0000, v2
	v_lshlrev_b32_e32 v2, 16, v3
	v_and_b32_e32 v3, 0xffff0000, v3
	v_pk_fma_f32 v[14:15], v[88:89], v[16:17], v[14:15]
	v_pk_fma_f32 v[2:3], v[90:91], v[2:3], v[20:21]
	v_lshlrev_b32_e32 v16, 16, v4
	v_and_b32_e32 v17, 0xffff0000, v4
	v_lshlrev_b32_e32 v4, 16, v5
	v_and_b32_e32 v5, 0xffff0000, v5
	v_pk_fma_f32 v[2:3], v[82:83], v[4:5], v[2:3]
	v_pk_fma_f32 v[4:5], v[80:81], v[16:17], v[14:15]
	s_waitcnt lgkmcnt(0)
	v_lshlrev_b32_e32 v14, 16, v10
	v_and_b32_e32 v15, 0xffff0000, v10
	v_lshlrev_b32_e32 v10, 16, v11
	v_and_b32_e32 v11, 0xffff0000, v11
	v_pk_fma_f32 v[14:15], v[84:85], v[14:15], v[4:5]
	v_pk_fma_f32 v[10:11], v[86:87], v[10:11], v[2:3]
	ds_read2st64_b64 v[2:5], v7 offset0:8 offset1:9
	v_lshlrev_b32_e32 v16, 16, v12
	v_and_b32_e32 v17, 0xffff0000, v12
	v_lshlrev_b32_e32 v12, 16, v13
	v_and_b32_e32 v13, 0xffff0000, v13
	v_pk_fma_f32 v[20:21], v[94:95], v[12:13], v[10:11]
	ds_read2st64_b64 v[10:13], v7 offset0:10 offset1:11
	v_pk_fma_f32 v[14:15], v[92:93], v[16:17], v[14:15]
	s_waitcnt lgkmcnt(1)
	v_lshlrev_b32_e32 v16, 16, v2
	v_and_b32_e32 v17, 0xffff0000, v2
	v_lshlrev_b32_e32 v2, 16, v3
	v_and_b32_e32 v3, 0xffff0000, v3
	v_pk_fma_f32 v[14:15], v[96:97], v[16:17], v[14:15]
	v_pk_fma_f32 v[2:3], v[98:99], v[2:3], v[20:21]
	v_lshlrev_b32_e32 v16, 16, v4
	v_and_b32_e32 v17, 0xffff0000, v4
	v_lshlrev_b32_e32 v4, 16, v5
	v_and_b32_e32 v5, 0xffff0000, v5
	v_pk_fma_f32 v[2:3], v[102:103], v[4:5], v[2:3]
	v_pk_fma_f32 v[4:5], v[100:101], v[16:17], v[14:15]
	s_waitcnt lgkmcnt(0)
	v_lshlrev_b32_e32 v14, 16, v10
	v_and_b32_e32 v15, 0xffff0000, v10
	v_lshlrev_b32_e32 v10, 16, v11
	v_and_b32_e32 v11, 0xffff0000, v11
	v_pk_fma_f32 v[14:15], v[104:105], v[14:15], v[4:5]
	v_pk_fma_f32 v[10:11], v[106:107], v[10:11], v[2:3]
	ds_read2st64_b64 v[2:5], v7 offset0:12 offset1:13
	v_lshlrev_b32_e32 v16, 16, v12
	v_and_b32_e32 v17, 0xffff0000, v12
	v_lshlrev_b32_e32 v12, 16, v13
	v_and_b32_e32 v13, 0xffff0000, v13
	v_pk_fma_f32 v[20:21], v[110:111], v[12:13], v[10:11]
	ds_read2st64_b64 v[10:13], v7 offset0:14 offset1:15
	v_pk_fma_f32 v[14:15], v[108:109], v[16:17], v[14:15]
	s_waitcnt lgkmcnt(1)
	v_lshlrev_b32_e32 v16, 16, v2
	v_and_b32_e32 v17, 0xffff0000, v2
	v_lshlrev_b32_e32 v2, 16, v3
	v_and_b32_e32 v3, 0xffff0000, v3
	v_pk_fma_f32 v[14:15], v[112:113], v[16:17], v[14:15]
	v_pk_fma_f32 v[2:3], v[114:115], v[2:3], v[20:21]
	v_lshlrev_b32_e32 v16, 16, v4
	v_and_b32_e32 v17, 0xffff0000, v4
	v_lshlrev_b32_e32 v4, 16, v5
	v_and_b32_e32 v5, 0xffff0000, v5
	v_pk_fma_f32 v[2:3], v[118:119], v[4:5], v[2:3]
	v_pk_fma_f32 v[4:5], v[116:117], v[16:17], v[14:15]
	s_waitcnt lgkmcnt(0)
	v_lshlrev_b32_e32 v14, 16, v10
	v_and_b32_e32 v15, 0xffff0000, v10
	v_lshlrev_b32_e32 v10, 16, v11
	v_and_b32_e32 v11, 0xffff0000, v11
	v_pk_fma_f32 v[14:15], v[120:121], v[14:15], v[4:5]
	v_pk_fma_f32 v[2:3], v[122:123], v[10:11], v[2:3]
	v_lshlrev_b32_e32 v10, 16, v12
	v_and_b32_e32 v11, 0xffff0000, v12
	v_lshlrev_b32_e32 v4, 16, v13
	v_and_b32_e32 v5, 0xffff0000, v13
	v_pk_fma_f32 v[4:5], v[126:127], v[4:5], v[2:3]
	v_pk_fma_f32 v[2:3], v[124:125], v[10:11], v[14:15]
	s_cbranch_scc1 .LBB0_1220
	s_lshl_b32 s5, s4, 3
	s_add_i32 s5, s5, s60
	s_cmpk_gt_u32 s5, 0x3ff
	s_cbranch_scc1 .LBB0_1220
; #define LAS __attribute__((address_space(3)))
; __device__ __forceinline__ unsigned pk2(float lo, float hi) { return f2bf(lo) | (f2bf(hi) << 16); }
; __device__ __forceinline__ void chunk_ab(const f32x4 (&v)[16], const LAS bf16_t* wl, int lane, f32x4& A, f32x4& B) {
;     A = (f32x4){0.f, 0.f, 0.f, 0.f}; B = A;
;     const LAS bf16_t* wlane = wl + 4 * lane; asm volatile("" : "+v"(wlane));
; #pragma unroll
;     for (int j = 0; j < 16; ++j) { const u32x2 wa = *(const LAS u32x2*)(wlane + j * 256), wb = *(const LAS u32x2*)(wlane + (16 + j) * 256);
;         A += v[j] * (f32x4){bflo(wa.x), bfhi(wa.x), bflo(wa.y), bfhi(wa.y)}; B += v[j] * (f32x4){bflo(wb.x), bfhi(wb.x), bflo(wb.y), bfhi(wb.y)}; }
; }
; __device__ __forceinline__ void cs_consume(const Prm& P, CStream& S, const LAS bf16_t* wlb, int NGW) {
;     ...
;         if (S.pend == 1) {
;             f32x4 A0, B0; chunk_ab(S.v, wlb, lane, A0, B0);
;             if (S.i >= 1) { const int n = 8 * p + S.i - 1; if (n < 1023) { const f32x4 s = S.Aprev + B0; st8_pl(dst + (size_t)n * 256 + 4 * lane, pk2(s[0], s[1]), pk2(s[2], s[3])); } }
;             S.Aprev = A0;
	ds_read2st64_b64 v[10:13], v7 offset0:16 offset1:17
	ds_read2st64_b64 v[14:17], v7 offset0:18 offset1:19
	ds_read2st64_b64 v[20:23], v7 offset0:20 offset1:21
	ds_read2st64_b64 v[24:27], v7 offset0:22 offset1:23
	ds_read2st64_b64 v[28:31], v7 offset0:24 offset1:25
	ds_read2st64_b64 v[32:35], v7 offset0:26 offset1:27
	ds_read2st64_b64 v[36:39], v7 offset0:28 offset1:29
	ds_read2st64_b64 v[40:43], v7 offset0:30 offset1:31
	s_waitcnt lgkmcnt(7)
	v_lshlrev_b32_e32 v44, 16, v10
	v_and_b32_e32 v45, 0xffff0000, v10
	v_lshlrev_b32_e32 v10, 16, v11
	v_and_b32_e32 v11, 0xffff0000, v11
	v_pk_fma_f32 v[10:11], v[66:67], v[10:11], 0 op_sel_hi:[1,1,0]
	v_pk_fma_f32 v[44:45], v[64:65], v[44:45], 0 op_sel_hi:[1,1,0]
	v_lshlrev_b32_e32 v46, 16, v12
	v_and_b32_e32 v47, 0xffff0000, v12
	v_lshlrev_b32_e32 v12, 16, v13
	v_and_b32_e32 v13, 0xffff0000, v13
	v_pk_fma_f32 v[44:45], v[68:69], v[46:47], v[44:45]
	v_pk_fma_f32 v[10:11], v[70:71], v[12:13], v[10:11]
	s_waitcnt lgkmcnt(6)
	v_lshlrev_b32_e32 v12, 16, v14
	v_and_b32_e32 v13, 0xffff0000, v14
	v_lshlrev_b32_e32 v14, 16, v15
	v_and_b32_e32 v15, 0xffff0000, v15
	v_pk_fma_f32 v[10:11], v[74:75], v[14:15], v[10:11]
	v_pk_fma_f32 v[12:13], v[72:73], v[12:13], v[44:45]
	v_lshlrev_b32_e32 v14, 16, v16
	v_and_b32_e32 v15, 0xffff0000, v16
	v_pk_fma_f32 v[12:13], v[76:77], v[14:15], v[12:13]
	s_waitcnt lgkmcnt(5)
	v_lshlrev_b32_e32 v14, 16, v20
	v_and_b32_e32 v15, 0xffff0000, v20
	v_pk_fma_f32 v[12:13], v[88:89], v[14:15], v[12:13]
	v_lshlrev_b32_e32 v14, 16, v22
	v_and_b32_e32 v15, 0xffff0000, v22
	v_lshlrev_b32_e32 v16, 16, v17
	v_and_b32_e32 v17, 0xffff0000, v17
	v_pk_fma_f32 v[12:13], v[80:81], v[14:15], v[12:13]
	s_waitcnt lgkmcnt(4)
	v_lshlrev_b32_e32 v14, 16, v24
	v_and_b32_e32 v15, 0xffff0000, v24
	v_pk_fma_f32 v[10:11], v[78:79], v[16:17], v[10:11]
	v_lshlrev_b32_e32 v16, 16, v21
	v_and_b32_e32 v17, 0xffff0000, v21
	v_pk_fma_f32 v[12:13], v[84:85], v[14:15], v[12:13]
	v_lshlrev_b32_e32 v14, 16, v26
	v_and_b32_e32 v15, 0xffff0000, v26
	v_pk_fma_f32 v[10:11], v[90:91], v[16:17], v[10:11]
	v_lshlrev_b32_e32 v16, 16, v23
	v_and_b32_e32 v17, 0xffff0000, v23
	v_pk_fma_f32 v[12:13], v[92:93], v[14:15], v[12:13]
	s_waitcnt lgkmcnt(3)
	v_lshlrev_b32_e32 v14, 16, v28
	v_and_b32_e32 v15, 0xffff0000, v28
	v_pk_fma_f32 v[10:11], v[82:83], v[16:17], v[10:11]
	v_lshlrev_b32_e32 v16, 16, v25
	v_and_b32_e32 v17, 0xffff0000, v25
	v_pk_fma_f32 v[12:13], v[96:97], v[14:15], v[12:13]
	v_lshlrev_b32_e32 v14, 16, v30
	v_and_b32_e32 v15, 0xffff0000, v30
	v_pk_fma_f32 v[10:11], v[86:87], v[16:17], v[10:11]
	v_lshlrev_b32_e32 v16, 16, v27
	v_and_b32_e32 v17, 0xffff0000, v27
	v_pk_fma_f32 v[12:13], v[100:101], v[14:15], v[12:13]
	s_waitcnt lgkmcnt(2)
	v_lshlrev_b32_e32 v14, 16, v32
	v_and_b32_e32 v15, 0xffff0000, v32
	v_pk_fma_f32 v[10:11], v[94:95], v[16:17], v[10:11]
	v_lshlrev_b32_e32 v16, 16, v29
	v_and_b32_e32 v17, 0xffff0000, v29
	v_pk_fma_f32 v[12:13], v[104:105], v[14:15], v[12:13]
	v_lshlrev_b32_e32 v14, 16, v34
	v_and_b32_e32 v15, 0xffff0000, v34
	v_pk_fma_f32 v[10:11], v[98:99], v[16:17], v[10:11]
	v_lshlrev_b32_e32 v16, 16, v31
	v_and_b32_e32 v17, 0xffff0000, v31
	v_pk_fma_f32 v[12:13], v[108:109], v[14:15], v[12:13]
	s_waitcnt lgkmcnt(1)
	v_lshlrev_b32_e32 v14, 16, v36
	v_and_b32_e32 v15, 0xffff0000, v36
	v_pk_fma_f32 v[10:11], v[102:103], v[16:17], v[10:11]
	v_lshlrev_b32_e32 v16, 16, v33
	v_and_b32_e32 v17, 0xffff0000, v33
	v_pk_fma_f32 v[12:13], v[112:113], v[14:15], v[12:13]
	v_lshlrev_b32_e32 v14, 16, v38
	v_and_b32_e32 v15, 0xffff0000, v38
	v_pk_fma_f32 v[10:11], v[106:107], v[16:17], v[10:11]
	v_lshlrev_b32_e32 v16, 16, v35
	v_and_b32_e32 v17, 0xffff0000, v35
	v_pk_fma_f32 v[12:13], v[116:117], v[14:15], v[12:13]
	s_waitcnt lgkmcnt(0)
	v_lshlrev_b32_e32 v14, 16, v40
	v_and_b32_e32 v15, 0xffff0000, v40
	v_pk_fma_f32 v[10:11], v[110:111], v[16:17], v[10:11]
	v_lshlrev_b32_e32 v16, 16, v37
	v_and_b32_e32 v17, 0xffff0000, v37
	v_pk_fma_f32 v[12:13], v[120:121], v[14:15], v[12:13]
	v_lshlrev_b32_e32 v14, 16, v42
	v_and_b32_e32 v15, 0xffff0000, v42
	v_pk_fma_f32 v[10:11], v[114:115], v[16:17], v[10:11]
	v_lshlrev_b32_e32 v16, 16, v39
	v_and_b32_e32 v17, 0xffff0000, v39
	v_pk_fma_f32 v[12:13], v[124:125], v[14:15], v[12:13]
	v_pk_fma_f32 v[10:11], v[118:119], v[16:17], v[10:11]
	v_lshlrev_b32_e32 v16, 16, v41
	v_and_b32_e32 v17, 0xffff0000, v41
	v_pk_add_f32 v[12:13], v[128:129], v[12:13]
	v_pk_fma_f32 v[10:11], v[122:123], v[16:17], v[10:11]
	v_lshlrev_b32_e32 v16, 16, v43
	v_and_b32_e32 v17, 0xffff0000, v43
	v_pk_fma_f32 v[10:11], v[126:127], v[16:17], v[10:11]
	s_add_i32 s38, s5, -1
	v_pk_add_f32 v[10:11], v[130:131], v[10:11]
	s_lshl_b64 s[6:7], s[38:39], 9
	v_cvt_pk_bf16_f32 v12, v12, v13
	s_add_u32 s6, s2, s6
	v_lshlrev_b32_e32 v14, 2, v1
	s_addc_u32 s7, s3, s7
	v_ashrrev_i32_e32 v15, 31, v14
	v_lshl_add_u64 v[14:15], v[14:15], 1, s[6:7]
	v_cvt_pk_bf16_f32 v13, v10, v11
	global_store_dwordx2 v[14:15], v[12:13], off

; #define LAS __attribute__((address_space(3)))
; __device__ __forceinline__ unsigned pk2(float lo, float hi) { return f2bf(lo) | (f2bf(hi) << 16); }
; __device__ __forceinline__ float ex2(float x) { return __builtin_amdgcn_exp2f(x); }
; __device__ __forceinline__ void chunk_ab(const f32x4 (&v)[16], const LAS bf16_t* wl, int lane, f32x4& A, f32x4& B) {
;     A = (f32x4){0.f, 0.f, 0.f, 0.f}; B = A;
;     const LAS bf16_t* wlane = wl + 4 * lane; asm volatile("" : "+v"(wlane));
; #pragma unroll
;     for (int j = 0; j < 16; ++j) { const u32x2 wa = *(const LAS u32x2*)(wlane + j * 256), wb = *(const LAS u32x2*)(wlane + (16 + j) * 256);
;         A += v[j] * (f32x4){bflo(wa.x), bfhi(wa.x), bflo(wa.y), bfhi(wa.y)}; B += v[j] * (f32x4){bflo(wb.x), bfhi(wb.x), bflo(wb.y), bfhi(wb.y)}; }
; }
; __device__ __forceinline__ void cs_consume(const Prm& P, CStream& S, const LAS bf16_t* wlb, int NGW) {
;     if (S.pend) {
;         int lane; asm volatile("v_mbcnt_lo_u32_b32 %0, -1, 0\n\tv_mbcnt_hi_u32_b32 %0, -1, %0" : "=v"(lane));
;         const int b = S.tk >> 7, p = S.tk & 127;
;         bf16_t* dst = (bf16_t*)(P.ws + WS_KCS) + (size_t)b * 1024 * 256;
;         if (S.pend == 1) {
;             f32x4 A0, B0; chunk_ab(S.v, wlb, lane, A0, B0);
;             if (S.i >= 1) { const int n = 8 * p + S.i - 1; if (n < 1023) { const f32x4 s = S.Aprev + B0; st8_pl(dst + (size_t)n * 256 + 4 * lane, pk2(s[0], s[1]), pk2(s[2], s[3])); } }
;             S.Aprev = A0;
; __device__ __forceinline__ void cmp_task_lds(const Prm& P, Ctx& C, int b, int kvh, int tg, CStream& CS, const LAS bf16_t* wlb, const int NGW, bf16x8 (&qnx)[4], int& qnx_tg, const int tg_next) {
;     ...
;     { const float mo = __shfl_xor(m, 32), lo = __shfl_xor(l, 32); const float M = fmaxf(m, mo); l = l * ex2(m - M) + lo * ex2(mo - M); m = M; }
;     const float ml = l > 0.f ? m + __builtin_log2f(l) : 1e30f;
;     cs_consume(P, CS, wlb, NGW);
.LBB0_1244:
	v_and_b32_e32 v2, 64, v217
	v_xor_b32_e32 v1, 32, v217
	v_add_u32_e32 v2, 64, v2
	v_cmp_lt_i32_e32 vcc, v1, v2
	s_nop 1
	v_cndmask_b32_e32 v1, v217, v1, vcc
	v_lshlrev_b32_e32 v1, 2, v1
	ds_bpermute_b32 v8, v1, v21
	ds_bpermute_b32 v7, v1, v20
	s_and_b64 vcc, exec, s[2:3]
	s_cbranch_vccz .LBB0_1256
	s_ashr_i32 s0, s62, 7
	s_ashr_i32 s1, s0, 31
	s_and_b32 s2, s62, 0x7f
	s_lshl_b64 s[0:1], s[0:1], 19
	s_add_u32 s0, s63, s0
	s_addc_u32 s1, s64, s1
	s_andn2_b64 vcc, exec, s[4:5]
	v_mbcnt_lo_u32_b32 v1, -1, 0
	v_mbcnt_hi_u32_b32 v1, -1, v1
	s_cbranch_vccnz .LBB0_1253
	v_lshl_add_u32 v6, v1, 3, s68
	ds_read2st64_b64 v[2:5], v6 offset1:1
	ds_read2st64_b64 v[10:13], v6 offset0:2 offset1:3
	s_cmp_lt_i32 s60, 1
	s_waitcnt lgkmcnt(1)
	v_lshlrev_b32_e32 v14, 16, v2
	v_and_b32_e32 v15, 0xffff0000, v2
	v_lshlrev_b32_e32 v2, 16, v3
	v_and_b32_e32 v3, 0xffff0000, v3
	s_waitcnt vmcnt(16)
	v_pk_fma_f32 v[14:15], v[64:65], v[14:15], 0 op_sel_hi:[1,1,0]
	v_pk_fma_f32 v[2:3], v[66:67], v[2:3], 0 op_sel_hi:[1,1,0]
	v_lshlrev_b32_e32 v16, 16, v4
	v_and_b32_e32 v17, 0xffff0000, v4
	v_lshlrev_b32_e32 v4, 16, v5
	v_and_b32_e32 v5, 0xffff0000, v5
	s_waitcnt vmcnt(15)
	v_pk_fma_f32 v[2:3], v[70:71], v[4:5], v[2:3]
	v_pk_fma_f32 v[4:5], v[68:69], v[16:17], v[14:15]
	s_waitcnt lgkmcnt(0)
	v_lshlrev_b32_e32 v14, 16, v10
	v_and_b32_e32 v15, 0xffff0000, v10
	v_lshlrev_b32_e32 v10, 16, v11
	v_and_b32_e32 v11, 0xffff0000, v11
	s_waitcnt vmcnt(14)
	v_pk_fma_f32 v[14:15], v[72:73], v[14:15], v[4:5]
	v_pk_fma_f32 v[10:11], v[74:75], v[10:11], v[2:3]
	ds_read2st64_b64 v[2:5], v6 offset0:4 offset1:5
	v_lshlrev_b32_e32 v16, 16, v12
	v_and_b32_e32 v17, 0xffff0000, v12
	v_lshlrev_b32_e32 v12, 16, v13
	v_and_b32_e32 v13, 0xffff0000, v13
	s_waitcnt vmcnt(13)
	v_pk_fma_f32 v[24:25], v[78:79], v[12:13], v[10:11]
	ds_read2st64_b64 v[10:13], v6 offset0:6 offset1:7
	v_pk_fma_f32 v[14:15], v[76:77], v[16:17], v[14:15]
	s_waitcnt lgkmcnt(1)
	v_lshlrev_b32_e32 v16, 16, v2
	v_and_b32_e32 v17, 0xffff0000, v2
	v_lshlrev_b32_e32 v2, 16, v3
	v_and_b32_e32 v3, 0xffff0000, v3
	s_waitcnt vmcnt(12)
	v_pk_fma_f32 v[14:15], v[88:89], v[16:17], v[14:15]
	v_pk_fma_f32 v[2:3], v[90:91], v[2:3], v[24:25]
	v_lshlrev_b32_e32 v16, 16, v4
	v_and_b32_e32 v17, 0xffff0000, v4
	v_lshlrev_b32_e32 v4, 16, v5
	v_and_b32_e32 v5, 0xffff0000, v5
	s_waitcnt vmcnt(11)
	v_pk_fma_f32 v[2:3], v[82:83], v[4:5], v[2:3]
	v_pk_fma_f32 v[4:5], v[80:81], v[16:17], v[14:15]
	s_waitcnt lgkmcnt(0)
	v_lshlrev_b32_e32 v14, 16, v10
	v_and_b32_e32 v15, 0xffff0000, v10
	v_lshlrev_b32_e32 v10, 16, v11
	v_and_b32_e32 v11, 0xffff0000, v11
	s_waitcnt vmcnt(10)
	v_pk_fma_f32 v[14:15], v[84:85], v[14:15], v[4:5]
	v_pk_fma_f32 v[10:11], v[86:87], v[10:11], v[2:3]
	ds_read2st64_b64 v[2:5], v6 offset0:8 offset1:9
	v_lshlrev_b32_e32 v16, 16, v12
	v_and_b32_e32 v17, 0xffff0000, v12
	v_lshlrev_b32_e32 v12, 16, v13
	v_and_b32_e32 v13, 0xffff0000, v13
	s_waitcnt vmcnt(9)
	v_pk_fma_f32 v[24:25], v[94:95], v[12:13], v[10:11]
	ds_read2st64_b64 v[10:13], v6 offset0:10 offset1:11
	v_pk_fma_f32 v[14:15], v[92:93], v[16:17], v[14:15]
	s_waitcnt lgkmcnt(1)
	v_lshlrev_b32_e32 v16, 16, v2
	v_and_b32_e32 v17, 0xffff0000, v2
	v_lshlrev_b32_e32 v2, 16, v3
	v_and_b32_e32 v3, 0xffff0000, v3
	s_waitcnt vmcnt(8)
	v_pk_fma_f32 v[14:15], v[96:97], v[16:17], v[14:15]
	v_pk_fma_f32 v[2:3], v[98:99], v[2:3], v[24:25]
	v_lshlrev_b32_e32 v16, 16, v4
	v_and_b32_e32 v17, 0xffff0000, v4
	v_lshlrev_b32_e32 v4, 16, v5
	v_and_b32_e32 v5, 0xffff0000, v5
	s_waitcnt vmcnt(7)
	v_pk_fma_f32 v[2:3], v[102:103], v[4:5], v[2:3]
	v_pk_fma_f32 v[4:5], v[100:101], v[16:17], v[14:15]
	s_waitcnt lgkmcnt(0)
	v_lshlrev_b32_e32 v14, 16, v10
	v_and_b32_e32 v15, 0xffff0000, v10
	v_lshlrev_b32_e32 v10, 16, v11
	v_and_b32_e32 v11, 0xffff0000, v11
	s_waitcnt vmcnt(6)
	v_pk_fma_f32 v[14:15], v[104:105], v[14:15], v[4:5]
	v_pk_fma_f32 v[10:11], v[106:107], v[10:11], v[2:3]
	ds_read2st64_b64 v[2:5], v6 offset0:12 offset1:13
	v_lshlrev_b32_e32 v16, 16, v12
	v_and_b32_e32 v17, 0xffff0000, v12
	v_lshlrev_b32_e32 v12, 16, v13
	v_and_b32_e32 v13, 0xffff0000, v13
	s_waitcnt vmcnt(5)
	v_pk_fma_f32 v[24:25], v[110:111], v[12:13], v[10:11]
	ds_read2st64_b64 v[10:13], v6 offset0:14 offset1:15
	v_pk_fma_f32 v[14:15], v[108:109], v[16:17], v[14:15]
	s_waitcnt lgkmcnt(1)
	v_lshlrev_b32_e32 v16, 16, v2
	v_and_b32_e32 v17, 0xffff0000, v2
	v_lshlrev_b32_e32 v2, 16, v3
	v_and_b32_e32 v3, 0xffff0000, v3
	s_waitcnt vmcnt(4)
	v_pk_fma_f32 v[14:15], v[112:113], v[16:17], v[14:15]
	v_pk_fma_f32 v[2:3], v[114:115], v[2:3], v[24:25]
	v_lshlrev_b32_e32 v16, 16, v4
	v_and_b32_e32 v17, 0xffff0000, v4
	v_lshlrev_b32_e32 v4, 16, v5
	v_and_b32_e32 v5, 0xffff0000, v5
	s_waitcnt vmcnt(3)
	v_pk_fma_f32 v[2:3], v[118:119], v[4:5], v[2:3]
	v_pk_fma_f32 v[4:5], v[116:117], v[16:17], v[14:15]
	s_waitcnt lgkmcnt(0)
	v_lshlrev_b32_e32 v14, 16, v10
	v_and_b32_e32 v15, 0xffff0000, v10
	v_lshlrev_b32_e32 v10, 16, v11
	v_and_b32_e32 v11, 0xffff0000, v11
	s_waitcnt vmcnt(2)
	v_pk_fma_f32 v[14:15], v[120:121], v[14:15], v[4:5]
	v_pk_fma_f32 v[2:3], v[122:123], v[10:11], v[2:3]
	v_lshlrev_b32_e32 v10, 16, v12
	v_and_b32_e32 v11, 0xffff0000, v12
	v_lshlrev_b32_e32 v4, 16, v13
	v_and_b32_e32 v5, 0xffff0000, v13
	s_waitcnt vmcnt(1)
	v_pk_fma_f32 v[4:5], v[126:127], v[4:5], v[2:3]
	v_pk_fma_f32 v[2:3], v[124:125], v[10:11], v[14:15]
	s_cbranch_scc1 .LBB0_1249
; #define LAS __attribute__((address_space(3)))
; __device__ __forceinline__ unsigned pk2(float lo, float hi) { return f2bf(lo) | (f2bf(hi) << 16); }
; __device__ __forceinline__ void chunk_ab(const f32x4 (&v)[16], const LAS bf16_t* wl, int lane, f32x4& A, f32x4& B) {
;     A = (f32x4){0.f, 0.f, 0.f, 0.f}; B = A;
;     const LAS bf16_t* wlane = wl + 4 * lane; asm volatile("" : "+v"(wlane));
; #pragma unroll
;     for (int j = 0; j < 16; ++j) { const u32x2 wa = *(const LAS u32x2*)(wlane + j * 256), wb = *(const LAS u32x2*)(wlane + (16 + j) * 256);
;         A += v[j] * (f32x4){bflo(wa.x), bfhi(wa.x), bflo(wa.y), bfhi(wa.y)}; B += v[j] * (f32x4){bflo(wb.x), bfhi(wb.x), bflo(wb.y), bfhi(wb.y)}; }
; }
; __device__ __forceinline__ void cs_consume(const Prm& P, CStream& S, const LAS bf16_t* wlb, int NGW) {
;     ...
;         if (S.pend == 1) {
;             f32x4 A0, B0; chunk_ab(S.v, wlb, lane, A0, B0);
;             if (S.i >= 1) { const int n = 8 * p + S.i - 1; if (n < 1023) { const f32x4 s = S.Aprev + B0; st8_pl(dst + (size_t)n * 256 + 4 * lane, pk2(s[0], s[1]), pk2(s[2], s[3])); } }
;             S.Aprev = A0;
	s_lshl_b32 s3, s2, 3
	s_add_i32 s3, s3, s60
	s_cmpk_gt_u32 s3, 0x3ff
	s_cbranch_scc1 .LBB0_1249
	ds_read2st64_b64 v[10:13], v6 offset0:16 offset1:17
	ds_read2st64_b64 v[14:17], v6 offset0:18 offset1:19
	ds_read2st64_b64 v[24:27], v6 offset0:20 offset1:21
	ds_read2st64_b64 v[28:31], v6 offset0:22 offset1:23
	ds_read2st64_b64 v[32:35], v6 offset0:24 offset1:25
	ds_read2st64_b64 v[36:39], v6 offset0:26 offset1:27
	ds_read2st64_b64 v[40:43], v6 offset0:28 offset1:29
	ds_read2st64_b64 v[44:47], v6 offset0:30 offset1:31
	s_waitcnt lgkmcnt(7)
	v_lshlrev_b32_e32 v48, 16, v10
	v_and_b32_e32 v49, 0xffff0000, v10
	v_lshlrev_b32_e32 v10, 16, v11
	v_and_b32_e32 v11, 0xffff0000, v11
	v_pk_fma_f32 v[10:11], v[66:67], v[10:11], 0 op_sel_hi:[1,1,0]
	v_pk_fma_f32 v[48:49], v[64:65], v[48:49], 0 op_sel_hi:[1,1,0]
	v_lshlrev_b32_e32 v50, 16, v12
	v_and_b32_e32 v51, 0xffff0000, v12
	v_lshlrev_b32_e32 v12, 16, v13
	v_and_b32_e32 v13, 0xffff0000, v13
	v_pk_fma_f32 v[48:49], v[68:69], v[50:51], v[48:49]
	v_pk_fma_f32 v[10:11], v[70:71], v[12:13], v[10:11]
	s_waitcnt lgkmcnt(6)
	v_lshlrev_b32_e32 v12, 16, v14
	v_and_b32_e32 v13, 0xffff0000, v14
	v_lshlrev_b32_e32 v14, 16, v15
	v_and_b32_e32 v15, 0xffff0000, v15
	v_pk_fma_f32 v[10:11], v[74:75], v[14:15], v[10:11]
	v_pk_fma_f32 v[12:13], v[72:73], v[12:13], v[48:49]
	v_lshlrev_b32_e32 v14, 16, v16
	v_and_b32_e32 v15, 0xffff0000, v16
	v_pk_fma_f32 v[12:13], v[76:77], v[14:15], v[12:13]
	s_waitcnt lgkmcnt(5)
	v_lshlrev_b32_e32 v14, 16, v24
	v_and_b32_e32 v15, 0xffff0000, v24
	v_pk_fma_f32 v[12:13], v[88:89], v[14:15], v[12:13]
	v_lshlrev_b32_e32 v14, 16, v26
	v_and_b32_e32 v15, 0xffff0000, v26
	v_lshlrev_b32_e32 v16, 16, v17
	v_and_b32_e32 v17, 0xffff0000, v17
	v_pk_fma_f32 v[12:13], v[80:81], v[14:15], v[12:13]
	s_waitcnt lgkmcnt(4)
	v_lshlrev_b32_e32 v14, 16, v28
	v_and_b32_e32 v15, 0xffff0000, v28
	v_pk_fma_f32 v[10:11], v[78:79], v[16:17], v[10:11]
	v_lshlrev_b32_e32 v16, 16, v25
	v_and_b32_e32 v17, 0xffff0000, v25
	v_pk_fma_f32 v[12:13], v[84:85], v[14:15], v[12:13]
	v_lshlrev_b32_e32 v14, 16, v30
	v_and_b32_e32 v15, 0xffff0000, v30
	v_pk_fma_f32 v[10:11], v[90:91], v[16:17], v[10:11]
	v_lshlrev_b32_e32 v16, 16, v27
	v_and_b32_e32 v17, 0xffff0000, v27
	v_pk_fma_f32 v[12:13], v[92:93], v[14:15], v[12:13]
	s_waitcnt lgkmcnt(3)
	v_lshlrev_b32_e32 v14, 16, v32
	v_and_b32_e32 v15, 0xffff0000, v32
	v_pk_fma_f32 v[10:11], v[82:83], v[16:17], v[10:11]
	v_lshlrev_b32_e32 v16, 16, v29
	v_and_b32_e32 v17, 0xffff0000, v29
	v_pk_fma_f32 v[12:13], v[96:97], v[14:15], v[12:13]
	v_lshlrev_b32_e32 v14, 16, v34
	v_and_b32_e32 v15, 0xffff0000, v34
	v_pk_fma_f32 v[10:11], v[86:87], v[16:17], v[10:11]
	v_lshlrev_b32_e32 v16, 16, v31
	v_and_b32_e32 v17, 0xffff0000, v31
	v_pk_fma_f32 v[12:13], v[100:101], v[14:15], v[12:13]
	s_waitcnt lgkmcnt(2)
	v_lshlrev_b32_e32 v14, 16, v36
	v_and_b32_e32 v15, 0xffff0000, v36
	v_pk_fma_f32 v[10:11], v[94:95], v[16:17], v[10:11]
	v_lshlrev_b32_e32 v16, 16, v33
	v_and_b32_e32 v17, 0xffff0000, v33
	v_pk_fma_f32 v[12:13], v[104:105], v[14:15], v[12:13]
	v_lshlrev_b32_e32 v14, 16, v38
	v_and_b32_e32 v15, 0xffff0000, v38
	v_pk_fma_f32 v[10:11], v[98:99], v[16:17], v[10:11]
	v_lshlrev_b32_e32 v16, 16, v35
	v_and_b32_e32 v17, 0xffff0000, v35
	v_pk_fma_f32 v[12:13], v[108:109], v[14:15], v[12:13]
	s_waitcnt lgkmcnt(1)
	v_lshlrev_b32_e32 v14, 16, v40
	v_and_b32_e32 v15, 0xffff0000, v40
	v_pk_fma_f32 v[10:11], v[102:103], v[16:17], v[10:11]
	v_lshlrev_b32_e32 v16, 16, v37
	v_and_b32_e32 v17, 0xffff0000, v37
	v_pk_fma_f32 v[12:13], v[112:113], v[14:15], v[12:13]
	v_lshlrev_b32_e32 v14, 16, v42
	v_and_b32_e32 v15, 0xffff0000, v42
	v_pk_fma_f32 v[10:11], v[106:107], v[16:17], v[10:11]
	v_lshlrev_b32_e32 v16, 16, v39
	v_and_b32_e32 v17, 0xffff0000, v39
	v_pk_fma_f32 v[12:13], v[116:117], v[14:15], v[12:13]
	s_waitcnt lgkmcnt(0)
	v_lshlrev_b32_e32 v14, 16, v44
	v_and_b32_e32 v15, 0xffff0000, v44
	v_pk_fma_f32 v[10:11], v[110:111], v[16:17], v[10:11]
	v_lshlrev_b32_e32 v16, 16, v41
	v_and_b32_e32 v17, 0xffff0000, v41
	v_pk_fma_f32 v[12:13], v[120:121], v[14:15], v[12:13]
	v_lshlrev_b32_e32 v14, 16, v46
	v_and_b32_e32 v15, 0xffff0000, v46
	v_pk_fma_f32 v[10:11], v[114:115], v[16:17], v[10:11]
	v_lshlrev_b32_e32 v16, 16, v43
	v_and_b32_e32 v17, 0xffff0000, v43
	v_pk_fma_f32 v[12:13], v[124:125], v[14:15], v[12:13]
	v_pk_fma_f32 v[10:11], v[118:119], v[16:17], v[10:11]
	v_lshlrev_b32_e32 v16, 16, v45
	v_and_b32_e32 v17, 0xffff0000, v45
	v_pk_add_f32 v[12:13], v[128:129], v[12:13]
	v_pk_fma_f32 v[10:11], v[122:123], v[16:17], v[10:11]
	v_lshlrev_b32_e32 v16, 16, v47
	v_and_b32_e32 v17, 0xffff0000, v47
	v_pk_fma_f32 v[10:11], v[126:127], v[16:17], v[10:11]
	s_add_i32 s38, s3, -1
	v_pk_add_f32 v[10:11], v[130:131], v[10:11]
	s_lshl_b64 s[4:5], s[38:39], 9
	v_cvt_pk_bf16_f32 v12, v12, v13
	s_add_u32 s4, s0, s4
	v_lshlrev_b32_e32 v14, 2, v1
	s_addc_u32 s5, s1, s5
	v_ashrrev_i32_e32 v15, 31, v14
	v_lshl_add_u64 v[14:15], v[14:15], 1, s[4:5]
	v_cvt_pk_bf16_f32 v13, v10, v11
	global_store_dwordx2 v[14:15], v[12:13], off

; #define LAS __attribute__((address_space(3)))
; __device__ __forceinline__ unsigned pk2(float lo, float hi) { return f2bf(lo) | (f2bf(hi) << 16); }
; #define CS_HOOK() do { cs_consume(P, CS, wlb, NGW); cs_issue(P, CS); } while (0)
; __device__ __forceinline__ void chunk_ab(const f32x4 (&v)[16], const LAS bf16_t* wl, int lane, f32x4& A, f32x4& B) {
;     A = (f32x4){0.f, 0.f, 0.f, 0.f}; B = A;
;     const LAS bf16_t* wlane = wl + 4 * lane; asm volatile("" : "+v"(wlane));
; #pragma unroll
;     for (int j = 0; j < 16; ++j) { const u32x2 wa = *(const LAS u32x2*)(wlane + j * 256), wb = *(const LAS u32x2*)(wlane + (16 + j) * 256);
;         A += v[j] * (f32x4){bflo(wa.x), bfhi(wa.x), bflo(wa.y), bfhi(wa.y)}; B += v[j] * (f32x4){bflo(wb.x), bfhi(wb.x), bflo(wb.y), bfhi(wb.y)}; }
; }
; __device__ __forceinline__ void cs_consume(const Prm& P, CStream& S, const LAS bf16_t* wlb, int NGW) {
;     if (S.pend) {
;         int lane; asm volatile("v_mbcnt_lo_u32_b32 %0, -1, 0\n\tv_mbcnt_hi_u32_b32 %0, -1, %0" : "=v"(lane));
;         const int b = S.tk >> 7, p = S.tk & 127;
;         bf16_t* dst = (bf16_t*)(P.ws + WS_KCS) + (size_t)b * 1024 * 256;
;         if (S.pend == 1) {
;             f32x4 A0, B0; chunk_ab(S.v, wlb, lane, A0, B0);
;             if (S.i >= 1) { const int n = 8 * p + S.i - 1; if (n < 1023) { const f32x4 s = S.Aprev + B0; st8_pl(dst + (size_t)n * 256 + 4 * lane, pk2(s[0], s[1]), pk2(s[2], s[3])); } }
;             S.Aprev = A0;
; __device__ __forceinline__ void cmp_task_lds(const Prm& P, Ctx& C, int b, int kvh, int tg, CStream& CS, const LAS bf16_t* wlb, const int NGW, bf16x8 (&qnx)[4], int& qnx_tg, const int tg_next) {
;     ...
;     for (int k4 = 0; k4 < 4; ++k4) {
;         if (4 * k4 < ntile) CS_HOOK();
;     ...
;         for (int i = 0; i < 4; ++i) { scr[0][i] = scr[1][i]; scr[1][i] = scr[2][i]; scr[2][i] = scr[3][i]; scr[3][i] = cur4[i]; }
.LBB0_1262:
	v_mov_b32_e32 v241, v235
	v_mov_b32_e32 v240, v234
	v_mov_b32_e32 v15, v233
	v_mov_b32_e32 v14, v236
	v_mov_b32_e32 v235, v205
	v_mov_b32_e32 v234, v204
	v_mov_b32_e32 v233, v207
	s_cmp_ge_i32 s12, s10
	v_mov_b32_e32 v236, v206
	s_cbranch_scc1 .LBB0_1272
	s_cmp_eq_u32 s38, 0
	s_cbranch_scc1 .LBB0_1276
	s_ashr_i32 s8, s62, 7
	s_ashr_i32 s9, s8, 31
	s_and_b32 s14, s62, 0x7f
	s_lshl_b64 s[8:9], s[8:9], 19
	s_add_u32 s8, s63, s8
	s_addc_u32 s9, s64, s9
	s_cmp_lg_u32 s38, 1
	v_mbcnt_lo_u32_b32 v1, -1, 0
	v_mbcnt_hi_u32_b32 v1, -1, v1
	s_cbranch_scc1 .LBB0_1273
	v_lshl_add_u32 v6, v1, 3, s68
	ds_read2st64_b64 v[2:5], v6 offset1:1
	ds_read2st64_b64 v[8:11], v6 offset0:2 offset1:3
	s_cmp_lt_i32 s60, 1
	s_waitcnt lgkmcnt(1)
	v_lshlrev_b32_e32 v12, 16, v2
	v_and_b32_e32 v13, 0xffff0000, v2
	v_lshlrev_b32_e32 v2, 16, v3
	v_and_b32_e32 v3, 0xffff0000, v3
	s_waitcnt vmcnt(15)
	v_pk_fma_f32 v[12:13], v[64:65], v[12:13], 0 op_sel_hi:[1,1,0]
	v_pk_fma_f32 v[2:3], v[66:67], v[2:3], 0 op_sel_hi:[1,1,0]
	v_lshlrev_b32_e32 v48, 16, v4
	v_and_b32_e32 v49, 0xffff0000, v4
	v_lshlrev_b32_e32 v4, 16, v5
	v_and_b32_e32 v5, 0xffff0000, v5
	s_waitcnt vmcnt(14)
	v_pk_fma_f32 v[2:3], v[70:71], v[4:5], v[2:3]
	v_pk_fma_f32 v[4:5], v[68:69], v[48:49], v[12:13]
	s_waitcnt lgkmcnt(0)
	v_lshlrev_b32_e32 v12, 16, v8
	v_and_b32_e32 v13, 0xffff0000, v8
	v_lshlrev_b32_e32 v8, 16, v9
	v_and_b32_e32 v9, 0xffff0000, v9
	s_waitcnt vmcnt(13)
	v_pk_fma_f32 v[12:13], v[72:73], v[12:13], v[4:5]
	v_pk_fma_f32 v[8:9], v[74:75], v[8:9], v[2:3]
	ds_read2st64_b64 v[2:5], v6 offset0:4 offset1:5
	v_lshlrev_b32_e32 v48, 16, v10
	v_and_b32_e32 v49, 0xffff0000, v10
	v_lshlrev_b32_e32 v10, 16, v11
	v_and_b32_e32 v11, 0xffff0000, v11
	s_waitcnt vmcnt(12)
	v_pk_fma_f32 v[50:51], v[78:79], v[10:11], v[8:9]
	ds_read2st64_b64 v[8:11], v6 offset0:6 offset1:7
	v_pk_fma_f32 v[12:13], v[76:77], v[48:49], v[12:13]
	s_waitcnt lgkmcnt(1)
	v_lshlrev_b32_e32 v48, 16, v2
	v_and_b32_e32 v49, 0xffff0000, v2
	v_lshlrev_b32_e32 v2, 16, v3
	v_and_b32_e32 v3, 0xffff0000, v3
	s_waitcnt vmcnt(11)
	v_pk_fma_f32 v[12:13], v[88:89], v[48:49], v[12:13]
	v_pk_fma_f32 v[2:3], v[90:91], v[2:3], v[50:51]
	v_lshlrev_b32_e32 v48, 16, v4
	v_and_b32_e32 v49, 0xffff0000, v4
	v_lshlrev_b32_e32 v4, 16, v5
	v_and_b32_e32 v5, 0xffff0000, v5
	s_waitcnt vmcnt(10)
	v_pk_fma_f32 v[2:3], v[82:83], v[4:5], v[2:3]
	v_pk_fma_f32 v[4:5], v[80:81], v[48:49], v[12:13]
	s_waitcnt lgkmcnt(0)
	v_lshlrev_b32_e32 v12, 16, v8
	v_and_b32_e32 v13, 0xffff0000, v8
	v_lshlrev_b32_e32 v8, 16, v9
	v_and_b32_e32 v9, 0xffff0000, v9
	s_waitcnt vmcnt(9)
	v_pk_fma_f32 v[12:13], v[84:85], v[12:13], v[4:5]
	v_pk_fma_f32 v[8:9], v[86:87], v[8:9], v[2:3]
	ds_read2st64_b64 v[2:5], v6 offset0:8 offset1:9
	v_lshlrev_b32_e32 v48, 16, v10
	v_and_b32_e32 v49, 0xffff0000, v10
	v_lshlrev_b32_e32 v10, 16, v11
	v_and_b32_e32 v11, 0xffff0000, v11
	s_waitcnt vmcnt(8)
	v_pk_fma_f32 v[50:51], v[94:95], v[10:11], v[8:9]
	ds_read2st64_b64 v[8:11], v6 offset0:10 offset1:11
	v_pk_fma_f32 v[12:13], v[92:93], v[48:49], v[12:13]
	s_waitcnt lgkmcnt(1)
	v_lshlrev_b32_e32 v48, 16, v2
	v_and_b32_e32 v49, 0xffff0000, v2
	v_lshlrev_b32_e32 v2, 16, v3
	v_and_b32_e32 v3, 0xffff0000, v3
	s_waitcnt vmcnt(7)
	v_pk_fma_f32 v[12:13], v[96:97], v[48:49], v[12:13]
	v_pk_fma_f32 v[2:3], v[98:99], v[2:3], v[50:51]
	v_lshlrev_b32_e32 v48, 16, v4
	v_and_b32_e32 v49, 0xffff0000, v4
	v_lshlrev_b32_e32 v4, 16, v5
	v_and_b32_e32 v5, 0xffff0000, v5
	s_waitcnt vmcnt(6)
	v_pk_fma_f32 v[2:3], v[102:103], v[4:5], v[2:3]
	v_pk_fma_f32 v[4:5], v[100:101], v[48:49], v[12:13]
	s_waitcnt lgkmcnt(0)
	v_lshlrev_b32_e32 v12, 16, v8
	v_and_b32_e32 v13, 0xffff0000, v8
	v_lshlrev_b32_e32 v8, 16, v9
	v_and_b32_e32 v9, 0xffff0000, v9
	s_waitcnt vmcnt(5)
	v_pk_fma_f32 v[12:13], v[104:105], v[12:13], v[4:5]
	v_pk_fma_f32 v[8:9], v[106:107], v[8:9], v[2:3]
	ds_read2st64_b64 v[2:5], v6 offset0:12 offset1:13
	v_lshlrev_b32_e32 v48, 16, v10
	v_and_b32_e32 v49, 0xffff0000, v10
	v_lshlrev_b32_e32 v10, 16, v11
	v_and_b32_e32 v11, 0xffff0000, v11
	s_waitcnt vmcnt(4)
	v_pk_fma_f32 v[50:51], v[110:111], v[10:11], v[8:9]
	ds_read2st64_b64 v[8:11], v6 offset0:14 offset1:15
	v_pk_fma_f32 v[12:13], v[108:109], v[48:49], v[12:13]
	s_waitcnt lgkmcnt(1)
	v_lshlrev_b32_e32 v48, 16, v2
	v_and_b32_e32 v49, 0xffff0000, v2
	v_lshlrev_b32_e32 v2, 16, v3
	v_and_b32_e32 v3, 0xffff0000, v3
	s_waitcnt vmcnt(3)
	v_pk_fma_f32 v[12:13], v[112:113], v[48:49], v[12:13]
	v_pk_fma_f32 v[2:3], v[114:115], v[2:3], v[50:51]
	v_lshlrev_b32_e32 v48, 16, v4
	v_and_b32_e32 v49, 0xffff0000, v4
	v_lshlrev_b32_e32 v4, 16, v5
	v_and_b32_e32 v5, 0xffff0000, v5
	s_waitcnt vmcnt(2)
	v_pk_fma_f32 v[2:3], v[118:119], v[4:5], v[2:3]
	v_pk_fma_f32 v[4:5], v[116:117], v[48:49], v[12:13]
	s_waitcnt lgkmcnt(0)
	v_lshlrev_b32_e32 v12, 16, v8
	v_and_b32_e32 v13, 0xffff0000, v8
	v_lshlrev_b32_e32 v8, 16, v9
	v_and_b32_e32 v9, 0xffff0000, v9
	s_waitcnt vmcnt(1)
	v_pk_fma_f32 v[12:13], v[120:121], v[12:13], v[4:5]
	v_pk_fma_f32 v[2:3], v[122:123], v[8:9], v[2:3]
	v_lshlrev_b32_e32 v8, 16, v10
	v_and_b32_e32 v9, 0xffff0000, v10
	v_lshlrev_b32_e32 v4, 16, v11
	v_and_b32_e32 v5, 0xffff0000, v11
	s_waitcnt vmcnt(0)
	v_pk_fma_f32 v[4:5], v[126:127], v[4:5], v[2:3]
	v_pk_fma_f32 v[2:3], v[124:125], v[8:9], v[12:13]
	s_cbranch_scc1 .LBB0_1268
; #define LAS __attribute__((address_space(3)))
; __device__ __forceinline__ unsigned pk2(float lo, float hi) { return f2bf(lo) | (f2bf(hi) << 16); }
; __device__ __forceinline__ void chunk_ab(const f32x4 (&v)[16], const LAS bf16_t* wl, int lane, f32x4& A, f32x4& B) {
;     A = (f32x4){0.f, 0.f, 0.f, 0.f}; B = A;
;     const LAS bf16_t* wlane = wl + 4 * lane; asm volatile("" : "+v"(wlane));
; #pragma unroll
;     for (int j = 0; j < 16; ++j) { const u32x2 wa = *(const LAS u32x2*)(wlane + j * 256), wb = *(const LAS u32x2*)(wlane + (16 + j) * 256);
;         A += v[j] * (f32x4){bflo(wa.x), bfhi(wa.x), bflo(wa.y), bfhi(wa.y)}; B += v[j] * (f32x4){bflo(wb.x), bfhi(wb.x), bflo(wb.y), bfhi(wb.y)}; }
; }
; __device__ __forceinline__ void cs_consume(const Prm& P, CStream& S, const LAS bf16_t* wlb, int NGW) {
;     ...
;         if (S.pend == 1) {
;             f32x4 A0, B0; chunk_ab(S.v, wlb, lane, A0, B0);
;             if (S.i >= 1) { const int n = 8 * p + S.i - 1; if (n < 1023) { const f32x4 s = S.Aprev + B0; st8_pl(dst + (size_t)n * 256 + 4 * lane, pk2(s[0], s[1]), pk2(s[2], s[3])); } }
;             S.Aprev = A0;
	s_lshl_b32 s15, s14, 3
	s_add_i32 s15, s15, s60
	s_cmpk_gt_u32 s15, 0x3ff
	s_cbranch_scc1 .LBB0_1268
	ds_read2st64_b64 v[8:11], v6 offset0:16 offset1:17
	ds_read2st64_b64 v[48:51], v6 offset0:18 offset1:19
	ds_read2st64_b64 v[52:55], v6 offset0:20 offset1:21
	ds_read2st64_b64 v[56:59], v6 offset0:22 offset1:23
	ds_read2st64_b64 v[60:63], v6 offset0:24 offset1:25
	ds_read2st64_b64 v[180:183], v6 offset0:26 offset1:27
	ds_read2st64_b64 v[184:187], v6 offset0:28 offset1:29
	ds_read2st64_b64 v[204:207], v6 offset0:30 offset1:31
	s_waitcnt lgkmcnt(7)
	v_lshlrev_b32_e32 v6, 16, v8
	v_and_b32_e32 v7, 0xffff0000, v8
	v_lshlrev_b32_e32 v8, 16, v9
	v_and_b32_e32 v9, 0xffff0000, v9
	v_pk_fma_f32 v[8:9], v[66:67], v[8:9], 0 op_sel_hi:[1,1,0]
	v_pk_fma_f32 v[6:7], v[64:65], v[6:7], 0 op_sel_hi:[1,1,0]
	v_lshlrev_b32_e32 v12, 16, v10
	v_and_b32_e32 v13, 0xffff0000, v10
	v_lshlrev_b32_e32 v10, 16, v11
	v_and_b32_e32 v11, 0xffff0000, v11
	v_pk_fma_f32 v[6:7], v[68:69], v[12:13], v[6:7]
	v_pk_fma_f32 v[8:9], v[70:71], v[10:11], v[8:9]
	s_waitcnt lgkmcnt(6)
	v_lshlrev_b32_e32 v10, 16, v48
	v_and_b32_e32 v11, 0xffff0000, v48
	v_pk_fma_f32 v[6:7], v[72:73], v[10:11], v[6:7]
	v_lshlrev_b32_e32 v10, 16, v50
	v_and_b32_e32 v11, 0xffff0000, v50
	v_lshlrev_b32_e32 v12, 16, v49
	v_and_b32_e32 v13, 0xffff0000, v49
	v_pk_fma_f32 v[6:7], v[76:77], v[10:11], v[6:7]
	s_waitcnt lgkmcnt(5)
	v_lshlrev_b32_e32 v10, 16, v52
	v_and_b32_e32 v11, 0xffff0000, v52
	v_pk_fma_f32 v[8:9], v[74:75], v[12:13], v[8:9]
	v_lshlrev_b32_e32 v12, 16, v51
	v_and_b32_e32 v13, 0xffff0000, v51
	v_pk_fma_f32 v[6:7], v[88:89], v[10:11], v[6:7]
	v_lshlrev_b32_e32 v10, 16, v54
	v_and_b32_e32 v11, 0xffff0000, v54
	v_pk_fma_f32 v[8:9], v[78:79], v[12:13], v[8:9]
	v_lshlrev_b32_e32 v12, 16, v53
	v_and_b32_e32 v13, 0xffff0000, v53
	v_pk_fma_f32 v[6:7], v[80:81], v[10:11], v[6:7]
	s_waitcnt lgkmcnt(4)
	v_lshlrev_b32_e32 v10, 16, v56
	v_and_b32_e32 v11, 0xffff0000, v56
	v_pk_fma_f32 v[8:9], v[90:91], v[12:13], v[8:9]
	v_lshlrev_b32_e32 v12, 16, v55
	v_and_b32_e32 v13, 0xffff0000, v55
	v_pk_fma_f32 v[6:7], v[84:85], v[10:11], v[6:7]
	v_lshlrev_b32_e32 v10, 16, v58
	v_and_b32_e32 v11, 0xffff0000, v58
	v_pk_fma_f32 v[8:9], v[82:83], v[12:13], v[8:9]
	v_lshlrev_b32_e32 v12, 16, v57
	v_and_b32_e32 v13, 0xffff0000, v57
	v_pk_fma_f32 v[6:7], v[92:93], v[10:11], v[6:7]
	s_waitcnt lgkmcnt(3)
	v_lshlrev_b32_e32 v10, 16, v60
	v_and_b32_e32 v11, 0xffff0000, v60
	v_pk_fma_f32 v[8:9], v[86:87], v[12:13], v[8:9]
	v_lshlrev_b32_e32 v12, 16, v59
	v_and_b32_e32 v13, 0xffff0000, v59
	v_pk_fma_f32 v[6:7], v[96:97], v[10:11], v[6:7]
	v_lshlrev_b32_e32 v10, 16, v62
	v_and_b32_e32 v11, 0xffff0000, v62
	v_pk_fma_f32 v[8:9], v[94:95], v[12:13], v[8:9]
	v_lshlrev_b32_e32 v12, 16, v61
	v_and_b32_e32 v13, 0xffff0000, v61
	v_pk_fma_f32 v[6:7], v[100:101], v[10:11], v[6:7]
	s_waitcnt lgkmcnt(2)
	v_lshlrev_b32_e32 v10, 16, v180
	v_and_b32_e32 v11, 0xffff0000, v180
	v_pk_fma_f32 v[8:9], v[98:99], v[12:13], v[8:9]
	v_lshlrev_b32_e32 v12, 16, v63
	v_and_b32_e32 v13, 0xffff0000, v63
	v_pk_fma_f32 v[6:7], v[104:105], v[10:11], v[6:7]
	v_lshlrev_b32_e32 v10, 16, v182
	v_and_b32_e32 v11, 0xffff0000, v182
	v_pk_fma_f32 v[8:9], v[102:103], v[12:13], v[8:9]
	v_lshlrev_b32_e32 v12, 16, v181
	v_and_b32_e32 v13, 0xffff0000, v181
	v_pk_fma_f32 v[6:7], v[108:109], v[10:11], v[6:7]
	s_waitcnt lgkmcnt(1)
	v_lshlrev_b32_e32 v10, 16, v184
	v_and_b32_e32 v11, 0xffff0000, v184
	v_pk_fma_f32 v[8:9], v[106:107], v[12:13], v[8:9]
	v_lshlrev_b32_e32 v12, 16, v183
	v_and_b32_e32 v13, 0xffff0000, v183
	v_pk_fma_f32 v[6:7], v[112:113], v[10:11], v[6:7]
	v_lshlrev_b32_e32 v10, 16, v186
	v_and_b32_e32 v11, 0xffff0000, v186
	v_pk_fma_f32 v[8:9], v[110:111], v[12:13], v[8:9]
	v_lshlrev_b32_e32 v12, 16, v185
	v_and_b32_e32 v13, 0xffff0000, v185
	v_pk_fma_f32 v[6:7], v[116:117], v[10:11], v[6:7]
	s_waitcnt lgkmcnt(0)
	v_lshlrev_b32_e32 v10, 16, v204
	v_and_b32_e32 v11, 0xffff0000, v204
	v_pk_fma_f32 v[8:9], v[114:115], v[12:13], v[8:9]
	v_lshlrev_b32_e32 v12, 16, v187
	v_and_b32_e32 v13, 0xffff0000, v187
	v_pk_fma_f32 v[6:7], v[120:121], v[10:11], v[6:7]
	v_lshlrev_b32_e32 v10, 16, v206
	v_and_b32_e32 v11, 0xffff0000, v206
	v_pk_fma_f32 v[8:9], v[118:119], v[12:13], v[8:9]
	v_lshlrev_b32_e32 v12, 16, v205
	v_and_b32_e32 v13, 0xffff0000, v205
	v_pk_fma_f32 v[6:7], v[124:125], v[10:11], v[6:7]
	v_pk_fma_f32 v[8:9], v[122:123], v[12:13], v[8:9]
	v_lshlrev_b32_e32 v12, 16, v207
	v_and_b32_e32 v13, 0xffff0000, v207
	v_pk_add_f32 v[6:7], v[128:129], v[6:7]
	v_pk_fma_f32 v[8:9], v[126:127], v[12:13], v[8:9]
	s_add_i32 s38, s15, -1
	v_pk_add_f32 v[8:9], v[130:131], v[8:9]
	s_lshl_b64 s[16:17], s[38:39], 9
	v_cvt_pk_bf16_f32 v6, v6, v7
	s_add_u32 s16, s8, s16
	v_lshlrev_b32_e32 v10, 2, v1
	s_addc_u32 s17, s9, s17
	v_ashrrev_i32_e32 v11, 31, v10
	v_lshl_add_u64 v[10:11], v[10:11], 1, s[16:17]
	v_cvt_pk_bf16_f32 v7, v8, v9
	global_store_dwordx2 v[10:11], v[6:7], off

; __device__ __forceinline__ unsigned pk2(float lo, float hi) { return f2bf(lo) | (f2bf(hi) << 16); }
; #define MFMA32(a, b, c) __builtin_amdgcn_mfma_f32_32x32x16_bf16((a), (b), (c), 0, 0, 0)
; __device__ __forceinline__ float quad_sum(float v) { v += __int_as_float(dpp_x1(__float_as_int(v))); v += __int_as_float(dpp_x2(__float_as_int(v))); return v; }
; __device__ __forceinline__ bf16x8 pack8(const f32x16& p, int base) {
;     u32x4 w; w.x = pk2(p[base + 0], p[base + 1]); w.y = pk2(p[base + 2], p[base + 3]); w.z = pk2(p[base + 4], p[base + 5]); w.w = pk2(p[base + 6], p[base + 7]);
;     return __builtin_bit_cast(bf16x8, w);
; }
; __device__ __forceinline__ void cmp_task_lds(const Prm& P, Ctx& C, int b, int kvh, int tg, CStream& CS, const LAS bf16_t* wlb, const int NGW, bf16x8 (&qnx)[4], int& qnx_tg, const int tg_next) {
;     ...
; #pragma unroll
;                 for (int i = 0; i < 4; ++i) { const float v = quad_sum(S[4 * i] + S[4 * i + 1] + S[4 * i + 2]); if (g == tt) cur4[i] = v; }
;                 bf16x8 pf[2]; pf[0] = pack8(S, 0); pf[1] = pack8(S, 8);
; #pragma unroll
;                 for (int dk = 0; dk < 4; ++dk)
;                     o[dk >> 1] = MFMA32(((bf16x8){vlo[dk][0], vlo[dk][1], vlo[dk][2], vlo[dk][3], vhh[dk][0], vhh[dk][1], vhh[dk][2], vhh[dk][3]}), pf[dk & 1], o[dk >> 1]);
.LBB0_1285:
	v_mov_b32_e32 v165, v48
	v_cvt_pk_bf16_f32 v48, v48, v49
	v_mov_b32_e32 v167, v49
	v_mov_b32_e32 v164, v52
	v_mov_b32_e32 v166, v53
	v_cvt_pk_bf16_f32 v49, v50, v51
	v_pk_add_f32 v[164:165], v[164:165], v[166:167]
	v_mov_b32_e32 v167, v50
	v_cvt_pk_bf16_f32 v50, v52, v53
	v_cvt_pk_bf16_f32 v51, v54, v55
	v_cvt_pk_bf16_f32 v52, v56, v57
	s_waitcnt lgkmcnt(6)
	v_mfma_f32_32x32x16_bf16 v[32:47], v[184:187], v[48:51], v[32:47]
	v_cvt_pk_bf16_f32 v53, v58, v59
	v_mov_b32_e32 v166, v54
	v_pk_add_f32 v[164:165], v[166:167], v[164:165]
	s_waitcnt lgkmcnt(2)
	v_mfma_f32_32x32x16_bf16 v[16:31], v[172:175], v[48:51], v[16:31]
	v_mov_b32_dpp v167, v165 quad_perm:[1,0,3,2] row_mask:0xf bank_mask:0xf bound_ctrl:1
	v_mov_b32_dpp v166, v164 quad_perm:[1,0,3,2] row_mask:0xf bank_mask:0xf bound_ctrl:1
	v_cvt_pk_bf16_f32 v54, v60, v61
	v_pk_add_f32 v[164:165], v[164:165], v[166:167]
	s_nop 1
	v_mov_b32_dpp v167, v165 quad_perm:[2,3,0,1] row_mask:0xf bank_mask:0xf bound_ctrl:1
	s_nop 0
	v_mov_b32_dpp v166, v164 quad_perm:[2,3,0,1] row_mask:0xf bank_mask:0xf bound_ctrl:1
	v_pk_add_f32 v[164:165], v[164:165], v[166:167]
	v_cvt_pk_bf16_f32 v55, v62, v63
	v_cndmask_b32_e64 v205, 0, v165, s[0:1]
	v_cndmask_b32_e64 v204, 0, v164, s[0:1]
	v_mov_b32_e32 v164, v60
	v_mov_b32_e32 v165, v56
	v_mfma_f32_32x32x16_bf16 v[32:47], v[180:183], v[52:55], v[32:47]
	v_mov_b32_e32 v56, v61
	v_add_f32_e64 v56, v164, v56
	v_add_f32_e64 v57, v165, v57
	v_mov_b32_e32 v60, v62
	v_mov_b32_e32 v61, v58
	v_pk_add_f32 v[56:57], v[60:61], v[56:57]
	s_waitcnt lgkmcnt(0)
	v_mfma_f32_32x32x16_bf16 v[16:31], v[168:171], v[52:55], v[16:31]
	v_mov_b32_dpp v59, v57 quad_perm:[1,0,3,2] row_mask:0xf bank_mask:0xf bound_ctrl:1
	v_mov_b32_dpp v58, v56 quad_perm:[1,0,3,2] row_mask:0xf bank_mask:0xf bound_ctrl:1
	v_add_f32_e64 v48, v56, v58
	v_add_f32_e64 v49, v57, v59
	s_nop 1
	v_mov_b32_dpp v51, v49 quad_perm:[2,3,0,1] row_mask:0xf bank_mask:0xf bound_ctrl:1
	v_mov_b32_dpp v50, v48 quad_perm:[2,3,0,1] row_mask:0xf bank_mask:0xf bound_ctrl:1
	v_pk_add_f32 v[48:49], v[48:49], v[50:51]
	s_nop 0
	v_cndmask_b32_e64 v207, 0, v49, s[0:1]
	v_cndmask_b32_e64 v206, 0, v48, s[0:1]

; __device__ __forceinline__ unsigned pk2(float lo, float hi) { return f2bf(lo) | (f2bf(hi) << 16); }
; #define MFMA32(a, b, c) __builtin_amdgcn_mfma_f32_32x32x16_bf16((a), (b), (c), 0, 0, 0)
; __device__ __forceinline__ float quad_sum(float v) { v += __int_as_float(dpp_x1(__float_as_int(v))); v += __int_as_float(dpp_x2(__float_as_int(v))); return v; }
; __device__ __forceinline__ bf16x8 pack8(const f32x16& p, int base) {
;     u32x4 w; w.x = pk2(p[base + 0], p[base + 1]); w.y = pk2(p[base + 2], p[base + 3]); w.z = pk2(p[base + 4], p[base + 5]); w.w = pk2(p[base + 6], p[base + 7]);
;     return __builtin_bit_cast(bf16x8, w);
; }
; __device__ __forceinline__ void cmp_task_lds(const Prm& P, Ctx& C, int b, int kvh, int tg, CStream& CS, const LAS bf16_t* wlb, const int NGW, bf16x8 (&qnx)[4], int& qnx_tg, const int tg_next) {
;     ...
; #pragma unroll
;                 for (int i = 0; i < 4; ++i) { const float v = quad_sum(S[4 * i] + S[4 * i + 1] + S[4 * i + 2]); if (g == tt) cur4[i] = v; }
;                 bf16x8 pf[2]; pf[0] = pack8(S, 0); pf[1] = pack8(S, 8);
; #pragma unroll
;                 for (int dk = 0; dk < 4; ++dk)
;                     o[dk >> 1] = MFMA32(((bf16x8){vlo[dk][0], vlo[dk][1], vlo[dk][2], vlo[dk][3], vhh[dk][0], vhh[dk][1], vhh[dk][2], vhh[dk][3]}), pf[dk & 1], o[dk >> 1]);
.LBB0_1291:
	v_mov_b32_e32 v2, v52
	v_mov_b32_e32 v3, v48
	v_mov_b32_e32 v4, v53
	v_mov_b32_e32 v5, v49
	v_pk_add_f32 v[2:3], v[2:3], v[4:5]
	v_mov_b32_e32 v4, v54
	v_mov_b32_e32 v5, v50
	v_pk_add_f32 v[2:3], v[4:5], v[2:3]
	v_mov_b32_e32 v208, v60
	v_mov_b32_e32 v209, v56
	v_mov_b32_dpp v5, v3 quad_perm:[1,0,3,2] row_mask:0xf bank_mask:0xf bound_ctrl:1
	v_mov_b32_dpp v4, v2 quad_perm:[1,0,3,2] row_mask:0xf bank_mask:0xf bound_ctrl:1
	v_pk_add_f32 v[2:3], v[2:3], v[4:5]
	s_nop 1
	v_mov_b32_dpp v5, v3 quad_perm:[2,3,0,1] row_mask:0xf bank_mask:0xf bound_ctrl:1
	v_mov_b32_dpp v4, v2 quad_perm:[2,3,0,1] row_mask:0xf bank_mask:0xf bound_ctrl:1
	v_pk_add_f32 v[2:3], v[2:3], v[4:5]
	v_cndmask_b32_e64 v204, v204, v2, s[2:3]
	v_cndmask_b32_e64 v205, v205, v3, s[2:3]
	v_cvt_pk_bf16_f32 v2, v48, v49
	v_cvt_pk_bf16_f32 v3, v50, v51
	v_cvt_pk_bf16_f32 v4, v52, v53
	v_cvt_pk_bf16_f32 v5, v54, v55
	v_cvt_pk_bf16_f32 v48, v56, v57
	s_waitcnt lgkmcnt(6)
	v_mfma_f32_32x32x16_bf16 v[32:47], v[184:187], v[2:5], v[32:47]
	v_cvt_pk_bf16_f32 v49, v58, v59
	v_cvt_pk_bf16_f32 v50, v60, v61
	s_waitcnt lgkmcnt(2)
	v_mfma_f32_32x32x16_bf16 v[16:31], v[10:13], v[2:5], v[16:31]
	v_cvt_pk_bf16_f32 v51, v62, v63
	v_mov_b32_e32 v52, v61
	v_mov_b32_e32 v53, v57
	v_mfma_f32_32x32x16_bf16 v[32:47], v[180:183], v[48:51], v[32:47]
	v_add_f32_e64 v52, v208, v52
	v_add_f32_e64 v53, v209, v53
	v_mov_b32_e32 v54, v62
	v_mov_b32_e32 v55, v58
	v_add_f32_e64 v52, v54, v52
	v_add_f32_e64 v53, v55, v53
	s_nop 1
	v_mov_b32_dpp v55, v53 quad_perm:[1,0,3,2] row_mask:0xf bank_mask:0xf bound_ctrl:1
	s_waitcnt lgkmcnt(0)
	v_mfma_f32_32x32x16_bf16 v[16:31], v[6:9], v[48:51], v[16:31]
	v_mov_b32_dpp v54, v52 quad_perm:[1,0,3,2] row_mask:0xf bank_mask:0xf bound_ctrl:1
	v_add_f32_e64 v2, v52, v54
	v_add_f32_e64 v3, v53, v55
	s_nop 1
	v_mov_b32_dpp v5, v3 quad_perm:[2,3,0,1] row_mask:0xf bank_mask:0xf bound_ctrl:1
	v_mov_b32_dpp v4, v2 quad_perm:[2,3,0,1] row_mask:0xf bank_mask:0xf bound_ctrl:1
	v_pk_add_f32 v[2:3], v[2:3], v[4:5]
	s_nop 0
	v_cndmask_b32_e64 v207, v207, v3, s[2:3]
	v_cndmask_b32_e64 v206, v206, v2, s[2:3]
	s_add_i32 s14, s12, 2
	s_cmp_ge_i32 s14, s10
	s_cbranch_scc0 .LBB0_1295

; __device__ __forceinline__ unsigned pk2(float lo, float hi) { return f2bf(lo) | (f2bf(hi) << 16); }
; #define MFMA32(a, b, c) __builtin_amdgcn_mfma_f32_32x32x16_bf16((a), (b), (c), 0, 0, 0)
; __device__ __forceinline__ float quad_sum(float v) { v += __int_as_float(dpp_x1(__float_as_int(v))); v += __int_as_float(dpp_x2(__float_as_int(v))); return v; }
; __device__ __forceinline__ bf16x8 pack8(const f32x16& p, int base) {
;     u32x4 w; w.x = pk2(p[base + 0], p[base + 1]); w.y = pk2(p[base + 2], p[base + 3]); w.z = pk2(p[base + 4], p[base + 5]); w.w = pk2(p[base + 6], p[base + 7]);
;     return __builtin_bit_cast(bf16x8, w);
; }
; __device__ __forceinline__ void cmp_task_lds(const Prm& P, Ctx& C, int b, int kvh, int tg, CStream& CS, const LAS bf16_t* wlb, const int NGW, bf16x8 (&qnx)[4], int& qnx_tg, const int tg_next) {
;     ...
; #pragma unroll
;                 for (int i = 0; i < 4; ++i) { const float v = quad_sum(S[4 * i] + S[4 * i + 1] + S[4 * i + 2]); if (g == tt) cur4[i] = v; }
;                 bf16x8 pf[2]; pf[0] = pack8(S, 0); pf[1] = pack8(S, 8);
; #pragma unroll
;                 for (int dk = 0; dk < 4; ++dk)
;                     o[dk >> 1] = MFMA32(((bf16x8){vlo[dk][0], vlo[dk][1], vlo[dk][2], vlo[dk][3], vhh[dk][0], vhh[dk][1], vhh[dk][2], vhh[dk][3]}), pf[dk & 1], o[dk >> 1]);
.LBB0_1299:
	v_mov_b32_e32 v164, v52
	v_mov_b32_e32 v165, v48
	v_mov_b32_e32 v166, v53
	v_mov_b32_e32 v167, v49
	v_pk_add_f32 v[164:165], v[164:165], v[166:167]
	v_mov_b32_e32 v166, v54
	v_mov_b32_e32 v167, v50
	v_pk_add_f32 v[164:165], v[166:167], v[164:165]
	s_nop 1
	v_mov_b32_dpp v167, v165 quad_perm:[1,0,3,2] row_mask:0xf bank_mask:0xf bound_ctrl:1
	v_mov_b32_dpp v166, v164 quad_perm:[1,0,3,2] row_mask:0xf bank_mask:0xf bound_ctrl:1
	v_pk_add_f32 v[164:165], v[164:165], v[166:167]
	s_nop 1
	v_mov_b32_dpp v167, v165 quad_perm:[2,3,0,1] row_mask:0xf bank_mask:0xf bound_ctrl:1
	v_mov_b32_dpp v166, v164 quad_perm:[2,3,0,1] row_mask:0xf bank_mask:0xf bound_ctrl:1
	v_pk_add_f32 v[164:165], v[164:165], v[166:167]
	v_cvt_pk_bf16_f32 v48, v48, v49
	v_cvt_pk_bf16_f32 v49, v50, v51
	v_cvt_pk_bf16_f32 v50, v52, v53
	v_cvt_pk_bf16_f32 v51, v54, v55
	v_cvt_pk_bf16_f32 v52, v56, v57
	s_waitcnt lgkmcnt(6)
	v_mfma_f32_32x32x16_bf16 v[32:47], v[184:187], v[48:51], v[32:47]
	v_cvt_pk_bf16_f32 v53, v58, v59
	v_cvt_pk_bf16_f32 v54, v60, v61
	s_waitcnt lgkmcnt(2)
	v_mfma_f32_32x32x16_bf16 v[16:31], v[172:175], v[48:51], v[16:31]
	v_cndmask_b32_e64 v205, v205, v165, s[4:5]
	v_mov_b32_e32 v165, v56
	v_cvt_pk_bf16_f32 v55, v62, v63
	v_cndmask_b32_e64 v204, v204, v164, s[4:5]
	v_mov_b32_e32 v164, v60
	v_mfma_f32_32x32x16_bf16 v[32:47], v[180:183], v[52:55], v[32:47]
	v_mov_b32_e32 v56, v61
	v_add_f32_e64 v56, v164, v56
	v_add_f32_e64 v57, v165, v57
	v_mov_b32_e32 v60, v62
	v_mov_b32_e32 v61, v58
	v_pk_add_f32 v[56:57], v[60:61], v[56:57]
	s_waitcnt lgkmcnt(0)
	v_mfma_f32_32x32x16_bf16 v[16:31], v[168:171], v[52:55], v[16:31]
	v_mov_b32_dpp v59, v57 quad_perm:[1,0,3,2] row_mask:0xf bank_mask:0xf bound_ctrl:1
	v_mov_b32_dpp v58, v56 quad_perm:[1,0,3,2] row_mask:0xf bank_mask:0xf bound_ctrl:1
	v_add_f32_e64 v48, v56, v58
	v_add_f32_e64 v49, v57, v59
	s_nop 1
	v_mov_b32_dpp v51, v49 quad_perm:[2,3,0,1] row_mask:0xf bank_mask:0xf bound_ctrl:1
	v_mov_b32_dpp v50, v48 quad_perm:[2,3,0,1] row_mask:0xf bank_mask:0xf bound_ctrl:1
	v_pk_add_f32 v[48:49], v[48:49], v[50:51]
	s_nop 0
	v_cndmask_b32_e64 v207, v207, v49, s[4:5]
	v_cndmask_b32_e64 v206, v206, v48, s[4:5]
	s_add_i32 s14, s12, 3
	s_cmp_ge_i32 s14, s10
	s_cbranch_scc1 .LBB0_1293

; __device__ __forceinline__ unsigned pk2(float lo, float hi) { return f2bf(lo) | (f2bf(hi) << 16); }
; #define MFMA32(a, b, c) __builtin_amdgcn_mfma_f32_32x32x16_bf16((a), (b), (c), 0, 0, 0)
; __device__ __forceinline__ float quad_sum(float v) { v += __int_as_float(dpp_x1(__float_as_int(v))); v += __int_as_float(dpp_x2(__float_as_int(v))); return v; }
; __device__ __forceinline__ bf16x8 pack8(const f32x16& p, int base) {
;     u32x4 w; w.x = pk2(p[base + 0], p[base + 1]); w.y = pk2(p[base + 2], p[base + 3]); w.z = pk2(p[base + 4], p[base + 5]); w.w = pk2(p[base + 6], p[base + 7]);
;     return __builtin_bit_cast(bf16x8, w);
; }
; __device__ __forceinline__ void cmp_task_lds(const Prm& P, Ctx& C, int b, int kvh, int tg, CStream& CS, const LAS bf16_t* wlb, const int NGW, bf16x8 (&qnx)[4], int& qnx_tg, const int tg_next) {
;     ...
; #pragma unroll
;                 for (int i = 0; i < 4; ++i) { const float v = quad_sum(S[4 * i] + S[4 * i + 1] + S[4 * i + 2]); if (g == tt) cur4[i] = v; }
;                 bf16x8 pf[2]; pf[0] = pack8(S, 0); pf[1] = pack8(S, 8);
; #pragma unroll
;                 for (int dk = 0; dk < 4; ++dk)
;                     o[dk >> 1] = MFMA32(((bf16x8){vlo[dk][0], vlo[dk][1], vlo[dk][2], vlo[dk][3], vhh[dk][0], vhh[dk][1], vhh[dk][2], vhh[dk][3]}), pf[dk & 1], o[dk >> 1]);
.LBB0_1304:
	v_mov_b32_e32 v2, v52
	v_mov_b32_e32 v3, v48
	v_mov_b32_e32 v4, v53
	v_mov_b32_e32 v5, v49
	v_pk_add_f32 v[2:3], v[2:3], v[4:5]
	v_mov_b32_e32 v4, v54
	v_mov_b32_e32 v5, v50
	v_pk_add_f32 v[2:3], v[4:5], v[2:3]
	v_bfe_u32 v1, v48, 16, 1
	v_add3_u32 v1, v48, v1, s70
	v_mov_b32_dpp v5, v3 quad_perm:[1,0,3,2] row_mask:0xf bank_mask:0xf bound_ctrl:1
	v_mov_b32_dpp v4, v2 quad_perm:[1,0,3,2] row_mask:0xf bank_mask:0xf bound_ctrl:1
	v_pk_add_f32 v[2:3], v[2:3], v[4:5]
	v_lshrrev_b32_e32 v1, 16, v1
	s_nop 0
	v_mov_b32_dpp v5, v3 quad_perm:[2,3,0,1] row_mask:0xf bank_mask:0xf bound_ctrl:1
	v_mov_b32_dpp v4, v2 quad_perm:[2,3,0,1] row_mask:0xf bank_mask:0xf bound_ctrl:1
	v_pk_add_f32 v[2:3], v[2:3], v[4:5]
	v_cndmask_b32_e64 v204, v204, v2, s[6:7]
	v_bfe_u32 v2, v49, 16, 1
	v_add3_u32 v2, v49, v2, s70
	v_and_or_b32 v2, v2, s69, v1
	v_cndmask_b32_e64 v205, v205, v3, s[6:7]
	v_cvt_pk_bf16_f32 v3, v50, v51
	v_cvt_pk_bf16_f32 v4, v52, v53
	v_cvt_pk_bf16_f32 v5, v54, v55
	v_cvt_pk_bf16_f32 v48, v56, v57
	s_waitcnt lgkmcnt(6)
	v_mfma_f32_32x32x16_bf16 v[32:47], v[184:187], v[2:5], v[32:47]
	v_cvt_pk_bf16_f32 v49, v58, v59
	v_cvt_pk_bf16_f32 v50, v60, v61
	s_waitcnt lgkmcnt(2)
	v_mfma_f32_32x32x16_bf16 v[16:31], v[10:13], v[2:5], v[16:31]
	v_bfe_u32 v1, v62, 16, 1
	v_add3_u32 v1, v62, v1, s70
	v_bfe_u32 v51, v63, 16, 1
	v_lshrrev_b32_e32 v1, 16, v1
	v_add3_u32 v51, v63, v51, s70
	v_and_or_b32 v51, v51, s69, v1
	v_mov_b32_e32 v208, v60
	v_mov_b32_e32 v209, v56
	v_mfma_f32_32x32x16_bf16 v[32:47], v[180:183], v[48:51], v[32:47]
	v_mov_b32_e32 v52, v61
	v_mov_b32_e32 v53, v57
	v_add_f32_e64 v52, v208, v52
	v_add_f32_e64 v53, v209, v53
	v_mov_b32_e32 v54, v62
	v_mov_b32_e32 v55, v58
	v_pk_add_f32 v[52:53], v[54:55], v[52:53]
	s_waitcnt lgkmcnt(0)
	v_mfma_f32_32x32x16_bf16 v[16:31], v[6:9], v[48:51], v[16:31]
	v_mov_b32_dpp v55, v53 quad_perm:[1,0,3,2] row_mask:0xf bank_mask:0xf bound_ctrl:1
	v_mov_b32_dpp v54, v52 quad_perm:[1,0,3,2] row_mask:0xf bank_mask:0xf bound_ctrl:1
	v_add_f32_e64 v2, v52, v54
	v_add_f32_e64 v3, v53, v55
	s_nop 1
	v_mov_b32_dpp v5, v3 quad_perm:[2,3,0,1] row_mask:0xf bank_mask:0xf bound_ctrl:1
	v_mov_b32_dpp v4, v2 quad_perm:[2,3,0,1] row_mask:0xf bank_mask:0xf bound_ctrl:1
	v_pk_add_f32 v[2:3], v[2:3], v[4:5]
	s_nop 0
	v_cndmask_b32_e64 v207, v207, v3, s[6:7]
	v_cndmask_b32_e64 v206, v206, v2, s[6:7]

; #define LAS __attribute__((address_space(3)))
; __device__ __forceinline__ unsigned pk2(float lo, float hi) { return f2bf(lo) | (f2bf(hi) << 16); }
; __device__ __forceinline__ void chunk_ab(const f32x4 (&v)[16], const LAS bf16_t* wl, int lane, f32x4& A, f32x4& B) {
;     A = (f32x4){0.f, 0.f, 0.f, 0.f}; B = A;
;     const LAS bf16_t* wlane = wl + 4 * lane; asm volatile("" : "+v"(wlane));
; #pragma unroll
;     for (int j = 0; j < 16; ++j) { const u32x2 wa = *(const LAS u32x2*)(wlane + j * 256), wb = *(const LAS u32x2*)(wlane + (16 + j) * 256);
;         A += v[j] * (f32x4){bflo(wa.x), bfhi(wa.x), bflo(wa.y), bfhi(wa.y)}; B += v[j] * (f32x4){bflo(wb.x), bfhi(wb.x), bflo(wb.y), bfhi(wb.y)}; }
; }
; __device__ __forceinline__ void cs_consume(const Prm& P, CStream& S, const LAS bf16_t* wlb, int NGW) {
;     if (S.pend) {
;         int lane; asm volatile("v_mbcnt_lo_u32_b32 %0, -1, 0\n\tv_mbcnt_hi_u32_b32 %0, -1, %0" : "=v"(lane));
;         const int b = S.tk >> 7, p = S.tk & 127;
;         bf16_t* dst = (bf16_t*)(P.ws + WS_KCS) + (size_t)b * 1024 * 256;
;         if (S.pend == 1) {
;             f32x4 A0, B0; chunk_ab(S.v, wlb, lane, A0, B0);
;             if (S.i >= 1) { const int n = 8 * p + S.i - 1; if (n < 1023) { const f32x4 s = S.Aprev + B0; st8_pl(dst + (size_t)n * 256 + 4 * lane, pk2(s[0], s[1]), pk2(s[2], s[3])); } }
;             S.Aprev = A0;
; __device__ __forceinline__ void phase_cmp(const Prm& P, Ctx& C) {
;     ...
; #pragma unroll 1
;         while (CS.tk < DB * NPAGES || CS.pend) { cs_consume(P, CS, wlb, NGW); cs_issue(P, CS); }
.LBB0_1412:
	s_cmp_eq_u32 s38, 0
	s_cbranch_scc1 .LBB0_1424
	s_ashr_i32 s2, s62, 7
	s_ashr_i32 s3, s2, 31
	s_and_b32 s4, s62, 0x7f
	s_lshl_b64 s[2:3], s[2:3], 19
	s_add_u32 s2, s63, s2
	s_addc_u32 s3, s64, s3
	s_cmp_lg_u32 s38, 1
	v_mbcnt_lo_u32_b32 v1, -1, 0
	v_mbcnt_hi_u32_b32 v1, -1, v1
	s_cbranch_scc1 .LBB0_1421
	v_lshl_add_u32 v8, v1, 3, s7
	ds_read2st64_b64 v[2:5], v8 offset1:1
	ds_read2st64_b64 v[10:13], v8 offset0:2 offset1:3
	s_cmp_lt_i32 s60, 1
	s_waitcnt lgkmcnt(1)
	v_lshlrev_b32_e32 v14, 16, v2
	v_and_b32_e32 v15, 0xffff0000, v2
	v_lshlrev_b32_e32 v2, 16, v3
	v_and_b32_e32 v3, 0xffff0000, v3
	s_waitcnt vmcnt(15)
	v_pk_fma_f32 v[14:15], v[64:65], v[14:15], 0 op_sel_hi:[1,1,0]
	v_pk_fma_f32 v[2:3], v[66:67], v[2:3], 0 op_sel_hi:[1,1,0]
	v_lshlrev_b32_e32 v16, 16, v4
	v_and_b32_e32 v17, 0xffff0000, v4
	v_lshlrev_b32_e32 v4, 16, v5
	v_and_b32_e32 v5, 0xffff0000, v5
	s_waitcnt vmcnt(14)
	v_pk_fma_f32 v[2:3], v[70:71], v[4:5], v[2:3]
	v_pk_fma_f32 v[4:5], v[68:69], v[16:17], v[14:15]
	s_waitcnt lgkmcnt(0)
	v_lshlrev_b32_e32 v14, 16, v10
	v_and_b32_e32 v15, 0xffff0000, v10
	v_lshlrev_b32_e32 v10, 16, v11
	v_and_b32_e32 v11, 0xffff0000, v11
	s_waitcnt vmcnt(13)
	v_pk_fma_f32 v[14:15], v[72:73], v[14:15], v[4:5]
	v_pk_fma_f32 v[10:11], v[74:75], v[10:11], v[2:3]
	ds_read2st64_b64 v[2:5], v8 offset0:4 offset1:5
	v_lshlrev_b32_e32 v16, 16, v12
	v_and_b32_e32 v17, 0xffff0000, v12
	v_lshlrev_b32_e32 v12, 16, v13
	v_and_b32_e32 v13, 0xffff0000, v13
	s_waitcnt vmcnt(12)
	v_pk_fma_f32 v[18:19], v[78:79], v[12:13], v[10:11]
	ds_read2st64_b64 v[10:13], v8 offset0:6 offset1:7
	v_pk_fma_f32 v[14:15], v[76:77], v[16:17], v[14:15]
	s_waitcnt lgkmcnt(1)
	v_lshlrev_b32_e32 v16, 16, v2
	v_and_b32_e32 v17, 0xffff0000, v2
	v_lshlrev_b32_e32 v2, 16, v3
	v_and_b32_e32 v3, 0xffff0000, v3
	s_waitcnt vmcnt(1)
	v_pk_fma_f32 v[14:15], v[88:89], v[16:17], v[14:15]
	v_pk_fma_f32 v[2:3], v[90:91], v[2:3], v[18:19]
	v_lshlrev_b32_e32 v16, 16, v4
	v_and_b32_e32 v17, 0xffff0000, v4
	v_lshlrev_b32_e32 v4, 16, v5
	v_and_b32_e32 v5, 0xffff0000, v5
	v_pk_fma_f32 v[2:3], v[82:83], v[4:5], v[2:3]
	v_pk_fma_f32 v[4:5], v[80:81], v[16:17], v[14:15]
	s_waitcnt lgkmcnt(0)
	v_lshlrev_b32_e32 v14, 16, v10
	v_and_b32_e32 v15, 0xffff0000, v10
	v_lshlrev_b32_e32 v10, 16, v11
	v_and_b32_e32 v11, 0xffff0000, v11
	v_pk_fma_f32 v[14:15], v[84:85], v[14:15], v[4:5]
	v_pk_fma_f32 v[10:11], v[86:87], v[10:11], v[2:3]
	ds_read2st64_b64 v[2:5], v8 offset0:8 offset1:9
	v_lshlrev_b32_e32 v16, 16, v12
	v_and_b32_e32 v17, 0xffff0000, v12
	v_lshlrev_b32_e32 v12, 16, v13
	v_and_b32_e32 v13, 0xffff0000, v13
	v_pk_fma_f32 v[18:19], v[94:95], v[12:13], v[10:11]
	ds_read2st64_b64 v[10:13], v8 offset0:10 offset1:11
	v_pk_fma_f32 v[14:15], v[92:93], v[16:17], v[14:15]
	s_waitcnt lgkmcnt(1)
	v_lshlrev_b32_e32 v16, 16, v2
	v_and_b32_e32 v17, 0xffff0000, v2
	v_lshlrev_b32_e32 v2, 16, v3
	v_and_b32_e32 v3, 0xffff0000, v3
	v_pk_fma_f32 v[14:15], v[96:97], v[16:17], v[14:15]
	v_pk_fma_f32 v[2:3], v[98:99], v[2:3], v[18:19]
	v_lshlrev_b32_e32 v16, 16, v4
	v_and_b32_e32 v17, 0xffff0000, v4
	v_lshlrev_b32_e32 v4, 16, v5
	v_and_b32_e32 v5, 0xffff0000, v5
	v_pk_fma_f32 v[2:3], v[102:103], v[4:5], v[2:3]
	v_pk_fma_f32 v[4:5], v[100:101], v[16:17], v[14:15]
	s_waitcnt lgkmcnt(0)
	v_lshlrev_b32_e32 v14, 16, v10
	v_and_b32_e32 v15, 0xffff0000, v10
	v_lshlrev_b32_e32 v10, 16, v11
	v_and_b32_e32 v11, 0xffff0000, v11
	v_pk_fma_f32 v[14:15], v[104:105], v[14:15], v[4:5]
	v_pk_fma_f32 v[10:11], v[106:107], v[10:11], v[2:3]
	ds_read2st64_b64 v[2:5], v8 offset0:12 offset1:13
	v_lshlrev_b32_e32 v16, 16, v12
	v_and_b32_e32 v17, 0xffff0000, v12
	v_lshlrev_b32_e32 v12, 16, v13
	v_and_b32_e32 v13, 0xffff0000, v13
	v_pk_fma_f32 v[18:19], v[110:111], v[12:13], v[10:11]
	ds_read2st64_b64 v[10:13], v8 offset0:14 offset1:15
	v_pk_fma_f32 v[14:15], v[108:109], v[16:17], v[14:15]
	s_waitcnt lgkmcnt(1)
	v_lshlrev_b32_e32 v16, 16, v2
	v_and_b32_e32 v17, 0xffff0000, v2
	v_lshlrev_b32_e32 v2, 16, v3
	v_and_b32_e32 v3, 0xffff0000, v3
	v_pk_fma_f32 v[14:15], v[112:113], v[16:17], v[14:15]
	v_pk_fma_f32 v[2:3], v[114:115], v[2:3], v[18:19]
	v_lshlrev_b32_e32 v16, 16, v4
	v_and_b32_e32 v17, 0xffff0000, v4
	v_lshlrev_b32_e32 v4, 16, v5
	v_and_b32_e32 v5, 0xffff0000, v5
	v_pk_fma_f32 v[2:3], v[118:119], v[4:5], v[2:3]
	v_pk_fma_f32 v[4:5], v[116:117], v[16:17], v[14:15]
	s_waitcnt lgkmcnt(0)
	v_lshlrev_b32_e32 v14, 16, v10
	v_and_b32_e32 v15, 0xffff0000, v10
	v_lshlrev_b32_e32 v10, 16, v11
	v_and_b32_e32 v11, 0xffff0000, v11
	v_pk_fma_f32 v[14:15], v[120:121], v[14:15], v[4:5]
	v_pk_fma_f32 v[2:3], v[122:123], v[10:11], v[2:3]
	v_lshlrev_b32_e32 v10, 16, v12
	v_and_b32_e32 v11, 0xffff0000, v12
	v_lshlrev_b32_e32 v4, 16, v13
	v_and_b32_e32 v5, 0xffff0000, v13
	s_waitcnt vmcnt(0)
	v_pk_fma_f32 v[4:5], v[126:127], v[4:5], v[2:3]
	v_pk_fma_f32 v[2:3], v[124:125], v[10:11], v[14:15]
	s_cbranch_scc1 .LBB0_1417
; #define LAS __attribute__((address_space(3)))
; __device__ __forceinline__ unsigned pk2(float lo, float hi) { return f2bf(lo) | (f2bf(hi) << 16); }
; __device__ __forceinline__ void chunk_ab(const f32x4 (&v)[16], const LAS bf16_t* wl, int lane, f32x4& A, f32x4& B) {
;     A = (f32x4){0.f, 0.f, 0.f, 0.f}; B = A;
;     const LAS bf16_t* wlane = wl + 4 * lane; asm volatile("" : "+v"(wlane));
; #pragma unroll
;     for (int j = 0; j < 16; ++j) { const u32x2 wa = *(const LAS u32x2*)(wlane + j * 256), wb = *(const LAS u32x2*)(wlane + (16 + j) * 256);
;         A += v[j] * (f32x4){bflo(wa.x), bfhi(wa.x), bflo(wa.y), bfhi(wa.y)}; B += v[j] * (f32x4){bflo(wb.x), bfhi(wb.x), bflo(wb.y), bfhi(wb.y)}; }
; }
; __device__ __forceinline__ void cs_consume(const Prm& P, CStream& S, const LAS bf16_t* wlb, int NGW) {
;     ...
;         if (S.pend == 1) {
;             f32x4 A0, B0; chunk_ab(S.v, wlb, lane, A0, B0);
;             if (S.i >= 1) { const int n = 8 * p + S.i - 1; if (n < 1023) { const f32x4 s = S.Aprev + B0; st8_pl(dst + (size_t)n * 256 + 4 * lane, pk2(s[0], s[1]), pk2(s[2], s[3])); } }
;             S.Aprev = A0;
	s_lshl_b32 s0, s4, 3
	s_add_i32 s0, s0, s60
	s_cmpk_gt_u32 s0, 0x3ff
	s_cbranch_scc1 .LBB0_1417
	ds_read2st64_b64 v[10:13], v8 offset0:16 offset1:17
	ds_read2st64_b64 v[14:17], v8 offset0:18 offset1:19
	ds_read2st64_b64 v[18:21], v8 offset0:20 offset1:21
	ds_read2st64_b64 v[22:25], v8 offset0:22 offset1:23
	ds_read2st64_b64 v[26:29], v8 offset0:24 offset1:25
	ds_read2st64_b64 v[30:33], v8 offset0:26 offset1:27
	ds_read2st64_b64 v[34:37], v8 offset0:28 offset1:29
	ds_read2st64_b64 v[38:41], v8 offset0:30 offset1:31
	s_waitcnt lgkmcnt(7)
	v_lshlrev_b32_e32 v8, 16, v10
	v_and_b32_e32 v9, 0xffff0000, v10
	v_lshlrev_b32_e32 v10, 16, v11
	v_and_b32_e32 v11, 0xffff0000, v11
	v_pk_fma_f32 v[10:11], v[66:67], v[10:11], 0 op_sel_hi:[1,1,0]
	v_pk_fma_f32 v[8:9], v[64:65], v[8:9], 0 op_sel_hi:[1,1,0]
	v_lshlrev_b32_e32 v42, 16, v12
	v_and_b32_e32 v43, 0xffff0000, v12
	v_lshlrev_b32_e32 v12, 16, v13
	v_and_b32_e32 v13, 0xffff0000, v13
	v_pk_fma_f32 v[8:9], v[68:69], v[42:43], v[8:9]
	v_pk_fma_f32 v[10:11], v[70:71], v[12:13], v[10:11]
	s_waitcnt lgkmcnt(6)
	v_lshlrev_b32_e32 v12, 16, v14
	v_and_b32_e32 v13, 0xffff0000, v14
	v_pk_fma_f32 v[8:9], v[72:73], v[12:13], v[8:9]
	v_lshlrev_b32_e32 v12, 16, v16
	v_and_b32_e32 v13, 0xffff0000, v16
	v_lshlrev_b32_e32 v14, 16, v15
	v_and_b32_e32 v15, 0xffff0000, v15
	v_pk_fma_f32 v[8:9], v[76:77], v[12:13], v[8:9]
	s_waitcnt lgkmcnt(5)
	v_lshlrev_b32_e32 v12, 16, v18
	v_and_b32_e32 v13, 0xffff0000, v18
	v_pk_fma_f32 v[10:11], v[74:75], v[14:15], v[10:11]
	v_lshlrev_b32_e32 v14, 16, v17
	v_and_b32_e32 v15, 0xffff0000, v17
	v_pk_fma_f32 v[8:9], v[88:89], v[12:13], v[8:9]
	v_lshlrev_b32_e32 v12, 16, v20
	v_and_b32_e32 v13, 0xffff0000, v20
	v_pk_fma_f32 v[10:11], v[78:79], v[14:15], v[10:11]
	v_lshlrev_b32_e32 v14, 16, v19
	v_and_b32_e32 v15, 0xffff0000, v19
	v_pk_fma_f32 v[8:9], v[80:81], v[12:13], v[8:9]
	s_waitcnt lgkmcnt(4)
	v_lshlrev_b32_e32 v12, 16, v22
	v_and_b32_e32 v13, 0xffff0000, v22
	v_pk_fma_f32 v[10:11], v[90:91], v[14:15], v[10:11]
	v_lshlrev_b32_e32 v14, 16, v21
	v_and_b32_e32 v15, 0xffff0000, v21
	v_pk_fma_f32 v[8:9], v[84:85], v[12:13], v[8:9]
	v_lshlrev_b32_e32 v12, 16, v24
	v_and_b32_e32 v13, 0xffff0000, v24
	v_pk_fma_f32 v[10:11], v[82:83], v[14:15], v[10:11]
	v_lshlrev_b32_e32 v14, 16, v23
	v_and_b32_e32 v15, 0xffff0000, v23
	v_pk_fma_f32 v[8:9], v[92:93], v[12:13], v[8:9]
	s_waitcnt lgkmcnt(3)
	v_lshlrev_b32_e32 v12, 16, v26
	v_and_b32_e32 v13, 0xffff0000, v26
	v_pk_fma_f32 v[10:11], v[86:87], v[14:15], v[10:11]
	v_lshlrev_b32_e32 v14, 16, v25
	v_and_b32_e32 v15, 0xffff0000, v25
	v_pk_fma_f32 v[8:9], v[96:97], v[12:13], v[8:9]
	v_lshlrev_b32_e32 v12, 16, v28
	v_and_b32_e32 v13, 0xffff0000, v28
	v_pk_fma_f32 v[10:11], v[94:95], v[14:15], v[10:11]
	v_lshlrev_b32_e32 v14, 16, v27
	v_and_b32_e32 v15, 0xffff0000, v27
	v_pk_fma_f32 v[8:9], v[100:101], v[12:13], v[8:9]
	s_waitcnt lgkmcnt(2)
	v_lshlrev_b32_e32 v12, 16, v30
	v_and_b32_e32 v13, 0xffff0000, v30
	v_pk_fma_f32 v[10:11], v[98:99], v[14:15], v[10:11]
	v_lshlrev_b32_e32 v14, 16, v29
	v_and_b32_e32 v15, 0xffff0000, v29
	v_pk_fma_f32 v[8:9], v[104:105], v[12:13], v[8:9]
	v_lshlrev_b32_e32 v12, 16, v32
	v_and_b32_e32 v13, 0xffff0000, v32
	v_pk_fma_f32 v[10:11], v[102:103], v[14:15], v[10:11]
	v_lshlrev_b32_e32 v14, 16, v31
	v_and_b32_e32 v15, 0xffff0000, v31
	v_pk_fma_f32 v[8:9], v[108:109], v[12:13], v[8:9]
	s_waitcnt lgkmcnt(1)
	v_lshlrev_b32_e32 v12, 16, v34
	v_and_b32_e32 v13, 0xffff0000, v34
	v_pk_fma_f32 v[10:11], v[106:107], v[14:15], v[10:11]
	v_lshlrev_b32_e32 v14, 16, v33
	v_and_b32_e32 v15, 0xffff0000, v33
	v_pk_fma_f32 v[8:9], v[112:113], v[12:13], v[8:9]
	v_lshlrev_b32_e32 v12, 16, v36
	v_and_b32_e32 v13, 0xffff0000, v36
	v_pk_fma_f32 v[10:11], v[110:111], v[14:15], v[10:11]
	v_lshlrev_b32_e32 v14, 16, v35
	v_and_b32_e32 v15, 0xffff0000, v35
	v_pk_fma_f32 v[8:9], v[116:117], v[12:13], v[8:9]
	s_waitcnt lgkmcnt(0)
	v_lshlrev_b32_e32 v12, 16, v38
	v_and_b32_e32 v13, 0xffff0000, v38
	v_pk_fma_f32 v[10:11], v[114:115], v[14:15], v[10:11]
	v_lshlrev_b32_e32 v14, 16, v37
	v_and_b32_e32 v15, 0xffff0000, v37
	v_pk_fma_f32 v[8:9], v[120:121], v[12:13], v[8:9]
	v_lshlrev_b32_e32 v12, 16, v40
	v_and_b32_e32 v13, 0xffff0000, v40
	v_pk_fma_f32 v[10:11], v[118:119], v[14:15], v[10:11]
	v_lshlrev_b32_e32 v14, 16, v39
	v_and_b32_e32 v15, 0xffff0000, v39
	v_pk_fma_f32 v[8:9], v[124:125], v[12:13], v[8:9]
	v_pk_fma_f32 v[10:11], v[122:123], v[14:15], v[10:11]
	v_lshlrev_b32_e32 v14, 16, v41
	v_and_b32_e32 v15, 0xffff0000, v41
	v_pk_add_f32 v[8:9], v[128:129], v[8:9]
	v_pk_fma_f32 v[10:11], v[126:127], v[14:15], v[10:11]
	s_add_i32 s0, s0, -1
	v_pk_add_f32 v[10:11], v[130:131], v[10:11]
	s_lshl_b64 s[10:11], s[0:1], 9
	v_cvt_pk_bf16_f32 v8, v8, v9
	s_add_u32 s10, s2, s10
	v_lshlrev_b32_e32 v12, 2, v1
	s_addc_u32 s11, s3, s11
	v_ashrrev_i32_e32 v13, 31, v12
	v_lshl_add_u64 v[12:13], v[12:13], 1, s[10:11]
	v_cvt_pk_bf16_f32 v9, v10, v11
	global_store_dwordx2 v[12:13], v[8:9], off

; #define LAS __attribute__((address_space(3)))
; __device__ __forceinline__ unsigned f2bf(float f) { unsigned u = __builtin_bit_cast(unsigned, f); return (u + 0x7fffu + ((u >> 16) & 1u)) >> 16; }
; __device__ __forceinline__ int crow(int r, int hi) { return (r & 3) + 8 * (r >> 2) + 4 * hi; }
; template <int MODE, int THRL>
; __device__ __forceinline__ void attn_unit(const Prm& P, int b, int h, int qb, LAS char* shm, int wid) {
;     ...
;   if (hi == 0) { const float gte = ((const float*)(P.ws + WS_G))[(row0 + r32) * 24 + h * 3 + (MODE == 0 ? 1 : 2)]; wsf[32 + r32] = l_reg > 0.f ? gte * __builtin_amdgcn_rcpf(l_reg) : 0.f; }
;   asm volatile("s_waitcnt lgkmcnt(0)" ::: "memory");
;   float rli[16];
; #pragma unroll
;   for (int r = 0; r < 16; ++r) rli[r] = wsf[32 + crow(r, hi)];
;   { LAS bf16_t* stg = (LAS bf16_t*)(shm + (MODE == 0 ? LDS_OS2 : LDS_OST)) + wid * 2048;
; #pragma unroll
;     for (int r = 0; r < 16; ++r) { const int orow = crow(r, hi);
; #pragma unroll
;       for (int d0 = 0; d0 < 2; ++d0) stg[orow * 64 + d0 * 32 + r32] = (bf16_t)f2bf(o[d0][r] * rli[r]); }
;     asm volatile("s_waitcnt lgkmcnt(0)" ::: "memory");
.LBB0_1481:
	s_or_b64 exec, exec, s[0:1]
	s_waitcnt lgkmcnt(0)
	ds_read_b128 v[74:77], v80 offset:49280
	ds_read_b128 v[82:85], v80 offset:49312
	ds_read_b128 v[86:89], v80 offset:49344
	ds_read_b128 v[78:81], v80 offset:49376
	v_lshlrev_b32_e32 v90, 1, v204
	v_lshlrev_b32_e32 v91, 9, v206
	v_readlane_b32 s2, v251, 47
	s_waitcnt lgkmcnt(3)
	v_mul_f32_e32 v32, v32, v74
	s_movk_i32 s3, 0x7fff
	v_add3_u32 v90, s2, v90, v91
	v_bfe_u32 v91, v32, 16, 1
	v_add3_u32 v32, v32, v91, s3
	v_mul_f32_e32 v16, v16, v74
	ds_write_b16_d16_hi v90, v32 offset:55296
	v_bfe_u32 v32, v16, 16, 1
	v_add3_u32 v16, v16, v32, s3
	ds_write_b16_d16_hi v90, v16 offset:55360
	v_mul_f32_e32 v16, v33, v75
	v_bfe_u32 v32, v16, 16, 1
	v_add3_u32 v16, v16, v32, s3
	ds_write_b16_d16_hi v90, v16 offset:55424
	v_mul_f32_e32 v16, v17, v75
	v_bfe_u32 v17, v16, 16, 1
	v_add3_u32 v16, v16, v17, s3
	ds_write_b16_d16_hi v90, v16 offset:55488
	v_mul_f32_e32 v16, v34, v76
	v_bfe_u32 v17, v16, 16, 1
	v_add3_u32 v16, v16, v17, s3
	ds_write_b16_d16_hi v90, v16 offset:55552
	v_mul_f32_e32 v16, v18, v76
	v_bfe_u32 v17, v16, 16, 1
	v_add3_u32 v16, v16, v17, s3
	ds_write_b16_d16_hi v90, v16 offset:55616
	v_mul_f32_e32 v16, v35, v77
	v_bfe_u32 v17, v16, 16, 1
	v_add3_u32 v16, v16, v17, s3
	ds_write_b16_d16_hi v90, v16 offset:55680
	v_mul_f32_e32 v16, v19, v77
	v_bfe_u32 v17, v16, 16, 1
	v_add3_u32 v16, v16, v17, s3
	ds_write_b16_d16_hi v90, v16 offset:55744
	s_waitcnt lgkmcnt(10)
	v_mul_f32_e32 v16, v36, v82
	v_bfe_u32 v17, v16, 16, 1
	v_add3_u32 v16, v16, v17, s3
	ds_write_b16_d16_hi v90, v16 offset:56320
	v_mul_f32_e32 v16, v20, v82
	v_bfe_u32 v17, v16, 16, 1
	v_add3_u32 v16, v16, v17, s3
	ds_write_b16_d16_hi v90, v16 offset:56384
	v_mul_f32_e32 v16, v37, v83
	v_bfe_u32 v17, v16, 16, 1
	v_add3_u32 v16, v16, v17, s3
	ds_write_b16_d16_hi v90, v16 offset:56448
	v_mul_f32_e32 v16, v21, v83
	v_bfe_u32 v17, v16, 16, 1
	v_add3_u32 v16, v16, v17, s3
	ds_write_b16_d16_hi v90, v16 offset:56512
	v_mul_f32_e32 v16, v38, v84
	v_bfe_u32 v17, v16, 16, 1
	v_add3_u32 v16, v16, v17, s3
	ds_write_b16_d16_hi v90, v16 offset:56576
	v_mul_f32_e32 v16, v22, v84
	v_bfe_u32 v17, v16, 16, 1
	v_add3_u32 v16, v16, v17, s3
	ds_write_b16_d16_hi v90, v16 offset:56640
	v_mul_f32_e32 v16, v39, v85
	v_bfe_u32 v17, v16, 16, 1
	v_add3_u32 v16, v16, v17, s3
	ds_write_b16_d16_hi v90, v16 offset:56704
	v_mul_f32_e32 v16, v23, v85
	v_bfe_u32 v17, v16, 16, 1
	v_add3_u32 v16, v16, v17, s3
	ds_write_b16_d16_hi v90, v16 offset:56768
	s_waitcnt lgkmcnt(14)
	v_mul_f32_e32 v16, v40, v86
	v_bfe_u32 v17, v16, 16, 1
	v_add3_u32 v16, v16, v17, s3
	ds_write_b16_d16_hi v90, v16 offset:57344
	v_mul_f32_e32 v16, v24, v86
	v_bfe_u32 v17, v16, 16, 1
	v_add3_u32 v16, v16, v17, s3
	ds_write_b16_d16_hi v90, v16 offset:57408
	v_mul_f32_e32 v16, v41, v87
	v_bfe_u32 v17, v16, 16, 1
	v_add3_u32 v16, v16, v17, s3
	ds_write_b16_d16_hi v90, v16 offset:57472
	v_mul_f32_e32 v16, v25, v87
	v_bfe_u32 v17, v16, 16, 1
	v_add3_u32 v16, v16, v17, s3
	ds_write_b16_d16_hi v90, v16 offset:57536
	v_mul_f32_e32 v16, v42, v88
	v_bfe_u32 v17, v16, 16, 1
	v_add3_u32 v16, v16, v17, s3
	ds_write_b16_d16_hi v90, v16 offset:57600
	v_mul_f32_e32 v16, v26, v88
	v_bfe_u32 v17, v16, 16, 1
	v_add3_u32 v16, v16, v17, s3
	ds_write_b16_d16_hi v90, v16 offset:57664
	v_mul_f32_e32 v16, v43, v89
	v_bfe_u32 v17, v16, 16, 1
	v_add3_u32 v16, v16, v17, s3
	ds_write_b16_d16_hi v90, v16 offset:57728
	v_mul_f32_e32 v16, v27, v89
	v_bfe_u32 v17, v16, 16, 1
	v_add3_u32 v16, v16, v17, s3
	ds_write_b16_d16_hi v90, v16 offset:57792
	v_mul_f32_e32 v16, v44, v78
	v_bfe_u32 v17, v16, 16, 1
	v_add3_u32 v16, v16, v17, s3
	ds_write_b16_d16_hi v90, v16 offset:58368
	v_mul_f32_e32 v16, v28, v78
	v_bfe_u32 v17, v16, 16, 1
	v_add3_u32 v16, v16, v17, s3
	ds_write_b16_d16_hi v90, v16 offset:58432
	v_mul_f32_e32 v16, v45, v79
	v_bfe_u32 v17, v16, 16, 1
	v_add3_u32 v16, v16, v17, s3
	ds_write_b16_d16_hi v90, v16 offset:58496
	v_mul_f32_e32 v16, v29, v79
	v_bfe_u32 v17, v16, 16, 1
	v_add3_u32 v16, v16, v17, s3
	ds_write_b16_d16_hi v90, v16 offset:58560
	v_mul_f32_e32 v16, v46, v80
	v_bfe_u32 v17, v16, 16, 1
	v_add3_u32 v16, v16, v17, s3
	ds_write_b16_d16_hi v90, v16 offset:58624
	v_mul_f32_e32 v16, v30, v80
	v_bfe_u32 v17, v16, 16, 1
	v_add3_u32 v16, v16, v17, s3
	ds_write_b16_d16_hi v90, v16 offset:58688
	v_mul_f32_e32 v16, v47, v81
	v_bfe_u32 v17, v16, 16, 1
	v_add3_u32 v16, v16, v17, s3
	ds_write_b16_d16_hi v90, v16 offset:58752
	v_mul_f32_e32 v16, v31, v81
	v_bfe_u32 v17, v16, 16, 1
	v_add3_u32 v16, v16, v17, s3
	ds_write_b16_d16_hi v90, v16 offset:58816
	v_add_u32_e32 v32, s2, v0
	v_add_u32_e32 v33, s46, v0
	v_lshlrev_b32_e32 v16, 7, v72
	s_waitcnt lgkmcnt(0)
	v_add_u32_e32 v17, v32, v16
	v_add_u32_e32 v16, v33, v16
	ds_read_b128 v[18:21], v17 offset:55296
	ds_read_b128 v[22:25], v16
	s_lshl_b64 s[0:1], s[4:5], 11
	v_readlane_b32 s4, v250, 49
	v_readlane_b32 s8, v250, 53
	s_waitcnt lgkmcnt(1)
	v_lshlrev_b32_e32 v27, 16, v19
	v_lshlrev_b32_e32 v26, 16, v18
	s_waitcnt lgkmcnt(0)
	v_lshlrev_b32_e32 v29, 16, v23
	v_lshlrev_b32_e32 v28, 16, v22
	v_and_b32_e32 v19, 0xffff0000, v19
	v_and_b32_e32 v18, 0xffff0000, v18
	v_and_b32_e32 v23, 0xffff0000, v23
	v_and_b32_e32 v22, 0xffff0000, v22
	v_pk_add_f32 v[26:27], v[26:27], v[28:29]
	s_waitcnt vmcnt(7)
	v_lshlrev_b32_e32 v29, 16, v61
	v_lshlrev_b32_e32 v28, 16, v60
	v_pk_add_f32 v[18:19], v[18:19], v[22:23]
	v_and_b32_e32 v23, 0xffff0000, v61
	v_and_b32_e32 v22, 0xffff0000, v60
	v_pk_add_f32 v[26:27], v[26:27], v[28:29]
	s_waitcnt vmcnt(6)
; #define LAS __attribute__((address_space(3)))
; __device__ __forceinline__ unsigned pk2(float lo, float hi) { return f2bf(lo) | (f2bf(hi) << 16); }
; template <int MODE, int THRL>
; __device__ __forceinline__ void attn_unit(const Prm& P, int b, int h, int qb, LAS char* shm, int wid) {
;     ...
;     if (MODE == 1) {
;       const LAS bf16_t* stg2 = (const LAS bf16_t*)(shm + LDS_OS2) + wid * 2048;
;       bf16_t* hp = (bf16_t*)(P.ws + WS_H2) + row0 * 1024 + 512 + h * 64;
; #pragma unroll
;       for (int i = 0; i < 4; ++i) { const int row = i * 8 + (lane_e >> 3), ch = lane_e & 7;
;         const u32x4 a = *(const LAS u32x4*)(stg + row * 64 + ch * 8), s2 = *(const LAS u32x4*)(stg2 + row * 64 + ch * 8);
;         const u32x4 oc = ocv[i], bg = bgv[i];
;         u32x4 w;
;         w.x = pk2((bflo(a.x) + bflo(s2.x) + bflo(oc.x)) * bflo(bg.x), (bfhi(a.x) + bfhi(s2.x) + bfhi(oc.x)) * bfhi(bg.x));
;         w.y = pk2((bflo(a.y) + bflo(s2.y) + bflo(oc.y)) * bflo(bg.y), (bfhi(a.y) + bfhi(s2.y) + bfhi(oc.y)) * bfhi(bg.y));
;         w.z = pk2((bflo(a.z) + bflo(s2.z) + bflo(oc.z)) * bflo(bg.z), (bfhi(a.z) + bfhi(s2.z) + bfhi(oc.z)) * bfhi(bg.z));
;         w.w = pk2((bflo(a.w) + bflo(s2.w) + bflo(oc.w)) * bflo(bg.w), (bfhi(a.w) + bfhi(s2.w) + bfhi(oc.w)) * bfhi(bg.w));
;         *(u32x4*)(hp + (long)row * 1024 + ch * 8) = w; }
	v_lshlrev_b32_e32 v29, 16, v65
	v_lshlrev_b32_e32 v28, 16, v64
	v_pk_add_f32 v[18:19], v[18:19], v[22:23]
	v_and_b32_e32 v23, 0xffff0000, v65
	v_and_b32_e32 v22, 0xffff0000, v64
	v_readlane_b32 s9, v250, 54
	s_add_u32 s0, s8, s0
	v_pk_mul_f32 v[26:27], v[26:27], v[28:29]
	v_pk_mul_f32 v[18:19], v[18:19], v[22:23]
	v_lshlrev_b32_e32 v23, 16, v21
	v_lshlrev_b32_e32 v22, 16, v20
	v_lshlrev_b32_e32 v29, 16, v25
	v_lshlrev_b32_e32 v28, 16, v24
	v_and_b32_e32 v21, 0xffff0000, v21
	v_and_b32_e32 v20, 0xffff0000, v20
	v_and_b32_e32 v25, 0xffff0000, v25
	v_and_b32_e32 v24, 0xffff0000, v24
	s_addc_u32 s1, s9, s1
	v_pk_add_f32 v[20:21], v[20:21], v[24:25]
	v_and_b32_e32 v25, 0xffff0000, v63
	v_and_b32_e32 v24, 0xffff0000, v62
	s_add_u32 s0, s0, s24
	v_pk_add_f32 v[22:23], v[22:23], v[28:29]
	v_lshlrev_b32_e32 v29, 16, v63
	v_lshlrev_b32_e32 v28, 16, v62
	v_pk_add_f32 v[20:21], v[20:21], v[24:25]
	v_and_b32_e32 v25, 0xffff0000, v67
	v_and_b32_e32 v24, 0xffff0000, v66
	s_addc_u32 s1, s1, 0
	v_pk_add_f32 v[22:23], v[22:23], v[28:29]
	v_lshlrev_b32_e32 v29, 16, v67
	v_lshlrev_b32_e32 v28, 16, v66
	v_pk_mul_f32 v[20:21], v[20:21], v[24:25]
	v_lshl_add_u64 v[16:17], s[0:1], 0, v[0:1]
	v_pk_mul_f32 v[22:23], v[22:23], v[28:29]
	v_bfe_u32 v0, v21, 16, 1
	v_add3_u32 v0, v21, v0, s3
	v_bfe_u32 v28, v23, 16, 1
	s_mov_b64 s[0:1], 0x13400400
	v_add3_u32 v23, v23, v28, s3
	v_lshl_add_u64 v[16:17], v[16:17], 0, s[0:1]
	v_lshrrev_b32_e32 v21, 16, v23
	s_mov_b32 s0, 0xffff0000
	v_and_or_b32 v21, v0, s0, v21
	v_lshlrev_b32_e32 v0, 7, v70
	v_cvt_pk_bf16_f32 v20, v22, v20
	v_add_u32_e32 v22, v32, v0
	v_add_u32_e32 v0, v33, v0
	v_cvt_pk_bf16_f32 v19, v27, v19
	v_cvt_pk_bf16_f32 v18, v26, v18
	ds_read_b128 v[22:25], v22 offset:55296
	ds_read_b128 v[26:29], v0
	v_lshlrev_b64 v[30:31], 11, v[72:73]
	v_lshl_add_u64 v[30:31], v[16:17], 0, v[30:31]
	global_store_dwordx4 v[30:31], v[18:21], off
	v_lshlrev_b64 v[30:31], 11, v[70:71]
	v_lshl_add_u64 v[30:31], v[16:17], 0, v[30:31]
	s_waitcnt lgkmcnt(1)
	v_lshlrev_b32_e32 v19, 16, v23
	v_lshlrev_b32_e32 v18, 16, v22
	s_waitcnt lgkmcnt(0)
	v_lshlrev_b32_e32 v21, 16, v27
	v_lshlrev_b32_e32 v20, 16, v26
	v_pk_add_f32 v[18:19], v[18:19], v[20:21]
	s_waitcnt vmcnt(6)
	v_lshlrev_b32_e32 v21, 16, v53
	v_lshlrev_b32_e32 v20, 16, v52
	v_pk_add_f32 v[18:19], v[18:19], v[20:21]
	s_waitcnt vmcnt(5)
	v_lshlrev_b32_e32 v21, 16, v57
	v_lshlrev_b32_e32 v20, 16, v56
	v_pk_mul_f32 v[18:19], v[18:19], v[20:21]
	v_and_b32_e32 v21, 0xffff0000, v23
	v_and_b32_e32 v20, 0xffff0000, v22
	v_and_b32_e32 v23, 0xffff0000, v27
	v_and_b32_e32 v22, 0xffff0000, v26
	v_pk_add_f32 v[20:21], v[20:21], v[22:23]
	v_and_b32_e32 v23, 0xffff0000, v53
	v_and_b32_e32 v22, 0xffff0000, v52
	v_pk_add_f32 v[20:21], v[20:21], v[22:23]
	v_and_b32_e32 v23, 0xffff0000, v57
	v_and_b32_e32 v22, 0xffff0000, v56
	v_pk_mul_f32 v[20:21], v[20:21], v[22:23]
	v_lshlrev_b32_e32 v23, 16, v25
	v_lshlrev_b32_e32 v22, 16, v24
	v_lshlrev_b32_e32 v27, 16, v29
	v_lshlrev_b32_e32 v26, 16, v28
	v_pk_add_f32 v[22:23], v[22:23], v[26:27]
	v_lshlrev_b32_e32 v27, 16, v55
	v_lshlrev_b32_e32 v26, 16, v54
	v_pk_add_f32 v[22:23], v[22:23], v[26:27]
	v_lshlrev_b32_e32 v27, 16, v59
	v_lshlrev_b32_e32 v26, 16, v58
	v_pk_mul_f32 v[22:23], v[22:23], v[26:27]
	v_and_b32_e32 v25, 0xffff0000, v25
	v_and_b32_e32 v24, 0xffff0000, v24
	v_and_b32_e32 v27, 0xffff0000, v29
	v_and_b32_e32 v26, 0xffff0000, v28
	v_pk_add_f32 v[24:25], v[24:25], v[26:27]
	v_and_b32_e32 v27, 0xffff0000, v55
	v_and_b32_e32 v26, 0xffff0000, v54
	v_pk_add_f32 v[24:25], v[24:25], v[26:27]
	v_and_b32_e32 v27, 0xffff0000, v59
	v_and_b32_e32 v26, 0xffff0000, v58
	v_pk_mul_f32 v[24:25], v[24:25], v[26:27]
	v_bfe_u32 v28, v20, 16, 1
	v_bfe_u32 v26, v24, 16, 1
	v_bfe_u32 v0, v25, 16, 1
	v_bfe_u32 v27, v21, 16, 1
	v_add3_u32 v28, v20, v28, s3
	v_add3_u32 v20, v24, v26, s3
	v_bfe_u32 v26, v23, 16, 1
	v_add3_u32 v27, v21, v27, s3
	v_add3_u32 v0, v25, v0, s3
	v_bfe_u32 v21, v18, 16, 1
	v_bfe_u32 v25, v22, 16, 1
	v_add3_u32 v23, v23, v26, s3
	v_bfe_u32 v24, v19, 16, 1
	v_add3_u32 v22, v22, v25, s3
	v_add3_u32 v18, v18, v21, s3
	v_lshrrev_b32_e32 v21, 16, v23
	v_add3_u32 v19, v19, v24, s3
	v_lshrrev_b32_e32 v22, 16, v22
	v_and_or_b32 v21, v0, s0, v21
	v_lshlrev_b32_e32 v0, 7, v68
	v_lshrrev_b32_e32 v18, 16, v18
	v_lshrrev_b32_e32 v19, 16, v19
	v_and_or_b32 v20, v20, s0, v22
	v_add_u32_e32 v22, v32, v0
	v_add_u32_e32 v0, v33, v0
	v_and_or_b32 v19, v27, s0, v19
	v_and_or_b32 v18, v28, s0, v18
	ds_read_b128 v[22:25], v22 offset:55296
	ds_read_b128 v[26:29], v0
	global_store_dwordx4 v[30:31], v[18:21], off
	v_readlane_b32 s5, v250, 50
	v_readlane_b32 s6, v250, 51
	s_waitcnt lgkmcnt(1)
; #define LAS __attribute__((address_space(3)))
; __device__ __forceinline__ unsigned pk2(float lo, float hi) { return f2bf(lo) | (f2bf(hi) << 16); }
; template <int MODE, int THRL>
; __device__ __forceinline__ void attn_unit(const Prm& P, int b, int h, int qb, LAS char* shm, int wid) {
;     ...
;     if (MODE == 1) {
;       const LAS bf16_t* stg2 = (const LAS bf16_t*)(shm + LDS_OS2) + wid * 2048;
;       bf16_t* hp = (bf16_t*)(P.ws + WS_H2) + row0 * 1024 + 512 + h * 64;
; #pragma unroll
;       for (int i = 0; i < 4; ++i) { const int row = i * 8 + (lane_e >> 3), ch = lane_e & 7;
;         const u32x4 a = *(const LAS u32x4*)(stg + row * 64 + ch * 8), s2 = *(const LAS u32x4*)(stg2 + row * 64 + ch * 8);
;         const u32x4 oc = ocv[i], bg = bgv[i];
;         u32x4 w;
;         w.x = pk2((bflo(a.x) + bflo(s2.x) + bflo(oc.x)) * bflo(bg.x), (bfhi(a.x) + bfhi(s2.x) + bfhi(oc.x)) * bfhi(bg.x));
;         w.y = pk2((bflo(a.y) + bflo(s2.y) + bflo(oc.y)) * bflo(bg.y), (bfhi(a.y) + bfhi(s2.y) + bfhi(oc.y)) * bfhi(bg.y));
;         w.z = pk2((bflo(a.z) + bflo(s2.z) + bflo(oc.z)) * bflo(bg.z), (bfhi(a.z) + bfhi(s2.z) + bfhi(oc.z)) * bfhi(bg.z));
;         w.w = pk2((bflo(a.w) + bflo(s2.w) + bflo(oc.w)) * bflo(bg.w), (bfhi(a.w) + bfhi(s2.w) + bfhi(oc.w)) * bfhi(bg.w));
;         *(u32x4*)(hp + (long)row * 1024 + ch * 8) = w; }
;     }
;   }
;   asm volatile("s_waitcnt vmcnt(0) lgkmcnt(0)\n\ts_barrier" ::: "memory");
	v_lshlrev_b32_e32 v19, 16, v23
	v_lshlrev_b32_e32 v18, 16, v22
	s_waitcnt lgkmcnt(0)
	v_lshlrev_b32_e32 v21, 16, v27
	v_lshlrev_b32_e32 v20, 16, v26
	v_pk_add_f32 v[18:19], v[18:19], v[20:21]
	s_waitcnt vmcnt(5)
	v_lshlrev_b32_e32 v21, 16, v11
	v_lshlrev_b32_e32 v20, 16, v10
	v_pk_add_f32 v[18:19], v[18:19], v[20:21]
	s_waitcnt vmcnt(4)
	v_lshlrev_b32_e32 v21, 16, v49
	v_lshlrev_b32_e32 v20, 16, v48
	v_pk_mul_f32 v[18:19], v[18:19], v[20:21]
	v_and_b32_e32 v21, 0xffff0000, v23
	v_and_b32_e32 v20, 0xffff0000, v22
	v_and_b32_e32 v23, 0xffff0000, v27
	v_and_b32_e32 v22, 0xffff0000, v26
	v_pk_add_f32 v[20:21], v[20:21], v[22:23]
	v_and_b32_e32 v11, 0xffff0000, v11
	v_and_b32_e32 v10, 0xffff0000, v10
	v_pk_add_f32 v[10:11], v[20:21], v[10:11]
	v_and_b32_e32 v21, 0xffff0000, v49
	v_and_b32_e32 v20, 0xffff0000, v48
	v_pk_mul_f32 v[10:11], v[10:11], v[20:21]
	v_lshlrev_b32_e32 v21, 16, v25
	v_lshlrev_b32_e32 v20, 16, v24
	v_lshlrev_b32_e32 v23, 16, v29
	v_lshlrev_b32_e32 v22, 16, v28
	v_pk_add_f32 v[20:21], v[20:21], v[22:23]
	v_lshlrev_b32_e32 v23, 16, v13
	v_lshlrev_b32_e32 v22, 16, v12
	v_pk_add_f32 v[20:21], v[20:21], v[22:23]
	v_lshlrev_b32_e32 v23, 16, v51
	v_lshlrev_b32_e32 v22, 16, v50
	v_pk_mul_f32 v[20:21], v[20:21], v[22:23]
	v_and_b32_e32 v23, 0xffff0000, v25
	v_and_b32_e32 v22, 0xffff0000, v24
	v_and_b32_e32 v25, 0xffff0000, v29
	v_and_b32_e32 v24, 0xffff0000, v28
	v_pk_add_f32 v[22:23], v[22:23], v[24:25]
	v_and_b32_e32 v13, 0xffff0000, v13
	v_and_b32_e32 v12, 0xffff0000, v12
	v_pk_add_f32 v[12:13], v[22:23], v[12:13]
	v_and_b32_e32 v23, 0xffff0000, v51
	v_and_b32_e32 v22, 0xffff0000, v50
	v_pk_mul_f32 v[12:13], v[12:13], v[22:23]
	v_bfe_u32 v0, v13, 16, 1
	v_add3_u32 v0, v13, v0, s3
	v_bfe_u32 v24, v21, 16, 1
	v_add3_u32 v21, v21, v24, s3
	v_lshrrev_b32_e32 v13, 16, v21
	v_and_or_b32 v13, v0, s0, v13
	v_lshlrev_b32_e32 v0, 7, v14
	v_cvt_pk_bf16_f32 v10, v18, v10
	v_add_u32_e32 v18, v32, v0
	v_add_u32_e32 v0, v33, v0
	v_cvt_pk_bf16_f32 v12, v20, v12
	v_cvt_pk_bf16_f32 v11, v19, v11
	ds_read_b128 v[18:21], v18 offset:55296
	ds_read_b128 v[22:25], v0
	v_lshlrev_b64 v[26:27], 11, v[68:69]
	v_lshl_add_u64 v[26:27], v[16:17], 0, v[26:27]
	global_store_dwordx4 v[26:27], v[10:13], off
	v_readlane_b32 s7, v250, 52
	v_readlane_b32 s10, v250, 55
	s_waitcnt lgkmcnt(1)
	v_lshlrev_b32_e32 v11, 16, v19
	v_lshlrev_b32_e32 v10, 16, v18
	s_waitcnt lgkmcnt(0)
	v_lshlrev_b32_e32 v13, 16, v23
	v_lshlrev_b32_e32 v12, 16, v22
	v_pk_add_f32 v[10:11], v[10:11], v[12:13]
	s_waitcnt vmcnt(4)
	v_lshlrev_b32_e32 v13, 16, v3
	v_lshlrev_b32_e32 v12, 16, v2
	v_pk_add_f32 v[10:11], v[10:11], v[12:13]
	s_waitcnt vmcnt(3)
	v_lshlrev_b32_e32 v13, 16, v7
	v_lshlrev_b32_e32 v12, 16, v6
	v_pk_mul_f32 v[10:11], v[10:11], v[12:13]
	v_and_b32_e32 v13, 0xffff0000, v19
	v_and_b32_e32 v12, 0xffff0000, v18
	v_and_b32_e32 v19, 0xffff0000, v23
	v_and_b32_e32 v18, 0xffff0000, v22
	v_pk_add_f32 v[12:13], v[12:13], v[18:19]
	v_and_b32_e32 v3, 0xffff0000, v3
	v_and_b32_e32 v2, 0xffff0000, v2
	v_pk_add_f32 v[2:3], v[12:13], v[2:3]
	v_and_b32_e32 v7, 0xffff0000, v7
	v_and_b32_e32 v6, 0xffff0000, v6
	v_pk_mul_f32 v[2:3], v[2:3], v[6:7]
	v_lshlrev_b32_e32 v7, 16, v21
	v_lshlrev_b32_e32 v6, 16, v20
	v_lshlrev_b32_e32 v13, 16, v25
	v_lshlrev_b32_e32 v12, 16, v24
	v_pk_add_f32 v[6:7], v[6:7], v[12:13]
	v_lshlrev_b32_e32 v13, 16, v5
	v_lshlrev_b32_e32 v12, 16, v4
	v_pk_add_f32 v[6:7], v[6:7], v[12:13]
	v_lshlrev_b32_e32 v13, 16, v9
	v_lshlrev_b32_e32 v12, 16, v8
	v_pk_mul_f32 v[6:7], v[6:7], v[12:13]
	v_and_b32_e32 v13, 0xffff0000, v21
	v_and_b32_e32 v12, 0xffff0000, v20
	v_and_b32_e32 v19, 0xffff0000, v25
	v_and_b32_e32 v18, 0xffff0000, v24
	v_pk_add_f32 v[12:13], v[12:13], v[18:19]
	v_and_b32_e32 v5, 0xffff0000, v5
	v_and_b32_e32 v4, 0xffff0000, v4
	v_pk_add_f32 v[4:5], v[12:13], v[4:5]
	v_and_b32_e32 v9, 0xffff0000, v9
	v_and_b32_e32 v8, 0xffff0000, v8
	v_pk_mul_f32 v[4:5], v[4:5], v[8:9]
	v_bfe_u32 v0, v5, 16, 1
	v_add3_u32 v0, v5, v0, s3
	v_bfe_u32 v12, v7, 16, 1
	v_add3_u32 v7, v7, v12, s3
	v_lshrrev_b32_e32 v5, 16, v7
	v_cvt_pk_bf16_f32 v4, v6, v4
	v_lshlrev_b64 v[6:7], 11, v[14:15]
	v_and_or_b32 v5, v0, s0, v5
	v_cvt_pk_bf16_f32 v3, v11, v3
	v_cvt_pk_bf16_f32 v2, v10, v2
	v_lshl_add_u64 v[6:7], v[16:17], 0, v[6:7]
	global_store_dwordx4 v[6:7], v[2:5], off
	s_waitcnt lgkmcnt(0)
	s_barrier
	v_readlane_b32 s0, v251, 63
	s_add_i32 s0, s0, 1
	s_mov_b64 s[2:3], 0
	v_writelane_b32 v251, s0, 63
	v_readlane_b32 s11, v250, 56

; __device__ __forceinline__ unsigned pk2(float lo, float hi) { return f2bf(lo) | (f2bf(hi) << 16); }
; __device__ __forceinline__ float ex2(float x) { return __builtin_amdgcn_exp2f(x); }
; __device__ __forceinline__ float quad_sum(float v) { v += __int_as_float(dpp_x1(__float_as_int(v))); v += __int_as_float(dpp_x2(__float_as_int(v))); return v; }
; __device__ __forceinline__ bf16x8 pack8(const f32x16& p, int base) {
;     u32x4 w; w.x = pk2(p[base + 0], p[base + 1]); w.y = pk2(p[base + 2], p[base + 3]); w.z = pk2(p[base + 4], p[base + 5]); w.w = pk2(p[base + 6], p[base + 7]);
;     return __builtin_bit_cast(bf16x8, w);
; }
; __device__ __forceinline__ void sample_task(const Prm& P, Ctx& C, int task) {
;     ...
;         float M = NEGB;
; #pragma unroll
;         for (int w = 0; w < 8; ++w) M = fmaxf(M, ml[(w * 32 + q) * 2]);
;         float L = 0.f;
; #pragma unroll
;         for (int w = 0; w < 8; ++w) L += ml[(w * 32 + q) * 2 + 1] * ex2(ml[(w * 32 + q) * 2] - M);
;         const float invl = L > 0.f ? 1.f / L : 0.f;
;         f32x16 o[2]; o[0] = f32x16{}; o[1] = f32x16{};
; #pragma unroll
;         for (int tt = 0; tt < 4; ++tt) { const int tile = C.wave + 8 * tt;
; #pragma unroll
;             for (int r = 0; r < 16; ++r) S[tt][r] = (S[tt][r] > -1e29f) ? ex2(S[tt][r] - M) * invl : 0.f;
; #pragma unroll
;             for (int i = 0; i < 4; ++i) { const float v = quad_sum(S[tt][4 * i] + S[tt][4 * i + 1] + S[tt][4 * i + 2]); if (g == 0) sc[slot * 256 + 8 * tile + 2 * i + hi] = v; }
.LBB0_1494:
	s_or_b64 exec, exec, vcc
	v_add_u32_e32 v0, 0x4000, v197
	s_waitcnt lgkmcnt(0)
	s_barrier
	ds_read2_b64 v[66:69], v0 offset1:32
	ds_read2_b64 v[70:73], v0 offset0:64 offset1:96
	ds_read2_b64 v[74:77], v0 offset0:128 offset1:160
	ds_read2_b64 v[78:81], v0 offset0:192 offset1:224
	s_mov_b32 s78, 0xf149f2ca
	s_waitcnt lgkmcnt(3)
	v_max3_f32 v0, v66, s78, v68
	s_waitcnt lgkmcnt(2)
	v_max3_f32 v0, v0, v70, v72
	s_waitcnt lgkmcnt(1)
	v_max3_f32 v0, v0, v74, v76
	s_waitcnt lgkmcnt(0)
	v_max3_f32 v0, v0, v78, v80
	v_sub_f32_e32 v66, v66, v0
	v_exp_f32_e32 v171, v66
	v_sub_f32_e32 v66, v68, v0
	v_exp_f32_e32 v170, v66
	v_sub_f32_e32 v68, v70, v0
	v_mov_b32_e32 v66, v69
	v_exp_f32_e32 v69, v68
	v_sub_f32_e32 v68, v72, v0
	v_exp_f32_e32 v68, v68
	v_pk_mul_f32 v[66:67], v[66:67], v[170:171]
	v_mov_b32_e32 v70, v73
	v_add_f32_e32 v67, 0, v67
	v_add_f32_e32 v72, v66, v67
	v_pk_mul_f32 v[66:67], v[68:69], v[70:71]
	v_sub_f32_e32 v68, v74, v0
	v_exp_f32_e32 v69, v68
	v_sub_f32_e32 v68, v76, v0
	v_exp_f32_e32 v68, v68
	v_add_f32_e32 v67, v67, v72
	v_mov_b32_e32 v74, v77
	v_add_f32_e32 v70, v66, v67
	v_pk_mul_f32 v[66:67], v[68:69], v[74:75]
	v_sub_f32_e32 v68, v78, v0
	v_exp_f32_e32 v69, v68
	v_sub_f32_e32 v68, v80, v0
	v_exp_f32_e32 v68, v68
	v_add_f32_e32 v67, v67, v70
	v_mov_b32_e32 v78, v81
	v_add_f32_e32 v70, v66, v67
	v_pk_mul_f32 v[66:67], v[68:69], v[78:79]
	v_sub_f32_e32 v50, v50, v0
	v_add_f32_e32 v67, v67, v70
	v_add_f32_e32 v66, v66, v67
	v_div_scale_f32 v67, s[82:83], v66, v66, 1.0
	v_rcp_f32_e32 v68, v67
	v_exp_f32_e32 v50, v50
	v_sub_f32_e32 v53, v53, v0
	v_exp_f32_e32 v53, v53
	v_fma_f32 v69, -v67, v68, 1.0
	v_fmac_f32_e32 v68, v69, v68
	v_div_scale_f32 v69, vcc, 1.0, v66, 1.0
	v_mul_f32_e32 v70, v69, v68
	v_fma_f32 v71, -v67, v70, v69
	v_fmac_f32_e32 v70, v71, v68
	v_fma_f32 v67, -v67, v70, v69
	v_div_fmas_f32 v67, v67, v68, v70
	v_div_fixup_f32 v67, v67, v66, 1.0
	v_cmp_lt_f32_e32 vcc, 0, v66
	v_sub_f32_e32 v66, v51, v0
	v_sub_f32_e32 v51, v52, v0
	v_exp_f32_e32 v51, v51
	v_exp_f32_e32 v52, v66
	v_cndmask_b32_e32 v170, 0, v67, vcc
	v_pk_mul_f32 v[50:51], v[50:51], v[170:171] op_sel_hi:[1,0]
	s_nop 0
	v_cndmask_b32_e64 v66, 0, v51, s[76:77]
	v_cndmask_b32_e64 v67, 0, v50, s[74:75]
	v_pk_mul_f32 v[50:51], v[52:53], v[170:171] op_sel_hi:[1,0]
	s_nop 0
	v_cndmask_b32_e64 v50, 0, v50, s[72:73]
	v_add_f32_e32 v52, v67, v50
	v_add_f32_e32 v52, v66, v52
	s_nop 1
	v_add_f32_dpp v52, v52, v52 quad_perm:[1,0,3,2] row_mask:0xf bank_mask:0xf bound_ctrl:1
	s_nop 1
	v_mov_b32_dpp v53, v52 quad_perm:[2,3,0,1] row_mask:0xf bank_mask:0xf bound_ctrl:1
	s_mov_b64 s[72:73], exec
	v_readlane_b32 s74, v251, 0
	v_readlane_b32 s75, v251, 1
	s_and_b64 s[74:75], s[72:73], s[74:75]
	s_mov_b64 exec, s[74:75]
	v_add_f32_e32 v52, v52, v53
	ds_write_b32 v179, v52
	s_or_b64 exec, exec, s[72:73]
	v_sub_f32_e32 v53, v55, v0
	v_sub_f32_e32 v52, v54, v0
	v_exp_f32_e32 v54, v53
	v_sub_f32_e32 v53, v56, v0
	v_sub_f32_e32 v55, v57, v0
	v_exp_f32_e32 v52, v52
	v_exp_f32_e32 v53, v53
	v_exp_f32_e32 v55, v55
	v_mov_b32_e32 v171, v170
	v_pk_mul_f32 v[56:57], v[52:53], v[170:171]
	v_pk_mul_f32 v[52:53], v[54:55], v[170:171]
	v_cndmask_b32_e64 v68, 0, v56, s[64:65]
	v_cndmask_b32_e64 v69, 0, v52, s[66:67]
	v_cndmask_b32_e64 v57, 0, v57, s[70:71]
	v_add_f32_e32 v52, v68, v69
	v_add_f32_e32 v52, v57, v52
	s_nop 1
	v_add_f32_dpp v52, v52, v52 quad_perm:[1,0,3,2] row_mask:0xf bank_mask:0xf bound_ctrl:1
	s_nop 1
	v_mov_b32_dpp v54, v52 quad_perm:[2,3,0,1] row_mask:0xf bank_mask:0xf bound_ctrl:1
	s_mov_b64 s[64:65], exec
	v_readlane_b32 s66, v251, 0
	v_readlane_b32 s67, v251, 1
	s_and_b64 s[66:67], s[64:65], s[66:67]
	s_mov_b64 exec, s[66:67]
	v_add_f32_e32 v52, v52, v54
	ds_write_b32 v179, v52 offset:8
	s_or_b64 exec, exec, s[64:65]
	v_sub_f32_e32 v52, v58, v0
	v_exp_f32_e32 v54, v52
	v_sub_f32_e32 v52, v59, v0
	v_exp_f32_e32 v58, v52
	v_sub_f32_e32 v52, v60, v0
	v_exp_f32_e32 v55, v52
	v_sub_f32_e32 v52, v61, v0
	v_exp_f32_e32 v59, v52
	v_pk_mul_f32 v[60:61], v[54:55], v[170:171]
	s_nop 0
	v_cndmask_b32_e64 v52, 0, v60, s[60:61]
	v_pk_mul_f32 v[54:55], v[58:59], v[170:171]
	v_cndmask_b32_e64 v56, 0, v61, s[68:69]
	v_cndmask_b32_e64 v54, 0, v54, s[62:63]
	v_add_f32_e32 v58, v52, v54
	v_add_f32_e32 v58, v56, v58
	s_nop 1
	v_add_f32_dpp v58, v58, v58 quad_perm:[1,0,3,2] row_mask:0xf bank_mask:0xf bound_ctrl:1
	s_nop 1
	v_mov_b32_dpp v59, v58 quad_perm:[2,3,0,1] row_mask:0xf bank_mask:0xf bound_ctrl:1
	s_mov_b64 s[60:61], exec
	v_readlane_b32 s62, v251, 0
	v_readlane_b32 s63, v251, 1
	s_and_b64 s[62:63], s[60:61], s[62:63]
	s_mov_b64 exec, s[62:63]
	v_add_f32_e32 v58, v58, v59
	ds_write_b32 v179, v58 offset:16
	s_or_b64 exec, exec, s[60:61]
	v_cndmask_b32_e64 v58, 0, v53, s[48:49]
	v_sub_f32_e32 v53, v62, v0
	v_exp_f32_e32 v60, v53
	v_sub_f32_e32 v53, v63, v0
	v_exp_f32_e32 v62, v53
	v_sub_f32_e32 v53, v64, v0
	v_exp_f32_e32 v61, v53
	v_sub_f32_e32 v53, v65, v0
	v_exp_f32_e32 v63, v53
	v_cndmask_b32_e64 v59, 0, v51, s[46:47]
	v_pk_mul_f32 v[60:61], v[60:61], v[170:171]
	v_cndmask_b32_e64 v51, 0, v55, s[58:59]
	v_pk_mul_f32 v[62:63], v[62:63], v[170:171]
	v_cndmask_b32_e64 v53, 0, v61, s[54:55]
	v_cndmask_b32_e64 v55, 0, v60, s[50:51]
	v_cndmask_b32_e64 v61, 0, v62, s[52:53]
	v_add_f32_e32 v62, v55, v61
	v_add_f32_e32 v62, v53, v62
	v_cndmask_b32_e64 v60, 0, v63, s[56:57]
	s_nop 0
	v_add_f32_dpp v62, v62, v62 quad_perm:[1,0,3,2] row_mask:0xf bank_mask:0xf bound_ctrl:1
	s_nop 1
	v_mov_b32_dpp v63, v62 quad_perm:[2,3,0,1] row_mask:0xf bank_mask:0xf bound_ctrl:1
	s_mov_b64 s[46:47], exec
	v_readlane_b32 s48, v251, 0
	v_readlane_b32 s49, v251, 1
	s_and_b64 s[48:49], s[46:47], s[48:49]
	s_mov_b64 exec, s[48:49]
	v_add_f32_e32 v62, v62, v63
	ds_write_b32 v179, v62 offset:24
	s_or_b64 exec, exec, s[46:47]
	v_bfe_u32 v63, v69, 16, 1
	s_movk_i32 s46, 0x7fff
	v_add3_u32 v63, v69, v63, s46
	v_bfe_u32 v62, v67, 16, 1
	v_bfe_u32 v65, v50, 16, 1
	v_add3_u32 v62, v67, v62, s46
	s_waitcnt vmcnt(15)
; #define LAS __attribute__((address_space(3)))
; __device__ __forceinline__ unsigned pk2(float lo, float hi) { return f2bf(lo) | (f2bf(hi) << 16); }
; #define LDS_WAIT() asm volatile("s_waitcnt lgkmcnt(0)" ::: "memory")
; #define MFMA32(a, b, c) __builtin_amdgcn_mfma_f32_32x32x16_bf16((a), (b), (c), 0, 0, 0)
; __device__ __forceinline__ bf16x8 pack8(const f32x16& p, int base) {
;     u32x4 w; w.x = pk2(p[base + 0], p[base + 1]); w.y = pk2(p[base + 2], p[base + 3]); w.z = pk2(p[base + 4], p[base + 5]); w.w = pk2(p[base + 6], p[base + 7]);
;     return __builtin_bit_cast(bf16x8, w);
; }
; __device__ __forceinline__ void sample_task(const Prm& P, Ctx& C, int task) {
;     ...
;             {
;                 const int key = lane >> 1, d0 = 32 * (lane & 1);
; #pragma unroll
;                 for (int c = 0; c < 4; ++c) { const unsigned w[4] = {vld[tt][c].x, vld[tt][c].y, vld[tt][c].z, vld[tt][c].w};
; #pragma unroll
;                     for (int e = 0; e < 4; ++e) { vts[(d0 + 8 * c + 2 * e) * 36 + key] = (bf16_t)(w[e] & 0xffffu); vts[(d0 + 8 * c + 2 * e + 1) * 36 + key] = (bf16_t)(w[e] >> 16); } }
;             }
;             LDS_WAIT();
;             bf16x8 pf[2]; pf[0] = pack8(S[tt], 0); pf[1] = pack8(S[tt], 8);
; #pragma unroll
;             for (int dblk = 0; dblk < 2; ++dblk)
; #pragma unroll
;                 for (int ks = 0; ks < 2; ++ks) { const LAS bf16_t* vp = vts + (32 * dblk + q) * 36 + 16 * ks + 4 * hi;
;                     const s16x4 lo = *(const LAS s16x4*)vp, hh = *(const LAS s16x4*)(vp + 8);
;                     o[dblk] = MFMA32(((bf16x8){lo[0], lo[1], lo[2], lo[3], hh[0], hh[1], hh[2], hh[3]}), pf[ks], o[dblk]); }
	ds_write_b16 v181, v142 offset:18432
	ds_write_b16_d16_hi v181, v142 offset:18504
	ds_write_b16 v181, v143 offset:18576
	ds_write_b16_d16_hi v181, v143 offset:18648
	ds_write_b16 v181, v144 offset:18720
	ds_write_b16_d16_hi v181, v144 offset:18792
	ds_write_b16 v181, v145 offset:18864
	ds_write_b16_d16_hi v181, v145 offset:18936
	s_waitcnt vmcnt(14)
	ds_write_b16 v181, v138 offset:19008
	ds_write_b16_d16_hi v181, v138 offset:19080
	ds_write_b16 v181, v139 offset:19152
	ds_write_b16_d16_hi v181, v139 offset:19224
	ds_write_b16 v181, v140 offset:19296
	ds_write_b16_d16_hi v181, v140 offset:19368
	ds_write_b16 v181, v141 offset:19440
	ds_write_b16_d16_hi v181, v141 offset:19512
	s_waitcnt vmcnt(13)
	ds_write_b16 v181, v134 offset:19584
	ds_write_b16_d16_hi v181, v134 offset:19656
	ds_write_b16 v181, v135 offset:19728
	ds_write_b16_d16_hi v181, v135 offset:19800
	ds_write_b16 v181, v136 offset:19872
	ds_write_b16_d16_hi v181, v136 offset:19944
	ds_write_b16 v181, v137 offset:20016
	ds_write_b16_d16_hi v181, v137 offset:20088
	s_waitcnt vmcnt(12)
	ds_write_b16 v181, v130 offset:20160
	ds_write_b16_d16_hi v181, v130 offset:20232
	ds_write_b16 v181, v131 offset:20304
	ds_write_b16_d16_hi v181, v131 offset:20376
	ds_write_b16 v181, v132 offset:20448
	ds_write_b16_d16_hi v181, v132 offset:20520
	ds_write_b16 v181, v133 offset:20592
	ds_write_b16_d16_hi v181, v133 offset:20664
	v_add3_u32 v50, v50, v65, s46
	v_lshrrev_b32_e32 v62, 16, v62
	s_mov_b32 s47, 0xffff0000
	s_waitcnt lgkmcnt(0)
	v_cvt_pk_bf16_f32 v69, v57, v58
	v_cvt_pk_bf16_f32 v67, v66, v59
	v_and_or_b32 v66, v50, s47, v62
	v_bfe_u32 v50, v60, 16, 1
	v_bfe_u32 v57, v61, 16, 1
	v_bfe_u32 v58, v51, 16, 1
	v_bfe_u32 v59, v54, 16, 1
	v_add_u32_e32 v130, 0x4800, v201
	v_add3_u32 v74, v54, v59, s46
	v_add3_u32 v75, v51, v58, s46
	v_add3_u32 v76, v61, v57, s46
	v_add3_u32 v77, v60, v50, s46
	ds_read2_b64 v[58:61], v130 offset1:2
	v_bfe_u32 v65, v68, 16, 1
	v_add3_u32 v65, v68, v65, s46
	v_lshrrev_b32_e32 v65, 16, v65
	v_bfe_u32 v50, v52, 16, 1
	v_and_or_b32 v68, v63, s47, v65
	v_bfe_u32 v51, v56, 16, 1
	v_bfe_u32 v54, v55, 16, 1
	v_bfe_u32 v57, v53, 16, 1
	v_add3_u32 v50, v52, v50, s46
	ds_read2_b64 v[70:73], v130 offset0:4 offset1:6
	v_add3_u32 v78, v53, v57, s46
	v_add3_u32 v79, v55, v54, s46
	v_add3_u32 v80, v56, v51, s46
	v_lshrrev_b32_e32 v81, 16, v50
	s_waitcnt lgkmcnt(1)
	v_mfma_f32_32x32x16_bf16 v[50:65], v[58:61], v[66:69], 0
	v_lshrrev_b32_e32 v80, 16, v80
	v_lshrrev_b32_e32 v79, 16, v79
	v_lshrrev_b32_e32 v78, 16, v78
	v_and_or_b32 v135, v77, s47, v78
	v_and_or_b32 v134, v76, s47, v79
	v_and_or_b32 v133, v75, s47, v80
	v_and_or_b32 v132, v74, s47, v81
	v_add_u32_e32 v131, 0x5000, v201
	ds_read2_b64 v[136:139], v131 offset0:36 offset1:38
	s_waitcnt lgkmcnt(1)
	v_mfma_f32_32x32x16_bf16 v[50:65], v[70:73], v[132:135], v[50:65]
	ds_read2_b64 v[70:73], v131 offset0:32 offset1:34
	v_sub_f32_e32 v2, v2, v0
	v_exp_f32_e32 v2, v2
	v_sub_f32_e32 v5, v5, v0
	v_exp_f32_e32 v5, v5
	s_waitcnt lgkmcnt(0)
	s_waitcnt lgkmcnt(0)
	v_mfma_f32_32x32x16_bf16 v[66:81], v[70:73], v[66:69], 0
	v_mfma_f32_32x32x16_bf16 v[66:81], v[136:139], v[132:135], v[66:81]
	v_sub_f32_e32 v132, v3, v0
	v_sub_f32_e32 v3, v4, v0
	v_exp_f32_e32 v3, v3
	v_exp_f32_e32 v4, v132
	v_pk_mul_f32 v[2:3], v[2:3], v[170:171]
	s_nop 0
	v_cndmask_b32_e64 v132, 0, v3, s[40:41]
	v_cndmask_b32_e64 v133, 0, v2, s[38:39]
	v_pk_mul_f32 v[2:3], v[4:5], v[170:171]
	s_nop 0
	v_cndmask_b32_e64 v2, 0, v2, s[44:45]
	v_add_f32_e32 v4, v133, v2
	v_add_f32_e32 v4, v132, v4
	s_nop 1
	v_add_f32_dpp v4, v4, v4 quad_perm:[1,0,3,2] row_mask:0xf bank_mask:0xf bound_ctrl:1
	s_nop 1
	v_mov_b32_dpp v5, v4 quad_perm:[2,3,0,1] row_mask:0xf bank_mask:0xf bound_ctrl:1
	s_mov_b64 s[38:39], exec
	v_readlane_b32 s40, v251, 0
	v_readlane_b32 s41, v251, 1
	s_and_b64 s[40:41], s[38:39], s[40:41]
	s_mov_b64 exec, s[40:41]
	v_add_f32_e32 v4, v4, v5
	ds_write_b32 v179, v4 offset:256
	s_or_b64 exec, exec, s[38:39]
	v_sub_f32_e32 v5, v7, v0
	v_sub_f32_e32 v4, v6, v0
	v_exp_f32_e32 v6, v5
	v_sub_f32_e32 v5, v8, v0
	v_sub_f32_e32 v7, v9, v0
	v_exp_f32_e32 v4, v4
	v_exp_f32_e32 v5, v5
	v_exp_f32_e32 v7, v7
	v_pk_mul_f32 v[8:9], v[4:5], v[170:171]
	v_pk_mul_f32 v[4:5], v[6:7], v[170:171]
	v_cndmask_b32_e64 v135, 0, v8, s[30:31]
	v_cndmask_b32_e64 v136, 0, v4, s[34:35]
	v_cndmask_b32_e64 v134, 0, v9, s[42:43]
	v_add_f32_e32 v4, v135, v136
	v_add_f32_e32 v4, v134, v4
	s_nop 1
	v_add_f32_dpp v4, v4, v4 quad_perm:[1,0,3,2] row_mask:0xf bank_mask:0xf bound_ctrl:1
	s_nop 1
	v_mov_b32_dpp v6, v4 quad_perm:[2,3,0,1] row_mask:0xf bank_mask:0xf bound_ctrl:1
	s_mov_b64 s[30:31], exec
	v_readlane_b32 s34, v251, 0
	v_readlane_b32 s35, v251, 1
	s_and_b64 s[34:35], s[30:31], s[34:35]
	s_mov_b64 exec, s[34:35]
	v_add_f32_e32 v4, v4, v6
	ds_write_b32 v179, v4 offset:264
	s_or_b64 exec, exec, s[30:31]
	v_sub_f32_e32 v4, v10, v0
	v_exp_f32_e32 v6, v4
	v_sub_f32_e32 v4, v11, v0
	v_exp_f32_e32 v8, v4
	v_sub_f32_e32 v4, v12, v0
	v_exp_f32_e32 v7, v4
	v_sub_f32_e32 v4, v13, v0
	v_exp_f32_e32 v9, v4
	v_pk_mul_f32 v[12:13], v[6:7], v[170:171]
	s_nop 0
	v_cndmask_b32_e64 v4, 0, v12, s[24:25]
	v_pk_mul_f32 v[6:7], v[8:9], v[170:171]
	v_cndmask_b32_e64 v10, 0, v13, s[36:37]
	v_cndmask_b32_e64 v6, 0, v6, s[26:27]
	v_add_f32_e32 v8, v4, v6
	v_add_f32_e32 v8, v10, v8
	s_nop 1
	v_add_f32_dpp v8, v8, v8 quad_perm:[1,0,3,2] row_mask:0xf bank_mask:0xf bound_ctrl:1
	s_nop 1
	v_mov_b32_dpp v9, v8 quad_perm:[2,3,0,1] row_mask:0xf bank_mask:0xf bound_ctrl:1
	s_mov_b64 s[24:25], exec
	v_readlane_b32 s26, v251, 0
	v_readlane_b32 s27, v251, 1
	s_and_b64 s[26:27], s[24:25], s[26:27]
	s_mov_b64 exec, s[26:27]
	v_add_f32_e32 v8, v8, v9
	ds_write_b32 v179, v8 offset:272
	s_or_b64 exec, exec, s[24:25]
	v_sub_f32_e32 v9, v15, v0
	v_sub_f32_e32 v8, v14, v0
	v_exp_f32_e32 v12, v9
	v_sub_f32_e32 v9, v16, v0
	v_sub_f32_e32 v11, v17, v0
	v_exp_f32_e32 v8, v8
	v_exp_f32_e32 v9, v9
	v_exp_f32_e32 v13, v11
	v_pk_mul_f32 v[14:15], v[8:9], v[170:171]
	v_pk_mul_f32 v[8:9], v[12:13], v[170:171]
	v_cndmask_b32_e64 v12, 0, v14, s[20:21]
	v_cndmask_b32_e64 v8, 0, v8, s[22:23]
	v_cndmask_b32_e64 v11, 0, v15, s[28:29]
	v_add_f32_e32 v13, v12, v8
	v_add_f32_e32 v13, v11, v13
	s_nop 1
	v_add_f32_dpp v13, v13, v13 quad_perm:[1,0,3,2] row_mask:0xf bank_mask:0xf bound_ctrl:1
	s_nop 1
	v_mov_b32_dpp v14, v13 quad_perm:[2,3,0,1] row_mask:0xf bank_mask:0xf bound_ctrl:1
	s_mov_b64 s[20:21], exec
	v_readlane_b32 s22, v251, 0
	v_readlane_b32 s23, v251, 1
	s_and_b64 s[22:23], s[20:21], s[22:23]
	s_mov_b64 exec, s[22:23]
	v_add_f32_e32 v13, v13, v14
	ds_write_b32 v179, v13 offset:280
	s_or_b64 exec, exec, s[20:21]
	v_cndmask_b32_e64 v3, 0, v3, s[8:9]
	v_cndmask_b32_e64 v5, 0, v5, s[10:11]
	s_movk_i32 s8, 0x7fff
	v_cndmask_b32_e64 v7, 0, v7, s[16:17]
	v_cndmask_b32_e64 v9, 0, v9, s[18:19]
	s_waitcnt vmcnt(11)
; #define LAS __attribute__((address_space(3)))
; __device__ __forceinline__ unsigned pk2(float lo, float hi) { return f2bf(lo) | (f2bf(hi) << 16); }
; #define LDS_WAIT() asm volatile("s_waitcnt lgkmcnt(0)" ::: "memory")
; #define MFMA32(a, b, c) __builtin_amdgcn_mfma_f32_32x32x16_bf16((a), (b), (c), 0, 0, 0)
; __device__ __forceinline__ bf16x8 pack8(const f32x16& p, int base) {
;     u32x4 w; w.x = pk2(p[base + 0], p[base + 1]); w.y = pk2(p[base + 2], p[base + 3]); w.z = pk2(p[base + 4], p[base + 5]); w.w = pk2(p[base + 6], p[base + 7]);
;     return __builtin_bit_cast(bf16x8, w);
; }
; __device__ __forceinline__ void sample_task(const Prm& P, Ctx& C, int task) {
;     ...
;             {
;                 const int key = lane >> 1, d0 = 32 * (lane & 1);
; #pragma unroll
;                 for (int c = 0; c < 4; ++c) { const unsigned w[4] = {vld[tt][c].x, vld[tt][c].y, vld[tt][c].z, vld[tt][c].w};
; #pragma unroll
;                     for (int e = 0; e < 4; ++e) { vts[(d0 + 8 * c + 2 * e) * 36 + key] = (bf16_t)(w[e] & 0xffffu); vts[(d0 + 8 * c + 2 * e + 1) * 36 + key] = (bf16_t)(w[e] >> 16); } }
;             }
;             LDS_WAIT();
;             bf16x8 pf[2]; pf[0] = pack8(S[tt], 0); pf[1] = pack8(S[tt], 8);
; #pragma unroll
;             for (int dblk = 0; dblk < 2; ++dblk)
; #pragma unroll
;                 for (int ks = 0; ks < 2; ++ks) { const LAS bf16_t* vp = vts + (32 * dblk + q) * 36 + 16 * ks + 4 * hi;
;                     const s16x4 lo = *(const LAS s16x4*)vp, hh = *(const LAS s16x4*)(vp + 8);
;                     o[dblk] = MFMA32(((bf16x8){lo[0], lo[1], lo[2], lo[3], hh[0], hh[1], hh[2], hh[3]}), pf[ks], o[dblk]); }
	ds_write_b16 v181, v126 offset:18432
	ds_write_b16_d16_hi v181, v126 offset:18504
	ds_write_b16 v181, v127 offset:18576
	ds_write_b16_d16_hi v181, v127 offset:18648
	ds_write_b16 v181, v128 offset:18720
	ds_write_b16_d16_hi v181, v128 offset:18792
	ds_write_b16 v181, v129 offset:18864
	ds_write_b16_d16_hi v181, v129 offset:18936
	s_waitcnt vmcnt(10)
	ds_write_b16 v181, v122 offset:19008
	ds_write_b16_d16_hi v181, v122 offset:19080
	ds_write_b16 v181, v123 offset:19152
	ds_write_b16_d16_hi v181, v123 offset:19224
	ds_write_b16 v181, v124 offset:19296
	ds_write_b16_d16_hi v181, v124 offset:19368
	ds_write_b16 v181, v125 offset:19440
	ds_write_b16_d16_hi v181, v125 offset:19512
	s_waitcnt vmcnt(9)
	ds_write_b16 v181, v118 offset:19584
	ds_write_b16_d16_hi v181, v118 offset:19656
	ds_write_b16 v181, v119 offset:19728
	ds_write_b16_d16_hi v181, v119 offset:19800
	ds_write_b16 v181, v120 offset:19872
	ds_write_b16_d16_hi v181, v120 offset:19944
	ds_write_b16 v181, v121 offset:20016
	ds_write_b16_d16_hi v181, v121 offset:20088
	s_waitcnt vmcnt(8)
	ds_write_b16 v181, v114 offset:20160
	ds_write_b16_d16_hi v181, v114 offset:20232
	ds_write_b16 v181, v115 offset:20304
	ds_write_b16_d16_hi v181, v115 offset:20376
	ds_write_b16 v181, v116 offset:20448
	ds_write_b16_d16_hi v181, v116 offset:20520
	ds_write_b16 v181, v117 offset:20592
	ds_write_b16_d16_hi v181, v117 offset:20664
	s_mov_b32 s9, 0xffff0000
	s_waitcnt lgkmcnt(0)
	v_cvt_pk_bf16_f32 v17, v134, v5
	v_cvt_pk_bf16_f32 v16, v135, v136
	v_cvt_pk_bf16_f32 v15, v132, v3
	v_cvt_pk_bf16_f32 v14, v133, v2
	v_bfe_u32 v2, v9, 16, 1
	v_bfe_u32 v3, v8, 16, 1
	v_bfe_u32 v5, v7, 16, 1
	v_bfe_u32 v13, v6, 16, 1
	v_add3_u32 v13, v6, v13, s8
	v_add3_u32 v114, v7, v5, s8
	v_add3_u32 v115, v8, v3, s8
	v_add3_u32 v116, v9, v2, s8
	ds_read2_b64 v[6:9], v130 offset1:2
	v_bfe_u32 v2, v4, 16, 1
	v_bfe_u32 v3, v10, 16, 1
	v_bfe_u32 v5, v12, 16, 1
	v_bfe_u32 v117, v11, 16, 1
	v_add3_u32 v2, v4, v2, s8
	v_add3_u32 v11, v11, v117, s8
	v_add3_u32 v12, v12, v5, s8
	v_add3_u32 v10, v10, v3, s8
	v_lshrrev_b32_e32 v117, 16, v2
	ds_read2_b64 v[2:5], v130 offset0:4 offset1:6
	s_waitcnt lgkmcnt(1)
	v_mfma_f32_32x32x16_bf16 v[50:65], v[6:9], v[14:17], v[50:65]
	v_lshrrev_b32_e32 v6, 16, v10
	v_lshrrev_b32_e32 v7, 16, v12
	v_lshrrev_b32_e32 v8, 16, v11
	v_and_or_b32 v9, v116, s9, v8
	v_and_or_b32 v8, v115, s9, v7
	v_and_or_b32 v7, v114, s9, v6
	v_and_or_b32 v6, v13, s9, v117
	s_waitcnt lgkmcnt(0)
	s_nop 0
	v_mfma_f32_32x32x16_bf16 v[50:65], v[2:5], v[6:9], v[50:65]
	ds_read2_b64 v[2:5], v131 offset0:32 offset1:34
	s_waitcnt lgkmcnt(0)
	v_mfma_f32_32x32x16_bf16 v[66:81], v[2:5], v[14:17], v[66:81]
	ds_read2_b64 v[2:5], v131 offset0:36 offset1:38
	s_waitcnt lgkmcnt(0)
	s_waitcnt lgkmcnt(0)
	v_mfma_f32_32x32x16_bf16 v[66:81], v[2:5], v[6:9], v[66:81]
	v_sub_f32_e32 v2, v18, v0
	v_sub_f32_e32 v3, v20, v0
	v_exp_f32_e32 v2, v2
	v_sub_f32_e32 v4, v19, v0
	v_exp_f32_e32 v3, v3
	v_sub_f32_e32 v5, v21, v0
	v_exp_f32_e32 v4, v4
	v_exp_f32_e32 v5, v5
	v_pk_mul_f32 v[2:3], v[2:3], v[170:171]
	s_nop 0
	v_cndmask_b32_e64 v10, 0, v3, s[6:7]
	v_cndmask_b32_e64 v11, 0, v2, s[0:1]
	v_pk_mul_f32 v[2:3], v[4:5], v[170:171]
	s_nop 0
	v_cndmask_b32_e64 v2, 0, v2, s[2:3]
	v_add_f32_e32 v4, v11, v2
	v_add_f32_e32 v4, v10, v4
	s_nop 1
	v_add_f32_dpp v4, v4, v4 quad_perm:[1,0,3,2] row_mask:0xf bank_mask:0xf bound_ctrl:1
	s_nop 1
	v_mov_b32_dpp v5, v4 quad_perm:[2,3,0,1] row_mask:0xf bank_mask:0xf bound_ctrl:1
	s_mov_b64 s[0:1], exec
	v_readlane_b32 s2, v251, 0
	v_readlane_b32 s3, v251, 1
	s_and_b64 s[2:3], s[0:1], s[2:3]
	s_mov_b64 exec, s[2:3]
	v_add_f32_e32 v4, v4, v5
	ds_write_b32 v179, v4 offset:512
	s_or_b64 exec, exec, s[0:1]
	v_sub_f32_e32 v5, v23, v0
	v_sub_f32_e32 v4, v22, v0
	v_exp_f32_e32 v6, v5
	v_sub_f32_e32 v5, v24, v0
	v_sub_f32_e32 v7, v25, v0
	v_exp_f32_e32 v4, v4
	v_exp_f32_e32 v5, v5
	v_exp_f32_e32 v7, v7
	v_pk_mul_f32 v[8:9], v[4:5], v[170:171]
	v_pk_mul_f32 v[4:5], v[6:7], v[170:171]
	v_cndmask_b32_e64 v14, 0, v8, s[92:93]
	v_cndmask_b32_e64 v15, 0, v4, s[94:95]
	v_cndmask_b32_e64 v13, 0, v9, s[4:5]
	v_add_f32_e32 v4, v14, v15
	v_add_f32_e32 v4, v13, v4
	s_nop 1
	v_add_f32_dpp v4, v4, v4 quad_perm:[1,0,3,2] row_mask:0xf bank_mask:0xf bound_ctrl:1
	s_nop 1
	v_mov_b32_dpp v6, v4 quad_perm:[2,3,0,1] row_mask:0xf bank_mask:0xf bound_ctrl:1
	s_mov_b64 s[0:1], exec
	v_readlane_b32 s2, v251, 0
	v_readlane_b32 s3, v251, 1
	s_and_b64 s[2:3], s[0:1], s[2:3]
	s_mov_b64 exec, s[2:3]
	v_add_f32_e32 v4, v4, v6
	ds_write_b32 v179, v4 offset:520
	s_or_b64 exec, exec, s[0:1]
	v_sub_f32_e32 v4, v26, v0
	v_exp_f32_e32 v6, v4
	v_sub_f32_e32 v4, v27, v0
	v_exp_f32_e32 v8, v4
	v_sub_f32_e32 v4, v28, v0
	v_exp_f32_e32 v7, v4
	v_sub_f32_e32 v4, v29, v0
	v_exp_f32_e32 v9, v4
	v_pk_mul_f32 v[16:17], v[6:7], v[170:171]
	s_nop 0
	v_cndmask_b32_e64 v4, 0, v16, s[88:89]
	v_pk_mul_f32 v[6:7], v[8:9], v[170:171]
	v_cndmask_b32_e64 v12, 0, v17, s[96:97]
	v_cndmask_b32_e64 v6, 0, v6, s[90:91]
	v_add_f32_e32 v8, v4, v6
	v_add_f32_e32 v8, v12, v8
	s_nop 1
	v_add_f32_dpp v8, v8, v8 quad_perm:[1,0,3,2] row_mask:0xf bank_mask:0xf bound_ctrl:1
	s_nop 1
	v_mov_b32_dpp v9, v8 quad_perm:[2,3,0,1] row_mask:0xf bank_mask:0xf bound_ctrl:1
	s_mov_b64 s[0:1], exec
	v_readlane_b32 s2, v251, 0
	v_readlane_b32 s3, v251, 1
	s_and_b64 s[2:3], s[0:1], s[2:3]
	s_mov_b64 exec, s[2:3]
	v_add_f32_e32 v8, v8, v9
	ds_write_b32 v179, v8 offset:528
	s_or_b64 exec, exec, s[0:1]
	v_sub_f32_e32 v9, v31, v0
	v_sub_f32_e32 v8, v30, v0
	v_exp_f32_e32 v16, v9
	v_sub_f32_e32 v9, v32, v0
	v_sub_f32_e32 v17, v33, v0
	v_exp_f32_e32 v8, v8
	v_exp_f32_e32 v9, v9
	v_exp_f32_e32 v17, v17
	v_pk_mul_f32 v[18:19], v[8:9], v[170:171]
	v_pk_mul_f32 v[8:9], v[16:17], v[170:171]
	v_cndmask_b32_e64 v17, 0, v18, s[84:85]
	v_cndmask_b32_e64 v8, 0, v8, s[86:87]
	v_cndmask_b32_e64 v16, 0, v19, s[14:15]
	v_add_f32_e32 v18, v17, v8
	v_add_f32_e32 v18, v16, v18
	s_nop 1
	v_add_f32_dpp v18, v18, v18 quad_perm:[1,0,3,2] row_mask:0xf bank_mask:0xf bound_ctrl:1
	s_nop 1
	v_mov_b32_dpp v19, v18 quad_perm:[2,3,0,1] row_mask:0xf bank_mask:0xf bound_ctrl:1
	s_mov_b64 s[0:1], exec
	v_readlane_b32 s2, v251, 0
	v_readlane_b32 s3, v251, 1
	s_and_b64 s[2:3], s[0:1], s[2:3]
	s_mov_b64 exec, s[2:3]
	v_add_f32_e32 v18, v18, v19
	ds_write_b32 v179, v18 offset:536
	s_or_b64 exec, exec, s[0:1]
	v_readlane_b32 s0, v253, 30
	v_readlane_b32 s1, v253, 31
	s_nop 1
	v_cndmask_b32_e64 v3, 0, v3, s[0:1]
	v_readlane_b32 s0, v253, 32
	v_readlane_b32 s1, v253, 33
	v_cndmask_b32_e64 v9, 0, v9, s[12:13]
	s_nop 0
	v_cndmask_b32_e64 v5, 0, v5, s[0:1]
	v_readlane_b32 s0, v253, 34
	v_readlane_b32 s1, v253, 35
	s_waitcnt vmcnt(7)
; #define LAS __attribute__((address_space(3)))
; __device__ __forceinline__ unsigned pk2(float lo, float hi) { return f2bf(lo) | (f2bf(hi) << 16); }
; #define LDS_WAIT() asm volatile("s_waitcnt lgkmcnt(0)" ::: "memory")
; #define MFMA32(a, b, c) __builtin_amdgcn_mfma_f32_32x32x16_bf16((a), (b), (c), 0, 0, 0)
; __device__ __forceinline__ bf16x8 pack8(const f32x16& p, int base) {
;     u32x4 w; w.x = pk2(p[base + 0], p[base + 1]); w.y = pk2(p[base + 2], p[base + 3]); w.z = pk2(p[base + 4], p[base + 5]); w.w = pk2(p[base + 6], p[base + 7]);
;     return __builtin_bit_cast(bf16x8, w);
; }
; __device__ __forceinline__ void sample_task(const Prm& P, Ctx& C, int task) {
;     ...
;             {
;                 const int key = lane >> 1, d0 = 32 * (lane & 1);
; #pragma unroll
;                 for (int c = 0; c < 4; ++c) { const unsigned w[4] = {vld[tt][c].x, vld[tt][c].y, vld[tt][c].z, vld[tt][c].w};
; #pragma unroll
;                     for (int e = 0; e < 4; ++e) { vts[(d0 + 8 * c + 2 * e) * 36 + key] = (bf16_t)(w[e] & 0xffffu); vts[(d0 + 8 * c + 2 * e + 1) * 36 + key] = (bf16_t)(w[e] >> 16); } }
;             }
;             LDS_WAIT();
;             bf16x8 pf[2]; pf[0] = pack8(S[tt], 0); pf[1] = pack8(S[tt], 8);
; #pragma unroll
;             for (int dblk = 0; dblk < 2; ++dblk)
; #pragma unroll
;                 for (int ks = 0; ks < 2; ++ks) { const LAS bf16_t* vp = vts + (32 * dblk + q) * 36 + 16 * ks + 4 * hi;
;                     const s16x4 lo = *(const LAS s16x4*)vp, hh = *(const LAS s16x4*)(vp + 8);
;                     o[dblk] = MFMA32(((bf16x8){lo[0], lo[1], lo[2], lo[3], hh[0], hh[1], hh[2], hh[3]}), pf[ks], o[dblk]); }
	ds_write_b16 v181, v110 offset:18432
	ds_write_b16_d16_hi v181, v110 offset:18504
	ds_write_b16 v181, v111 offset:18576
	ds_write_b16_d16_hi v181, v111 offset:18648
	ds_write_b16 v181, v112 offset:18720
	ds_write_b16_d16_hi v181, v112 offset:18792
	ds_write_b16 v181, v113 offset:18864
	ds_write_b16_d16_hi v181, v113 offset:18936
	s_waitcnt vmcnt(6)
	ds_write_b16 v181, v106 offset:19008
	ds_write_b16_d16_hi v181, v106 offset:19080
	ds_write_b16 v181, v107 offset:19152
	ds_write_b16_d16_hi v181, v107 offset:19224
	ds_write_b16 v181, v108 offset:19296
	ds_write_b16_d16_hi v181, v108 offset:19368
	ds_write_b16 v181, v109 offset:19440
	ds_write_b16_d16_hi v181, v109 offset:19512
	s_waitcnt vmcnt(5)
	ds_write_b16 v181, v102 offset:19584
	ds_write_b16_d16_hi v181, v102 offset:19656
	ds_write_b16 v181, v103 offset:19728
	ds_write_b16_d16_hi v181, v103 offset:19800
	ds_write_b16 v181, v104 offset:19872
	ds_write_b16_d16_hi v181, v104 offset:19944
	ds_write_b16 v181, v105 offset:20016
	ds_write_b16_d16_hi v181, v105 offset:20088
	s_waitcnt vmcnt(4)
	ds_write_b16 v181, v98 offset:20160
	ds_write_b16_d16_hi v181, v98 offset:20232
	ds_write_b16 v181, v99 offset:20304
	ds_write_b16_d16_hi v181, v99 offset:20376
	ds_write_b16 v181, v100 offset:20448
	ds_write_b16_d16_hi v181, v100 offset:20520
	ds_write_b16 v181, v101 offset:20592
	ds_write_b16_d16_hi v181, v101 offset:20664
	v_cndmask_b32_e64 v7, 0, v7, s[0:1]
	s_movk_i32 s0, 0x7fff
	s_mov_b32 s1, 0xffff0000
	s_waitcnt lgkmcnt(0)
	v_cvt_pk_bf16_f32 v21, v13, v5
	v_cvt_pk_bf16_f32 v19, v10, v3
	v_cvt_pk_bf16_f32 v18, v11, v2
	v_bfe_u32 v2, v9, 16, 1
	v_bfe_u32 v3, v8, 16, 1
	v_bfe_u32 v5, v7, 16, 1
	v_bfe_u32 v10, v6, 16, 1
	v_cvt_pk_bf16_f32 v20, v14, v15
	v_add3_u32 v10, v6, v10, s0
	v_add3_u32 v11, v7, v5, s0
	v_add3_u32 v13, v8, v3, s0
	v_add3_u32 v14, v9, v2, s0
	ds_read2_b64 v[6:9], v130 offset1:2
	v_bfe_u32 v2, v4, 16, 1
	v_bfe_u32 v3, v12, 16, 1
	v_bfe_u32 v5, v17, 16, 1
	v_bfe_u32 v15, v16, 16, 1
	v_add3_u32 v2, v4, v2, s0
	v_add3_u32 v15, v16, v15, s0
	v_add3_u32 v16, v17, v5, s0
	v_add3_u32 v12, v12, v3, s0
	v_lshrrev_b32_e32 v17, 16, v2
	ds_read2_b64 v[2:5], v130 offset0:4 offset1:6
	s_waitcnt lgkmcnt(1)
	v_mfma_f32_32x32x16_bf16 v[50:65], v[6:9], v[18:21], v[50:65]
	v_lshrrev_b32_e32 v6, 16, v12
	v_lshrrev_b32_e32 v7, 16, v16
	v_lshrrev_b32_e32 v8, 16, v15
	v_and_or_b32 v9, v14, s1, v8
	v_and_or_b32 v8, v13, s1, v7
	v_and_or_b32 v7, v11, s1, v6
	v_and_or_b32 v6, v10, s1, v17
	v_readlane_b32 s0, v253, 40
	v_readlane_b32 s1, v253, 41
	s_waitcnt lgkmcnt(0)
	v_mfma_f32_32x32x16_bf16 v[50:65], v[2:5], v[6:9], v[50:65]
	ds_read2_b64 v[2:5], v131 offset0:32 offset1:34
	s_waitcnt lgkmcnt(0)
	v_mfma_f32_32x32x16_bf16 v[66:81], v[2:5], v[18:21], v[66:81]
	ds_read2_b64 v[2:5], v131 offset0:36 offset1:38
	s_waitcnt lgkmcnt(0)
	s_waitcnt lgkmcnt(0)
	v_mfma_f32_32x32x16_bf16 v[66:81], v[2:5], v[6:9], v[66:81]
	v_sub_f32_e32 v2, v34, v0
	v_sub_f32_e32 v3, v36, v0
	v_exp_f32_e32 v2, v2
	v_exp_f32_e32 v3, v3
	v_sub_f32_e32 v4, v35, v0
	v_sub_f32_e32 v5, v37, v0
	v_exp_f32_e32 v4, v4
	v_exp_f32_e32 v5, v5
	v_pk_mul_f32 v[2:3], v[2:3], v[170:171]
	s_nop 0
	v_cndmask_b32_e64 v10, 0, v3, s[0:1]
	v_readlane_b32 s0, v253, 36
	v_readlane_b32 s1, v253, 37
	s_nop 1
	v_cndmask_b32_e64 v11, 0, v2, s[0:1]
	v_readlane_b32 s0, v253, 38
	v_pk_mul_f32 v[2:3], v[4:5], v[170:171]
	v_readlane_b32 s1, v253, 39
	s_nop 1
	v_cndmask_b32_e64 v2, 0, v2, s[0:1]
	v_add_f32_e32 v4, v11, v2
	v_add_f32_e32 v4, v10, v4
	s_nop 1
	v_add_f32_dpp v4, v4, v4 quad_perm:[1,0,3,2] row_mask:0xf bank_mask:0xf bound_ctrl:1
	s_nop 1
	v_mov_b32_dpp v5, v4 quad_perm:[2,3,0,1] row_mask:0xf bank_mask:0xf bound_ctrl:1
	s_mov_b64 s[0:1], exec
	v_readlane_b32 s2, v251, 0
	v_readlane_b32 s3, v251, 1
	s_and_b64 s[2:3], s[0:1], s[2:3]
	s_mov_b64 exec, s[2:3]
	v_add_f32_e32 v4, v4, v5
	ds_write_b32 v179, v4 offset:768
	s_or_b64 exec, exec, s[0:1]
	v_sub_f32_e32 v5, v39, v0
	v_sub_f32_e32 v4, v38, v0
	v_exp_f32_e32 v6, v5
	v_sub_f32_e32 v5, v40, v0
	v_exp_f32_e32 v4, v4
	v_exp_f32_e32 v5, v5
	v_sub_f32_e32 v7, v41, v0
	v_readlane_b32 s0, v253, 48
	v_exp_f32_e32 v7, v7
	v_pk_mul_f32 v[8:9], v[4:5], v[170:171]
	v_readlane_b32 s1, v253, 49
	v_pk_mul_f32 v[4:5], v[6:7], v[170:171]
	s_nop 0
	v_cndmask_b32_e64 v13, 0, v9, s[0:1]
	v_readlane_b32 s0, v253, 44
	v_readlane_b32 s1, v253, 45
	s_nop 1
	v_cndmask_b32_e64 v14, 0, v8, s[0:1]
	v_readlane_b32 s0, v253, 46
	v_readlane_b32 s1, v253, 47
	s_nop 1
	v_cndmask_b32_e64 v15, 0, v4, s[0:1]
	v_add_f32_e32 v4, v14, v15
	v_add_f32_e32 v4, v13, v4
	s_nop 1
	v_add_f32_dpp v4, v4, v4 quad_perm:[1,0,3,2] row_mask:0xf bank_mask:0xf bound_ctrl:1
	s_nop 1
	v_mov_b32_dpp v6, v4 quad_perm:[2,3,0,1] row_mask:0xf bank_mask:0xf bound_ctrl:1
	s_mov_b64 s[0:1], exec
	v_readlane_b32 s2, v251, 0
	v_readlane_b32 s3, v251, 1
	s_and_b64 s[2:3], s[0:1], s[2:3]
	s_mov_b64 exec, s[2:3]
	v_add_f32_e32 v4, v4, v6
	ds_write_b32 v179, v4 offset:776
	s_or_b64 exec, exec, s[0:1]
	v_sub_f32_e32 v4, v42, v0
	v_exp_f32_e32 v6, v4
	v_sub_f32_e32 v4, v43, v0
	v_exp_f32_e32 v8, v4
	v_sub_f32_e32 v4, v44, v0
	v_exp_f32_e32 v7, v4
	v_sub_f32_e32 v4, v45, v0
	v_readlane_b32 s0, v253, 56
	v_exp_f32_e32 v9, v4
	v_pk_mul_f32 v[16:17], v[6:7], v[170:171]
	v_readlane_b32 s1, v253, 57
	v_pk_mul_f32 v[6:7], v[8:9], v[170:171]
	s_nop 0
	v_cndmask_b32_e64 v4, 0, v17, s[0:1]
	v_readlane_b32 s0, v253, 52
	v_readlane_b32 s1, v253, 53
	s_nop 1
	v_cndmask_b32_e64 v12, 0, v16, s[0:1]
	v_readlane_b32 s0, v253, 54
	v_readlane_b32 s1, v253, 55
	s_nop 1
	v_cndmask_b32_e64 v6, 0, v6, s[0:1]
	v_add_f32_e32 v8, v12, v6
	v_add_f32_e32 v8, v4, v8
	s_nop 1
; #define LAS __attribute__((address_space(3)))
; __device__ __forceinline__ unsigned pk2(float lo, float hi) { return f2bf(lo) | (f2bf(hi) << 16); }
; __device__ __forceinline__ float ex2(float x) { return __builtin_amdgcn_exp2f(x); }
; #define LDS_WAIT() asm volatile("s_waitcnt lgkmcnt(0)" ::: "memory")
; #define MFMA32(a, b, c) __builtin_amdgcn_mfma_f32_32x32x16_bf16((a), (b), (c), 0, 0, 0)
; __device__ __forceinline__ bf16x8 pack8(const f32x16& p, int base) {
;     u32x4 w; w.x = pk2(p[base + 0], p[base + 1]); w.y = pk2(p[base + 2], p[base + 3]); w.z = pk2(p[base + 4], p[base + 5]); w.w = pk2(p[base + 6], p[base + 7]);
;     return __builtin_bit_cast(bf16x8, w);
; }
; __device__ __forceinline__ void sample_task(const Prm& P, Ctx& C, int task) {
;     ...
;             for (int r = 0; r < 16; ++r) S[tt][r] = (S[tt][r] > -1e29f) ? ex2(S[tt][r] - M) * invl : 0.f;
; #pragma unroll
;             for (int i = 0; i < 4; ++i) { const float v = quad_sum(S[tt][4 * i] + S[tt][4 * i + 1] + S[tt][4 * i + 2]); if (g == 0) sc[slot * 256 + 8 * tile + 2 * i + hi] = v; }
;             {
;                 const int key = lane >> 1, d0 = 32 * (lane & 1);
; #pragma unroll
;                 for (int c = 0; c < 4; ++c) { const unsigned w[4] = {vld[tt][c].x, vld[tt][c].y, vld[tt][c].z, vld[tt][c].w};
; #pragma unroll
;                     for (int e = 0; e < 4; ++e) { vts[(d0 + 8 * c + 2 * e) * 36 + key] = (bf16_t)(w[e] & 0xffffu); vts[(d0 + 8 * c + 2 * e + 1) * 36 + key] = (bf16_t)(w[e] >> 16); } }
;             }
;             LDS_WAIT();
;             bf16x8 pf[2]; pf[0] = pack8(S[tt], 0); pf[1] = pack8(S[tt], 8);
; #pragma unroll
;             for (int dblk = 0; dblk < 2; ++dblk)
; #pragma unroll
;                 for (int ks = 0; ks < 2; ++ks) { const LAS bf16_t* vp = vts + (32 * dblk + q) * 36 + 16 * ks + 4 * hi;
;                     const s16x4 lo = *(const LAS s16x4*)vp, hh = *(const LAS s16x4*)(vp + 8);
;                     o[dblk] = MFMA32(((bf16x8){lo[0], lo[1], lo[2], lo[3], hh[0], hh[1], hh[2], hh[3]}), pf[ks], o[dblk]); }
;             LDS_WAIT();
;         }
; #pragma unroll
;         for (int dblk = 0; dblk < 2; ++dblk)
; #pragma unroll
;             for (int r = 0; r < 16; ++r) atomicAdd((float*)(oacc + (dblk * 16 + r) * 64 + lane), o[dblk][r]);
;         __syncthreads();
	v_add_f32_dpp v8, v8, v8 quad_perm:[1,0,3,2] row_mask:0xf bank_mask:0xf bound_ctrl:1
	s_nop 1
	v_mov_b32_dpp v9, v8 quad_perm:[2,3,0,1] row_mask:0xf bank_mask:0xf bound_ctrl:1
	s_mov_b64 s[0:1], exec
	v_readlane_b32 s2, v251, 0
	v_readlane_b32 s3, v251, 1
	s_and_b64 s[2:3], s[0:1], s[2:3]
	s_mov_b64 exec, s[2:3]
	v_add_f32_e32 v8, v8, v9
	ds_write_b32 v179, v8 offset:784
	s_or_b64 exec, exec, s[0:1]
	v_sub_f32_e32 v9, v47, v0
	v_sub_f32_e32 v8, v46, v0
	v_exp_f32_e32 v16, v9
	v_sub_f32_e32 v9, v48, v0
	v_exp_f32_e32 v8, v8
	v_exp_f32_e32 v9, v9
	v_sub_f32_e32 v0, v49, v0
	v_exp_f32_e32 v17, v0
	v_readlane_b32 s0, v252, 0
	v_pk_mul_f32 v[18:19], v[8:9], v[170:171]
	v_readlane_b32 s1, v252, 1
	v_pk_mul_f32 v[8:9], v[16:17], v[170:171]
	s_nop 0
	v_cndmask_b32_e64 v0, 0, v19, s[0:1]
	v_readlane_b32 s0, v253, 60
	v_readlane_b32 s1, v253, 61
	s_nop 1
	v_cndmask_b32_e64 v16, 0, v18, s[0:1]
	v_readlane_b32 s0, v253, 62
	v_readlane_b32 s1, v253, 63
	s_nop 1
	v_cndmask_b32_e64 v8, 0, v8, s[0:1]
	v_add_f32_e32 v17, v16, v8
	v_add_f32_e32 v17, v0, v17
	s_nop 1
	v_add_f32_dpp v17, v17, v17 quad_perm:[1,0,3,2] row_mask:0xf bank_mask:0xf bound_ctrl:1
	s_nop 1
	v_mov_b32_dpp v18, v17 quad_perm:[2,3,0,1] row_mask:0xf bank_mask:0xf bound_ctrl:1
	s_mov_b64 s[0:1], exec
	v_readlane_b32 s2, v251, 0
	v_readlane_b32 s3, v251, 1
	s_and_b64 s[2:3], s[0:1], s[2:3]
	s_mov_b64 exec, s[2:3]
	v_add_f32_e32 v17, v17, v18
	ds_write_b32 v179, v17 offset:792
	s_or_b64 exec, exec, s[0:1]
	v_readlane_b32 s0, v253, 42
	v_readlane_b32 s1, v253, 43
	s_nop 1
	v_cndmask_b32_e64 v3, 0, v3, s[0:1]
	v_readlane_b32 s0, v253, 50
	v_readlane_b32 s1, v253, 51
	s_waitcnt vmcnt(3)
	ds_write_b16 v181, v94 offset:18432
	ds_write_b16_d16_hi v181, v94 offset:18504
	ds_write_b16 v181, v95 offset:18576
	ds_write_b16_d16_hi v181, v95 offset:18648
	ds_write_b16 v181, v96 offset:18720
	ds_write_b16_d16_hi v181, v96 offset:18792
	ds_write_b16 v181, v97 offset:18864
	ds_write_b16_d16_hi v181, v97 offset:18936
	s_waitcnt vmcnt(2)
	ds_write_b16 v181, v90 offset:19008
	ds_write_b16_d16_hi v181, v90 offset:19080
	ds_write_b16 v181, v91 offset:19152
	ds_write_b16_d16_hi v181, v91 offset:19224
	ds_write_b16 v181, v92 offset:19296
	ds_write_b16_d16_hi v181, v92 offset:19368
	ds_write_b16 v181, v93 offset:19440
	ds_write_b16_d16_hi v181, v93 offset:19512
	s_waitcnt vmcnt(1)
	ds_write_b16 v181, v86 offset:19584
	ds_write_b16_d16_hi v181, v86 offset:19656
	ds_write_b16 v181, v87 offset:19728
	ds_write_b16_d16_hi v181, v87 offset:19800
	ds_write_b16 v181, v88 offset:19872
	ds_write_b16_d16_hi v181, v88 offset:19944
	ds_write_b16 v181, v89 offset:20016
	ds_write_b16_d16_hi v181, v89 offset:20088
	s_waitcnt vmcnt(0)
	ds_write_b16 v181, v82 offset:20160
	ds_write_b16_d16_hi v181, v82 offset:20232
	ds_write_b16 v181, v83 offset:20304
	ds_write_b16_d16_hi v181, v83 offset:20376
	ds_write_b16 v181, v84 offset:20448
	ds_write_b16_d16_hi v181, v84 offset:20520
	ds_write_b16 v181, v85 offset:20592
	ds_write_b16_d16_hi v181, v85 offset:20664
	v_cndmask_b32_e64 v5, 0, v5, s[0:1]
	v_readlane_b32 s0, v253, 58
	v_readlane_b32 s1, v253, 59
	s_waitcnt lgkmcnt(0)
	s_movk_i32 s24, 0x7fff
	v_cndmask_b32_e64 v7, 0, v7, s[0:1]
	v_readlane_b32 s0, v252, 2
	v_readlane_b32 s1, v252, 3
	s_nop 1
	v_cndmask_b32_e64 v9, 0, v9, s[0:1]
	s_movk_i32 s0, 0x7fff
	s_mov_b32 s1, 0xffff0000
	v_cvt_pk_bf16_f32 v21, v13, v5
	v_cvt_pk_bf16_f32 v19, v10, v3
	v_cvt_pk_bf16_f32 v18, v11, v2
	v_bfe_u32 v2, v9, 16, 1
	v_bfe_u32 v3, v8, 16, 1
	v_bfe_u32 v5, v7, 16, 1
	v_bfe_u32 v10, v6, 16, 1
	v_cvt_pk_bf16_f32 v20, v14, v15
	v_add3_u32 v10, v6, v10, s0
	v_add3_u32 v11, v7, v5, s0
	v_add3_u32 v13, v8, v3, s0
	v_add3_u32 v14, v9, v2, s0
	ds_read2_b64 v[6:9], v130 offset1:2
	v_bfe_u32 v2, v12, 16, 1
	v_bfe_u32 v3, v4, 16, 1
	v_bfe_u32 v5, v16, 16, 1
	v_bfe_u32 v15, v0, 16, 1
	v_add3_u32 v2, v12, v2, s0
	v_add3_u32 v0, v0, v15, s0
	v_add3_u32 v15, v16, v5, s0
	v_add3_u32 v16, v4, v3, s0
	v_lshrrev_b32_e32 v12, 16, v2
	ds_read2_b64 v[2:5], v130 offset0:4 offset1:6
	s_waitcnt lgkmcnt(1)
	v_mfma_f32_32x32x16_bf16 v[50:65], v[6:9], v[18:21], v[50:65]
	v_lshrrev_b32_e32 v6, 16, v16
	v_lshrrev_b32_e32 v7, 16, v15
	v_lshrrev_b32_e32 v0, 16, v0
	v_and_or_b32 v9, v14, s1, v0
	v_and_or_b32 v8, v13, s1, v7
	v_and_or_b32 v7, v11, s1, v6
	v_and_or_b32 v6, v10, s1, v12
	v_readlane_b32 s0, v250, 62
	v_readlane_b32 s1, v250, 63
	s_waitcnt lgkmcnt(0)
	v_mfma_f32_32x32x16_bf16 v[50:65], v[2:5], v[6:9], v[50:65]
	ds_read2_b64 v[2:5], v131 offset0:32 offset1:34
	s_andn2_b64 vcc, exec, s[0:1]
	s_waitcnt lgkmcnt(0)
	v_mfma_f32_32x32x16_bf16 v[66:81], v[2:5], v[18:21], v[66:81]
	ds_read2_b64 v[2:5], v131 offset0:36 offset1:38
	s_waitcnt lgkmcnt(0)
	s_waitcnt lgkmcnt(0)
	v_mfma_f32_32x32x16_bf16 v[66:81], v[2:5], v[6:9], v[66:81]
	s_nop 4
	ds_add_f32 v183, v50 offset:8192
	ds_add_f32 v183, v51 offset:8448
	ds_add_f32 v183, v52 offset:8704
	ds_add_f32 v183, v53 offset:8960
	ds_add_f32 v183, v54 offset:9216
	ds_add_f32 v183, v55 offset:9472
	ds_add_f32 v183, v56 offset:9728
	ds_add_f32 v183, v57 offset:9984
	ds_add_f32 v183, v58 offset:10240
	ds_add_f32 v183, v59 offset:10496
	ds_add_f32 v183, v60 offset:10752
	ds_add_f32 v183, v61 offset:11008
	ds_add_f32 v183, v62 offset:11264
	ds_add_f32 v183, v63 offset:11520
	ds_add_f32 v183, v64 offset:11776
	ds_add_f32 v183, v65 offset:12032
	ds_add_f32 v183, v66 offset:12288
	ds_add_f32 v183, v67 offset:12544
	ds_add_f32 v183, v68 offset:12800
	ds_add_f32 v183, v69 offset:13056
	ds_add_f32 v183, v70 offset:13312
	ds_add_f32 v183, v71 offset:13568
	ds_add_f32 v183, v72 offset:13824
	ds_add_f32 v183, v73 offset:14080
	ds_add_f32 v183, v74 offset:14336
	ds_add_f32 v183, v75 offset:14592
	ds_add_f32 v183, v76 offset:14848
	ds_add_f32 v183, v77 offset:15104
	ds_add_f32 v183, v78 offset:15360
	ds_add_f32 v183, v79 offset:15616
	ds_add_f32 v183, v80 offset:15872
	ds_add_f32 v183, v81 offset:16128
	s_waitcnt lgkmcnt(0)
	s_barrier
; __device__ __forceinline__ int crow(int r, int hi) { return (r & 3) + 8 * (r >> 2) + 4 * hi; }
; __device__ __forceinline__ void sample_task(const Prm& P, Ctx& C, int task) {
;     ...
;         if (C.wave == 0) {
;             if (slot == ts) { const float gate = ((const float*)(P.ws + WS_G))[row * 24 + head * 3 + 0];
; #pragma unroll
;                 for (int dblk = 0; dblk < 2; ++dblk)
; #pragma unroll
;                     for (int r = 0; r < 16; ++r) ocs[g * 64 + 32 * dblk + crow(r, hi)] = oacc[(dblk * 16 + r) * 64 + lane] * gate; }
	s_cbranch_vccnz .LBB0_1555
	v_readlane_b32 s0, v251, 2
	s_nop 1
	v_cmp_eq_u32_e32 vcc, s0, v173
	s_and_saveexec_b64 s[0:1], vcc
	s_cbranch_execz .LBB0_1529
	s_mul_i32 s2, s81, 0x60
	s_mul_hi_u32 s3, s80, 0x60
	s_add_i32 s3, s3, s2
	s_mul_i32 s2, s80, 0x60
	v_readlane_b32 s4, v251, 21
	v_mul_u32_u24_e32 v0, 3, v172
	s_add_u32 s2, s4, s2
	v_readlane_b32 s4, v251, 22
	s_addc_u32 s3, s4, s3
	v_lshlrev_b32_e32 v0, 2, v0
	global_load_dword v0, v0, s[2:3]
	ds_read_b32 v2, v183 offset:8192
	s_waitcnt vmcnt(0) lgkmcnt(0)
	v_mul_f32_e32 v2, v0, v2
	ds_write_b32 v199, v2
	ds_read_b32 v2, v183 offset:8448
	s_waitcnt lgkmcnt(0)
	v_mul_f32_e32 v2, v0, v2
	ds_write_b32 v199, v2 offset:4
	ds_read_b32 v2, v183 offset:8704
	s_waitcnt lgkmcnt(0)
	v_mul_f32_e32 v2, v0, v2
	ds_write_b32 v199, v2 offset:8
	ds_read_b32 v2, v183 offset:8960
	s_waitcnt lgkmcnt(0)
	v_mul_f32_e32 v2, v0, v2
	ds_write_b32 v199, v2 offset:12
	ds_read_b32 v2, v183 offset:9216
	s_waitcnt lgkmcnt(0)
	v_mul_f32_e32 v2, v0, v2
	ds_write_b32 v199, v2 offset:32
	ds_read_b32 v2, v183 offset:9472
	s_waitcnt lgkmcnt(0)
	v_mul_f32_e32 v2, v0, v2
	ds_write_b32 v199, v2 offset:36
	ds_read_b32 v2, v183 offset:9728
	s_waitcnt lgkmcnt(0)
	v_mul_f32_e32 v2, v0, v2
	ds_write_b32 v199, v2 offset:40
	ds_read_b32 v2, v183 offset:9984
	s_waitcnt lgkmcnt(0)
	v_mul_f32_e32 v2, v0, v2
	ds_write_b32 v199, v2 offset:44
	ds_read_b32 v2, v183 offset:10240
	s_waitcnt lgkmcnt(0)
	v_mul_f32_e32 v2, v0, v2
	ds_write_b32 v199, v2 offset:64
	ds_read_b32 v2, v183 offset:10496
	s_waitcnt lgkmcnt(0)
	v_mul_f32_e32 v2, v0, v2
	ds_write_b32 v199, v2 offset:68
	ds_read_b32 v2, v183 offset:10752
	s_waitcnt lgkmcnt(0)
	v_mul_f32_e32 v2, v0, v2
	ds_write_b32 v199, v2 offset:72
	ds_read_b32 v2, v183 offset:11008
	s_waitcnt lgkmcnt(0)
	v_mul_f32_e32 v2, v0, v2
	ds_write_b32 v199, v2 offset:76
	ds_read_b32 v2, v183 offset:11264
	s_waitcnt lgkmcnt(0)
	v_mul_f32_e32 v2, v0, v2
	ds_write_b32 v199, v2 offset:96
	ds_read_b32 v2, v183 offset:11520
	s_waitcnt lgkmcnt(0)
	v_mul_f32_e32 v2, v0, v2
	ds_write_b32 v199, v2 offset:100
	ds_read_b32 v2, v183 offset:11776
	s_waitcnt lgkmcnt(0)
	v_mul_f32_e32 v2, v0, v2
	ds_write_b32 v199, v2 offset:104
	ds_read_b32 v2, v183 offset:12032
	s_waitcnt lgkmcnt(0)
	v_mul_f32_e32 v2, v0, v2
	ds_write_b32 v199, v2 offset:108
	ds_read_b32 v2, v183 offset:12288
	s_waitcnt lgkmcnt(0)
	v_mul_f32_e32 v2, v0, v2
	ds_write_b32 v199, v2 offset:128
	ds_read_b32 v2, v183 offset:12544
	s_waitcnt lgkmcnt(0)
	v_mul_f32_e32 v2, v0, v2
	ds_write_b32 v199, v2 offset:132
	ds_read_b32 v2, v183 offset:12800
	s_waitcnt lgkmcnt(0)
	v_mul_f32_e32 v2, v0, v2
	ds_write_b32 v199, v2 offset:136
	ds_read_b32 v2, v183 offset:13056
	s_waitcnt lgkmcnt(0)
	v_mul_f32_e32 v2, v0, v2
	ds_write_b32 v199, v2 offset:140
	ds_read_b32 v2, v183 offset:13312
	s_waitcnt lgkmcnt(0)
	v_mul_f32_e32 v2, v0, v2
	ds_write_b32 v199, v2 offset:160
	ds_read_b32 v2, v183 offset:13568
	s_waitcnt lgkmcnt(0)
	v_mul_f32_e32 v2, v0, v2
	ds_write_b32 v199, v2 offset:164
	ds_read_b32 v2, v183 offset:13824
	s_waitcnt lgkmcnt(0)
	v_mul_f32_e32 v2, v0, v2
	ds_write_b32 v199, v2 offset:168
	ds_read_b32 v2, v183 offset:14080
	s_waitcnt lgkmcnt(0)
	v_mul_f32_e32 v2, v0, v2
	ds_write_b32 v199, v2 offset:172
	ds_read_b32 v2, v183 offset:14336
	s_waitcnt lgkmcnt(0)
	v_mul_f32_e32 v2, v0, v2
	ds_write_b32 v199, v2 offset:192
	ds_read_b32 v2, v183 offset:14592
	s_waitcnt lgkmcnt(0)
	v_mul_f32_e32 v2, v0, v2
	ds_write_b32 v199, v2 offset:196
	ds_read_b32 v2, v183 offset:14848
	s_waitcnt lgkmcnt(0)
	v_mul_f32_e32 v2, v0, v2
	ds_write_b32 v199, v2 offset:200
	ds_read_b32 v2, v183 offset:15104
	s_waitcnt lgkmcnt(0)
	v_mul_f32_e32 v2, v0, v2
	ds_write_b32 v199, v2 offset:204
	ds_read_b32 v2, v183 offset:15360
	s_waitcnt lgkmcnt(0)
	v_mul_f32_e32 v2, v0, v2
	ds_write_b32 v199, v2 offset:224
	ds_read_b32 v2, v183 offset:15616
	s_waitcnt lgkmcnt(0)
	v_mul_f32_e32 v2, v0, v2
	ds_write_b32 v199, v2 offset:228
	ds_read_b32 v2, v183 offset:15872
	s_waitcnt lgkmcnt(0)
	v_mul_f32_e32 v2, v0, v2
	ds_write_b32 v199, v2 offset:232
	ds_read_b32 v2, v183 offset:16128
	s_waitcnt lgkmcnt(0)
	v_mul_f32_e32 v0, v0, v2
	ds_write_b32 v199, v0 offset:236

; #define EPI_LOOP_ROWS(body) _Pragma("unroll") for (int ai = 0; ai < 2; ++ai) _Pragma("unroll") for (int m = 0; m < 4; ++m) { const int row = u.pm * 256 + ai * 128 + wr * 64 + m * 16 + fr; body }
; __device__ __forceinline__ unsigned f2bf(float f) { unsigned u = __builtin_bit_cast(unsigned, f); return (u + 0x7fffu + ((u >> 16) & 1u)) >> 16; }
; __device__ __forceinline__ unsigned pk2(float lo, float hi) { return f2bf(lo) | (f2bf(hi) << 16); }
; __device__ __forceinline__ void st8bf(bf16_t* p, f32x4 a, f32x4 b) { u32x4 w; w.x = pk2(a[0], a[1]); w.y = pk2(a[2], a[3]); w.z = pk2(b[0], b[1]); w.w = pk2(b[2], b[3]); st16(p, w); }
;     __device__ __forceinline__ void operator()(const f32x4 (&acc)[2][2][4][2], const pg8::Unit& u, int wr, int wc, int fr, int fq) const {
;         const int cw = wc * 32 + 8 * fq;
;         EPI_LOOP_ROWS( _Pragma("unroll") for (int bj = 0; bj < 2; ++bj) st8bf(W3P + (size_t)row * 1024 + u.pn * 256 + bj * 128 + cw, acc[ai][bj][m][0], acc[ai][bj][m][1]); )
;     }
.LBB0_1777:
	v_lshl_add_u32 v128, s0, 8, v128
	v_or_b32_e32 v134, s13, v129
	v_ashrrev_i32_e32 v129, 31, v128
	v_lshlrev_b64 v[130:131], 11, v[128:129]
	v_bfe_u32 v129, v124, 16, 1
	s_movk_i32 s4, 0x7fff
	v_add3_u32 v124, v124, v129, s4
	v_bfe_u32 v129, v125, 16, 1
	v_lshrrev_b32_e32 v124, 16, v124
	v_add3_u32 v125, v125, v129, s4
	s_mov_b32 s5, 0xffff0000
	v_and_or_b32 v124, v125, s5, v124
	v_cvt_pk_bf16_f32 v125, v126, v127
	v_cvt_pk_bf16_f32 v126, v120, v121
	v_bfe_u32 v120, v122, 16, 1
	v_add3_u32 v120, v122, v120, s4
	v_bfe_u32 v121, v123, 16, 1
	v_lshrrev_b32_e32 v120, 16, v120
	v_add3_u32 v121, v123, v121, s4
	v_and_or_b32 v127, v121, s5, v120
	v_bfe_u32 v120, v116, 16, 1
	v_add3_u32 v116, v116, v120, s4
	v_bfe_u32 v120, v117, 16, 1
	v_lshrrev_b32_e32 v116, 16, v116
	v_add3_u32 v117, v117, v120, s4
	v_and_or_b32 v116, v117, s5, v116
	v_cvt_pk_bf16_f32 v117, v118, v119
	v_cvt_pk_bf16_f32 v118, v112, v113
	v_bfe_u32 v112, v114, 16, 1
	v_add3_u32 v112, v114, v112, s4
	v_bfe_u32 v114, v108, 16, 1
	v_add3_u32 v108, v108, v114, s4
	v_bfe_u32 v114, v109, 16, 1
	v_lshrrev_b32_e32 v108, 16, v108
	v_add3_u32 v109, v109, v114, s4
	v_and_or_b32 v108, v109, s5, v108
	v_cvt_pk_bf16_f32 v109, v110, v111
	v_cvt_pk_bf16_f32 v110, v104, v105
	v_bfe_u32 v104, v106, 16, 1
	v_add3_u32 v104, v106, v104, s4
	v_bfe_u32 v105, v107, 16, 1
	v_lshrrev_b32_e32 v104, 16, v104
	v_add3_u32 v105, v107, v105, s4
	v_and_or_b32 v111, v105, s5, v104
	v_bfe_u32 v104, v100, 16, 1
	v_add3_u32 v100, v100, v104, s4
	v_bfe_u32 v104, v101, 16, 1
	v_lshrrev_b32_e32 v100, 16, v100
	v_add3_u32 v101, v101, v104, s4
	v_and_or_b32 v100, v101, s5, v100
	v_cvt_pk_bf16_f32 v101, v102, v103
	v_cvt_pk_bf16_f32 v102, v96, v97
	v_bfe_u32 v96, v98, 16, 1
	v_add3_u32 v96, v98, v96, s4
	v_bfe_u32 v98, v92, 16, 1
	v_add3_u32 v92, v92, v98, s4
	v_bfe_u32 v98, v93, 16, 1
	v_lshrrev_b32_e32 v92, 16, v92
	v_add3_u32 v93, v93, v98, s4
	v_and_or_b32 v92, v93, s5, v92
	v_cvt_pk_bf16_f32 v93, v94, v95
	v_cvt_pk_bf16_f32 v94, v88, v89
	v_bfe_u32 v88, v90, 16, 1
	v_add3_u32 v88, v90, v88, s4
	v_bfe_u32 v89, v91, 16, 1
	v_lshrrev_b32_e32 v88, 16, v88
	v_add3_u32 v89, v91, v89, s4
	v_and_or_b32 v95, v89, s5, v88
	v_bfe_u32 v88, v84, 16, 1
	v_add3_u32 v84, v84, v88, s4
	v_bfe_u32 v88, v85, 16, 1
	v_lshrrev_b32_e32 v84, 16, v84
	v_add3_u32 v85, v85, v88, s4
	v_and_or_b32 v84, v85, s5, v84
	v_cvt_pk_bf16_f32 v85, v86, v87
	v_cvt_pk_bf16_f32 v86, v80, v81
	v_bfe_u32 v80, v82, 16, 1
	v_add3_u32 v80, v82, v80, s4
	v_bfe_u32 v82, v76, 16, 1
	v_add3_u32 v76, v76, v82, s4
	v_bfe_u32 v82, v77, 16, 1
	v_lshrrev_b32_e32 v76, 16, v76
	v_add3_u32 v77, v77, v82, s4
	v_and_or_b32 v76, v77, s5, v76
	v_cvt_pk_bf16_f32 v77, v78, v79
	v_cvt_pk_bf16_f32 v78, v72, v73
	v_bfe_u32 v72, v74, 16, 1
	v_add3_u32 v72, v74, v72, s4
	v_bfe_u32 v73, v75, 16, 1
	v_lshrrev_b32_e32 v72, 16, v72
	v_add3_u32 v73, v75, v73, s4
	v_and_or_b32 v79, v73, s5, v72
	v_bfe_u32 v72, v68, 16, 1
	v_add3_u32 v68, v68, v72, s4
	v_bfe_u32 v72, v69, 16, 1
	v_lshrrev_b32_e32 v68, 16, v68
	v_add3_u32 v69, v69, v72, s4
	v_and_or_b32 v68, v69, s5, v68
	v_cvt_pk_bf16_f32 v69, v70, v71
	v_bfe_u32 v81, v83, 16, 1
	v_cvt_pk_bf16_f32 v70, v60, v61
	v_readlane_b32 s24, v250, 49
	v_lshrrev_b32_e32 v80, 16, v80
	v_add3_u32 v81, v83, v81, s4
	v_readlane_b32 s28, v250, 53
	v_and_or_b32 v87, v81, s5, v80
	v_or_b32_e32 v80, 48, v128
	v_readlane_b32 s29, v250, 54
	s_add_u32 s2, s28, 0x2b00000
	v_ashrrev_i32_e32 v81, 31, v80
	v_cvt_pk_bf16_f32 v71, v62, v63
	v_add_u32_e32 v60, 0x80, v128
	s_addc_u32 s3, s29, 0
	v_lshlrev_b64 v[80:81], 11, v[80:81]
	v_ashrrev_i32_e32 v61, 31, v60
	v_lshl_add_u64 v[130:131], s[2:3], 0, v[130:131]
	s_lshl_b32 s0, s12, 9
	v_lshl_add_u64 v[80:81], s[2:3], 0, v[80:81]
	v_lshlrev_b64 v[60:61], 11, v[60:61]
	v_lshl_add_u64 v[132:133], v[130:131], 0, s[0:1]
	v_lshlrev_b32_e32 v130, 1, v134
	v_mov_b32_e32 v131, 0
	v_lshl_add_u64 v[80:81], v[80:81], 0, s[0:1]
	v_lshl_add_u64 v[60:61], s[2:3], 0, v[60:61]
	v_lshl_add_u64 v[80:81], v[80:81], 0, v[130:131]
	v_lshl_add_u64 v[60:61], v[60:61], 0, s[0:1]
	global_store_dwordx4 v[80:81], v[68:71], off offset:256
	s_nop 1
	v_lshl_add_u64 v[68:69], v[60:61], 0, v[130:131]
	v_cvt_pk_bf16_f32 v60, v64, v65
	v_cvt_pk_bf16_f32 v61, v66, v67
	v_cvt_pk_bf16_f32 v62, v56, v57
	v_bfe_u32 v56, v58, 16, 1
	v_add3_u32 v56, v58, v56, s4
	v_bfe_u32 v57, v59, 16, 1
	v_lshrrev_b32_e32 v56, 16, v56
	v_add3_u32 v57, v59, v57, s4
	v_and_or_b32 v63, v57, s5, v56
	v_bfe_u32 v56, v52, 16, 1
	v_add3_u32 v52, v52, v56, s4
	v_bfe_u32 v56, v53, 16, 1
	v_lshrrev_b32_e32 v52, 16, v52
	v_add3_u32 v53, v53, v56, s4
	v_and_or_b32 v52, v53, s5, v52
	v_cvt_pk_bf16_f32 v53, v54, v55
	v_cvt_pk_bf16_f32 v54, v48, v49
	v_bfe_u32 v48, v50, 16, 1
; #define EPI_LOOP_ROWS(body) _Pragma("unroll") for (int ai = 0; ai < 2; ++ai) _Pragma("unroll") for (int m = 0; m < 4; ++m) { const int row = u.pm * 256 + ai * 128 + wr * 64 + m * 16 + fr; body }
; __device__ __forceinline__ unsigned f2bf(float f) { unsigned u = __builtin_bit_cast(unsigned, f); return (u + 0x7fffu + ((u >> 16) & 1u)) >> 16; }
; __device__ __forceinline__ unsigned pk2(float lo, float hi) { return f2bf(lo) | (f2bf(hi) << 16); }
; __device__ __forceinline__ void st8bf(bf16_t* p, f32x4 a, f32x4 b) { u32x4 w; w.x = pk2(a[0], a[1]); w.y = pk2(a[2], a[3]); w.z = pk2(b[0], b[1]); w.w = pk2(b[2], b[3]); st16(p, w); }
;     __device__ __forceinline__ void operator()(const f32x4 (&acc)[2][2][4][2], const pg8::Unit& u, int wr, int wc, int fr, int fq) const {
;         const int cw = wc * 32 + 8 * fq;
;         EPI_LOOP_ROWS( _Pragma("unroll") for (int bj = 0; bj < 2; ++bj) st8bf(W3P + (size_t)row * 1024 + u.pn * 256 + bj * 128 + cw, acc[ai][bj][m][0], acc[ai][bj][m][1]); )
;     }
	v_add3_u32 v48, v50, v48, s4
	v_bfe_u32 v50, v44, 16, 1
	v_add3_u32 v44, v44, v50, s4
	v_bfe_u32 v50, v45, 16, 1
	v_lshrrev_b32_e32 v44, 16, v44
	v_add3_u32 v45, v45, v50, s4
	v_and_or_b32 v44, v45, s5, v44
	v_cvt_pk_bf16_f32 v45, v46, v47
	v_cvt_pk_bf16_f32 v46, v40, v41
	v_bfe_u32 v40, v42, 16, 1
	v_add3_u32 v40, v42, v40, s4
	v_bfe_u32 v41, v43, 16, 1
	v_lshrrev_b32_e32 v40, 16, v40
	v_add3_u32 v41, v43, v41, s4
	v_and_or_b32 v47, v41, s5, v40
	v_bfe_u32 v40, v36, 16, 1
	v_add3_u32 v36, v36, v40, s4
	v_bfe_u32 v40, v37, 16, 1
	v_lshrrev_b32_e32 v36, 16, v36
	v_add3_u32 v37, v37, v40, s4
	v_and_or_b32 v36, v37, s5, v36
	v_cvt_pk_bf16_f32 v37, v38, v39
	v_cvt_pk_bf16_f32 v38, v32, v33
	v_bfe_u32 v32, v34, 16, 1
	v_add3_u32 v32, v34, v32, s4
	v_bfe_u32 v34, v28, 16, 1
	v_add3_u32 v28, v28, v34, s4
	v_bfe_u32 v34, v29, 16, 1
	v_lshrrev_b32_e32 v28, 16, v28
	v_add3_u32 v29, v29, v34, s4
	v_and_or_b32 v28, v29, s5, v28
	v_cvt_pk_bf16_f32 v29, v30, v31
	v_cvt_pk_bf16_f32 v30, v24, v25
	v_bfe_u32 v24, v26, 16, 1
	v_add3_u32 v24, v26, v24, s4
	v_bfe_u32 v25, v27, 16, 1
	v_lshrrev_b32_e32 v24, 16, v24
	v_add3_u32 v25, v27, v25, s4
	v_and_or_b32 v31, v25, s5, v24
	v_bfe_u32 v24, v20, 16, 1
	v_add3_u32 v20, v20, v24, s4
	v_bfe_u32 v24, v21, 16, 1
	v_lshrrev_b32_e32 v20, 16, v20
	v_add3_u32 v21, v21, v24, s4
	v_and_or_b32 v20, v21, s5, v20
	v_cvt_pk_bf16_f32 v21, v22, v23
	v_cvt_pk_bf16_f32 v22, v16, v17
	v_bfe_u32 v16, v18, 16, 1
	v_add3_u32 v16, v18, v16, s4
	v_bfe_u32 v18, v12, 16, 1
	v_add3_u32 v12, v12, v18, s4
	v_bfe_u32 v18, v13, 16, 1
	v_lshrrev_b32_e32 v12, 16, v12
	v_add3_u32 v13, v13, v18, s4
	v_and_or_b32 v12, v13, s5, v12
	v_cvt_pk_bf16_f32 v13, v14, v15
	v_cvt_pk_bf16_f32 v14, v8, v9
	v_cvt_pk_bf16_f32 v15, v10, v11
	v_cvt_pk_bf16_f32 v4, v4, v5
	v_bfe_u32 v113, v115, 16, 1
	v_bfe_u32 v97, v99, 16, 1
	v_bfe_u32 v49, v51, 16, 1
	v_bfe_u32 v33, v35, 16, 1
	v_bfe_u32 v17, v19, 16, 1
	v_lshrrev_b32_e32 v112, 16, v112
	v_add3_u32 v113, v115, v113, s4
	v_lshrrev_b32_e32 v96, 16, v96
	v_add3_u32 v97, v99, v97, s4
	v_lshrrev_b32_e32 v48, 16, v48
	v_add3_u32 v49, v51, v49, s4
	v_lshrrev_b32_e32 v32, 16, v32
	v_add3_u32 v33, v35, v33, s4
	v_lshrrev_b32_e32 v16, 16, v16
	v_add3_u32 v17, v19, v17, s4
	v_cvt_pk_bf16_f32 v5, v6, v7
	v_and_or_b32 v119, v113, s5, v112
	v_or_b32_e32 v112, 16, v128
	v_and_or_b32 v103, v97, s5, v96
	v_or_b32_e32 v96, 32, v128
	v_and_or_b32 v55, v49, s5, v48
	v_add_u32_e32 v48, 0x90, v128
	v_and_or_b32 v39, v33, s5, v32
	v_add_u32_e32 v32, 0xa0, v128
	v_and_or_b32 v23, v17, s5, v16
	v_add_u32_e32 v16, 0xb0, v128
	v_ashrrev_i32_e32 v113, 31, v112
	v_ashrrev_i32_e32 v97, 31, v96
	v_ashrrev_i32_e32 v49, 31, v48
	v_ashrrev_i32_e32 v33, 31, v32
	v_ashrrev_i32_e32 v17, 31, v16
	v_lshlrev_b64 v[112:113], 11, v[112:113]
	v_lshlrev_b64 v[96:97], 11, v[96:97]
	v_lshlrev_b64 v[48:49], 11, v[48:49]
	v_lshlrev_b64 v[32:33], 11, v[32:33]
	v_lshlrev_b64 v[16:17], 11, v[16:17]
	v_cvt_pk_bf16_f32 v6, v0, v1
	v_lshl_add_u64 v[112:113], s[2:3], 0, v[112:113]
	v_lshl_add_u64 v[96:97], s[2:3], 0, v[96:97]
	v_lshl_add_u64 v[48:49], s[2:3], 0, v[48:49]
	v_lshl_add_u64 v[32:33], s[2:3], 0, v[32:33]
	v_lshl_add_u64 v[16:17], s[2:3], 0, v[16:17]
	v_lshl_add_u64 v[112:113], v[112:113], 0, s[0:1]
	v_lshl_add_u64 v[96:97], v[96:97], 0, s[0:1]
	v_lshl_add_u64 v[48:49], v[48:49], 0, s[0:1]
	v_lshl_add_u64 v[32:33], v[32:33], 0, s[0:1]
	v_lshl_add_u64 v[16:17], v[16:17], 0, s[0:1]
	v_lshl_add_u64 v[132:133], v[132:133], 0, v[130:131]
	v_lshl_add_u64 v[112:113], v[112:113], 0, v[130:131]
	v_lshl_add_u64 v[96:97], v[96:97], 0, v[130:131]
	v_lshl_add_u64 v[48:49], v[48:49], 0, v[130:131]
	v_lshl_add_u64 v[32:33], v[32:33], 0, v[130:131]
	v_lshl_add_u64 v[16:17], v[16:17], 0, v[130:131]
	v_cvt_pk_bf16_f32 v7, v2, v3
	global_store_dwordx4 v[132:133], v[124:127], off
	global_store_dwordx4 v[132:133], v[116:119], off offset:256
	global_store_dwordx4 v[112:113], v[108:111], off
	global_store_dwordx4 v[112:113], v[100:103], off offset:256
	global_store_dwordx4 v[96:97], v[92:95], off
	global_store_dwordx4 v[96:97], v[84:87], off offset:256
	global_store_dwordx4 v[80:81], v[76:79], off
	global_store_dwordx4 v[68:69], v[60:63], off
	global_store_dwordx4 v[68:69], v[52:55], off offset:256
	global_store_dwordx4 v[48:49], v[44:47], off
	global_store_dwordx4 v[48:49], v[36:39], off offset:256
	global_store_dwordx4 v[32:33], v[28:31], off
	global_store_dwordx4 v[32:33], v[20:23], off offset:256
	global_store_dwordx4 v[16:17], v[12:15], off
	global_store_dwordx4 v[16:17], v[4:7], off offset:256
	s_waitcnt vmcnt(0)
	v_readlane_b32 s31, v250, 56
	v_readlane_b32 s25, v250, 50
	v_readlane_b32 s26, v250, 51
	v_readlane_b32 s27, v250, 52
	v_readlane_b32 s30, v250, 55
	s_barrier

; #define MFMA16(a, b, c) __builtin_amdgcn_mfma_f32_16x16x32_bf16((a), (b), (c), 0, 0, 0)
;     ...
;         const int t = base + pw * C.G + C.bid;
;         const int mt = t % nmt, nt = t / nmt, pn = nt >> 3, sub = nt & 7;
;         const bool glu = E::is_glu(pn);
;         const bool act = t < ntask && !(glu && sub >= 4);
;         f32x4 acc[4];
; #pragma unroll
;         for (int j = 0; j < 4; ++j) acc[j] = (f32x4){0.f, 0.f, 0.f, 0.f};
;         if (act) {
;             const bf16_t* ap = A + (size_t)(mt * mt_stride + r) * lda + (size_t)pn * a_tile_off + kh * Kh + 8 * fq;
;             const bf16_t* bp = Bt + (size_t)(256 * pn + 32 * sub + 8 * (r >> 2) + (r & 3)) * ldb + kh * Kh + 8 * fq;
;             if (glu) {
; #pragma unroll 8
;                 for (int k0 = 0; k0 < Kh; k0 += 32) { const bf16x8 a = *(const bf16x8*)(ap + k0);
;                     acc[0] = MFMA16(*(const bf16x8*)(bp + k0), a, acc[0]); acc[1] = MFMA16(*(const bf16x8*)(bp + 4 * ldb + k0), a, acc[1]);
;                     acc[2] = MFMA16(*(const bf16x8*)(bp + 128 * ldb + k0), a, acc[2]); acc[3] = MFMA16(*(const bf16x8*)(bp + 132 * ldb + k0), a, acc[3]); }
;             } else {
; #pragma unroll 8
;                 for (int k0 = 0; k0 < Kh; k0 += 32) { const bf16x8 a = *(const bf16x8*)(ap + k0);
;                     acc[0] = MFMA16(*(const bf16x8*)(bp + k0), a, acc[0]); acc[1] = MFMA16(*(const bf16x8*)(bp + 4 * ldb + k0), a, acc[1]); }
.LBB0_1833:
	s_add_i32 s22, s27, s36
	s_ashr_i32 s4, s22, 31
	s_lshr_b32 s4, s4, 29
	s_add_i32 s4, s22, s4
	s_and_b32 s5, s4, -8
	s_bfe_u32 s21, s4, 0x30003
	s_sub_i32 s8, s22, s5
	s_ashr_i32 s20, s4, 6
	s_cmpk_lt_i32 s22, 0x100
	s_cselect_b64 s[4:5], -1, 0
	s_cmpk_gt_i32 s22, 0xff
	v_mov_b32_e32 v0, 0
	v_mov_b32_e32 v1, 0
	v_mov_b32_e32 v2, 0
	v_mov_b32_e32 v3, 0
	v_mov_b32_e32 v4, 0
	v_mov_b32_e32 v5, 0
	v_mov_b32_e32 v6, 0
	v_mov_b32_e32 v7, 0
	s_cbranch_scc1 .LBB0_1835
	v_lshl_or_b32 v0, s8, 4, v27
	v_ashrrev_i32_e32 v1, 31, v0
	s_lshl_b32 s22, s20, 8
	s_lshl_b32 s23, s21, 5
	v_lshlrev_b64 v[0:1], 11, v[0:1]
	s_or_b32 s22, s22, s23
	v_lshl_add_u64 v[60:61], v[10:11], 0, v[0:1]
	v_or_b32_e32 v0, s22, v9
	v_ashrrev_i32_e32 v1, 31, v0
	v_lshlrev_b64 v[0:1], 11, v[0:1]
	v_lshl_add_u64 v[62:63], v[12:13], 0, v[0:1]
	v_add_co_u32_e32 v64, vcc, s30, v62
	s_nop 1
	v_addc_co_u32_e32 v65, vcc, 0, v63, vcc
	global_load_dwordx4 v[122:125], v[60:61], off
	global_load_dwordx4 v[126:129], v[62:63], off
	global_load_dwordx4 v[130:133], v[64:65], off
	global_load_dwordx4 v[134:137], v[60:61], off offset:64
	global_load_dwordx4 v[138:141], v[62:63], off offset:64
	global_load_dwordx4 v[142:145], v[64:65], off offset:64
	global_load_dwordx4 v[146:149], v[60:61], off offset:128
	global_load_dwordx4 v[150:153], v[62:63], off offset:128
	global_load_dwordx4 v[154:157], v[64:65], off offset:128
	global_load_dwordx4 v[176:179], v[60:61], off offset:192
	global_load_dwordx4 v[180:183], v[62:63], off offset:192
	global_load_dwordx4 v[184:187], v[64:65], off offset:192
	s_waitcnt vmcnt(9)
	v_mfma_f32_16x16x32_bf16 v[4:7], v[126:129], v[122:125], 0
	v_mfma_f32_16x16x32_bf16 v[0:3], v[130:133], v[122:125], 0
	s_waitcnt vmcnt(6)
	v_mfma_f32_16x16x32_bf16 v[4:7], v[138:141], v[134:137], v[4:7]
	v_mfma_f32_16x16x32_bf16 v[0:3], v[142:145], v[134:137], v[0:3]
	s_waitcnt vmcnt(3)
	v_mfma_f32_16x16x32_bf16 v[4:7], v[150:153], v[146:149], v[4:7]
	v_mfma_f32_16x16x32_bf16 v[0:3], v[154:157], v[146:149], v[0:3]
	s_waitcnt vmcnt(0)
	v_mfma_f32_16x16x32_bf16 v[4:7], v[180:183], v[176:179], v[4:7]
	v_mfma_f32_16x16x32_bf16 v[0:3], v[184:187], v[176:179], v[0:3]
	s_nop 0

; __device__ __forceinline__ void ln_row(const float* xin, const float* dp, const float* gam, const float* bet, float* of, bf16_t* ob, int lane) {
;     f32x4 v[4]; float s = 0.f;
; #pragma unroll
;     for (int j = 0; j < 4; ++j) { const f32x4 a = *(const f32x4*)(xin + 4 * lane + 256 * j), d = *(const f32x4*)(dp + 4 * lane + 256 * j); v[j] = a * ALPHA + d; s += (v[j][0] + v[j][1]) + (v[j][2] + v[j][3]); }
;     const float mean = wave_sum(s) * (1.f / DM); float q = 0.f;
.LBB0_1847:
	s_or_b32 s8, s4, s22
	s_lshl_b64 s[4:5], s[8:9], 10
	s_add_u32 s4, s4, 0x2000000
	s_addc_u32 s5, s5, 0
	s_lshl_b64 s[38:39], s[8:9], 12
	v_lshl_add_u64 v[68:69], v[16:17], 0, s[38:39]
	v_lshl_add_u64 v[72:73], v[14:15], 0, s[38:39]
	global_load_dwordx4 v[40:43], v[18:19], off
	global_load_dwordx4 v[44:47], v[20:21], off
	global_load_dwordx4 v[4:7], v[72:73], off
	global_load_dwordx4 v[48:51], v[68:69], off
	global_load_dwordx4 v[52:55], v[68:69], off offset:1024
	global_load_dwordx4 v[56:59], v[72:73], off offset:1024
	global_load_dwordx4 v[60:63], v[72:73], off offset:2048
	global_load_dwordx4 v[64:67], v[68:69], off offset:2048
	s_nop 0
	global_load_dwordx4 v[68:71], v[68:69], off offset:3072
	s_nop 0
	global_load_dwordx4 v[72:75], v[72:73], off offset:3072
	v_mov_b32_e32 v39, 0
	v_mov_b32_e32 v76, 0
	v_lshl_add_u64 v[2:3], s[4:5], 2, v[22:23]
	v_lshl_add_u64 v[0:1], s[4:5], 1, v[24:25]
	v_mov_b32_e32 v77, 0
	v_mov_b32_e32 v78, 0
	s_waitcnt vmcnt(6)
	v_pk_fma_f32 v[48:49], v[48:49], s[18:19], v[4:5] op_sel_hi:[1,0,1]
	v_pk_fma_f32 v[50:51], v[50:51], s[18:19], v[6:7] op_sel_hi:[1,0,1]
	s_waitcnt vmcnt(4)
	v_pk_fma_f32 v[52:53], v[52:53], s[18:19], v[56:57] op_sel_hi:[1,0,1]
	v_pk_fma_f32 v[54:55], v[54:55], s[18:19], v[58:59] op_sel_hi:[1,0,1]
	s_waitcnt vmcnt(2)
	v_pk_fma_f32 v[56:57], v[66:67], s[18:19], v[62:63] op_sel_hi:[1,0,1]
	v_pk_fma_f32 v[58:59], v[64:65], s[18:19], v[60:61] op_sel_hi:[1,0,1]
	v_pk_mov_b32 v[60:61], v[48:49], v[50:51] op_sel:[1,0]
	v_mov_b32_e32 v62, v48
	v_mov_b32_e32 v63, v51
	v_pk_mov_b32 v[64:65], v[52:53], v[54:55] op_sel:[1,0]
	v_mov_b32_e32 v66, v52
	v_mov_b32_e32 v67, v55
	v_pk_add_f32 v[60:61], v[60:61], v[62:63]
	v_pk_add_f32 v[62:63], v[64:65], v[66:67]
	s_waitcnt vmcnt(0)
; __device__ __forceinline__ unsigned pk2(float lo, float hi) { return f2bf(lo) | (f2bf(hi) << 16); }
; __device__ __forceinline__ void ln_row(const float* xin, const float* dp, const float* gam, const float* bet, float* of, bf16_t* ob, int lane) {
;     ...
;     const float mean = wave_sum(s) * (1.f / DM); float q = 0.f;
; #pragma unroll
;     for (int j = 0; j < 4; ++j) { v[j] = v[j] - mean; q += (v[j][0] * v[j][0] + v[j][1] * v[j][1]) + (v[j][2] * v[j][2] + v[j][3] * v[j][3]); }
;     const float rstd = 1.f / sqrtf(wave_sum(q) * (1.f / DM) + LN_EPS);
; #pragma unroll
;     for (int j = 0; j < 4; ++j) { const f32x4 gg = *(const f32x4*)(gam + 4 * lane + 256 * j), bb = *(const f32x4*)(bet + 4 * lane + 256 * j); const f32x4 o = v[j] * rstd * gg + bb;
;         *(f32x4*)(of + 4 * lane + 256 * j) = o;
;         if (ob) { u32x2 w; w.x = pk2(o[0], o[1]); w.y = pk2(o[2], o[3]); *(u32x2*)(ob + 4 * lane + 256 * j) = w; } }
	v_pk_fma_f32 v[6:7], v[70:71], s[18:19], v[74:75] op_sel_hi:[1,0,1]
	v_pk_fma_f32 v[4:5], v[68:69], s[18:19], v[72:73] op_sel_hi:[1,0,1]
	v_add_f32_e32 v66, v60, v61
	v_pk_add_f32 v[60:61], v[62:63], v[62:63] op_sel:[0,1] op_sel_hi:[1,0]
	v_add_f32_e32 v68, v58, v59
	v_add_f32_e32 v70, v56, v57
	v_mov_b32_e32 v73, v4
	v_mov_b32_e32 v69, v6
	v_mov_b32_e32 v71, v7
	v_add_f32_e32 v72, 0, v66
	v_mov_b32_e32 v61, v5
	v_pk_add_f32 v[64:65], v[68:69], v[70:71]
	v_pk_add_f32 v[60:61], v[72:73], v[60:61]
	s_nop 0
	v_pk_add_f32 v[60:61], v[60:61], v[64:65]
	s_nop 0
	v_add_f32_e32 v60, v60, v61
	s_nop 1
	v_add_f32_dpp v60, v60, v60 row_shr:1 row_mask:0xf bank_mask:0xf bound_ctrl:1
	s_nop 1
	v_add_f32_dpp v60, v60, v60 row_shr:2 row_mask:0xf bank_mask:0xf bound_ctrl:1
	s_nop 1
	v_add_f32_dpp v60, v60, v60 row_shr:4 row_mask:0xf bank_mask:0xf bound_ctrl:1
	s_nop 1
	v_add_f32_dpp v60, v60, v60 row_shr:8 row_mask:0xf bank_mask:0xf bound_ctrl:1
	s_nop 1
	v_mov_b32_dpp v39, v60 row_bcast:15 row_mask:0xa bank_mask:0xf
	v_add_f32_e32 v39, v60, v39
	s_nop 1
	v_mov_b32_dpp v76, v39 row_bcast:31 row_mask:0xc bank_mask:0xf
	v_add_f32_e32 v39, v39, v76
	s_nop 0
	v_readlane_b32 s4, v39, 63
	s_nop 1
	v_fmac_f32_e32 v51, s4, v37
	v_fmac_f32_e32 v49, s4, v37
	v_fmac_f32_e32 v55, s4, v37
	v_fmac_f32_e32 v53, s4, v37
	v_fma_f32 v50, s4, v37, v50
	v_fma_f32 v48, s4, v37, v48
	v_fma_f32 v54, s4, v37, v54
	v_fma_f32 v52, s4, v37, v52
	v_fmac_f32_e32 v57, s4, v37
	v_fmac_f32_e32 v59, s4, v37
	v_mul_f32_e32 v39, v49, v49
	v_mul_f32_e32 v60, v51, v51
	v_mul_f32_e32 v61, v53, v53
	v_mul_f32_e32 v62, v55, v55
	v_fma_f32 v56, s4, v37, v56
	v_fma_f32 v58, s4, v37, v58
	v_fmac_f32_e32 v7, s4, v37
	v_fmac_f32_e32 v5, s4, v37
	v_mul_f32_e32 v63, v59, v59
	v_mul_f32_e32 v64, v57, v57
	v_fmac_f32_e32 v39, v48, v48
	v_fmac_f32_e32 v60, v50, v50
	v_fmac_f32_e32 v61, v52, v52
	v_fmac_f32_e32 v62, v54, v54
	v_fma_f32 v6, s4, v37, v6
	v_fma_f32 v4, s4, v37, v4
	v_mul_f32_e32 v65, v5, v5
	v_mul_f32_e32 v66, v7, v7
	v_fmac_f32_e32 v63, v58, v58
	v_fmac_f32_e32 v64, v56, v56
	v_add_f32_e32 v39, v39, v60
	v_add_f32_e32 v60, v61, v62
	v_fmac_f32_e32 v65, v4, v4
	v_fmac_f32_e32 v66, v6, v6
	v_add_f32_e32 v61, v63, v64
	v_add_f32_e32 v39, v39, v60
	v_add_f32_e32 v62, v65, v66
	v_add_f32_e32 v39, v61, v39
	v_add_f32_e32 v39, v62, v39
	s_nop 1
	v_add_f32_dpp v39, v39, v39 row_shr:1 row_mask:0xf bank_mask:0xf bound_ctrl:1
	s_nop 1
	v_add_f32_dpp v39, v39, v39 row_shr:2 row_mask:0xf bank_mask:0xf bound_ctrl:1
	s_nop 1
	v_add_f32_dpp v39, v39, v39 row_shr:4 row_mask:0xf bank_mask:0xf bound_ctrl:1
	s_nop 1
	v_add_f32_dpp v39, v39, v39 row_shr:8 row_mask:0xf bank_mask:0xf bound_ctrl:1
	s_nop 1
	v_mov_b32_dpp v77, v39 row_bcast:15 row_mask:0xa bank_mask:0xf
	v_add_f32_e32 v39, v39, v77
	s_nop 1
	v_mov_b32_dpp v78, v39 row_bcast:31 row_mask:0xc bank_mask:0xf
	v_add_f32_e32 v39, v39, v78
	s_nop 0
	v_readlane_b32 s4, v39, 63
	s_nop 1
	v_fma_f32 v39, s4, v38, v34
	v_mul_f32_e32 v60, 0x4f800000, v39
	v_cmp_gt_f32_e32 vcc, s31, v39
	s_nop 1
	v_cndmask_b32_e32 v39, v39, v60, vcc
	v_sqrt_f32_e32 v60, v39
	s_nop 0
	v_add_u32_e32 v61, -1, v60
	v_add_u32_e32 v62, 1, v60
	v_fma_f32 v63, -v61, v60, v39
	v_fma_f32 v64, -v62, v60, v39
	v_cmp_ge_f32_e64 s[4:5], 0, v63
	s_nop 1
	v_cndmask_b32_e64 v60, v60, v61, s[4:5]
	v_cmp_lt_f32_e64 s[4:5], 0, v64
	s_nop 1
	v_cndmask_b32_e64 v60, v60, v62, s[4:5]
	v_mul_f32_e32 v61, 0x37800000, v60
	v_cndmask_b32_e32 v60, v60, v61, vcc
	v_cmp_class_f32_e32 vcc, v39, v35
	s_nop 1
	v_cndmask_b32_e32 v39, v60, v39, vcc
	v_div_scale_f32 v60, s[4:5], v39, v39, 1.0
	v_rcp_f32_e32 v62, v60
	v_div_scale_f32 v61, vcc, 1.0, v39, 1.0
	s_mov_b32 s4, 1
	v_fma_f32 v63, -v60, v62, 1.0
	v_fmac_f32_e32 v62, v63, v62
	v_mul_f32_e32 v63, v61, v62
	v_fma_f32 v64, -v60, v63, v61
	v_fmac_f32_e32 v63, v64, v62
	v_fma_f32 v60, -v60, v63, v61
	v_div_fmas_f32 v60, v60, v62, v63
	v_div_fixup_f32 v60, v60, v39, 1.0
	v_pk_mul_f32 v[48:49], v[48:49], v[60:61] op_sel_hi:[1,0]
	v_pk_mul_f32 v[50:51], v[50:51], v[60:61] op_sel_hi:[1,0]
	v_pk_fma_f32 v[40:41], v[40:41], v[48:49], v[44:45]
	v_pk_fma_f32 v[42:43], v[42:43], v[50:51], v[46:47]
	v_bfe_u32 v39, v40, 16, 1
	v_bfe_u32 v44, v41, 16, 1
	global_store_dwordx4 v[2:3], v[40:43], off
	v_add3_u32 v39, v40, v39, s34
	s_nop 0
	v_add3_u32 v40, v41, v44, s34
	v_lshrrev_b32_e32 v39, 16, v39
	v_and_or_b32 v40, v40, s35, v39
	v_cvt_pk_bf16_f32 v41, v42, v43
	global_store_dwordx2 v[0:1], v[40:41], off
	global_load_dwordx4 v[40:43], v[18:19], off offset:1024
	s_nop 0
	global_load_dwordx4 v[44:47], v[20:21], off offset:1024
	v_pk_mul_f32 v[48:49], v[54:55], v[60:61] op_sel_hi:[1,0]
	v_pk_mul_f32 v[50:51], v[52:53], v[60:61] op_sel_hi:[1,0]
	v_pk_mul_f32 v[6:7], v[6:7], v[60:61] op_sel_hi:[1,0]
	v_pk_mul_f32 v[4:5], v[4:5], v[60:61] op_sel_hi:[1,0]
	s_and_b64 vcc, exec, s[20:21]
	s_mov_b64 s[20:21], 0
	s_waitcnt vmcnt(0)
	v_pk_fma_f32 v[40:41], v[40:41], v[50:51], v[44:45]
	v_pk_fma_f32 v[42:43], v[42:43], v[48:49], v[46:47]
	v_bfe_u32 v39, v40, 16, 1
	v_bfe_u32 v44, v41, 16, 1
	global_store_dwordx4 v[2:3], v[40:43], off offset:1024
	v_add3_u32 v39, v40, v39, s34
	s_nop 0
	v_add3_u32 v40, v41, v44, s34
	v_lshrrev_b32_e32 v39, 16, v39
	v_and_or_b32 v40, v40, s35, v39
	v_cvt_pk_bf16_f32 v41, v42, v43
	global_store_dwordx2 v[0:1], v[40:41], off offset:512
	global_load_dwordx4 v[40:43], v[18:19], off offset:2048
	s_nop 0
	global_load_dwordx4 v[44:47], v[20:21], off offset:2048
	v_pk_mul_f32 v[48:49], v[56:57], v[60:61] op_sel_hi:[1,0]
	v_pk_mul_f32 v[50:51], v[58:59], v[60:61] op_sel_hi:[1,0]
	s_waitcnt vmcnt(0)
	v_pk_fma_f32 v[42:43], v[48:49], v[42:43], v[46:47]
	v_pk_fma_f32 v[40:41], v[50:51], v[40:41], v[44:45]
	v_bfe_u32 v39, v40, 16, 1
	v_bfe_u32 v44, v41, 16, 1
	global_store_dwordx4 v[2:3], v[40:43], off offset:2048
	v_add3_u32 v39, v40, v39, s34
	s_nop 0
	v_add3_u32 v40, v41, v44, s34
	v_lshrrev_b32_e32 v39, 16, v39
	v_and_or_b32 v40, v40, s35, v39
	v_cvt_pk_bf16_f32 v41, v42, v43
	global_store_dwordx2 v[0:1], v[40:41], off offset:1024
	global_load_dwordx4 v[40:43], v[18:19], off offset:3072
	s_nop 0
	global_load_dwordx4 v[44:47], v[20:21], off offset:3072
	s_waitcnt vmcnt(0)
	v_pk_fma_f32 v[4:5], v[4:5], v[40:41], v[44:45]
	v_pk_fma_f32 v[6:7], v[6:7], v[42:43], v[46:47]
	global_store_dwordx4 v[2:3], v[4:7], off offset:3072
	v_bfe_u32 v2, v4, 16, 1
	v_bfe_u32 v3, v5, 16, 1
	v_add3_u32 v2, v4, v2, s34
	v_add3_u32 v3, v5, v3, s34
	v_lshrrev_b32_e32 v2, 16, v2
	v_and_or_b32 v2, v3, s35, v2
	v_cvt_pk_bf16_f32 v3, v6, v7
	global_store_dwordx2 v[0:1], v[2:3], off offset:1536
	s_cbranch_vccnz .LBB0_1847

; __device__ __forceinline__ unsigned pk2(float lo, float hi) { return f2bf(lo) | (f2bf(hi) << 16); }
; __device__ __forceinline__ void ln_row(const float* xin, const float* dp, const float* gam, const float* bet, float* of, bf16_t* ob, int lane) {
;     f32x4 v[4]; float s = 0.f;
; #pragma unroll
;     for (int j = 0; j < 4; ++j) { const f32x4 a = *(const f32x4*)(xin + 4 * lane + 256 * j), d = *(const f32x4*)(dp + 4 * lane + 256 * j); v[j] = a * ALPHA + d; s += (v[j][0] + v[j][1]) + (v[j][2] + v[j][3]); }
;     const float mean = wave_sum(s) * (1.f / DM); float q = 0.f;
; #pragma unroll
;     for (int j = 0; j < 4; ++j) { v[j] = v[j] - mean; q += (v[j][0] * v[j][0] + v[j][1] * v[j][1]) + (v[j][2] * v[j][2] + v[j][3] * v[j][3]); }
;     const float rstd = 1.f / sqrtf(wave_sum(q) * (1.f / DM) + LN_EPS);
; #pragma unroll
;     for (int j = 0; j < 4; ++j) { const f32x4 gg = *(const f32x4*)(gam + 4 * lane + 256 * j), bb = *(const f32x4*)(bet + 4 * lane + 256 * j); const f32x4 o = v[j] * rstd * gg + bb;
;         *(f32x4*)(of + 4 * lane + 256 * j) = o;
;         if (ob) { u32x2 w; w.x = pk2(o[0], o[1]); w.y = pk2(o[2], o[3]); *(u32x2*)(ob + 4 * lane + 256 * j) = w; } }
.LBB0_1856:
	s_or_b32 s8, s4, s22
	s_lshl_b64 s[4:5], s[8:9], 10
	s_add_u32 s4, s4, 0x2000000
	s_addc_u32 s5, s5, 0
	s_lshl_b64 s[38:39], s[8:9], 12
	v_lshl_add_u64 v[68:69], v[16:17], 0, s[38:39]
	v_lshl_add_u64 v[72:73], v[14:15], 0, s[38:39]
	global_load_dwordx4 v[40:43], v[18:19], off
	global_load_dwordx4 v[44:47], v[20:21], off
	global_load_dwordx4 v[4:7], v[72:73], off
	global_load_dwordx4 v[48:51], v[68:69], off
	global_load_dwordx4 v[52:55], v[68:69], off offset:1024
	global_load_dwordx4 v[56:59], v[72:73], off offset:1024
	global_load_dwordx4 v[60:63], v[72:73], off offset:2048
	global_load_dwordx4 v[64:67], v[68:69], off offset:2048
	s_nop 0
	global_load_dwordx4 v[68:71], v[68:69], off offset:3072
	s_nop 0
	global_load_dwordx4 v[72:75], v[72:73], off offset:3072
	v_mov_b32_e32 v39, 0
	v_mov_b32_e32 v76, 0
	v_lshl_add_u64 v[2:3], s[4:5], 2, v[22:23]
	v_lshl_add_u64 v[0:1], s[4:5], 1, v[24:25]
	v_mov_b32_e32 v77, 0
	v_mov_b32_e32 v78, 0
	s_waitcnt vmcnt(6)
	v_pk_fma_f32 v[48:49], v[48:49], s[18:19], v[4:5] op_sel_hi:[1,0,1]
	v_pk_fma_f32 v[50:51], v[50:51], s[18:19], v[6:7] op_sel_hi:[1,0,1]
	s_waitcnt vmcnt(4)
	v_pk_fma_f32 v[52:53], v[52:53], s[18:19], v[56:57] op_sel_hi:[1,0,1]
	v_pk_fma_f32 v[54:55], v[54:55], s[18:19], v[58:59] op_sel_hi:[1,0,1]
	s_waitcnt vmcnt(2)
	v_pk_fma_f32 v[56:57], v[66:67], s[18:19], v[62:63] op_sel_hi:[1,0,1]
	v_pk_fma_f32 v[58:59], v[64:65], s[18:19], v[60:61] op_sel_hi:[1,0,1]
	v_pk_mov_b32 v[60:61], v[48:49], v[50:51] op_sel:[1,0]
	v_mov_b32_e32 v62, v48
	v_mov_b32_e32 v63, v51
	v_pk_mov_b32 v[64:65], v[52:53], v[54:55] op_sel:[1,0]
	v_mov_b32_e32 v66, v52
	v_mov_b32_e32 v67, v55
	v_pk_add_f32 v[60:61], v[60:61], v[62:63]
	v_pk_add_f32 v[62:63], v[64:65], v[66:67]
	s_waitcnt vmcnt(0)
	v_pk_fma_f32 v[6:7], v[70:71], s[18:19], v[74:75] op_sel_hi:[1,0,1]
	v_pk_fma_f32 v[4:5], v[68:69], s[18:19], v[72:73] op_sel_hi:[1,0,1]
	v_add_f32_e32 v66, v60, v61
	v_pk_add_f32 v[60:61], v[62:63], v[62:63] op_sel:[0,1] op_sel_hi:[1,0]
	v_add_f32_e32 v68, v58, v59
	v_add_f32_e32 v70, v56, v57
	v_mov_b32_e32 v73, v4
	v_mov_b32_e32 v69, v6
	v_mov_b32_e32 v71, v7
	v_add_f32_e32 v72, 0, v66
	v_mov_b32_e32 v61, v5
	v_pk_add_f32 v[64:65], v[68:69], v[70:71]
	v_pk_add_f32 v[60:61], v[72:73], v[60:61]
	s_nop 0
	v_pk_add_f32 v[60:61], v[60:61], v[64:65]
	s_nop 0
	v_add_f32_e32 v60, v60, v61
	s_nop 1
	v_add_f32_dpp v60, v60, v60 row_shr:1 row_mask:0xf bank_mask:0xf bound_ctrl:1
	s_nop 1
	v_add_f32_dpp v60, v60, v60 row_shr:2 row_mask:0xf bank_mask:0xf bound_ctrl:1
	s_nop 1
	v_add_f32_dpp v60, v60, v60 row_shr:4 row_mask:0xf bank_mask:0xf bound_ctrl:1
	s_nop 1
	v_add_f32_dpp v60, v60, v60 row_shr:8 row_mask:0xf bank_mask:0xf bound_ctrl:1
	s_nop 1
	v_mov_b32_dpp v39, v60 row_bcast:15 row_mask:0xa bank_mask:0xf
	v_add_f32_e32 v39, v60, v39
	s_nop 1
	v_mov_b32_dpp v76, v39 row_bcast:31 row_mask:0xc bank_mask:0xf
	v_add_f32_e32 v39, v39, v76
	s_nop 0
	v_readlane_b32 s4, v39, 63
	s_nop 1
	v_fmac_f32_e32 v51, s4, v37
	v_fmac_f32_e32 v49, s4, v37
	v_fmac_f32_e32 v55, s4, v37
	v_fmac_f32_e32 v53, s4, v37
	v_fma_f32 v50, s4, v37, v50
	v_fma_f32 v48, s4, v37, v48
	v_fma_f32 v54, s4, v37, v54
	v_fma_f32 v52, s4, v37, v52
	v_fmac_f32_e32 v57, s4, v37
	v_fmac_f32_e32 v59, s4, v37
	v_mul_f32_e32 v39, v49, v49
	v_mul_f32_e32 v60, v51, v51
	v_mul_f32_e32 v61, v53, v53
	v_mul_f32_e32 v62, v55, v55
	v_fma_f32 v56, s4, v37, v56
	v_fma_f32 v58, s4, v37, v58
	v_fmac_f32_e32 v7, s4, v37
	v_fmac_f32_e32 v5, s4, v37
	v_mul_f32_e32 v63, v59, v59
	v_mul_f32_e32 v64, v57, v57
	v_fmac_f32_e32 v39, v48, v48
	v_fmac_f32_e32 v60, v50, v50
	v_fmac_f32_e32 v61, v52, v52
	v_fmac_f32_e32 v62, v54, v54
	v_fma_f32 v6, s4, v37, v6
	v_fma_f32 v4, s4, v37, v4
	v_mul_f32_e32 v65, v5, v5
	v_mul_f32_e32 v66, v7, v7
	v_fmac_f32_e32 v63, v58, v58
	v_fmac_f32_e32 v64, v56, v56
	v_add_f32_e32 v39, v39, v60
	v_add_f32_e32 v60, v61, v62
	v_fmac_f32_e32 v65, v4, v4
	v_fmac_f32_e32 v66, v6, v6
	v_add_f32_e32 v61, v63, v64
	v_add_f32_e32 v39, v39, v60
	v_add_f32_e32 v62, v65, v66
	v_add_f32_e32 v39, v61, v39
	v_add_f32_e32 v39, v62, v39
	s_nop 1
	v_add_f32_dpp v39, v39, v39 row_shr:1 row_mask:0xf bank_mask:0xf bound_ctrl:1
	s_nop 1
	v_add_f32_dpp v39, v39, v39 row_shr:2 row_mask:0xf bank_mask:0xf bound_ctrl:1
	s_nop 1
	v_add_f32_dpp v39, v39, v39 row_shr:4 row_mask:0xf bank_mask:0xf bound_ctrl:1
	s_nop 1
	v_add_f32_dpp v39, v39, v39 row_shr:8 row_mask:0xf bank_mask:0xf bound_ctrl:1
	s_nop 1
	v_mov_b32_dpp v77, v39 row_bcast:15 row_mask:0xa bank_mask:0xf
	v_add_f32_e32 v39, v39, v77
	s_nop 1
	v_mov_b32_dpp v78, v39 row_bcast:31 row_mask:0xc bank_mask:0xf
	v_add_f32_e32 v39, v39, v78
	s_nop 0
	v_readlane_b32 s4, v39, 63
	s_nop 1
	v_fma_f32 v39, s4, v38, v34
	v_mul_f32_e32 v60, 0x4f800000, v39
	v_cmp_gt_f32_e32 vcc, s31, v39
	s_nop 1
	v_cndmask_b32_e32 v39, v39, v60, vcc
	v_sqrt_f32_e32 v60, v39
	s_nop 0
	v_add_u32_e32 v61, -1, v60
	v_add_u32_e32 v62, 1, v60
	v_fma_f32 v63, -v61, v60, v39
	v_fma_f32 v64, -v62, v60, v39
	v_cmp_ge_f32_e64 s[4:5], 0, v63
	s_nop 1
	v_cndmask_b32_e64 v60, v60, v61, s[4:5]
	v_cmp_lt_f32_e64 s[4:5], 0, v64
	s_nop 1
	v_cndmask_b32_e64 v60, v60, v62, s[4:5]
	v_mul_f32_e32 v61, 0x37800000, v60
	v_cndmask_b32_e32 v60, v60, v61, vcc
	v_cmp_class_f32_e32 vcc, v39, v35
	s_nop 1
	v_cndmask_b32_e32 v39, v60, v39, vcc
	v_div_scale_f32 v60, s[4:5], v39, v39, 1.0
	v_rcp_f32_e32 v62, v60
	v_div_scale_f32 v61, vcc, 1.0, v39, 1.0
	s_mov_b32 s4, 1
	v_fma_f32 v63, -v60, v62, 1.0
	v_fmac_f32_e32 v62, v63, v62
	v_mul_f32_e32 v63, v61, v62
	v_fma_f32 v64, -v60, v63, v61
	v_fmac_f32_e32 v63, v64, v62
	v_fma_f32 v60, -v60, v63, v61
	v_div_fmas_f32 v60, v60, v62, v63
	v_div_fixup_f32 v60, v60, v39, 1.0
	v_pk_mul_f32 v[48:49], v[48:49], v[60:61] op_sel_hi:[1,0]
	v_pk_mul_f32 v[50:51], v[50:51], v[60:61] op_sel_hi:[1,0]
	v_pk_fma_f32 v[40:41], v[40:41], v[48:49], v[44:45]
	v_pk_fma_f32 v[42:43], v[42:43], v[50:51], v[46:47]
	v_bfe_u32 v39, v40, 16, 1
	v_bfe_u32 v44, v41, 16, 1
	global_store_dwordx4 v[2:3], v[40:43], off
	v_add3_u32 v39, v40, v39, s34
	s_nop 0
	v_add3_u32 v40, v41, v44, s34
	v_lshrrev_b32_e32 v39, 16, v39
	v_and_or_b32 v40, v40, s35, v39
	v_cvt_pk_bf16_f32 v41, v42, v43
	global_store_dwordx2 v[0:1], v[40:41], off
	global_load_dwordx4 v[40:43], v[18:19], off offset:1024
	s_nop 0
	global_load_dwordx4 v[44:47], v[20:21], off offset:1024
	v_pk_mul_f32 v[48:49], v[54:55], v[60:61] op_sel_hi:[1,0]
	v_pk_mul_f32 v[50:51], v[52:53], v[60:61] op_sel_hi:[1,0]
	v_pk_mul_f32 v[6:7], v[6:7], v[60:61] op_sel_hi:[1,0]
	v_pk_mul_f32 v[4:5], v[4:5], v[60:61] op_sel_hi:[1,0]
	s_and_b64 vcc, exec, s[20:21]
	s_mov_b64 s[20:21], 0
	s_waitcnt vmcnt(0)
; __device__ __forceinline__ unsigned pk2(float lo, float hi) { return f2bf(lo) | (f2bf(hi) << 16); }
; __device__ __forceinline__ void ln_row(const float* xin, const float* dp, const float* gam, const float* bet, float* of, bf16_t* ob, int lane) {
;     ...
;     for (int j = 0; j < 4; ++j) { const f32x4 gg = *(const f32x4*)(gam + 4 * lane + 256 * j), bb = *(const f32x4*)(bet + 4 * lane + 256 * j); const f32x4 o = v[j] * rstd * gg + bb;
;         *(f32x4*)(of + 4 * lane + 256 * j) = o;
;         if (ob) { u32x2 w; w.x = pk2(o[0], o[1]); w.y = pk2(o[2], o[3]); *(u32x2*)(ob + 4 * lane + 256 * j) = w; } }
	v_pk_fma_f32 v[40:41], v[40:41], v[50:51], v[44:45]
	v_pk_fma_f32 v[42:43], v[42:43], v[48:49], v[46:47]
	v_bfe_u32 v39, v40, 16, 1
	v_bfe_u32 v44, v41, 16, 1
	global_store_dwordx4 v[2:3], v[40:43], off offset:1024
	v_add3_u32 v39, v40, v39, s34
	s_nop 0
	v_add3_u32 v40, v41, v44, s34
	v_lshrrev_b32_e32 v39, 16, v39
	v_and_or_b32 v40, v40, s35, v39
	v_cvt_pk_bf16_f32 v41, v42, v43
	global_store_dwordx2 v[0:1], v[40:41], off offset:512
	global_load_dwordx4 v[40:43], v[18:19], off offset:2048
	s_nop 0
	global_load_dwordx4 v[44:47], v[20:21], off offset:2048
	v_pk_mul_f32 v[48:49], v[56:57], v[60:61] op_sel_hi:[1,0]
	v_pk_mul_f32 v[50:51], v[58:59], v[60:61] op_sel_hi:[1,0]
	s_waitcnt vmcnt(0)
	v_pk_fma_f32 v[42:43], v[48:49], v[42:43], v[46:47]
	v_pk_fma_f32 v[40:41], v[50:51], v[40:41], v[44:45]
	v_bfe_u32 v39, v40, 16, 1
	v_bfe_u32 v44, v41, 16, 1
	global_store_dwordx4 v[2:3], v[40:43], off offset:2048
	v_add3_u32 v39, v40, v39, s34
	s_nop 0
	v_add3_u32 v40, v41, v44, s34
	v_lshrrev_b32_e32 v39, 16, v39
	v_and_or_b32 v40, v40, s35, v39
	v_cvt_pk_bf16_f32 v41, v42, v43
	global_store_dwordx2 v[0:1], v[40:41], off offset:1024
	global_load_dwordx4 v[40:43], v[18:19], off offset:3072
	s_nop 0
	global_load_dwordx4 v[44:47], v[20:21], off offset:3072
	s_waitcnt vmcnt(0)
	v_pk_fma_f32 v[4:5], v[4:5], v[40:41], v[44:45]
	v_pk_fma_f32 v[6:7], v[6:7], v[42:43], v[46:47]
	global_store_dwordx4 v[2:3], v[4:7], off offset:3072
	v_bfe_u32 v2, v4, 16, 1
	v_bfe_u32 v39, v6, 16, 1
	v_bfe_u32 v3, v5, 16, 1
	v_bfe_u32 v40, v7, 16, 1
	v_add3_u32 v2, v4, v2, s34
	v_add3_u32 v4, v6, v39, s34
	v_add3_u32 v3, v5, v3, s34
	v_add3_u32 v5, v7, v40, s34
	v_lshrrev_b32_e32 v2, 16, v2
	v_lshrrev_b32_e32 v4, 16, v4
	v_and_or_b32 v2, v3, s35, v2
	v_and_or_b32 v3, v5, s35, v4
	global_store_dwordx2 v[0:1], v[2:3], off offset:1536
	s_cbranch_vccnz .LBB0_1856

; __device__ __forceinline__ unsigned pk2(float lo, float hi) { return f2bf(lo) | (f2bf(hi) << 16); }
;     __device__ __forceinline__ void fused(f32x4 (&acc)[2][2][4][2], const pg8::Unit& u, int wr, int wc, int fr, int fq, LAS unsigned char* lds, int wid, int lane) const {
;     ...
;             for (int m = 0; m < 4; ++m) { const int r = ai * 128 + wr * 64 + m * 16 + fr; const f32x2v sr = S[r]; const size_t off = (size_t)(u.pm * 256 + r) * DM + col0;
; #pragma unroll
;                 for (int bj = 0; bj < 2; ++bj)
; #pragma unroll
;                     for (int n = 0; n < 2; ++n) { f32x4 o = (acc[ai][bj][m][n] - sr.x) * sr.y * gg[bj][n] + bb[bj][n];
;                         if (bad) o = (f32x4){qnan, qnan, qnan, qnan};
;                         if (outf) *(f32x4*)(outf + off + bj * 128 + n * 16) = o;
;                         if (outb) { u32x2 w; w.x = pk2(o[0], o[1]); w.y = pk2(o[2], o[3]); *(u32x2*)(outb + off + bj * 128 + n * 16) = w; } } }
.LBB0_1917:
	s_or_b64 exec, exec, s[40:41]
	s_waitcnt lgkmcnt(0)
	s_barrier
	s_waitcnt lgkmcnt(1)
	ds_read_b64 v[180:181], v195
	ds_read_b64 v[182:183], v197
	ds_read_b64 v[184:185], v199
	ds_read_b64 v[186:187], v201
	s_waitcnt lgkmcnt(4)
	v_cmp_eq_u32_e32 vcc, 0, v164
	s_waitcnt lgkmcnt(3)
	v_sub_f32_e32 v145, v145, v180
	v_sub_f32_e32 v144, v144, v180
	v_pk_mul_f32 v[144:145], v[180:181], v[144:145] op_sel:[1,0]
	v_sub_f32_e32 v147, v147, v180
	s_waitcnt vmcnt(5)
	v_pk_fma_f32 v[144:145], v[88:89], v[144:145], v[92:93]
	v_sub_f32_e32 v146, v146, v180
	v_cndmask_b32_e32 v144, v217, v144, vcc
	v_pk_mul_f32 v[146:147], v[180:181], v[146:147] op_sel:[1,0]
	v_cndmask_b32_e32 v145, v217, v145, vcc
	v_bfe_u32 v164, v144, 16, 1
	v_pk_fma_f32 v[146:147], v[90:91], v[146:147], v[94:95]
	v_add3_u32 v144, v144, v164, s68
	v_bfe_u32 v164, v145, 16, 1
	v_cndmask_b32_e32 v146, v217, v146, vcc
	v_lshrrev_b32_e32 v144, 16, v144
	v_add3_u32 v145, v145, v164, s68
	v_cndmask_b32_e32 v147, v217, v147, vcc
	v_and_or_b32 v144, v145, s65, v144
	v_sub_f32_e32 v133, v133, v180
	v_sub_f32_e32 v132, v132, v180
	v_pk_mul_f32 v[132:133], v[180:181], v[132:133] op_sel:[1,0]
	v_cvt_pk_bf16_f32 v145, v146, v147
	v_lshl_add_u64 v[146:147], s[14:15], 0, v[178:179]
	s_waitcnt vmcnt(4)
	v_pk_fma_f32 v[132:133], v[76:77], v[132:133], v[80:81]
	v_lshl_add_u64 v[146:147], v[146:147], 0, v[176:177]
	v_sub_f32_e32 v135, v135, v180
	v_sub_f32_e32 v134, v134, v180
	v_cndmask_b32_e32 v132, v217, v132, vcc
	global_store_dwordx2 v[146:147], v[144:145], off
	v_pk_mul_f32 v[134:135], v[180:181], v[134:135] op_sel:[1,0]
	v_cndmask_b32_e32 v133, v217, v133, vcc
	v_bfe_u32 v144, v132, 16, 1
	v_pk_fma_f32 v[134:135], v[78:79], v[134:135], v[82:83]
	v_add3_u32 v132, v132, v144, s68
	v_bfe_u32 v144, v133, 16, 1
	v_cndmask_b32_e32 v134, v217, v134, vcc
	v_lshrrev_b32_e32 v132, 16, v132
	v_add3_u32 v133, v133, v144, s68
	v_cndmask_b32_e32 v135, v217, v135, vcc
	v_and_or_b32 v132, v133, s65, v132
	v_bfe_u32 v133, v134, 16, 1
	v_sub_f32_e32 v117, v117, v180
	v_sub_f32_e32 v116, v116, v180
	v_add3_u32 v133, v134, v133, s68
	v_bfe_u32 v134, v135, 16, 1
	v_pk_mul_f32 v[116:117], v[180:181], v[116:117] op_sel:[1,0]
	v_lshrrev_b32_e32 v133, 16, v133
	v_add3_u32 v134, v135, v134, s68
	s_waitcnt vmcnt(2)
	v_pk_fma_f32 v[116:117], v[52:53], v[116:117], v[56:57]
	v_and_or_b32 v133, v134, s65, v133
	v_sub_f32_e32 v119, v119, v180
	v_sub_f32_e32 v118, v118, v180
	v_cndmask_b32_e32 v116, v217, v116, vcc
	global_store_dwordx2 v[146:147], v[132:133], off offset:32
	v_pk_mul_f32 v[118:119], v[180:181], v[118:119] op_sel:[1,0]
	v_cndmask_b32_e32 v117, v217, v117, vcc
	v_bfe_u32 v132, v116, 16, 1
	v_pk_fma_f32 v[118:119], v[54:55], v[118:119], v[58:59]
	v_add3_u32 v116, v116, v132, s68
	v_bfe_u32 v132, v117, 16, 1
	v_cndmask_b32_e32 v118, v217, v118, vcc
	v_lshrrev_b32_e32 v116, 16, v116
	v_add3_u32 v117, v117, v132, s68
	v_cndmask_b32_e32 v119, v217, v119, vcc
	v_and_or_b32 v116, v117, s65, v116
	v_sub_f32_e32 v101, v101, v180
	v_sub_f32_e32 v100, v100, v180
	v_pk_mul_f32 v[100:101], v[180:181], v[100:101] op_sel:[1,0]
	s_waitcnt vmcnt(2)
	v_pk_fma_f32 v[100:101], v[20:21], v[100:101], v[32:33]
	v_cvt_pk_bf16_f32 v117, v118, v119
	v_sub_f32_e32 v103, v103, v180
	v_sub_f32_e32 v102, v102, v180
	v_cndmask_b32_e32 v100, v217, v100, vcc
	global_store_dwordx2 v[146:147], v[116:117], off offset:256
	v_pk_mul_f32 v[102:103], v[180:181], v[102:103] op_sel:[1,0]
	v_cndmask_b32_e32 v101, v217, v101, vcc
	v_pk_fma_f32 v[102:103], v[22:23], v[102:103], v[34:35]
	v_cndmask_b32_e32 v102, v217, v102, vcc
	v_cndmask_b32_e32 v103, v217, v103, vcc
	v_cvt_pk_bf16_f32 v100, v100, v101
	v_cvt_pk_bf16_f32 v101, v102, v103
	s_waitcnt lgkmcnt(2)
	v_sub_f32_e32 v103, v149, v182
	v_sub_f32_e32 v102, v148, v182
	v_pk_mul_f32 v[102:103], v[182:183], v[102:103] op_sel:[1,0]
	v_sub_f32_e32 v117, v151, v182
	v_pk_fma_f32 v[102:103], v[88:89], v[102:103], v[92:93]
	v_sub_f32_e32 v116, v150, v182
	v_cndmask_b32_e32 v102, v217, v102, vcc
	v_pk_mul_f32 v[116:117], v[182:183], v[116:117] op_sel:[1,0]
	v_cndmask_b32_e32 v103, v217, v103, vcc
	v_pk_fma_f32 v[116:117], v[90:91], v[116:117], v[94:95]
	global_store_dwordx2 v[146:147], v[100:101], off offset:288
	v_add_u32_e32 v100, s31, v196
	v_cndmask_b32_e32 v116, v217, v116, vcc
	v_ashrrev_i32_e32 v101, 31, v100
	v_cndmask_b32_e32 v117, v217, v117, vcc
	v_cvt_pk_bf16_f32 v102, v102, v103
	v_lshlrev_b64 v[100:101], 11, v[100:101]
	v_lshl_add_u64 v[100:101], s[14:15], 0, v[100:101]
	v_cvt_pk_bf16_f32 v103, v116, v117
	v_lshl_add_u64 v[100:101], v[100:101], 0, v[176:177]
	global_store_dwordx2 v[100:101], v[102:103], off
	v_sub_f32_e32 v103, v137, v182
	v_sub_f32_e32 v102, v136, v182
	v_pk_mul_f32 v[102:103], v[182:183], v[102:103] op_sel:[1,0]
	v_sub_f32_e32 v117, v139, v182
	v_pk_fma_f32 v[102:103], v[76:77], v[102:103], v[80:81]
	v_sub_f32_e32 v116, v138, v182
	v_cndmask_b32_e32 v102, v217, v102, vcc
	v_pk_mul_f32 v[116:117], v[182:183], v[116:117] op_sel:[1,0]
	v_cndmask_b32_e32 v103, v217, v103, vcc
	v_pk_fma_f32 v[116:117], v[78:79], v[116:117], v[82:83]
	v_cndmask_b32_e32 v116, v217, v116, vcc
	v_cndmask_b32_e32 v117, v217, v117, vcc
	v_cvt_pk_bf16_f32 v102, v102, v103
	v_cvt_pk_bf16_f32 v103, v116, v117
	global_store_dwordx2 v[100:101], v[102:103], off offset:32
	v_sub_f32_e32 v103, v121, v182
	v_sub_f32_e32 v102, v120, v182
	v_pk_mul_f32 v[102:103], v[182:183], v[102:103] op_sel:[1,0]
	v_sub_f32_e32 v117, v123, v182
	v_pk_fma_f32 v[102:103], v[52:53], v[102:103], v[56:57]
	v_sub_f32_e32 v116, v122, v182
	v_cndmask_b32_e32 v102, v217, v102, vcc
	v_pk_mul_f32 v[116:117], v[182:183], v[116:117] op_sel:[1,0]
	v_cndmask_b32_e32 v103, v217, v103, vcc
	v_bfe_u32 v118, v102, 16, 1
	v_pk_fma_f32 v[116:117], v[54:55], v[116:117], v[58:59]
	v_add3_u32 v102, v102, v118, s68
	v_bfe_u32 v118, v103, 16, 1
	v_cndmask_b32_e32 v116, v217, v116, vcc
	v_lshrrev_b32_e32 v102, 16, v102
	v_add3_u32 v103, v103, v118, s68
	v_cndmask_b32_e32 v117, v217, v117, vcc
	v_and_or_b32 v102, v103, s65, v102
	v_bfe_u32 v103, v116, 16, 1
	v_add3_u32 v103, v116, v103, s68
	v_bfe_u32 v116, v117, 16, 1
	v_lshrrev_b32_e32 v103, 16, v103
	v_add3_u32 v116, v117, v116, s68
	v_and_or_b32 v103, v116, s65, v103
	global_store_dwordx2 v[100:101], v[102:103], off offset:256
	v_sub_f32_e32 v103, v105, v182
	v_sub_f32_e32 v102, v104, v182
	v_pk_mul_f32 v[102:103], v[182:183], v[102:103] op_sel:[1,0]
	v_sub_f32_e32 v105, v107, v182
	v_pk_fma_f32 v[102:103], v[20:21], v[102:103], v[32:33]
	v_sub_f32_e32 v104, v106, v182
	v_cndmask_b32_e32 v102, v217, v102, vcc
	v_pk_mul_f32 v[104:105], v[182:183], v[104:105] op_sel:[1,0]
	v_cndmask_b32_e32 v103, v217, v103, vcc
	v_pk_fma_f32 v[104:105], v[22:23], v[104:105], v[34:35]
	v_cndmask_b32_e32 v104, v217, v104, vcc
	v_cndmask_b32_e32 v105, v217, v105, vcc
	v_cvt_pk_bf16_f32 v102, v102, v103
	v_cvt_pk_bf16_f32 v103, v104, v105
	global_store_dwordx2 v[100:101], v[102:103], off offset:288
	s_waitcnt lgkmcnt(1)
; __device__ __forceinline__ unsigned pk2(float lo, float hi) { return f2bf(lo) | (f2bf(hi) << 16); }
;     __device__ __forceinline__ void fused(f32x4 (&acc)[2][2][4][2], const pg8::Unit& u, int wr, int wc, int fr, int fq, LAS unsigned char* lds, int wid, int lane) const {
;     ...
;             for (int m = 0; m < 4; ++m) { const int r = ai * 128 + wr * 64 + m * 16 + fr; const f32x2v sr = S[r]; const size_t off = (size_t)(u.pm * 256 + r) * DM + col0;
; #pragma unroll
;                 for (int bj = 0; bj < 2; ++bj)
; #pragma unroll
;                     for (int n = 0; n < 2; ++n) { f32x4 o = (acc[ai][bj][m][n] - sr.x) * sr.y * gg[bj][n] + bb[bj][n];
;                         if (bad) o = (f32x4){qnan, qnan, qnan, qnan};
;                         if (outf) *(f32x4*)(outf + off + bj * 128 + n * 16) = o;
;                         if (outb) { u32x2 w; w.x = pk2(o[0], o[1]); w.y = pk2(o[2], o[3]); *(u32x2*)(outb + off + bj * 128 + n * 16) = w; } } }
	v_sub_f32_e32 v103, v157, v184
	v_sub_f32_e32 v102, v156, v184
	v_pk_mul_f32 v[102:103], v[184:185], v[102:103] op_sel:[1,0]
	v_sub_f32_e32 v105, v159, v184
	v_pk_fma_f32 v[102:103], v[88:89], v[102:103], v[92:93]
	v_sub_f32_e32 v104, v158, v184
	v_cndmask_b32_e32 v102, v217, v102, vcc
	v_pk_mul_f32 v[104:105], v[184:185], v[104:105] op_sel:[1,0]
	v_cndmask_b32_e32 v103, v217, v103, vcc
	v_pk_fma_f32 v[104:105], v[90:91], v[104:105], v[94:95]
	v_add_u32_e32 v100, s31, v198
	v_cndmask_b32_e32 v104, v217, v104, vcc
	v_ashrrev_i32_e32 v101, 31, v100
	v_cndmask_b32_e32 v105, v217, v105, vcc
	v_cvt_pk_bf16_f32 v102, v102, v103
	v_lshlrev_b64 v[100:101], 11, v[100:101]
	v_lshl_add_u64 v[100:101], s[14:15], 0, v[100:101]
	v_cvt_pk_bf16_f32 v103, v104, v105
	v_lshl_add_u64 v[100:101], v[100:101], 0, v[176:177]
	global_store_dwordx2 v[100:101], v[102:103], off
	v_sub_f32_e32 v103, v141, v184
	v_sub_f32_e32 v102, v140, v184
	v_pk_mul_f32 v[102:103], v[184:185], v[102:103] op_sel:[1,0]
	v_sub_f32_e32 v105, v143, v184
	v_pk_fma_f32 v[102:103], v[76:77], v[102:103], v[80:81]
	v_sub_f32_e32 v104, v142, v184
	v_cndmask_b32_e32 v102, v217, v102, vcc
	v_pk_mul_f32 v[104:105], v[184:185], v[104:105] op_sel:[1,0]
	v_cndmask_b32_e32 v103, v217, v103, vcc
	v_pk_fma_f32 v[104:105], v[78:79], v[104:105], v[82:83]
	v_cndmask_b32_e32 v104, v217, v104, vcc
	v_cndmask_b32_e32 v105, v217, v105, vcc
	v_cvt_pk_bf16_f32 v102, v102, v103
	v_cvt_pk_bf16_f32 v103, v104, v105
	global_store_dwordx2 v[100:101], v[102:103], off offset:32
	v_sub_f32_e32 v103, v125, v184
	v_sub_f32_e32 v102, v124, v184
	v_pk_mul_f32 v[102:103], v[184:185], v[102:103] op_sel:[1,0]
	v_sub_f32_e32 v105, v127, v184
	v_pk_fma_f32 v[102:103], v[52:53], v[102:103], v[56:57]
	v_sub_f32_e32 v104, v126, v184
	v_cndmask_b32_e32 v102, v217, v102, vcc
	v_pk_mul_f32 v[104:105], v[184:185], v[104:105] op_sel:[1,0]
	v_cndmask_b32_e32 v103, v217, v103, vcc
	v_pk_fma_f32 v[104:105], v[54:55], v[104:105], v[58:59]
	v_cndmask_b32_e32 v104, v217, v104, vcc
	v_cndmask_b32_e32 v105, v217, v105, vcc
	v_cvt_pk_bf16_f32 v102, v102, v103
	v_cvt_pk_bf16_f32 v103, v104, v105
	global_store_dwordx2 v[100:101], v[102:103], off offset:256
	v_sub_f32_e32 v103, v109, v184
	v_sub_f32_e32 v102, v108, v184
	v_pk_mul_f32 v[102:103], v[184:185], v[102:103] op_sel:[1,0]
	v_sub_f32_e32 v105, v111, v184
	v_pk_fma_f32 v[102:103], v[20:21], v[102:103], v[32:33]
	v_sub_f32_e32 v104, v110, v184
	v_cndmask_b32_e32 v102, v217, v102, vcc
	v_pk_mul_f32 v[104:105], v[184:185], v[104:105] op_sel:[1,0]
	v_cndmask_b32_e32 v103, v217, v103, vcc
	v_pk_fma_f32 v[104:105], v[22:23], v[104:105], v[34:35]
	v_cndmask_b32_e32 v104, v217, v104, vcc
	v_cndmask_b32_e32 v105, v217, v105, vcc
	v_cvt_pk_bf16_f32 v102, v102, v103
	v_cvt_pk_bf16_f32 v103, v104, v105
	global_store_dwordx2 v[100:101], v[102:103], off offset:288
	s_waitcnt lgkmcnt(0)
	v_sub_f32_e32 v103, v153, v186
	v_sub_f32_e32 v102, v152, v186
	v_pk_mul_f32 v[102:103], v[186:187], v[102:103] op_sel:[1,0]
	v_sub_f32_e32 v105, v155, v186
	v_pk_fma_f32 v[102:103], v[88:89], v[102:103], v[92:93]
	v_sub_f32_e32 v104, v154, v186
	v_cndmask_b32_e32 v102, v217, v102, vcc
	v_pk_mul_f32 v[104:105], v[186:187], v[104:105] op_sel:[1,0]
	v_cndmask_b32_e32 v103, v217, v103, vcc
	v_pk_fma_f32 v[104:105], v[90:91], v[104:105], v[94:95]
	v_add_u32_e32 v100, s31, v200
	v_cndmask_b32_e32 v104, v217, v104, vcc
	v_ashrrev_i32_e32 v101, 31, v100
	v_cndmask_b32_e32 v105, v217, v105, vcc
	v_cvt_pk_bf16_f32 v102, v102, v103
	v_lshlrev_b64 v[100:101], 11, v[100:101]
	v_lshl_add_u64 v[100:101], s[14:15], 0, v[100:101]
	v_cvt_pk_bf16_f32 v103, v104, v105
	v_lshl_add_u64 v[100:101], v[100:101], 0, v[176:177]
	global_store_dwordx2 v[100:101], v[102:103], off
	v_sub_f32_e32 v103, v129, v186
	v_sub_f32_e32 v102, v128, v186
	v_pk_mul_f32 v[102:103], v[186:187], v[102:103] op_sel:[1,0]
	v_sub_f32_e32 v105, v131, v186
	v_pk_fma_f32 v[102:103], v[76:77], v[102:103], v[80:81]
	v_sub_f32_e32 v104, v130, v186
	v_cndmask_b32_e32 v102, v217, v102, vcc
	v_pk_mul_f32 v[104:105], v[186:187], v[104:105] op_sel:[1,0]
	v_cndmask_b32_e32 v103, v217, v103, vcc
	v_pk_fma_f32 v[104:105], v[78:79], v[104:105], v[82:83]
	v_cndmask_b32_e32 v104, v217, v104, vcc
	v_cndmask_b32_e32 v105, v217, v105, vcc
	v_cvt_pk_bf16_f32 v102, v102, v103
	v_cvt_pk_bf16_f32 v103, v104, v105
	global_store_dwordx2 v[100:101], v[102:103], off offset:32
	v_sub_f32_e32 v103, v113, v186
	v_sub_f32_e32 v102, v112, v186
	v_pk_mul_f32 v[102:103], v[186:187], v[102:103] op_sel:[1,0]
	v_sub_f32_e32 v105, v115, v186
	v_pk_fma_f32 v[102:103], v[52:53], v[102:103], v[56:57]
	v_sub_f32_e32 v104, v114, v186
	v_cndmask_b32_e32 v102, v217, v102, vcc
	v_pk_mul_f32 v[104:105], v[186:187], v[104:105] op_sel:[1,0]
	v_cndmask_b32_e32 v103, v217, v103, vcc
	v_pk_fma_f32 v[104:105], v[54:55], v[104:105], v[58:59]
	v_cndmask_b32_e32 v104, v217, v104, vcc
	v_cndmask_b32_e32 v105, v217, v105, vcc
	v_cvt_pk_bf16_f32 v102, v102, v103
	v_sub_f32_e32 v97, v97, v186
	v_sub_f32_e32 v96, v96, v186
	v_pk_mul_f32 v[96:97], v[186:187], v[96:97] op_sel:[1,0]
	v_pk_fma_f32 v[96:97], v[20:21], v[96:97], v[32:33]
	v_cvt_pk_bf16_f32 v103, v104, v105
	v_sub_f32_e32 v99, v99, v186
	v_sub_f32_e32 v98, v98, v186
	v_cndmask_b32_e32 v96, v217, v96, vcc
	global_store_dwordx2 v[100:101], v[102:103], off offset:256
	v_pk_mul_f32 v[98:99], v[186:187], v[98:99] op_sel:[1,0]
	v_cndmask_b32_e32 v97, v217, v97, vcc
	v_pk_fma_f32 v[98:99], v[22:23], v[98:99], v[34:35]
	v_cndmask_b32_e32 v98, v217, v98, vcc
	v_cndmask_b32_e32 v99, v217, v99, vcc
	v_cvt_pk_bf16_f32 v96, v96, v97
	v_cvt_pk_bf16_f32 v97, v98, v99
	global_store_dwordx2 v[100:101], v[96:97], off offset:288
	ds_read_b64 v[96:97], v203
	v_add_u32_e32 v104, s31, v202
	v_ashrrev_i32_e32 v105, 31, v104
	ds_read_b64 v[98:99], v205
	ds_read_b64 v[100:101], v207
	ds_read_b64 v[102:103], v209
	s_waitcnt lgkmcnt(3)
; __device__ __forceinline__ unsigned pk2(float lo, float hi) { return f2bf(lo) | (f2bf(hi) << 16); }
;     __device__ __forceinline__ void fused(f32x4 (&acc)[2][2][4][2], const pg8::Unit& u, int wr, int wc, int fr, int fq, LAS unsigned char* lds, int wid, int lane) const {
;     ...
;             for (int m = 0; m < 4; ++m) { const int r = ai * 128 + wr * 64 + m * 16 + fr; const f32x2v sr = S[r]; const size_t off = (size_t)(u.pm * 256 + r) * DM + col0;
; #pragma unroll
;                 for (int bj = 0; bj < 2; ++bj)
; #pragma unroll
;                     for (int n = 0; n < 2; ++n) { f32x4 o = (acc[ai][bj][m][n] - sr.x) * sr.y * gg[bj][n] + bb[bj][n];
;                         if (bad) o = (f32x4){qnan, qnan, qnan, qnan};
;                         if (outf) *(f32x4*)(outf + off + bj * 128 + n * 16) = o;
;                         if (outb) { u32x2 w; w.x = pk2(o[0], o[1]); w.y = pk2(o[2], o[3]); *(u32x2*)(outb + off + bj * 128 + n * 16) = w; } } }
	v_sub_f32_e32 v61, v61, v96
	v_sub_f32_e32 v60, v60, v96
	v_pk_mul_f32 v[60:61], v[96:97], v[60:61] op_sel:[1,0]
	v_sub_f32_e32 v63, v63, v96
	v_pk_fma_f32 v[60:61], v[88:89], v[60:61], v[92:93]
	v_sub_f32_e32 v62, v62, v96
	v_cndmask_b32_e32 v60, v217, v60, vcc
	v_pk_mul_f32 v[62:63], v[96:97], v[62:63] op_sel:[1,0]
	v_cndmask_b32_e32 v61, v217, v61, vcc
	v_bfe_u32 v106, v60, 16, 1
	v_pk_fma_f32 v[62:63], v[90:91], v[62:63], v[94:95]
	v_add3_u32 v60, v60, v106, s68
	v_bfe_u32 v106, v61, 16, 1
	v_cndmask_b32_e32 v62, v217, v62, vcc
	v_lshrrev_b32_e32 v60, 16, v60
	v_add3_u32 v61, v61, v106, s68
	v_cndmask_b32_e32 v63, v217, v63, vcc
	v_and_or_b32 v60, v61, s65, v60
	v_sub_f32_e32 v37, v37, v96
	v_sub_f32_e32 v36, v36, v96
	v_cvt_pk_bf16_f32 v61, v62, v63
	v_lshlrev_b64 v[62:63], 11, v[104:105]
	v_pk_mul_f32 v[36:37], v[96:97], v[36:37] op_sel:[1,0]
	v_lshl_add_u64 v[62:63], s[14:15], 0, v[62:63]
	v_pk_fma_f32 v[36:37], v[76:77], v[36:37], v[80:81]
	v_lshl_add_u64 v[62:63], v[62:63], 0, v[176:177]
	v_sub_f32_e32 v39, v39, v96
	v_sub_f32_e32 v38, v38, v96
	v_cndmask_b32_e32 v36, v217, v36, vcc
	global_store_dwordx2 v[62:63], v[60:61], off
	v_pk_mul_f32 v[38:39], v[96:97], v[38:39] op_sel:[1,0]
	v_cndmask_b32_e32 v37, v217, v37, vcc
	v_bfe_u32 v60, v36, 16, 1
	v_pk_fma_f32 v[38:39], v[78:79], v[38:39], v[82:83]
	v_add3_u32 v36, v36, v60, s68
	v_bfe_u32 v60, v37, 16, 1
	v_cndmask_b32_e32 v38, v217, v38, vcc
	v_lshrrev_b32_e32 v36, 16, v36
	v_add3_u32 v37, v37, v60, s68
	v_cndmask_b32_e32 v39, v217, v39, vcc
	v_and_or_b32 v36, v37, s65, v36
	v_bfe_u32 v37, v38, 16, 1
	v_sub_f32_e32 v13, v13, v96
	v_sub_f32_e32 v12, v12, v96
	v_add3_u32 v37, v38, v37, s68
	v_bfe_u32 v38, v39, 16, 1
	v_pk_mul_f32 v[12:13], v[96:97], v[12:13] op_sel:[1,0]
	v_lshrrev_b32_e32 v37, 16, v37
	v_add3_u32 v38, v39, v38, s68
	v_pk_fma_f32 v[12:13], v[52:53], v[12:13], v[56:57]
	v_and_or_b32 v37, v38, s65, v37
	v_sub_f32_e32 v15, v15, v96
	v_sub_f32_e32 v14, v14, v96
	v_cndmask_b32_e32 v12, v217, v12, vcc
	global_store_dwordx2 v[62:63], v[36:37], off offset:32
	v_pk_mul_f32 v[14:15], v[96:97], v[14:15] op_sel:[1,0]
	v_cndmask_b32_e32 v13, v217, v13, vcc
	v_bfe_u32 v36, v12, 16, 1
	v_pk_fma_f32 v[14:15], v[54:55], v[14:15], v[58:59]
	v_add3_u32 v12, v12, v36, s68
	v_bfe_u32 v36, v13, 16, 1
	v_cndmask_b32_e32 v14, v217, v14, vcc
	v_lshrrev_b32_e32 v12, 16, v12
	v_add3_u32 v13, v13, v36, s68
	v_cndmask_b32_e32 v15, v217, v15, vcc
	v_and_or_b32 v12, v13, s65, v12
	v_sub_f32_e32 v1, v1, v96
	v_sub_f32_e32 v0, v0, v96
	v_pk_mul_f32 v[0:1], v[96:97], v[0:1] op_sel:[1,0]
	v_pk_fma_f32 v[0:1], v[20:21], v[0:1], v[32:33]
	v_cvt_pk_bf16_f32 v13, v14, v15
	v_sub_f32_e32 v3, v3, v96
	v_sub_f32_e32 v2, v2, v96
	v_cndmask_b32_e32 v0, v217, v0, vcc
	global_store_dwordx2 v[62:63], v[12:13], off offset:256
	v_pk_mul_f32 v[2:3], v[96:97], v[2:3] op_sel:[1,0]
	v_cndmask_b32_e32 v1, v217, v1, vcc
	v_pk_fma_f32 v[2:3], v[22:23], v[2:3], v[34:35]
	v_cndmask_b32_e32 v2, v217, v2, vcc
	v_cndmask_b32_e32 v3, v217, v3, vcc
	v_cvt_pk_bf16_f32 v0, v0, v1
	v_cvt_pk_bf16_f32 v1, v2, v3
	s_waitcnt lgkmcnt(2)
	v_sub_f32_e32 v3, v65, v98
	v_sub_f32_e32 v2, v64, v98
	v_pk_mul_f32 v[2:3], v[98:99], v[2:3] op_sel:[1,0]
	v_sub_f32_e32 v13, v67, v98
	v_pk_fma_f32 v[2:3], v[88:89], v[2:3], v[92:93]
	v_sub_f32_e32 v12, v66, v98
	v_cndmask_b32_e32 v2, v217, v2, vcc
	v_pk_mul_f32 v[12:13], v[98:99], v[12:13] op_sel:[1,0]
	v_cndmask_b32_e32 v3, v217, v3, vcc
	v_pk_fma_f32 v[12:13], v[90:91], v[12:13], v[94:95]
	global_store_dwordx2 v[62:63], v[0:1], off offset:288
	v_add_u32_e32 v0, s31, v204
	v_cndmask_b32_e32 v12, v217, v12, vcc
	v_ashrrev_i32_e32 v1, 31, v0
	v_cndmask_b32_e32 v13, v217, v13, vcc
	v_cvt_pk_bf16_f32 v2, v2, v3
	v_lshlrev_b64 v[0:1], 11, v[0:1]
	v_lshl_add_u64 v[0:1], s[14:15], 0, v[0:1]
	v_cvt_pk_bf16_f32 v3, v12, v13
	v_lshl_add_u64 v[0:1], v[0:1], 0, v[176:177]
	global_store_dwordx2 v[0:1], v[2:3], off
	v_sub_f32_e32 v3, v41, v98
	v_sub_f32_e32 v2, v40, v98
	v_pk_mul_f32 v[2:3], v[98:99], v[2:3] op_sel:[1,0]
	v_sub_f32_e32 v13, v43, v98
	v_pk_fma_f32 v[2:3], v[76:77], v[2:3], v[80:81]
	v_sub_f32_e32 v12, v42, v98
	v_cndmask_b32_e32 v2, v217, v2, vcc
	v_pk_mul_f32 v[12:13], v[98:99], v[12:13] op_sel:[1,0]
	v_cndmask_b32_e32 v3, v217, v3, vcc
	v_pk_fma_f32 v[12:13], v[78:79], v[12:13], v[82:83]
	v_cndmask_b32_e32 v12, v217, v12, vcc
	v_cndmask_b32_e32 v13, v217, v13, vcc
	v_cvt_pk_bf16_f32 v2, v2, v3
	v_cvt_pk_bf16_f32 v3, v12, v13
	global_store_dwordx2 v[0:1], v[2:3], off offset:32
	v_sub_f32_e32 v3, v25, v98
	v_sub_f32_e32 v2, v24, v98
	v_pk_mul_f32 v[2:3], v[98:99], v[2:3] op_sel:[1,0]
	v_sub_f32_e32 v13, v27, v98
	v_pk_fma_f32 v[2:3], v[52:53], v[2:3], v[56:57]
	v_sub_f32_e32 v12, v26, v98
	v_cndmask_b32_e32 v2, v217, v2, vcc
	v_pk_mul_f32 v[12:13], v[98:99], v[12:13] op_sel:[1,0]
	v_cndmask_b32_e32 v3, v217, v3, vcc
	v_pk_fma_f32 v[12:13], v[54:55], v[12:13], v[58:59]
	v_cndmask_b32_e32 v12, v217, v12, vcc
	v_cndmask_b32_e32 v13, v217, v13, vcc
	v_cvt_pk_bf16_f32 v2, v2, v3
	v_cvt_pk_bf16_f32 v3, v12, v13
	global_store_dwordx2 v[0:1], v[2:3], off offset:256
	v_sub_f32_e32 v3, v5, v98
	v_sub_f32_e32 v2, v4, v98
	v_pk_mul_f32 v[2:3], v[98:99], v[2:3] op_sel:[1,0]
	v_sub_f32_e32 v5, v7, v98
	v_pk_fma_f32 v[2:3], v[20:21], v[2:3], v[32:33]
	v_sub_f32_e32 v4, v6, v98
	v_cndmask_b32_e32 v2, v217, v2, vcc
	v_pk_mul_f32 v[4:5], v[98:99], v[4:5] op_sel:[1,0]
	v_cndmask_b32_e32 v3, v217, v3, vcc
	v_pk_fma_f32 v[4:5], v[22:23], v[4:5], v[34:35]
	v_cndmask_b32_e32 v4, v217, v4, vcc
	v_cndmask_b32_e32 v5, v217, v5, vcc
	v_cvt_pk_bf16_f32 v2, v2, v3
	v_cvt_pk_bf16_f32 v3, v4, v5
	global_store_dwordx2 v[0:1], v[2:3], off offset:288
	s_waitcnt lgkmcnt(1)
; __device__ __forceinline__ unsigned pk2(float lo, float hi) { return f2bf(lo) | (f2bf(hi) << 16); }
;     __device__ __forceinline__ void fused(f32x4 (&acc)[2][2][4][2], const pg8::Unit& u, int wr, int wc, int fr, int fq, LAS unsigned char* lds, int wid, int lane) const {
;     ...
;             for (int m = 0; m < 4; ++m) { const int r = ai * 128 + wr * 64 + m * 16 + fr; const f32x2v sr = S[r]; const size_t off = (size_t)(u.pm * 256 + r) * DM + col0;
; #pragma unroll
;                 for (int bj = 0; bj < 2; ++bj)
; #pragma unroll
;                     for (int n = 0; n < 2; ++n) { f32x4 o = (acc[ai][bj][m][n] - sr.x) * sr.y * gg[bj][n] + bb[bj][n];
;                         if (bad) o = (f32x4){qnan, qnan, qnan, qnan};
;                         if (outf) *(f32x4*)(outf + off + bj * 128 + n * 16) = o;
;                         if (outb) { u32x2 w; w.x = pk2(o[0], o[1]); w.y = pk2(o[2], o[3]); *(u32x2*)(outb + off + bj * 128 + n * 16) = w; } } }
	v_sub_f32_e32 v3, v69, v100
	v_sub_f32_e32 v2, v68, v100
	v_pk_mul_f32 v[2:3], v[100:101], v[2:3] op_sel:[1,0]
	v_sub_f32_e32 v5, v71, v100
	v_pk_fma_f32 v[2:3], v[88:89], v[2:3], v[92:93]
	v_sub_f32_e32 v4, v70, v100
	v_cndmask_b32_e32 v2, v217, v2, vcc
	v_pk_mul_f32 v[4:5], v[100:101], v[4:5] op_sel:[1,0]
	v_cndmask_b32_e32 v3, v217, v3, vcc
	v_pk_fma_f32 v[4:5], v[90:91], v[4:5], v[94:95]
	v_add_u32_e32 v0, s31, v206
	v_cndmask_b32_e32 v4, v217, v4, vcc
	v_ashrrev_i32_e32 v1, 31, v0
	v_cndmask_b32_e32 v5, v217, v5, vcc
	v_cvt_pk_bf16_f32 v2, v2, v3
	v_lshlrev_b64 v[0:1], 11, v[0:1]
	v_lshl_add_u64 v[0:1], s[14:15], 0, v[0:1]
	v_cvt_pk_bf16_f32 v3, v4, v5
	v_lshl_add_u64 v[0:1], v[0:1], 0, v[176:177]
	global_store_dwordx2 v[0:1], v[2:3], off
	v_sub_f32_e32 v3, v45, v100
	v_sub_f32_e32 v2, v44, v100
	v_pk_mul_f32 v[2:3], v[100:101], v[2:3] op_sel:[1,0]
	v_sub_f32_e32 v5, v47, v100
	v_pk_fma_f32 v[2:3], v[76:77], v[2:3], v[80:81]
	v_sub_f32_e32 v4, v46, v100
	v_cndmask_b32_e32 v2, v217, v2, vcc
	v_pk_mul_f32 v[4:5], v[100:101], v[4:5] op_sel:[1,0]
	v_cndmask_b32_e32 v3, v217, v3, vcc
	v_pk_fma_f32 v[4:5], v[78:79], v[4:5], v[82:83]
	v_cndmask_b32_e32 v4, v217, v4, vcc
	v_cndmask_b32_e32 v5, v217, v5, vcc
	v_cvt_pk_bf16_f32 v2, v2, v3
	v_cvt_pk_bf16_f32 v3, v4, v5
	global_store_dwordx2 v[0:1], v[2:3], off offset:32
	v_sub_f32_e32 v3, v29, v100
	v_sub_f32_e32 v2, v28, v100
	v_pk_mul_f32 v[2:3], v[100:101], v[2:3] op_sel:[1,0]
	v_sub_f32_e32 v5, v31, v100
	v_pk_fma_f32 v[2:3], v[52:53], v[2:3], v[56:57]
	v_sub_f32_e32 v4, v30, v100
	v_cndmask_b32_e32 v2, v217, v2, vcc
	v_pk_mul_f32 v[4:5], v[100:101], v[4:5] op_sel:[1,0]
	v_cndmask_b32_e32 v3, v217, v3, vcc
	v_pk_fma_f32 v[4:5], v[54:55], v[4:5], v[58:59]
	v_cndmask_b32_e32 v4, v217, v4, vcc
	v_cndmask_b32_e32 v5, v217, v5, vcc
	v_cvt_pk_bf16_f32 v2, v2, v3
	v_cvt_pk_bf16_f32 v3, v4, v5
	global_store_dwordx2 v[0:1], v[2:3], off offset:256
	v_sub_f32_e32 v3, v9, v100
	v_sub_f32_e32 v2, v8, v100
	v_pk_mul_f32 v[2:3], v[100:101], v[2:3] op_sel:[1,0]
	v_sub_f32_e32 v5, v11, v100
	v_pk_fma_f32 v[2:3], v[20:21], v[2:3], v[32:33]
	v_sub_f32_e32 v4, v10, v100
	v_cndmask_b32_e32 v2, v217, v2, vcc
	v_pk_mul_f32 v[4:5], v[100:101], v[4:5] op_sel:[1,0]
	v_cndmask_b32_e32 v3, v217, v3, vcc
	v_pk_fma_f32 v[4:5], v[22:23], v[4:5], v[34:35]
	v_cndmask_b32_e32 v4, v217, v4, vcc
	v_cndmask_b32_e32 v5, v217, v5, vcc
	v_cvt_pk_bf16_f32 v2, v2, v3
	v_cvt_pk_bf16_f32 v3, v4, v5
	global_store_dwordx2 v[0:1], v[2:3], off offset:288
	s_waitcnt lgkmcnt(0)
	v_sub_f32_e32 v3, v85, v102
	v_sub_f32_e32 v2, v84, v102
	v_pk_mul_f32 v[2:3], v[102:103], v[2:3] op_sel:[1,0]
	v_sub_f32_e32 v5, v87, v102
	v_pk_fma_f32 v[2:3], v[88:89], v[2:3], v[92:93]
	v_sub_f32_e32 v4, v86, v102
	v_cndmask_b32_e32 v2, v217, v2, vcc
	v_pk_mul_f32 v[4:5], v[102:103], v[4:5] op_sel:[1,0]
	v_cndmask_b32_e32 v3, v217, v3, vcc
	v_pk_fma_f32 v[4:5], v[90:91], v[4:5], v[94:95]
	v_add_u32_e32 v0, s31, v208
	v_cndmask_b32_e32 v4, v217, v4, vcc
	v_ashrrev_i32_e32 v1, 31, v0
	v_cndmask_b32_e32 v5, v217, v5, vcc
	v_cvt_pk_bf16_f32 v2, v2, v3
	v_lshlrev_b64 v[0:1], 11, v[0:1]
	v_lshl_add_u64 v[0:1], s[14:15], 0, v[0:1]
	v_cvt_pk_bf16_f32 v3, v4, v5
	v_lshl_add_u64 v[0:1], v[0:1], 0, v[176:177]
	global_store_dwordx2 v[0:1], v[2:3], off
	v_sub_f32_e32 v3, v73, v102
	v_sub_f32_e32 v2, v72, v102
	v_pk_mul_f32 v[2:3], v[102:103], v[2:3] op_sel:[1,0]
	v_sub_f32_e32 v5, v75, v102
	v_pk_fma_f32 v[2:3], v[76:77], v[2:3], v[80:81]
	v_sub_f32_e32 v4, v74, v102
	v_cndmask_b32_e32 v2, v217, v2, vcc
	v_pk_mul_f32 v[4:5], v[102:103], v[4:5] op_sel:[1,0]
	v_cndmask_b32_e32 v3, v217, v3, vcc
	v_pk_fma_f32 v[4:5], v[78:79], v[4:5], v[82:83]
	v_cndmask_b32_e32 v4, v217, v4, vcc
	v_cndmask_b32_e32 v5, v217, v5, vcc
	v_cvt_pk_bf16_f32 v2, v2, v3
	v_cvt_pk_bf16_f32 v3, v4, v5
	global_store_dwordx2 v[0:1], v[2:3], off offset:32
	v_sub_f32_e32 v3, v49, v102
	v_sub_f32_e32 v2, v48, v102
	v_pk_mul_f32 v[2:3], v[102:103], v[2:3] op_sel:[1,0]
	v_sub_f32_e32 v5, v51, v102
	v_pk_fma_f32 v[2:3], v[52:53], v[2:3], v[56:57]
	v_sub_f32_e32 v4, v50, v102
	v_cndmask_b32_e32 v2, v217, v2, vcc
	v_pk_mul_f32 v[4:5], v[102:103], v[4:5] op_sel:[1,0]
	v_cndmask_b32_e32 v3, v217, v3, vcc
	v_pk_fma_f32 v[4:5], v[54:55], v[4:5], v[58:59]
	v_cndmask_b32_e32 v4, v217, v4, vcc
	v_cndmask_b32_e32 v5, v217, v5, vcc
	v_cvt_pk_bf16_f32 v2, v2, v3
	v_cvt_pk_bf16_f32 v3, v4, v5
	global_store_dwordx2 v[0:1], v[2:3], off offset:256
	v_sub_f32_e32 v3, v17, v102
	v_sub_f32_e32 v2, v16, v102
	v_pk_mul_f32 v[2:3], v[102:103], v[2:3] op_sel:[1,0]
	v_sub_f32_e32 v5, v19, v102
	v_pk_fma_f32 v[2:3], v[20:21], v[2:3], v[32:33]
	v_sub_f32_e32 v4, v18, v102
	v_cndmask_b32_e32 v2, v217, v2, vcc
	v_pk_mul_f32 v[4:5], v[102:103], v[4:5] op_sel:[1,0]
	v_cndmask_b32_e32 v3, v217, v3, vcc
	v_pk_fma_f32 v[4:5], v[22:23], v[4:5], v[34:35]
	v_cndmask_b32_e32 v4, v217, v4, vcc
	v_cndmask_b32_e32 v5, v217, v5, vcc
	v_cvt_pk_bf16_f32 v2, v2, v3
	v_cvt_pk_bf16_f32 v3, v4, v5
	s_andn2_b64 vcc, exec, s[8:9]
	s_mov_b64 s[8:9], -1
	global_store_dwordx2 v[0:1], v[2:3], off offset:288
	s_cbranch_vccnz .LBB0_1866
	s_andn2_b64 vcc, exec, s[16:17]
	s_cbranch_vccnz .LBB0_1865
	s_barrier
	s_branch .LBB0_1865

; __device__ __forceinline__ void st8bf(bf16_t* p, f32x4 a, f32x4 b) { u32x4 w; w.x = pk2(a[0], a[1]); w.y = pk2(a[2], a[3]); w.z = pk2(b[0], b[1]); w.w = pk2(b[2], b[3]); st16(p, w); }
;     __device__ __forceinline__ void st(int pn, int row, int c, f32x4 v0, f32x4 v1) const {
;     ...
;                 const float inv = 1.f / (float)w;
;                 st8bf(DMs + (size_t)row * 1024 + col, (f32x4){s[0] * inv - x[0], s[1] * inv - x[1], s[2] * inv - x[2], s[3] * inv - x[3]}, (f32x4){s[4] * inv - x[4], s[5] * inv - x[5], s[6] * inv - x[6], s[7] * inv - x[7]});
.LBB0_1975:
	s_or_b64 exec, exec, s[8:9]
	v_cvt_f32_u32_e32 v37, s12
	v_lshlrev_b64 v[28:29], 10, v[16:17]
	v_readlane_b32 s4, v251, 0
	v_readlane_b32 s5, v251, 1
	v_div_scale_f32 v16, s[8:9], v37, v37, 1.0
	v_rcp_f32_e32 v38, v16
	v_div_scale_f32 v39, vcc, 1.0, v37, 1.0
	v_lshl_add_u64 v[28:29], v[28:29], 1, s[4:5]
	v_fma_f32 v40, -v16, v38, 1.0
	v_fmac_f32_e32 v38, v40, v38
	v_mul_f32_e32 v40, v39, v38
	v_fma_f32 v41, -v16, v40, v39
	v_fmac_f32_e32 v40, v41, v38
	v_fma_f32 v16, -v16, v40, v39
	v_div_fmas_f32 v16, v16, v38, v40
	v_div_fixup_f32 v16, v16, v37, 1.0
	v_lshl_add_u64 v[18:19], v[18:19], 1, v[28:29]
	v_mov_b32_e32 v29, v22
	v_mov_b32_e32 v39, v6
	v_mov_b32_e32 v22, v21
	v_mov_b32_e32 v6, v5
	v_mov_b32_e32 v38, v4
	v_pk_fma_f32 v[4:5], v[16:17], v[22:23], v[6:7] op_sel_hi:[0,1,1] neg_lo:[0,0,1] neg_hi:[0,0,1]
	v_mov_b32_e32 v7, v26
	v_mov_b32_e32 v21, v2
	v_mov_b32_e32 v26, v25
	v_mov_b32_e32 v2, v1
	v_mov_b32_e32 v28, v20
	v_mov_b32_e32 v6, v24
	v_mov_b32_e32 v20, v0
	v_pk_fma_f32 v[0:1], v[16:17], v[26:27], v[2:3] op_sel_hi:[0,1,1] neg_lo:[0,0,1] neg_hi:[0,0,1]
	v_pk_fma_f32 v[28:29], v[16:17], v[28:29], v[38:39] op_sel_hi:[0,1,1] neg_lo:[0,0,1] neg_hi:[0,0,1]
	v_pk_fma_f32 v[6:7], v[16:17], v[6:7], v[20:21] op_sel_hi:[0,1,1] neg_lo:[0,0,1] neg_hi:[0,0,1]
	v_cvt_pk_bf16_f32 v3, v7, v1
	v_cvt_pk_bf16_f32 v2, v6, v0
	v_cvt_pk_bf16_f32 v1, v29, v5
	v_cvt_pk_bf16_f32 v0, v28, v4
	global_store_dwordx4 v[18:19], v[0:3], off

; #define MFMA16(a, b, c) __builtin_amdgcn_mfma_f32_16x16x32_bf16((a), (b), (c), 0, 0, 0)
;     ...
;             const bf16_t* ap = A + (size_t)(mt * mt_stride + r) * lda + (size_t)pn * a_tile_off + kh * Kh + 8 * fq;
;             const bf16_t* bp = Bt + (size_t)(256 * pn + 32 * sub + 8 * (r >> 2) + (r & 3)) * ldb + kh * Kh + 8 * fq;
;             if (glu) {
; #pragma unroll 8
;                 for (int k0 = 0; k0 < Kh; k0 += 32) { const bf16x8 a = *(const bf16x8*)(ap + k0);
;                     acc[0] = MFMA16(*(const bf16x8*)(bp + k0), a, acc[0]); acc[1] = MFMA16(*(const bf16x8*)(bp + 4 * ldb + k0), a, acc[1]);
;                     acc[2] = MFMA16(*(const bf16x8*)(bp + 128 * ldb + k0), a, acc[2]); acc[3] = MFMA16(*(const bf16x8*)(bp + 132 * ldb + k0), a, acc[3]); }
;             } else {
; #pragma unroll 8
;                 for (int k0 = 0; k0 < Kh; k0 += 32) { const bf16x8 a = *(const bf16x8*)(ap + k0);
;                     acc[0] = MFMA16(*(const bf16x8*)(bp + k0), a, acc[0]); acc[1] = MFMA16(*(const bf16x8*)(bp + 4 * ldb + k0), a, acc[1]); }
.LBB0_1978:
	s_add_i32 s12, s63, s68
	s_ashr_i32 s8, s12, 31
	s_lshr_b32 s8, s8, 29
	s_add_i32 s8, s12, s8
	s_and_b32 s9, s8, -8
	s_bfe_u32 s10, s8, 0x30003
	s_sub_i32 s11, s12, s9
	s_ashr_i32 s69, s8, 6
	s_cmpk_lt_i32 s12, 0x200
	s_cselect_b64 s[8:9], -1, 0
	s_cmpk_gt_i32 s12, 0x1ff
	v_mov_b32_e32 v0, 0
	v_mov_b32_e32 v1, 0
	v_mov_b32_e32 v2, 0
	v_mov_b32_e32 v3, 0
	v_mov_b32_e32 v4, 0
	v_mov_b32_e32 v5, 0
	v_mov_b32_e32 v6, 0
	v_mov_b32_e32 v7, 0
	s_cbranch_scc1 .LBB0_1980
	v_lshl_or_b32 v0, s11, 4, v31
	v_ashrrev_i32_e32 v1, 31, v0
	s_lshl_b32 s12, s69, 8
	s_lshl_b32 s48, s10, 5
	v_lshlrev_b64 v[0:1], 11, v[0:1]
	s_or_b32 s12, s12, s48
	v_lshl_add_u64 v[54:55], v[12:13], 0, v[0:1]
	v_or_b32_e32 v0, s12, v9
	v_ashrrev_i32_e32 v1, 31, v0
	v_lshlrev_b64 v[0:1], 11, v[0:1]
	v_lshl_add_u64 v[56:57], v[14:15], 0, v[0:1]
	v_add_co_u32_e32 v58, vcc, s64, v56
	s_nop 1
	v_addc_co_u32_e32 v59, vcc, 0, v57, vcc
	global_load_dwordx4 v[150:153], v[54:55], off
	global_load_dwordx4 v[154:157], v[56:57], off
	global_load_dwordx4 v[158:161], v[58:59], off
	global_load_dwordx4 v[162:165], v[54:55], off offset:64
	global_load_dwordx4 v[166:169], v[56:57], off offset:64
	global_load_dwordx4 v[180:183], v[58:59], off offset:64
	global_load_dwordx4 v[184:187], v[54:55], off offset:128
	global_load_dwordx4 v[188:191], v[56:57], off offset:128
	global_load_dwordx4 v[192:195], v[58:59], off offset:128
	global_load_dwordx4 v[196:199], v[54:55], off offset:192
	global_load_dwordx4 v[200:203], v[56:57], off offset:192
	global_load_dwordx4 v[204:207], v[58:59], off offset:192
	global_load_dwordx4 v[208:211], v[54:55], off offset:256
	global_load_dwordx4 v[212:215], v[56:57], off offset:256
	global_load_dwordx4 v[216:219], v[58:59], off offset:256
	global_load_dwordx4 v[220:223], v[54:55], off offset:320
	global_load_dwordx4 v[224:227], v[56:57], off offset:320
	global_load_dwordx4 v[228:231], v[58:59], off offset:320
	global_load_dwordx4 v[232:235], v[54:55], off offset:384
	global_load_dwordx4 v[236:239], v[56:57], off offset:384
	global_load_dwordx4 v[240:243], v[58:59], off offset:384
	global_load_dwordx4 v[244:247], v[54:55], off offset:448
	global_load_dwordx4 v[18:21], v[56:57], off offset:448
	global_load_dwordx4 v[22:25], v[58:59], off offset:448
	s_waitcnt vmcnt(21)
	v_mfma_f32_16x16x32_bf16 v[4:7], v[154:157], v[150:153], 0
	v_mfma_f32_16x16x32_bf16 v[0:3], v[158:161], v[150:153], 0
	s_waitcnt vmcnt(18)
	v_mfma_f32_16x16x32_bf16 v[4:7], v[166:169], v[162:165], v[4:7]
	v_mfma_f32_16x16x32_bf16 v[0:3], v[180:183], v[162:165], v[0:3]
	s_waitcnt vmcnt(15)
	v_mfma_f32_16x16x32_bf16 v[4:7], v[188:191], v[184:187], v[4:7]
	v_mfma_f32_16x16x32_bf16 v[0:3], v[192:195], v[184:187], v[0:3]
	s_waitcnt vmcnt(12)
	v_mfma_f32_16x16x32_bf16 v[4:7], v[200:203], v[196:199], v[4:7]
	v_mfma_f32_16x16x32_bf16 v[0:3], v[204:207], v[196:199], v[0:3]
	s_waitcnt vmcnt(9)
	v_mfma_f32_16x16x32_bf16 v[4:7], v[212:215], v[208:211], v[4:7]
	v_mfma_f32_16x16x32_bf16 v[0:3], v[216:219], v[208:211], v[0:3]
	s_waitcnt vmcnt(6)
	v_mfma_f32_16x16x32_bf16 v[4:7], v[224:227], v[220:223], v[4:7]
	v_mfma_f32_16x16x32_bf16 v[0:3], v[228:231], v[220:223], v[0:3]
	s_waitcnt vmcnt(3)
	v_mfma_f32_16x16x32_bf16 v[4:7], v[236:239], v[232:235], v[4:7]
	v_mfma_f32_16x16x32_bf16 v[0:3], v[240:243], v[232:235], v[0:3]
	s_waitcnt vmcnt(0)
	v_mfma_f32_16x16x32_bf16 v[4:7], v[18:21], v[244:247], v[4:7]
	v_mfma_f32_16x16x32_bf16 v[0:3], v[22:25], v[244:247], v[0:3]
	s_nop 0

; __device__ __forceinline__ void st8bf(bf16_t* p, f32x4 a, f32x4 b) { u32x4 w; w.x = pk2(a[0], a[1]); w.y = pk2(a[2], a[3]); w.z = pk2(b[0], b[1]); w.w = pk2(b[2], b[3]); st16(p, w); }
; __device__ __forceinline__ f32x4 sig4(f32x4 v) { f32x4 r; r[0] = sigmoidf_(v[0]); r[1] = sigmoidf_(v[1]); r[2] = sigmoidf_(v[2]); r[3] = sigmoidf_(v[3]); return r; }
;     __device__ __forceinline__ void st(int pn, int row, int c, f32x4 v0, f32x4 v1) const {
;     ...
;         else st8bf(GT + (size_t)row * 1024 + (pn - 4) * 256 + c, v0 * sig4(v0), v1 * sig4(v1));
;     ...
;         if (kh == 0 && act) {
; #pragma unroll
;             for (int q = 0; q < KS - 1; ++q)
; #pragma unroll
;                 for (int j = 0; j < NACC; ++j) acc[j] += red[((pw * (KS - 1) + q) * NACC + j) * 64 + lane];
;             const int row = row_base + mt * mt_stride + r, c = 32 * sub + 8 * fq;
;             if (glu) epi.st_glu(pn, row, c, acc[0], acc[1], acc[2], acc[3]); else epi.st(pn, row, c, acc[0], acc[1]);
.LBB0_1982:
	s_and_b64 s[8:9], s[14:15], s[8:9]
	s_andn2_b64 vcc, exec, s[8:9]
	s_waitcnt vmcnt(0) lgkmcnt(0)
	s_barrier
	s_cbranch_vccnz .LBB0_1977
	v_add_u32_e32 v16, s60, v33
	ds_read_b128 v[18:21], v16
	ds_read_b128 v[22:25], v16 offset:1024
	ds_read_b128 v[26:29], v16 offset:2048
	s_cmp_gt_i32 s69, 3
	s_mov_b64 s[8:9], -1
	s_waitcnt lgkmcnt(2)
	v_pk_add_f32 v[6:7], v[6:7], v[20:21]
	v_pk_add_f32 v[18:19], v[4:5], v[18:19]
	s_waitcnt lgkmcnt(1)
	v_pk_add_f32 v[24:25], v[2:3], v[24:25]
	v_pk_add_f32 v[22:23], v[0:1], v[22:23]
	ds_read_b128 v[0:3], v16 offset:3072
	s_waitcnt lgkmcnt(1)
	v_pk_add_f32 v[28:29], v[6:7], v[28:29]
	ds_read_b128 v[4:7], v16 offset:4096
	v_pk_add_f32 v[26:27], v[18:19], v[26:27]
	ds_read_b128 v[18:21], v16 offset:5120
	s_waitcnt lgkmcnt(2)
	v_pk_add_f32 v[2:3], v[24:25], v[2:3]
	v_pk_add_f32 v[0:1], v[22:23], v[0:1]
	s_waitcnt lgkmcnt(1)
	v_pk_add_f32 v[6:7], v[28:29], v[6:7]
	v_pk_add_f32 v[4:5], v[26:27], v[4:5]
	s_waitcnt lgkmcnt(0)
	v_pk_add_f32 v[2:3], v[2:3], v[20:21]
	v_pk_add_f32 v[0:1], v[0:1], v[18:19]
	v_lshl_add_u32 v18, s10, 5, v8
	v_lshl_add_u32 v16, s11, 4, v34
	s_cbranch_scc0 .LBB0_1985
	v_lshlrev_b64 v[20:21], 11, v[16:17]
	s_lshl_b32 s8, s69, 8
	v_mul_f32_e32 v19, 0xbfb8aa3b, v4
	v_lshl_add_u64 v[20:21], s[54:55], 0, v[20:21]
	s_add_i32 s12, s8, 0xfffffc00
	v_exp_f32_e32 v22, v19
	v_lshl_add_u64 v[20:21], s[12:13], 1, v[20:21]
	v_ashrrev_i32_e32 v19, 31, v18
	v_lshl_add_u64 v[24:25], v[18:19], 1, v[20:21]
	v_mul_f32_e32 v20, 0xbfb8aa3b, v5
	v_exp_f32_e32 v21, v20
	v_mul_f32_e32 v20, 0xbfb8aa3b, v6
	v_add_f32_e32 v19, 1.0, v22
	v_exp_f32_e32 v22, v20
	v_rcp_f32_e32 v20, v19
	v_add_f32_e32 v19, 1.0, v21
	v_rcp_f32_e32 v21, v19
	v_add_f32_e32 v19, 1.0, v22
	v_mul_f32_e32 v22, 0xbfb8aa3b, v7
	v_exp_f32_e32 v23, v22
	v_mul_f32_e32 v22, 0xbfb8aa3b, v0
	v_exp_f32_e32 v26, v22
	v_rcp_f32_e32 v22, v19
	v_add_f32_e32 v19, 1.0, v23
	v_rcp_f32_e32 v23, v19
	v_add_f32_e32 v19, 1.0, v26
	v_mul_f32_e32 v27, 0xbfb8aa3b, v2
	v_rcp_f32_e32 v26, v19
	v_mul_f32_e32 v19, 0xbfb8aa3b, v1
	v_exp_f32_e32 v27, v27
	v_mul_f32_e32 v28, 0xbfb8aa3b, v3
	v_exp_f32_e32 v19, v19
	v_exp_f32_e32 v29, v28
	v_add_f32_e32 v27, 1.0, v27
	v_rcp_f32_e32 v28, v27
	v_add_f32_e32 v19, 1.0, v19
	v_add_f32_e32 v27, 1.0, v29
	v_pk_mul_f32 v[20:21], v[4:5], v[20:21]
	v_rcp_f32_e32 v29, v27
	v_rcp_f32_e32 v27, v19
	v_pk_mul_f32 v[22:23], v[6:7], v[22:23]
	v_cvt_pk_bf16_f32 v20, v20, v21
	v_pk_mul_f32 v[26:27], v[0:1], v[26:27]
	v_cvt_pk_bf16_f32 v21, v22, v23
	v_pk_mul_f32 v[28:29], v[2:3], v[28:29]
	v_cvt_pk_bf16_f32 v22, v26, v27
	v_cvt_pk_bf16_f32 v23, v28, v29
	global_store_dwordx4 v[24:25], v[20:23], off
	s_mov_b64 s[8:9], 0

; __device__ __forceinline__ void st16f(float* p, f32x4 v) { st16(p, __builtin_bit_cast(u32x4, v)); }
; __device__ __forceinline__ void st8bf(bf16_t* p, f32x4 a, f32x4 b) { u32x4 w; w.x = pk2(a[0], a[1]); w.y = pk2(a[2], a[3]); w.z = pk2(b[0], b[1]); w.w = pk2(b[2], b[3]); st16(p, w); }
;     __device__ __forceinline__ void st(int pn, int row, int c, f32x4 v0, f32x4 v1) const {
;     ...
;         if (pn < 4) { const int col = pn * 256 + c; float* o = nullptr;
;             if (smp) o = out + O_POOLS + ((size_t)b * 15 + 11 + t) * 1024 + col;
;             st8bf(V + (size_t)row * 1024 + col, v0, v1); if (o) { st16f(o, v0); st16f(o + 4, v1); }
.LBB0_1988:
	s_or_b64 exec, exec, s[8:9]
	v_lshlrev_b64 v[22:23], 11, v[16:17]
	v_lshl_add_u64 v[22:23], s[52:53], 0, v[22:23]
	v_lshl_add_u64 v[26:27], v[18:19], 1, v[22:23]
	v_cvt_pk_bf16_f32 v22, v4, v5
	v_cvt_pk_bf16_f32 v23, v6, v7
	v_cvt_pk_bf16_f32 v24, v0, v1
	v_bfe_u32 v25, v2, 16, 1
	v_add3_u32 v25, v2, v25, s65
	v_bfe_u32 v28, v3, 16, 1
	v_lshrrev_b32_e32 v25, 16, v25
	v_add3_u32 v28, v3, v28, s65
	v_and_or_b32 v25, v28, s66, v25
	v_cmp_ne_u64_e64 s[8:9], 0, v[20:21]
	global_store_dwordx4 v[26:27], v[22:25], off
	s_and_saveexec_b64 s[10:11], s[8:9]
	s_cbranch_execz .LBB0_1990
	global_store_dwordx4 v[20:21], v[4:7], off
	global_store_dwordx4 v[20:21], v[0:3], off offset:16

; #define MFMA16(a, b, c) __builtin_amdgcn_mfma_f32_16x16x32_bf16((a), (b), (c), 0, 0, 0)
;     ...
;             const bf16_t* ap = A + (size_t)(mt * mt_stride + r) * lda + (size_t)pn * a_tile_off + kh * Kh + 8 * fq;
;             const bf16_t* bp = Bt + (size_t)(256 * pn + 32 * sub + 8 * (r >> 2) + (r & 3)) * ldb + kh * Kh + 8 * fq;
;             if (glu) {
; #pragma unroll 8
;                 for (int k0 = 0; k0 < Kh; k0 += 32) { const bf16x8 a = *(const bf16x8*)(ap + k0);
;                     acc[0] = MFMA16(*(const bf16x8*)(bp + k0), a, acc[0]); acc[1] = MFMA16(*(const bf16x8*)(bp + 4 * ldb + k0), a, acc[1]);
;                     acc[2] = MFMA16(*(const bf16x8*)(bp + 128 * ldb + k0), a, acc[2]); acc[3] = MFMA16(*(const bf16x8*)(bp + 132 * ldb + k0), a, acc[3]); }
;             } else {
; #pragma unroll 8
;                 for (int k0 = 0; k0 < Kh; k0 += 32) { const bf16x8 a = *(const bf16x8*)(ap + k0);
;                     acc[0] = MFMA16(*(const bf16x8*)(bp + k0), a, acc[0]); acc[1] = MFMA16(*(const bf16x8*)(bp + 4 * ldb + k0), a, acc[1]); }
.LBB0_2025:
	s_add_i32 s12, s16, s14
	s_ashr_i32 s13, s12, 31
	s_lshr_b32 s13, s13, 30
	s_add_i32 s13, s12, s13
	s_and_b32 s18, s13, -4
	s_bfe_u32 s19, s13, 0x30002
	s_sub_i32 s20, s12, s18
	s_ashr_i32 s18, s13, 5
	s_cmpk_gt_i32 s12, 0x7f
	s_cselect_b64 s[12:13], -1, 0
	s_and_b64 vcc, exec, s[12:13]
	v_mov_b32_e32 v4, 0
	v_mov_b32_e32 v5, 0
	v_mov_b32_e32 v6, 0
	v_mov_b32_e32 v7, 0
	v_mov_b32_e32 v0, 0
	v_mov_b32_e32 v1, 0
	v_mov_b32_e32 v2, 0
	v_mov_b32_e32 v3, 0
	s_cbranch_vccnz .LBB0_2027
	v_lshl_or_b32 v0, s20, 13, v31
	v_ashrrev_i32_e32 v1, 31, v0
	s_lshl_b32 s21, s18, 8
	s_lshl_b32 s22, s19, 5
	v_lshlrev_b64 v[0:1], 11, v[0:1]
	s_or_b32 s21, s21, s22
	v_lshl_add_u64 v[42:43], v[12:13], 0, v[0:1]
	v_or_b32_e32 v0, s21, v9
	v_ashrrev_i32_e32 v1, 31, v0
	v_lshlrev_b64 v[0:1], 11, v[0:1]
	v_lshl_add_u64 v[44:45], v[10:11], 0, v[0:1]
	v_add_co_u32_e32 v46, vcc, s17, v44
	s_nop 1
	v_addc_co_u32_e32 v47, vcc, 0, v45, vcc
	global_load_dwordx4 v[150:153], v[42:43], off
	global_load_dwordx4 v[154:157], v[44:45], off
	global_load_dwordx4 v[158:161], v[46:47], off
	global_load_dwordx4 v[162:165], v[42:43], off offset:64
	global_load_dwordx4 v[166:169], v[44:45], off offset:64
	global_load_dwordx4 v[180:183], v[46:47], off offset:64
	global_load_dwordx4 v[184:187], v[42:43], off offset:128
	global_load_dwordx4 v[188:191], v[44:45], off offset:128
	global_load_dwordx4 v[192:195], v[46:47], off offset:128
	global_load_dwordx4 v[196:199], v[42:43], off offset:192
	global_load_dwordx4 v[200:203], v[44:45], off offset:192
	global_load_dwordx4 v[204:207], v[46:47], off offset:192
	s_waitcnt vmcnt(9)
	v_mfma_f32_16x16x32_bf16 v[0:3], v[154:157], v[150:153], 0
	v_mfma_f32_16x16x32_bf16 v[4:7], v[158:161], v[150:153], 0
	s_waitcnt vmcnt(6)
	v_mfma_f32_16x16x32_bf16 v[0:3], v[166:169], v[162:165], v[0:3]
	v_mfma_f32_16x16x32_bf16 v[4:7], v[180:183], v[162:165], v[4:7]
	s_waitcnt vmcnt(3)
	v_mfma_f32_16x16x32_bf16 v[0:3], v[188:191], v[184:187], v[0:3]
	v_mfma_f32_16x16x32_bf16 v[4:7], v[192:195], v[184:187], v[4:7]
	s_waitcnt vmcnt(0)
	v_mfma_f32_16x16x32_bf16 v[0:3], v[200:203], v[196:199], v[0:3]
	v_mfma_f32_16x16x32_bf16 v[4:7], v[204:207], v[196:199], v[4:7]
	s_nop 0

; __device__ __forceinline__ void st16f(float* p, f32x4 v) { st16(p, __builtin_bit_cast(u32x4, v)); }
; __device__ __forceinline__ void st8bf(bf16_t* p, f32x4 a, f32x4 b) { u32x4 w; w.x = pk2(a[0], a[1]); w.y = pk2(a[2], a[3]); w.z = pk2(b[0], b[1]); w.w = pk2(b[2], b[3]); st16(p, w); }
; __device__ __forceinline__ f32x4 sig4(f32x4 v) { f32x4 r; r[0] = sigmoidf_(v[0]); r[1] = sigmoidf_(v[1]); r[2] = sigmoidf_(v[2]); r[3] = sigmoidf_(v[3]); return r; }
;     __device__ __forceinline__ void st(int pn, int row, int c, f32x4 v0, f32x4 v1) const {
;         const bool smp = row >= MP; const int b = smp ? (row - MP) >> 2 : row >> 13, t = smp ? (row - MP) & 3 : row & (SEQ - 1);
;         if (pn < 4) { const int col = pn * 256 + c; float* o = nullptr;
;             if (smp) o = out + O_POOLS + ((size_t)b * 15 + 11 + t) * 1024 + col;
;             st8bf(V + (size_t)row * 1024 + col, v0, v1); if (o) { st16f(o, v0); st16f(o + 4, v1); }
;             if (smp) {
;                 const int w = 2 << pn;
;                 float x[8] = {v0[0], v0[1], v0[2], v0[3], v1[0], v1[1], v1[2], v1[3]}, s[8];
; #pragma unroll
;                 for (int e = 0; e < 8; ++e) { s[e] = 0.f;
; #pragma unroll
;                     for (int tp = 0; tp < 4; ++tp) { const float xo = quad_bcast(x[e], tp); if (tp <= t && t - tp < w) s[e] += xo; } }
;                 const int e_lo = 15 + t - w + 1;
; #pragma unroll
;                 for (int e2 = 0; e2 < 15; ++e2) if (e2 >= e_lo) { const float* sp = state_pool + ((size_t)b * 15 + e2) * 1024 + col; const f32x4 a = *(const f32x4*)sp, d = *(const f32x4*)(sp + 4);
;                     s[0] += a[0]; s[1] += a[1]; s[2] += a[2]; s[3] += a[3]; s[4] += d[0]; s[5] += d[1]; s[6] += d[2]; s[7] += d[3]; }
;                 const float inv = 1.f / (float)w;
;                 st8bf(DMs + (size_t)row * 1024 + col, (f32x4){s[0] * inv - x[0], s[1] * inv - x[1], s[2] * inv - x[2], s[3] * inv - x[3]}, (f32x4){s[4] * inv - x[4], s[5] * inv - x[5], s[6] * inv - x[6], s[7] * inv - x[7]});
;             } }
;         else st8bf(GT + (size_t)row * 1024 + (pn - 4) * 256 + c, v0 * sig4(v0), v1 * sig4(v1));
.LBB0_2049:
	s_cmp_gt_i32 s46, 3
	v_lshl_add_u32 v150, s8, 8, v175
	s_cselect_b64 s[72:73], -1, 0
	s_lshl_b32 s8, 2, s46
	s_lshl_b32 s70, s46, 8
	v_subrev_co_u32_e64 v138, s[40:41], s8, v172
	v_ashrrev_i32_e32 v151, 31, v150
	s_add_i32 s60, s70, 0xfffffc00
	v_cmp_gt_u32_e64 s[42:43], s8, v173
	v_cmp_gt_u32_e64 s[44:45], s8, v174
	v_cmp_gt_i32_e64 s[38:39], -15, v138
	v_cmp_gt_i32_e64 s[36:37], -14, v138
	v_cmp_gt_i32_e64 s[34:35], -13, v138
	v_cmp_gt_i32_e64 s[30:31], -12, v138
	v_cmp_gt_i32_e64 s[28:29], -11, v138
	v_cmp_gt_i32_e64 s[26:27], -10, v138
	v_cmp_gt_i32_e64 s[24:25], -9, v138
	v_cmp_gt_i32_e64 s[22:23], -8, v138
	v_cmp_gt_i32_e64 s[20:21], -7, v138
	v_cmp_gt_i32_e64 s[92:93], -6, v138
	v_cmp_gt_i32_e64 s[62:63], -5, v138
	v_cmp_gt_i32_e64 s[94:95], -4, v138
	v_cmp_gt_i32_e64 s[58:59], -3, v138
	v_cmp_gt_i32_e64 s[56:57], -2, v138
	v_cmp_gt_i32_e64 s[76:77], -1, v138
	v_cmp_lt_i32_e64 s[48:49], s89, v150
	v_lshlrev_b64 v[158:159], 11, v[150:151]
	s_mov_b64 s[74:75], -1
	s_and_b64 vcc, exec, s[72:73]
	s_cbranch_vccz .LBB0_2051
	v_mul_f32_e32 v138, 0xbfb8aa3b, v124
	v_lshl_add_u64 v[152:153], s[54:55], 0, v[158:159]
	v_exp_f32_e32 v154, v138
	v_lshl_add_u64 v[152:153], s[60:61], 1, v[152:153]
	v_lshlrev_b32_e32 v138, 1, v140
	v_lshl_add_u64 v[156:157], v[152:153], 0, v[138:139]
	v_mul_f32_e32 v152, 0xbfb8aa3b, v125
	v_exp_f32_e32 v153, v152
	v_mul_f32_e32 v152, 0xbfb8aa3b, v126
	v_add_f32_e32 v138, 1.0, v154
	v_exp_f32_e32 v154, v152
	v_rcp_f32_e32 v152, v138
	v_add_f32_e32 v138, 1.0, v153
	v_rcp_f32_e32 v153, v138
	v_add_f32_e32 v138, 1.0, v154
	v_mul_f32_e32 v154, 0xbfb8aa3b, v127
	v_exp_f32_e32 v155, v154
	v_mul_f32_e32 v154, 0xbfb8aa3b, v120
	v_exp_f32_e32 v160, v154
	v_rcp_f32_e32 v154, v138
	v_add_f32_e32 v138, 1.0, v155
	v_rcp_f32_e32 v155, v138
	v_add_f32_e32 v138, 1.0, v160
	v_mul_f32_e32 v161, 0xbfb8aa3b, v122
	v_rcp_f32_e32 v160, v138
	v_mul_f32_e32 v138, 0xbfb8aa3b, v121
	v_exp_f32_e32 v161, v161
	v_mul_f32_e32 v162, 0xbfb8aa3b, v123
	v_exp_f32_e32 v138, v138
	v_exp_f32_e32 v163, v162
	v_add_f32_e32 v161, 1.0, v161
	v_rcp_f32_e32 v162, v161
	v_add_f32_e32 v138, 1.0, v138
	v_add_f32_e32 v161, 1.0, v163
	v_pk_mul_f32 v[152:153], v[124:125], v[152:153]
	v_rcp_f32_e32 v163, v161
	v_rcp_f32_e32 v161, v138
	v_pk_mul_f32 v[154:155], v[126:127], v[154:155]
	v_cvt_pk_bf16_f32 v152, v152, v153
	v_pk_mul_f32 v[160:161], v[120:121], v[160:161]
	v_cvt_pk_bf16_f32 v153, v154, v155
	v_pk_mul_f32 v[162:163], v[122:123], v[162:163]
	v_cvt_pk_bf16_f32 v154, v160, v161
	v_cvt_pk_bf16_f32 v155, v162, v163
	global_store_dwordx4 v[156:157], v[152:155], off
	s_mov_b64 s[74:75], 0
.LBB0_2051:
	v_readlane_b32 s4, v250, 60
	v_readlane_b32 s5, v250, 61
	v_add_u32_e32 v138, 0xffff8000, v150
	s_and_b64 s[42:43], s[4:5], s[42:43]
	v_readlane_b32 s4, v251, 2
	s_lshl_b32 s46, s46, 23
	v_lshrrev_b32_e32 v138, 2, v138
	v_readlane_b32 s5, v251, 3
	s_sub_i32 s68, 0.5, s46
	v_mad_u64_u32 v[152:153], s[46:47], v138, 15, v[128:129]
	s_and_b64 s[44:45], s[4:5], s[44:45]
	v_lshlrev_b64 v[156:157], 12, v[152:153]
	v_lshlrev_b64 v[152:153], 10, v[150:151]
	s_andn2_b64 vcc, exec, s[74:75]
	v_mad_u64_u32 v[154:155], s[46:47], v138, s90, 0
	s_cbranch_vccnz .LBB0_2071
	v_or_b32_e32 v160, s70, v140
	v_ashrrev_i32_e32 v161, 31, v160
	v_lshl_add_u64 v[162:163], v[152:153], 1, s[52:53]
	v_lshl_add_u64 v[166:167], v[160:161], 1, v[162:163]
	v_cvt_pk_bf16_f32 v162, v124, v125
	v_cvt_pk_bf16_f32 v163, v126, v127
	v_cvt_pk_bf16_f32 v164, v120, v121
	v_bfe_u32 v138, v122, 16, 1
	v_add3_u32 v138, v122, v138, s89
	v_bfe_u32 v151, v123, 16, 1
	v_lshrrev_b32_e32 v138, 16, v138
	v_add3_u32 v151, v123, v151, s89
	v_and_or_b32 v165, v151, s91, v138
	global_store_dwordx4 v[166:167], v[162:165], off
	s_and_saveexec_b64 s[46:47], s[48:49]
	s_cbranch_execz .LBB0_2070
;     __device__ __forceinline__ void st(int pn, int row, int c, f32x4 v0, f32x4 v1) const {
;     ...
;             if (smp) {
;                 const int w = 2 << pn;
;                 float x[8] = {v0[0], v0[1], v0[2], v0[3], v1[0], v1[1], v1[2], v1[3]}, s[8];
; #pragma unroll
;                 for (int e = 0; e < 8; ++e) { s[e] = 0.f;
; #pragma unroll
;                     for (int tp = 0; tp < 4; ++tp) { const float xo = quad_bcast(x[e], tp); if (tp <= t && t - tp < w) s[e] += xo; } }
;                 const int e_lo = 15 + t - w + 1;
; #pragma unroll
;                 for (int e2 = 0; e2 < 15; ++e2) if (e2 >= e_lo) { const float* sp = state_pool + ((size_t)b * 15 + e2) * 1024 + col; const f32x4 a = *(const f32x4*)sp, d = *(const f32x4*)(sp + 4);
;                     s[0] += a[0]; s[1] += a[1]; s[2] += a[2]; s[3] += a[3]; s[4] += d[0]; s[5] += d[1]; s[6] += d[2]; s[7] += d[3]; }
	v_mov_b32_dpp v138, v124 quad_perm:[0,0,0,0] row_mask:0xf bank_mask:0xf bound_ctrl:1
	v_add_f32_e32 v138, 0, v138
	v_cndmask_b32_e64 v138, 0, v138, s[40:41]
	v_readlane_b32 s4, v250, 58
	v_readlane_b32 s5, v250, 59
	v_add_f32_dpp v151, v124, v138 quad_perm:[1,1,1,1] row_mask:0xf bank_mask:0xf bound_ctrl:1
	v_cndmask_b32_e64 v138, v138, v151, s[44:45]
	v_lshl_add_u64 v[162:163], s[4:5], 0, v[156:157]
	v_lshlrev_b64 v[170:171], 2, v[160:161]
	v_add_f32_dpp v151, v124, v138 quad_perm:[2,2,2,2] row_mask:0xf bank_mask:0xf bound_ctrl:1
	v_cndmask_b32_e64 v138, v138, v151, s[42:43]
	v_lshl_add_u64 v[162:163], v[162:163], 0, v[170:171]
	global_store_dwordx4 v[162:163], v[124:127], off
	global_store_dwordx4 v[162:163], v[120:123], off offset:16
	v_add_f32_dpp v151, v124, v138 quad_perm:[3,3,3,3] row_mask:0xf bank_mask:0xf bound_ctrl:1
	v_cndmask_b32_e64 v162, v138, v151, s[0:1]
	v_mov_b32_dpp v138, v125 quad_perm:[0,0,0,0] row_mask:0xf bank_mask:0xf bound_ctrl:1
	v_add_f32_e32 v138, 0, v138
	v_cndmask_b32_e64 v138, 0, v138, s[40:41]
	v_readlane_b32 s4, v250, 12
	v_readlane_b32 s16, v250, 24
	v_add_f32_dpp v151, v125, v138 quad_perm:[1,1,1,1] row_mask:0xf bank_mask:0xf bound_ctrl:1
	v_cndmask_b32_e64 v138, v138, v151, s[44:45]
	v_readlane_b32 s17, v250, 25
	v_readlane_b32 s5, v250, 13
	v_add_f32_dpp v151, v125, v138 quad_perm:[2,2,2,2] row_mask:0xf bank_mask:0xf bound_ctrl:1
	v_cndmask_b32_e64 v138, v138, v151, s[42:43]
	v_lshl_add_u64 v[170:171], s[16:17], 0, v[170:171]
	v_lshl_add_u64 v[170:171], v[170:171], 0, v[154:155]
	v_add_f32_dpp v151, v125, v138 quad_perm:[3,3,3,3] row_mask:0xf bank_mask:0xf bound_ctrl:1
	v_cndmask_b32_e64 v163, v138, v151, s[0:1]
	v_mov_b32_dpp v138, v126 quad_perm:[0,0,0,0] row_mask:0xf bank_mask:0xf bound_ctrl:1
	v_add_f32_e32 v138, 0, v138
	v_cndmask_b32_e64 v138, 0, v138, s[40:41]
	v_readlane_b32 s6, v250, 14
	v_readlane_b32 s7, v250, 15
	v_add_f32_dpp v151, v126, v138 quad_perm:[1,1,1,1] row_mask:0xf bank_mask:0xf bound_ctrl:1
	v_cndmask_b32_e64 v138, v138, v151, s[44:45]
	v_readlane_b32 s8, v250, 16
	v_readlane_b32 s9, v250, 17
	v_add_f32_dpp v151, v126, v138 quad_perm:[2,2,2,2] row_mask:0xf bank_mask:0xf bound_ctrl:1
	v_cndmask_b32_e64 v138, v138, v151, s[42:43]
	v_readlane_b32 s10, v250, 18
	v_readlane_b32 s11, v250, 19
	v_add_f32_dpp v151, v126, v138 quad_perm:[3,3,3,3] row_mask:0xf bank_mask:0xf bound_ctrl:1
	v_cndmask_b32_e64 v164, v138, v151, s[0:1]
	v_mov_b32_dpp v138, v127 quad_perm:[0,0,0,0] row_mask:0xf bank_mask:0xf bound_ctrl:1
	v_add_f32_e32 v138, 0, v138
	v_cndmask_b32_e64 v138, 0, v138, s[40:41]
	v_readlane_b32 s12, v250, 20
	v_readlane_b32 s13, v250, 21
	v_add_f32_dpp v151, v127, v138 quad_perm:[1,1,1,1] row_mask:0xf bank_mask:0xf bound_ctrl:1
	v_cndmask_b32_e64 v138, v138, v151, s[44:45]
	v_readlane_b32 s14, v250, 22
	v_readlane_b32 s15, v250, 23
	v_add_f32_dpp v151, v127, v138 quad_perm:[2,2,2,2] row_mask:0xf bank_mask:0xf bound_ctrl:1
	v_cndmask_b32_e64 v138, v138, v151, s[42:43]
	v_readlane_b32 s18, v250, 26
	v_readlane_b32 s19, v250, 27
	v_add_f32_dpp v151, v127, v138 quad_perm:[3,3,3,3] row_mask:0xf bank_mask:0xf bound_ctrl:1
	v_cndmask_b32_e64 v165, v138, v151, s[0:1]
	v_mov_b32_dpp v138, v120 quad_perm:[0,0,0,0] row_mask:0xf bank_mask:0xf bound_ctrl:1
	v_add_f32_e32 v138, 0, v138
	v_cndmask_b32_e64 v138, 0, v138, s[40:41]
	s_nop 1
	v_add_f32_dpp v151, v120, v138 quad_perm:[1,1,1,1] row_mask:0xf bank_mask:0xf bound_ctrl:1
	v_cndmask_b32_e64 v138, v138, v151, s[44:45]
	s_nop 1
	v_add_f32_dpp v151, v120, v138 quad_perm:[2,2,2,2] row_mask:0xf bank_mask:0xf bound_ctrl:1
	v_cndmask_b32_e64 v138, v138, v151, s[42:43]
	s_nop 1
	v_add_f32_dpp v151, v120, v138 quad_perm:[3,3,3,3] row_mask:0xf bank_mask:0xf bound_ctrl:1
	v_cndmask_b32_e64 v166, v138, v151, s[0:1]
	v_mov_b32_dpp v138, v121 quad_perm:[0,0,0,0] row_mask:0xf bank_mask:0xf bound_ctrl:1
	v_add_f32_e32 v138, 0, v138
	v_cndmask_b32_e64 v138, 0, v138, s[40:41]
	s_nop 1
	v_add_f32_dpp v151, v121, v138 quad_perm:[1,1,1,1] row_mask:0xf bank_mask:0xf bound_ctrl:1
	v_cndmask_b32_e64 v138, v138, v151, s[44:45]
	s_nop 1
	v_add_f32_dpp v151, v121, v138 quad_perm:[2,2,2,2] row_mask:0xf bank_mask:0xf bound_ctrl:1
	v_cndmask_b32_e64 v138, v138, v151, s[42:43]
	s_nop 1
	v_add_f32_dpp v151, v121, v138 quad_perm:[3,3,3,3] row_mask:0xf bank_mask:0xf bound_ctrl:1
	v_cndmask_b32_e64 v167, v138, v151, s[0:1]
	v_mov_b32_dpp v138, v122 quad_perm:[0,0,0,0] row_mask:0xf bank_mask:0xf bound_ctrl:1
	v_add_f32_e32 v138, 0, v138
	v_cndmask_b32_e64 v138, 0, v138, s[40:41]
	s_nop 1
	v_add_f32_dpp v151, v122, v138 quad_perm:[1,1,1,1] row_mask:0xf bank_mask:0xf bound_ctrl:1
	v_cndmask_b32_e64 v138, v138, v151, s[44:45]
	s_nop 1
	v_add_f32_dpp v151, v122, v138 quad_perm:[2,2,2,2] row_mask:0xf bank_mask:0xf bound_ctrl:1
	v_cndmask_b32_e64 v138, v138, v151, s[42:43]
	s_nop 1
	v_add_f32_dpp v151, v122, v138 quad_perm:[3,3,3,3] row_mask:0xf bank_mask:0xf bound_ctrl:1
	v_cndmask_b32_e64 v168, v138, v151, s[0:1]
	v_mov_b32_dpp v138, v123 quad_perm:[0,0,0,0] row_mask:0xf bank_mask:0xf bound_ctrl:1
	v_add_f32_e32 v138, 0, v138
	v_cndmask_b32_e64 v138, 0, v138, s[40:41]
	s_nop 1
	v_add_f32_dpp v151, v123, v138 quad_perm:[1,1,1,1] row_mask:0xf bank_mask:0xf bound_ctrl:1
	v_cndmask_b32_e64 v138, v138, v151, s[44:45]
	s_nop 1
	v_add_f32_dpp v151, v123, v138 quad_perm:[2,2,2,2] row_mask:0xf bank_mask:0xf bound_ctrl:1
	v_cndmask_b32_e64 v138, v138, v151, s[42:43]
	s_nop 1
	v_add_f32_dpp v151, v123, v138 quad_perm:[3,3,3,3] row_mask:0xf bank_mask:0xf bound_ctrl:1
	v_cndmask_b32_e64 v169, v138, v151, s[0:1]
	s_and_saveexec_b64 s[74:75], s[38:39]
	s_cbranch_execz .LBB0_2404
	global_load_dwordx4 v[180:183], v[170:171], off offset:16
	global_load_dwordx4 v[184:187], v[170:171], off
	s_waitcnt vmcnt(0)
	v_pk_add_f32 v[166:167], v[166:167], v[180:181]
	v_pk_add_f32 v[168:169], v[168:169], v[182:183]
	v_pk_add_f32 v[164:165], v[164:165], v[186:187]
	v_pk_add_f32 v[162:163], v[162:163], v[184:185]
	s_or_b64 exec, exec, s[74:75]
	s_and_saveexec_b64 s[74:75], s[36:37]
	s_cbranch_execnz .LBB0_2405

; __device__ __forceinline__ void st8bf(bf16_t* p, f32x4 a, f32x4 b) { u32x4 w; w.x = pk2(a[0], a[1]); w.y = pk2(a[2], a[3]); w.z = pk2(b[0], b[1]); w.w = pk2(b[2], b[3]); st16(p, w); }
;     __device__ __forceinline__ void st(int pn, int row, int c, f32x4 v0, f32x4 v1) const {
;     ...
;                 const float inv = 1.f / (float)w;
;                 st8bf(DMs + (size_t)row * 1024 + col, (f32x4){s[0] * inv - x[0], s[1] * inv - x[1], s[2] * inv - x[2], s[3] * inv - x[3]}, (f32x4){s[4] * inv - x[4], s[5] * inv - x[5], s[6] * inv - x[6], s[7] * inv - x[7]});
.LBB0_2069:
	s_or_b64 exec, exec, s[74:75]
	v_readlane_b32 s4, v251, 0
	v_readlane_b32 s5, v251, 1
	v_mov_b32_e32 v181, v126
	v_mov_b32_e32 v126, v125
	v_lshl_add_u64 v[170:171], v[152:153], 1, s[4:5]
	v_lshl_add_u64 v[160:161], v[160:161], 1, v[170:171]
	v_mov_b32_e32 v171, v164
	v_mov_b32_e32 v164, v163
	v_mov_b32_e32 v180, v124
	v_pk_fma_f32 v[124:125], s[68:69], v[164:165], v[126:127] op_sel_hi:[0,1,1] neg_lo:[0,0,1] neg_hi:[0,0,1]
	v_mov_b32_e32 v127, v168
	v_mov_b32_e32 v163, v122
	v_mov_b32_e32 v168, v167
	v_mov_b32_e32 v122, v121
	v_mov_b32_e32 v170, v162
	v_mov_b32_e32 v126, v166
	v_mov_b32_e32 v162, v120
	v_pk_fma_f32 v[120:121], s[68:69], v[168:169], v[122:123] op_sel_hi:[0,1,1] neg_lo:[0,0,1] neg_hi:[0,0,1]
	v_pk_fma_f32 v[170:171], s[68:69], v[170:171], v[180:181] op_sel_hi:[0,1,1] neg_lo:[0,0,1] neg_hi:[0,0,1]
	v_pk_fma_f32 v[126:127], s[68:69], v[126:127], v[162:163] op_sel_hi:[0,1,1] neg_lo:[0,0,1] neg_hi:[0,0,1]
	v_cvt_pk_bf16_f32 v123, v127, v121
	v_cvt_pk_bf16_f32 v122, v126, v120
	v_cvt_pk_bf16_f32 v121, v171, v125
	v_cvt_pk_bf16_f32 v120, v170, v124
	global_store_dwordx4 v[160:161], v[120:123], off

; __device__ __forceinline__ void st8bf(bf16_t* p, f32x4 a, f32x4 b) { u32x4 w; w.x = pk2(a[0], a[1]); w.y = pk2(a[2], a[3]); w.z = pk2(b[0], b[1]); w.w = pk2(b[2], b[3]); st16(p, w); }
; __device__ __forceinline__ f32x4 sig4(f32x4 v) { f32x4 r; r[0] = sigmoidf_(v[0]); r[1] = sigmoidf_(v[1]); r[2] = sigmoidf_(v[2]); r[3] = sigmoidf_(v[3]); return r; }
;     __device__ __forceinline__ void st(int pn, int row, int c, f32x4 v0, f32x4 v1) const {
;     ...
;         else st8bf(GT + (size_t)row * 1024 + (pn - 4) * 256 + c, v0 * sig4(v0), v1 * sig4(v1));
.LBB0_2071:
	s_nop 0
	v_cndmask_b32_e64 v120, 0, 1, s[72:73]
	v_cmp_ne_u32_e64 s[46:47], 1, v120
	s_andn2_b64 vcc, exec, s[72:73]
	s_mov_b64 s[72:73], -1
	s_cbranch_vccnz .LBB0_2073
	v_lshl_add_u64 v[120:121], s[54:55], 0, v[158:159]
	v_mul_f32_e32 v122, 0xbfb8aa3b, v116
	v_exp_f32_e32 v122, v122
	v_lshl_add_u64 v[120:121], s[60:61], 1, v[120:121]
	v_lshlrev_b32_e32 v138, 1, v140
	v_lshl_add_u64 v[124:125], v[120:121], 0, v[138:139]
	v_mul_f32_e32 v121, 0xbfb8aa3b, v117
	v_exp_f32_e32 v121, v121
	v_add_f32_e32 v120, 1.0, v122
	v_mul_f32_e32 v122, 0xbfb8aa3b, v118
	v_mul_f32_e32 v123, 0xbfb8aa3b, v119
	v_exp_f32_e32 v122, v122
	v_exp_f32_e32 v123, v123
	v_mul_f32_e32 v138, 0xbfb8aa3b, v114
	v_add_f32_e32 v121, 1.0, v121
	v_exp_f32_e32 v138, v138
	v_mul_f32_e32 v151, 0xbfb8aa3b, v115
	v_rcp_f32_e32 v120, v120
	v_rcp_f32_e32 v121, v121
	v_mul_f32_e32 v126, 0xbfb8aa3b, v112
	v_mul_f32_e32 v127, 0xbfb8aa3b, v113
	v_exp_f32_e32 v151, v151
	v_exp_f32_e32 v126, v126
	v_exp_f32_e32 v127, v127
	v_add_f32_e32 v122, 1.0, v122
	v_add_f32_e32 v123, 1.0, v123
	v_rcp_f32_e32 v122, v122
	v_rcp_f32_e32 v123, v123
	v_add_f32_e32 v138, 1.0, v138
	v_rcp_f32_e32 v158, v138
	v_add_f32_e32 v138, 1.0, v151
	v_pk_mul_f32 v[120:121], v[116:117], v[120:121]
	v_add_f32_e32 v126, 1.0, v126
	v_add_f32_e32 v127, 1.0, v127
	v_rcp_f32_e32 v159, v138
	v_rcp_f32_e32 v126, v126
	v_rcp_f32_e32 v127, v127
	v_pk_mul_f32 v[122:123], v[118:119], v[122:123]
	v_cvt_pk_bf16_f32 v120, v120, v121
	v_pk_mul_f32 v[126:127], v[112:113], v[126:127]
	v_cvt_pk_bf16_f32 v121, v122, v123
	v_pk_mul_f32 v[158:159], v[114:115], v[158:159]
	v_cvt_pk_bf16_f32 v122, v126, v127
	v_cvt_pk_bf16_f32 v123, v158, v159
	s_mov_b64 s[72:73], 0
	global_store_dwordx4 v[124:125], v[120:123], off offset:256
; __device__ __forceinline__ void st16f(float* p, f32x4 v) { st16(p, __builtin_bit_cast(u32x4, v)); }
; __device__ __forceinline__ void st8bf(bf16_t* p, f32x4 a, f32x4 b) { u32x4 w; w.x = pk2(a[0], a[1]); w.y = pk2(a[2], a[3]); w.z = pk2(b[0], b[1]); w.w = pk2(b[2], b[3]); st16(p, w); }
;     __device__ __forceinline__ void st(int pn, int row, int c, f32x4 v0, f32x4 v1) const {
;     ...
;         if (pn < 4) { const int col = pn * 256 + c; float* o = nullptr;
;             if (smp) o = out + O_POOLS + ((size_t)b * 15 + 11 + t) * 1024 + col;
;             st8bf(V + (size_t)row * 1024 + col, v0, v1); if (o) { st16f(o, v0); st16f(o + 4, v1); }
;             if (smp) {
;                 const int w = 2 << pn;
;                 float x[8] = {v0[0], v0[1], v0[2], v0[3], v1[0], v1[1], v1[2], v1[3]}, s[8];
; #pragma unroll
;                 for (int e = 0; e < 8; ++e) { s[e] = 0.f;
; #pragma unroll
;                     for (int tp = 0; tp < 4; ++tp) { const float xo = quad_bcast(x[e], tp); if (tp <= t && t - tp < w) s[e] += xo; } }
;                 const int e_lo = 15 + t - w + 1;
; #pragma unroll
;                 for (int e2 = 0; e2 < 15; ++e2) if (e2 >= e_lo) { const float* sp = state_pool + ((size_t)b * 15 + e2) * 1024 + col; const f32x4 a = *(const f32x4*)sp, d = *(const f32x4*)(sp + 4);
;                     s[0] += a[0]; s[1] += a[1]; s[2] += a[2]; s[3] += a[3]; s[4] += d[0]; s[5] += d[1]; s[6] += d[2]; s[7] += d[3]; }
.LBB0_2073:
	s_andn2_b64 vcc, exec, s[72:73]
	s_cbranch_vccnz .LBB0_2093
	s_ashr_i32 s71, s70, 31
	v_lshl_add_u64 v[122:123], v[152:153], 1, s[52:53]
	v_lshl_add_u64 v[120:121], s[70:71], 0, v[140:141]
	v_lshl_add_u64 v[126:127], v[120:121], 1, v[122:123]
	v_cvt_pk_bf16_f32 v122, v116, v117
	v_cvt_pk_bf16_f32 v123, v118, v119
	v_cvt_pk_bf16_f32 v124, v112, v113
	v_bfe_u32 v125, v114, 16, 1
	v_add3_u32 v125, v114, v125, s89
	v_bfe_u32 v138, v115, 16, 1
	v_lshrrev_b32_e32 v125, 16, v125
	v_add3_u32 v138, v115, v138, s89
	v_and_or_b32 v125, v138, s91, v125
	global_store_dwordx4 v[126:127], v[122:125], off offset:256
	s_and_saveexec_b64 s[72:73], s[48:49]
	s_cbranch_execz .LBB0_2092
	v_readlane_b32 s4, v250, 58
	v_readlane_b32 s5, v250, 59
	v_lshlrev_b64 v[158:159], 2, v[120:121]
	s_nop 0
	v_lshl_add_u64 v[122:123], s[4:5], 0, v[156:157]
	v_lshl_add_u64 v[122:123], v[122:123], 0, v[158:159]
	global_store_dwordx4 v[122:123], v[116:119], off offset:512
	global_store_dwordx4 v[122:123], v[112:115], off offset:528
	v_mov_b32_dpp v122, v116 quad_perm:[0,0,0,0] row_mask:0xf bank_mask:0xf bound_ctrl:1
	v_add_f32_e32 v122, 0, v122
	v_cndmask_b32_e64 v122, 0, v122, s[40:41]
	v_readlane_b32 s4, v250, 12
	v_readlane_b32 s16, v250, 24
	v_add_f32_dpp v123, v116, v122 quad_perm:[1,1,1,1] row_mask:0xf bank_mask:0xf bound_ctrl:1
	v_cndmask_b32_e64 v122, v122, v123, s[44:45]
	v_readlane_b32 s17, v250, 25
	v_readlane_b32 s5, v250, 13
	v_add_f32_dpp v123, v116, v122 quad_perm:[2,2,2,2] row_mask:0xf bank_mask:0xf bound_ctrl:1
	v_cndmask_b32_e64 v122, v122, v123, s[42:43]
	v_lshl_add_u64 v[158:159], s[16:17], 0, v[158:159]
	v_lshl_add_u64 v[154:155], v[158:159], 0, v[154:155]
	v_add_f32_dpp v123, v116, v122 quad_perm:[3,3,3,3] row_mask:0xf bank_mask:0xf bound_ctrl:1
	v_cndmask_b32_e64 v122, v122, v123, s[0:1]
	v_readlane_b32 s6, v250, 14
	v_mov_b32_dpp v123, v117 quad_perm:[0,0,0,0] row_mask:0xf bank_mask:0xf bound_ctrl:1
	v_add_f32_e32 v123, 0, v123
	v_cndmask_b32_e64 v123, 0, v123, s[40:41]
	v_readlane_b32 s7, v250, 15
	v_readlane_b32 s8, v250, 16
	v_add_f32_dpp v124, v117, v123 quad_perm:[1,1,1,1] row_mask:0xf bank_mask:0xf bound_ctrl:1
	v_cndmask_b32_e64 v123, v123, v124, s[44:45]
	v_readlane_b32 s9, v250, 17
	v_readlane_b32 s10, v250, 18
	v_add_f32_dpp v124, v117, v123 quad_perm:[2,2,2,2] row_mask:0xf bank_mask:0xf bound_ctrl:1
	v_cndmask_b32_e64 v123, v123, v124, s[42:43]
	v_readlane_b32 s11, v250, 19
	v_readlane_b32 s12, v250, 20
	v_add_f32_dpp v124, v117, v123 quad_perm:[3,3,3,3] row_mask:0xf bank_mask:0xf bound_ctrl:1
	v_cndmask_b32_e64 v123, v123, v124, s[0:1]
	v_readlane_b32 s13, v250, 21
	v_mov_b32_dpp v124, v118 quad_perm:[0,0,0,0] row_mask:0xf bank_mask:0xf bound_ctrl:1
	v_add_f32_e32 v124, 0, v124
	v_cndmask_b32_e64 v124, 0, v124, s[40:41]
	v_readlane_b32 s14, v250, 22
	v_readlane_b32 s15, v250, 23
	v_add_f32_dpp v125, v118, v124 quad_perm:[1,1,1,1] row_mask:0xf bank_mask:0xf bound_ctrl:1
	v_cndmask_b32_e64 v124, v124, v125, s[44:45]
	v_readlane_b32 s18, v250, 26
	v_readlane_b32 s19, v250, 27
	v_add_f32_dpp v125, v118, v124 quad_perm:[2,2,2,2] row_mask:0xf bank_mask:0xf bound_ctrl:1
	v_cndmask_b32_e64 v124, v124, v125, s[42:43]
	s_nop 1
	v_add_f32_dpp v125, v118, v124 quad_perm:[3,3,3,3] row_mask:0xf bank_mask:0xf bound_ctrl:1
	v_cndmask_b32_e64 v124, v124, v125, s[0:1]
	s_nop 0
	v_mov_b32_dpp v125, v119 quad_perm:[0,0,0,0] row_mask:0xf bank_mask:0xf bound_ctrl:1
	v_add_f32_e32 v125, 0, v125
	v_cndmask_b32_e64 v125, 0, v125, s[40:41]
	s_nop 1
	v_add_f32_dpp v126, v119, v125 quad_perm:[1,1,1,1] row_mask:0xf bank_mask:0xf bound_ctrl:1
	v_cndmask_b32_e64 v125, v125, v126, s[44:45]
	s_nop 1
	v_add_f32_dpp v126, v119, v125 quad_perm:[2,2,2,2] row_mask:0xf bank_mask:0xf bound_ctrl:1
	v_cndmask_b32_e64 v125, v125, v126, s[42:43]
	s_nop 1
	v_add_f32_dpp v126, v119, v125 quad_perm:[3,3,3,3] row_mask:0xf bank_mask:0xf bound_ctrl:1
	v_cndmask_b32_e64 v125, v125, v126, s[0:1]
	s_nop 0
	v_mov_b32_dpp v126, v112 quad_perm:[0,0,0,0] row_mask:0xf bank_mask:0xf bound_ctrl:1
	v_add_f32_e32 v126, 0, v126
	v_cndmask_b32_e64 v126, 0, v126, s[40:41]
	s_nop 1
	v_add_f32_dpp v127, v112, v126 quad_perm:[1,1,1,1] row_mask:0xf bank_mask:0xf bound_ctrl:1
	v_cndmask_b32_e64 v126, v126, v127, s[44:45]
	s_nop 1
	v_add_f32_dpp v127, v112, v126 quad_perm:[2,2,2,2] row_mask:0xf bank_mask:0xf bound_ctrl:1
	v_cndmask_b32_e64 v126, v126, v127, s[42:43]
	s_nop 1
	v_add_f32_dpp v127, v112, v126 quad_perm:[3,3,3,3] row_mask:0xf bank_mask:0xf bound_ctrl:1
	v_cndmask_b32_e64 v126, v126, v127, s[0:1]
	s_nop 0
	v_mov_b32_dpp v127, v113 quad_perm:[0,0,0,0] row_mask:0xf bank_mask:0xf bound_ctrl:1
	v_add_f32_e32 v127, 0, v127
	v_cndmask_b32_e64 v127, 0, v127, s[40:41]
	s_nop 1
	v_add_f32_dpp v138, v113, v127 quad_perm:[1,1,1,1] row_mask:0xf bank_mask:0xf bound_ctrl:1
	v_cndmask_b32_e64 v127, v127, v138, s[44:45]
	s_nop 1
	v_add_f32_dpp v138, v113, v127 quad_perm:[2,2,2,2] row_mask:0xf bank_mask:0xf bound_ctrl:1
	v_cndmask_b32_e64 v127, v127, v138, s[42:43]
	s_nop 1
	v_add_f32_dpp v138, v113, v127 quad_perm:[3,3,3,3] row_mask:0xf bank_mask:0xf bound_ctrl:1
	v_cndmask_b32_e64 v127, v127, v138, s[0:1]
	s_nop 0
	v_mov_b32_dpp v138, v114 quad_perm:[0,0,0,0] row_mask:0xf bank_mask:0xf bound_ctrl:1
	v_add_f32_e32 v138, 0, v138
	v_cndmask_b32_e64 v138, 0, v138, s[40:41]
	s_nop 1
	v_add_f32_dpp v151, v114, v138 quad_perm:[1,1,1,1] row_mask:0xf bank_mask:0xf bound_ctrl:1
	v_cndmask_b32_e64 v138, v138, v151, s[44:45]
	s_nop 1
	v_add_f32_dpp v151, v114, v138 quad_perm:[2,2,2,2] row_mask:0xf bank_mask:0xf bound_ctrl:1
	v_cndmask_b32_e64 v138, v138, v151, s[42:43]
	s_nop 1
	v_add_f32_dpp v151, v114, v138 quad_perm:[3,3,3,3] row_mask:0xf bank_mask:0xf bound_ctrl:1
	v_cndmask_b32_e64 v156, v138, v151, s[0:1]
	v_mov_b32_dpp v138, v115 quad_perm:[0,0,0,0] row_mask:0xf bank_mask:0xf bound_ctrl:1
	v_add_f32_e32 v138, 0, v138
	v_cndmask_b32_e64 v138, 0, v138, s[40:41]
	s_nop 1
	v_add_f32_dpp v151, v115, v138 quad_perm:[1,1,1,1] row_mask:0xf bank_mask:0xf bound_ctrl:1
	v_cndmask_b32_e64 v138, v138, v151, s[44:45]
	s_nop 1
	v_add_f32_dpp v151, v115, v138 quad_perm:[2,2,2,2] row_mask:0xf bank_mask:0xf bound_ctrl:1
	v_cndmask_b32_e64 v138, v138, v151, s[42:43]
	s_nop 1
	v_add_f32_dpp v151, v115, v138 quad_perm:[3,3,3,3] row_mask:0xf bank_mask:0xf bound_ctrl:1
	v_cndmask_b32_e64 v157, v138, v151, s[0:1]
	s_and_saveexec_b64 s[48:49], s[38:39]
	s_cbranch_execz .LBB0_2418
	global_load_dwordx4 v[158:161], v[154:155], off offset:528
	global_load_dwordx4 v[162:165], v[154:155], off offset:512
	s_waitcnt vmcnt(0)
	v_pk_add_f32 v[126:127], v[126:127], v[158:159]
	v_pk_add_f32 v[156:157], v[156:157], v[160:161]
	v_pk_add_f32 v[124:125], v[124:125], v[164:165]
	v_pk_add_f32 v[122:123], v[122:123], v[162:163]
	s_or_b64 exec, exec, s[48:49]
	s_and_saveexec_b64 s[48:49], s[36:37]
	s_cbranch_execnz .LBB0_2419

; __device__ __forceinline__ void st8bf(bf16_t* p, f32x4 a, f32x4 b) { u32x4 w; w.x = pk2(a[0], a[1]); w.y = pk2(a[2], a[3]); w.z = pk2(b[0], b[1]); w.w = pk2(b[2], b[3]); st16(p, w); }
;     __device__ __forceinline__ void st(int pn, int row, int c, f32x4 v0, f32x4 v1) const {
;     ...
;                 const float inv = 1.f / (float)w;
;                 st8bf(DMs + (size_t)row * 1024 + col, (f32x4){s[0] * inv - x[0], s[1] * inv - x[1], s[2] * inv - x[2], s[3] * inv - x[3]}, (f32x4){s[4] * inv - x[4], s[5] * inv - x[5], s[6] * inv - x[6], s[7] * inv - x[7]});
.LBB0_2091:
	s_or_b64 exec, exec, s[48:49]
	v_readlane_b32 s4, v251, 0
	v_readlane_b32 s5, v251, 1
	v_mov_b32_e32 v155, v118
	v_mov_b32_e32 v118, v117
	v_lshl_add_u64 v[152:153], v[152:153], 1, s[4:5]
	v_lshl_add_u64 v[120:121], v[120:121], 1, v[152:153]
	v_mov_b32_e32 v153, v124
	v_mov_b32_e32 v124, v123
	v_mov_b32_e32 v154, v116
	v_pk_fma_f32 v[116:117], s[68:69], v[124:125], v[118:119] op_sel_hi:[0,1,1] neg_lo:[0,0,1] neg_hi:[0,0,1]
	v_mov_b32_e32 v119, v156
	v_mov_b32_e32 v123, v114
	v_mov_b32_e32 v156, v127
	v_mov_b32_e32 v114, v113
	v_mov_b32_e32 v152, v122
	v_mov_b32_e32 v118, v126
	v_mov_b32_e32 v122, v112
	v_pk_fma_f32 v[112:113], s[68:69], v[156:157], v[114:115] op_sel_hi:[0,1,1] neg_lo:[0,0,1] neg_hi:[0,0,1]
	v_pk_fma_f32 v[152:153], s[68:69], v[152:153], v[154:155] op_sel_hi:[0,1,1] neg_lo:[0,0,1] neg_hi:[0,0,1]
	v_pk_fma_f32 v[118:119], s[68:69], v[118:119], v[122:123] op_sel_hi:[0,1,1] neg_lo:[0,0,1] neg_hi:[0,0,1]
	v_cvt_pk_bf16_f32 v115, v119, v113
	v_cvt_pk_bf16_f32 v114, v118, v112
	v_cvt_pk_bf16_f32 v113, v153, v117
	v_cvt_pk_bf16_f32 v112, v152, v116
	global_store_dwordx4 v[120:121], v[112:115], off offset:256

; __device__ __forceinline__ void st16f(float* p, f32x4 v) { st16(p, __builtin_bit_cast(u32x4, v)); }
; __device__ __forceinline__ void st8bf(bf16_t* p, f32x4 a, f32x4 b) { u32x4 w; w.x = pk2(a[0], a[1]); w.y = pk2(a[2], a[3]); w.z = pk2(b[0], b[1]); w.w = pk2(b[2], b[3]); st16(p, w); }
; __device__ __forceinline__ f32x4 sig4(f32x4 v) { f32x4 r; r[0] = sigmoidf_(v[0]); r[1] = sigmoidf_(v[1]); r[2] = sigmoidf_(v[2]); r[3] = sigmoidf_(v[3]); return r; }
;     __device__ __forceinline__ void st(int pn, int row, int c, f32x4 v0, f32x4 v1) const {
;         const bool smp = row >= MP; const int b = smp ? (row - MP) >> 2 : row >> 13, t = smp ? (row - MP) & 3 : row & (SEQ - 1);
;         if (pn < 4) { const int col = pn * 256 + c; float* o = nullptr;
;             if (smp) o = out + O_POOLS + ((size_t)b * 15 + 11 + t) * 1024 + col;
;             st8bf(V + (size_t)row * 1024 + col, v0, v1); if (o) { st16f(o, v0); st16f(o + 4, v1); }
;             if (smp) {
;                 const int w = 2 << pn;
;                 float x[8] = {v0[0], v0[1], v0[2], v0[3], v1[0], v1[1], v1[2], v1[3]}, s[8];
; #pragma unroll
;                 for (int e = 0; e < 8; ++e) { s[e] = 0.f;
; #pragma unroll
;                     for (int tp = 0; tp < 4; ++tp) { const float xo = quad_bcast(x[e], tp); if (tp <= t && t - tp < w) s[e] += xo; } }
;                 const int e_lo = 15 + t - w + 1;
; #pragma unroll
;                 for (int e2 = 0; e2 < 15; ++e2) if (e2 >= e_lo) { const float* sp = state_pool + ((size_t)b * 15 + e2) * 1024 + col; const f32x4 a = *(const f32x4*)sp, d = *(const f32x4*)(sp + 4);
;                     s[0] += a[0]; s[1] += a[1]; s[2] += a[2]; s[3] += a[3]; s[4] += d[0]; s[5] += d[1]; s[6] += d[2]; s[7] += d[3]; }
;                 const float inv = 1.f / (float)w;
;                 st8bf(DMs + (size_t)row * 1024 + col, (f32x4){s[0] * inv - x[0], s[1] * inv - x[1], s[2] * inv - x[2], s[3] * inv - x[3]}, (f32x4){s[4] * inv - x[4], s[5] * inv - x[5], s[6] * inv - x[6], s[7] * inv - x[7]});
;             } }
;         else st8bf(GT + (size_t)row * 1024 + (pn - 4) * 256 + c, v0 * sig4(v0), v1 * sig4(v1));
.LBB0_2093:
	s_nop 0
	v_or_b32_e32 v112, 16, v150
	v_ashrrev_i32_e32 v113, 31, v112
	v_cmp_lt_i32_e64 s[48:49], s89, v112
	v_lshlrev_b64 v[118:119], 11, v[112:113]
	s_and_b64 vcc, exec, s[46:47]
	s_mov_b64 s[72:73], -1
	s_cbranch_vccnz .LBB0_2095
	v_lshl_add_u64 v[114:115], s[54:55], 0, v[118:119]
	v_mul_f32_e32 v116, 0xbfb8aa3b, v108
	v_exp_f32_e32 v116, v116
	v_lshl_add_u64 v[114:115], s[60:61], 1, v[114:115]
	v_lshlrev_b32_e32 v138, 1, v140
	v_lshl_add_u64 v[120:121], v[114:115], 0, v[138:139]
	v_mul_f32_e32 v115, 0xbfb8aa3b, v109
	v_exp_f32_e32 v115, v115
	v_add_f32_e32 v114, 1.0, v116
	v_mul_f32_e32 v116, 0xbfb8aa3b, v110
	v_mul_f32_e32 v117, 0xbfb8aa3b, v111
	v_exp_f32_e32 v116, v116
	v_exp_f32_e32 v117, v117
	v_add_f32_e32 v115, 1.0, v115
	v_rcp_f32_e32 v114, v114
	v_rcp_f32_e32 v115, v115
	v_mul_f32_e32 v122, 0xbfb8aa3b, v104
	v_mul_f32_e32 v123, 0xbfb8aa3b, v105
	v_exp_f32_e32 v122, v122
	v_exp_f32_e32 v123, v123
	v_add_f32_e32 v116, 1.0, v116
	v_add_f32_e32 v117, 1.0, v117
	v_rcp_f32_e32 v116, v116
	v_rcp_f32_e32 v117, v117
	v_mul_f32_e32 v124, 0xbfb8aa3b, v106
	v_mul_f32_e32 v125, 0xbfb8aa3b, v107
	v_exp_f32_e32 v124, v124
	v_exp_f32_e32 v125, v125
	v_pk_mul_f32 v[114:115], v[108:109], v[114:115]
	v_add_f32_e32 v122, 1.0, v122
	v_add_f32_e32 v123, 1.0, v123
	v_rcp_f32_e32 v122, v122
	v_rcp_f32_e32 v123, v123
	v_pk_mul_f32 v[116:117], v[110:111], v[116:117]
	v_add_f32_e32 v124, 1.0, v124
	v_add_f32_e32 v125, 1.0, v125
	v_cvt_pk_bf16_f32 v114, v114, v115
	v_rcp_f32_e32 v124, v124
	v_rcp_f32_e32 v125, v125
	v_pk_mul_f32 v[122:123], v[104:105], v[122:123]
	v_cvt_pk_bf16_f32 v115, v116, v117
	v_pk_mul_f32 v[124:125], v[106:107], v[124:125]
	v_cvt_pk_bf16_f32 v116, v122, v123
	v_cvt_pk_bf16_f32 v117, v124, v125
	s_mov_b64 s[72:73], 0
	global_store_dwordx4 v[120:121], v[114:117], off
.LBB0_2095:
	s_nop 1
	v_add_u32_e32 v114, 0xffff8010, v150
	v_lshrrev_b32_e32 v120, 2, v114
	v_mad_u64_u32 v[114:115], s[74:75], v120, 15, v[128:129]
	v_lshlrev_b64 v[116:117], 12, v[114:115]
	v_lshlrev_b64 v[112:113], 10, v[112:113]
	s_andn2_b64 vcc, exec, s[72:73]
	v_mad_u64_u32 v[114:115], s[72:73], v120, s90, 0
	s_cbranch_vccnz .LBB0_2116
	v_or_b32_e32 v120, s70, v140
	v_ashrrev_i32_e32 v121, 31, v120
	v_lshl_add_u64 v[122:123], v[112:113], 1, s[52:53]
	v_lshl_add_u64 v[126:127], v[120:121], 1, v[122:123]
	v_cvt_pk_bf16_f32 v122, v108, v109
	v_cvt_pk_bf16_f32 v123, v110, v111
	v_cvt_pk_bf16_f32 v124, v104, v105
	v_bfe_u32 v125, v106, 16, 1
	v_add3_u32 v125, v106, v125, s89
	v_bfe_u32 v138, v107, 16, 1
	v_lshrrev_b32_e32 v125, 16, v125
	v_add3_u32 v138, v107, v138, s89
	v_and_or_b32 v125, v138, s91, v125
	global_store_dwordx4 v[126:127], v[122:125], off
	s_and_saveexec_b64 s[72:73], s[48:49]
	s_cbranch_execz .LBB0_2114
;     __device__ __forceinline__ void st(int pn, int row, int c, f32x4 v0, f32x4 v1) const {
;     ...
;             if (smp) {
;                 const int w = 2 << pn;
;                 float x[8] = {v0[0], v0[1], v0[2], v0[3], v1[0], v1[1], v1[2], v1[3]}, s[8];
; #pragma unroll
;                 for (int e = 0; e < 8; ++e) { s[e] = 0.f;
; #pragma unroll
;                     for (int tp = 0; tp < 4; ++tp) { const float xo = quad_bcast(x[e], tp); if (tp <= t && t - tp < w) s[e] += xo; } }
;                 const int e_lo = 15 + t - w + 1;
; #pragma unroll
;                 for (int e2 = 0; e2 < 15; ++e2) if (e2 >= e_lo) { const float* sp = state_pool + ((size_t)b * 15 + e2) * 1024 + col; const f32x4 a = *(const f32x4*)sp, d = *(const f32x4*)(sp + 4);
;                     s[0] += a[0]; s[1] += a[1]; s[2] += a[2]; s[3] += a[3]; s[4] += d[0]; s[5] += d[1]; s[6] += d[2]; s[7] += d[3]; }
	v_readlane_b32 s4, v250, 58
	v_readlane_b32 s5, v250, 59
	v_lshlrev_b64 v[154:155], 2, v[120:121]
	s_nop 0
	v_lshl_add_u64 v[122:123], s[4:5], 0, v[116:117]
	v_lshl_add_u64 v[122:123], v[122:123], 0, v[154:155]
	global_store_dwordx4 v[122:123], v[108:111], off
	global_store_dwordx4 v[122:123], v[104:107], off offset:16
	v_mov_b32_dpp v122, v108 quad_perm:[0,0,0,0] row_mask:0xf bank_mask:0xf bound_ctrl:1
	v_add_f32_e32 v122, 0, v122
	v_cndmask_b32_e64 v122, 0, v122, s[40:41]
	v_readlane_b32 s4, v250, 12
	v_readlane_b32 s16, v250, 24
	v_add_f32_dpp v123, v108, v122 quad_perm:[1,1,1,1] row_mask:0xf bank_mask:0xf bound_ctrl:1
	v_cndmask_b32_e64 v122, v122, v123, s[44:45]
	v_readlane_b32 s17, v250, 25
	v_readlane_b32 s5, v250, 13
	v_add_f32_dpp v123, v108, v122 quad_perm:[2,2,2,2] row_mask:0xf bank_mask:0xf bound_ctrl:1
	v_cndmask_b32_e64 v122, v122, v123, s[42:43]
	v_lshl_add_u64 v[154:155], s[16:17], 0, v[154:155]
	v_lshl_add_u64 v[154:155], v[154:155], 0, v[114:115]
	v_add_f32_dpp v123, v108, v122 quad_perm:[3,3,3,3] row_mask:0xf bank_mask:0xf bound_ctrl:1
	v_cndmask_b32_e64 v122, v122, v123, s[0:1]
	v_readlane_b32 s6, v250, 14
	v_mov_b32_dpp v123, v109 quad_perm:[0,0,0,0] row_mask:0xf bank_mask:0xf bound_ctrl:1
	v_add_f32_e32 v123, 0, v123
	v_cndmask_b32_e64 v123, 0, v123, s[40:41]
	v_readlane_b32 s7, v250, 15
	v_readlane_b32 s8, v250, 16
	v_add_f32_dpp v124, v109, v123 quad_perm:[1,1,1,1] row_mask:0xf bank_mask:0xf bound_ctrl:1
	v_cndmask_b32_e64 v123, v123, v124, s[44:45]
	v_readlane_b32 s9, v250, 17
	v_readlane_b32 s10, v250, 18
	v_add_f32_dpp v124, v109, v123 quad_perm:[2,2,2,2] row_mask:0xf bank_mask:0xf bound_ctrl:1
	v_cndmask_b32_e64 v123, v123, v124, s[42:43]
	v_readlane_b32 s11, v250, 19
	v_readlane_b32 s12, v250, 20
	v_add_f32_dpp v124, v109, v123 quad_perm:[3,3,3,3] row_mask:0xf bank_mask:0xf bound_ctrl:1
	v_cndmask_b32_e64 v123, v123, v124, s[0:1]
	v_readlane_b32 s13, v250, 21
	v_mov_b32_dpp v124, v110 quad_perm:[0,0,0,0] row_mask:0xf bank_mask:0xf bound_ctrl:1
	v_add_f32_e32 v124, 0, v124
	v_cndmask_b32_e64 v124, 0, v124, s[40:41]
	v_readlane_b32 s14, v250, 22
	v_readlane_b32 s15, v250, 23
	v_add_f32_dpp v125, v110, v124 quad_perm:[1,1,1,1] row_mask:0xf bank_mask:0xf bound_ctrl:1
	v_cndmask_b32_e64 v124, v124, v125, s[44:45]
	v_readlane_b32 s18, v250, 26
	v_readlane_b32 s19, v250, 27
	v_add_f32_dpp v125, v110, v124 quad_perm:[2,2,2,2] row_mask:0xf bank_mask:0xf bound_ctrl:1
	v_cndmask_b32_e64 v124, v124, v125, s[42:43]
	s_nop 1
	v_add_f32_dpp v125, v110, v124 quad_perm:[3,3,3,3] row_mask:0xf bank_mask:0xf bound_ctrl:1
	v_cndmask_b32_e64 v124, v124, v125, s[0:1]
	s_nop 0
	v_mov_b32_dpp v125, v111 quad_perm:[0,0,0,0] row_mask:0xf bank_mask:0xf bound_ctrl:1
	v_add_f32_e32 v125, 0, v125
	v_cndmask_b32_e64 v125, 0, v125, s[40:41]
	s_nop 1
	v_add_f32_dpp v126, v111, v125 quad_perm:[1,1,1,1] row_mask:0xf bank_mask:0xf bound_ctrl:1
	v_cndmask_b32_e64 v125, v125, v126, s[44:45]
	s_nop 1
	v_add_f32_dpp v126, v111, v125 quad_perm:[2,2,2,2] row_mask:0xf bank_mask:0xf bound_ctrl:1
	v_cndmask_b32_e64 v125, v125, v126, s[42:43]
	s_nop 1
	v_add_f32_dpp v126, v111, v125 quad_perm:[3,3,3,3] row_mask:0xf bank_mask:0xf bound_ctrl:1
	v_cndmask_b32_e64 v125, v125, v126, s[0:1]
	s_nop 0
	v_mov_b32_dpp v126, v104 quad_perm:[0,0,0,0] row_mask:0xf bank_mask:0xf bound_ctrl:1
	v_add_f32_e32 v126, 0, v126
	v_cndmask_b32_e64 v126, 0, v126, s[40:41]
	s_nop 1
	v_add_f32_dpp v127, v104, v126 quad_perm:[1,1,1,1] row_mask:0xf bank_mask:0xf bound_ctrl:1
	v_cndmask_b32_e64 v126, v126, v127, s[44:45]
	s_nop 1
	v_add_f32_dpp v127, v104, v126 quad_perm:[2,2,2,2] row_mask:0xf bank_mask:0xf bound_ctrl:1
	v_cndmask_b32_e64 v126, v126, v127, s[42:43]
	s_nop 1
	v_add_f32_dpp v127, v104, v126 quad_perm:[3,3,3,3] row_mask:0xf bank_mask:0xf bound_ctrl:1
	v_cndmask_b32_e64 v126, v126, v127, s[0:1]
	s_nop 0
	v_mov_b32_dpp v127, v105 quad_perm:[0,0,0,0] row_mask:0xf bank_mask:0xf bound_ctrl:1
	v_add_f32_e32 v127, 0, v127
	v_cndmask_b32_e64 v127, 0, v127, s[40:41]
	s_nop 1
	v_add_f32_dpp v138, v105, v127 quad_perm:[1,1,1,1] row_mask:0xf bank_mask:0xf bound_ctrl:1
	v_cndmask_b32_e64 v127, v127, v138, s[44:45]
	s_nop 1
	v_add_f32_dpp v138, v105, v127 quad_perm:[2,2,2,2] row_mask:0xf bank_mask:0xf bound_ctrl:1
	v_cndmask_b32_e64 v127, v127, v138, s[42:43]
	s_nop 1
	v_add_f32_dpp v138, v105, v127 quad_perm:[3,3,3,3] row_mask:0xf bank_mask:0xf bound_ctrl:1
	v_cndmask_b32_e64 v127, v127, v138, s[0:1]
	s_nop 0
	v_mov_b32_dpp v138, v106 quad_perm:[0,0,0,0] row_mask:0xf bank_mask:0xf bound_ctrl:1
	v_add_f32_e32 v138, 0, v138
	v_cndmask_b32_e64 v138, 0, v138, s[40:41]
	s_nop 1
	v_add_f32_dpp v151, v106, v138 quad_perm:[1,1,1,1] row_mask:0xf bank_mask:0xf bound_ctrl:1
	v_cndmask_b32_e64 v138, v138, v151, s[44:45]
	s_nop 1
	v_add_f32_dpp v151, v106, v138 quad_perm:[2,2,2,2] row_mask:0xf bank_mask:0xf bound_ctrl:1
	v_cndmask_b32_e64 v138, v138, v151, s[42:43]
	s_nop 1
	v_add_f32_dpp v151, v106, v138 quad_perm:[3,3,3,3] row_mask:0xf bank_mask:0xf bound_ctrl:1
	v_cndmask_b32_e64 v152, v138, v151, s[0:1]
	v_mov_b32_dpp v138, v107 quad_perm:[0,0,0,0] row_mask:0xf bank_mask:0xf bound_ctrl:1
	v_add_f32_e32 v138, 0, v138
	v_cndmask_b32_e64 v138, 0, v138, s[40:41]
	s_nop 1
	v_add_f32_dpp v151, v107, v138 quad_perm:[1,1,1,1] row_mask:0xf bank_mask:0xf bound_ctrl:1
	v_cndmask_b32_e64 v138, v138, v151, s[44:45]
	s_nop 1
	v_add_f32_dpp v151, v107, v138 quad_perm:[2,2,2,2] row_mask:0xf bank_mask:0xf bound_ctrl:1
	v_cndmask_b32_e64 v138, v138, v151, s[42:43]
	s_nop 1
	v_add_f32_dpp v151, v107, v138 quad_perm:[3,3,3,3] row_mask:0xf bank_mask:0xf bound_ctrl:1
	v_cndmask_b32_e64 v153, v138, v151, s[0:1]
	s_and_saveexec_b64 s[74:75], s[38:39]
	s_cbranch_execz .LBB0_2432
	global_load_dwordx4 v[156:159], v[154:155], off offset:16
	global_load_dwordx4 v[160:163], v[154:155], off
	s_waitcnt vmcnt(0)
	v_pk_add_f32 v[126:127], v[126:127], v[156:157]
	v_pk_add_f32 v[152:153], v[152:153], v[158:159]
	v_pk_add_f32 v[124:125], v[124:125], v[162:163]
	v_pk_add_f32 v[122:123], v[122:123], v[160:161]
	s_or_b64 exec, exec, s[74:75]
	s_and_saveexec_b64 s[74:75], s[36:37]
	s_cbranch_execnz .LBB0_2433

; __device__ __forceinline__ void st8bf(bf16_t* p, f32x4 a, f32x4 b) { u32x4 w; w.x = pk2(a[0], a[1]); w.y = pk2(a[2], a[3]); w.z = pk2(b[0], b[1]); w.w = pk2(b[2], b[3]); st16(p, w); }
;     __device__ __forceinline__ void st(int pn, int row, int c, f32x4 v0, f32x4 v1) const {
;     ...
;                 const float inv = 1.f / (float)w;
;                 st8bf(DMs + (size_t)row * 1024 + col, (f32x4){s[0] * inv - x[0], s[1] * inv - x[1], s[2] * inv - x[2], s[3] * inv - x[3]}, (f32x4){s[4] * inv - x[4], s[5] * inv - x[5], s[6] * inv - x[6], s[7] * inv - x[7]});
.LBB0_2113:
	s_or_b64 exec, exec, s[74:75]
	v_readlane_b32 s4, v251, 0
	v_readlane_b32 s5, v251, 1
	v_mov_b32_e32 v157, v110
	v_mov_b32_e32 v110, v109
	v_lshl_add_u64 v[154:155], v[112:113], 1, s[4:5]
	v_lshl_add_u64 v[120:121], v[120:121], 1, v[154:155]
	v_mov_b32_e32 v155, v124
	v_mov_b32_e32 v124, v123
	v_mov_b32_e32 v156, v108
	v_pk_fma_f32 v[108:109], s[68:69], v[124:125], v[110:111] op_sel_hi:[0,1,1] neg_lo:[0,0,1] neg_hi:[0,0,1]
	v_mov_b32_e32 v111, v152
	v_mov_b32_e32 v123, v106
	v_mov_b32_e32 v152, v127
	v_mov_b32_e32 v106, v105
	v_mov_b32_e32 v154, v122
	v_mov_b32_e32 v110, v126
	v_mov_b32_e32 v122, v104
	v_pk_fma_f32 v[104:105], s[68:69], v[152:153], v[106:107] op_sel_hi:[0,1,1] neg_lo:[0,0,1] neg_hi:[0,0,1]
	v_pk_fma_f32 v[154:155], s[68:69], v[154:155], v[156:157] op_sel_hi:[0,1,1] neg_lo:[0,0,1] neg_hi:[0,0,1]
	v_pk_fma_f32 v[110:111], s[68:69], v[110:111], v[122:123] op_sel_hi:[0,1,1] neg_lo:[0,0,1] neg_hi:[0,0,1]
	v_cvt_pk_bf16_f32 v107, v111, v105
	v_cvt_pk_bf16_f32 v106, v110, v104
	v_cvt_pk_bf16_f32 v105, v155, v109
	v_cvt_pk_bf16_f32 v104, v154, v108
	global_store_dwordx4 v[120:121], v[104:107], off

; __device__ __forceinline__ void st8bf(bf16_t* p, f32x4 a, f32x4 b) { u32x4 w; w.x = pk2(a[0], a[1]); w.y = pk2(a[2], a[3]); w.z = pk2(b[0], b[1]); w.w = pk2(b[2], b[3]); st16(p, w); }
; __device__ __forceinline__ f32x4 sig4(f32x4 v) { f32x4 r; r[0] = sigmoidf_(v[0]); r[1] = sigmoidf_(v[1]); r[2] = sigmoidf_(v[2]); r[3] = sigmoidf_(v[3]); return r; }
;     __device__ __forceinline__ void st(int pn, int row, int c, f32x4 v0, f32x4 v1) const {
;     ...
;         else st8bf(GT + (size_t)row * 1024 + (pn - 4) * 256 + c, v0 * sig4(v0), v1 * sig4(v1));
.LBB0_2117:
	v_lshl_add_u64 v[104:105], s[54:55], 0, v[118:119]
	v_mul_f32_e32 v106, 0xbfb8aa3b, v100
	v_exp_f32_e32 v106, v106
	v_lshl_add_u64 v[104:105], s[60:61], 1, v[104:105]
	v_lshlrev_b32_e32 v138, 1, v140
	v_lshl_add_u64 v[108:109], v[104:105], 0, v[138:139]
	v_mul_f32_e32 v105, 0xbfb8aa3b, v101
	v_exp_f32_e32 v105, v105
	v_add_f32_e32 v104, 1.0, v106
	v_mul_f32_e32 v106, 0xbfb8aa3b, v102
	v_mul_f32_e32 v107, 0xbfb8aa3b, v103
	v_exp_f32_e32 v106, v106
	v_exp_f32_e32 v107, v107
	v_add_f32_e32 v105, 1.0, v105
	v_rcp_f32_e32 v104, v104
	v_rcp_f32_e32 v105, v105
	v_mul_f32_e32 v110, 0xbfb8aa3b, v96
	v_mul_f32_e32 v111, 0xbfb8aa3b, v97
	v_exp_f32_e32 v110, v110
	v_exp_f32_e32 v111, v111
	v_add_f32_e32 v106, 1.0, v106
	v_add_f32_e32 v107, 1.0, v107
	v_rcp_f32_e32 v106, v106
	v_rcp_f32_e32 v107, v107
	v_mul_f32_e32 v118, 0xbfb8aa3b, v98
	v_mul_f32_e32 v119, 0xbfb8aa3b, v99
	v_exp_f32_e32 v118, v118
	v_exp_f32_e32 v119, v119
	v_pk_mul_f32 v[104:105], v[100:101], v[104:105]
	v_add_f32_e32 v110, 1.0, v110
	v_add_f32_e32 v111, 1.0, v111
	v_bfe_u32 v120, v104, 16, 1
	v_rcp_f32_e32 v110, v110
	v_rcp_f32_e32 v111, v111
	v_add3_u32 v104, v104, v120, s89
	v_bfe_u32 v120, v105, 16, 1
	v_pk_mul_f32 v[106:107], v[102:103], v[106:107]
	v_lshrrev_b32_e32 v104, 16, v104
	v_add3_u32 v105, v105, v120, s89
	v_add_f32_e32 v118, 1.0, v118
	v_add_f32_e32 v119, 1.0, v119
	v_and_or_b32 v104, v105, s91, v104
	v_rcp_f32_e32 v118, v118
	v_rcp_f32_e32 v119, v119
	v_pk_mul_f32 v[110:111], v[96:97], v[110:111]
	v_cvt_pk_bf16_f32 v105, v106, v107
	v_pk_mul_f32 v[118:119], v[98:99], v[118:119]
	v_cvt_pk_bf16_f32 v106, v110, v111
	v_cvt_pk_bf16_f32 v107, v118, v119
	global_store_dwordx4 v[108:109], v[104:107], off offset:256
	s_cbranch_execnz .LBB0_2137
; __device__ __forceinline__ void st16f(float* p, f32x4 v) { st16(p, __builtin_bit_cast(u32x4, v)); }
; __device__ __forceinline__ void st8bf(bf16_t* p, f32x4 a, f32x4 b) { u32x4 w; w.x = pk2(a[0], a[1]); w.y = pk2(a[2], a[3]); w.z = pk2(b[0], b[1]); w.w = pk2(b[2], b[3]); st16(p, w); }
;     __device__ __forceinline__ void st(int pn, int row, int c, f32x4 v0, f32x4 v1) const {
;     ...
;         if (pn < 4) { const int col = pn * 256 + c; float* o = nullptr;
;             if (smp) o = out + O_POOLS + ((size_t)b * 15 + 11 + t) * 1024 + col;
;             st8bf(V + (size_t)row * 1024 + col, v0, v1); if (o) { st16f(o, v0); st16f(o + 4, v1); }
;             if (smp) {
;                 const int w = 2 << pn;
;                 float x[8] = {v0[0], v0[1], v0[2], v0[3], v1[0], v1[1], v1[2], v1[3]}, s[8];
; #pragma unroll
;                 for (int e = 0; e < 8; ++e) { s[e] = 0.f;
; #pragma unroll
;                     for (int tp = 0; tp < 4; ++tp) { const float xo = quad_bcast(x[e], tp); if (tp <= t && t - tp < w) s[e] += xo; } }
;                 const int e_lo = 15 + t - w + 1;
; #pragma unroll
;                 for (int e2 = 0; e2 < 15; ++e2) if (e2 >= e_lo) { const float* sp = state_pool + ((size_t)b * 15 + e2) * 1024 + col; const f32x4 a = *(const f32x4*)sp, d = *(const f32x4*)(sp + 4);
;                     s[0] += a[0]; s[1] += a[1]; s[2] += a[2]; s[3] += a[3]; s[4] += d[0]; s[5] += d[1]; s[6] += d[2]; s[7] += d[3]; }
.LBB0_2118:
	s_ashr_i32 s71, s70, 31
	v_lshl_add_u64 v[106:107], v[112:113], 1, s[52:53]
	v_lshl_add_u64 v[104:105], s[70:71], 0, v[140:141]
	v_lshl_add_u64 v[110:111], v[104:105], 1, v[106:107]
	v_cvt_pk_bf16_f32 v106, v100, v101
	v_cvt_pk_bf16_f32 v107, v102, v103
	v_cvt_pk_bf16_f32 v108, v96, v97
	v_cvt_pk_bf16_f32 v109, v98, v99
	global_store_dwordx4 v[110:111], v[106:109], off offset:256
	s_and_saveexec_b64 s[72:73], s[48:49]
	s_cbranch_execz .LBB0_2136
	v_readlane_b32 s4, v250, 58
	v_readlane_b32 s5, v250, 59
	v_lshlrev_b64 v[118:119], 2, v[104:105]
	s_nop 0
	v_lshl_add_u64 v[106:107], s[4:5], 0, v[116:117]
	v_lshl_add_u64 v[106:107], v[106:107], 0, v[118:119]
	global_store_dwordx4 v[106:107], v[100:103], off offset:512
	global_store_dwordx4 v[106:107], v[96:99], off offset:528
	v_mov_b32_dpp v106, v100 quad_perm:[0,0,0,0] row_mask:0xf bank_mask:0xf bound_ctrl:1
	v_add_f32_e32 v106, 0, v106
	v_cndmask_b32_e64 v106, 0, v106, s[40:41]
	v_readlane_b32 s4, v250, 12
	v_readlane_b32 s16, v250, 24
	v_add_f32_dpp v107, v100, v106 quad_perm:[1,1,1,1] row_mask:0xf bank_mask:0xf bound_ctrl:1
	v_cndmask_b32_e64 v106, v106, v107, s[44:45]
	v_readlane_b32 s17, v250, 25
	v_readlane_b32 s5, v250, 13
	v_add_f32_dpp v107, v100, v106 quad_perm:[2,2,2,2] row_mask:0xf bank_mask:0xf bound_ctrl:1
	v_cndmask_b32_e64 v106, v106, v107, s[42:43]
	v_lshl_add_u64 v[118:119], s[16:17], 0, v[118:119]
	v_lshl_add_u64 v[114:115], v[118:119], 0, v[114:115]
	v_add_f32_dpp v107, v100, v106 quad_perm:[3,3,3,3] row_mask:0xf bank_mask:0xf bound_ctrl:1
	v_cndmask_b32_e64 v106, v106, v107, s[0:1]
	v_readlane_b32 s6, v250, 14
	v_mov_b32_dpp v107, v101 quad_perm:[0,0,0,0] row_mask:0xf bank_mask:0xf bound_ctrl:1
	v_add_f32_e32 v107, 0, v107
	v_cndmask_b32_e64 v107, 0, v107, s[40:41]
	v_readlane_b32 s7, v250, 15
	v_readlane_b32 s8, v250, 16
	v_add_f32_dpp v108, v101, v107 quad_perm:[1,1,1,1] row_mask:0xf bank_mask:0xf bound_ctrl:1
	v_cndmask_b32_e64 v107, v107, v108, s[44:45]
	v_readlane_b32 s9, v250, 17
	v_readlane_b32 s10, v250, 18
	v_add_f32_dpp v108, v101, v107 quad_perm:[2,2,2,2] row_mask:0xf bank_mask:0xf bound_ctrl:1
	v_cndmask_b32_e64 v107, v107, v108, s[42:43]
	v_readlane_b32 s11, v250, 19
	v_readlane_b32 s12, v250, 20
	v_add_f32_dpp v108, v101, v107 quad_perm:[3,3,3,3] row_mask:0xf bank_mask:0xf bound_ctrl:1
	v_cndmask_b32_e64 v107, v107, v108, s[0:1]
	v_readlane_b32 s13, v250, 21
	v_mov_b32_dpp v108, v102 quad_perm:[0,0,0,0] row_mask:0xf bank_mask:0xf bound_ctrl:1
	v_add_f32_e32 v108, 0, v108
	v_cndmask_b32_e64 v108, 0, v108, s[40:41]
	v_readlane_b32 s14, v250, 22
	v_readlane_b32 s15, v250, 23
	v_add_f32_dpp v109, v102, v108 quad_perm:[1,1,1,1] row_mask:0xf bank_mask:0xf bound_ctrl:1
	v_cndmask_b32_e64 v108, v108, v109, s[44:45]
	v_readlane_b32 s18, v250, 26
	v_readlane_b32 s19, v250, 27
	v_add_f32_dpp v109, v102, v108 quad_perm:[2,2,2,2] row_mask:0xf bank_mask:0xf bound_ctrl:1
	v_cndmask_b32_e64 v108, v108, v109, s[42:43]
	s_nop 1
	v_add_f32_dpp v109, v102, v108 quad_perm:[3,3,3,3] row_mask:0xf bank_mask:0xf bound_ctrl:1
	v_cndmask_b32_e64 v108, v108, v109, s[0:1]
	s_nop 0
	v_mov_b32_dpp v109, v103 quad_perm:[0,0,0,0] row_mask:0xf bank_mask:0xf bound_ctrl:1
	v_add_f32_e32 v109, 0, v109
	v_cndmask_b32_e64 v109, 0, v109, s[40:41]
	s_nop 1
	v_add_f32_dpp v110, v103, v109 quad_perm:[1,1,1,1] row_mask:0xf bank_mask:0xf bound_ctrl:1
	v_cndmask_b32_e64 v109, v109, v110, s[44:45]
	s_nop 1
	v_add_f32_dpp v110, v103, v109 quad_perm:[2,2,2,2] row_mask:0xf bank_mask:0xf bound_ctrl:1
	v_cndmask_b32_e64 v109, v109, v110, s[42:43]
	s_nop 1
	v_add_f32_dpp v110, v103, v109 quad_perm:[3,3,3,3] row_mask:0xf bank_mask:0xf bound_ctrl:1
	v_cndmask_b32_e64 v109, v109, v110, s[0:1]
	s_nop 0
	v_mov_b32_dpp v110, v96 quad_perm:[0,0,0,0] row_mask:0xf bank_mask:0xf bound_ctrl:1
	v_add_f32_e32 v110, 0, v110
	v_cndmask_b32_e64 v110, 0, v110, s[40:41]
	s_nop 1
	v_add_f32_dpp v111, v96, v110 quad_perm:[1,1,1,1] row_mask:0xf bank_mask:0xf bound_ctrl:1
	v_cndmask_b32_e64 v110, v110, v111, s[44:45]
	s_nop 1
	v_add_f32_dpp v111, v96, v110 quad_perm:[2,2,2,2] row_mask:0xf bank_mask:0xf bound_ctrl:1
	v_cndmask_b32_e64 v110, v110, v111, s[42:43]
	s_nop 1
	v_add_f32_dpp v111, v96, v110 quad_perm:[3,3,3,3] row_mask:0xf bank_mask:0xf bound_ctrl:1
	v_cndmask_b32_e64 v110, v110, v111, s[0:1]
	s_nop 0
	v_mov_b32_dpp v111, v97 quad_perm:[0,0,0,0] row_mask:0xf bank_mask:0xf bound_ctrl:1
	v_add_f32_e32 v111, 0, v111
	v_cndmask_b32_e64 v111, 0, v111, s[40:41]
	s_nop 1
	v_add_f32_dpp v116, v97, v111 quad_perm:[1,1,1,1] row_mask:0xf bank_mask:0xf bound_ctrl:1
	v_cndmask_b32_e64 v111, v111, v116, s[44:45]
	s_nop 1
	v_add_f32_dpp v116, v97, v111 quad_perm:[2,2,2,2] row_mask:0xf bank_mask:0xf bound_ctrl:1
	v_cndmask_b32_e64 v111, v111, v116, s[42:43]
	s_nop 1
	v_add_f32_dpp v116, v97, v111 quad_perm:[3,3,3,3] row_mask:0xf bank_mask:0xf bound_ctrl:1
	v_cndmask_b32_e64 v111, v111, v116, s[0:1]
	s_nop 0
	v_mov_b32_dpp v116, v98 quad_perm:[0,0,0,0] row_mask:0xf bank_mask:0xf bound_ctrl:1
	v_add_f32_e32 v116, 0, v116
	v_cndmask_b32_e64 v116, 0, v116, s[40:41]
	s_nop 1
	v_add_f32_dpp v117, v98, v116 quad_perm:[1,1,1,1] row_mask:0xf bank_mask:0xf bound_ctrl:1
	v_cndmask_b32_e64 v116, v116, v117, s[44:45]
	s_nop 1
	v_add_f32_dpp v117, v98, v116 quad_perm:[2,2,2,2] row_mask:0xf bank_mask:0xf bound_ctrl:1
	v_cndmask_b32_e64 v116, v116, v117, s[42:43]
	s_nop 1
	v_add_f32_dpp v117, v98, v116 quad_perm:[3,3,3,3] row_mask:0xf bank_mask:0xf bound_ctrl:1
	v_cndmask_b32_e64 v116, v116, v117, s[0:1]
	s_nop 0
	v_mov_b32_dpp v117, v99 quad_perm:[0,0,0,0] row_mask:0xf bank_mask:0xf bound_ctrl:1
	v_add_f32_e32 v117, 0, v117
	v_cndmask_b32_e64 v117, 0, v117, s[40:41]
	s_nop 1
	v_add_f32_dpp v120, v99, v117 quad_perm:[1,1,1,1] row_mask:0xf bank_mask:0xf bound_ctrl:1
	v_cndmask_b32_e64 v117, v117, v120, s[44:45]
	s_nop 1
	v_add_f32_dpp v120, v99, v117 quad_perm:[2,2,2,2] row_mask:0xf bank_mask:0xf bound_ctrl:1
	v_cndmask_b32_e64 v117, v117, v120, s[42:43]
	s_nop 1
	v_add_f32_dpp v120, v99, v117 quad_perm:[3,3,3,3] row_mask:0xf bank_mask:0xf bound_ctrl:1
	v_cndmask_b32_e64 v117, v117, v120, s[0:1]
	s_and_saveexec_b64 s[48:49], s[38:39]
	s_cbranch_execz .LBB0_2446
	global_load_dwordx4 v[118:121], v[114:115], off offset:528
	global_load_dwordx4 v[122:125], v[114:115], off offset:512
	s_waitcnt vmcnt(0)
	v_pk_add_f32 v[110:111], v[110:111], v[118:119]
	v_pk_add_f32 v[116:117], v[116:117], v[120:121]
	v_pk_add_f32 v[108:109], v[108:109], v[124:125]
	v_pk_add_f32 v[106:107], v[106:107], v[122:123]
	s_or_b64 exec, exec, s[48:49]
	s_and_saveexec_b64 s[48:49], s[36:37]
	s_cbranch_execnz .LBB0_2447

; __device__ __forceinline__ void st8bf(bf16_t* p, f32x4 a, f32x4 b) { u32x4 w; w.x = pk2(a[0], a[1]); w.y = pk2(a[2], a[3]); w.z = pk2(b[0], b[1]); w.w = pk2(b[2], b[3]); st16(p, w); }
;     __device__ __forceinline__ void st(int pn, int row, int c, f32x4 v0, f32x4 v1) const {
;     ...
;                 const float inv = 1.f / (float)w;
;                 st8bf(DMs + (size_t)row * 1024 + col, (f32x4){s[0] * inv - x[0], s[1] * inv - x[1], s[2] * inv - x[2], s[3] * inv - x[3]}, (f32x4){s[4] * inv - x[4], s[5] * inv - x[5], s[6] * inv - x[6], s[7] * inv - x[7]});
.LBB0_2135:
	s_or_b64 exec, exec, s[48:49]
	v_readlane_b32 s4, v251, 0
	v_readlane_b32 s5, v251, 1
	v_mov_b32_e32 v115, v102
	v_mov_b32_e32 v102, v101
	v_lshl_add_u64 v[112:113], v[112:113], 1, s[4:5]
	v_lshl_add_u64 v[104:105], v[104:105], 1, v[112:113]
	v_mov_b32_e32 v113, v108
	v_mov_b32_e32 v108, v107
	v_mov_b32_e32 v114, v100
	v_pk_fma_f32 v[100:101], s[68:69], v[108:109], v[102:103] op_sel_hi:[0,1,1] neg_lo:[0,0,1] neg_hi:[0,0,1]
	v_mov_b32_e32 v103, v116
	v_mov_b32_e32 v107, v98
	v_mov_b32_e32 v116, v111
	v_mov_b32_e32 v98, v97
	v_mov_b32_e32 v112, v106
	v_mov_b32_e32 v102, v110
	v_mov_b32_e32 v106, v96
	v_pk_fma_f32 v[96:97], s[68:69], v[116:117], v[98:99] op_sel_hi:[0,1,1] neg_lo:[0,0,1] neg_hi:[0,0,1]
	v_pk_fma_f32 v[112:113], s[68:69], v[112:113], v[114:115] op_sel_hi:[0,1,1] neg_lo:[0,0,1] neg_hi:[0,0,1]
	v_pk_fma_f32 v[102:103], s[68:69], v[102:103], v[106:107] op_sel_hi:[0,1,1] neg_lo:[0,0,1] neg_hi:[0,0,1]
	v_cvt_pk_bf16_f32 v99, v103, v97
	v_cvt_pk_bf16_f32 v98, v102, v96
	v_cvt_pk_bf16_f32 v97, v113, v101
	v_cvt_pk_bf16_f32 v96, v112, v100
	global_store_dwordx4 v[104:105], v[96:99], off offset:256

; __device__ __forceinline__ void st16f(float* p, f32x4 v) { st16(p, __builtin_bit_cast(u32x4, v)); }
; __device__ __forceinline__ void st8bf(bf16_t* p, f32x4 a, f32x4 b) { u32x4 w; w.x = pk2(a[0], a[1]); w.y = pk2(a[2], a[3]); w.z = pk2(b[0], b[1]); w.w = pk2(b[2], b[3]); st16(p, w); }
; __device__ __forceinline__ f32x4 sig4(f32x4 v) { f32x4 r; r[0] = sigmoidf_(v[0]); r[1] = sigmoidf_(v[1]); r[2] = sigmoidf_(v[2]); r[3] = sigmoidf_(v[3]); return r; }
;     __device__ __forceinline__ void st(int pn, int row, int c, f32x4 v0, f32x4 v1) const {
;         const bool smp = row >= MP; const int b = smp ? (row - MP) >> 2 : row >> 13, t = smp ? (row - MP) & 3 : row & (SEQ - 1);
;         if (pn < 4) { const int col = pn * 256 + c; float* o = nullptr;
;             if (smp) o = out + O_POOLS + ((size_t)b * 15 + 11 + t) * 1024 + col;
;             st8bf(V + (size_t)row * 1024 + col, v0, v1); if (o) { st16f(o, v0); st16f(o + 4, v1); }
;             if (smp) {
;                 const int w = 2 << pn;
;                 float x[8] = {v0[0], v0[1], v0[2], v0[3], v1[0], v1[1], v1[2], v1[3]}, s[8];
; #pragma unroll
;                 for (int e = 0; e < 8; ++e) { s[e] = 0.f;
; #pragma unroll
;                     for (int tp = 0; tp < 4; ++tp) { const float xo = quad_bcast(x[e], tp); if (tp <= t && t - tp < w) s[e] += xo; } }
;                 const int e_lo = 15 + t - w + 1;
; #pragma unroll
;                 for (int e2 = 0; e2 < 15; ++e2) if (e2 >= e_lo) { const float* sp = state_pool + ((size_t)b * 15 + e2) * 1024 + col; const f32x4 a = *(const f32x4*)sp, d = *(const f32x4*)(sp + 4);
;                     s[0] += a[0]; s[1] += a[1]; s[2] += a[2]; s[3] += a[3]; s[4] += d[0]; s[5] += d[1]; s[6] += d[2]; s[7] += d[3]; }
;                 const float inv = 1.f / (float)w;
;                 st8bf(DMs + (size_t)row * 1024 + col, (f32x4){s[0] * inv - x[0], s[1] * inv - x[1], s[2] * inv - x[2], s[3] * inv - x[3]}, (f32x4){s[4] * inv - x[4], s[5] * inv - x[5], s[6] * inv - x[6], s[7] * inv - x[7]});
;             } }
;         else st8bf(GT + (size_t)row * 1024 + (pn - 4) * 256 + c, v0 * sig4(v0), v1 * sig4(v1));
.LBB0_2137:
	s_nop 0
	v_or_b32_e32 v96, 32, v150
	v_ashrrev_i32_e32 v97, 31, v96
	v_cmp_lt_i32_e64 s[48:49], s89, v96
	v_lshlrev_b64 v[102:103], 11, v[96:97]
	s_and_b64 vcc, exec, s[46:47]
	s_mov_b64 s[72:73], -1
	s_cbranch_vccnz .LBB0_2139
	v_lshl_add_u64 v[98:99], s[54:55], 0, v[102:103]
	v_mul_f32_e32 v100, 0xbfb8aa3b, v92
	v_exp_f32_e32 v100, v100
	v_lshl_add_u64 v[98:99], s[60:61], 1, v[98:99]
	v_lshlrev_b32_e32 v138, 1, v140
	v_lshl_add_u64 v[104:105], v[98:99], 0, v[138:139]
	v_mul_f32_e32 v99, 0xbfb8aa3b, v93
	v_exp_f32_e32 v99, v99
	v_add_f32_e32 v98, 1.0, v100
	v_mul_f32_e32 v100, 0xbfb8aa3b, v94
	v_mul_f32_e32 v101, 0xbfb8aa3b, v95
	v_exp_f32_e32 v100, v100
	v_exp_f32_e32 v101, v101
	v_add_f32_e32 v99, 1.0, v99
	v_rcp_f32_e32 v98, v98
	v_rcp_f32_e32 v99, v99
	v_mul_f32_e32 v106, 0xbfb8aa3b, v88
	v_mul_f32_e32 v107, 0xbfb8aa3b, v89
	v_exp_f32_e32 v106, v106
	v_exp_f32_e32 v107, v107
	v_add_f32_e32 v100, 1.0, v100
	v_add_f32_e32 v101, 1.0, v101
	v_rcp_f32_e32 v100, v100
	v_rcp_f32_e32 v101, v101
	v_mul_f32_e32 v108, 0xbfb8aa3b, v90
	v_mul_f32_e32 v109, 0xbfb8aa3b, v91
	v_exp_f32_e32 v108, v108
	v_exp_f32_e32 v109, v109
	v_pk_mul_f32 v[98:99], v[92:93], v[98:99]
	v_add_f32_e32 v106, 1.0, v106
	v_add_f32_e32 v107, 1.0, v107
	v_rcp_f32_e32 v106, v106
	v_rcp_f32_e32 v107, v107
	v_pk_mul_f32 v[100:101], v[94:95], v[100:101]
	v_add_f32_e32 v108, 1.0, v108
	v_add_f32_e32 v109, 1.0, v109
	v_cvt_pk_bf16_f32 v98, v98, v99
	v_rcp_f32_e32 v108, v108
	v_rcp_f32_e32 v109, v109
	v_pk_mul_f32 v[106:107], v[88:89], v[106:107]
	v_cvt_pk_bf16_f32 v99, v100, v101
	v_pk_mul_f32 v[108:109], v[90:91], v[108:109]
	v_cvt_pk_bf16_f32 v100, v106, v107
	v_cvt_pk_bf16_f32 v101, v108, v109
	s_mov_b64 s[72:73], 0
	global_store_dwordx4 v[104:105], v[98:101], off
; __device__ __forceinline__ void st16f(float* p, f32x4 v) { st16(p, __builtin_bit_cast(u32x4, v)); }
; __device__ __forceinline__ void st8bf(bf16_t* p, f32x4 a, f32x4 b) { u32x4 w; w.x = pk2(a[0], a[1]); w.y = pk2(a[2], a[3]); w.z = pk2(b[0], b[1]); w.w = pk2(b[2], b[3]); st16(p, w); }
;     __device__ __forceinline__ void st(int pn, int row, int c, f32x4 v0, f32x4 v1) const {
;         const bool smp = row >= MP; const int b = smp ? (row - MP) >> 2 : row >> 13, t = smp ? (row - MP) & 3 : row & (SEQ - 1);
;         if (pn < 4) { const int col = pn * 256 + c; float* o = nullptr;
;             if (smp) o = out + O_POOLS + ((size_t)b * 15 + 11 + t) * 1024 + col;
;             st8bf(V + (size_t)row * 1024 + col, v0, v1); if (o) { st16f(o, v0); st16f(o + 4, v1); }
;             if (smp) {
;                 const int w = 2 << pn;
;                 float x[8] = {v0[0], v0[1], v0[2], v0[3], v1[0], v1[1], v1[2], v1[3]}, s[8];
; #pragma unroll
;                 for (int e = 0; e < 8; ++e) { s[e] = 0.f;
; #pragma unroll
;                     for (int tp = 0; tp < 4; ++tp) { const float xo = quad_bcast(x[e], tp); if (tp <= t && t - tp < w) s[e] += xo; } }
;                 const int e_lo = 15 + t - w + 1;
; #pragma unroll
;                 for (int e2 = 0; e2 < 15; ++e2) if (e2 >= e_lo) { const float* sp = state_pool + ((size_t)b * 15 + e2) * 1024 + col; const f32x4 a = *(const f32x4*)sp, d = *(const f32x4*)(sp + 4);
;                     s[0] += a[0]; s[1] += a[1]; s[2] += a[2]; s[3] += a[3]; s[4] += d[0]; s[5] += d[1]; s[6] += d[2]; s[7] += d[3]; }
.LBB0_2139:
	s_nop 1
	v_add_u32_e32 v98, 0xffff8020, v150
	v_lshrrev_b32_e32 v104, 2, v98
	v_mad_u64_u32 v[98:99], s[74:75], v104, 15, v[128:129]
	v_lshlrev_b64 v[100:101], 12, v[98:99]
	v_lshlrev_b64 v[96:97], 10, v[96:97]
	s_andn2_b64 vcc, exec, s[72:73]
	v_mad_u64_u32 v[98:99], s[72:73], v104, s90, 0
	s_cbranch_vccnz .LBB0_2160
	v_or_b32_e32 v104, s70, v140
	v_ashrrev_i32_e32 v105, 31, v104
	v_lshl_add_u64 v[106:107], v[96:97], 1, s[52:53]
	v_lshl_add_u64 v[110:111], v[104:105], 1, v[106:107]
	v_cvt_pk_bf16_f32 v106, v92, v93
	v_cvt_pk_bf16_f32 v107, v94, v95
	v_cvt_pk_bf16_f32 v108, v88, v89
	v_bfe_u32 v109, v90, 16, 1
	v_add3_u32 v109, v90, v109, s89
	v_bfe_u32 v112, v91, 16, 1
	v_lshrrev_b32_e32 v109, 16, v109
	v_add3_u32 v112, v91, v112, s89
	v_and_or_b32 v109, v112, s91, v109
	global_store_dwordx4 v[110:111], v[106:109], off
	s_and_saveexec_b64 s[72:73], s[48:49]
	s_cbranch_execz .LBB0_2158
	v_readlane_b32 s4, v250, 58
	v_readlane_b32 s5, v250, 59
	v_lshlrev_b64 v[114:115], 2, v[104:105]
	s_nop 0
	v_lshl_add_u64 v[106:107], s[4:5], 0, v[100:101]
	v_lshl_add_u64 v[106:107], v[106:107], 0, v[114:115]
	global_store_dwordx4 v[106:107], v[92:95], off
	global_store_dwordx4 v[106:107], v[88:91], off offset:16
	v_mov_b32_dpp v106, v92 quad_perm:[0,0,0,0] row_mask:0xf bank_mask:0xf bound_ctrl:1
	v_add_f32_e32 v106, 0, v106
	v_cndmask_b32_e64 v106, 0, v106, s[40:41]
	v_readlane_b32 s4, v250, 12
	v_readlane_b32 s16, v250, 24
	v_add_f32_dpp v107, v92, v106 quad_perm:[1,1,1,1] row_mask:0xf bank_mask:0xf bound_ctrl:1
	v_cndmask_b32_e64 v106, v106, v107, s[44:45]
	v_readlane_b32 s17, v250, 25
	v_readlane_b32 s5, v250, 13
	v_add_f32_dpp v107, v92, v106 quad_perm:[2,2,2,2] row_mask:0xf bank_mask:0xf bound_ctrl:1
	v_cndmask_b32_e64 v106, v106, v107, s[42:43]
	v_lshl_add_u64 v[114:115], s[16:17], 0, v[114:115]
	v_lshl_add_u64 v[114:115], v[114:115], 0, v[98:99]
	v_add_f32_dpp v107, v92, v106 quad_perm:[3,3,3,3] row_mask:0xf bank_mask:0xf bound_ctrl:1
	v_cndmask_b32_e64 v106, v106, v107, s[0:1]
	v_readlane_b32 s6, v250, 14
	v_mov_b32_dpp v107, v93 quad_perm:[0,0,0,0] row_mask:0xf bank_mask:0xf bound_ctrl:1
	v_add_f32_e32 v107, 0, v107
	v_cndmask_b32_e64 v107, 0, v107, s[40:41]
	v_readlane_b32 s7, v250, 15
	v_readlane_b32 s8, v250, 16
	v_add_f32_dpp v108, v93, v107 quad_perm:[1,1,1,1] row_mask:0xf bank_mask:0xf bound_ctrl:1
	v_cndmask_b32_e64 v107, v107, v108, s[44:45]
	v_readlane_b32 s9, v250, 17
	v_readlane_b32 s10, v250, 18
	v_add_f32_dpp v108, v93, v107 quad_perm:[2,2,2,2] row_mask:0xf bank_mask:0xf bound_ctrl:1
	v_cndmask_b32_e64 v107, v107, v108, s[42:43]
	v_readlane_b32 s11, v250, 19
	v_readlane_b32 s12, v250, 20
	v_add_f32_dpp v108, v93, v107 quad_perm:[3,3,3,3] row_mask:0xf bank_mask:0xf bound_ctrl:1
	v_cndmask_b32_e64 v107, v107, v108, s[0:1]
	v_readlane_b32 s13, v250, 21
	v_mov_b32_dpp v108, v94 quad_perm:[0,0,0,0] row_mask:0xf bank_mask:0xf bound_ctrl:1
	v_add_f32_e32 v108, 0, v108
	v_cndmask_b32_e64 v108, 0, v108, s[40:41]
	v_readlane_b32 s14, v250, 22
	v_readlane_b32 s15, v250, 23
	v_add_f32_dpp v109, v94, v108 quad_perm:[1,1,1,1] row_mask:0xf bank_mask:0xf bound_ctrl:1
	v_cndmask_b32_e64 v108, v108, v109, s[44:45]
	v_readlane_b32 s18, v250, 26
	v_readlane_b32 s19, v250, 27
	v_add_f32_dpp v109, v94, v108 quad_perm:[2,2,2,2] row_mask:0xf bank_mask:0xf bound_ctrl:1
	v_cndmask_b32_e64 v108, v108, v109, s[42:43]
	s_nop 1
	v_add_f32_dpp v109, v94, v108 quad_perm:[3,3,3,3] row_mask:0xf bank_mask:0xf bound_ctrl:1
	v_cndmask_b32_e64 v108, v108, v109, s[0:1]
	s_nop 0
	v_mov_b32_dpp v109, v95 quad_perm:[0,0,0,0] row_mask:0xf bank_mask:0xf bound_ctrl:1
	v_add_f32_e32 v109, 0, v109
	v_cndmask_b32_e64 v109, 0, v109, s[40:41]
	s_nop 1
	v_add_f32_dpp v110, v95, v109 quad_perm:[1,1,1,1] row_mask:0xf bank_mask:0xf bound_ctrl:1
	v_cndmask_b32_e64 v109, v109, v110, s[44:45]
	s_nop 1
	v_add_f32_dpp v110, v95, v109 quad_perm:[2,2,2,2] row_mask:0xf bank_mask:0xf bound_ctrl:1
	v_cndmask_b32_e64 v109, v109, v110, s[42:43]
	s_nop 1
	v_add_f32_dpp v110, v95, v109 quad_perm:[3,3,3,3] row_mask:0xf bank_mask:0xf bound_ctrl:1
	v_cndmask_b32_e64 v109, v109, v110, s[0:1]
	s_nop 0
	v_mov_b32_dpp v110, v88 quad_perm:[0,0,0,0] row_mask:0xf bank_mask:0xf bound_ctrl:1
	v_add_f32_e32 v110, 0, v110
	v_cndmask_b32_e64 v110, 0, v110, s[40:41]
	s_nop 1
	v_add_f32_dpp v111, v88, v110 quad_perm:[1,1,1,1] row_mask:0xf bank_mask:0xf bound_ctrl:1
	v_cndmask_b32_e64 v110, v110, v111, s[44:45]
	s_nop 1
	v_add_f32_dpp v111, v88, v110 quad_perm:[2,2,2,2] row_mask:0xf bank_mask:0xf bound_ctrl:1
	v_cndmask_b32_e64 v110, v110, v111, s[42:43]
	s_nop 1
	v_add_f32_dpp v111, v88, v110 quad_perm:[3,3,3,3] row_mask:0xf bank_mask:0xf bound_ctrl:1
	v_cndmask_b32_e64 v110, v110, v111, s[0:1]
	s_nop 0
	v_mov_b32_dpp v111, v89 quad_perm:[0,0,0,0] row_mask:0xf bank_mask:0xf bound_ctrl:1
	v_add_f32_e32 v111, 0, v111
	v_cndmask_b32_e64 v111, 0, v111, s[40:41]
	s_nop 1
	v_add_f32_dpp v112, v89, v111 quad_perm:[1,1,1,1] row_mask:0xf bank_mask:0xf bound_ctrl:1
	v_cndmask_b32_e64 v111, v111, v112, s[44:45]
	s_nop 1
	v_add_f32_dpp v112, v89, v111 quad_perm:[2,2,2,2] row_mask:0xf bank_mask:0xf bound_ctrl:1
	v_cndmask_b32_e64 v111, v111, v112, s[42:43]
	s_nop 1
	v_add_f32_dpp v112, v89, v111 quad_perm:[3,3,3,3] row_mask:0xf bank_mask:0xf bound_ctrl:1
	v_cndmask_b32_e64 v111, v111, v112, s[0:1]
	s_nop 0
	v_mov_b32_dpp v112, v90 quad_perm:[0,0,0,0] row_mask:0xf bank_mask:0xf bound_ctrl:1
	v_add_f32_e32 v112, 0, v112
	v_cndmask_b32_e64 v112, 0, v112, s[40:41]
	s_nop 1
	v_add_f32_dpp v113, v90, v112 quad_perm:[1,1,1,1] row_mask:0xf bank_mask:0xf bound_ctrl:1
	v_cndmask_b32_e64 v112, v112, v113, s[44:45]
	s_nop 1
	v_add_f32_dpp v113, v90, v112 quad_perm:[2,2,2,2] row_mask:0xf bank_mask:0xf bound_ctrl:1
	v_cndmask_b32_e64 v112, v112, v113, s[42:43]
	s_nop 1
	v_add_f32_dpp v113, v90, v112 quad_perm:[3,3,3,3] row_mask:0xf bank_mask:0xf bound_ctrl:1
	v_cndmask_b32_e64 v112, v112, v113, s[0:1]
	s_nop 0
	v_mov_b32_dpp v113, v91 quad_perm:[0,0,0,0] row_mask:0xf bank_mask:0xf bound_ctrl:1
	v_add_f32_e32 v113, 0, v113
	v_cndmask_b32_e64 v113, 0, v113, s[40:41]
	s_nop 1
	v_add_f32_dpp v116, v91, v113 quad_perm:[1,1,1,1] row_mask:0xf bank_mask:0xf bound_ctrl:1
	v_cndmask_b32_e64 v113, v113, v116, s[44:45]
	s_nop 1
	v_add_f32_dpp v116, v91, v113 quad_perm:[2,2,2,2] row_mask:0xf bank_mask:0xf bound_ctrl:1
	v_cndmask_b32_e64 v113, v113, v116, s[42:43]
	s_nop 1
	v_add_f32_dpp v116, v91, v113 quad_perm:[3,3,3,3] row_mask:0xf bank_mask:0xf bound_ctrl:1
	v_cndmask_b32_e64 v113, v113, v116, s[0:1]
	s_and_saveexec_b64 s[74:75], s[38:39]
	s_cbranch_execz .LBB0_2460
	global_load_dwordx4 v[116:119], v[114:115], off offset:16
	global_load_dwordx4 v[120:123], v[114:115], off
	s_waitcnt vmcnt(0)
	v_pk_add_f32 v[110:111], v[110:111], v[116:117]
	v_pk_add_f32 v[112:113], v[112:113], v[118:119]
	v_pk_add_f32 v[108:109], v[108:109], v[122:123]
	v_pk_add_f32 v[106:107], v[106:107], v[120:121]
	s_or_b64 exec, exec, s[74:75]
	s_and_saveexec_b64 s[74:75], s[36:37]
	s_cbranch_execnz .LBB0_2461

; __device__ __forceinline__ void st8bf(bf16_t* p, f32x4 a, f32x4 b) { u32x4 w; w.x = pk2(a[0], a[1]); w.y = pk2(a[2], a[3]); w.z = pk2(b[0], b[1]); w.w = pk2(b[2], b[3]); st16(p, w); }
;     __device__ __forceinline__ void st(int pn, int row, int c, f32x4 v0, f32x4 v1) const {
;     ...
;                 const float inv = 1.f / (float)w;
;                 st8bf(DMs + (size_t)row * 1024 + col, (f32x4){s[0] * inv - x[0], s[1] * inv - x[1], s[2] * inv - x[2], s[3] * inv - x[3]}, (f32x4){s[4] * inv - x[4], s[5] * inv - x[5], s[6] * inv - x[6], s[7] * inv - x[7]});
.LBB0_2157:
	s_or_b64 exec, exec, s[74:75]
	v_readlane_b32 s4, v251, 0
	v_readlane_b32 s5, v251, 1
	v_mov_b32_e32 v117, v94
	v_mov_b32_e32 v94, v93
	v_lshl_add_u64 v[114:115], v[96:97], 1, s[4:5]
	v_lshl_add_u64 v[104:105], v[104:105], 1, v[114:115]
	v_mov_b32_e32 v115, v108
	v_mov_b32_e32 v108, v107
	v_mov_b32_e32 v116, v92
	v_pk_fma_f32 v[92:93], s[68:69], v[108:109], v[94:95] op_sel_hi:[0,1,1] neg_lo:[0,0,1] neg_hi:[0,0,1]
	v_mov_b32_e32 v95, v112
	v_mov_b32_e32 v107, v90
	v_mov_b32_e32 v112, v111
	v_mov_b32_e32 v90, v89
	v_mov_b32_e32 v114, v106
	v_mov_b32_e32 v94, v110
	v_mov_b32_e32 v106, v88
	v_pk_fma_f32 v[88:89], s[68:69], v[112:113], v[90:91] op_sel_hi:[0,1,1] neg_lo:[0,0,1] neg_hi:[0,0,1]
	v_pk_fma_f32 v[114:115], s[68:69], v[114:115], v[116:117] op_sel_hi:[0,1,1] neg_lo:[0,0,1] neg_hi:[0,0,1]
	v_pk_fma_f32 v[94:95], s[68:69], v[94:95], v[106:107] op_sel_hi:[0,1,1] neg_lo:[0,0,1] neg_hi:[0,0,1]
	v_cvt_pk_bf16_f32 v91, v95, v89
	v_cvt_pk_bf16_f32 v90, v94, v88
	v_cvt_pk_bf16_f32 v89, v115, v93
	v_cvt_pk_bf16_f32 v88, v114, v92
	global_store_dwordx4 v[104:105], v[88:91], off

; __device__ __forceinline__ unsigned pk2(float lo, float hi) { return f2bf(lo) | (f2bf(hi) << 16); }
; __device__ __forceinline__ float sigmoidf_(float x) { return __builtin_amdgcn_rcpf(1.0f + __expf(-x)); }
; __device__ __forceinline__ void st8bf(bf16_t* p, f32x4 a, f32x4 b) { u32x4 w; w.x = pk2(a[0], a[1]); w.y = pk2(a[2], a[3]); w.z = pk2(b[0], b[1]); w.w = pk2(b[2], b[3]); st16(p, w); }
; __device__ __forceinline__ void stnt8(float* o, f32x4 a, f32x4 b) { __builtin_nontemporal_store(a, (f32x4*)o); __builtin_nontemporal_store(b, (f32x4*)(o + 4)); }
; __device__ __forceinline__ f32x4 sig4(f32x4 v) { f32x4 r; r[0] = sigmoidf_(v[0]); r[1] = sigmoidf_(v[1]); r[2] = sigmoidf_(v[2]); r[3] = sigmoidf_(v[3]); return r; }
;     __device__ __forceinline__ void st(int pn, int row, int c, f32x4 v0, f32x4 v1) const {
;     ...
;         else st8bf(GT + (size_t)row * 1024 + (pn - 4) * 256 + c, v0 * sig4(v0), v1 * sig4(v1));
.LBB0_2161:
	v_lshl_add_u64 v[88:89], s[54:55], 0, v[102:103]
	v_mul_f32_e32 v90, 0xbfb8aa3b, v84
	v_exp_f32_e32 v90, v90
	v_lshl_add_u64 v[88:89], s[60:61], 1, v[88:89]
	v_lshlrev_b32_e32 v138, 1, v140
	v_lshl_add_u64 v[92:93], v[88:89], 0, v[138:139]
	v_mul_f32_e32 v89, 0xbfb8aa3b, v85
	v_exp_f32_e32 v89, v89
	v_add_f32_e32 v88, 1.0, v90
	v_mul_f32_e32 v90, 0xbfb8aa3b, v86
	v_mul_f32_e32 v91, 0xbfb8aa3b, v87
	v_exp_f32_e32 v90, v90
	v_exp_f32_e32 v91, v91
	v_add_f32_e32 v89, 1.0, v89
	v_rcp_f32_e32 v88, v88
	v_rcp_f32_e32 v89, v89
	v_mul_f32_e32 v94, 0xbfb8aa3b, v80
	v_mul_f32_e32 v95, 0xbfb8aa3b, v81
	v_exp_f32_e32 v94, v94
	v_exp_f32_e32 v95, v95
	v_add_f32_e32 v90, 1.0, v90
	v_add_f32_e32 v91, 1.0, v91
	v_rcp_f32_e32 v90, v90
	v_rcp_f32_e32 v91, v91
	v_mul_f32_e32 v102, 0xbfb8aa3b, v82
	v_mul_f32_e32 v103, 0xbfb8aa3b, v83
	v_exp_f32_e32 v102, v102
	v_exp_f32_e32 v103, v103
	v_pk_mul_f32 v[88:89], v[84:85], v[88:89]
	v_add_f32_e32 v94, 1.0, v94
	v_add_f32_e32 v95, 1.0, v95
	v_bfe_u32 v104, v88, 16, 1
	v_rcp_f32_e32 v94, v94
	v_rcp_f32_e32 v95, v95
	v_add3_u32 v88, v88, v104, s89
	v_bfe_u32 v104, v89, 16, 1
	v_pk_mul_f32 v[90:91], v[86:87], v[90:91]
	v_lshrrev_b32_e32 v88, 16, v88
	v_add3_u32 v89, v89, v104, s89
	v_add_f32_e32 v102, 1.0, v102
	v_add_f32_e32 v103, 1.0, v103
	v_and_or_b32 v88, v89, s91, v88
	v_rcp_f32_e32 v102, v102
	v_rcp_f32_e32 v103, v103
	v_pk_mul_f32 v[94:95], v[80:81], v[94:95]
	v_cvt_pk_bf16_f32 v89, v90, v91
	v_pk_mul_f32 v[102:103], v[82:83], v[102:103]
	v_cvt_pk_bf16_f32 v90, v94, v95
	v_cvt_pk_bf16_f32 v91, v102, v103
	global_store_dwordx4 v[92:93], v[88:91], off offset:256
	s_cbranch_execnz .LBB0_2181
; __device__ __forceinline__ void st16f(float* p, f32x4 v) { st16(p, __builtin_bit_cast(u32x4, v)); }
; __device__ __forceinline__ void st8bf(bf16_t* p, f32x4 a, f32x4 b) { u32x4 w; w.x = pk2(a[0], a[1]); w.y = pk2(a[2], a[3]); w.z = pk2(b[0], b[1]); w.w = pk2(b[2], b[3]); st16(p, w); }
;     __device__ __forceinline__ void st(int pn, int row, int c, f32x4 v0, f32x4 v1) const {
;     ...
;         if (pn < 4) { const int col = pn * 256 + c; float* o = nullptr;
;             if (smp) o = out + O_POOLS + ((size_t)b * 15 + 11 + t) * 1024 + col;
;             st8bf(V + (size_t)row * 1024 + col, v0, v1); if (o) { st16f(o, v0); st16f(o + 4, v1); }
;             if (smp) {
;                 const int w = 2 << pn;
;                 float x[8] = {v0[0], v0[1], v0[2], v0[3], v1[0], v1[1], v1[2], v1[3]}, s[8];
; #pragma unroll
;                 for (int e = 0; e < 8; ++e) { s[e] = 0.f;
; #pragma unroll
;                     for (int tp = 0; tp < 4; ++tp) { const float xo = quad_bcast(x[e], tp); if (tp <= t && t - tp < w) s[e] += xo; } }
;                 const int e_lo = 15 + t - w + 1;
; #pragma unroll
;                 for (int e2 = 0; e2 < 15; ++e2) if (e2 >= e_lo) { const float* sp = state_pool + ((size_t)b * 15 + e2) * 1024 + col; const f32x4 a = *(const f32x4*)sp, d = *(const f32x4*)(sp + 4);
;                     s[0] += a[0]; s[1] += a[1]; s[2] += a[2]; s[3] += a[3]; s[4] += d[0]; s[5] += d[1]; s[6] += d[2]; s[7] += d[3]; }
.LBB0_2162:
	s_ashr_i32 s71, s70, 31
	v_lshl_add_u64 v[90:91], v[96:97], 1, s[52:53]
	v_lshl_add_u64 v[88:89], s[70:71], 0, v[140:141]
	v_lshl_add_u64 v[94:95], v[88:89], 1, v[90:91]
	v_cvt_pk_bf16_f32 v90, v84, v85
	v_cvt_pk_bf16_f32 v91, v86, v87
	v_cvt_pk_bf16_f32 v92, v80, v81
	v_cvt_pk_bf16_f32 v93, v82, v83
	global_store_dwordx4 v[94:95], v[90:93], off offset:256
	s_and_saveexec_b64 s[72:73], s[48:49]
	s_cbranch_execz .LBB0_2180
	v_readlane_b32 s4, v250, 58
	v_readlane_b32 s5, v250, 59
	v_lshlrev_b64 v[102:103], 2, v[88:89]
	s_nop 0
	v_lshl_add_u64 v[90:91], s[4:5], 0, v[100:101]
	v_lshl_add_u64 v[90:91], v[90:91], 0, v[102:103]
	global_store_dwordx4 v[90:91], v[84:87], off offset:512
	global_store_dwordx4 v[90:91], v[80:83], off offset:528
	v_mov_b32_dpp v90, v84 quad_perm:[0,0,0,0] row_mask:0xf bank_mask:0xf bound_ctrl:1
	v_add_f32_e32 v90, 0, v90
	v_cndmask_b32_e64 v90, 0, v90, s[40:41]
	v_readlane_b32 s4, v250, 12
	v_readlane_b32 s16, v250, 24
	v_add_f32_dpp v91, v84, v90 quad_perm:[1,1,1,1] row_mask:0xf bank_mask:0xf bound_ctrl:1
	v_cndmask_b32_e64 v90, v90, v91, s[44:45]
	v_readlane_b32 s17, v250, 25
	v_readlane_b32 s5, v250, 13
	v_add_f32_dpp v91, v84, v90 quad_perm:[2,2,2,2] row_mask:0xf bank_mask:0xf bound_ctrl:1
	v_cndmask_b32_e64 v90, v90, v91, s[42:43]
	v_lshl_add_u64 v[102:103], s[16:17], 0, v[102:103]
	v_lshl_add_u64 v[98:99], v[102:103], 0, v[98:99]
	v_add_f32_dpp v91, v84, v90 quad_perm:[3,3,3,3] row_mask:0xf bank_mask:0xf bound_ctrl:1
	v_cndmask_b32_e64 v90, v90, v91, s[0:1]
	v_readlane_b32 s6, v250, 14
	v_mov_b32_dpp v91, v85 quad_perm:[0,0,0,0] row_mask:0xf bank_mask:0xf bound_ctrl:1
	v_add_f32_e32 v91, 0, v91
	v_cndmask_b32_e64 v91, 0, v91, s[40:41]
	v_readlane_b32 s7, v250, 15
	v_readlane_b32 s8, v250, 16
	v_add_f32_dpp v92, v85, v91 quad_perm:[1,1,1,1] row_mask:0xf bank_mask:0xf bound_ctrl:1
	v_cndmask_b32_e64 v91, v91, v92, s[44:45]
	v_readlane_b32 s9, v250, 17
	v_readlane_b32 s10, v250, 18
	v_add_f32_dpp v92, v85, v91 quad_perm:[2,2,2,2] row_mask:0xf bank_mask:0xf bound_ctrl:1
	v_cndmask_b32_e64 v91, v91, v92, s[42:43]
	v_readlane_b32 s11, v250, 19
	v_readlane_b32 s12, v250, 20
	v_add_f32_dpp v92, v85, v91 quad_perm:[3,3,3,3] row_mask:0xf bank_mask:0xf bound_ctrl:1
	v_cndmask_b32_e64 v91, v91, v92, s[0:1]
	v_readlane_b32 s13, v250, 21
	v_mov_b32_dpp v92, v86 quad_perm:[0,0,0,0] row_mask:0xf bank_mask:0xf bound_ctrl:1
	v_add_f32_e32 v92, 0, v92
	v_cndmask_b32_e64 v92, 0, v92, s[40:41]
	v_readlane_b32 s14, v250, 22
	v_readlane_b32 s15, v250, 23
	v_add_f32_dpp v93, v86, v92 quad_perm:[1,1,1,1] row_mask:0xf bank_mask:0xf bound_ctrl:1
	v_cndmask_b32_e64 v92, v92, v93, s[44:45]
	v_readlane_b32 s18, v250, 26
	v_readlane_b32 s19, v250, 27
	v_add_f32_dpp v93, v86, v92 quad_perm:[2,2,2,2] row_mask:0xf bank_mask:0xf bound_ctrl:1
	v_cndmask_b32_e64 v92, v92, v93, s[42:43]
	s_nop 1
	v_add_f32_dpp v93, v86, v92 quad_perm:[3,3,3,3] row_mask:0xf bank_mask:0xf bound_ctrl:1
	v_cndmask_b32_e64 v92, v92, v93, s[0:1]
	s_nop 0
	v_mov_b32_dpp v93, v87 quad_perm:[0,0,0,0] row_mask:0xf bank_mask:0xf bound_ctrl:1
	v_add_f32_e32 v93, 0, v93
	v_cndmask_b32_e64 v93, 0, v93, s[40:41]
	s_nop 1
	v_add_f32_dpp v94, v87, v93 quad_perm:[1,1,1,1] row_mask:0xf bank_mask:0xf bound_ctrl:1
	v_cndmask_b32_e64 v93, v93, v94, s[44:45]
	s_nop 1
	v_add_f32_dpp v94, v87, v93 quad_perm:[2,2,2,2] row_mask:0xf bank_mask:0xf bound_ctrl:1
	v_cndmask_b32_e64 v93, v93, v94, s[42:43]
	s_nop 1
	v_add_f32_dpp v94, v87, v93 quad_perm:[3,3,3,3] row_mask:0xf bank_mask:0xf bound_ctrl:1
	v_cndmask_b32_e64 v93, v93, v94, s[0:1]
	s_nop 0
	v_mov_b32_dpp v94, v80 quad_perm:[0,0,0,0] row_mask:0xf bank_mask:0xf bound_ctrl:1
	v_add_f32_e32 v94, 0, v94
	v_cndmask_b32_e64 v94, 0, v94, s[40:41]
	s_nop 1
	v_add_f32_dpp v95, v80, v94 quad_perm:[1,1,1,1] row_mask:0xf bank_mask:0xf bound_ctrl:1
	v_cndmask_b32_e64 v94, v94, v95, s[44:45]
	s_nop 1
	v_add_f32_dpp v95, v80, v94 quad_perm:[2,2,2,2] row_mask:0xf bank_mask:0xf bound_ctrl:1
	v_cndmask_b32_e64 v94, v94, v95, s[42:43]
	s_nop 1
	v_add_f32_dpp v95, v80, v94 quad_perm:[3,3,3,3] row_mask:0xf bank_mask:0xf bound_ctrl:1
	v_cndmask_b32_e64 v94, v94, v95, s[0:1]
	s_nop 0
	v_mov_b32_dpp v95, v81 quad_perm:[0,0,0,0] row_mask:0xf bank_mask:0xf bound_ctrl:1
	v_add_f32_e32 v95, 0, v95
	v_cndmask_b32_e64 v95, 0, v95, s[40:41]
	s_nop 1
	v_add_f32_dpp v100, v81, v95 quad_perm:[1,1,1,1] row_mask:0xf bank_mask:0xf bound_ctrl:1
	v_cndmask_b32_e64 v95, v95, v100, s[44:45]
	s_nop 1
	v_add_f32_dpp v100, v81, v95 quad_perm:[2,2,2,2] row_mask:0xf bank_mask:0xf bound_ctrl:1
	v_cndmask_b32_e64 v95, v95, v100, s[42:43]
	s_nop 1
	v_add_f32_dpp v100, v81, v95 quad_perm:[3,3,3,3] row_mask:0xf bank_mask:0xf bound_ctrl:1
	v_cndmask_b32_e64 v95, v95, v100, s[0:1]
	s_nop 0
	v_mov_b32_dpp v100, v82 quad_perm:[0,0,0,0] row_mask:0xf bank_mask:0xf bound_ctrl:1
	v_add_f32_e32 v100, 0, v100
	v_cndmask_b32_e64 v100, 0, v100, s[40:41]
	s_nop 1
	v_add_f32_dpp v101, v82, v100 quad_perm:[1,1,1,1] row_mask:0xf bank_mask:0xf bound_ctrl:1
	v_cndmask_b32_e64 v100, v100, v101, s[44:45]
	s_nop 1
	v_add_f32_dpp v101, v82, v100 quad_perm:[2,2,2,2] row_mask:0xf bank_mask:0xf bound_ctrl:1
	v_cndmask_b32_e64 v100, v100, v101, s[42:43]
	s_nop 1
	v_add_f32_dpp v101, v82, v100 quad_perm:[3,3,3,3] row_mask:0xf bank_mask:0xf bound_ctrl:1
	v_cndmask_b32_e64 v100, v100, v101, s[0:1]
	s_nop 0
	v_mov_b32_dpp v101, v83 quad_perm:[0,0,0,0] row_mask:0xf bank_mask:0xf bound_ctrl:1
	v_add_f32_e32 v101, 0, v101
	v_cndmask_b32_e64 v101, 0, v101, s[40:41]
	s_nop 1
	v_add_f32_dpp v104, v83, v101 quad_perm:[1,1,1,1] row_mask:0xf bank_mask:0xf bound_ctrl:1
	v_cndmask_b32_e64 v101, v101, v104, s[44:45]
	s_nop 1
	v_add_f32_dpp v104, v83, v101 quad_perm:[2,2,2,2] row_mask:0xf bank_mask:0xf bound_ctrl:1
	v_cndmask_b32_e64 v101, v101, v104, s[42:43]
	s_nop 1
	v_add_f32_dpp v104, v83, v101 quad_perm:[3,3,3,3] row_mask:0xf bank_mask:0xf bound_ctrl:1
	v_cndmask_b32_e64 v101, v101, v104, s[0:1]
	s_and_saveexec_b64 s[48:49], s[38:39]
	s_cbranch_execz .LBB0_2474
	global_load_dwordx4 v[102:105], v[98:99], off offset:528
	global_load_dwordx4 v[106:109], v[98:99], off offset:512
	s_waitcnt vmcnt(0)
	v_pk_add_f32 v[94:95], v[94:95], v[102:103]
	v_pk_add_f32 v[100:101], v[100:101], v[104:105]
	v_pk_add_f32 v[92:93], v[92:93], v[108:109]
	v_pk_add_f32 v[90:91], v[90:91], v[106:107]
	s_or_b64 exec, exec, s[48:49]
	s_and_saveexec_b64 s[48:49], s[36:37]
	s_cbranch_execnz .LBB0_2475

; __device__ __forceinline__ void st8bf(bf16_t* p, f32x4 a, f32x4 b) { u32x4 w; w.x = pk2(a[0], a[1]); w.y = pk2(a[2], a[3]); w.z = pk2(b[0], b[1]); w.w = pk2(b[2], b[3]); st16(p, w); }
;     __device__ __forceinline__ void st(int pn, int row, int c, f32x4 v0, f32x4 v1) const {
;     ...
;                 const float inv = 1.f / (float)w;
;                 st8bf(DMs + (size_t)row * 1024 + col, (f32x4){s[0] * inv - x[0], s[1] * inv - x[1], s[2] * inv - x[2], s[3] * inv - x[3]}, (f32x4){s[4] * inv - x[4], s[5] * inv - x[5], s[6] * inv - x[6], s[7] * inv - x[7]});
.LBB0_2179:
	s_or_b64 exec, exec, s[48:49]
	v_readlane_b32 s4, v251, 0
	v_readlane_b32 s5, v251, 1
	v_mov_b32_e32 v99, v86
	v_mov_b32_e32 v86, v85
	v_lshl_add_u64 v[96:97], v[96:97], 1, s[4:5]
	v_lshl_add_u64 v[88:89], v[88:89], 1, v[96:97]
	v_mov_b32_e32 v97, v92
	v_mov_b32_e32 v92, v91
	v_mov_b32_e32 v98, v84
	v_pk_fma_f32 v[84:85], s[68:69], v[92:93], v[86:87] op_sel_hi:[0,1,1] neg_lo:[0,0,1] neg_hi:[0,0,1]
	v_mov_b32_e32 v87, v100
	v_mov_b32_e32 v91, v82
	v_mov_b32_e32 v100, v95
	v_mov_b32_e32 v82, v81
	v_mov_b32_e32 v96, v90
	v_mov_b32_e32 v86, v94
	v_mov_b32_e32 v90, v80
	v_pk_fma_f32 v[80:81], s[68:69], v[100:101], v[82:83] op_sel_hi:[0,1,1] neg_lo:[0,0,1] neg_hi:[0,0,1]
	v_pk_fma_f32 v[96:97], s[68:69], v[96:97], v[98:99] op_sel_hi:[0,1,1] neg_lo:[0,0,1] neg_hi:[0,0,1]
	v_pk_fma_f32 v[86:87], s[68:69], v[86:87], v[90:91] op_sel_hi:[0,1,1] neg_lo:[0,0,1] neg_hi:[0,0,1]
	v_cvt_pk_bf16_f32 v83, v87, v81
	v_cvt_pk_bf16_f32 v82, v86, v80
	v_cvt_pk_bf16_f32 v81, v97, v85
	v_cvt_pk_bf16_f32 v80, v96, v84
	global_store_dwordx4 v[88:89], v[80:83], off offset:256

; __device__ __forceinline__ void st8bf(bf16_t* p, f32x4 a, f32x4 b) { u32x4 w; w.x = pk2(a[0], a[1]); w.y = pk2(a[2], a[3]); w.z = pk2(b[0], b[1]); w.w = pk2(b[2], b[3]); st16(p, w); }
; __device__ __forceinline__ f32x4 sig4(f32x4 v) { f32x4 r; r[0] = sigmoidf_(v[0]); r[1] = sigmoidf_(v[1]); r[2] = sigmoidf_(v[2]); r[3] = sigmoidf_(v[3]); return r; }
; #define EPI_LOOP_ROWS(body) _Pragma("unroll") for (int ai = 0; ai < 2; ++ai) _Pragma("unroll") for (int m = 0; m < 4; ++m) { const int row = u.pm * 256 + ai * 128 + wr * 64 + m * 16 + fr; body }
;     __device__ __forceinline__ void st(int pn, int row, int c, f32x4 v0, f32x4 v1) const {
;     ...
;         else st8bf(GT + (size_t)row * 1024 + (pn - 4) * 256 + c, v0 * sig4(v0), v1 * sig4(v1));
;     }
;     __device__ __forceinline__ void operator()(const f32x4 (&acc)[2][2][4][2], const pg8::Unit& u, int wr, int wc, int fr, int fq) const {
;         const int cw = wc * 32 + 8 * fq;
;         EPI_LOOP_ROWS( _Pragma("unroll") for (int bj = 0; bj < 2; ++bj) st(u.pn, row, bj * 128 + cw, acc[ai][bj][m][0], acc[ai][bj][m][1]); )
.LBB0_2181:
	s_nop 0
	v_or_b32_e32 v80, 48, v150
	v_ashrrev_i32_e32 v81, 31, v80
	v_cmp_lt_i32_e64 s[48:49], s89, v80
	v_lshlrev_b64 v[86:87], 11, v[80:81]
	s_and_b64 vcc, exec, s[46:47]
	s_mov_b64 s[72:73], -1
	s_cbranch_vccnz .LBB0_2183
	v_lshl_add_u64 v[82:83], s[54:55], 0, v[86:87]
	v_mul_f32_e32 v84, 0xbfb8aa3b, v76
	v_exp_f32_e32 v84, v84
	v_lshl_add_u64 v[82:83], s[60:61], 1, v[82:83]
	v_lshlrev_b32_e32 v138, 1, v140
	v_lshl_add_u64 v[88:89], v[82:83], 0, v[138:139]
	v_mul_f32_e32 v83, 0xbfb8aa3b, v77
	v_exp_f32_e32 v83, v83
	v_add_f32_e32 v82, 1.0, v84
	v_mul_f32_e32 v84, 0xbfb8aa3b, v78
	v_mul_f32_e32 v85, 0xbfb8aa3b, v79
	v_exp_f32_e32 v84, v84
	v_exp_f32_e32 v85, v85
	v_add_f32_e32 v83, 1.0, v83
	v_rcp_f32_e32 v82, v82
	v_rcp_f32_e32 v83, v83
	v_mul_f32_e32 v90, 0xbfb8aa3b, v72
	v_mul_f32_e32 v91, 0xbfb8aa3b, v73
	v_exp_f32_e32 v90, v90
	v_exp_f32_e32 v91, v91
	v_add_f32_e32 v84, 1.0, v84
	v_add_f32_e32 v85, 1.0, v85
	v_rcp_f32_e32 v84, v84
	v_rcp_f32_e32 v85, v85
	v_mul_f32_e32 v92, 0xbfb8aa3b, v74
	v_mul_f32_e32 v93, 0xbfb8aa3b, v75
	v_exp_f32_e32 v92, v92
	v_exp_f32_e32 v93, v93
	v_pk_mul_f32 v[82:83], v[76:77], v[82:83]
	v_add_f32_e32 v90, 1.0, v90
	v_add_f32_e32 v91, 1.0, v91
	v_rcp_f32_e32 v90, v90
	v_rcp_f32_e32 v91, v91
	v_pk_mul_f32 v[84:85], v[78:79], v[84:85]
	v_add_f32_e32 v92, 1.0, v92
	v_add_f32_e32 v93, 1.0, v93
	v_cvt_pk_bf16_f32 v82, v82, v83
	v_rcp_f32_e32 v92, v92
	v_rcp_f32_e32 v93, v93
	v_pk_mul_f32 v[90:91], v[72:73], v[90:91]
	v_cvt_pk_bf16_f32 v83, v84, v85
	v_pk_mul_f32 v[92:93], v[74:75], v[92:93]
	v_cvt_pk_bf16_f32 v84, v90, v91
	v_cvt_pk_bf16_f32 v85, v92, v93
	s_mov_b64 s[72:73], 0
	global_store_dwordx4 v[88:89], v[82:85], off
; __device__ __forceinline__ void st16f(float* p, f32x4 v) { st16(p, __builtin_bit_cast(u32x4, v)); }
; __device__ __forceinline__ void st8bf(bf16_t* p, f32x4 a, f32x4 b) { u32x4 w; w.x = pk2(a[0], a[1]); w.y = pk2(a[2], a[3]); w.z = pk2(b[0], b[1]); w.w = pk2(b[2], b[3]); st16(p, w); }
;     __device__ __forceinline__ void st(int pn, int row, int c, f32x4 v0, f32x4 v1) const {
;         const bool smp = row >= MP; const int b = smp ? (row - MP) >> 2 : row >> 13, t = smp ? (row - MP) & 3 : row & (SEQ - 1);
;         if (pn < 4) { const int col = pn * 256 + c; float* o = nullptr;
;             if (smp) o = out + O_POOLS + ((size_t)b * 15 + 11 + t) * 1024 + col;
;             st8bf(V + (size_t)row * 1024 + col, v0, v1); if (o) { st16f(o, v0); st16f(o + 4, v1); }
;             if (smp) {
;                 const int w = 2 << pn;
;                 float x[8] = {v0[0], v0[1], v0[2], v0[3], v1[0], v1[1], v1[2], v1[3]}, s[8];
; #pragma unroll
;                 for (int e = 0; e < 8; ++e) { s[e] = 0.f;
; #pragma unroll
;                     for (int tp = 0; tp < 4; ++tp) { const float xo = quad_bcast(x[e], tp); if (tp <= t && t - tp < w) s[e] += xo; } }
;                 const int e_lo = 15 + t - w + 1;
; #pragma unroll
;                 for (int e2 = 0; e2 < 15; ++e2) if (e2 >= e_lo) { const float* sp = state_pool + ((size_t)b * 15 + e2) * 1024 + col; const f32x4 a = *(const f32x4*)sp, d = *(const f32x4*)(sp + 4);
;                     s[0] += a[0]; s[1] += a[1]; s[2] += a[2]; s[3] += a[3]; s[4] += d[0]; s[5] += d[1]; s[6] += d[2]; s[7] += d[3]; }
.LBB0_2183:
	s_nop 1
	v_add_u32_e32 v82, 0xffff8030, v150
	v_lshrrev_b32_e32 v88, 2, v82
	v_mad_u64_u32 v[82:83], s[74:75], v88, 15, v[128:129]
	v_lshlrev_b64 v[84:85], 12, v[82:83]
	v_lshlrev_b64 v[80:81], 10, v[80:81]
	s_andn2_b64 vcc, exec, s[72:73]
	v_mad_u64_u32 v[82:83], s[72:73], v88, s90, 0
	s_cbranch_vccnz .LBB0_2204
	v_or_b32_e32 v88, s70, v140
	v_ashrrev_i32_e32 v89, 31, v88
	v_lshl_add_u64 v[90:91], v[80:81], 1, s[52:53]
	v_lshl_add_u64 v[94:95], v[88:89], 1, v[90:91]
	v_cvt_pk_bf16_f32 v90, v76, v77
	v_cvt_pk_bf16_f32 v91, v78, v79
	v_cvt_pk_bf16_f32 v92, v72, v73
	v_bfe_u32 v93, v74, 16, 1
	v_add3_u32 v93, v74, v93, s89
	v_bfe_u32 v96, v75, 16, 1
	v_lshrrev_b32_e32 v93, 16, v93
	v_add3_u32 v96, v75, v96, s89
	v_and_or_b32 v93, v96, s91, v93
	global_store_dwordx4 v[94:95], v[90:93], off
	s_and_saveexec_b64 s[72:73], s[48:49]
	s_cbranch_execz .LBB0_2202
	v_readlane_b32 s4, v250, 58
	v_readlane_b32 s5, v250, 59
	v_lshlrev_b64 v[98:99], 2, v[88:89]
	s_nop 0
	v_lshl_add_u64 v[90:91], s[4:5], 0, v[84:85]
	v_lshl_add_u64 v[90:91], v[90:91], 0, v[98:99]
	global_store_dwordx4 v[90:91], v[76:79], off
	global_store_dwordx4 v[90:91], v[72:75], off offset:16
	v_mov_b32_dpp v90, v76 quad_perm:[0,0,0,0] row_mask:0xf bank_mask:0xf bound_ctrl:1
	v_add_f32_e32 v90, 0, v90
	v_cndmask_b32_e64 v90, 0, v90, s[40:41]
	v_readlane_b32 s4, v250, 12
	v_readlane_b32 s16, v250, 24
	v_add_f32_dpp v91, v76, v90 quad_perm:[1,1,1,1] row_mask:0xf bank_mask:0xf bound_ctrl:1
	v_cndmask_b32_e64 v90, v90, v91, s[44:45]
	v_readlane_b32 s17, v250, 25
	v_readlane_b32 s5, v250, 13
	v_add_f32_dpp v91, v76, v90 quad_perm:[2,2,2,2] row_mask:0xf bank_mask:0xf bound_ctrl:1
	v_cndmask_b32_e64 v90, v90, v91, s[42:43]
	v_lshl_add_u64 v[98:99], s[16:17], 0, v[98:99]
	v_lshl_add_u64 v[98:99], v[98:99], 0, v[82:83]
	v_add_f32_dpp v91, v76, v90 quad_perm:[3,3,3,3] row_mask:0xf bank_mask:0xf bound_ctrl:1
	v_cndmask_b32_e64 v90, v90, v91, s[0:1]
	v_readlane_b32 s6, v250, 14
	v_mov_b32_dpp v91, v77 quad_perm:[0,0,0,0] row_mask:0xf bank_mask:0xf bound_ctrl:1
	v_add_f32_e32 v91, 0, v91
	v_cndmask_b32_e64 v91, 0, v91, s[40:41]
	v_readlane_b32 s7, v250, 15
	v_readlane_b32 s8, v250, 16
	v_add_f32_dpp v92, v77, v91 quad_perm:[1,1,1,1] row_mask:0xf bank_mask:0xf bound_ctrl:1
	v_cndmask_b32_e64 v91, v91, v92, s[44:45]
	v_readlane_b32 s9, v250, 17
	v_readlane_b32 s10, v250, 18
	v_add_f32_dpp v92, v77, v91 quad_perm:[2,2,2,2] row_mask:0xf bank_mask:0xf bound_ctrl:1
	v_cndmask_b32_e64 v91, v91, v92, s[42:43]
	v_readlane_b32 s11, v250, 19
	v_readlane_b32 s12, v250, 20
	v_add_f32_dpp v92, v77, v91 quad_perm:[3,3,3,3] row_mask:0xf bank_mask:0xf bound_ctrl:1
	v_cndmask_b32_e64 v91, v91, v92, s[0:1]
	v_readlane_b32 s13, v250, 21
	v_mov_b32_dpp v92, v78 quad_perm:[0,0,0,0] row_mask:0xf bank_mask:0xf bound_ctrl:1
	v_add_f32_e32 v92, 0, v92
	v_cndmask_b32_e64 v92, 0, v92, s[40:41]
	v_readlane_b32 s14, v250, 22
	v_readlane_b32 s15, v250, 23
	v_add_f32_dpp v93, v78, v92 quad_perm:[1,1,1,1] row_mask:0xf bank_mask:0xf bound_ctrl:1
	v_cndmask_b32_e64 v92, v92, v93, s[44:45]
	v_readlane_b32 s18, v250, 26
	v_readlane_b32 s19, v250, 27
	v_add_f32_dpp v93, v78, v92 quad_perm:[2,2,2,2] row_mask:0xf bank_mask:0xf bound_ctrl:1
	v_cndmask_b32_e64 v92, v92, v93, s[42:43]
	s_nop 1
	v_add_f32_dpp v93, v78, v92 quad_perm:[3,3,3,3] row_mask:0xf bank_mask:0xf bound_ctrl:1
	v_cndmask_b32_e64 v92, v92, v93, s[0:1]
	s_nop 0
	v_mov_b32_dpp v93, v79 quad_perm:[0,0,0,0] row_mask:0xf bank_mask:0xf bound_ctrl:1
	v_add_f32_e32 v93, 0, v93
	v_cndmask_b32_e64 v93, 0, v93, s[40:41]
	s_nop 1
	v_add_f32_dpp v94, v79, v93 quad_perm:[1,1,1,1] row_mask:0xf bank_mask:0xf bound_ctrl:1
	v_cndmask_b32_e64 v93, v93, v94, s[44:45]
	s_nop 1
	v_add_f32_dpp v94, v79, v93 quad_perm:[2,2,2,2] row_mask:0xf bank_mask:0xf bound_ctrl:1
	v_cndmask_b32_e64 v93, v93, v94, s[42:43]
	s_nop 1
	v_add_f32_dpp v94, v79, v93 quad_perm:[3,3,3,3] row_mask:0xf bank_mask:0xf bound_ctrl:1
	v_cndmask_b32_e64 v93, v93, v94, s[0:1]
	s_nop 0
	v_mov_b32_dpp v94, v72 quad_perm:[0,0,0,0] row_mask:0xf bank_mask:0xf bound_ctrl:1
	v_add_f32_e32 v94, 0, v94
	v_cndmask_b32_e64 v94, 0, v94, s[40:41]
	s_nop 1
	v_add_f32_dpp v95, v72, v94 quad_perm:[1,1,1,1] row_mask:0xf bank_mask:0xf bound_ctrl:1
	v_cndmask_b32_e64 v94, v94, v95, s[44:45]
	s_nop 1
	v_add_f32_dpp v95, v72, v94 quad_perm:[2,2,2,2] row_mask:0xf bank_mask:0xf bound_ctrl:1
	v_cndmask_b32_e64 v94, v94, v95, s[42:43]
	s_nop 1
	v_add_f32_dpp v95, v72, v94 quad_perm:[3,3,3,3] row_mask:0xf bank_mask:0xf bound_ctrl:1
	v_cndmask_b32_e64 v94, v94, v95, s[0:1]
	s_nop 0
	v_mov_b32_dpp v95, v73 quad_perm:[0,0,0,0] row_mask:0xf bank_mask:0xf bound_ctrl:1
	v_add_f32_e32 v95, 0, v95
	v_cndmask_b32_e64 v95, 0, v95, s[40:41]
	s_nop 1
	v_add_f32_dpp v96, v73, v95 quad_perm:[1,1,1,1] row_mask:0xf bank_mask:0xf bound_ctrl:1
	v_cndmask_b32_e64 v95, v95, v96, s[44:45]
	s_nop 1
	v_add_f32_dpp v96, v73, v95 quad_perm:[2,2,2,2] row_mask:0xf bank_mask:0xf bound_ctrl:1
	v_cndmask_b32_e64 v95, v95, v96, s[42:43]
	s_nop 1
	v_add_f32_dpp v96, v73, v95 quad_perm:[3,3,3,3] row_mask:0xf bank_mask:0xf bound_ctrl:1
	v_cndmask_b32_e64 v95, v95, v96, s[0:1]
	s_nop 0
	v_mov_b32_dpp v96, v74 quad_perm:[0,0,0,0] row_mask:0xf bank_mask:0xf bound_ctrl:1
	v_add_f32_e32 v96, 0, v96
	v_cndmask_b32_e64 v96, 0, v96, s[40:41]
	s_nop 1
	v_add_f32_dpp v97, v74, v96 quad_perm:[1,1,1,1] row_mask:0xf bank_mask:0xf bound_ctrl:1
	v_cndmask_b32_e64 v96, v96, v97, s[44:45]
	s_nop 1
	v_add_f32_dpp v97, v74, v96 quad_perm:[2,2,2,2] row_mask:0xf bank_mask:0xf bound_ctrl:1
	v_cndmask_b32_e64 v96, v96, v97, s[42:43]
	s_nop 1
	v_add_f32_dpp v97, v74, v96 quad_perm:[3,3,3,3] row_mask:0xf bank_mask:0xf bound_ctrl:1
	v_cndmask_b32_e64 v96, v96, v97, s[0:1]
	s_nop 0
	v_mov_b32_dpp v97, v75 quad_perm:[0,0,0,0] row_mask:0xf bank_mask:0xf bound_ctrl:1
	v_add_f32_e32 v97, 0, v97
	v_cndmask_b32_e64 v97, 0, v97, s[40:41]
	s_nop 1
	v_add_f32_dpp v100, v75, v97 quad_perm:[1,1,1,1] row_mask:0xf bank_mask:0xf bound_ctrl:1
	v_cndmask_b32_e64 v97, v97, v100, s[44:45]
	s_nop 1
	v_add_f32_dpp v100, v75, v97 quad_perm:[2,2,2,2] row_mask:0xf bank_mask:0xf bound_ctrl:1
	v_cndmask_b32_e64 v97, v97, v100, s[42:43]
	s_nop 1
	v_add_f32_dpp v100, v75, v97 quad_perm:[3,3,3,3] row_mask:0xf bank_mask:0xf bound_ctrl:1
	v_cndmask_b32_e64 v97, v97, v100, s[0:1]
	s_and_saveexec_b64 s[74:75], s[38:39]
	s_cbranch_execz .LBB0_2488
	global_load_dwordx4 v[100:103], v[98:99], off offset:16
	global_load_dwordx4 v[104:107], v[98:99], off
	s_waitcnt vmcnt(0)
	v_pk_add_f32 v[94:95], v[94:95], v[100:101]
	v_pk_add_f32 v[96:97], v[96:97], v[102:103]
	v_pk_add_f32 v[92:93], v[92:93], v[106:107]
	v_pk_add_f32 v[90:91], v[90:91], v[104:105]
	s_or_b64 exec, exec, s[74:75]
	s_and_saveexec_b64 s[74:75], s[36:37]
	s_cbranch_execnz .LBB0_2489

; __device__ __forceinline__ void st8bf(bf16_t* p, f32x4 a, f32x4 b) { u32x4 w; w.x = pk2(a[0], a[1]); w.y = pk2(a[2], a[3]); w.z = pk2(b[0], b[1]); w.w = pk2(b[2], b[3]); st16(p, w); }
;     __device__ __forceinline__ void st(int pn, int row, int c, f32x4 v0, f32x4 v1) const {
;     ...
;                 const float inv = 1.f / (float)w;
;                 st8bf(DMs + (size_t)row * 1024 + col, (f32x4){s[0] * inv - x[0], s[1] * inv - x[1], s[2] * inv - x[2], s[3] * inv - x[3]}, (f32x4){s[4] * inv - x[4], s[5] * inv - x[5], s[6] * inv - x[6], s[7] * inv - x[7]});
.LBB0_2201:
	s_or_b64 exec, exec, s[74:75]
	v_readlane_b32 s4, v251, 0
	v_readlane_b32 s5, v251, 1
	v_mov_b32_e32 v101, v78
	v_mov_b32_e32 v78, v77
	v_lshl_add_u64 v[98:99], v[80:81], 1, s[4:5]
	v_lshl_add_u64 v[88:89], v[88:89], 1, v[98:99]
	v_mov_b32_e32 v99, v92
	v_mov_b32_e32 v92, v91
	v_mov_b32_e32 v100, v76
	v_pk_fma_f32 v[76:77], s[68:69], v[92:93], v[78:79] op_sel_hi:[0,1,1] neg_lo:[0,0,1] neg_hi:[0,0,1]
	v_mov_b32_e32 v79, v96
	v_mov_b32_e32 v91, v74
	v_mov_b32_e32 v96, v95
	v_mov_b32_e32 v74, v73
	v_mov_b32_e32 v98, v90
	v_mov_b32_e32 v78, v94
	v_mov_b32_e32 v90, v72
	v_pk_fma_f32 v[72:73], s[68:69], v[96:97], v[74:75] op_sel_hi:[0,1,1] neg_lo:[0,0,1] neg_hi:[0,0,1]
	v_pk_fma_f32 v[98:99], s[68:69], v[98:99], v[100:101] op_sel_hi:[0,1,1] neg_lo:[0,0,1] neg_hi:[0,0,1]
	v_pk_fma_f32 v[78:79], s[68:69], v[78:79], v[90:91] op_sel_hi:[0,1,1] neg_lo:[0,0,1] neg_hi:[0,0,1]
	v_cvt_pk_bf16_f32 v75, v79, v73
	v_cvt_pk_bf16_f32 v74, v78, v72
	v_cvt_pk_bf16_f32 v73, v99, v77
	v_cvt_pk_bf16_f32 v72, v98, v76
	global_store_dwordx4 v[88:89], v[72:75], off

; __device__ __forceinline__ unsigned pk2(float lo, float hi) { return f2bf(lo) | (f2bf(hi) << 16); }
; __device__ __forceinline__ float sigmoidf_(float x) { return __builtin_amdgcn_rcpf(1.0f + __expf(-x)); }
; __device__ __forceinline__ void st8bf(bf16_t* p, f32x4 a, f32x4 b) { u32x4 w; w.x = pk2(a[0], a[1]); w.y = pk2(a[2], a[3]); w.z = pk2(b[0], b[1]); w.w = pk2(b[2], b[3]); st16(p, w); }
; __device__ __forceinline__ void stnt8(float* o, f32x4 a, f32x4 b) { __builtin_nontemporal_store(a, (f32x4*)o); __builtin_nontemporal_store(b, (f32x4*)(o + 4)); }
; __device__ __forceinline__ f32x4 sig4(f32x4 v) { f32x4 r; r[0] = sigmoidf_(v[0]); r[1] = sigmoidf_(v[1]); r[2] = sigmoidf_(v[2]); r[3] = sigmoidf_(v[3]); return r; }
;     __device__ __forceinline__ void st(int pn, int row, int c, f32x4 v0, f32x4 v1) const {
;     ...
;         else st8bf(GT + (size_t)row * 1024 + (pn - 4) * 256 + c, v0 * sig4(v0), v1 * sig4(v1));
.LBB0_2205:
	v_lshl_add_u64 v[72:73], s[54:55], 0, v[86:87]
	v_mul_f32_e32 v74, 0xbfb8aa3b, v68
	v_exp_f32_e32 v74, v74
	v_lshl_add_u64 v[72:73], s[60:61], 1, v[72:73]
	v_lshlrev_b32_e32 v138, 1, v140
	v_lshl_add_u64 v[76:77], v[72:73], 0, v[138:139]
	v_mul_f32_e32 v73, 0xbfb8aa3b, v69
	v_exp_f32_e32 v73, v73
	v_add_f32_e32 v72, 1.0, v74
	v_mul_f32_e32 v74, 0xbfb8aa3b, v70
	v_mul_f32_e32 v75, 0xbfb8aa3b, v71
	v_exp_f32_e32 v74, v74
	v_exp_f32_e32 v75, v75
	v_add_f32_e32 v73, 1.0, v73
	v_rcp_f32_e32 v72, v72
	v_rcp_f32_e32 v73, v73
	v_mul_f32_e32 v78, 0xbfb8aa3b, v64
	v_mul_f32_e32 v79, 0xbfb8aa3b, v65
	v_exp_f32_e32 v78, v78
	v_exp_f32_e32 v79, v79
	v_add_f32_e32 v74, 1.0, v74
	v_add_f32_e32 v75, 1.0, v75
	v_rcp_f32_e32 v74, v74
	v_rcp_f32_e32 v75, v75
	v_mul_f32_e32 v86, 0xbfb8aa3b, v66
	v_mul_f32_e32 v87, 0xbfb8aa3b, v67
	v_exp_f32_e32 v86, v86
	v_exp_f32_e32 v87, v87
	v_pk_mul_f32 v[72:73], v[68:69], v[72:73]
	v_add_f32_e32 v78, 1.0, v78
	v_add_f32_e32 v79, 1.0, v79
	v_bfe_u32 v88, v72, 16, 1
	v_rcp_f32_e32 v78, v78
	v_rcp_f32_e32 v79, v79
	v_add3_u32 v72, v72, v88, s89
	v_bfe_u32 v88, v73, 16, 1
	v_pk_mul_f32 v[74:75], v[70:71], v[74:75]
	v_lshrrev_b32_e32 v72, 16, v72
	v_add3_u32 v73, v73, v88, s89
	v_add_f32_e32 v86, 1.0, v86
	v_add_f32_e32 v87, 1.0, v87
	v_and_or_b32 v72, v73, s91, v72
	v_rcp_f32_e32 v86, v86
	v_rcp_f32_e32 v87, v87
	v_pk_mul_f32 v[78:79], v[64:65], v[78:79]
	v_cvt_pk_bf16_f32 v73, v74, v75
	v_pk_mul_f32 v[86:87], v[66:67], v[86:87]
	v_cvt_pk_bf16_f32 v74, v78, v79
	v_cvt_pk_bf16_f32 v75, v86, v87
	global_store_dwordx4 v[76:77], v[72:75], off offset:256
	s_cbranch_execnz .LBB0_2225
; __device__ __forceinline__ void st16f(float* p, f32x4 v) { st16(p, __builtin_bit_cast(u32x4, v)); }
; __device__ __forceinline__ void st8bf(bf16_t* p, f32x4 a, f32x4 b) { u32x4 w; w.x = pk2(a[0], a[1]); w.y = pk2(a[2], a[3]); w.z = pk2(b[0], b[1]); w.w = pk2(b[2], b[3]); st16(p, w); }
;     __device__ __forceinline__ void st(int pn, int row, int c, f32x4 v0, f32x4 v1) const {
;     ...
;         if (pn < 4) { const int col = pn * 256 + c; float* o = nullptr;
;             if (smp) o = out + O_POOLS + ((size_t)b * 15 + 11 + t) * 1024 + col;
;             st8bf(V + (size_t)row * 1024 + col, v0, v1); if (o) { st16f(o, v0); st16f(o + 4, v1); }
;             if (smp) {
;                 const int w = 2 << pn;
;                 float x[8] = {v0[0], v0[1], v0[2], v0[3], v1[0], v1[1], v1[2], v1[3]}, s[8];
; #pragma unroll
;                 for (int e = 0; e < 8; ++e) { s[e] = 0.f;
; #pragma unroll
;                     for (int tp = 0; tp < 4; ++tp) { const float xo = quad_bcast(x[e], tp); if (tp <= t && t - tp < w) s[e] += xo; } }
;                 const int e_lo = 15 + t - w + 1;
; #pragma unroll
;                 for (int e2 = 0; e2 < 15; ++e2) if (e2 >= e_lo) { const float* sp = state_pool + ((size_t)b * 15 + e2) * 1024 + col; const f32x4 a = *(const f32x4*)sp, d = *(const f32x4*)(sp + 4);
;                     s[0] += a[0]; s[1] += a[1]; s[2] += a[2]; s[3] += a[3]; s[4] += d[0]; s[5] += d[1]; s[6] += d[2]; s[7] += d[3]; }
.LBB0_2206:
	s_ashr_i32 s71, s70, 31
	v_lshl_add_u64 v[74:75], v[80:81], 1, s[52:53]
	v_lshl_add_u64 v[72:73], s[70:71], 0, v[140:141]
	v_lshl_add_u64 v[78:79], v[72:73], 1, v[74:75]
	v_cvt_pk_bf16_f32 v74, v68, v69
	v_cvt_pk_bf16_f32 v75, v70, v71
	v_cvt_pk_bf16_f32 v76, v64, v65
	v_cvt_pk_bf16_f32 v77, v66, v67
	global_store_dwordx4 v[78:79], v[74:77], off offset:256
	s_and_saveexec_b64 s[72:73], s[48:49]
	s_cbranch_execz .LBB0_2224
	v_readlane_b32 s4, v250, 58
	v_readlane_b32 s5, v250, 59
	v_lshlrev_b64 v[86:87], 2, v[72:73]
	s_nop 0
	v_lshl_add_u64 v[74:75], s[4:5], 0, v[84:85]
	v_lshl_add_u64 v[74:75], v[74:75], 0, v[86:87]
	global_store_dwordx4 v[74:75], v[68:71], off offset:512
	global_store_dwordx4 v[74:75], v[64:67], off offset:528
	v_mov_b32_dpp v74, v68 quad_perm:[0,0,0,0] row_mask:0xf bank_mask:0xf bound_ctrl:1
	v_add_f32_e32 v74, 0, v74
	v_cndmask_b32_e64 v74, 0, v74, s[40:41]
	v_readlane_b32 s4, v250, 12
	v_readlane_b32 s16, v250, 24
	v_add_f32_dpp v75, v68, v74 quad_perm:[1,1,1,1] row_mask:0xf bank_mask:0xf bound_ctrl:1
	v_cndmask_b32_e64 v74, v74, v75, s[44:45]
	v_readlane_b32 s17, v250, 25
	v_readlane_b32 s5, v250, 13
	v_add_f32_dpp v75, v68, v74 quad_perm:[2,2,2,2] row_mask:0xf bank_mask:0xf bound_ctrl:1
	v_cndmask_b32_e64 v74, v74, v75, s[42:43]
	v_lshl_add_u64 v[86:87], s[16:17], 0, v[86:87]
	v_lshl_add_u64 v[82:83], v[86:87], 0, v[82:83]
	v_add_f32_dpp v75, v68, v74 quad_perm:[3,3,3,3] row_mask:0xf bank_mask:0xf bound_ctrl:1
	v_cndmask_b32_e64 v74, v74, v75, s[0:1]
	v_readlane_b32 s6, v250, 14
	v_mov_b32_dpp v75, v69 quad_perm:[0,0,0,0] row_mask:0xf bank_mask:0xf bound_ctrl:1
	v_add_f32_e32 v75, 0, v75
	v_cndmask_b32_e64 v75, 0, v75, s[40:41]
	v_readlane_b32 s7, v250, 15
	v_readlane_b32 s8, v250, 16
	v_add_f32_dpp v76, v69, v75 quad_perm:[1,1,1,1] row_mask:0xf bank_mask:0xf bound_ctrl:1
	v_cndmask_b32_e64 v75, v75, v76, s[44:45]
	v_readlane_b32 s9, v250, 17
	v_readlane_b32 s10, v250, 18
	v_add_f32_dpp v76, v69, v75 quad_perm:[2,2,2,2] row_mask:0xf bank_mask:0xf bound_ctrl:1
	v_cndmask_b32_e64 v75, v75, v76, s[42:43]
	v_readlane_b32 s11, v250, 19
	v_readlane_b32 s12, v250, 20
	v_add_f32_dpp v76, v69, v75 quad_perm:[3,3,3,3] row_mask:0xf bank_mask:0xf bound_ctrl:1
	v_cndmask_b32_e64 v75, v75, v76, s[0:1]
	v_readlane_b32 s13, v250, 21
	v_mov_b32_dpp v76, v70 quad_perm:[0,0,0,0] row_mask:0xf bank_mask:0xf bound_ctrl:1
	v_add_f32_e32 v76, 0, v76
	v_cndmask_b32_e64 v76, 0, v76, s[40:41]
	v_readlane_b32 s14, v250, 22
	v_readlane_b32 s15, v250, 23
	v_add_f32_dpp v77, v70, v76 quad_perm:[1,1,1,1] row_mask:0xf bank_mask:0xf bound_ctrl:1
	v_cndmask_b32_e64 v76, v76, v77, s[44:45]
	v_readlane_b32 s18, v250, 26
	v_readlane_b32 s19, v250, 27
	v_add_f32_dpp v77, v70, v76 quad_perm:[2,2,2,2] row_mask:0xf bank_mask:0xf bound_ctrl:1
	v_cndmask_b32_e64 v76, v76, v77, s[42:43]
	s_nop 1
	v_add_f32_dpp v77, v70, v76 quad_perm:[3,3,3,3] row_mask:0xf bank_mask:0xf bound_ctrl:1
	v_cndmask_b32_e64 v76, v76, v77, s[0:1]
	s_nop 0
	v_mov_b32_dpp v77, v71 quad_perm:[0,0,0,0] row_mask:0xf bank_mask:0xf bound_ctrl:1
	v_add_f32_e32 v77, 0, v77
	v_cndmask_b32_e64 v77, 0, v77, s[40:41]
	s_nop 1
	v_add_f32_dpp v78, v71, v77 quad_perm:[1,1,1,1] row_mask:0xf bank_mask:0xf bound_ctrl:1
	v_cndmask_b32_e64 v77, v77, v78, s[44:45]
	s_nop 1
	v_add_f32_dpp v78, v71, v77 quad_perm:[2,2,2,2] row_mask:0xf bank_mask:0xf bound_ctrl:1
	v_cndmask_b32_e64 v77, v77, v78, s[42:43]
	s_nop 1
	v_add_f32_dpp v78, v71, v77 quad_perm:[3,3,3,3] row_mask:0xf bank_mask:0xf bound_ctrl:1
	v_cndmask_b32_e64 v77, v77, v78, s[0:1]
	s_nop 0
	v_mov_b32_dpp v78, v64 quad_perm:[0,0,0,0] row_mask:0xf bank_mask:0xf bound_ctrl:1
	v_add_f32_e32 v78, 0, v78
	v_cndmask_b32_e64 v78, 0, v78, s[40:41]
	s_nop 1
	v_add_f32_dpp v79, v64, v78 quad_perm:[1,1,1,1] row_mask:0xf bank_mask:0xf bound_ctrl:1
	v_cndmask_b32_e64 v78, v78, v79, s[44:45]
	s_nop 1
	v_add_f32_dpp v79, v64, v78 quad_perm:[2,2,2,2] row_mask:0xf bank_mask:0xf bound_ctrl:1
	v_cndmask_b32_e64 v78, v78, v79, s[42:43]
	s_nop 1
	v_add_f32_dpp v79, v64, v78 quad_perm:[3,3,3,3] row_mask:0xf bank_mask:0xf bound_ctrl:1
	v_cndmask_b32_e64 v78, v78, v79, s[0:1]
	s_nop 0
	v_mov_b32_dpp v79, v65 quad_perm:[0,0,0,0] row_mask:0xf bank_mask:0xf bound_ctrl:1
	v_add_f32_e32 v79, 0, v79
	v_cndmask_b32_e64 v79, 0, v79, s[40:41]
	s_nop 1
	v_add_f32_dpp v84, v65, v79 quad_perm:[1,1,1,1] row_mask:0xf bank_mask:0xf bound_ctrl:1
	v_cndmask_b32_e64 v79, v79, v84, s[44:45]
	s_nop 1
	v_add_f32_dpp v84, v65, v79 quad_perm:[2,2,2,2] row_mask:0xf bank_mask:0xf bound_ctrl:1
	v_cndmask_b32_e64 v79, v79, v84, s[42:43]
	s_nop 1
	v_add_f32_dpp v84, v65, v79 quad_perm:[3,3,3,3] row_mask:0xf bank_mask:0xf bound_ctrl:1
	v_cndmask_b32_e64 v79, v79, v84, s[0:1]
	s_nop 0
	v_mov_b32_dpp v84, v66 quad_perm:[0,0,0,0] row_mask:0xf bank_mask:0xf bound_ctrl:1
	v_add_f32_e32 v84, 0, v84
	v_cndmask_b32_e64 v84, 0, v84, s[40:41]
	s_nop 1
	v_add_f32_dpp v85, v66, v84 quad_perm:[1,1,1,1] row_mask:0xf bank_mask:0xf bound_ctrl:1
	v_cndmask_b32_e64 v84, v84, v85, s[44:45]
	s_nop 1
	v_add_f32_dpp v85, v66, v84 quad_perm:[2,2,2,2] row_mask:0xf bank_mask:0xf bound_ctrl:1
	v_cndmask_b32_e64 v84, v84, v85, s[42:43]
	s_nop 1
	v_add_f32_dpp v85, v66, v84 quad_perm:[3,3,3,3] row_mask:0xf bank_mask:0xf bound_ctrl:1
	v_cndmask_b32_e64 v84, v84, v85, s[0:1]
	s_nop 0
	v_mov_b32_dpp v85, v67 quad_perm:[0,0,0,0] row_mask:0xf bank_mask:0xf bound_ctrl:1
	v_add_f32_e32 v85, 0, v85
	v_cndmask_b32_e64 v85, 0, v85, s[40:41]
	s_nop 1
	v_add_f32_dpp v88, v67, v85 quad_perm:[1,1,1,1] row_mask:0xf bank_mask:0xf bound_ctrl:1
	v_cndmask_b32_e64 v85, v85, v88, s[44:45]
	s_nop 1
	v_add_f32_dpp v88, v67, v85 quad_perm:[2,2,2,2] row_mask:0xf bank_mask:0xf bound_ctrl:1
	v_cndmask_b32_e64 v85, v85, v88, s[42:43]
	s_nop 1
	v_add_f32_dpp v88, v67, v85 quad_perm:[3,3,3,3] row_mask:0xf bank_mask:0xf bound_ctrl:1
	v_cndmask_b32_e64 v85, v85, v88, s[0:1]
	s_and_saveexec_b64 s[48:49], s[38:39]
	s_cbranch_execz .LBB0_2502
	global_load_dwordx4 v[86:89], v[82:83], off offset:528
	global_load_dwordx4 v[90:93], v[82:83], off offset:512
	s_waitcnt vmcnt(0)
	v_pk_add_f32 v[78:79], v[78:79], v[86:87]
	v_pk_add_f32 v[84:85], v[84:85], v[88:89]
	v_pk_add_f32 v[76:77], v[76:77], v[92:93]
	v_pk_add_f32 v[74:75], v[74:75], v[90:91]
	s_or_b64 exec, exec, s[48:49]
	s_and_saveexec_b64 s[48:49], s[36:37]
	s_cbranch_execnz .LBB0_2503

; __device__ __forceinline__ void st8bf(bf16_t* p, f32x4 a, f32x4 b) { u32x4 w; w.x = pk2(a[0], a[1]); w.y = pk2(a[2], a[3]); w.z = pk2(b[0], b[1]); w.w = pk2(b[2], b[3]); st16(p, w); }
;     __device__ __forceinline__ void st(int pn, int row, int c, f32x4 v0, f32x4 v1) const {
;     ...
;                 const float inv = 1.f / (float)w;
;                 st8bf(DMs + (size_t)row * 1024 + col, (f32x4){s[0] * inv - x[0], s[1] * inv - x[1], s[2] * inv - x[2], s[3] * inv - x[3]}, (f32x4){s[4] * inv - x[4], s[5] * inv - x[5], s[6] * inv - x[6], s[7] * inv - x[7]});
.LBB0_2223:
	s_or_b64 exec, exec, s[48:49]
	v_readlane_b32 s4, v251, 0
	v_readlane_b32 s5, v251, 1
	v_mov_b32_e32 v83, v70
	v_mov_b32_e32 v70, v69
	v_lshl_add_u64 v[80:81], v[80:81], 1, s[4:5]
	v_lshl_add_u64 v[72:73], v[72:73], 1, v[80:81]
	v_mov_b32_e32 v81, v76
	v_mov_b32_e32 v76, v75
	v_mov_b32_e32 v82, v68
	v_pk_fma_f32 v[68:69], s[68:69], v[76:77], v[70:71] op_sel_hi:[0,1,1] neg_lo:[0,0,1] neg_hi:[0,0,1]
	v_mov_b32_e32 v71, v84
	v_mov_b32_e32 v75, v66
	v_mov_b32_e32 v84, v79
	v_mov_b32_e32 v66, v65
	v_mov_b32_e32 v80, v74
	v_mov_b32_e32 v70, v78
	v_mov_b32_e32 v74, v64
	v_pk_fma_f32 v[64:65], s[68:69], v[84:85], v[66:67] op_sel_hi:[0,1,1] neg_lo:[0,0,1] neg_hi:[0,0,1]
	v_pk_fma_f32 v[80:81], s[68:69], v[80:81], v[82:83] op_sel_hi:[0,1,1] neg_lo:[0,0,1] neg_hi:[0,0,1]
	v_pk_fma_f32 v[70:71], s[68:69], v[70:71], v[74:75] op_sel_hi:[0,1,1] neg_lo:[0,0,1] neg_hi:[0,0,1]
	v_cvt_pk_bf16_f32 v67, v71, v65
	v_cvt_pk_bf16_f32 v66, v70, v64
	v_cvt_pk_bf16_f32 v65, v81, v69
	v_cvt_pk_bf16_f32 v64, v80, v68
	global_store_dwordx4 v[72:73], v[64:67], off offset:256

; __device__ __forceinline__ void st8bf(bf16_t* p, f32x4 a, f32x4 b) { u32x4 w; w.x = pk2(a[0], a[1]); w.y = pk2(a[2], a[3]); w.z = pk2(b[0], b[1]); w.w = pk2(b[2], b[3]); st16(p, w); }
; __device__ __forceinline__ f32x4 sig4(f32x4 v) { f32x4 r; r[0] = sigmoidf_(v[0]); r[1] = sigmoidf_(v[1]); r[2] = sigmoidf_(v[2]); r[3] = sigmoidf_(v[3]); return r; }
; #define EPI_LOOP_ROWS(body) _Pragma("unroll") for (int ai = 0; ai < 2; ++ai) _Pragma("unroll") for (int m = 0; m < 4; ++m) { const int row = u.pm * 256 + ai * 128 + wr * 64 + m * 16 + fr; body }
;     __device__ __forceinline__ void st(int pn, int row, int c, f32x4 v0, f32x4 v1) const {
;     ...
;         else st8bf(GT + (size_t)row * 1024 + (pn - 4) * 256 + c, v0 * sig4(v0), v1 * sig4(v1));
;     }
;     __device__ __forceinline__ void operator()(const f32x4 (&acc)[2][2][4][2], const pg8::Unit& u, int wr, int wc, int fr, int fq) const {
;         const int cw = wc * 32 + 8 * fq;
;         EPI_LOOP_ROWS( _Pragma("unroll") for (int bj = 0; bj < 2; ++bj) st(u.pn, row, bj * 128 + cw, acc[ai][bj][m][0], acc[ai][bj][m][1]); )
.LBB0_2225:
	s_nop 0
	v_add_u32_e32 v64, 0x80, v150
	v_ashrrev_i32_e32 v65, 31, v64
	v_cmp_lt_i32_e64 s[48:49], s89, v64
	v_lshlrev_b64 v[70:71], 11, v[64:65]
	s_and_b64 vcc, exec, s[46:47]
	s_mov_b64 s[72:73], -1
	s_cbranch_vccnz .LBB0_2227
	v_lshl_add_u64 v[66:67], s[54:55], 0, v[70:71]
	v_mul_f32_e32 v68, 0xbfb8aa3b, v60
	v_exp_f32_e32 v68, v68
	v_lshl_add_u64 v[66:67], s[60:61], 1, v[66:67]
	v_lshlrev_b32_e32 v138, 1, v140
	v_lshl_add_u64 v[72:73], v[66:67], 0, v[138:139]
	v_mul_f32_e32 v67, 0xbfb8aa3b, v61
	v_exp_f32_e32 v67, v67
	v_add_f32_e32 v66, 1.0, v68
	v_mul_f32_e32 v68, 0xbfb8aa3b, v62
	v_mul_f32_e32 v69, 0xbfb8aa3b, v63
	v_exp_f32_e32 v68, v68
	v_exp_f32_e32 v69, v69
	v_add_f32_e32 v67, 1.0, v67
	v_rcp_f32_e32 v66, v66
	v_rcp_f32_e32 v67, v67
	v_mul_f32_e32 v74, 0xbfb8aa3b, v56
	v_mul_f32_e32 v75, 0xbfb8aa3b, v57
	v_exp_f32_e32 v74, v74
	v_exp_f32_e32 v75, v75
	v_add_f32_e32 v68, 1.0, v68
	v_add_f32_e32 v69, 1.0, v69
	v_rcp_f32_e32 v68, v68
	v_rcp_f32_e32 v69, v69
	v_mul_f32_e32 v76, 0xbfb8aa3b, v58
	v_mul_f32_e32 v77, 0xbfb8aa3b, v59
	v_exp_f32_e32 v76, v76
	v_exp_f32_e32 v77, v77
	v_pk_mul_f32 v[66:67], v[60:61], v[66:67]
	v_add_f32_e32 v74, 1.0, v74
	v_add_f32_e32 v75, 1.0, v75
	v_rcp_f32_e32 v74, v74
	v_rcp_f32_e32 v75, v75
	v_pk_mul_f32 v[68:69], v[62:63], v[68:69]
	v_add_f32_e32 v76, 1.0, v76
	v_add_f32_e32 v77, 1.0, v77
	v_cvt_pk_bf16_f32 v66, v66, v67
	v_rcp_f32_e32 v76, v76
	v_rcp_f32_e32 v77, v77
	v_pk_mul_f32 v[74:75], v[56:57], v[74:75]
	v_cvt_pk_bf16_f32 v67, v68, v69
	v_pk_mul_f32 v[76:77], v[58:59], v[76:77]
	v_cvt_pk_bf16_f32 v68, v74, v75
	v_cvt_pk_bf16_f32 v69, v76, v77
	s_mov_b64 s[72:73], 0
	global_store_dwordx4 v[72:73], v[66:69], off
; __device__ __forceinline__ void st16f(float* p, f32x4 v) { st16(p, __builtin_bit_cast(u32x4, v)); }
; __device__ __forceinline__ void st8bf(bf16_t* p, f32x4 a, f32x4 b) { u32x4 w; w.x = pk2(a[0], a[1]); w.y = pk2(a[2], a[3]); w.z = pk2(b[0], b[1]); w.w = pk2(b[2], b[3]); st16(p, w); }
;     __device__ __forceinline__ void st(int pn, int row, int c, f32x4 v0, f32x4 v1) const {
;         const bool smp = row >= MP; const int b = smp ? (row - MP) >> 2 : row >> 13, t = smp ? (row - MP) & 3 : row & (SEQ - 1);
;         if (pn < 4) { const int col = pn * 256 + c; float* o = nullptr;
;             if (smp) o = out + O_POOLS + ((size_t)b * 15 + 11 + t) * 1024 + col;
;             st8bf(V + (size_t)row * 1024 + col, v0, v1); if (o) { st16f(o, v0); st16f(o + 4, v1); }
;             if (smp) {
;                 const int w = 2 << pn;
;                 float x[8] = {v0[0], v0[1], v0[2], v0[3], v1[0], v1[1], v1[2], v1[3]}, s[8];
; #pragma unroll
;                 for (int e = 0; e < 8; ++e) { s[e] = 0.f;
; #pragma unroll
;                     for (int tp = 0; tp < 4; ++tp) { const float xo = quad_bcast(x[e], tp); if (tp <= t && t - tp < w) s[e] += xo; } }
;                 const int e_lo = 15 + t - w + 1;
; #pragma unroll
;                 for (int e2 = 0; e2 < 15; ++e2) if (e2 >= e_lo) { const float* sp = state_pool + ((size_t)b * 15 + e2) * 1024 + col; const f32x4 a = *(const f32x4*)sp, d = *(const f32x4*)(sp + 4);
;                     s[0] += a[0]; s[1] += a[1]; s[2] += a[2]; s[3] += a[3]; s[4] += d[0]; s[5] += d[1]; s[6] += d[2]; s[7] += d[3]; }
.LBB0_2227:
	s_nop 1
	v_add_u32_e32 v66, 0xffff8080, v150
	v_lshrrev_b32_e32 v72, 2, v66
	v_mad_u64_u32 v[66:67], s[74:75], v72, 15, v[128:129]
	v_lshlrev_b64 v[68:69], 12, v[66:67]
	v_lshlrev_b64 v[64:65], 10, v[64:65]
	s_andn2_b64 vcc, exec, s[72:73]
	v_mad_u64_u32 v[66:67], s[72:73], v72, s90, 0
	s_cbranch_vccnz .LBB0_2248
	v_or_b32_e32 v72, s70, v140
	v_ashrrev_i32_e32 v73, 31, v72
	v_lshl_add_u64 v[74:75], v[64:65], 1, s[52:53]
	v_lshl_add_u64 v[78:79], v[72:73], 1, v[74:75]
	v_cvt_pk_bf16_f32 v74, v60, v61
	v_cvt_pk_bf16_f32 v75, v62, v63
	v_cvt_pk_bf16_f32 v76, v56, v57
	v_bfe_u32 v77, v58, 16, 1
	v_add3_u32 v77, v58, v77, s89
	v_bfe_u32 v80, v59, 16, 1
	v_lshrrev_b32_e32 v77, 16, v77
	v_add3_u32 v80, v59, v80, s89
	v_and_or_b32 v77, v80, s91, v77
	global_store_dwordx4 v[78:79], v[74:77], off
	s_and_saveexec_b64 s[72:73], s[48:49]
	s_cbranch_execz .LBB0_2246
	v_readlane_b32 s4, v250, 58
	v_readlane_b32 s5, v250, 59
	v_lshlrev_b64 v[82:83], 2, v[72:73]
	s_nop 0
	v_lshl_add_u64 v[74:75], s[4:5], 0, v[68:69]
	v_lshl_add_u64 v[74:75], v[74:75], 0, v[82:83]
	global_store_dwordx4 v[74:75], v[60:63], off
	global_store_dwordx4 v[74:75], v[56:59], off offset:16
	v_mov_b32_dpp v74, v60 quad_perm:[0,0,0,0] row_mask:0xf bank_mask:0xf bound_ctrl:1
	v_add_f32_e32 v74, 0, v74
	v_cndmask_b32_e64 v74, 0, v74, s[40:41]
	v_readlane_b32 s4, v250, 12
	v_readlane_b32 s16, v250, 24
	v_add_f32_dpp v75, v60, v74 quad_perm:[1,1,1,1] row_mask:0xf bank_mask:0xf bound_ctrl:1
	v_cndmask_b32_e64 v74, v74, v75, s[44:45]
	v_readlane_b32 s17, v250, 25
	v_readlane_b32 s5, v250, 13
	v_add_f32_dpp v75, v60, v74 quad_perm:[2,2,2,2] row_mask:0xf bank_mask:0xf bound_ctrl:1
	v_cndmask_b32_e64 v74, v74, v75, s[42:43]
	v_lshl_add_u64 v[82:83], s[16:17], 0, v[82:83]
	v_lshl_add_u64 v[82:83], v[82:83], 0, v[66:67]
	v_add_f32_dpp v75, v60, v74 quad_perm:[3,3,3,3] row_mask:0xf bank_mask:0xf bound_ctrl:1
	v_cndmask_b32_e64 v74, v74, v75, s[0:1]
	v_readlane_b32 s6, v250, 14
	v_mov_b32_dpp v75, v61 quad_perm:[0,0,0,0] row_mask:0xf bank_mask:0xf bound_ctrl:1
	v_add_f32_e32 v75, 0, v75
	v_cndmask_b32_e64 v75, 0, v75, s[40:41]
	v_readlane_b32 s7, v250, 15
	v_readlane_b32 s8, v250, 16
	v_add_f32_dpp v76, v61, v75 quad_perm:[1,1,1,1] row_mask:0xf bank_mask:0xf bound_ctrl:1
	v_cndmask_b32_e64 v75, v75, v76, s[44:45]
	v_readlane_b32 s9, v250, 17
	v_readlane_b32 s10, v250, 18
	v_add_f32_dpp v76, v61, v75 quad_perm:[2,2,2,2] row_mask:0xf bank_mask:0xf bound_ctrl:1
	v_cndmask_b32_e64 v75, v75, v76, s[42:43]
	v_readlane_b32 s11, v250, 19
	v_readlane_b32 s12, v250, 20
	v_add_f32_dpp v76, v61, v75 quad_perm:[3,3,3,3] row_mask:0xf bank_mask:0xf bound_ctrl:1
	v_cndmask_b32_e64 v75, v75, v76, s[0:1]
	v_readlane_b32 s13, v250, 21
	v_mov_b32_dpp v76, v62 quad_perm:[0,0,0,0] row_mask:0xf bank_mask:0xf bound_ctrl:1
	v_add_f32_e32 v76, 0, v76
	v_cndmask_b32_e64 v76, 0, v76, s[40:41]
	v_readlane_b32 s14, v250, 22
	v_readlane_b32 s15, v250, 23
	v_add_f32_dpp v77, v62, v76 quad_perm:[1,1,1,1] row_mask:0xf bank_mask:0xf bound_ctrl:1
	v_cndmask_b32_e64 v76, v76, v77, s[44:45]
	v_readlane_b32 s18, v250, 26
	v_readlane_b32 s19, v250, 27
	v_add_f32_dpp v77, v62, v76 quad_perm:[2,2,2,2] row_mask:0xf bank_mask:0xf bound_ctrl:1
	v_cndmask_b32_e64 v76, v76, v77, s[42:43]
	s_nop 1
	v_add_f32_dpp v77, v62, v76 quad_perm:[3,3,3,3] row_mask:0xf bank_mask:0xf bound_ctrl:1
	v_cndmask_b32_e64 v76, v76, v77, s[0:1]
	s_nop 0
	v_mov_b32_dpp v77, v63 quad_perm:[0,0,0,0] row_mask:0xf bank_mask:0xf bound_ctrl:1
	v_add_f32_e32 v77, 0, v77
	v_cndmask_b32_e64 v77, 0, v77, s[40:41]
	s_nop 1
	v_add_f32_dpp v78, v63, v77 quad_perm:[1,1,1,1] row_mask:0xf bank_mask:0xf bound_ctrl:1
	v_cndmask_b32_e64 v77, v77, v78, s[44:45]
	s_nop 1
	v_add_f32_dpp v78, v63, v77 quad_perm:[2,2,2,2] row_mask:0xf bank_mask:0xf bound_ctrl:1
	v_cndmask_b32_e64 v77, v77, v78, s[42:43]
	s_nop 1
	v_add_f32_dpp v78, v63, v77 quad_perm:[3,3,3,3] row_mask:0xf bank_mask:0xf bound_ctrl:1
	v_cndmask_b32_e64 v77, v77, v78, s[0:1]
	s_nop 0
	v_mov_b32_dpp v78, v56 quad_perm:[0,0,0,0] row_mask:0xf bank_mask:0xf bound_ctrl:1
	v_add_f32_e32 v78, 0, v78
	v_cndmask_b32_e64 v78, 0, v78, s[40:41]
	s_nop 1
	v_add_f32_dpp v79, v56, v78 quad_perm:[1,1,1,1] row_mask:0xf bank_mask:0xf bound_ctrl:1
	v_cndmask_b32_e64 v78, v78, v79, s[44:45]
	s_nop 1
	v_add_f32_dpp v79, v56, v78 quad_perm:[2,2,2,2] row_mask:0xf bank_mask:0xf bound_ctrl:1
	v_cndmask_b32_e64 v78, v78, v79, s[42:43]
	s_nop 1
	v_add_f32_dpp v79, v56, v78 quad_perm:[3,3,3,3] row_mask:0xf bank_mask:0xf bound_ctrl:1
	v_cndmask_b32_e64 v78, v78, v79, s[0:1]
	s_nop 0
	v_mov_b32_dpp v79, v57 quad_perm:[0,0,0,0] row_mask:0xf bank_mask:0xf bound_ctrl:1
	v_add_f32_e32 v79, 0, v79
	v_cndmask_b32_e64 v79, 0, v79, s[40:41]
	s_nop 1
	v_add_f32_dpp v80, v57, v79 quad_perm:[1,1,1,1] row_mask:0xf bank_mask:0xf bound_ctrl:1
	v_cndmask_b32_e64 v79, v79, v80, s[44:45]
	s_nop 1
	v_add_f32_dpp v80, v57, v79 quad_perm:[2,2,2,2] row_mask:0xf bank_mask:0xf bound_ctrl:1
	v_cndmask_b32_e64 v79, v79, v80, s[42:43]
	s_nop 1
	v_add_f32_dpp v80, v57, v79 quad_perm:[3,3,3,3] row_mask:0xf bank_mask:0xf bound_ctrl:1
	v_cndmask_b32_e64 v79, v79, v80, s[0:1]
	s_nop 0
	v_mov_b32_dpp v80, v58 quad_perm:[0,0,0,0] row_mask:0xf bank_mask:0xf bound_ctrl:1
	v_add_f32_e32 v80, 0, v80
	v_cndmask_b32_e64 v80, 0, v80, s[40:41]
	s_nop 1
	v_add_f32_dpp v81, v58, v80 quad_perm:[1,1,1,1] row_mask:0xf bank_mask:0xf bound_ctrl:1
	v_cndmask_b32_e64 v80, v80, v81, s[44:45]
	s_nop 1
	v_add_f32_dpp v81, v58, v80 quad_perm:[2,2,2,2] row_mask:0xf bank_mask:0xf bound_ctrl:1
	v_cndmask_b32_e64 v80, v80, v81, s[42:43]
	s_nop 1
	v_add_f32_dpp v81, v58, v80 quad_perm:[3,3,3,3] row_mask:0xf bank_mask:0xf bound_ctrl:1
	v_cndmask_b32_e64 v80, v80, v81, s[0:1]
	s_nop 0
	v_mov_b32_dpp v81, v59 quad_perm:[0,0,0,0] row_mask:0xf bank_mask:0xf bound_ctrl:1
	v_add_f32_e32 v81, 0, v81
	v_cndmask_b32_e64 v81, 0, v81, s[40:41]
	s_nop 1
	v_add_f32_dpp v84, v59, v81 quad_perm:[1,1,1,1] row_mask:0xf bank_mask:0xf bound_ctrl:1
	v_cndmask_b32_e64 v81, v81, v84, s[44:45]
	s_nop 1
	v_add_f32_dpp v84, v59, v81 quad_perm:[2,2,2,2] row_mask:0xf bank_mask:0xf bound_ctrl:1
	v_cndmask_b32_e64 v81, v81, v84, s[42:43]
	s_nop 1
	v_add_f32_dpp v84, v59, v81 quad_perm:[3,3,3,3] row_mask:0xf bank_mask:0xf bound_ctrl:1
	v_cndmask_b32_e64 v81, v81, v84, s[0:1]
	s_and_saveexec_b64 s[74:75], s[38:39]
	s_cbranch_execz .LBB0_2516
	global_load_dwordx4 v[84:87], v[82:83], off offset:16
	global_load_dwordx4 v[88:91], v[82:83], off
	s_waitcnt vmcnt(0)
	v_pk_add_f32 v[78:79], v[78:79], v[84:85]
	v_pk_add_f32 v[80:81], v[80:81], v[86:87]
	v_pk_add_f32 v[76:77], v[76:77], v[90:91]
	v_pk_add_f32 v[74:75], v[74:75], v[88:89]
	s_or_b64 exec, exec, s[74:75]
	s_and_saveexec_b64 s[74:75], s[36:37]
	s_cbranch_execnz .LBB0_2517

; __device__ __forceinline__ void st8bf(bf16_t* p, f32x4 a, f32x4 b) { u32x4 w; w.x = pk2(a[0], a[1]); w.y = pk2(a[2], a[3]); w.z = pk2(b[0], b[1]); w.w = pk2(b[2], b[3]); st16(p, w); }
;     __device__ __forceinline__ void st(int pn, int row, int c, f32x4 v0, f32x4 v1) const {
;     ...
;                 const float inv = 1.f / (float)w;
;                 st8bf(DMs + (size_t)row * 1024 + col, (f32x4){s[0] * inv - x[0], s[1] * inv - x[1], s[2] * inv - x[2], s[3] * inv - x[3]}, (f32x4){s[4] * inv - x[4], s[5] * inv - x[5], s[6] * inv - x[6], s[7] * inv - x[7]});
.LBB0_2245:
	s_or_b64 exec, exec, s[74:75]
	v_readlane_b32 s4, v251, 0
	v_readlane_b32 s5, v251, 1
	v_mov_b32_e32 v85, v62
	v_mov_b32_e32 v62, v61
	v_lshl_add_u64 v[82:83], v[64:65], 1, s[4:5]
	v_lshl_add_u64 v[72:73], v[72:73], 1, v[82:83]
	v_mov_b32_e32 v83, v76
	v_mov_b32_e32 v76, v75
	v_mov_b32_e32 v84, v60
	v_pk_fma_f32 v[60:61], s[68:69], v[76:77], v[62:63] op_sel_hi:[0,1,1] neg_lo:[0,0,1] neg_hi:[0,0,1]
	v_mov_b32_e32 v63, v80
	v_mov_b32_e32 v75, v58
	v_mov_b32_e32 v80, v79
	v_mov_b32_e32 v58, v57
	v_mov_b32_e32 v82, v74
	v_mov_b32_e32 v62, v78
	v_mov_b32_e32 v74, v56
	v_pk_fma_f32 v[56:57], s[68:69], v[80:81], v[58:59] op_sel_hi:[0,1,1] neg_lo:[0,0,1] neg_hi:[0,0,1]
	v_pk_fma_f32 v[82:83], s[68:69], v[82:83], v[84:85] op_sel_hi:[0,1,1] neg_lo:[0,0,1] neg_hi:[0,0,1]
	v_pk_fma_f32 v[62:63], s[68:69], v[62:63], v[74:75] op_sel_hi:[0,1,1] neg_lo:[0,0,1] neg_hi:[0,0,1]
	v_cvt_pk_bf16_f32 v59, v63, v57
	v_cvt_pk_bf16_f32 v58, v62, v56
	v_cvt_pk_bf16_f32 v57, v83, v61
	v_cvt_pk_bf16_f32 v56, v82, v60
	global_store_dwordx4 v[72:73], v[56:59], off

; __device__ __forceinline__ unsigned pk2(float lo, float hi) { return f2bf(lo) | (f2bf(hi) << 16); }
; __device__ __forceinline__ float sigmoidf_(float x) { return __builtin_amdgcn_rcpf(1.0f + __expf(-x)); }
; __device__ __forceinline__ void st8bf(bf16_t* p, f32x4 a, f32x4 b) { u32x4 w; w.x = pk2(a[0], a[1]); w.y = pk2(a[2], a[3]); w.z = pk2(b[0], b[1]); w.w = pk2(b[2], b[3]); st16(p, w); }
; __device__ __forceinline__ void stnt8(float* o, f32x4 a, f32x4 b) { __builtin_nontemporal_store(a, (f32x4*)o); __builtin_nontemporal_store(b, (f32x4*)(o + 4)); }
; __device__ __forceinline__ f32x4 sig4(f32x4 v) { f32x4 r; r[0] = sigmoidf_(v[0]); r[1] = sigmoidf_(v[1]); r[2] = sigmoidf_(v[2]); r[3] = sigmoidf_(v[3]); return r; }
;     __device__ __forceinline__ void st(int pn, int row, int c, f32x4 v0, f32x4 v1) const {
;     ...
;         else st8bf(GT + (size_t)row * 1024 + (pn - 4) * 256 + c, v0 * sig4(v0), v1 * sig4(v1));
.LBB0_2249:
	v_lshl_add_u64 v[56:57], s[54:55], 0, v[70:71]
	v_mul_f32_e32 v58, 0xbfb8aa3b, v52
	v_exp_f32_e32 v58, v58
	v_lshl_add_u64 v[56:57], s[60:61], 1, v[56:57]
	v_lshlrev_b32_e32 v138, 1, v140
	v_lshl_add_u64 v[60:61], v[56:57], 0, v[138:139]
	v_mul_f32_e32 v57, 0xbfb8aa3b, v53
	v_exp_f32_e32 v57, v57
	v_add_f32_e32 v56, 1.0, v58
	v_mul_f32_e32 v58, 0xbfb8aa3b, v54
	v_mul_f32_e32 v59, 0xbfb8aa3b, v55
	v_exp_f32_e32 v58, v58
	v_exp_f32_e32 v59, v59
	v_add_f32_e32 v57, 1.0, v57
	v_rcp_f32_e32 v56, v56
	v_rcp_f32_e32 v57, v57
	v_mul_f32_e32 v62, 0xbfb8aa3b, v48
	v_mul_f32_e32 v63, 0xbfb8aa3b, v49
	v_exp_f32_e32 v62, v62
	v_exp_f32_e32 v63, v63
	v_add_f32_e32 v58, 1.0, v58
	v_add_f32_e32 v59, 1.0, v59
	v_rcp_f32_e32 v58, v58
	v_rcp_f32_e32 v59, v59
	v_mul_f32_e32 v70, 0xbfb8aa3b, v50
	v_mul_f32_e32 v71, 0xbfb8aa3b, v51
	v_exp_f32_e32 v70, v70
	v_exp_f32_e32 v71, v71
	v_pk_mul_f32 v[56:57], v[52:53], v[56:57]
	v_add_f32_e32 v62, 1.0, v62
	v_add_f32_e32 v63, 1.0, v63
	v_bfe_u32 v72, v56, 16, 1
	v_rcp_f32_e32 v62, v62
	v_rcp_f32_e32 v63, v63
	v_add3_u32 v56, v56, v72, s89
	v_bfe_u32 v72, v57, 16, 1
	v_pk_mul_f32 v[58:59], v[54:55], v[58:59]
	v_lshrrev_b32_e32 v56, 16, v56
	v_add3_u32 v57, v57, v72, s89
	v_add_f32_e32 v70, 1.0, v70
	v_add_f32_e32 v71, 1.0, v71
	v_and_or_b32 v56, v57, s91, v56
	v_rcp_f32_e32 v70, v70
	v_rcp_f32_e32 v71, v71
	v_pk_mul_f32 v[62:63], v[48:49], v[62:63]
	v_cvt_pk_bf16_f32 v57, v58, v59
	v_pk_mul_f32 v[70:71], v[50:51], v[70:71]
	v_cvt_pk_bf16_f32 v58, v62, v63
	v_cvt_pk_bf16_f32 v59, v70, v71
	global_store_dwordx4 v[60:61], v[56:59], off offset:256
	s_cbranch_execnz .LBB0_2269
; __device__ __forceinline__ void st16f(float* p, f32x4 v) { st16(p, __builtin_bit_cast(u32x4, v)); }
; __device__ __forceinline__ void st8bf(bf16_t* p, f32x4 a, f32x4 b) { u32x4 w; w.x = pk2(a[0], a[1]); w.y = pk2(a[2], a[3]); w.z = pk2(b[0], b[1]); w.w = pk2(b[2], b[3]); st16(p, w); }
;     __device__ __forceinline__ void st(int pn, int row, int c, f32x4 v0, f32x4 v1) const {
;     ...
;         if (pn < 4) { const int col = pn * 256 + c; float* o = nullptr;
;             if (smp) o = out + O_POOLS + ((size_t)b * 15 + 11 + t) * 1024 + col;
;             st8bf(V + (size_t)row * 1024 + col, v0, v1); if (o) { st16f(o, v0); st16f(o + 4, v1); }
;             if (smp) {
;                 const int w = 2 << pn;
;                 float x[8] = {v0[0], v0[1], v0[2], v0[3], v1[0], v1[1], v1[2], v1[3]}, s[8];
; #pragma unroll
;                 for (int e = 0; e < 8; ++e) { s[e] = 0.f;
; #pragma unroll
;                     for (int tp = 0; tp < 4; ++tp) { const float xo = quad_bcast(x[e], tp); if (tp <= t && t - tp < w) s[e] += xo; } }
;                 const int e_lo = 15 + t - w + 1;
; #pragma unroll
;                 for (int e2 = 0; e2 < 15; ++e2) if (e2 >= e_lo) { const float* sp = state_pool + ((size_t)b * 15 + e2) * 1024 + col; const f32x4 a = *(const f32x4*)sp, d = *(const f32x4*)(sp + 4);
;                     s[0] += a[0]; s[1] += a[1]; s[2] += a[2]; s[3] += a[3]; s[4] += d[0]; s[5] += d[1]; s[6] += d[2]; s[7] += d[3]; }
.LBB0_2250:
	s_ashr_i32 s71, s70, 31
	v_lshl_add_u64 v[58:59], v[64:65], 1, s[52:53]
	v_lshl_add_u64 v[56:57], s[70:71], 0, v[140:141]
	v_lshl_add_u64 v[62:63], v[56:57], 1, v[58:59]
	v_cvt_pk_bf16_f32 v58, v52, v53
	v_cvt_pk_bf16_f32 v59, v54, v55
	v_cvt_pk_bf16_f32 v60, v48, v49
	v_cvt_pk_bf16_f32 v61, v50, v51
	global_store_dwordx4 v[62:63], v[58:61], off offset:256
	s_and_saveexec_b64 s[72:73], s[48:49]
	s_cbranch_execz .LBB0_2268
	v_readlane_b32 s4, v250, 58
	v_readlane_b32 s5, v250, 59
	v_lshlrev_b64 v[70:71], 2, v[56:57]
	s_nop 0
	v_lshl_add_u64 v[58:59], s[4:5], 0, v[68:69]
	v_lshl_add_u64 v[58:59], v[58:59], 0, v[70:71]
	global_store_dwordx4 v[58:59], v[52:55], off offset:512
	global_store_dwordx4 v[58:59], v[48:51], off offset:528
	v_mov_b32_dpp v58, v52 quad_perm:[0,0,0,0] row_mask:0xf bank_mask:0xf bound_ctrl:1
	v_add_f32_e32 v58, 0, v58
	v_cndmask_b32_e64 v58, 0, v58, s[40:41]
	v_readlane_b32 s4, v250, 12
	v_readlane_b32 s16, v250, 24
	v_add_f32_dpp v59, v52, v58 quad_perm:[1,1,1,1] row_mask:0xf bank_mask:0xf bound_ctrl:1
	v_cndmask_b32_e64 v58, v58, v59, s[44:45]
	v_readlane_b32 s17, v250, 25
	v_readlane_b32 s5, v250, 13
	v_add_f32_dpp v59, v52, v58 quad_perm:[2,2,2,2] row_mask:0xf bank_mask:0xf bound_ctrl:1
	v_cndmask_b32_e64 v58, v58, v59, s[42:43]
	v_lshl_add_u64 v[70:71], s[16:17], 0, v[70:71]
	v_lshl_add_u64 v[66:67], v[70:71], 0, v[66:67]
	v_add_f32_dpp v59, v52, v58 quad_perm:[3,3,3,3] row_mask:0xf bank_mask:0xf bound_ctrl:1
	v_cndmask_b32_e64 v58, v58, v59, s[0:1]
	v_readlane_b32 s6, v250, 14
	v_mov_b32_dpp v59, v53 quad_perm:[0,0,0,0] row_mask:0xf bank_mask:0xf bound_ctrl:1
	v_add_f32_e32 v59, 0, v59
	v_cndmask_b32_e64 v59, 0, v59, s[40:41]
	v_readlane_b32 s7, v250, 15
	v_readlane_b32 s8, v250, 16
	v_add_f32_dpp v60, v53, v59 quad_perm:[1,1,1,1] row_mask:0xf bank_mask:0xf bound_ctrl:1
	v_cndmask_b32_e64 v59, v59, v60, s[44:45]
	v_readlane_b32 s9, v250, 17
	v_readlane_b32 s10, v250, 18
	v_add_f32_dpp v60, v53, v59 quad_perm:[2,2,2,2] row_mask:0xf bank_mask:0xf bound_ctrl:1
	v_cndmask_b32_e64 v59, v59, v60, s[42:43]
	v_readlane_b32 s11, v250, 19
	v_readlane_b32 s12, v250, 20
	v_add_f32_dpp v60, v53, v59 quad_perm:[3,3,3,3] row_mask:0xf bank_mask:0xf bound_ctrl:1
	v_cndmask_b32_e64 v59, v59, v60, s[0:1]
	v_readlane_b32 s13, v250, 21
	v_mov_b32_dpp v60, v54 quad_perm:[0,0,0,0] row_mask:0xf bank_mask:0xf bound_ctrl:1
	v_add_f32_e32 v60, 0, v60
	v_cndmask_b32_e64 v60, 0, v60, s[40:41]
	v_readlane_b32 s14, v250, 22
	v_readlane_b32 s15, v250, 23
	v_add_f32_dpp v61, v54, v60 quad_perm:[1,1,1,1] row_mask:0xf bank_mask:0xf bound_ctrl:1
	v_cndmask_b32_e64 v60, v60, v61, s[44:45]
	v_readlane_b32 s18, v250, 26
	v_readlane_b32 s19, v250, 27
	v_add_f32_dpp v61, v54, v60 quad_perm:[2,2,2,2] row_mask:0xf bank_mask:0xf bound_ctrl:1
	v_cndmask_b32_e64 v60, v60, v61, s[42:43]
	s_nop 1
	v_add_f32_dpp v61, v54, v60 quad_perm:[3,3,3,3] row_mask:0xf bank_mask:0xf bound_ctrl:1
	v_cndmask_b32_e64 v60, v60, v61, s[0:1]
	s_nop 0
	v_mov_b32_dpp v61, v55 quad_perm:[0,0,0,0] row_mask:0xf bank_mask:0xf bound_ctrl:1
	v_add_f32_e32 v61, 0, v61
	v_cndmask_b32_e64 v61, 0, v61, s[40:41]
	s_nop 1
	v_add_f32_dpp v62, v55, v61 quad_perm:[1,1,1,1] row_mask:0xf bank_mask:0xf bound_ctrl:1
	v_cndmask_b32_e64 v61, v61, v62, s[44:45]
	s_nop 1
	v_add_f32_dpp v62, v55, v61 quad_perm:[2,2,2,2] row_mask:0xf bank_mask:0xf bound_ctrl:1
	v_cndmask_b32_e64 v61, v61, v62, s[42:43]
	s_nop 1
	v_add_f32_dpp v62, v55, v61 quad_perm:[3,3,3,3] row_mask:0xf bank_mask:0xf bound_ctrl:1
	v_cndmask_b32_e64 v61, v61, v62, s[0:1]
	s_nop 0
	v_mov_b32_dpp v62, v48 quad_perm:[0,0,0,0] row_mask:0xf bank_mask:0xf bound_ctrl:1
	v_add_f32_e32 v62, 0, v62
	v_cndmask_b32_e64 v62, 0, v62, s[40:41]
	s_nop 1
	v_add_f32_dpp v63, v48, v62 quad_perm:[1,1,1,1] row_mask:0xf bank_mask:0xf bound_ctrl:1
	v_cndmask_b32_e64 v62, v62, v63, s[44:45]
	s_nop 1
	v_add_f32_dpp v63, v48, v62 quad_perm:[2,2,2,2] row_mask:0xf bank_mask:0xf bound_ctrl:1
	v_cndmask_b32_e64 v62, v62, v63, s[42:43]
	s_nop 1
	v_add_f32_dpp v63, v48, v62 quad_perm:[3,3,3,3] row_mask:0xf bank_mask:0xf bound_ctrl:1
	v_cndmask_b32_e64 v62, v62, v63, s[0:1]
	s_nop 0
	v_mov_b32_dpp v63, v49 quad_perm:[0,0,0,0] row_mask:0xf bank_mask:0xf bound_ctrl:1
	v_add_f32_e32 v63, 0, v63
	v_cndmask_b32_e64 v63, 0, v63, s[40:41]
	s_nop 1
	v_add_f32_dpp v68, v49, v63 quad_perm:[1,1,1,1] row_mask:0xf bank_mask:0xf bound_ctrl:1
	v_cndmask_b32_e64 v63, v63, v68, s[44:45]
	s_nop 1
	v_add_f32_dpp v68, v49, v63 quad_perm:[2,2,2,2] row_mask:0xf bank_mask:0xf bound_ctrl:1
	v_cndmask_b32_e64 v63, v63, v68, s[42:43]
	s_nop 1
	v_add_f32_dpp v68, v49, v63 quad_perm:[3,3,3,3] row_mask:0xf bank_mask:0xf bound_ctrl:1
	v_cndmask_b32_e64 v63, v63, v68, s[0:1]
	s_nop 0
	v_mov_b32_dpp v68, v50 quad_perm:[0,0,0,0] row_mask:0xf bank_mask:0xf bound_ctrl:1
	v_add_f32_e32 v68, 0, v68
	v_cndmask_b32_e64 v68, 0, v68, s[40:41]
	s_nop 1
	v_add_f32_dpp v69, v50, v68 quad_perm:[1,1,1,1] row_mask:0xf bank_mask:0xf bound_ctrl:1
	v_cndmask_b32_e64 v68, v68, v69, s[44:45]
	s_nop 1
	v_add_f32_dpp v69, v50, v68 quad_perm:[2,2,2,2] row_mask:0xf bank_mask:0xf bound_ctrl:1
	v_cndmask_b32_e64 v68, v68, v69, s[42:43]
	s_nop 1
	v_add_f32_dpp v69, v50, v68 quad_perm:[3,3,3,3] row_mask:0xf bank_mask:0xf bound_ctrl:1
	v_cndmask_b32_e64 v68, v68, v69, s[0:1]
	s_nop 0
	v_mov_b32_dpp v69, v51 quad_perm:[0,0,0,0] row_mask:0xf bank_mask:0xf bound_ctrl:1
	v_add_f32_e32 v69, 0, v69
	v_cndmask_b32_e64 v69, 0, v69, s[40:41]
	s_nop 1
	v_add_f32_dpp v72, v51, v69 quad_perm:[1,1,1,1] row_mask:0xf bank_mask:0xf bound_ctrl:1
	v_cndmask_b32_e64 v69, v69, v72, s[44:45]
	s_nop 1
	v_add_f32_dpp v72, v51, v69 quad_perm:[2,2,2,2] row_mask:0xf bank_mask:0xf bound_ctrl:1
	v_cndmask_b32_e64 v69, v69, v72, s[42:43]
	s_nop 1
	v_add_f32_dpp v72, v51, v69 quad_perm:[3,3,3,3] row_mask:0xf bank_mask:0xf bound_ctrl:1
	v_cndmask_b32_e64 v69, v69, v72, s[0:1]
	s_and_saveexec_b64 s[48:49], s[38:39]
	s_cbranch_execz .LBB0_2530
	global_load_dwordx4 v[70:73], v[66:67], off offset:528
	global_load_dwordx4 v[74:77], v[66:67], off offset:512
	s_waitcnt vmcnt(0)
	v_pk_add_f32 v[62:63], v[62:63], v[70:71]
	v_pk_add_f32 v[68:69], v[68:69], v[72:73]
	v_pk_add_f32 v[60:61], v[60:61], v[76:77]
	v_pk_add_f32 v[58:59], v[58:59], v[74:75]
	s_or_b64 exec, exec, s[48:49]
	s_and_saveexec_b64 s[48:49], s[36:37]
	s_cbranch_execnz .LBB0_2531

; __device__ __forceinline__ void st8bf(bf16_t* p, f32x4 a, f32x4 b) { u32x4 w; w.x = pk2(a[0], a[1]); w.y = pk2(a[2], a[3]); w.z = pk2(b[0], b[1]); w.w = pk2(b[2], b[3]); st16(p, w); }
;     __device__ __forceinline__ void st(int pn, int row, int c, f32x4 v0, f32x4 v1) const {
;     ...
;                 const float inv = 1.f / (float)w;
;                 st8bf(DMs + (size_t)row * 1024 + col, (f32x4){s[0] * inv - x[0], s[1] * inv - x[1], s[2] * inv - x[2], s[3] * inv - x[3]}, (f32x4){s[4] * inv - x[4], s[5] * inv - x[5], s[6] * inv - x[6], s[7] * inv - x[7]});
.LBB0_2267:
	s_or_b64 exec, exec, s[48:49]
	v_readlane_b32 s4, v251, 0
	v_readlane_b32 s5, v251, 1
	v_mov_b32_e32 v67, v54
	v_mov_b32_e32 v54, v53
	v_lshl_add_u64 v[64:65], v[64:65], 1, s[4:5]
	v_lshl_add_u64 v[56:57], v[56:57], 1, v[64:65]
	v_mov_b32_e32 v65, v60
	v_mov_b32_e32 v60, v59
	v_mov_b32_e32 v66, v52
	v_pk_fma_f32 v[52:53], s[68:69], v[60:61], v[54:55] op_sel_hi:[0,1,1] neg_lo:[0,0,1] neg_hi:[0,0,1]
	v_mov_b32_e32 v55, v68
	v_mov_b32_e32 v59, v50
	v_mov_b32_e32 v68, v63
	v_mov_b32_e32 v50, v49
	v_mov_b32_e32 v64, v58
	v_mov_b32_e32 v54, v62
	v_mov_b32_e32 v58, v48
	v_pk_fma_f32 v[48:49], s[68:69], v[68:69], v[50:51] op_sel_hi:[0,1,1] neg_lo:[0,0,1] neg_hi:[0,0,1]
	v_pk_fma_f32 v[64:65], s[68:69], v[64:65], v[66:67] op_sel_hi:[0,1,1] neg_lo:[0,0,1] neg_hi:[0,0,1]
	v_pk_fma_f32 v[54:55], s[68:69], v[54:55], v[58:59] op_sel_hi:[0,1,1] neg_lo:[0,0,1] neg_hi:[0,0,1]
	v_cvt_pk_bf16_f32 v51, v55, v49
	v_cvt_pk_bf16_f32 v50, v54, v48
	v_cvt_pk_bf16_f32 v49, v65, v53
	v_cvt_pk_bf16_f32 v48, v64, v52
	global_store_dwordx4 v[56:57], v[48:51], off offset:256

; __device__ __forceinline__ void st8bf(bf16_t* p, f32x4 a, f32x4 b) { u32x4 w; w.x = pk2(a[0], a[1]); w.y = pk2(a[2], a[3]); w.z = pk2(b[0], b[1]); w.w = pk2(b[2], b[3]); st16(p, w); }
; __device__ __forceinline__ f32x4 sig4(f32x4 v) { f32x4 r; r[0] = sigmoidf_(v[0]); r[1] = sigmoidf_(v[1]); r[2] = sigmoidf_(v[2]); r[3] = sigmoidf_(v[3]); return r; }
; #define EPI_LOOP_ROWS(body) _Pragma("unroll") for (int ai = 0; ai < 2; ++ai) _Pragma("unroll") for (int m = 0; m < 4; ++m) { const int row = u.pm * 256 + ai * 128 + wr * 64 + m * 16 + fr; body }
;     __device__ __forceinline__ void st(int pn, int row, int c, f32x4 v0, f32x4 v1) const {
;     ...
;         else st8bf(GT + (size_t)row * 1024 + (pn - 4) * 256 + c, v0 * sig4(v0), v1 * sig4(v1));
;     }
;     __device__ __forceinline__ void operator()(const f32x4 (&acc)[2][2][4][2], const pg8::Unit& u, int wr, int wc, int fr, int fq) const {
;         const int cw = wc * 32 + 8 * fq;
;         EPI_LOOP_ROWS( _Pragma("unroll") for (int bj = 0; bj < 2; ++bj) st(u.pn, row, bj * 128 + cw, acc[ai][bj][m][0], acc[ai][bj][m][1]); )
.LBB0_2269:
	s_nop 0
	v_add_u32_e32 v48, 0x90, v150
	v_ashrrev_i32_e32 v49, 31, v48
	v_cmp_lt_i32_e64 s[48:49], s89, v48
	v_lshlrev_b64 v[54:55], 11, v[48:49]
	s_and_b64 vcc, exec, s[46:47]
	s_mov_b64 s[72:73], -1
	s_cbranch_vccnz .LBB0_2271
	v_lshl_add_u64 v[50:51], s[54:55], 0, v[54:55]
	v_mul_f32_e32 v52, 0xbfb8aa3b, v44
	v_exp_f32_e32 v52, v52
	v_lshl_add_u64 v[50:51], s[60:61], 1, v[50:51]
	v_lshlrev_b32_e32 v138, 1, v140
	v_lshl_add_u64 v[56:57], v[50:51], 0, v[138:139]
	v_mul_f32_e32 v51, 0xbfb8aa3b, v45
	v_exp_f32_e32 v51, v51
	v_add_f32_e32 v50, 1.0, v52
	v_mul_f32_e32 v52, 0xbfb8aa3b, v46
	v_mul_f32_e32 v53, 0xbfb8aa3b, v47
	v_exp_f32_e32 v52, v52
	v_exp_f32_e32 v53, v53
	v_add_f32_e32 v51, 1.0, v51
	v_rcp_f32_e32 v50, v50
	v_rcp_f32_e32 v51, v51
	v_mul_f32_e32 v58, 0xbfb8aa3b, v40
	v_mul_f32_e32 v59, 0xbfb8aa3b, v41
	v_exp_f32_e32 v58, v58
	v_exp_f32_e32 v59, v59
	v_add_f32_e32 v52, 1.0, v52
	v_add_f32_e32 v53, 1.0, v53
	v_rcp_f32_e32 v52, v52
	v_rcp_f32_e32 v53, v53
	v_mul_f32_e32 v60, 0xbfb8aa3b, v42
	v_mul_f32_e32 v61, 0xbfb8aa3b, v43
	v_exp_f32_e32 v60, v60
	v_exp_f32_e32 v61, v61
	v_pk_mul_f32 v[50:51], v[44:45], v[50:51]
	v_add_f32_e32 v58, 1.0, v58
	v_add_f32_e32 v59, 1.0, v59
	v_rcp_f32_e32 v58, v58
	v_rcp_f32_e32 v59, v59
	v_pk_mul_f32 v[52:53], v[46:47], v[52:53]
	v_add_f32_e32 v60, 1.0, v60
	v_add_f32_e32 v61, 1.0, v61
	v_cvt_pk_bf16_f32 v50, v50, v51
	v_rcp_f32_e32 v60, v60
	v_rcp_f32_e32 v61, v61
	v_pk_mul_f32 v[58:59], v[40:41], v[58:59]
	v_cvt_pk_bf16_f32 v51, v52, v53
	v_pk_mul_f32 v[60:61], v[42:43], v[60:61]
	v_cvt_pk_bf16_f32 v52, v58, v59
	v_cvt_pk_bf16_f32 v53, v60, v61
	s_mov_b64 s[72:73], 0
	global_store_dwordx4 v[56:57], v[50:53], off
; __device__ __forceinline__ void st16f(float* p, f32x4 v) { st16(p, __builtin_bit_cast(u32x4, v)); }
; __device__ __forceinline__ void st8bf(bf16_t* p, f32x4 a, f32x4 b) { u32x4 w; w.x = pk2(a[0], a[1]); w.y = pk2(a[2], a[3]); w.z = pk2(b[0], b[1]); w.w = pk2(b[2], b[3]); st16(p, w); }
;     __device__ __forceinline__ void st(int pn, int row, int c, f32x4 v0, f32x4 v1) const {
;         const bool smp = row >= MP; const int b = smp ? (row - MP) >> 2 : row >> 13, t = smp ? (row - MP) & 3 : row & (SEQ - 1);
;         if (pn < 4) { const int col = pn * 256 + c; float* o = nullptr;
;             if (smp) o = out + O_POOLS + ((size_t)b * 15 + 11 + t) * 1024 + col;
;             st8bf(V + (size_t)row * 1024 + col, v0, v1); if (o) { st16f(o, v0); st16f(o + 4, v1); }
;             if (smp) {
;                 const int w = 2 << pn;
;                 float x[8] = {v0[0], v0[1], v0[2], v0[3], v1[0], v1[1], v1[2], v1[3]}, s[8];
; #pragma unroll
;                 for (int e = 0; e < 8; ++e) { s[e] = 0.f;
; #pragma unroll
;                     for (int tp = 0; tp < 4; ++tp) { const float xo = quad_bcast(x[e], tp); if (tp <= t && t - tp < w) s[e] += xo; } }
;                 const int e_lo = 15 + t - w + 1;
; #pragma unroll
;                 for (int e2 = 0; e2 < 15; ++e2) if (e2 >= e_lo) { const float* sp = state_pool + ((size_t)b * 15 + e2) * 1024 + col; const f32x4 a = *(const f32x4*)sp, d = *(const f32x4*)(sp + 4);
;                     s[0] += a[0]; s[1] += a[1]; s[2] += a[2]; s[3] += a[3]; s[4] += d[0]; s[5] += d[1]; s[6] += d[2]; s[7] += d[3]; }
.LBB0_2271:
	s_nop 1
	v_add_u32_e32 v50, 0xffff8090, v150
	v_lshrrev_b32_e32 v56, 2, v50
	v_mad_u64_u32 v[50:51], s[74:75], v56, 15, v[128:129]
	v_lshlrev_b64 v[52:53], 12, v[50:51]
	v_lshlrev_b64 v[48:49], 10, v[48:49]
	s_andn2_b64 vcc, exec, s[72:73]
	v_mad_u64_u32 v[50:51], s[72:73], v56, s90, 0
	s_cbranch_vccnz .LBB0_2292
	v_or_b32_e32 v56, s70, v140
	v_ashrrev_i32_e32 v57, 31, v56
	v_lshl_add_u64 v[58:59], v[48:49], 1, s[52:53]
	v_lshl_add_u64 v[62:63], v[56:57], 1, v[58:59]
	v_cvt_pk_bf16_f32 v58, v44, v45
	v_cvt_pk_bf16_f32 v59, v46, v47
	v_cvt_pk_bf16_f32 v60, v40, v41
	v_bfe_u32 v61, v42, 16, 1
	v_add3_u32 v61, v42, v61, s89
	v_bfe_u32 v64, v43, 16, 1
	v_lshrrev_b32_e32 v61, 16, v61
	v_add3_u32 v64, v43, v64, s89
	v_and_or_b32 v61, v64, s91, v61
	global_store_dwordx4 v[62:63], v[58:61], off
	s_and_saveexec_b64 s[72:73], s[48:49]
	s_cbranch_execz .LBB0_2290
	v_readlane_b32 s4, v250, 58
	v_readlane_b32 s5, v250, 59
	v_lshlrev_b64 v[66:67], 2, v[56:57]
	s_nop 0
	v_lshl_add_u64 v[58:59], s[4:5], 0, v[52:53]
	v_lshl_add_u64 v[58:59], v[58:59], 0, v[66:67]
	global_store_dwordx4 v[58:59], v[44:47], off
	global_store_dwordx4 v[58:59], v[40:43], off offset:16
	v_mov_b32_dpp v58, v44 quad_perm:[0,0,0,0] row_mask:0xf bank_mask:0xf bound_ctrl:1
	v_add_f32_e32 v58, 0, v58
	v_cndmask_b32_e64 v58, 0, v58, s[40:41]
	v_readlane_b32 s4, v250, 12
	v_readlane_b32 s16, v250, 24
	v_add_f32_dpp v59, v44, v58 quad_perm:[1,1,1,1] row_mask:0xf bank_mask:0xf bound_ctrl:1
	v_cndmask_b32_e64 v58, v58, v59, s[44:45]
	v_readlane_b32 s17, v250, 25
	v_readlane_b32 s5, v250, 13
	v_add_f32_dpp v59, v44, v58 quad_perm:[2,2,2,2] row_mask:0xf bank_mask:0xf bound_ctrl:1
	v_cndmask_b32_e64 v58, v58, v59, s[42:43]
	v_lshl_add_u64 v[66:67], s[16:17], 0, v[66:67]
	v_lshl_add_u64 v[66:67], v[66:67], 0, v[50:51]
	v_add_f32_dpp v59, v44, v58 quad_perm:[3,3,3,3] row_mask:0xf bank_mask:0xf bound_ctrl:1
	v_cndmask_b32_e64 v58, v58, v59, s[0:1]
	v_readlane_b32 s6, v250, 14
	v_mov_b32_dpp v59, v45 quad_perm:[0,0,0,0] row_mask:0xf bank_mask:0xf bound_ctrl:1
	v_add_f32_e32 v59, 0, v59
	v_cndmask_b32_e64 v59, 0, v59, s[40:41]
	v_readlane_b32 s7, v250, 15
	v_readlane_b32 s8, v250, 16
	v_add_f32_dpp v60, v45, v59 quad_perm:[1,1,1,1] row_mask:0xf bank_mask:0xf bound_ctrl:1
	v_cndmask_b32_e64 v59, v59, v60, s[44:45]
	v_readlane_b32 s9, v250, 17
	v_readlane_b32 s10, v250, 18
	v_add_f32_dpp v60, v45, v59 quad_perm:[2,2,2,2] row_mask:0xf bank_mask:0xf bound_ctrl:1
	v_cndmask_b32_e64 v59, v59, v60, s[42:43]
	v_readlane_b32 s11, v250, 19
	v_readlane_b32 s12, v250, 20
	v_add_f32_dpp v60, v45, v59 quad_perm:[3,3,3,3] row_mask:0xf bank_mask:0xf bound_ctrl:1
	v_cndmask_b32_e64 v59, v59, v60, s[0:1]
	v_readlane_b32 s13, v250, 21
	v_mov_b32_dpp v60, v46 quad_perm:[0,0,0,0] row_mask:0xf bank_mask:0xf bound_ctrl:1
	v_add_f32_e32 v60, 0, v60
	v_cndmask_b32_e64 v60, 0, v60, s[40:41]
	v_readlane_b32 s14, v250, 22
	v_readlane_b32 s15, v250, 23
	v_add_f32_dpp v61, v46, v60 quad_perm:[1,1,1,1] row_mask:0xf bank_mask:0xf bound_ctrl:1
	v_cndmask_b32_e64 v60, v60, v61, s[44:45]
	v_readlane_b32 s18, v250, 26
	v_readlane_b32 s19, v250, 27
	v_add_f32_dpp v61, v46, v60 quad_perm:[2,2,2,2] row_mask:0xf bank_mask:0xf bound_ctrl:1
	v_cndmask_b32_e64 v60, v60, v61, s[42:43]
	s_nop 1
	v_add_f32_dpp v61, v46, v60 quad_perm:[3,3,3,3] row_mask:0xf bank_mask:0xf bound_ctrl:1
	v_cndmask_b32_e64 v60, v60, v61, s[0:1]
	s_nop 0
	v_mov_b32_dpp v61, v47 quad_perm:[0,0,0,0] row_mask:0xf bank_mask:0xf bound_ctrl:1
	v_add_f32_e32 v61, 0, v61
	v_cndmask_b32_e64 v61, 0, v61, s[40:41]
	s_nop 1
	v_add_f32_dpp v62, v47, v61 quad_perm:[1,1,1,1] row_mask:0xf bank_mask:0xf bound_ctrl:1
	v_cndmask_b32_e64 v61, v61, v62, s[44:45]
	s_nop 1
	v_add_f32_dpp v62, v47, v61 quad_perm:[2,2,2,2] row_mask:0xf bank_mask:0xf bound_ctrl:1
	v_cndmask_b32_e64 v61, v61, v62, s[42:43]
	s_nop 1
	v_add_f32_dpp v62, v47, v61 quad_perm:[3,3,3,3] row_mask:0xf bank_mask:0xf bound_ctrl:1
	v_cndmask_b32_e64 v61, v61, v62, s[0:1]
	s_nop 0
	v_mov_b32_dpp v62, v40 quad_perm:[0,0,0,0] row_mask:0xf bank_mask:0xf bound_ctrl:1
	v_add_f32_e32 v62, 0, v62
	v_cndmask_b32_e64 v62, 0, v62, s[40:41]
	s_nop 1
	v_add_f32_dpp v63, v40, v62 quad_perm:[1,1,1,1] row_mask:0xf bank_mask:0xf bound_ctrl:1
	v_cndmask_b32_e64 v62, v62, v63, s[44:45]
	s_nop 1
	v_add_f32_dpp v63, v40, v62 quad_perm:[2,2,2,2] row_mask:0xf bank_mask:0xf bound_ctrl:1
	v_cndmask_b32_e64 v62, v62, v63, s[42:43]
	s_nop 1
	v_add_f32_dpp v63, v40, v62 quad_perm:[3,3,3,3] row_mask:0xf bank_mask:0xf bound_ctrl:1
	v_cndmask_b32_e64 v62, v62, v63, s[0:1]
	s_nop 0
	v_mov_b32_dpp v63, v41 quad_perm:[0,0,0,0] row_mask:0xf bank_mask:0xf bound_ctrl:1
	v_add_f32_e32 v63, 0, v63
	v_cndmask_b32_e64 v63, 0, v63, s[40:41]
	s_nop 1
	v_add_f32_dpp v64, v41, v63 quad_perm:[1,1,1,1] row_mask:0xf bank_mask:0xf bound_ctrl:1
	v_cndmask_b32_e64 v63, v63, v64, s[44:45]
	s_nop 1
	v_add_f32_dpp v64, v41, v63 quad_perm:[2,2,2,2] row_mask:0xf bank_mask:0xf bound_ctrl:1
	v_cndmask_b32_e64 v63, v63, v64, s[42:43]
	s_nop 1
	v_add_f32_dpp v64, v41, v63 quad_perm:[3,3,3,3] row_mask:0xf bank_mask:0xf bound_ctrl:1
	v_cndmask_b32_e64 v63, v63, v64, s[0:1]
	s_nop 0
	v_mov_b32_dpp v64, v42 quad_perm:[0,0,0,0] row_mask:0xf bank_mask:0xf bound_ctrl:1
	v_add_f32_e32 v64, 0, v64
	v_cndmask_b32_e64 v64, 0, v64, s[40:41]
	s_nop 1
	v_add_f32_dpp v65, v42, v64 quad_perm:[1,1,1,1] row_mask:0xf bank_mask:0xf bound_ctrl:1
	v_cndmask_b32_e64 v64, v64, v65, s[44:45]
	s_nop 1
	v_add_f32_dpp v65, v42, v64 quad_perm:[2,2,2,2] row_mask:0xf bank_mask:0xf bound_ctrl:1
	v_cndmask_b32_e64 v64, v64, v65, s[42:43]
	s_nop 1
	v_add_f32_dpp v65, v42, v64 quad_perm:[3,3,3,3] row_mask:0xf bank_mask:0xf bound_ctrl:1
	v_cndmask_b32_e64 v64, v64, v65, s[0:1]
	s_nop 0
	v_mov_b32_dpp v65, v43 quad_perm:[0,0,0,0] row_mask:0xf bank_mask:0xf bound_ctrl:1
	v_add_f32_e32 v65, 0, v65
	v_cndmask_b32_e64 v65, 0, v65, s[40:41]
	s_nop 1
	v_add_f32_dpp v68, v43, v65 quad_perm:[1,1,1,1] row_mask:0xf bank_mask:0xf bound_ctrl:1
	v_cndmask_b32_e64 v65, v65, v68, s[44:45]
	s_nop 1
	v_add_f32_dpp v68, v43, v65 quad_perm:[2,2,2,2] row_mask:0xf bank_mask:0xf bound_ctrl:1
	v_cndmask_b32_e64 v65, v65, v68, s[42:43]
	s_nop 1
	v_add_f32_dpp v68, v43, v65 quad_perm:[3,3,3,3] row_mask:0xf bank_mask:0xf bound_ctrl:1
	v_cndmask_b32_e64 v65, v65, v68, s[0:1]
	s_and_saveexec_b64 s[74:75], s[38:39]
	s_cbranch_execz .LBB0_2544
	global_load_dwordx4 v[68:71], v[66:67], off offset:16
	global_load_dwordx4 v[72:75], v[66:67], off
	s_waitcnt vmcnt(0)
	v_pk_add_f32 v[62:63], v[62:63], v[68:69]
	v_pk_add_f32 v[64:65], v[64:65], v[70:71]
	v_pk_add_f32 v[60:61], v[60:61], v[74:75]
	v_pk_add_f32 v[58:59], v[58:59], v[72:73]
	s_or_b64 exec, exec, s[74:75]
	s_and_saveexec_b64 s[74:75], s[36:37]
	s_cbranch_execnz .LBB0_2545

; __device__ __forceinline__ void st8bf(bf16_t* p, f32x4 a, f32x4 b) { u32x4 w; w.x = pk2(a[0], a[1]); w.y = pk2(a[2], a[3]); w.z = pk2(b[0], b[1]); w.w = pk2(b[2], b[3]); st16(p, w); }
;     __device__ __forceinline__ void st(int pn, int row, int c, f32x4 v0, f32x4 v1) const {
;     ...
;                 const float inv = 1.f / (float)w;
;                 st8bf(DMs + (size_t)row * 1024 + col, (f32x4){s[0] * inv - x[0], s[1] * inv - x[1], s[2] * inv - x[2], s[3] * inv - x[3]}, (f32x4){s[4] * inv - x[4], s[5] * inv - x[5], s[6] * inv - x[6], s[7] * inv - x[7]});
.LBB0_2289:
	s_or_b64 exec, exec, s[74:75]
	v_readlane_b32 s4, v251, 0
	v_readlane_b32 s5, v251, 1
	v_mov_b32_e32 v69, v46
	v_mov_b32_e32 v46, v45
	v_lshl_add_u64 v[66:67], v[48:49], 1, s[4:5]
	v_lshl_add_u64 v[56:57], v[56:57], 1, v[66:67]
	v_mov_b32_e32 v67, v60
	v_mov_b32_e32 v60, v59
	v_mov_b32_e32 v68, v44
	v_pk_fma_f32 v[44:45], s[68:69], v[60:61], v[46:47] op_sel_hi:[0,1,1] neg_lo:[0,0,1] neg_hi:[0,0,1]
	v_mov_b32_e32 v47, v64
	v_mov_b32_e32 v59, v42
	v_mov_b32_e32 v64, v63
	v_mov_b32_e32 v42, v41
	v_mov_b32_e32 v66, v58
	v_mov_b32_e32 v46, v62
	v_mov_b32_e32 v58, v40
	v_pk_fma_f32 v[40:41], s[68:69], v[64:65], v[42:43] op_sel_hi:[0,1,1] neg_lo:[0,0,1] neg_hi:[0,0,1]
	v_pk_fma_f32 v[66:67], s[68:69], v[66:67], v[68:69] op_sel_hi:[0,1,1] neg_lo:[0,0,1] neg_hi:[0,0,1]
	v_pk_fma_f32 v[46:47], s[68:69], v[46:47], v[58:59] op_sel_hi:[0,1,1] neg_lo:[0,0,1] neg_hi:[0,0,1]
	v_cvt_pk_bf16_f32 v43, v47, v41
	v_cvt_pk_bf16_f32 v42, v46, v40
	v_cvt_pk_bf16_f32 v41, v67, v45
	v_cvt_pk_bf16_f32 v40, v66, v44
	global_store_dwordx4 v[56:57], v[40:43], off

; __device__ __forceinline__ unsigned pk2(float lo, float hi) { return f2bf(lo) | (f2bf(hi) << 16); }
; __device__ __forceinline__ float sigmoidf_(float x) { return __builtin_amdgcn_rcpf(1.0f + __expf(-x)); }
; __device__ __forceinline__ void st8bf(bf16_t* p, f32x4 a, f32x4 b) { u32x4 w; w.x = pk2(a[0], a[1]); w.y = pk2(a[2], a[3]); w.z = pk2(b[0], b[1]); w.w = pk2(b[2], b[3]); st16(p, w); }
; __device__ __forceinline__ void stnt8(float* o, f32x4 a, f32x4 b) { __builtin_nontemporal_store(a, (f32x4*)o); __builtin_nontemporal_store(b, (f32x4*)(o + 4)); }
; __device__ __forceinline__ f32x4 sig4(f32x4 v) { f32x4 r; r[0] = sigmoidf_(v[0]); r[1] = sigmoidf_(v[1]); r[2] = sigmoidf_(v[2]); r[3] = sigmoidf_(v[3]); return r; }
;     __device__ __forceinline__ void st(int pn, int row, int c, f32x4 v0, f32x4 v1) const {
;     ...
;         else st8bf(GT + (size_t)row * 1024 + (pn - 4) * 256 + c, v0 * sig4(v0), v1 * sig4(v1));
.LBB0_2293:
	v_lshl_add_u64 v[40:41], s[54:55], 0, v[54:55]
	v_mul_f32_e32 v42, 0xbfb8aa3b, v36
	v_exp_f32_e32 v42, v42
	v_lshl_add_u64 v[40:41], s[60:61], 1, v[40:41]
	v_lshlrev_b32_e32 v138, 1, v140
	v_lshl_add_u64 v[44:45], v[40:41], 0, v[138:139]
	v_mul_f32_e32 v41, 0xbfb8aa3b, v37
	v_exp_f32_e32 v41, v41
	v_add_f32_e32 v40, 1.0, v42
	v_mul_f32_e32 v42, 0xbfb8aa3b, v38
	v_mul_f32_e32 v43, 0xbfb8aa3b, v39
	v_exp_f32_e32 v42, v42
	v_exp_f32_e32 v43, v43
	v_add_f32_e32 v41, 1.0, v41
	v_rcp_f32_e32 v40, v40
	v_rcp_f32_e32 v41, v41
	v_mul_f32_e32 v46, 0xbfb8aa3b, v32
	v_mul_f32_e32 v47, 0xbfb8aa3b, v33
	v_exp_f32_e32 v46, v46
	v_exp_f32_e32 v47, v47
	v_add_f32_e32 v42, 1.0, v42
	v_add_f32_e32 v43, 1.0, v43
	v_rcp_f32_e32 v42, v42
	v_rcp_f32_e32 v43, v43
	v_mul_f32_e32 v54, 0xbfb8aa3b, v34
	v_mul_f32_e32 v55, 0xbfb8aa3b, v35
	v_exp_f32_e32 v54, v54
	v_exp_f32_e32 v55, v55
	v_pk_mul_f32 v[40:41], v[36:37], v[40:41]
	v_add_f32_e32 v46, 1.0, v46
	v_add_f32_e32 v47, 1.0, v47
	v_bfe_u32 v56, v40, 16, 1
	v_rcp_f32_e32 v46, v46
	v_rcp_f32_e32 v47, v47
	v_add3_u32 v40, v40, v56, s89
	v_bfe_u32 v56, v41, 16, 1
	v_pk_mul_f32 v[42:43], v[38:39], v[42:43]
	v_lshrrev_b32_e32 v40, 16, v40
	v_add3_u32 v41, v41, v56, s89
	v_add_f32_e32 v54, 1.0, v54
	v_add_f32_e32 v55, 1.0, v55
	v_and_or_b32 v40, v41, s91, v40
	v_rcp_f32_e32 v54, v54
	v_rcp_f32_e32 v55, v55
	v_pk_mul_f32 v[46:47], v[32:33], v[46:47]
	v_cvt_pk_bf16_f32 v41, v42, v43
	v_pk_mul_f32 v[54:55], v[34:35], v[54:55]
	v_cvt_pk_bf16_f32 v42, v46, v47
	v_cvt_pk_bf16_f32 v43, v54, v55
	global_store_dwordx4 v[44:45], v[40:43], off offset:256
	s_cbranch_execnz .LBB0_2313
; __device__ __forceinline__ void st16f(float* p, f32x4 v) { st16(p, __builtin_bit_cast(u32x4, v)); }
; __device__ __forceinline__ void st8bf(bf16_t* p, f32x4 a, f32x4 b) { u32x4 w; w.x = pk2(a[0], a[1]); w.y = pk2(a[2], a[3]); w.z = pk2(b[0], b[1]); w.w = pk2(b[2], b[3]); st16(p, w); }
;     __device__ __forceinline__ void st(int pn, int row, int c, f32x4 v0, f32x4 v1) const {
;     ...
;         if (pn < 4) { const int col = pn * 256 + c; float* o = nullptr;
;             if (smp) o = out + O_POOLS + ((size_t)b * 15 + 11 + t) * 1024 + col;
;             st8bf(V + (size_t)row * 1024 + col, v0, v1); if (o) { st16f(o, v0); st16f(o + 4, v1); }
;             if (smp) {
;                 const int w = 2 << pn;
;                 float x[8] = {v0[0], v0[1], v0[2], v0[3], v1[0], v1[1], v1[2], v1[3]}, s[8];
; #pragma unroll
;                 for (int e = 0; e < 8; ++e) { s[e] = 0.f;
; #pragma unroll
;                     for (int tp = 0; tp < 4; ++tp) { const float xo = quad_bcast(x[e], tp); if (tp <= t && t - tp < w) s[e] += xo; } }
;                 const int e_lo = 15 + t - w + 1;
; #pragma unroll
;                 for (int e2 = 0; e2 < 15; ++e2) if (e2 >= e_lo) { const float* sp = state_pool + ((size_t)b * 15 + e2) * 1024 + col; const f32x4 a = *(const f32x4*)sp, d = *(const f32x4*)(sp + 4);
;                     s[0] += a[0]; s[1] += a[1]; s[2] += a[2]; s[3] += a[3]; s[4] += d[0]; s[5] += d[1]; s[6] += d[2]; s[7] += d[3]; }
.LBB0_2294:
	s_ashr_i32 s71, s70, 31
	v_lshl_add_u64 v[42:43], v[48:49], 1, s[52:53]
	v_lshl_add_u64 v[40:41], s[70:71], 0, v[140:141]
	v_lshl_add_u64 v[46:47], v[40:41], 1, v[42:43]
	v_cvt_pk_bf16_f32 v42, v36, v37
	v_cvt_pk_bf16_f32 v43, v38, v39
	v_cvt_pk_bf16_f32 v44, v32, v33
	v_cvt_pk_bf16_f32 v45, v34, v35
	global_store_dwordx4 v[46:47], v[42:45], off offset:256
	s_and_saveexec_b64 s[72:73], s[48:49]
	s_cbranch_execz .LBB0_2312
	v_readlane_b32 s4, v250, 58
	v_readlane_b32 s5, v250, 59
	v_lshlrev_b64 v[54:55], 2, v[40:41]
	s_nop 0
	v_lshl_add_u64 v[42:43], s[4:5], 0, v[52:53]
	v_lshl_add_u64 v[42:43], v[42:43], 0, v[54:55]
	global_store_dwordx4 v[42:43], v[36:39], off offset:512
	global_store_dwordx4 v[42:43], v[32:35], off offset:528
	v_mov_b32_dpp v42, v36 quad_perm:[0,0,0,0] row_mask:0xf bank_mask:0xf bound_ctrl:1
	v_add_f32_e32 v42, 0, v42
	v_cndmask_b32_e64 v42, 0, v42, s[40:41]
	v_readlane_b32 s4, v250, 12
	v_readlane_b32 s16, v250, 24
	v_add_f32_dpp v43, v36, v42 quad_perm:[1,1,1,1] row_mask:0xf bank_mask:0xf bound_ctrl:1
	v_cndmask_b32_e64 v42, v42, v43, s[44:45]
	v_readlane_b32 s17, v250, 25
	v_readlane_b32 s5, v250, 13
	v_add_f32_dpp v43, v36, v42 quad_perm:[2,2,2,2] row_mask:0xf bank_mask:0xf bound_ctrl:1
	v_cndmask_b32_e64 v42, v42, v43, s[42:43]
	v_lshl_add_u64 v[54:55], s[16:17], 0, v[54:55]
	v_lshl_add_u64 v[50:51], v[54:55], 0, v[50:51]
	v_add_f32_dpp v43, v36, v42 quad_perm:[3,3,3,3] row_mask:0xf bank_mask:0xf bound_ctrl:1
	v_cndmask_b32_e64 v42, v42, v43, s[0:1]
	v_readlane_b32 s6, v250, 14
	v_mov_b32_dpp v43, v37 quad_perm:[0,0,0,0] row_mask:0xf bank_mask:0xf bound_ctrl:1
	v_add_f32_e32 v43, 0, v43
	v_cndmask_b32_e64 v43, 0, v43, s[40:41]
	v_readlane_b32 s7, v250, 15
	v_readlane_b32 s8, v250, 16
	v_add_f32_dpp v44, v37, v43 quad_perm:[1,1,1,1] row_mask:0xf bank_mask:0xf bound_ctrl:1
	v_cndmask_b32_e64 v43, v43, v44, s[44:45]
	v_readlane_b32 s9, v250, 17
	v_readlane_b32 s10, v250, 18
	v_add_f32_dpp v44, v37, v43 quad_perm:[2,2,2,2] row_mask:0xf bank_mask:0xf bound_ctrl:1
	v_cndmask_b32_e64 v43, v43, v44, s[42:43]
	v_readlane_b32 s11, v250, 19
	v_readlane_b32 s12, v250, 20
	v_add_f32_dpp v44, v37, v43 quad_perm:[3,3,3,3] row_mask:0xf bank_mask:0xf bound_ctrl:1
	v_cndmask_b32_e64 v43, v43, v44, s[0:1]
	v_readlane_b32 s13, v250, 21
	v_mov_b32_dpp v44, v38 quad_perm:[0,0,0,0] row_mask:0xf bank_mask:0xf bound_ctrl:1
	v_add_f32_e32 v44, 0, v44
	v_cndmask_b32_e64 v44, 0, v44, s[40:41]
	v_readlane_b32 s14, v250, 22
	v_readlane_b32 s15, v250, 23
	v_add_f32_dpp v45, v38, v44 quad_perm:[1,1,1,1] row_mask:0xf bank_mask:0xf bound_ctrl:1
	v_cndmask_b32_e64 v44, v44, v45, s[44:45]
	v_readlane_b32 s18, v250, 26
	v_readlane_b32 s19, v250, 27
	v_add_f32_dpp v45, v38, v44 quad_perm:[2,2,2,2] row_mask:0xf bank_mask:0xf bound_ctrl:1
	v_cndmask_b32_e64 v44, v44, v45, s[42:43]
	s_nop 1
	v_add_f32_dpp v45, v38, v44 quad_perm:[3,3,3,3] row_mask:0xf bank_mask:0xf bound_ctrl:1
	v_cndmask_b32_e64 v44, v44, v45, s[0:1]
	s_nop 0
	v_mov_b32_dpp v45, v39 quad_perm:[0,0,0,0] row_mask:0xf bank_mask:0xf bound_ctrl:1
	v_add_f32_e32 v45, 0, v45
	v_cndmask_b32_e64 v45, 0, v45, s[40:41]
	s_nop 1
	v_add_f32_dpp v46, v39, v45 quad_perm:[1,1,1,1] row_mask:0xf bank_mask:0xf bound_ctrl:1
	v_cndmask_b32_e64 v45, v45, v46, s[44:45]
	s_nop 1
	v_add_f32_dpp v46, v39, v45 quad_perm:[2,2,2,2] row_mask:0xf bank_mask:0xf bound_ctrl:1
	v_cndmask_b32_e64 v45, v45, v46, s[42:43]
	s_nop 1
	v_add_f32_dpp v46, v39, v45 quad_perm:[3,3,3,3] row_mask:0xf bank_mask:0xf bound_ctrl:1
	v_cndmask_b32_e64 v45, v45, v46, s[0:1]
	s_nop 0
	v_mov_b32_dpp v46, v32 quad_perm:[0,0,0,0] row_mask:0xf bank_mask:0xf bound_ctrl:1
	v_add_f32_e32 v46, 0, v46
	v_cndmask_b32_e64 v46, 0, v46, s[40:41]
	s_nop 1
	v_add_f32_dpp v47, v32, v46 quad_perm:[1,1,1,1] row_mask:0xf bank_mask:0xf bound_ctrl:1
	v_cndmask_b32_e64 v46, v46, v47, s[44:45]
	s_nop 1
	v_add_f32_dpp v47, v32, v46 quad_perm:[2,2,2,2] row_mask:0xf bank_mask:0xf bound_ctrl:1
	v_cndmask_b32_e64 v46, v46, v47, s[42:43]
	s_nop 1
	v_add_f32_dpp v47, v32, v46 quad_perm:[3,3,3,3] row_mask:0xf bank_mask:0xf bound_ctrl:1
	v_cndmask_b32_e64 v46, v46, v47, s[0:1]
	s_nop 0
	v_mov_b32_dpp v47, v33 quad_perm:[0,0,0,0] row_mask:0xf bank_mask:0xf bound_ctrl:1
	v_add_f32_e32 v47, 0, v47
	v_cndmask_b32_e64 v47, 0, v47, s[40:41]
	s_nop 1
	v_add_f32_dpp v52, v33, v47 quad_perm:[1,1,1,1] row_mask:0xf bank_mask:0xf bound_ctrl:1
	v_cndmask_b32_e64 v47, v47, v52, s[44:45]
	s_nop 1
	v_add_f32_dpp v52, v33, v47 quad_perm:[2,2,2,2] row_mask:0xf bank_mask:0xf bound_ctrl:1
	v_cndmask_b32_e64 v47, v47, v52, s[42:43]
	s_nop 1
	v_add_f32_dpp v52, v33, v47 quad_perm:[3,3,3,3] row_mask:0xf bank_mask:0xf bound_ctrl:1
	v_cndmask_b32_e64 v47, v47, v52, s[0:1]
	s_nop 0
	v_mov_b32_dpp v52, v34 quad_perm:[0,0,0,0] row_mask:0xf bank_mask:0xf bound_ctrl:1
	v_add_f32_e32 v52, 0, v52
	v_cndmask_b32_e64 v52, 0, v52, s[40:41]
	s_nop 1
	v_add_f32_dpp v53, v34, v52 quad_perm:[1,1,1,1] row_mask:0xf bank_mask:0xf bound_ctrl:1
	v_cndmask_b32_e64 v52, v52, v53, s[44:45]
	s_nop 1
	v_add_f32_dpp v53, v34, v52 quad_perm:[2,2,2,2] row_mask:0xf bank_mask:0xf bound_ctrl:1
	v_cndmask_b32_e64 v52, v52, v53, s[42:43]
	s_nop 1
	v_add_f32_dpp v53, v34, v52 quad_perm:[3,3,3,3] row_mask:0xf bank_mask:0xf bound_ctrl:1
	v_cndmask_b32_e64 v52, v52, v53, s[0:1]
	s_nop 0
	v_mov_b32_dpp v53, v35 quad_perm:[0,0,0,0] row_mask:0xf bank_mask:0xf bound_ctrl:1
	v_add_f32_e32 v53, 0, v53
	v_cndmask_b32_e64 v53, 0, v53, s[40:41]
	s_nop 1
	v_add_f32_dpp v56, v35, v53 quad_perm:[1,1,1,1] row_mask:0xf bank_mask:0xf bound_ctrl:1
	v_cndmask_b32_e64 v53, v53, v56, s[44:45]
	s_nop 1
	v_add_f32_dpp v56, v35, v53 quad_perm:[2,2,2,2] row_mask:0xf bank_mask:0xf bound_ctrl:1
	v_cndmask_b32_e64 v53, v53, v56, s[42:43]
	s_nop 1
	v_add_f32_dpp v56, v35, v53 quad_perm:[3,3,3,3] row_mask:0xf bank_mask:0xf bound_ctrl:1
	v_cndmask_b32_e64 v53, v53, v56, s[0:1]
	s_and_saveexec_b64 s[48:49], s[38:39]
	s_cbranch_execz .LBB0_2558
	global_load_dwordx4 v[54:57], v[50:51], off offset:528
	global_load_dwordx4 v[58:61], v[50:51], off offset:512
	s_waitcnt vmcnt(0)
	v_pk_add_f32 v[46:47], v[46:47], v[54:55]
	v_pk_add_f32 v[52:53], v[52:53], v[56:57]
	v_pk_add_f32 v[44:45], v[44:45], v[60:61]
	v_pk_add_f32 v[42:43], v[42:43], v[58:59]
	s_or_b64 exec, exec, s[48:49]
	s_and_saveexec_b64 s[48:49], s[36:37]
	s_cbranch_execnz .LBB0_2559

; __device__ __forceinline__ void st8bf(bf16_t* p, f32x4 a, f32x4 b) { u32x4 w; w.x = pk2(a[0], a[1]); w.y = pk2(a[2], a[3]); w.z = pk2(b[0], b[1]); w.w = pk2(b[2], b[3]); st16(p, w); }
;     __device__ __forceinline__ void st(int pn, int row, int c, f32x4 v0, f32x4 v1) const {
;     ...
;                 const float inv = 1.f / (float)w;
;                 st8bf(DMs + (size_t)row * 1024 + col, (f32x4){s[0] * inv - x[0], s[1] * inv - x[1], s[2] * inv - x[2], s[3] * inv - x[3]}, (f32x4){s[4] * inv - x[4], s[5] * inv - x[5], s[6] * inv - x[6], s[7] * inv - x[7]});
.LBB0_2311:
	s_or_b64 exec, exec, s[48:49]
	v_readlane_b32 s4, v251, 0
	v_readlane_b32 s5, v251, 1
	v_mov_b32_e32 v51, v38
	v_mov_b32_e32 v38, v37
	v_lshl_add_u64 v[48:49], v[48:49], 1, s[4:5]
	v_lshl_add_u64 v[40:41], v[40:41], 1, v[48:49]
	v_mov_b32_e32 v49, v44
	v_mov_b32_e32 v44, v43
	v_mov_b32_e32 v50, v36
	v_pk_fma_f32 v[36:37], s[68:69], v[44:45], v[38:39] op_sel_hi:[0,1,1] neg_lo:[0,0,1] neg_hi:[0,0,1]
	v_mov_b32_e32 v39, v52
	v_mov_b32_e32 v43, v34
	v_mov_b32_e32 v52, v47
	v_mov_b32_e32 v34, v33
	v_mov_b32_e32 v48, v42
	v_mov_b32_e32 v38, v46
	v_mov_b32_e32 v42, v32
	v_pk_fma_f32 v[32:33], s[68:69], v[52:53], v[34:35] op_sel_hi:[0,1,1] neg_lo:[0,0,1] neg_hi:[0,0,1]
	v_pk_fma_f32 v[48:49], s[68:69], v[48:49], v[50:51] op_sel_hi:[0,1,1] neg_lo:[0,0,1] neg_hi:[0,0,1]
	v_pk_fma_f32 v[38:39], s[68:69], v[38:39], v[42:43] op_sel_hi:[0,1,1] neg_lo:[0,0,1] neg_hi:[0,0,1]
	v_cvt_pk_bf16_f32 v35, v39, v33
	v_cvt_pk_bf16_f32 v34, v38, v32
	v_cvt_pk_bf16_f32 v33, v49, v37
	v_cvt_pk_bf16_f32 v32, v48, v36
	global_store_dwordx4 v[40:41], v[32:35], off offset:256

; __device__ __forceinline__ void st8bf(bf16_t* p, f32x4 a, f32x4 b) { u32x4 w; w.x = pk2(a[0], a[1]); w.y = pk2(a[2], a[3]); w.z = pk2(b[0], b[1]); w.w = pk2(b[2], b[3]); st16(p, w); }
; __device__ __forceinline__ f32x4 sig4(f32x4 v) { f32x4 r; r[0] = sigmoidf_(v[0]); r[1] = sigmoidf_(v[1]); r[2] = sigmoidf_(v[2]); r[3] = sigmoidf_(v[3]); return r; }
; #define EPI_LOOP_ROWS(body) _Pragma("unroll") for (int ai = 0; ai < 2; ++ai) _Pragma("unroll") for (int m = 0; m < 4; ++m) { const int row = u.pm * 256 + ai * 128 + wr * 64 + m * 16 + fr; body }
;     __device__ __forceinline__ void st(int pn, int row, int c, f32x4 v0, f32x4 v1) const {
;     ...
;         else st8bf(GT + (size_t)row * 1024 + (pn - 4) * 256 + c, v0 * sig4(v0), v1 * sig4(v1));
;     }
;     __device__ __forceinline__ void operator()(const f32x4 (&acc)[2][2][4][2], const pg8::Unit& u, int wr, int wc, int fr, int fq) const {
;         const int cw = wc * 32 + 8 * fq;
;         EPI_LOOP_ROWS( _Pragma("unroll") for (int bj = 0; bj < 2; ++bj) st(u.pn, row, bj * 128 + cw, acc[ai][bj][m][0], acc[ai][bj][m][1]); )
.LBB0_2313:
	s_nop 0
	v_add_u32_e32 v32, 0xa0, v150
	v_ashrrev_i32_e32 v33, 31, v32
	v_cmp_lt_i32_e64 s[48:49], s89, v32
	v_lshlrev_b64 v[38:39], 11, v[32:33]
	s_and_b64 vcc, exec, s[46:47]
	s_mov_b64 s[72:73], -1
	s_cbranch_vccnz .LBB0_2315
	v_lshl_add_u64 v[34:35], s[54:55], 0, v[38:39]
	v_mul_f32_e32 v36, 0xbfb8aa3b, v28
	v_exp_f32_e32 v36, v36
	v_lshl_add_u64 v[34:35], s[60:61], 1, v[34:35]
	v_lshlrev_b32_e32 v138, 1, v140
	v_lshl_add_u64 v[40:41], v[34:35], 0, v[138:139]
	v_mul_f32_e32 v35, 0xbfb8aa3b, v29
	v_exp_f32_e32 v35, v35
	v_add_f32_e32 v34, 1.0, v36
	v_mul_f32_e32 v36, 0xbfb8aa3b, v30
	v_mul_f32_e32 v37, 0xbfb8aa3b, v31
	v_exp_f32_e32 v36, v36
	v_exp_f32_e32 v37, v37
	v_add_f32_e32 v35, 1.0, v35
	v_rcp_f32_e32 v34, v34
	v_rcp_f32_e32 v35, v35
	v_mul_f32_e32 v42, 0xbfb8aa3b, v24
	v_mul_f32_e32 v43, 0xbfb8aa3b, v25
	v_exp_f32_e32 v42, v42
	v_exp_f32_e32 v43, v43
	v_add_f32_e32 v36, 1.0, v36
	v_add_f32_e32 v37, 1.0, v37
	v_rcp_f32_e32 v36, v36
	v_rcp_f32_e32 v37, v37
	v_mul_f32_e32 v44, 0xbfb8aa3b, v26
	v_mul_f32_e32 v45, 0xbfb8aa3b, v27
	v_exp_f32_e32 v44, v44
	v_exp_f32_e32 v45, v45
	v_pk_mul_f32 v[34:35], v[28:29], v[34:35]
	v_add_f32_e32 v42, 1.0, v42
	v_add_f32_e32 v43, 1.0, v43
	v_rcp_f32_e32 v42, v42
	v_rcp_f32_e32 v43, v43
	v_pk_mul_f32 v[36:37], v[30:31], v[36:37]
	v_add_f32_e32 v44, 1.0, v44
	v_add_f32_e32 v45, 1.0, v45
	v_cvt_pk_bf16_f32 v34, v34, v35
	v_rcp_f32_e32 v44, v44
	v_rcp_f32_e32 v45, v45
	v_pk_mul_f32 v[42:43], v[24:25], v[42:43]
	v_cvt_pk_bf16_f32 v35, v36, v37
	v_pk_mul_f32 v[44:45], v[26:27], v[44:45]
	v_cvt_pk_bf16_f32 v36, v42, v43
	v_cvt_pk_bf16_f32 v37, v44, v45
	s_mov_b64 s[72:73], 0
	global_store_dwordx4 v[40:41], v[34:37], off
; __device__ __forceinline__ void st16f(float* p, f32x4 v) { st16(p, __builtin_bit_cast(u32x4, v)); }
; __device__ __forceinline__ void st8bf(bf16_t* p, f32x4 a, f32x4 b) { u32x4 w; w.x = pk2(a[0], a[1]); w.y = pk2(a[2], a[3]); w.z = pk2(b[0], b[1]); w.w = pk2(b[2], b[3]); st16(p, w); }
;     __device__ __forceinline__ void st(int pn, int row, int c, f32x4 v0, f32x4 v1) const {
;         const bool smp = row >= MP; const int b = smp ? (row - MP) >> 2 : row >> 13, t = smp ? (row - MP) & 3 : row & (SEQ - 1);
;         if (pn < 4) { const int col = pn * 256 + c; float* o = nullptr;
;             if (smp) o = out + O_POOLS + ((size_t)b * 15 + 11 + t) * 1024 + col;
;             st8bf(V + (size_t)row * 1024 + col, v0, v1); if (o) { st16f(o, v0); st16f(o + 4, v1); }
;             if (smp) {
;                 const int w = 2 << pn;
;                 float x[8] = {v0[0], v0[1], v0[2], v0[3], v1[0], v1[1], v1[2], v1[3]}, s[8];
; #pragma unroll
;                 for (int e = 0; e < 8; ++e) { s[e] = 0.f;
; #pragma unroll
;                     for (int tp = 0; tp < 4; ++tp) { const float xo = quad_bcast(x[e], tp); if (tp <= t && t - tp < w) s[e] += xo; } }
;                 const int e_lo = 15 + t - w + 1;
; #pragma unroll
;                 for (int e2 = 0; e2 < 15; ++e2) if (e2 >= e_lo) { const float* sp = state_pool + ((size_t)b * 15 + e2) * 1024 + col; const f32x4 a = *(const f32x4*)sp, d = *(const f32x4*)(sp + 4);
;                     s[0] += a[0]; s[1] += a[1]; s[2] += a[2]; s[3] += a[3]; s[4] += d[0]; s[5] += d[1]; s[6] += d[2]; s[7] += d[3]; }
.LBB0_2315:
	s_nop 1
	v_add_u32_e32 v34, 0xffff80a0, v150
	v_lshrrev_b32_e32 v40, 2, v34
	v_mad_u64_u32 v[34:35], s[74:75], v40, 15, v[128:129]
	v_lshlrev_b64 v[36:37], 12, v[34:35]
	v_lshlrev_b64 v[32:33], 10, v[32:33]
	s_andn2_b64 vcc, exec, s[72:73]
	v_mad_u64_u32 v[34:35], s[72:73], v40, s90, 0
	s_cbranch_vccnz .LBB0_2336
	v_or_b32_e32 v40, s70, v140
	v_ashrrev_i32_e32 v41, 31, v40
	v_lshl_add_u64 v[42:43], v[32:33], 1, s[52:53]
	v_lshl_add_u64 v[46:47], v[40:41], 1, v[42:43]
	v_cvt_pk_bf16_f32 v42, v28, v29
	v_cvt_pk_bf16_f32 v43, v30, v31
	v_cvt_pk_bf16_f32 v44, v24, v25
	v_bfe_u32 v45, v26, 16, 1
	v_add3_u32 v45, v26, v45, s89
	v_bfe_u32 v48, v27, 16, 1
	v_lshrrev_b32_e32 v45, 16, v45
	v_add3_u32 v48, v27, v48, s89
	v_and_or_b32 v45, v48, s91, v45
	global_store_dwordx4 v[46:47], v[42:45], off
	s_and_saveexec_b64 s[72:73], s[48:49]
	s_cbranch_execz .LBB0_2334
	v_readlane_b32 s4, v250, 58
	v_readlane_b32 s5, v250, 59
	v_lshlrev_b64 v[50:51], 2, v[40:41]
	s_nop 0
	v_lshl_add_u64 v[42:43], s[4:5], 0, v[36:37]
	v_lshl_add_u64 v[42:43], v[42:43], 0, v[50:51]
	global_store_dwordx4 v[42:43], v[28:31], off
	global_store_dwordx4 v[42:43], v[24:27], off offset:16
	v_mov_b32_dpp v42, v28 quad_perm:[0,0,0,0] row_mask:0xf bank_mask:0xf bound_ctrl:1
	v_add_f32_e32 v42, 0, v42
	v_cndmask_b32_e64 v42, 0, v42, s[40:41]
	v_readlane_b32 s4, v250, 12
	v_readlane_b32 s16, v250, 24
	v_add_f32_dpp v43, v28, v42 quad_perm:[1,1,1,1] row_mask:0xf bank_mask:0xf bound_ctrl:1
	v_cndmask_b32_e64 v42, v42, v43, s[44:45]
	v_readlane_b32 s17, v250, 25
	v_readlane_b32 s5, v250, 13
	v_add_f32_dpp v43, v28, v42 quad_perm:[2,2,2,2] row_mask:0xf bank_mask:0xf bound_ctrl:1
	v_cndmask_b32_e64 v42, v42, v43, s[42:43]
	v_lshl_add_u64 v[50:51], s[16:17], 0, v[50:51]
	v_lshl_add_u64 v[50:51], v[50:51], 0, v[34:35]
	v_add_f32_dpp v43, v28, v42 quad_perm:[3,3,3,3] row_mask:0xf bank_mask:0xf bound_ctrl:1
	v_cndmask_b32_e64 v42, v42, v43, s[0:1]
	v_readlane_b32 s6, v250, 14
	v_mov_b32_dpp v43, v29 quad_perm:[0,0,0,0] row_mask:0xf bank_mask:0xf bound_ctrl:1
	v_add_f32_e32 v43, 0, v43
	v_cndmask_b32_e64 v43, 0, v43, s[40:41]
	v_readlane_b32 s7, v250, 15
	v_readlane_b32 s8, v250, 16
	v_add_f32_dpp v44, v29, v43 quad_perm:[1,1,1,1] row_mask:0xf bank_mask:0xf bound_ctrl:1
	v_cndmask_b32_e64 v43, v43, v44, s[44:45]
	v_readlane_b32 s9, v250, 17
	v_readlane_b32 s10, v250, 18
	v_add_f32_dpp v44, v29, v43 quad_perm:[2,2,2,2] row_mask:0xf bank_mask:0xf bound_ctrl:1
	v_cndmask_b32_e64 v43, v43, v44, s[42:43]
	v_readlane_b32 s11, v250, 19
	v_readlane_b32 s12, v250, 20
	v_add_f32_dpp v44, v29, v43 quad_perm:[3,3,3,3] row_mask:0xf bank_mask:0xf bound_ctrl:1
	v_cndmask_b32_e64 v43, v43, v44, s[0:1]
	v_readlane_b32 s13, v250, 21
	v_mov_b32_dpp v44, v30 quad_perm:[0,0,0,0] row_mask:0xf bank_mask:0xf bound_ctrl:1
	v_add_f32_e32 v44, 0, v44
	v_cndmask_b32_e64 v44, 0, v44, s[40:41]
	v_readlane_b32 s14, v250, 22
	v_readlane_b32 s15, v250, 23
	v_add_f32_dpp v45, v30, v44 quad_perm:[1,1,1,1] row_mask:0xf bank_mask:0xf bound_ctrl:1
	v_cndmask_b32_e64 v44, v44, v45, s[44:45]
	v_readlane_b32 s18, v250, 26
	v_readlane_b32 s19, v250, 27
	v_add_f32_dpp v45, v30, v44 quad_perm:[2,2,2,2] row_mask:0xf bank_mask:0xf bound_ctrl:1
	v_cndmask_b32_e64 v44, v44, v45, s[42:43]
	s_nop 1
	v_add_f32_dpp v45, v30, v44 quad_perm:[3,3,3,3] row_mask:0xf bank_mask:0xf bound_ctrl:1
	v_cndmask_b32_e64 v44, v44, v45, s[0:1]
	s_nop 0
	v_mov_b32_dpp v45, v31 quad_perm:[0,0,0,0] row_mask:0xf bank_mask:0xf bound_ctrl:1
	v_add_f32_e32 v45, 0, v45
	v_cndmask_b32_e64 v45, 0, v45, s[40:41]
	s_nop 1
	v_add_f32_dpp v46, v31, v45 quad_perm:[1,1,1,1] row_mask:0xf bank_mask:0xf bound_ctrl:1
	v_cndmask_b32_e64 v45, v45, v46, s[44:45]
	s_nop 1
	v_add_f32_dpp v46, v31, v45 quad_perm:[2,2,2,2] row_mask:0xf bank_mask:0xf bound_ctrl:1
	v_cndmask_b32_e64 v45, v45, v46, s[42:43]
	s_nop 1
	v_add_f32_dpp v46, v31, v45 quad_perm:[3,3,3,3] row_mask:0xf bank_mask:0xf bound_ctrl:1
	v_cndmask_b32_e64 v45, v45, v46, s[0:1]
	s_nop 0
	v_mov_b32_dpp v46, v24 quad_perm:[0,0,0,0] row_mask:0xf bank_mask:0xf bound_ctrl:1
	v_add_f32_e32 v46, 0, v46
	v_cndmask_b32_e64 v46, 0, v46, s[40:41]
	s_nop 1
	v_add_f32_dpp v47, v24, v46 quad_perm:[1,1,1,1] row_mask:0xf bank_mask:0xf bound_ctrl:1
	v_cndmask_b32_e64 v46, v46, v47, s[44:45]
	s_nop 1
	v_add_f32_dpp v47, v24, v46 quad_perm:[2,2,2,2] row_mask:0xf bank_mask:0xf bound_ctrl:1
	v_cndmask_b32_e64 v46, v46, v47, s[42:43]
	s_nop 1
	v_add_f32_dpp v47, v24, v46 quad_perm:[3,3,3,3] row_mask:0xf bank_mask:0xf bound_ctrl:1
	v_cndmask_b32_e64 v46, v46, v47, s[0:1]
	s_nop 0
	v_mov_b32_dpp v47, v25 quad_perm:[0,0,0,0] row_mask:0xf bank_mask:0xf bound_ctrl:1
	v_add_f32_e32 v47, 0, v47
	v_cndmask_b32_e64 v47, 0, v47, s[40:41]
	s_nop 1
	v_add_f32_dpp v48, v25, v47 quad_perm:[1,1,1,1] row_mask:0xf bank_mask:0xf bound_ctrl:1
	v_cndmask_b32_e64 v47, v47, v48, s[44:45]
	s_nop 1
	v_add_f32_dpp v48, v25, v47 quad_perm:[2,2,2,2] row_mask:0xf bank_mask:0xf bound_ctrl:1
	v_cndmask_b32_e64 v47, v47, v48, s[42:43]
	s_nop 1
	v_add_f32_dpp v48, v25, v47 quad_perm:[3,3,3,3] row_mask:0xf bank_mask:0xf bound_ctrl:1
	v_cndmask_b32_e64 v47, v47, v48, s[0:1]
	s_nop 0
	v_mov_b32_dpp v48, v26 quad_perm:[0,0,0,0] row_mask:0xf bank_mask:0xf bound_ctrl:1
	v_add_f32_e32 v48, 0, v48
	v_cndmask_b32_e64 v48, 0, v48, s[40:41]
	s_nop 1
	v_add_f32_dpp v49, v26, v48 quad_perm:[1,1,1,1] row_mask:0xf bank_mask:0xf bound_ctrl:1
	v_cndmask_b32_e64 v48, v48, v49, s[44:45]
	s_nop 1
	v_add_f32_dpp v49, v26, v48 quad_perm:[2,2,2,2] row_mask:0xf bank_mask:0xf bound_ctrl:1
	v_cndmask_b32_e64 v48, v48, v49, s[42:43]
	s_nop 1
	v_add_f32_dpp v49, v26, v48 quad_perm:[3,3,3,3] row_mask:0xf bank_mask:0xf bound_ctrl:1
	v_cndmask_b32_e64 v48, v48, v49, s[0:1]
	s_nop 0
	v_mov_b32_dpp v49, v27 quad_perm:[0,0,0,0] row_mask:0xf bank_mask:0xf bound_ctrl:1
	v_add_f32_e32 v49, 0, v49
	v_cndmask_b32_e64 v49, 0, v49, s[40:41]
	s_nop 1
	v_add_f32_dpp v52, v27, v49 quad_perm:[1,1,1,1] row_mask:0xf bank_mask:0xf bound_ctrl:1
	v_cndmask_b32_e64 v49, v49, v52, s[44:45]
	s_nop 1
	v_add_f32_dpp v52, v27, v49 quad_perm:[2,2,2,2] row_mask:0xf bank_mask:0xf bound_ctrl:1
	v_cndmask_b32_e64 v49, v49, v52, s[42:43]
	s_nop 1
	v_add_f32_dpp v52, v27, v49 quad_perm:[3,3,3,3] row_mask:0xf bank_mask:0xf bound_ctrl:1
	v_cndmask_b32_e64 v49, v49, v52, s[0:1]
	s_and_saveexec_b64 s[74:75], s[38:39]
	s_cbranch_execz .LBB0_2572
	global_load_dwordx4 v[52:55], v[50:51], off offset:16
	global_load_dwordx4 v[56:59], v[50:51], off
	s_waitcnt vmcnt(0)
	v_pk_add_f32 v[46:47], v[46:47], v[52:53]
	v_pk_add_f32 v[48:49], v[48:49], v[54:55]
	v_pk_add_f32 v[44:45], v[44:45], v[58:59]
	v_pk_add_f32 v[42:43], v[42:43], v[56:57]
	s_or_b64 exec, exec, s[74:75]
	s_and_saveexec_b64 s[74:75], s[36:37]
	s_cbranch_execnz .LBB0_2573

; __device__ __forceinline__ void fir_tile(const Prm& P, Ctx& C, int pm, int gi) {
;     const bf16_t* Z = (const bf16_t*)(P.ws + WS_V); const bf16_t* GT = (const bf16_t*)(P.ws + WS_GT); bf16_t* MX = (bf16_t*)(P.ws + WS_MX);
;     constexpr int RUN = 16;
;     const int c0 = 256 * gi + (C.tid & 31) * 8, row0 = 256 * pm + (C.tid >> 5) * RUN, w = 2 << gi, t0 = row0 & (SEQ - 1);
;     const bf16_t* zp = Z + (size_t)row0 * 1024 + c0;
;     u32x4 x[RUN + 15];
; #pragma unroll
;     for (int j = 0; j < RUN + 15; ++j) { const int k = j - 15; x[j] = (k >= 1 - w && t0 + k >= 0) ? *(const u32x4*)(zp + (ptrdiff_t)k * 1024) : (u32x4){0u, 0u, 0u, 0u}; }
;     const f32x4 sc0 = *(const f32x4*)(P.pool_scale + c0), sc1 = *(const f32x4*)(P.pool_scale + c0 + 4);
;     float s[8];
; #pragma unroll
;     for (int e = 0; e < 8; ++e) s[e] = 0.f;
; #pragma unroll
;     for (int j = 0; j < 15; ++j) acc8(s, x[j], 1.f);
.LBB0_2760:
	v_readlane_b32 s20, v250, 0
	v_readlane_b32 s22, v250, 2
	v_readlane_b32 s23, v250, 3
	s_waitcnt vmcnt(0)
	v_lshlrev_b32_e32 v199, 16, v93
	v_lshlrev_b32_e32 v198, 16, v92
	v_and_b32_e32 v201, 0xffff0000, v93
	v_and_b32_e32 v200, 0xffff0000, v92
	v_lshlrev_b64 v[92:93], 1, v[168:169]
	v_lshl_add_u64 v[4:5], v[168:169], 2, s[22:23]
	v_lshlrev_b32_e32 v190, 16, v98
	v_and_b32_e32 v192, 0xffff0000, v98
	v_lshlrev_b32_e32 v191, 16, v99
	v_and_b32_e32 v193, 0xffff0000, v99
	v_lshl_add_u64 v[98:99], s[4:5], 0, v[92:93]
	global_load_dwordx4 v[0:3], v[4:5], off offset:16
	s_nop 0
	global_load_dwordx4 v[4:7], v[4:5], off
	v_lshlrev_b32_e32 v186, 16, v96
	v_and_b32_e32 v188, 0xffff0000, v96
	v_lshlrev_b32_e32 v187, 16, v97
	v_and_b32_e32 v189, 0xffff0000, v97
	v_lshl_add_u64 v[96:97], s[6:7], 0, v[92:93]
	v_lshl_add_u64 v[92:93], v[98:99], 0, v[196:197]
	v_lshlrev_b32_e32 v203, 16, v95
	v_lshlrev_b32_e32 v202, 16, v94
	v_and_b32_e32 v205, 0xffff0000, v95
	v_and_b32_e32 v204, 0xffff0000, v94
	global_load_dwordx4 v[92:95], v[92:93], off
	v_and_b32_e32 v217, 0xffff0000, v69
	v_and_b32_e32 v216, 0xffff0000, v68
	v_lshlrev_b32_e32 v207, 16, v65
	v_lshlrev_b32_e32 v206, 16, v64
	v_and_b32_e32 v209, 0xffff0000, v65
	v_and_b32_e32 v208, 0xffff0000, v64
	v_pk_add_f32 v[64:65], v[216:217], 0 op_sel_hi:[1,0]
	v_lshlrev_b32_e32 v175, 16, v85
	v_lshlrev_b32_e32 v174, 16, v84
	v_and_b32_e32 v177, 0xffff0000, v85
	v_and_b32_e32 v176, 0xffff0000, v84
	v_and_b32_e32 v85, 0xffff0000, v73
	v_and_b32_e32 v84, 0xffff0000, v72
	v_pk_add_f32 v[64:65], v[64:65], v[208:209]
	v_and_b32_e32 v183, 0xffff0000, v77
	v_pk_add_f32 v[64:65], v[64:65], v[84:85]
	v_and_b32_e32 v182, 0xffff0000, v76
	v_pk_add_f32 v[64:65], v[64:65], v[200:201]
	v_lshlrev_b32_e32 v137, 16, v105
	v_pk_add_f32 v[64:65], v[64:65], v[188:189]
	v_lshlrev_b32_e32 v136, 16, v104
	v_pk_add_f32 v[64:65], v[64:65], v[182:183]
	v_and_b32_e32 v139, 0xffff0000, v105
	v_and_b32_e32 v138, 0xffff0000, v104
	v_lshlrev_b32_e32 v141, 16, v107
	v_lshlrev_b32_e32 v140, 16, v106
	v_and_b32_e32 v143, 0xffff0000, v107
	v_and_b32_e32 v142, 0xffff0000, v106
	v_lshlrev_b32_e32 v105, 16, v129
	v_lshlrev_b32_e32 v104, 16, v128
	v_and_b32_e32 v107, 0xffff0000, v129
	v_and_b32_e32 v106, 0xffff0000, v128
	v_lshlrev_b32_e32 v129, 16, v81
	v_lshlrev_b32_e32 v128, 16, v80
	v_and_b32_e32 v81, 0xffff0000, v81
	v_and_b32_e32 v80, 0xffff0000, v80
	v_pk_add_f32 v[64:65], v[64:65], v[176:177]
	v_and_b32_e32 v163, 0xffff0000, v117
	v_and_b32_e32 v162, 0xffff0000, v116
	v_pk_add_f32 v[64:65], v[64:65], v[80:81]
	v_and_b32_e32 v155, 0xffff0000, v109
	v_and_b32_e32 v154, 0xffff0000, v108
	v_pk_add_f32 v[64:65], v[64:65], v[162:163]
	v_and_b32_e32 v147, 0xffff0000, v113
	v_and_b32_e32 v146, 0xffff0000, v112
	v_pk_add_f32 v[64:65], v[64:65], v[154:155]
	v_lshlrev_b32_e32 v135, 16, v125
	v_pk_add_f32 v[64:65], v[64:65], v[146:147]
	v_lshlrev_b32_e32 v134, 16, v124
	v_and_b32_e32 v125, 0xffff0000, v125
	v_and_b32_e32 v124, 0xffff0000, v124
	v_pk_add_f32 v[64:65], v[64:65], v[138:139]
	v_lshlrev_b32_e32 v145, 16, v113
	v_lshlrev_b32_e32 v144, 16, v112
	v_and_b32_e32 v113, 0xffff0000, v121
	v_and_b32_e32 v112, 0xffff0000, v120
	v_pk_add_f32 v[64:65], v[64:65], v[124:125]
	v_lshlrev_b32_e32 v169, 16, v77
	v_pk_add_f32 v[64:65], v[64:65], v[112:113]
	v_lshlrev_b32_e32 v168, 16, v76
	v_and_b32_e32 v77, 0xffff0000, v101
	v_and_b32_e32 v76, 0xffff0000, v100
	v_pk_add_f32 v[64:65], v[64:65], v[106:107]
	v_lshlrev_b32_e32 v221, 16, v71
	v_lshlrev_b32_e32 v220, 16, v70
	v_pk_add_f32 v[218:219], v[64:65], v[76:77]
	v_lshlrev_b32_e32 v211, 16, v67
	v_lshlrev_b32_e32 v210, 16, v66
	v_pk_add_f32 v[64:65], v[220:221], 0 op_sel_hi:[1,0]
	v_lshlrev_b32_e32 v165, 16, v119
	v_lshlrev_b32_e32 v164, 16, v118
	v_and_b32_e32 v167, 0xffff0000, v119
	v_and_b32_e32 v166, 0xffff0000, v118
	v_lshlrev_b32_e32 v149, 16, v115
	v_lshlrev_b32_e32 v148, 16, v114
	v_lshlrev_b32_e32 v119, 16, v123
	v_lshlrev_b32_e32 v118, 16, v122
	v_and_b32_e32 v151, 0xffff0000, v115
	v_and_b32_e32 v150, 0xffff0000, v114
	v_and_b32_e32 v115, 0xffff0000, v123
	v_and_b32_e32 v114, 0xffff0000, v122
	v_lshlrev_b32_e32 v123, 16, v101
	v_lshlrev_b32_e32 v122, 16, v100
	v_lshlrev_b32_e32 v101, 16, v75
	v_lshlrev_b32_e32 v100, 16, v74
	v_pk_add_f32 v[64:65], v[64:65], v[210:211]
	v_lshlrev_b32_e32 v185, 16, v79
	v_pk_add_f32 v[64:65], v[64:65], v[100:101]
	v_lshlrev_b32_e32 v184, 16, v78
	v_pk_add_f32 v[64:65], v[64:65], v[202:203]
	v_lshlrev_b32_e32 v179, 16, v87
	v_pk_add_f32 v[64:65], v[64:65], v[190:191]
	v_lshlrev_b32_e32 v178, 16, v86
	v_pk_add_f32 v[64:65], v[64:65], v[184:185]
	v_lshlrev_b32_e32 v153, 16, v109
	v_lshlrev_b32_e32 v152, 16, v108
	v_lshlrev_b32_e32 v157, 16, v111
	v_lshlrev_b32_e32 v156, 16, v110
	v_and_b32_e32 v159, 0xffff0000, v111
	v_and_b32_e32 v158, 0xffff0000, v110
	v_lshlrev_b32_e32 v109, 16, v131
	v_lshlrev_b32_e32 v108, 16, v130
	v_and_b32_e32 v111, 0xffff0000, v131
	v_and_b32_e32 v110, 0xffff0000, v130
	v_lshlrev_b32_e32 v131, 16, v73
	v_lshlrev_b32_e32 v130, 16, v72
	v_lshlrev_b32_e32 v73, 16, v83
	v_lshlrev_b32_e32 v72, 16, v82
	v_pk_add_f32 v[64:65], v[64:65], v[178:179]
	v_lshlrev_b32_e32 v161, 16, v117
	v_pk_add_f32 v[64:65], v[64:65], v[72:73]
	v_lshlrev_b32_e32 v160, 16, v116
; __device__ __forceinline__ unsigned pk2(float lo, float hi) { return f2bf(lo) | (f2bf(hi) << 16); }
; __device__ __forceinline__ void fir_tile(const Prm& P, Ctx& C, int pm, int gi) {
;     ...
;     for (int j = 0; j < 15; ++j) acc8(s, x[j], 1.f);
; #pragma unroll
;     for (int j = 0; j < RUN; ++j) {
;         const int t = t0 + j;
;         const u32x4 g = *(const u32x4*)(GT + (size_t)(row0 + j) * 1024 + c0);
;         acc8(s, x[15 + j], 1.f);
;         const float inv = 1.f / (float)(t + 1 < w ? t + 1 : w);
;         const u32x4 xc = x[15 + j];
;         u32x4 o;
;         o.x = pk2((s[0] * inv - bflo(xc.x)) * sc0[0] * bflo(g.x), (s[1] * inv - bfhi(xc.x)) * sc0[1] * bfhi(g.x));
;         o.y = pk2((s[2] * inv - bflo(xc.y)) * sc0[2] * bflo(g.y), (s[3] * inv - bfhi(xc.y)) * sc0[3] * bfhi(g.y));
;         o.z = pk2((s[4] * inv - bflo(xc.z)) * sc1[0] * bflo(g.z), (s[5] * inv - bfhi(xc.z)) * sc1[1] * bfhi(g.z));
;         o.w = pk2((s[6] * inv - bflo(xc.w)) * sc1[2] * bflo(g.w), (s[7] * inv - bfhi(xc.w)) * sc1[3] * bfhi(g.w));
;         *(u32x4*)(MX + (size_t)(row0 + j) * 1024 + c0) = o;
	v_pk_add_f32 v[64:65], v[64:65], v[164:165]
	v_lshlrev_b32_e32 v117, 16, v121
	v_pk_add_f32 v[64:65], v[64:65], v[156:157]
	v_lshlrev_b32_e32 v116, 16, v120
	v_pk_add_f32 v[64:65], v[64:65], v[148:149]
	v_lshlrev_b32_e32 v121, 16, v127
	v_lshlrev_b32_e32 v120, 16, v126
	v_pk_add_f32 v[64:65], v[64:65], v[140:141]
	v_lshlrev_b32_e32 v213, 16, v69
	v_pk_add_f32 v[64:65], v[64:65], v[120:121]
	v_lshlrev_b32_e32 v212, 16, v68
	v_pk_add_f32 v[64:65], v[64:65], v[118:119]
	v_pk_add_f32 v[170:171], v[212:213], 0 op_sel_hi:[1,0]
	v_lshlrev_b32_e32 v69, 16, v103
	v_lshlrev_b32_e32 v68, 16, v102
	v_pk_add_f32 v[64:65], v[64:65], v[108:109]
	v_and_b32_e32 v195, 0xffff0000, v79
	v_and_b32_e32 v194, 0xffff0000, v78
	v_and_b32_e32 v79, 0xffff0000, v71
	v_and_b32_e32 v78, 0xffff0000, v70
	v_pk_add_f32 v[170:171], v[170:171], v[206:207]
	v_pk_add_f32 v[222:223], v[64:65], v[68:69]
	v_and_b32_e32 v71, 0xffff0000, v67
	v_and_b32_e32 v70, 0xffff0000, v66
	v_pk_add_f32 v[64:65], v[78:79], 0 op_sel_hi:[1,0]
	v_pk_add_f32 v[170:171], v[170:171], v[130:131]
	v_and_b32_e32 v181, 0xffff0000, v87
	v_and_b32_e32 v180, 0xffff0000, v86
	v_and_b32_e32 v87, 0xffff0000, v75
	v_and_b32_e32 v86, 0xffff0000, v74
	v_pk_add_f32 v[64:65], v[64:65], v[70:71]
	v_pk_add_f32 v[170:171], v[170:171], v[198:199]
	v_pk_add_f32 v[64:65], v[64:65], v[86:87]
	v_pk_add_f32 v[170:171], v[170:171], v[186:187]
	v_pk_add_f32 v[64:65], v[64:65], v[204:205]
	v_or_b32_e32 v133, 1, v226
	v_pk_add_f32 v[170:171], v[170:171], v[168:169]
	v_pk_add_f32 v[64:65], v[64:65], v[192:193]
	v_pk_add_f32 v[170:171], v[170:171], v[174:175]
	v_pk_add_f32 v[64:65], v[64:65], v[194:195]
	v_min_i32_e32 v66, s16, v133
	v_pk_add_f32 v[170:171], v[170:171], v[128:129]
	v_and_b32_e32 v173, 0xffff0000, v83
	v_and_b32_e32 v172, 0xffff0000, v82
	v_pk_add_f32 v[64:65], v[64:65], v[180:181]
	v_cvt_f32_i32_e32 v74, v66
	v_pk_add_f32 v[170:171], v[170:171], v[160:161]
	v_pk_add_f32 v[64:65], v[64:65], v[172:173]
	v_pk_add_f32 v[170:171], v[170:171], v[152:153]
	v_pk_add_f32 v[64:65], v[64:65], v[166:167]
	v_pk_add_f32 v[170:171], v[170:171], v[144:145]
	v_pk_add_f32 v[64:65], v[64:65], v[158:159]
	v_pk_add_f32 v[170:171], v[170:171], v[136:137]
	v_pk_add_f32 v[64:65], v[64:65], v[150:151]
	v_div_scale_f32 v75, s[10:11], v74, v74, 1.0
	v_and_b32_e32 v127, 0xffff0000, v127
	v_and_b32_e32 v126, 0xffff0000, v126
	v_pk_add_f32 v[170:171], v[170:171], v[134:135]
	v_pk_add_f32 v[64:65], v[64:65], v[142:143]
	v_rcp_f32_e32 v82, v75
	v_pk_add_f32 v[170:171], v[170:171], v[116:117]
	v_pk_add_f32 v[64:65], v[64:65], v[126:127]
	v_pk_add_f32 v[170:171], v[170:171], v[104:105]
	v_pk_add_f32 v[64:65], v[64:65], v[114:115]
	v_pk_add_f32 v[214:215], v[170:171], v[122:123]
	v_and_b32_e32 v171, 0xffff0000, v103
	v_and_b32_e32 v170, 0xffff0000, v102
	v_pk_add_f32 v[64:65], v[64:65], v[110:111]
	s_waitcnt vmcnt(0)
	v_lshlrev_b32_e32 v103, 16, v93
	v_pk_add_f32 v[66:67], v[64:65], v[170:171]
	v_fma_f32 v64, -v75, v82, 1.0
	v_fmac_f32_e32 v82, v64, v82
	v_div_scale_f32 v64, vcc, 1.0, v74, 1.0
	v_mul_f32_e32 v65, v64, v82
	v_fma_f32 v83, -v75, v65, v64
	v_fmac_f32_e32 v65, v83, v82
	v_fma_f32 v64, -v75, v65, v64
	v_div_fmas_f32 v64, v64, v82, v65
	v_div_fixup_f32 v74, v64, v74, 1.0
	v_pk_fma_f32 v[82:83], v[74:75], v[214:215], v[122:123] op_sel_hi:[0,1,1] neg_lo:[0,0,1] neg_hi:[0,0,1]
	v_mov_b32_e32 v64, v4
	v_mov_b32_e32 v65, v6
	v_pk_mul_f32 v[82:83], v[82:83], v[64:65]
	v_lshlrev_b32_e32 v102, 16, v92
	v_pk_mul_f32 v[82:83], v[82:83], v[102:103]
	v_pk_fma_f32 v[102:103], v[74:75], v[218:219], v[76:77] op_sel_hi:[0,1,1] neg_lo:[0,0,1] neg_hi:[0,0,1]
	v_mov_b32_e32 v6, v5
	v_pk_mul_f32 v[4:5], v[102:103], v[6:7]
	v_and_b32_e32 v93, 0xffff0000, v93
	v_and_b32_e32 v92, 0xffff0000, v92
	v_pk_mul_f32 v[92:93], v[4:5], v[92:93]
	v_pk_fma_f32 v[102:103], v[74:75], v[222:223], v[68:69] op_sel_hi:[0,1,1] neg_lo:[0,0,1] neg_hi:[0,0,1]
	v_mov_b32_e32 v5, v2
	v_pk_fma_f32 v[74:75], v[74:75], v[66:67], v[170:171] op_sel_hi:[0,1,1] neg_lo:[0,0,1] neg_hi:[0,0,1]
	v_mov_b32_e32 v2, v1
	v_mov_b32_e32 v4, v0
	v_pk_mul_f32 v[0:1], v[74:75], v[2:3]
	v_and_b32_e32 v75, 0xffff0000, v95
	v_and_b32_e32 v74, 0xffff0000, v94
	v_pk_mul_f32 v[102:103], v[102:103], v[4:5]
	v_lshlrev_b32_e32 v229, 16, v95
	v_lshlrev_b32_e32 v228, 16, v94
	v_pk_mul_f32 v[0:1], v[0:1], v[74:75]
	v_pk_mul_f32 v[102:103], v[102:103], v[228:229]
	v_bfe_u32 v94, v93, 16, 1
	v_bfe_u32 v95, v92, 16, 1
	s_movk_i32 s1, 0x7fff
	v_add3_u32 v92, v92, v95, s1
	v_add3_u32 v93, v93, v94, s1
	v_bfe_u32 v74, v82, 16, 1
	v_bfe_u32 v75, v83, 16, 1
	v_add3_u32 v75, v83, v75, s1
	v_add3_u32 v74, v82, v74, s1
	s_mov_b32 s0, 0xffff0000
	v_lshrrev_b32_e32 v74, 16, v74
	v_lshrrev_b32_e32 v75, 16, v75
	v_cvt_pk_bf16_f32 v95, v103, v1
	v_cvt_pk_bf16_f32 v94, v102, v0
	v_and_or_b32 v93, v93, s0, v75
	v_and_or_b32 v92, v92, s0, v74
	v_lshl_add_u64 v[0:1], v[96:97], 0, v[196:197]
	s_cmp_lt_i32 s14, 1
	v_readlane_b32 s21, v250, 1
	v_readlane_b32 s24, v250, 4
	v_readlane_b32 s25, v250, 5
	v_readlane_b32 s26, v250, 6
	v_readlane_b32 s27, v250, 7
	global_store_dwordx4 v[0:1], v[92:95], off
	s_cbranch_scc1 .LBB0_2765
	s_cmp_gt_i32 s14, 1
	s_cbranch_scc0 .LBB0_2766
	s_cmp_eq_u32 s14, 2
	s_mov_b64 s[0:1], -1
	s_cbranch_scc0 .LBB0_2764
	s_mov_b64 s[0:1], 0

; __device__ __forceinline__ unsigned pk2(float lo, float hi) { return f2bf(lo) | (f2bf(hi) << 16); }
; __device__ __forceinline__ void fir_tile(const Prm& P, Ctx& C, int pm, int gi) {
;     ...
;     for (int j = 0; j < RUN; ++j) {
;         const int t = t0 + j;
;         const u32x4 g = *(const u32x4*)(GT + (size_t)(row0 + j) * 1024 + c0);
;         acc8(s, x[15 + j], 1.f);
;         const float inv = 1.f / (float)(t + 1 < w ? t + 1 : w);
;         const u32x4 xc = x[15 + j];
;         u32x4 o;
;         o.x = pk2((s[0] * inv - bflo(xc.x)) * sc0[0] * bflo(g.x), (s[1] * inv - bfhi(xc.x)) * sc0[1] * bfhi(g.x));
;         o.y = pk2((s[2] * inv - bflo(xc.y)) * sc0[2] * bflo(g.y), (s[3] * inv - bfhi(xc.y)) * sc0[3] * bfhi(g.y));
;         o.z = pk2((s[4] * inv - bflo(xc.z)) * sc1[0] * bflo(g.z), (s[5] * inv - bfhi(xc.z)) * sc1[1] * bfhi(g.z));
;         o.w = pk2((s[6] * inv - bflo(xc.w)) * sc1[2] * bflo(g.w), (s[7] * inv - bfhi(xc.w)) * sc1[3] * bfhi(g.w));
;         *(u32x4*)(MX + (size_t)(row0 + j) * 1024 + c0) = o;
;         if (w == 2) acc8(s, x[15 + j - 1], -1.f); else if (w == 4) acc8(s, x[15 + j - 3], -1.f); else if (w == 8) acc8(s, x[15 + j - 7], -1.f); else acc8(s, x[j], -1.f);
.LBB0_2773:
	v_or_b32_e32 v78, 1, v132
	v_ashrrev_i32_e32 v79, 31, v78
	v_lshlrev_b64 v[94:95], 11, v[78:79]
	v_lshl_add_u64 v[78:79], v[98:99], 0, v[94:95]
	global_load_dwordx4 v[228:231], v[78:79], off
	v_pk_add_f32 v[196:197], v[222:223], v[82:83] neg_lo:[0,1] neg_hi:[0,1]
	v_or_b32_e32 v82, 2, v226
	v_min_i32_e32 v82, s16, v82
	v_cvt_f32_i32_e32 v133, v82
	v_pk_add_f32 v[102:103], v[218:219], v[74:75] neg_lo:[0,1] neg_hi:[0,1]
	v_and_b32_e32 v75, 0xffff0000, v89
	v_and_b32_e32 v74, 0xffff0000, v88
	v_pk_add_f32 v[82:83], v[102:103], v[74:75]
	v_div_scale_f32 v102, s[0:1], v133, v133, 1.0
	v_rcp_f32_e32 v103, v102
	v_lshlrev_b32_e32 v79, 16, v91
	v_lshlrev_b32_e32 v78, 16, v90
	v_pk_add_f32 v[212:213], v[66:67], v[92:93] neg_lo:[0,1] neg_hi:[0,1]
	v_lshlrev_b32_e32 v67, 16, v89
	v_lshlrev_b32_e32 v66, 16, v88
	v_pk_add_f32 v[88:89], v[196:197], v[78:79]
	v_fma_f32 v197, -v102, v103, 1.0
	v_div_scale_f32 v196, vcc, 1.0, v133, 1.0
	v_fmac_f32_e32 v103, v197, v103
	v_and_b32_e32 v93, 0xffff0000, v91
	v_and_b32_e32 v92, 0xffff0000, v90
	v_mul_f32_e32 v197, v196, v103
	v_pk_add_f32 v[90:91], v[212:213], v[92:93]
	v_fma_f32 v212, -v102, v197, v196
	v_fmac_f32_e32 v197, v212, v103
	v_fma_f32 v102, -v102, v197, v196
	v_pk_add_f32 v[0:1], v[214:215], v[0:1] neg_lo:[0,1] neg_hi:[0,1]
	v_div_fmas_f32 v102, v102, v103, v197
	v_pk_add_f32 v[0:1], v[0:1], v[66:67]
	v_div_fixup_f32 v102, v102, v133, 1.0
	v_pk_fma_f32 v[196:197], v[102:103], v[0:1], v[66:67] op_sel_hi:[0,1,1] neg_lo:[0,0,1] neg_hi:[0,0,1]
	v_pk_fma_f32 v[212:213], v[102:103], v[82:83], v[74:75] op_sel_hi:[0,1,1] neg_lo:[0,0,1] neg_hi:[0,0,1]
	v_pk_fma_f32 v[214:215], v[102:103], v[88:89], v[78:79] op_sel_hi:[0,1,1] neg_lo:[0,0,1] neg_hi:[0,0,1]
	v_pk_fma_f32 v[102:103], v[102:103], v[90:91], v[92:93] op_sel_hi:[0,1,1] neg_lo:[0,0,1] neg_hi:[0,0,1]
	v_pk_mul_f32 v[196:197], v[64:65], v[196:197]
	v_pk_mul_f32 v[214:215], v[4:5], v[214:215]
	v_pk_mul_f32 v[102:103], v[2:3], v[102:103]
	v_pk_mul_f32 v[212:213], v[6:7], v[212:213]
	s_movk_i32 s11, 0x7fff
	s_mov_b32 s10, 0xffff0000
	v_lshl_add_u64 v[94:95], v[96:97], 0, v[94:95]
	s_cmp_lt_i32 s14, 1
	s_mov_b64 s[0:1], 0
	s_waitcnt vmcnt(0)
	v_lshlrev_b32_e32 v217, 16, v229
	v_lshlrev_b32_e32 v216, 16, v228
	v_lshlrev_b32_e32 v221, 16, v231
	v_lshlrev_b32_e32 v220, 16, v230
	v_and_b32_e32 v223, 0xffff0000, v231
	v_and_b32_e32 v222, 0xffff0000, v230
	v_and_b32_e32 v219, 0xffff0000, v229
	v_and_b32_e32 v218, 0xffff0000, v228
	v_pk_mul_f32 v[196:197], v[196:197], v[216:217]
	v_pk_mul_f32 v[214:215], v[214:215], v[220:221]
	v_pk_mul_f32 v[102:103], v[102:103], v[222:223]
	v_pk_mul_f32 v[212:213], v[212:213], v[218:219]
	v_bfe_u32 v133, v103, 16, 1
	v_bfe_u32 v220, v197, 16, 1
	v_bfe_u32 v221, v214, 16, 1
	v_bfe_u32 v222, v215, 16, 1
	v_bfe_u32 v216, v102, 16, 1
	v_bfe_u32 v217, v213, 16, 1
	v_add3_u32 v103, v103, v133, s11
	v_add3_u32 v133, v215, v222, s11
	v_add3_u32 v214, v214, v221, s11
	v_add3_u32 v197, v197, v220, s11
	v_add3_u32 v213, v213, v217, s11
	v_add3_u32 v102, v102, v216, s11
	v_lshrrev_b32_e32 v197, 16, v197
	v_lshrrev_b32_e32 v214, 16, v214
	v_lshrrev_b32_e32 v133, 16, v133
	v_and_or_b32 v215, v103, s10, v133
	v_and_or_b32 v214, v102, s10, v214
	v_and_or_b32 v213, v213, s10, v197
	v_cvt_pk_bf16_f32 v212, v196, v212
	global_store_dwordx4 v[94:95], v[212:215], off
	s_cbranch_scc1 .LBB0_2776
	s_cmp_gt_i32 s14, 1
	s_cbranch_scc0 .LBB0_2777
	s_cmp_lg_u32 s14, 2
	s_mov_b64 s[12:13], 0
	s_cselect_b64 s[10:11], -1, 0
	s_branch .LBB0_2778

; __device__ __forceinline__ unsigned pk2(float lo, float hi) { return f2bf(lo) | (f2bf(hi) << 16); }
; __device__ __forceinline__ void fir_tile(const Prm& P, Ctx& C, int pm, int gi) {
;     ...
;     for (int j = 0; j < RUN; ++j) {
;         const int t = t0 + j;
;         const u32x4 g = *(const u32x4*)(GT + (size_t)(row0 + j) * 1024 + c0);
;         acc8(s, x[15 + j], 1.f);
;         const float inv = 1.f / (float)(t + 1 < w ? t + 1 : w);
;         const u32x4 xc = x[15 + j];
;         u32x4 o;
;         o.x = pk2((s[0] * inv - bflo(xc.x)) * sc0[0] * bflo(g.x), (s[1] * inv - bfhi(xc.x)) * sc0[1] * bfhi(g.x));
;         o.y = pk2((s[2] * inv - bflo(xc.y)) * sc0[2] * bflo(g.y), (s[3] * inv - bfhi(xc.y)) * sc0[3] * bfhi(g.y));
;         o.z = pk2((s[4] * inv - bflo(xc.z)) * sc1[0] * bflo(g.z), (s[5] * inv - bfhi(xc.z)) * sc1[1] * bfhi(g.z));
;         o.w = pk2((s[6] * inv - bflo(xc.w)) * sc1[2] * bflo(g.w), (s[7] * inv - bfhi(xc.w)) * sc1[3] * bfhi(g.w));
;         *(u32x4*)(MX + (size_t)(row0 + j) * 1024 + c0) = o;
;         if (w == 2) acc8(s, x[15 + j - 1], -1.f); else if (w == 4) acc8(s, x[15 + j - 3], -1.f); else if (w == 8) acc8(s, x[15 + j - 7], -1.f); else acc8(s, x[j], -1.f);
.LBB0_2786:
	v_or_b32_e32 v70, 2, v132
	v_ashrrev_i32_e32 v71, 31, v70
	v_lshlrev_b64 v[210:211], 11, v[70:71]
	v_lshl_add_u64 v[70:71], v[98:99], 0, v[210:211]
	global_load_dwordx4 v[206:209], v[70:71], off
	v_pk_add_f32 v[214:215], v[0:1], v[94:95] neg_lo:[0,1] neg_hi:[0,1]
	v_pk_add_f32 v[102:103], v[82:83], v[102:103] neg_lo:[0,1] neg_hi:[0,1]
	v_lshlrev_b32_e32 v82, 16, v62
	v_and_b32_e32 v94, 0xffff0000, v62
	v_or_b32_e32 v62, 3, v226
	v_min_i32_e32 v62, s16, v62
	v_cvt_f32_i32_e32 v133, v62
	v_and_b32_e32 v71, 0xffff0000, v61
	v_and_b32_e32 v70, 0xffff0000, v60
	v_lshlrev_b32_e32 v83, 16, v63
	v_and_b32_e32 v95, 0xffff0000, v63
	v_pk_add_f32 v[62:63], v[102:103], v[70:71]
	v_div_scale_f32 v102, s[0:1], v133, v133, 1.0
	v_rcp_f32_e32 v103, v102
	v_pk_add_f32 v[88:89], v[88:89], v[196:197] neg_lo:[0,1] neg_hi:[0,1]
	v_div_scale_f32 v196, vcc, 1.0, v133, 1.0
	v_fma_f32 v197, -v102, v103, 1.0
	v_fmac_f32_e32 v103, v197, v103
	v_mul_f32_e32 v197, v196, v103
	v_pk_add_f32 v[90:91], v[90:91], v[212:213] neg_lo:[0,1] neg_hi:[0,1]
	v_fma_f32 v212, -v102, v197, v196
	v_fmac_f32_e32 v197, v212, v103
	v_fma_f32 v102, -v102, v197, v196
	v_lshlrev_b32_e32 v1, 16, v61
	v_lshlrev_b32_e32 v0, 16, v60
	v_div_fmas_f32 v102, v102, v103, v197
	v_pk_add_f32 v[60:61], v[214:215], v[0:1]
	v_pk_add_f32 v[88:89], v[88:89], v[82:83]
	v_pk_add_f32 v[90:91], v[90:91], v[94:95]
	v_div_fixup_f32 v102, v102, v133, 1.0
	v_pk_fma_f32 v[196:197], v[102:103], v[60:61], v[0:1] op_sel_hi:[0,1,1] neg_lo:[0,0,1] neg_hi:[0,0,1]
	v_pk_fma_f32 v[212:213], v[102:103], v[62:63], v[70:71] op_sel_hi:[0,1,1] neg_lo:[0,0,1] neg_hi:[0,0,1]
	v_pk_fma_f32 v[214:215], v[102:103], v[88:89], v[82:83] op_sel_hi:[0,1,1] neg_lo:[0,0,1] neg_hi:[0,0,1]
	v_pk_fma_f32 v[102:103], v[102:103], v[90:91], v[94:95] op_sel_hi:[0,1,1] neg_lo:[0,0,1] neg_hi:[0,0,1]
	v_pk_mul_f32 v[196:197], v[64:65], v[196:197]
	v_pk_mul_f32 v[212:213], v[6:7], v[212:213]
	v_pk_mul_f32 v[214:215], v[4:5], v[214:215]
	v_pk_mul_f32 v[102:103], v[2:3], v[102:103]
	s_movk_i32 s11, 0x7fff
	s_mov_b32 s10, 0xffff0000
	s_cmp_lt_i32 s14, 1
	s_mov_b64 s[0:1], 0
	s_waitcnt vmcnt(0)
	v_lshlrev_b32_e32 v217, 16, v207
	v_lshlrev_b32_e32 v216, 16, v206
	v_and_b32_e32 v207, 0xffff0000, v207
	v_and_b32_e32 v206, 0xffff0000, v206
	v_lshlrev_b32_e32 v219, 16, v209
	v_lshlrev_b32_e32 v218, 16, v208
	v_and_b32_e32 v209, 0xffff0000, v209
	v_and_b32_e32 v208, 0xffff0000, v208
	v_pk_mul_f32 v[196:197], v[196:197], v[216:217]
	v_pk_mul_f32 v[206:207], v[212:213], v[206:207]
	v_pk_mul_f32 v[212:213], v[214:215], v[218:219]
	v_pk_mul_f32 v[102:103], v[102:103], v[208:209]
	v_bfe_u32 v133, v103, 16, 1
	v_bfe_u32 v208, v102, 16, 1
	v_bfe_u32 v216, v197, 16, 1
	v_bfe_u32 v217, v212, 16, 1
	v_bfe_u32 v218, v213, 16, 1
	v_bfe_u32 v209, v207, 16, 1
	v_add3_u32 v102, v102, v208, s11
	v_add3_u32 v103, v103, v133, s11
	v_add3_u32 v133, v213, v218, s11
	v_add3_u32 v208, v212, v217, s11
	v_add3_u32 v197, v197, v216, s11
	v_add3_u32 v207, v207, v209, s11
	v_lshrrev_b32_e32 v197, 16, v197
	v_lshrrev_b32_e32 v208, 16, v208
	v_lshrrev_b32_e32 v133, 16, v133
	v_and_or_b32 v209, v103, s10, v133
	v_and_or_b32 v208, v102, s10, v208
	v_and_or_b32 v207, v207, s10, v197
	v_cvt_pk_bf16_f32 v206, v196, v206
	v_lshl_add_u64 v[102:103], v[96:97], 0, v[210:211]
	global_store_dwordx4 v[102:103], v[206:209], off
	s_cbranch_scc1 .LBB0_2789
	s_cmp_gt_i32 s14, 1
	s_cbranch_scc0 .LBB0_2790
	s_cmp_lg_u32 s14, 2
	s_mov_b64 s[12:13], 0
	s_cselect_b64 s[10:11], -1, 0
	s_branch .LBB0_2791

; __device__ __forceinline__ unsigned pk2(float lo, float hi) { return f2bf(lo) | (f2bf(hi) << 16); }
; __device__ __forceinline__ void fir_tile(const Prm& P, Ctx& C, int pm, int gi) {
;     ...
;     for (int j = 0; j < RUN; ++j) {
;         const int t = t0 + j;
;         const u32x4 g = *(const u32x4*)(GT + (size_t)(row0 + j) * 1024 + c0);
;         acc8(s, x[15 + j], 1.f);
;         const float inv = 1.f / (float)(t + 1 < w ? t + 1 : w);
;         const u32x4 xc = x[15 + j];
;         u32x4 o;
;         o.x = pk2((s[0] * inv - bflo(xc.x)) * sc0[0] * bflo(g.x), (s[1] * inv - bfhi(xc.x)) * sc0[1] * bfhi(g.x));
;         o.y = pk2((s[2] * inv - bflo(xc.y)) * sc0[2] * bflo(g.y), (s[3] * inv - bfhi(xc.y)) * sc0[3] * bfhi(g.y));
;         o.z = pk2((s[4] * inv - bflo(xc.z)) * sc1[0] * bflo(g.z), (s[5] * inv - bfhi(xc.z)) * sc1[1] * bfhi(g.z));
;         o.w = pk2((s[6] * inv - bflo(xc.w)) * sc1[2] * bflo(g.w), (s[7] * inv - bfhi(xc.w)) * sc1[3] * bfhi(g.w));
;         *(u32x4*)(MX + (size_t)(row0 + j) * 1024 + c0) = o;
;         if (w == 2) acc8(s, x[15 + j - 1], -1.f); else if (w == 4) acc8(s, x[15 + j - 3], -1.f); else if (w == 8) acc8(s, x[15 + j - 7], -1.f); else acc8(s, x[j], -1.f);
.LBB0_2799:
	v_or_b32_e32 v84, 3, v132
	v_ashrrev_i32_e32 v85, 31, v84
	v_lshlrev_b64 v[130:131], 11, v[84:85]
	v_lshl_add_u64 v[84:85], v[98:99], 0, v[130:131]
	global_load_dwordx4 v[210:213], v[84:85], off
	v_lshlrev_b32_e32 v84, 16, v58
	v_and_b32_e32 v100, 0xffff0000, v58
	v_or_b32_e32 v58, 4, v226
	v_min_i32_e32 v58, s16, v58
	v_cvt_f32_i32_e32 v133, v58
	v_pk_add_f32 v[86:87], v[60:61], v[102:103] neg_lo:[0,1] neg_hi:[0,1]
	v_pk_add_f32 v[102:103], v[62:63], v[196:197] neg_lo:[0,1] neg_hi:[0,1]
	v_and_b32_e32 v63, 0xffff0000, v57
	v_and_b32_e32 v62, 0xffff0000, v56
	v_lshlrev_b32_e32 v85, 16, v59
	v_and_b32_e32 v101, 0xffff0000, v59
	v_pk_add_f32 v[58:59], v[102:103], v[62:63]
	v_div_scale_f32 v102, s[0:1], v133, v133, 1.0
	v_rcp_f32_e32 v103, v102
	v_pk_add_f32 v[88:89], v[88:89], v[206:207] neg_lo:[0,1] neg_hi:[0,1]
	v_pk_add_f32 v[90:91], v[90:91], v[208:209] neg_lo:[0,1] neg_hi:[0,1]
	v_lshlrev_b32_e32 v61, 16, v57
	v_lshlrev_b32_e32 v60, 16, v56
	v_pk_add_f32 v[56:57], v[86:87], v[60:61]
	v_pk_add_f32 v[86:87], v[88:89], v[84:85]
	v_pk_add_f32 v[88:89], v[90:91], v[100:101]
	v_fma_f32 v91, -v102, v103, 1.0
	v_div_scale_f32 v90, vcc, 1.0, v133, 1.0
	v_fmac_f32_e32 v103, v91, v103
	v_mul_f32_e32 v91, v90, v103
	v_fma_f32 v196, -v102, v91, v90
	v_fmac_f32_e32 v91, v196, v103
	v_fma_f32 v90, -v102, v91, v90
	v_div_fmas_f32 v90, v90, v103, v91
	v_div_fixup_f32 v90, v90, v133, 1.0
	v_pk_fma_f32 v[102:103], v[90:91], v[56:57], v[60:61] op_sel_hi:[0,1,1] neg_lo:[0,0,1] neg_hi:[0,0,1]
	v_pk_fma_f32 v[196:197], v[90:91], v[58:59], v[62:63] op_sel_hi:[0,1,1] neg_lo:[0,0,1] neg_hi:[0,0,1]
	v_pk_fma_f32 v[206:207], v[90:91], v[86:87], v[84:85] op_sel_hi:[0,1,1] neg_lo:[0,0,1] neg_hi:[0,0,1]
	v_pk_fma_f32 v[90:91], v[90:91], v[88:89], v[100:101] op_sel_hi:[0,1,1] neg_lo:[0,0,1] neg_hi:[0,0,1]
	v_pk_mul_f32 v[102:103], v[64:65], v[102:103]
	v_pk_mul_f32 v[206:207], v[4:5], v[206:207]
	v_pk_mul_f32 v[90:91], v[2:3], v[90:91]
	v_pk_mul_f32 v[196:197], v[6:7], v[196:197]
	s_movk_i32 s11, 0x7fff
	s_mov_b32 s10, 0xffff0000
	s_cmp_lt_i32 s14, 1
	s_mov_b64 s[0:1], 0
	s_waitcnt vmcnt(0)
	v_lshlrev_b32_e32 v209, 16, v211
	v_lshlrev_b32_e32 v208, 16, v210
	v_lshlrev_b32_e32 v215, 16, v213
	v_lshlrev_b32_e32 v214, 16, v212
	v_and_b32_e32 v213, 0xffff0000, v213
	v_and_b32_e32 v212, 0xffff0000, v212
	v_and_b32_e32 v211, 0xffff0000, v211
	v_and_b32_e32 v210, 0xffff0000, v210
	v_pk_mul_f32 v[102:103], v[102:103], v[208:209]
	v_pk_mul_f32 v[206:207], v[206:207], v[214:215]
	v_pk_mul_f32 v[90:91], v[90:91], v[212:213]
	v_pk_mul_f32 v[196:197], v[196:197], v[210:211]
	v_bfe_u32 v133, v91, 16, 1
	v_bfe_u32 v212, v103, 16, 1
	v_bfe_u32 v213, v206, 16, 1
	v_bfe_u32 v214, v207, 16, 1
	v_bfe_u32 v208, v90, 16, 1
	v_bfe_u32 v209, v197, 16, 1
	v_add3_u32 v91, v91, v133, s11
	v_add3_u32 v133, v207, v214, s11
	v_add3_u32 v206, v206, v213, s11
	v_add3_u32 v103, v103, v212, s11
	v_add3_u32 v197, v197, v209, s11
	v_add3_u32 v90, v90, v208, s11
	v_lshrrev_b32_e32 v103, 16, v103
	v_lshrrev_b32_e32 v206, 16, v206
	v_lshrrev_b32_e32 v133, 16, v133
	v_and_or_b32 v209, v91, s10, v133
	v_and_or_b32 v208, v90, s10, v206
	v_and_or_b32 v207, v197, s10, v103
	v_cvt_pk_bf16_f32 v206, v102, v196
	v_lshl_add_u64 v[90:91], v[96:97], 0, v[130:131]
	global_store_dwordx4 v[90:91], v[206:209], off
	s_cbranch_scc1 .LBB0_2802
	s_cmp_gt_i32 s14, 1
	s_cbranch_scc0 .LBB0_2803
	s_cmp_lg_u32 s14, 2
	s_mov_b64 s[12:13], 0
	s_cselect_b64 s[10:11], -1, 0
	s_branch .LBB0_2804

; __device__ __forceinline__ unsigned pk2(float lo, float hi) { return f2bf(lo) | (f2bf(hi) << 16); }
; __device__ __forceinline__ void fir_tile(const Prm& P, Ctx& C, int pm, int gi) {
;     ...
;     for (int j = 0; j < RUN; ++j) {
;         const int t = t0 + j;
;         const u32x4 g = *(const u32x4*)(GT + (size_t)(row0 + j) * 1024 + c0);
;         acc8(s, x[15 + j], 1.f);
;         const float inv = 1.f / (float)(t + 1 < w ? t + 1 : w);
;         const u32x4 xc = x[15 + j];
;         u32x4 o;
;         o.x = pk2((s[0] * inv - bflo(xc.x)) * sc0[0] * bflo(g.x), (s[1] * inv - bfhi(xc.x)) * sc0[1] * bfhi(g.x));
;         o.y = pk2((s[2] * inv - bflo(xc.y)) * sc0[2] * bflo(g.y), (s[3] * inv - bfhi(xc.y)) * sc0[3] * bfhi(g.y));
;         o.z = pk2((s[4] * inv - bflo(xc.z)) * sc1[0] * bflo(g.z), (s[5] * inv - bfhi(xc.z)) * sc1[1] * bfhi(g.z));
;         o.w = pk2((s[6] * inv - bflo(xc.w)) * sc1[2] * bflo(g.w), (s[7] * inv - bfhi(xc.w)) * sc1[3] * bfhi(g.w));
;         *(u32x4*)(MX + (size_t)(row0 + j) * 1024 + c0) = o;
;         if (w == 2) acc8(s, x[15 + j - 1], -1.f); else if (w == 4) acc8(s, x[15 + j - 3], -1.f); else if (w == 8) acc8(s, x[15 + j - 7], -1.f); else acc8(s, x[j], -1.f);
.LBB0_2825:
	v_or_b32_e32 v186, 5, v132
	v_ashrrev_i32_e32 v187, 31, v186
	v_lshlrev_b64 v[192:193], 11, v[186:187]
	v_lshl_add_u64 v[186:187], v[98:99], 0, v[192:193]
	global_load_dwordx4 v[188:191], v[186:187], off
	v_pk_add_f32 v[186:187], v[52:53], v[130:131] neg_lo:[0,1] neg_hi:[0,1]
	v_pk_add_f32 v[198:199], v[88:89], v[198:199] neg_lo:[0,1] neg_hi:[0,1]
	v_lshlrev_b32_e32 v88, 16, v50
	v_and_b32_e32 v130, 0xffff0000, v50
	v_or_b32_e32 v50, 6, v226
	v_min_i32_e32 v50, s16, v50
	v_cvt_f32_i32_e32 v133, v50
	v_pk_add_f32 v[196:197], v[54:55], v[196:197] neg_lo:[0,1] neg_hi:[0,1]
	v_and_b32_e32 v55, 0xffff0000, v49
	v_and_b32_e32 v54, 0xffff0000, v48
	v_lshlrev_b32_e32 v89, 16, v51
	v_and_b32_e32 v131, 0xffff0000, v51
	v_pk_add_f32 v[50:51], v[196:197], v[54:55]
	v_div_scale_f32 v196, s[0:1], v133, v133, 1.0
	v_rcp_f32_e32 v197, v196
	v_pk_add_f32 v[200:201], v[90:91], v[200:201] neg_lo:[0,1] neg_hi:[0,1]
	v_pk_add_f32 v[90:91], v[198:199], v[88:89]
	v_div_scale_f32 v198, vcc, 1.0, v133, 1.0
	v_fma_f32 v199, -v196, v197, 1.0
	v_fmac_f32_e32 v197, v199, v197
	v_lshlrev_b32_e32 v53, 16, v49
	v_lshlrev_b32_e32 v52, 16, v48
	v_mul_f32_e32 v199, v198, v197
	v_pk_add_f32 v[48:49], v[186:187], v[52:53]
	v_pk_add_f32 v[186:187], v[200:201], v[130:131]
	v_fma_f32 v200, -v196, v199, v198
	v_fmac_f32_e32 v199, v200, v197
	v_fma_f32 v196, -v196, v199, v198
	v_div_fmas_f32 v196, v196, v197, v199
	v_div_fixup_f32 v196, v196, v133, 1.0
	v_pk_fma_f32 v[198:199], v[196:197], v[48:49], v[52:53] op_sel_hi:[0,1,1] neg_lo:[0,0,1] neg_hi:[0,0,1]
	v_pk_fma_f32 v[200:201], v[196:197], v[50:51], v[54:55] op_sel_hi:[0,1,1] neg_lo:[0,0,1] neg_hi:[0,0,1]
	v_pk_fma_f32 v[202:203], v[196:197], v[90:91], v[88:89] op_sel_hi:[0,1,1] neg_lo:[0,0,1] neg_hi:[0,0,1]
	v_pk_fma_f32 v[196:197], v[196:197], v[186:187], v[130:131] op_sel_hi:[0,1,1] neg_lo:[0,0,1] neg_hi:[0,0,1]
	v_pk_mul_f32 v[198:199], v[64:65], v[198:199]
	v_pk_mul_f32 v[200:201], v[6:7], v[200:201]
	v_pk_mul_f32 v[202:203], v[4:5], v[202:203]
	v_pk_mul_f32 v[196:197], v[2:3], v[196:197]
	s_movk_i32 s11, 0x7fff
	s_mov_b32 s10, 0xffff0000
	v_lshl_add_u64 v[192:193], v[96:97], 0, v[192:193]
	s_cmp_lt_i32 s14, 1
	s_mov_b64 s[0:1], 0
	s_waitcnt vmcnt(0)
	v_lshlrev_b32_e32 v205, 16, v189
	v_lshlrev_b32_e32 v204, 16, v188
	v_and_b32_e32 v189, 0xffff0000, v189
	v_and_b32_e32 v188, 0xffff0000, v188
	v_lshlrev_b32_e32 v207, 16, v191
	v_lshlrev_b32_e32 v206, 16, v190
	v_and_b32_e32 v191, 0xffff0000, v191
	v_and_b32_e32 v190, 0xffff0000, v190
	v_pk_mul_f32 v[198:199], v[198:199], v[204:205]
	v_pk_mul_f32 v[188:189], v[200:201], v[188:189]
	v_pk_mul_f32 v[200:201], v[202:203], v[206:207]
	v_pk_mul_f32 v[190:191], v[196:197], v[190:191]
	v_bfe_u32 v197, v189, 16, 1
	v_bfe_u32 v133, v191, 16, 1
	v_bfe_u32 v196, v190, 16, 1
	v_bfe_u32 v204, v199, 16, 1
	v_bfe_u32 v205, v200, 16, 1
	v_bfe_u32 v206, v201, 16, 1
	v_add3_u32 v189, v189, v197, s11
	v_add3_u32 v190, v190, v196, s11
	v_add3_u32 v133, v191, v133, s11
	v_add3_u32 v191, v201, v206, s11
	v_add3_u32 v196, v200, v205, s11
	v_add3_u32 v197, v199, v204, s11
	v_lshrrev_b32_e32 v197, 16, v197
	v_lshrrev_b32_e32 v196, 16, v196
	v_lshrrev_b32_e32 v191, 16, v191
	v_and_or_b32 v191, v133, s10, v191
	v_and_or_b32 v190, v190, s10, v196
	v_and_or_b32 v189, v189, s10, v197
	v_cvt_pk_bf16_f32 v188, v198, v188
	global_store_dwordx4 v[192:193], v[188:191], off
	s_cbranch_scc1 .LBB0_2828
	s_cmp_gt_i32 s14, 1
	s_cbranch_scc0 .LBB0_2829
	s_cmp_lg_u32 s14, 2
	s_mov_b64 s[12:13], 0
	s_cselect_b64 s[10:11], -1, 0
	s_branch .LBB0_2830

; __device__ __forceinline__ void fir_tile(const Prm& P, Ctx& C, int pm, int gi) {
;     ...
; #pragma unroll
;     for (int j = 0; j < RUN + 15; ++j) { const int k = j - 15; x[j] = (k >= 1 - w && t0 + k >= 0) ? *(const u32x4*)(zp + (ptrdiff_t)k * 1024) : (u32x4){0u, 0u, 0u, 0u}; }
;     const f32x4 sc0 = *(const f32x4*)(P.pool_scale + c0), sc1 = *(const f32x4*)(P.pool_scale + c0 + 4);
;     float s[8];
; #pragma unroll
;     for (int e = 0; e < 8; ++e) s[e] = 0.f;
; #pragma unroll
;     for (int j = 0; j < 15; ++j) acc8(s, x[j], 1.f);
; #pragma unroll
;     for (int j = 0; j < RUN; ++j) {
;         const int t = t0 + j;
;         const u32x4 g = *(const u32x4*)(GT + (size_t)(row0 + j) * 1024 + c0);
;         acc8(s, x[15 + j], 1.f);
;         const float inv = 1.f / (float)(t + 1 < w ? t + 1 : w);
.LBB0_3018:
	v_readlane_b32 s16, v250, 0
	v_readlane_b32 s18, v250, 2
	v_readlane_b32 s19, v250, 3
	s_waitcnt vmcnt(0)
	v_lshlrev_b32_e32 v199, 16, v93
	v_lshlrev_b32_e32 v198, 16, v92
	v_and_b32_e32 v201, 0xffff0000, v93
	v_and_b32_e32 v200, 0xffff0000, v92
	v_lshlrev_b64 v[92:93], 1, v[168:169]
	v_lshl_add_u64 v[4:5], v[168:169], 2, s[18:19]
	v_lshlrev_b32_e32 v190, 16, v98
	v_and_b32_e32 v192, 0xffff0000, v98
	v_lshlrev_b32_e32 v191, 16, v99
	v_and_b32_e32 v193, 0xffff0000, v99
	v_lshl_add_u64 v[98:99], s[4:5], 0, v[92:93]
	global_load_dwordx4 v[0:3], v[4:5], off offset:16
	s_nop 0
	global_load_dwordx4 v[4:7], v[4:5], off
	v_lshlrev_b32_e32 v186, 16, v96
	v_and_b32_e32 v188, 0xffff0000, v96
	v_lshlrev_b32_e32 v187, 16, v97
	v_and_b32_e32 v189, 0xffff0000, v97
	v_lshl_add_u64 v[96:97], s[6:7], 0, v[92:93]
	v_lshl_add_u64 v[92:93], v[98:99], 0, v[196:197]
	v_lshlrev_b32_e32 v203, 16, v95
	v_lshlrev_b32_e32 v202, 16, v94
	v_and_b32_e32 v205, 0xffff0000, v95
	v_and_b32_e32 v204, 0xffff0000, v94
	global_load_dwordx4 v[92:95], v[92:93], off
	v_and_b32_e32 v217, 0xffff0000, v69
	v_and_b32_e32 v216, 0xffff0000, v68
	v_lshlrev_b32_e32 v207, 16, v65
	v_lshlrev_b32_e32 v206, 16, v64
	v_and_b32_e32 v209, 0xffff0000, v65
	v_and_b32_e32 v208, 0xffff0000, v64
	v_pk_add_f32 v[64:65], v[216:217], 0 op_sel_hi:[1,0]
	v_lshlrev_b32_e32 v175, 16, v85
	v_lshlrev_b32_e32 v174, 16, v84
	v_and_b32_e32 v177, 0xffff0000, v85
	v_and_b32_e32 v176, 0xffff0000, v84
	v_and_b32_e32 v85, 0xffff0000, v73
	v_and_b32_e32 v84, 0xffff0000, v72
	v_pk_add_f32 v[64:65], v[64:65], v[208:209]
	v_and_b32_e32 v183, 0xffff0000, v77
	v_pk_add_f32 v[64:65], v[64:65], v[84:85]
	v_and_b32_e32 v182, 0xffff0000, v76
	v_pk_add_f32 v[64:65], v[64:65], v[200:201]
	v_lshlrev_b32_e32 v137, 16, v105
	v_pk_add_f32 v[64:65], v[64:65], v[188:189]
	v_lshlrev_b32_e32 v136, 16, v104
	v_pk_add_f32 v[64:65], v[64:65], v[182:183]
	v_and_b32_e32 v139, 0xffff0000, v105
	v_and_b32_e32 v138, 0xffff0000, v104
	v_lshlrev_b32_e32 v141, 16, v107
	v_lshlrev_b32_e32 v140, 16, v106
	v_and_b32_e32 v143, 0xffff0000, v107
	v_and_b32_e32 v142, 0xffff0000, v106
	v_lshlrev_b32_e32 v105, 16, v129
	v_lshlrev_b32_e32 v104, 16, v128
	v_and_b32_e32 v107, 0xffff0000, v129
	v_and_b32_e32 v106, 0xffff0000, v128
	v_lshlrev_b32_e32 v129, 16, v81
	v_lshlrev_b32_e32 v128, 16, v80
	v_and_b32_e32 v81, 0xffff0000, v81
	v_and_b32_e32 v80, 0xffff0000, v80
	v_pk_add_f32 v[64:65], v[64:65], v[176:177]
	v_and_b32_e32 v163, 0xffff0000, v117
	v_and_b32_e32 v162, 0xffff0000, v116
	v_pk_add_f32 v[64:65], v[64:65], v[80:81]
	v_and_b32_e32 v155, 0xffff0000, v109
	v_and_b32_e32 v154, 0xffff0000, v108
	v_pk_add_f32 v[64:65], v[64:65], v[162:163]
	v_and_b32_e32 v147, 0xffff0000, v113
	v_and_b32_e32 v146, 0xffff0000, v112
	v_pk_add_f32 v[64:65], v[64:65], v[154:155]
	v_lshlrev_b32_e32 v135, 16, v125
	v_pk_add_f32 v[64:65], v[64:65], v[146:147]
	v_lshlrev_b32_e32 v134, 16, v124
	v_and_b32_e32 v125, 0xffff0000, v125
	v_and_b32_e32 v124, 0xffff0000, v124
	v_pk_add_f32 v[64:65], v[64:65], v[138:139]
	v_lshlrev_b32_e32 v145, 16, v113
	v_lshlrev_b32_e32 v144, 16, v112
	v_and_b32_e32 v113, 0xffff0000, v121
	v_and_b32_e32 v112, 0xffff0000, v120
	v_pk_add_f32 v[64:65], v[64:65], v[124:125]
	v_lshlrev_b32_e32 v169, 16, v77
	v_pk_add_f32 v[64:65], v[64:65], v[112:113]
	v_lshlrev_b32_e32 v168, 16, v76
	v_and_b32_e32 v77, 0xffff0000, v101
	v_and_b32_e32 v76, 0xffff0000, v100
	v_pk_add_f32 v[64:65], v[64:65], v[106:107]
	v_lshlrev_b32_e32 v221, 16, v71
	v_lshlrev_b32_e32 v220, 16, v70
	v_pk_add_f32 v[218:219], v[64:65], v[76:77]
	v_lshlrev_b32_e32 v211, 16, v67
	v_lshlrev_b32_e32 v210, 16, v66
	v_pk_add_f32 v[64:65], v[220:221], 0 op_sel_hi:[1,0]
	v_lshlrev_b32_e32 v165, 16, v119
	v_lshlrev_b32_e32 v164, 16, v118
	v_and_b32_e32 v167, 0xffff0000, v119
	v_and_b32_e32 v166, 0xffff0000, v118
	v_lshlrev_b32_e32 v149, 16, v115
	v_lshlrev_b32_e32 v148, 16, v114
	v_lshlrev_b32_e32 v119, 16, v123
	v_lshlrev_b32_e32 v118, 16, v122
	v_and_b32_e32 v151, 0xffff0000, v115
	v_and_b32_e32 v150, 0xffff0000, v114
	v_and_b32_e32 v115, 0xffff0000, v123
	v_and_b32_e32 v114, 0xffff0000, v122
	v_lshlrev_b32_e32 v123, 16, v101
	v_lshlrev_b32_e32 v122, 16, v100
	v_lshlrev_b32_e32 v101, 16, v75
	v_lshlrev_b32_e32 v100, 16, v74
	v_pk_add_f32 v[64:65], v[64:65], v[210:211]
	v_lshlrev_b32_e32 v185, 16, v79
	v_pk_add_f32 v[64:65], v[64:65], v[100:101]
	v_lshlrev_b32_e32 v184, 16, v78
	v_pk_add_f32 v[64:65], v[64:65], v[202:203]
	v_lshlrev_b32_e32 v179, 16, v87
	v_pk_add_f32 v[64:65], v[64:65], v[190:191]
	v_lshlrev_b32_e32 v178, 16, v86
	v_pk_add_f32 v[64:65], v[64:65], v[184:185]
	v_lshlrev_b32_e32 v153, 16, v109
	v_lshlrev_b32_e32 v152, 16, v108
	v_lshlrev_b32_e32 v157, 16, v111
	v_lshlrev_b32_e32 v156, 16, v110
	v_and_b32_e32 v159, 0xffff0000, v111
	v_and_b32_e32 v158, 0xffff0000, v110
	v_lshlrev_b32_e32 v109, 16, v131
	v_lshlrev_b32_e32 v108, 16, v130
	v_and_b32_e32 v111, 0xffff0000, v131
	v_and_b32_e32 v110, 0xffff0000, v130
	v_lshlrev_b32_e32 v131, 16, v73
	v_lshlrev_b32_e32 v130, 16, v72
	v_lshlrev_b32_e32 v73, 16, v83
	v_lshlrev_b32_e32 v72, 16, v82
	v_pk_add_f32 v[64:65], v[64:65], v[178:179]
	v_lshlrev_b32_e32 v161, 16, v117
	v_pk_add_f32 v[64:65], v[64:65], v[72:73]
	v_lshlrev_b32_e32 v160, 16, v116
; __device__ __forceinline__ unsigned pk2(float lo, float hi) { return f2bf(lo) | (f2bf(hi) << 16); }
; __device__ __forceinline__ void fir_tile(const Prm& P, Ctx& C, int pm, int gi) {
;     ...
;     for (int j = 0; j < 15; ++j) acc8(s, x[j], 1.f);
; #pragma unroll
;     for (int j = 0; j < RUN; ++j) {
;         const int t = t0 + j;
;         const u32x4 g = *(const u32x4*)(GT + (size_t)(row0 + j) * 1024 + c0);
;         acc8(s, x[15 + j], 1.f);
;         const float inv = 1.f / (float)(t + 1 < w ? t + 1 : w);
;         const u32x4 xc = x[15 + j];
;         u32x4 o;
;         o.x = pk2((s[0] * inv - bflo(xc.x)) * sc0[0] * bflo(g.x), (s[1] * inv - bfhi(xc.x)) * sc0[1] * bfhi(g.x));
;         o.y = pk2((s[2] * inv - bflo(xc.y)) * sc0[2] * bflo(g.y), (s[3] * inv - bfhi(xc.y)) * sc0[3] * bfhi(g.y));
;         o.z = pk2((s[4] * inv - bflo(xc.z)) * sc1[0] * bflo(g.z), (s[5] * inv - bfhi(xc.z)) * sc1[1] * bfhi(g.z));
;         o.w = pk2((s[6] * inv - bflo(xc.w)) * sc1[2] * bflo(g.w), (s[7] * inv - bfhi(xc.w)) * sc1[3] * bfhi(g.w));
;         *(u32x4*)(MX + (size_t)(row0 + j) * 1024 + c0) = o;
	v_pk_add_f32 v[64:65], v[64:65], v[164:165]
	v_lshlrev_b32_e32 v117, 16, v121
	v_pk_add_f32 v[64:65], v[64:65], v[156:157]
	v_lshlrev_b32_e32 v116, 16, v120
	v_pk_add_f32 v[64:65], v[64:65], v[148:149]
	v_lshlrev_b32_e32 v121, 16, v127
	v_lshlrev_b32_e32 v120, 16, v126
	v_pk_add_f32 v[64:65], v[64:65], v[140:141]
	v_lshlrev_b32_e32 v213, 16, v69
	v_pk_add_f32 v[64:65], v[64:65], v[120:121]
	v_lshlrev_b32_e32 v212, 16, v68
	v_pk_add_f32 v[64:65], v[64:65], v[118:119]
	v_pk_add_f32 v[170:171], v[212:213], 0 op_sel_hi:[1,0]
	v_lshlrev_b32_e32 v69, 16, v103
	v_lshlrev_b32_e32 v68, 16, v102
	v_pk_add_f32 v[64:65], v[64:65], v[108:109]
	v_and_b32_e32 v195, 0xffff0000, v79
	v_and_b32_e32 v194, 0xffff0000, v78
	v_and_b32_e32 v79, 0xffff0000, v71
	v_and_b32_e32 v78, 0xffff0000, v70
	v_pk_add_f32 v[170:171], v[170:171], v[206:207]
	v_pk_add_f32 v[222:223], v[64:65], v[68:69]
	v_and_b32_e32 v71, 0xffff0000, v67
	v_and_b32_e32 v70, 0xffff0000, v66
	v_pk_add_f32 v[64:65], v[78:79], 0 op_sel_hi:[1,0]
	v_pk_add_f32 v[170:171], v[170:171], v[130:131]
	v_and_b32_e32 v181, 0xffff0000, v87
	v_and_b32_e32 v180, 0xffff0000, v86
	v_and_b32_e32 v87, 0xffff0000, v75
	v_and_b32_e32 v86, 0xffff0000, v74
	v_pk_add_f32 v[64:65], v[64:65], v[70:71]
	v_pk_add_f32 v[170:171], v[170:171], v[198:199]
	v_pk_add_f32 v[64:65], v[64:65], v[86:87]
	v_pk_add_f32 v[170:171], v[170:171], v[186:187]
	v_pk_add_f32 v[64:65], v[64:65], v[204:205]
	v_or_b32_e32 v133, 1, v224
	v_pk_add_f32 v[170:171], v[170:171], v[168:169]
	v_pk_add_f32 v[64:65], v[64:65], v[192:193]
	v_pk_add_f32 v[170:171], v[170:171], v[174:175]
	v_pk_add_f32 v[64:65], v[64:65], v[194:195]
	v_min_i32_e32 v66, s10, v133
	v_pk_add_f32 v[170:171], v[170:171], v[128:129]
	v_and_b32_e32 v173, 0xffff0000, v83
	v_and_b32_e32 v172, 0xffff0000, v82
	v_pk_add_f32 v[64:65], v[64:65], v[180:181]
	v_cvt_f32_i32_e32 v74, v66
	v_pk_add_f32 v[170:171], v[170:171], v[160:161]
	v_pk_add_f32 v[64:65], v[64:65], v[172:173]
	v_pk_add_f32 v[170:171], v[170:171], v[152:153]
	v_pk_add_f32 v[64:65], v[64:65], v[166:167]
	v_pk_add_f32 v[170:171], v[170:171], v[144:145]
	v_pk_add_f32 v[64:65], v[64:65], v[158:159]
	v_pk_add_f32 v[170:171], v[170:171], v[136:137]
	v_pk_add_f32 v[64:65], v[64:65], v[150:151]
	v_div_scale_f32 v75, s[4:5], v74, v74, 1.0
	v_and_b32_e32 v127, 0xffff0000, v127
	v_and_b32_e32 v126, 0xffff0000, v126
	v_pk_add_f32 v[170:171], v[170:171], v[134:135]
	v_pk_add_f32 v[64:65], v[64:65], v[142:143]
	v_rcp_f32_e32 v82, v75
	v_pk_add_f32 v[170:171], v[170:171], v[116:117]
	v_pk_add_f32 v[64:65], v[64:65], v[126:127]
	v_pk_add_f32 v[170:171], v[170:171], v[104:105]
	v_pk_add_f32 v[64:65], v[64:65], v[114:115]
	v_pk_add_f32 v[214:215], v[170:171], v[122:123]
	v_and_b32_e32 v171, 0xffff0000, v103
	v_and_b32_e32 v170, 0xffff0000, v102
	v_pk_add_f32 v[64:65], v[64:65], v[110:111]
	s_waitcnt vmcnt(0)
	v_lshlrev_b32_e32 v103, 16, v93
	v_pk_add_f32 v[66:67], v[64:65], v[170:171]
	v_fma_f32 v64, -v75, v82, 1.0
	v_fmac_f32_e32 v82, v64, v82
	v_div_scale_f32 v64, vcc, 1.0, v74, 1.0
	v_mul_f32_e32 v65, v64, v82
	v_fma_f32 v83, -v75, v65, v64
	v_fmac_f32_e32 v65, v83, v82
	v_fma_f32 v64, -v75, v65, v64
	v_div_fmas_f32 v64, v64, v82, v65
	v_div_fixup_f32 v74, v64, v74, 1.0
	v_pk_fma_f32 v[82:83], v[74:75], v[214:215], v[122:123] op_sel_hi:[0,1,1] neg_lo:[0,0,1] neg_hi:[0,0,1]
	v_mov_b32_e32 v64, v4
	v_mov_b32_e32 v65, v6
	v_pk_mul_f32 v[82:83], v[82:83], v[64:65]
	v_lshlrev_b32_e32 v102, 16, v92
	v_pk_mul_f32 v[82:83], v[82:83], v[102:103]
	v_pk_fma_f32 v[102:103], v[74:75], v[218:219], v[76:77] op_sel_hi:[0,1,1] neg_lo:[0,0,1] neg_hi:[0,0,1]
	v_mov_b32_e32 v6, v5
	v_pk_mul_f32 v[4:5], v[102:103], v[6:7]
	v_and_b32_e32 v93, 0xffff0000, v93
	v_and_b32_e32 v92, 0xffff0000, v92
	v_pk_mul_f32 v[92:93], v[4:5], v[92:93]
	v_pk_fma_f32 v[102:103], v[74:75], v[222:223], v[68:69] op_sel_hi:[0,1,1] neg_lo:[0,0,1] neg_hi:[0,0,1]
	v_mov_b32_e32 v5, v2
	v_pk_fma_f32 v[74:75], v[74:75], v[66:67], v[170:171] op_sel_hi:[0,1,1] neg_lo:[0,0,1] neg_hi:[0,0,1]
	v_mov_b32_e32 v2, v1
	v_mov_b32_e32 v4, v0
	v_pk_mul_f32 v[0:1], v[74:75], v[2:3]
	v_and_b32_e32 v75, 0xffff0000, v95
	v_and_b32_e32 v74, 0xffff0000, v94
	v_pk_mul_f32 v[102:103], v[102:103], v[4:5]
	v_lshlrev_b32_e32 v227, 16, v95
	v_lshlrev_b32_e32 v226, 16, v94
	v_pk_mul_f32 v[0:1], v[0:1], v[74:75]
	v_pk_mul_f32 v[102:103], v[102:103], v[226:227]
	v_bfe_u32 v94, v93, 16, 1
	v_bfe_u32 v95, v92, 16, 1
	s_movk_i32 s1, 0x7fff
	v_add3_u32 v92, v92, v95, s1
	v_add3_u32 v93, v93, v94, s1
	v_bfe_u32 v74, v82, 16, 1
	v_bfe_u32 v75, v83, 16, 1
	v_add3_u32 v75, v83, v75, s1
	v_add3_u32 v74, v82, v74, s1
	s_mov_b32 s0, 0xffff0000
	v_lshrrev_b32_e32 v74, 16, v74
	v_lshrrev_b32_e32 v75, 16, v75
	v_cvt_pk_bf16_f32 v95, v103, v1
	v_cvt_pk_bf16_f32 v94, v102, v0
	v_and_or_b32 v93, v93, s0, v75
	v_and_or_b32 v92, v92, s0, v74
	v_lshl_add_u64 v[0:1], v[96:97], 0, v[196:197]
	s_cmp_lt_i32 s14, 1
	v_readlane_b32 s17, v250, 1
	v_readlane_b32 s20, v250, 4
	v_readlane_b32 s21, v250, 5
	v_readlane_b32 s22, v250, 6
	v_readlane_b32 s23, v250, 7
	global_store_dwordx4 v[0:1], v[92:95], off
	s_cbranch_scc1 .LBB0_3023
	s_cmp_gt_i32 s14, 1
	s_cbranch_scc0 .LBB0_3024
	s_cmp_eq_u32 s14, 2
	s_mov_b64 s[0:1], -1
	s_cbranch_scc0 .LBB0_3022
	s_mov_b64 s[0:1], 0

; __device__ __forceinline__ unsigned pk2(float lo, float hi) { return f2bf(lo) | (f2bf(hi) << 16); }
; __device__ __forceinline__ void fir_tile(const Prm& P, Ctx& C, int pm, int gi) {
;     ...
;     for (int j = 0; j < RUN; ++j) {
;         const int t = t0 + j;
;         const u32x4 g = *(const u32x4*)(GT + (size_t)(row0 + j) * 1024 + c0);
;         acc8(s, x[15 + j], 1.f);
;         const float inv = 1.f / (float)(t + 1 < w ? t + 1 : w);
;         const u32x4 xc = x[15 + j];
;         u32x4 o;
;         o.x = pk2((s[0] * inv - bflo(xc.x)) * sc0[0] * bflo(g.x), (s[1] * inv - bfhi(xc.x)) * sc0[1] * bfhi(g.x));
;         o.y = pk2((s[2] * inv - bflo(xc.y)) * sc0[2] * bflo(g.y), (s[3] * inv - bfhi(xc.y)) * sc0[3] * bfhi(g.y));
;         o.z = pk2((s[4] * inv - bflo(xc.z)) * sc1[0] * bflo(g.z), (s[5] * inv - bfhi(xc.z)) * sc1[1] * bfhi(g.z));
;         o.w = pk2((s[6] * inv - bflo(xc.w)) * sc1[2] * bflo(g.w), (s[7] * inv - bfhi(xc.w)) * sc1[3] * bfhi(g.w));
;         *(u32x4*)(MX + (size_t)(row0 + j) * 1024 + c0) = o;
;         if (w == 2) acc8(s, x[15 + j - 1], -1.f); else if (w == 4) acc8(s, x[15 + j - 3], -1.f); else if (w == 8) acc8(s, x[15 + j - 7], -1.f); else acc8(s, x[j], -1.f);
.LBB0_3031:
	v_or_b32_e32 v78, 1, v132
	v_ashrrev_i32_e32 v79, 31, v78
	v_lshlrev_b64 v[94:95], 11, v[78:79]
	v_lshl_add_u64 v[78:79], v[98:99], 0, v[94:95]
	global_load_dwordx4 v[226:229], v[78:79], off
	v_pk_add_f32 v[196:197], v[222:223], v[82:83] neg_lo:[0,1] neg_hi:[0,1]
	v_or_b32_e32 v82, 2, v224
	v_min_i32_e32 v82, s10, v82
	v_cvt_f32_i32_e32 v133, v82
	v_pk_add_f32 v[102:103], v[218:219], v[74:75] neg_lo:[0,1] neg_hi:[0,1]
	v_and_b32_e32 v75, 0xffff0000, v89
	v_and_b32_e32 v74, 0xffff0000, v88
	v_pk_add_f32 v[82:83], v[102:103], v[74:75]
	v_div_scale_f32 v102, s[0:1], v133, v133, 1.0
	v_rcp_f32_e32 v103, v102
	v_lshlrev_b32_e32 v79, 16, v91
	v_lshlrev_b32_e32 v78, 16, v90
	v_pk_add_f32 v[212:213], v[66:67], v[92:93] neg_lo:[0,1] neg_hi:[0,1]
	v_lshlrev_b32_e32 v67, 16, v89
	v_lshlrev_b32_e32 v66, 16, v88
	v_pk_add_f32 v[88:89], v[196:197], v[78:79]
	v_fma_f32 v197, -v102, v103, 1.0
	v_div_scale_f32 v196, vcc, 1.0, v133, 1.0
	v_fmac_f32_e32 v103, v197, v103
	v_and_b32_e32 v93, 0xffff0000, v91
	v_and_b32_e32 v92, 0xffff0000, v90
	v_mul_f32_e32 v197, v196, v103
	v_pk_add_f32 v[90:91], v[212:213], v[92:93]
	v_fma_f32 v212, -v102, v197, v196
	v_fmac_f32_e32 v197, v212, v103
	v_fma_f32 v102, -v102, v197, v196
	v_pk_add_f32 v[0:1], v[214:215], v[0:1] neg_lo:[0,1] neg_hi:[0,1]
	v_div_fmas_f32 v102, v102, v103, v197
	v_pk_add_f32 v[0:1], v[0:1], v[66:67]
	v_div_fixup_f32 v102, v102, v133, 1.0
	v_pk_fma_f32 v[196:197], v[102:103], v[0:1], v[66:67] op_sel_hi:[0,1,1] neg_lo:[0,0,1] neg_hi:[0,0,1]
	v_pk_fma_f32 v[212:213], v[102:103], v[82:83], v[74:75] op_sel_hi:[0,1,1] neg_lo:[0,0,1] neg_hi:[0,0,1]
	v_pk_fma_f32 v[214:215], v[102:103], v[88:89], v[78:79] op_sel_hi:[0,1,1] neg_lo:[0,0,1] neg_hi:[0,0,1]
	v_pk_fma_f32 v[102:103], v[102:103], v[90:91], v[92:93] op_sel_hi:[0,1,1] neg_lo:[0,0,1] neg_hi:[0,0,1]
	v_pk_mul_f32 v[196:197], v[64:65], v[196:197]
	v_pk_mul_f32 v[214:215], v[4:5], v[214:215]
	v_pk_mul_f32 v[102:103], v[2:3], v[102:103]
	v_pk_mul_f32 v[212:213], v[6:7], v[212:213]
	s_movk_i32 s5, 0x7fff
	s_mov_b32 s4, 0xffff0000
	v_lshl_add_u64 v[94:95], v[96:97], 0, v[94:95]
	s_cmp_lt_i32 s14, 1
	s_mov_b64 s[0:1], 0
	s_waitcnt vmcnt(0)
	v_lshlrev_b32_e32 v217, 16, v227
	v_lshlrev_b32_e32 v216, 16, v226
	v_lshlrev_b32_e32 v221, 16, v229
	v_lshlrev_b32_e32 v220, 16, v228
	v_and_b32_e32 v223, 0xffff0000, v229
	v_and_b32_e32 v222, 0xffff0000, v228
	v_and_b32_e32 v219, 0xffff0000, v227
	v_and_b32_e32 v218, 0xffff0000, v226
	v_pk_mul_f32 v[196:197], v[196:197], v[216:217]
	v_pk_mul_f32 v[214:215], v[214:215], v[220:221]
	v_pk_mul_f32 v[102:103], v[102:103], v[222:223]
	v_pk_mul_f32 v[212:213], v[212:213], v[218:219]
	v_bfe_u32 v133, v103, 16, 1
	v_bfe_u32 v220, v197, 16, 1
	v_bfe_u32 v221, v214, 16, 1
	v_bfe_u32 v222, v215, 16, 1
	v_bfe_u32 v216, v102, 16, 1
	v_bfe_u32 v217, v213, 16, 1
	v_add3_u32 v103, v103, v133, s5
	v_add3_u32 v133, v215, v222, s5
	v_add3_u32 v214, v214, v221, s5
	v_add3_u32 v197, v197, v220, s5
	v_add3_u32 v213, v213, v217, s5
	v_add3_u32 v102, v102, v216, s5
	v_lshrrev_b32_e32 v197, 16, v197
	v_lshrrev_b32_e32 v214, 16, v214
	v_lshrrev_b32_e32 v133, 16, v133
	v_and_or_b32 v215, v103, s4, v133
	v_and_or_b32 v214, v102, s4, v214
	v_and_or_b32 v213, v213, s4, v197
	v_cvt_pk_bf16_f32 v212, v196, v212
	global_store_dwordx4 v[94:95], v[212:215], off
	s_cbranch_scc1 .LBB0_3034
	s_cmp_gt_i32 s14, 1
	s_cbranch_scc0 .LBB0_3035
	s_cmp_lg_u32 s14, 2
	s_mov_b64 s[6:7], 0
	s_cselect_b64 s[4:5], -1, 0
	s_branch .LBB0_3036

; __device__ __forceinline__ unsigned pk2(float lo, float hi) { return f2bf(lo) | (f2bf(hi) << 16); }
; __device__ __forceinline__ void fir_tile(const Prm& P, Ctx& C, int pm, int gi) {
;     ...
;     for (int j = 0; j < RUN; ++j) {
;         const int t = t0 + j;
;         const u32x4 g = *(const u32x4*)(GT + (size_t)(row0 + j) * 1024 + c0);
;         acc8(s, x[15 + j], 1.f);
;         const float inv = 1.f / (float)(t + 1 < w ? t + 1 : w);
;         const u32x4 xc = x[15 + j];
;         u32x4 o;
;         o.x = pk2((s[0] * inv - bflo(xc.x)) * sc0[0] * bflo(g.x), (s[1] * inv - bfhi(xc.x)) * sc0[1] * bfhi(g.x));
;         o.y = pk2((s[2] * inv - bflo(xc.y)) * sc0[2] * bflo(g.y), (s[3] * inv - bfhi(xc.y)) * sc0[3] * bfhi(g.y));
;         o.z = pk2((s[4] * inv - bflo(xc.z)) * sc1[0] * bflo(g.z), (s[5] * inv - bfhi(xc.z)) * sc1[1] * bfhi(g.z));
;         o.w = pk2((s[6] * inv - bflo(xc.w)) * sc1[2] * bflo(g.w), (s[7] * inv - bfhi(xc.w)) * sc1[3] * bfhi(g.w));
;         *(u32x4*)(MX + (size_t)(row0 + j) * 1024 + c0) = o;
;         if (w == 2) acc8(s, x[15 + j - 1], -1.f); else if (w == 4) acc8(s, x[15 + j - 3], -1.f); else if (w == 8) acc8(s, x[15 + j - 7], -1.f); else acc8(s, x[j], -1.f);
.LBB0_3044:
	v_or_b32_e32 v70, 2, v132
	v_ashrrev_i32_e32 v71, 31, v70
	v_lshlrev_b64 v[210:211], 11, v[70:71]
	v_lshl_add_u64 v[70:71], v[98:99], 0, v[210:211]
	global_load_dwordx4 v[206:209], v[70:71], off
	v_pk_add_f32 v[214:215], v[0:1], v[94:95] neg_lo:[0,1] neg_hi:[0,1]
	v_pk_add_f32 v[102:103], v[82:83], v[102:103] neg_lo:[0,1] neg_hi:[0,1]
	v_lshlrev_b32_e32 v82, 16, v62
	v_and_b32_e32 v94, 0xffff0000, v62
	v_or_b32_e32 v62, 3, v224
	v_min_i32_e32 v62, s10, v62
	v_cvt_f32_i32_e32 v133, v62
	v_and_b32_e32 v71, 0xffff0000, v61
	v_and_b32_e32 v70, 0xffff0000, v60
	v_lshlrev_b32_e32 v83, 16, v63
	v_and_b32_e32 v95, 0xffff0000, v63
	v_pk_add_f32 v[62:63], v[102:103], v[70:71]
	v_div_scale_f32 v102, s[0:1], v133, v133, 1.0
	v_rcp_f32_e32 v103, v102
	v_pk_add_f32 v[88:89], v[88:89], v[196:197] neg_lo:[0,1] neg_hi:[0,1]
	v_div_scale_f32 v196, vcc, 1.0, v133, 1.0
	v_fma_f32 v197, -v102, v103, 1.0
	v_fmac_f32_e32 v103, v197, v103
	v_mul_f32_e32 v197, v196, v103
	v_pk_add_f32 v[90:91], v[90:91], v[212:213] neg_lo:[0,1] neg_hi:[0,1]
	v_fma_f32 v212, -v102, v197, v196
	v_fmac_f32_e32 v197, v212, v103
	v_fma_f32 v102, -v102, v197, v196
	v_lshlrev_b32_e32 v1, 16, v61
	v_lshlrev_b32_e32 v0, 16, v60
	v_div_fmas_f32 v102, v102, v103, v197
	v_pk_add_f32 v[60:61], v[214:215], v[0:1]
	v_pk_add_f32 v[88:89], v[88:89], v[82:83]
	v_pk_add_f32 v[90:91], v[90:91], v[94:95]
	v_div_fixup_f32 v102, v102, v133, 1.0
	v_pk_fma_f32 v[196:197], v[102:103], v[60:61], v[0:1] op_sel_hi:[0,1,1] neg_lo:[0,0,1] neg_hi:[0,0,1]
	v_pk_fma_f32 v[212:213], v[102:103], v[62:63], v[70:71] op_sel_hi:[0,1,1] neg_lo:[0,0,1] neg_hi:[0,0,1]
	v_pk_fma_f32 v[214:215], v[102:103], v[88:89], v[82:83] op_sel_hi:[0,1,1] neg_lo:[0,0,1] neg_hi:[0,0,1]
	v_pk_fma_f32 v[102:103], v[102:103], v[90:91], v[94:95] op_sel_hi:[0,1,1] neg_lo:[0,0,1] neg_hi:[0,0,1]
	v_pk_mul_f32 v[196:197], v[64:65], v[196:197]
	v_pk_mul_f32 v[212:213], v[6:7], v[212:213]
	v_pk_mul_f32 v[214:215], v[4:5], v[214:215]
	v_pk_mul_f32 v[102:103], v[2:3], v[102:103]
	s_movk_i32 s5, 0x7fff
	s_mov_b32 s4, 0xffff0000
	s_cmp_lt_i32 s14, 1
	s_mov_b64 s[0:1], 0
	s_waitcnt vmcnt(0)
	v_lshlrev_b32_e32 v217, 16, v207
	v_lshlrev_b32_e32 v216, 16, v206
	v_and_b32_e32 v207, 0xffff0000, v207
	v_and_b32_e32 v206, 0xffff0000, v206
	v_lshlrev_b32_e32 v219, 16, v209
	v_lshlrev_b32_e32 v218, 16, v208
	v_and_b32_e32 v209, 0xffff0000, v209
	v_and_b32_e32 v208, 0xffff0000, v208
	v_pk_mul_f32 v[196:197], v[196:197], v[216:217]
	v_pk_mul_f32 v[206:207], v[212:213], v[206:207]
	v_pk_mul_f32 v[212:213], v[214:215], v[218:219]
	v_pk_mul_f32 v[102:103], v[102:103], v[208:209]
	v_bfe_u32 v133, v103, 16, 1
	v_bfe_u32 v208, v102, 16, 1
	v_bfe_u32 v216, v197, 16, 1
	v_bfe_u32 v217, v212, 16, 1
	v_bfe_u32 v218, v213, 16, 1
	v_bfe_u32 v209, v207, 16, 1
	v_add3_u32 v102, v102, v208, s5
	v_add3_u32 v103, v103, v133, s5
	v_add3_u32 v133, v213, v218, s5
	v_add3_u32 v208, v212, v217, s5
	v_add3_u32 v197, v197, v216, s5
	v_add3_u32 v207, v207, v209, s5
	v_lshrrev_b32_e32 v197, 16, v197
	v_lshrrev_b32_e32 v208, 16, v208
	v_lshrrev_b32_e32 v133, 16, v133
	v_and_or_b32 v209, v103, s4, v133
	v_and_or_b32 v208, v102, s4, v208
	v_and_or_b32 v207, v207, s4, v197
	v_cvt_pk_bf16_f32 v206, v196, v206
	v_lshl_add_u64 v[102:103], v[96:97], 0, v[210:211]
	global_store_dwordx4 v[102:103], v[206:209], off
	s_cbranch_scc1 .LBB0_3047
	s_cmp_gt_i32 s14, 1
	s_cbranch_scc0 .LBB0_3048
	s_cmp_lg_u32 s14, 2
	s_mov_b64 s[6:7], 0
	s_cselect_b64 s[4:5], -1, 0
	s_branch .LBB0_3049

; __device__ __forceinline__ unsigned pk2(float lo, float hi) { return f2bf(lo) | (f2bf(hi) << 16); }
; __device__ __forceinline__ void fir_tile(const Prm& P, Ctx& C, int pm, int gi) {
;     ...
;     for (int j = 0; j < RUN; ++j) {
;         const int t = t0 + j;
;         const u32x4 g = *(const u32x4*)(GT + (size_t)(row0 + j) * 1024 + c0);
;         acc8(s, x[15 + j], 1.f);
;         const float inv = 1.f / (float)(t + 1 < w ? t + 1 : w);
;         const u32x4 xc = x[15 + j];
;         u32x4 o;
;         o.x = pk2((s[0] * inv - bflo(xc.x)) * sc0[0] * bflo(g.x), (s[1] * inv - bfhi(xc.x)) * sc0[1] * bfhi(g.x));
;         o.y = pk2((s[2] * inv - bflo(xc.y)) * sc0[2] * bflo(g.y), (s[3] * inv - bfhi(xc.y)) * sc0[3] * bfhi(g.y));
;         o.z = pk2((s[4] * inv - bflo(xc.z)) * sc1[0] * bflo(g.z), (s[5] * inv - bfhi(xc.z)) * sc1[1] * bfhi(g.z));
;         o.w = pk2((s[6] * inv - bflo(xc.w)) * sc1[2] * bflo(g.w), (s[7] * inv - bfhi(xc.w)) * sc1[3] * bfhi(g.w));
;         *(u32x4*)(MX + (size_t)(row0 + j) * 1024 + c0) = o;
;         if (w == 2) acc8(s, x[15 + j - 1], -1.f); else if (w == 4) acc8(s, x[15 + j - 3], -1.f); else if (w == 8) acc8(s, x[15 + j - 7], -1.f); else acc8(s, x[j], -1.f);
.LBB0_3057:
	v_or_b32_e32 v84, 3, v132
	v_ashrrev_i32_e32 v85, 31, v84
	v_lshlrev_b64 v[130:131], 11, v[84:85]
	v_lshl_add_u64 v[84:85], v[98:99], 0, v[130:131]
	global_load_dwordx4 v[210:213], v[84:85], off
	v_lshlrev_b32_e32 v84, 16, v58
	v_and_b32_e32 v100, 0xffff0000, v58
	v_or_b32_e32 v58, 4, v224
	v_min_i32_e32 v58, s10, v58
	v_cvt_f32_i32_e32 v133, v58
	v_pk_add_f32 v[86:87], v[60:61], v[102:103] neg_lo:[0,1] neg_hi:[0,1]
	v_pk_add_f32 v[102:103], v[62:63], v[196:197] neg_lo:[0,1] neg_hi:[0,1]
	v_and_b32_e32 v63, 0xffff0000, v57
	v_and_b32_e32 v62, 0xffff0000, v56
	v_lshlrev_b32_e32 v85, 16, v59
	v_and_b32_e32 v101, 0xffff0000, v59
	v_pk_add_f32 v[58:59], v[102:103], v[62:63]
	v_div_scale_f32 v102, s[0:1], v133, v133, 1.0
	v_rcp_f32_e32 v103, v102
	v_pk_add_f32 v[88:89], v[88:89], v[206:207] neg_lo:[0,1] neg_hi:[0,1]
	v_pk_add_f32 v[90:91], v[90:91], v[208:209] neg_lo:[0,1] neg_hi:[0,1]
	v_lshlrev_b32_e32 v61, 16, v57
	v_lshlrev_b32_e32 v60, 16, v56
	v_pk_add_f32 v[56:57], v[86:87], v[60:61]
	v_pk_add_f32 v[86:87], v[88:89], v[84:85]
	v_pk_add_f32 v[88:89], v[90:91], v[100:101]
	v_fma_f32 v91, -v102, v103, 1.0
	v_div_scale_f32 v90, vcc, 1.0, v133, 1.0
	v_fmac_f32_e32 v103, v91, v103
	v_mul_f32_e32 v91, v90, v103
	v_fma_f32 v196, -v102, v91, v90
	v_fmac_f32_e32 v91, v196, v103
	v_fma_f32 v90, -v102, v91, v90
	v_div_fmas_f32 v90, v90, v103, v91
	v_div_fixup_f32 v90, v90, v133, 1.0
	v_pk_fma_f32 v[102:103], v[90:91], v[56:57], v[60:61] op_sel_hi:[0,1,1] neg_lo:[0,0,1] neg_hi:[0,0,1]
	v_pk_fma_f32 v[196:197], v[90:91], v[58:59], v[62:63] op_sel_hi:[0,1,1] neg_lo:[0,0,1] neg_hi:[0,0,1]
	v_pk_fma_f32 v[206:207], v[90:91], v[86:87], v[84:85] op_sel_hi:[0,1,1] neg_lo:[0,0,1] neg_hi:[0,0,1]
	v_pk_fma_f32 v[90:91], v[90:91], v[88:89], v[100:101] op_sel_hi:[0,1,1] neg_lo:[0,0,1] neg_hi:[0,0,1]
	v_pk_mul_f32 v[102:103], v[64:65], v[102:103]
	v_pk_mul_f32 v[206:207], v[4:5], v[206:207]
	v_pk_mul_f32 v[90:91], v[2:3], v[90:91]
	v_pk_mul_f32 v[196:197], v[6:7], v[196:197]
	s_movk_i32 s5, 0x7fff
	s_mov_b32 s4, 0xffff0000
	s_cmp_lt_i32 s14, 1
	s_mov_b64 s[0:1], 0
	s_waitcnt vmcnt(0)
	v_lshlrev_b32_e32 v209, 16, v211
	v_lshlrev_b32_e32 v208, 16, v210
	v_lshlrev_b32_e32 v215, 16, v213
	v_lshlrev_b32_e32 v214, 16, v212
	v_and_b32_e32 v213, 0xffff0000, v213
	v_and_b32_e32 v212, 0xffff0000, v212
	v_and_b32_e32 v211, 0xffff0000, v211
	v_and_b32_e32 v210, 0xffff0000, v210
	v_pk_mul_f32 v[102:103], v[102:103], v[208:209]
	v_pk_mul_f32 v[206:207], v[206:207], v[214:215]
	v_pk_mul_f32 v[90:91], v[90:91], v[212:213]
	v_pk_mul_f32 v[196:197], v[196:197], v[210:211]
	v_bfe_u32 v133, v91, 16, 1
	v_bfe_u32 v212, v103, 16, 1
	v_bfe_u32 v213, v206, 16, 1
	v_bfe_u32 v214, v207, 16, 1
	v_bfe_u32 v208, v90, 16, 1
	v_bfe_u32 v209, v197, 16, 1
	v_add3_u32 v91, v91, v133, s5
	v_add3_u32 v133, v207, v214, s5
	v_add3_u32 v206, v206, v213, s5
	v_add3_u32 v103, v103, v212, s5
	v_add3_u32 v197, v197, v209, s5
	v_add3_u32 v90, v90, v208, s5
	v_lshrrev_b32_e32 v103, 16, v103
	v_lshrrev_b32_e32 v206, 16, v206
	v_lshrrev_b32_e32 v133, 16, v133
	v_and_or_b32 v209, v91, s4, v133
	v_and_or_b32 v208, v90, s4, v206
	v_and_or_b32 v207, v197, s4, v103
	v_cvt_pk_bf16_f32 v206, v102, v196
	v_lshl_add_u64 v[90:91], v[96:97], 0, v[130:131]
	global_store_dwordx4 v[90:91], v[206:209], off
	s_cbranch_scc1 .LBB0_3060
	s_cmp_gt_i32 s14, 1
	s_cbranch_scc0 .LBB0_3061
	s_cmp_lg_u32 s14, 2
	s_mov_b64 s[6:7], 0
	s_cselect_b64 s[4:5], -1, 0
	s_branch .LBB0_3062

; __device__ __forceinline__ unsigned pk2(float lo, float hi) { return f2bf(lo) | (f2bf(hi) << 16); }
; __device__ __forceinline__ void fir_tile(const Prm& P, Ctx& C, int pm, int gi) {
;     ...
;     for (int j = 0; j < RUN; ++j) {
;         const int t = t0 + j;
;         const u32x4 g = *(const u32x4*)(GT + (size_t)(row0 + j) * 1024 + c0);
;         acc8(s, x[15 + j], 1.f);
;         const float inv = 1.f / (float)(t + 1 < w ? t + 1 : w);
;         const u32x4 xc = x[15 + j];
;         u32x4 o;
;         o.x = pk2((s[0] * inv - bflo(xc.x)) * sc0[0] * bflo(g.x), (s[1] * inv - bfhi(xc.x)) * sc0[1] * bfhi(g.x));
;         o.y = pk2((s[2] * inv - bflo(xc.y)) * sc0[2] * bflo(g.y), (s[3] * inv - bfhi(xc.y)) * sc0[3] * bfhi(g.y));
;         o.z = pk2((s[4] * inv - bflo(xc.z)) * sc1[0] * bflo(g.z), (s[5] * inv - bfhi(xc.z)) * sc1[1] * bfhi(g.z));
;         o.w = pk2((s[6] * inv - bflo(xc.w)) * sc1[2] * bflo(g.w), (s[7] * inv - bfhi(xc.w)) * sc1[3] * bfhi(g.w));
;         *(u32x4*)(MX + (size_t)(row0 + j) * 1024 + c0) = o;
;         if (w == 2) acc8(s, x[15 + j - 1], -1.f); else if (w == 4) acc8(s, x[15 + j - 3], -1.f); else if (w == 8) acc8(s, x[15 + j - 7], -1.f); else acc8(s, x[j], -1.f);
.LBB0_3083:
	v_or_b32_e32 v186, 5, v132
	v_ashrrev_i32_e32 v187, 31, v186
	v_lshlrev_b64 v[192:193], 11, v[186:187]
	v_lshl_add_u64 v[186:187], v[98:99], 0, v[192:193]
	global_load_dwordx4 v[188:191], v[186:187], off
	v_pk_add_f32 v[186:187], v[52:53], v[130:131] neg_lo:[0,1] neg_hi:[0,1]
	v_pk_add_f32 v[198:199], v[88:89], v[198:199] neg_lo:[0,1] neg_hi:[0,1]
	v_lshlrev_b32_e32 v88, 16, v50
	v_and_b32_e32 v130, 0xffff0000, v50
	v_or_b32_e32 v50, 6, v224
	v_min_i32_e32 v50, s10, v50
	v_cvt_f32_i32_e32 v133, v50
	v_pk_add_f32 v[196:197], v[54:55], v[196:197] neg_lo:[0,1] neg_hi:[0,1]
	v_and_b32_e32 v55, 0xffff0000, v49
	v_and_b32_e32 v54, 0xffff0000, v48
	v_lshlrev_b32_e32 v89, 16, v51
	v_and_b32_e32 v131, 0xffff0000, v51
	v_pk_add_f32 v[50:51], v[196:197], v[54:55]
	v_div_scale_f32 v196, s[0:1], v133, v133, 1.0
	v_rcp_f32_e32 v197, v196
	v_pk_add_f32 v[200:201], v[90:91], v[200:201] neg_lo:[0,1] neg_hi:[0,1]
	v_pk_add_f32 v[90:91], v[198:199], v[88:89]
	v_div_scale_f32 v198, vcc, 1.0, v133, 1.0
	v_fma_f32 v199, -v196, v197, 1.0
	v_fmac_f32_e32 v197, v199, v197
	v_lshlrev_b32_e32 v53, 16, v49
	v_lshlrev_b32_e32 v52, 16, v48
	v_mul_f32_e32 v199, v198, v197
	v_pk_add_f32 v[48:49], v[186:187], v[52:53]
	v_pk_add_f32 v[186:187], v[200:201], v[130:131]
	v_fma_f32 v200, -v196, v199, v198
	v_fmac_f32_e32 v199, v200, v197
	v_fma_f32 v196, -v196, v199, v198
	v_div_fmas_f32 v196, v196, v197, v199
	v_div_fixup_f32 v196, v196, v133, 1.0
	v_pk_fma_f32 v[198:199], v[196:197], v[48:49], v[52:53] op_sel_hi:[0,1,1] neg_lo:[0,0,1] neg_hi:[0,0,1]
	v_pk_fma_f32 v[200:201], v[196:197], v[50:51], v[54:55] op_sel_hi:[0,1,1] neg_lo:[0,0,1] neg_hi:[0,0,1]
	v_pk_fma_f32 v[202:203], v[196:197], v[90:91], v[88:89] op_sel_hi:[0,1,1] neg_lo:[0,0,1] neg_hi:[0,0,1]
	v_pk_fma_f32 v[196:197], v[196:197], v[186:187], v[130:131] op_sel_hi:[0,1,1] neg_lo:[0,0,1] neg_hi:[0,0,1]
	v_pk_mul_f32 v[198:199], v[64:65], v[198:199]
	v_pk_mul_f32 v[200:201], v[6:7], v[200:201]
	v_pk_mul_f32 v[202:203], v[4:5], v[202:203]
	v_pk_mul_f32 v[196:197], v[2:3], v[196:197]
	s_movk_i32 s5, 0x7fff
	s_mov_b32 s4, 0xffff0000
	v_lshl_add_u64 v[192:193], v[96:97], 0, v[192:193]
	s_cmp_lt_i32 s14, 1
	s_mov_b64 s[0:1], 0
	s_waitcnt vmcnt(0)
	v_lshlrev_b32_e32 v205, 16, v189
	v_lshlrev_b32_e32 v204, 16, v188
	v_and_b32_e32 v189, 0xffff0000, v189
	v_and_b32_e32 v188, 0xffff0000, v188
	v_lshlrev_b32_e32 v207, 16, v191
	v_lshlrev_b32_e32 v206, 16, v190
	v_and_b32_e32 v191, 0xffff0000, v191
	v_and_b32_e32 v190, 0xffff0000, v190
	v_pk_mul_f32 v[198:199], v[198:199], v[204:205]
	v_pk_mul_f32 v[188:189], v[200:201], v[188:189]
	v_pk_mul_f32 v[200:201], v[202:203], v[206:207]
	v_pk_mul_f32 v[190:191], v[196:197], v[190:191]
	v_bfe_u32 v197, v189, 16, 1
	v_bfe_u32 v133, v191, 16, 1
	v_bfe_u32 v196, v190, 16, 1
	v_bfe_u32 v204, v199, 16, 1
	v_bfe_u32 v205, v200, 16, 1
	v_bfe_u32 v206, v201, 16, 1
	v_add3_u32 v189, v189, v197, s5
	v_add3_u32 v190, v190, v196, s5
	v_add3_u32 v133, v191, v133, s5
	v_add3_u32 v191, v201, v206, s5
	v_add3_u32 v196, v200, v205, s5
	v_add3_u32 v197, v199, v204, s5
	v_lshrrev_b32_e32 v197, 16, v197
	v_lshrrev_b32_e32 v196, 16, v196
	v_lshrrev_b32_e32 v191, 16, v191
	v_and_or_b32 v191, v133, s4, v191
	v_and_or_b32 v190, v190, s4, v196
	v_and_or_b32 v189, v189, s4, v197
	v_cvt_pk_bf16_f32 v188, v198, v188
	global_store_dwordx4 v[192:193], v[188:191], off
	s_cbranch_scc1 .LBB0_3086
	s_cmp_gt_i32 s14, 1
	s_cbranch_scc0 .LBB0_3087
	s_cmp_lg_u32 s14, 2
	s_mov_b64 s[6:7], 0
	s_cselect_b64 s[4:5], -1, 0
	s_branch .LBB0_3088

; __device__ __forceinline__ unsigned pk2(float lo, float hi) { return f2bf(lo) | (f2bf(hi) << 16); }
; __device__ __forceinline__ void fir_tile(const Prm& P, Ctx& C, int pm, int gi) {
;     ...
;     for (int j = 0; j < RUN; ++j) {
;         const int t = t0 + j;
;         const u32x4 g = *(const u32x4*)(GT + (size_t)(row0 + j) * 1024 + c0);
;         acc8(s, x[15 + j], 1.f);
;         const float inv = 1.f / (float)(t + 1 < w ? t + 1 : w);
;         const u32x4 xc = x[15 + j];
;         u32x4 o;
;         o.x = pk2((s[0] * inv - bflo(xc.x)) * sc0[0] * bflo(g.x), (s[1] * inv - bfhi(xc.x)) * sc0[1] * bfhi(g.x));
;         o.y = pk2((s[2] * inv - bflo(xc.y)) * sc0[2] * bflo(g.y), (s[3] * inv - bfhi(xc.y)) * sc0[3] * bfhi(g.y));
;         o.z = pk2((s[4] * inv - bflo(xc.z)) * sc1[0] * bflo(g.z), (s[5] * inv - bfhi(xc.z)) * sc1[1] * bfhi(g.z));
;         o.w = pk2((s[6] * inv - bflo(xc.w)) * sc1[2] * bflo(g.w), (s[7] * inv - bfhi(xc.w)) * sc1[3] * bfhi(g.w));
;         *(u32x4*)(MX + (size_t)(row0 + j) * 1024 + c0) = o;
.LBB0_3205:
	v_or_b32_e32 v16, 15, v132
	v_ashrrev_i32_e32 v17, 31, v16
	v_lshlrev_b64 v[20:21], 11, v[16:17]
	v_lshl_add_u64 v[16:17], v[98:99], 0, v[20:21]
	global_load_dwordx4 v[16:19], v[16:17], off
	v_add_u32_e32 v28, 16, v224
	v_min_i32_e32 v28, s10, v28
	v_cvt_f32_i32_e32 v28, v28
	v_pk_add_f32 v[22:23], v[32:33], v[42:43] neg_lo:[0,1] neg_hi:[0,1]
	v_pk_add_f32 v[0:1], v[0:1], v[44:45] neg_lo:[0,1] neg_hi:[0,1]
	v_pk_add_f32 v[12:13], v[12:13], v[40:41] neg_lo:[0,1] neg_hi:[0,1]
	v_div_scale_f32 v29, s[0:1], v28, v28, 1.0
	v_rcp_f32_e32 v30, v29
	v_div_scale_f32 v31, vcc, 1.0, v28, 1.0
	v_pk_add_f32 v[14:15], v[14:15], v[46:47] neg_lo:[0,1] neg_hi:[0,1]
	v_fma_f32 v32, -v29, v30, 1.0
	v_fmac_f32_e32 v30, v32, v30
	v_mul_f32_e32 v32, v31, v30
	v_fma_f32 v33, -v29, v32, v31
	v_fmac_f32_e32 v32, v33, v30
	v_fma_f32 v29, -v29, v32, v31
	v_lshlrev_b32_e32 v24, 16, v8
	v_and_b32_e32 v8, 0xffff0000, v8
	v_lshlrev_b32_e32 v25, 16, v9
	v_and_b32_e32 v9, 0xffff0000, v9
	v_lshlrev_b32_e32 v26, 16, v10
	v_lshlrev_b32_e32 v27, 16, v11
	v_div_fmas_f32 v29, v29, v30, v32
	v_and_b32_e32 v10, 0xffff0000, v10
	v_and_b32_e32 v11, 0xffff0000, v11
	v_pk_add_f32 v[0:1], v[0:1], v[24:25]
	v_pk_add_f32 v[12:13], v[12:13], v[8:9]
	v_pk_add_f32 v[14:15], v[14:15], v[26:27]
	v_div_fixup_f32 v28, v29, v28, 1.0
	v_pk_add_f32 v[22:23], v[22:23], v[10:11]
	v_pk_fma_f32 v[0:1], v[28:29], v[0:1], v[24:25] op_sel_hi:[0,1,1] neg_lo:[0,0,1] neg_hi:[0,0,1]
	v_pk_fma_f32 v[8:9], v[28:29], v[12:13], v[8:9] op_sel_hi:[0,1,1] neg_lo:[0,0,1] neg_hi:[0,0,1]
	v_pk_fma_f32 v[12:13], v[28:29], v[14:15], v[26:27] op_sel_hi:[0,1,1] neg_lo:[0,0,1] neg_hi:[0,0,1]
	v_pk_fma_f32 v[10:11], v[28:29], v[22:23], v[10:11] op_sel_hi:[0,1,1] neg_lo:[0,0,1] neg_hi:[0,0,1]
	v_pk_mul_f32 v[0:1], v[64:65], v[0:1]
	v_pk_mul_f32 v[6:7], v[6:7], v[8:9]
	v_pk_mul_f32 v[4:5], v[4:5], v[12:13]
	v_pk_mul_f32 v[2:3], v[2:3], v[10:11]
	s_movk_i32 s5, 0x7fff
	s_mov_b32 s4, 0xffff0000
	s_waitcnt vmcnt(0)
	v_lshlrev_b32_e32 v9, 16, v17
	v_lshlrev_b32_e32 v8, 16, v16
	v_lshlrev_b32_e32 v13, 16, v19
	v_lshlrev_b32_e32 v12, 16, v18
	v_and_b32_e32 v11, 0xffff0000, v17
	v_and_b32_e32 v10, 0xffff0000, v16
	v_and_b32_e32 v15, 0xffff0000, v19
	v_and_b32_e32 v14, 0xffff0000, v18
	v_pk_mul_f32 v[0:1], v[0:1], v[8:9]
	v_pk_mul_f32 v[4:5], v[4:5], v[12:13]
	v_pk_mul_f32 v[6:7], v[6:7], v[10:11]
	v_pk_mul_f32 v[2:3], v[2:3], v[14:15]
	v_cvt_pk_bf16_f32 v3, v5, v3
	v_cvt_pk_bf16_f32 v2, v4, v2
	v_cvt_pk_bf16_f32 v1, v1, v7
	v_cvt_pk_bf16_f32 v0, v0, v6
	v_lshl_add_u64 v[4:5], v[96:97], 0, v[20:21]
	global_store_dwordx4 v[4:5], v[0:3], off

; #define MFMA16(a, b, c) __builtin_amdgcn_mfma_f32_16x16x32_bf16((a), (b), (c), 0, 0, 0)
;     ...
;     for (int base = 0; base < ntask; base += NPW * C.G) {
;         const int t = base + pw * C.G + C.bid;
;         const int mt = t % nmt, nt = t / nmt, pn = nt >> 3, sub = nt & 7;
;         const bool glu = E::is_glu(pn);
;         const bool act = t < ntask && !(glu && sub >= 4);
;         f32x4 acc[4];
; #pragma unroll
;         for (int j = 0; j < 4; ++j) acc[j] = (f32x4){0.f, 0.f, 0.f, 0.f};
;         if (act) {
;             const bf16_t* ap = A + (size_t)(mt * mt_stride + r) * lda + (size_t)pn * a_tile_off + kh * Kh + 8 * fq;
;             const bf16_t* bp = Bt + (size_t)(256 * pn + 32 * sub + 8 * (r >> 2) + (r & 3)) * ldb + kh * Kh + 8 * fq;
;             if (glu) {
; #pragma unroll 8
;                 for (int k0 = 0; k0 < Kh; k0 += 32) { const bf16x8 a = *(const bf16x8*)(ap + k0);
;                     acc[0] = MFMA16(*(const bf16x8*)(bp + k0), a, acc[0]); acc[1] = MFMA16(*(const bf16x8*)(bp + 4 * ldb + k0), a, acc[1]);
;                     acc[2] = MFMA16(*(const bf16x8*)(bp + 128 * ldb + k0), a, acc[2]); acc[3] = MFMA16(*(const bf16x8*)(bp + 132 * ldb + k0), a, acc[3]); }
;             } else {
; #pragma unroll 8
;                 for (int k0 = 0; k0 < Kh; k0 += 32) { const bf16x8 a = *(const bf16x8*)(ap + k0);
;                     acc[0] = MFMA16(*(const bf16x8*)(bp + k0), a, acc[0]); acc[1] = MFMA16(*(const bf16x8*)(bp + 4 * ldb + k0), a, acc[1]); }
.LBB0_3261:
	s_add_i32 s22, s27, s34
	s_ashr_i32 s4, s22, 31
	s_lshr_b32 s4, s4, 29
	s_add_i32 s4, s22, s4
	s_and_b32 s5, s4, -8
	s_bfe_u32 s21, s4, 0x30003
	s_sub_i32 s8, s22, s5
	s_ashr_i32 s20, s4, 6
	s_cmpk_lt_i32 s22, 0x100
	s_cselect_b64 s[4:5], -1, 0
	s_cmpk_gt_i32 s22, 0xff
	v_mov_b32_e32 v0, 0
	v_mov_b32_e32 v1, 0
	v_mov_b32_e32 v2, 0
	v_mov_b32_e32 v3, 0
	v_mov_b32_e32 v4, 0
	v_mov_b32_e32 v5, 0
	v_mov_b32_e32 v6, 0
	v_mov_b32_e32 v7, 0
	s_cbranch_scc1 .LBB0_3263
	v_lshl_or_b32 v0, s8, 4, v25
	v_ashrrev_i32_e32 v1, 31, v0
	s_lshl_b32 s22, s20, 8
	s_lshl_b32 s23, s21, 5
	v_lshlrev_b64 v[0:1], 11, v[0:1]
	s_or_b32 s22, s22, s23
	v_lshl_add_u64 v[58:59], v[10:11], 0, v[0:1]
	v_or_b32_e32 v0, s22, v9
	v_ashrrev_i32_e32 v1, 31, v0
	v_lshlrev_b64 v[0:1], 11, v[0:1]
	v_lshl_add_u64 v[60:61], v[12:13], 0, v[0:1]
	v_add_co_u32_e32 v62, vcc, s29, v60
	s_nop 1
	v_addc_co_u32_e32 v63, vcc, 0, v61, vcc
	global_load_dwordx4 v[128:131], v[58:59], off
	global_load_dwordx4 v[132:135], v[60:61], off
	global_load_dwordx4 v[136:139], v[62:63], off
	global_load_dwordx4 v[140:143], v[58:59], off offset:64
	global_load_dwordx4 v[144:147], v[60:61], off offset:64
	global_load_dwordx4 v[148:151], v[62:63], off offset:64
	global_load_dwordx4 v[152:155], v[58:59], off offset:128
	global_load_dwordx4 v[156:159], v[60:61], off offset:128
	global_load_dwordx4 v[216:219], v[62:63], off offset:128
	global_load_dwordx4 v[220:223], v[58:59], off offset:192
	global_load_dwordx4 v[224:227], v[60:61], off offset:192
	global_load_dwordx4 v[228:231], v[62:63], off offset:192
	s_waitcnt vmcnt(9)
	v_mfma_f32_16x16x32_bf16 v[4:7], v[132:135], v[128:131], 0
	v_mfma_f32_16x16x32_bf16 v[0:3], v[136:139], v[128:131], 0
	s_waitcnt vmcnt(6)
	v_mfma_f32_16x16x32_bf16 v[4:7], v[144:147], v[140:143], v[4:7]
	v_mfma_f32_16x16x32_bf16 v[0:3], v[148:151], v[140:143], v[0:3]
	s_waitcnt vmcnt(3)
	v_mfma_f32_16x16x32_bf16 v[4:7], v[156:159], v[152:155], v[4:7]
	v_mfma_f32_16x16x32_bf16 v[0:3], v[216:219], v[152:155], v[0:3]
	s_waitcnt vmcnt(0)
	v_mfma_f32_16x16x32_bf16 v[4:7], v[224:227], v[220:223], v[4:7]
	v_mfma_f32_16x16x32_bf16 v[0:3], v[228:231], v[220:223], v[0:3]
	s_nop 0
